# K-loop: the last-iteration address select chain (cmp + 6 cselect) becomes cmp + rare out-of-line branch; peeled first iteration drops it; on top of v61
# baseline (speedup 1.0000x reference)
; #define PG8_STAGE(bufoff, gbase, voff) do { _Pragma("unroll") for (int _i = 0; _i < 2; ++_i) \
;         __builtin_amdgcn_global_load_lds((const unsigned*)((const char*)(gbase) + (voff)[_i]), (LAS unsigned*)(lds + (bufoff) + ldsw + _i * 8192), 16, 0, 0); } while (0)
; #define PG8_LDA(dst, b, h) do { _Pragma("unroll") for (int m = 0; m < 4; ++m) _Pragma("unroll") for (int k = 0; k < 2; ++k) dst[m][k] = *(const LAS bf16x8*)(lds + PG8_SA(b, h) + aoff + m * 2048 + k * 1024); } while (0)
; #define PG8_LDB(dst, b, h) do { _Pragma("unroll") for (int n = 0; n < 2; ++n) _Pragma("unroll") for (int k = 0; k < 2; ++k) dst[n][k] = *(const LAS bf16x8*)(lds + PG8_SB(b, h) + boff + n * 2048 + k * 1024); } while (0)
; #define PG8_WAIT_V(n) asm volatile("s_waitcnt vmcnt(" #n ")" ::: "memory")
; #define PG8_WAIT_L(n) asm volatile("s_waitcnt lgkmcnt(" #n ")" ::: "memory")
; template <class Epi, class Sched, bool ABLK = false, bool ALIGN_EPI = true, bool SP2 = true, bool BBLK = true>
; __device__ __forceinline__ void gemm_phase(LAS unsigned char* lds, const Gemm g, const Sched& S, const Epi& E) {
;     ...
;         const bool has_next = S.next(ui + 1, nxt);
;         const int nt = cur.nt;
;         const char* nuA = has_next ? a_unit(nxt) : uA; const int ntbA = has_next ? nxt.k0 / BK : tbA; const char* nB = has_next ? (const char*)g.Bt + (size_t)nxt.pn * tstepB + b_k0(nxt.k0) : cB;
;         for (int t = 0; t < nt; t += 2) {
;             const bool last = (t == nt - 2);
;             const char* a1 = a_tile(uA, tbA + t + 1);
;             const char* a2 = last ? a_tile(nuA, ntbA) : a_tile(uA, tbA + t + 2); const char* b2 = last ? nB : cB + (size_t)(t + 2) * kstepB;
;             const char* a3 = last ? a_tile(nuA, ntbA + 1) : a_tile(uA, tbA + t + 3); const char* b3 = b2 + kstepB;
;             if (last && has_next) S.a_ready(nxt);
;             if constexpr (SP2) {
;             PG8_LDB(B0, 0, 0); PG8_LDB(B1, 0, 1); PG8_SCHED; PG8_LDA(At, 0, 0); PG8_STAGE(PG8_SA(1, 1), a1 + hstepA, voffA);
;             PG8_WAIT_V(8); PG8_WAIT_L(0); PG8_BAR; PG8_MMA(0, 0, At, B0); PG8_MMA(0, 1, At, B1); PG8_BAR; PG8_SCHED;
;             PG8_LDA(At, 0, 1); PG8_STAGE(PG8_SB(0, 0), b2, voffB); PG8_STAGE(PG8_SB(0, 1), b2 + hstepB, voffB); PG8_STAGE(PG8_SA(0, 0), a2, voffA);
;             PG8_WAIT_V(8); PG8_WAIT_L(0); PG8_BAR; PG8_MMA(1, 0, At, B0); PG8_MMA(1, 1, At, B1); PG8_BAR; PG8_SCHED;
.LBB0_349:
	s_ashr_i32 s9, s8, 31
	s_lshl_b64 s[4:5], s[8:9], 20
	s_add_u32 s12, s36, s4
	s_addc_u32 s13, s37, s5
	s_and_b64 s[4:5], s[14:15], exec
	s_cselect_b32 s4, s13, s25
	s_cselect_b32 s5, s12, s24
	s_ashr_i32 s11, s10, 31
	s_lshl_b64 s[18:19], s[10:11], 20
	s_add_u32 s18, s0, s18
	s_addc_u32 s19, s1, s19
	s_and_b64 s[28:29], s[14:15], exec
	s_cselect_b32 s9, s19, s27
	s_cselect_b32 s11, s18, s26
	s_add_u32 s50, s5, 0x80
	s_addc_u32 s51, s4, 0
	s_add_u32 s52, s26, 0x10000
	v_mov_b32_e32 v2, 0
	s_addc_u32 s53, s27, 0
	v_lshl_add_u64 v[142:143], s[24:25], 0, v[138:139]
	v_lshl_add_u64 v[144:145], s[24:25], 0, v[140:141]
	s_mov_b32 s54, -2
	s_mov_b64 s[26:27], 0
	ds_read_b128 v[152:155], v148
	ds_read_b128 v[156:159], v148 offset:1024
	ds_read_b128 v[160:163], v148 offset:2048
	ds_read_b128 v[164:167], v148 offset:3072
	ds_read_b128 v[168:171], v149
	ds_read_b128 v[172:175], v149 offset:1024
	ds_read_b128 v[176:179], v149 offset:2048
	ds_read_b128 v[180:183], v149 offset:3072
	s_add_u32 s28, s24, s26
	s_addc_u32 s29, s25, s27
	s_add_u32 s34, s28, 0x100
	s_addc_u32 s35, s29, 0
	s_add_u32 s28, s28, 0x180
	s_addc_u32 s29, s29, 0
	s_mov_b64 s[30:31], s[52:53]
	s_mov_b32 m0, s49
	v_lshl_add_u64 v[216:217], v[142:143], 0, s[26:27]
	ds_read_b128 v[184:187], v150
	ds_read_b128 v[188:191], v150 offset:1024
	ds_read_b128 v[192:195], v150 offset:2048
	ds_read_b128 v[196:199], v150 offset:3072
	ds_read_b128 v[200:203], v150 offset:4096
	ds_read_b128 v[204:207], v150 offset:5120
	ds_read_b128 v[208:211], v150 offset:6144
	ds_read_b128 v[212:215], v150 offset:7168
	global_load_lds_dwordx4 v[216:217], off
	v_lshl_add_u64 v[216:217], v[144:145], 0, s[26:27]
	s_add_i32 m0, s21, 0xe000
	s_nop 0
	global_load_lds_dwordx4 v[216:217], off
	s_waitcnt vmcnt(8) lgkmcnt(0)
	s_barrier
	v_mfma_f32_16x16x32_bf16 v[122:125], v[152:155], v[184:187], 0
	v_mfma_f32_16x16x32_bf16 v[118:121], v[160:163], v[184:187], 0
	v_mfma_f32_16x16x32_bf16 v[106:109], v[152:155], v[192:195], 0
	v_mfma_f32_16x16x32_bf16 v[102:105], v[160:163], v[192:195], 0
	v_mfma_f32_16x16x32_bf16 v[90:93], v[152:155], v[200:203], 0
	v_mfma_f32_16x16x32_bf16 v[86:89], v[160:163], v[200:203], 0
	v_mfma_f32_16x16x32_bf16 v[74:77], v[152:155], v[208:211], 0
	v_mfma_f32_16x16x32_bf16 v[70:73], v[160:163], v[208:211], 0
	v_mfma_f32_16x16x32_bf16 v[122:125], v[156:159], v[188:191], v[122:125]
	v_mfma_f32_16x16x32_bf16 v[118:121], v[164:167], v[188:191], v[118:121]
	v_mfma_f32_16x16x32_bf16 v[106:109], v[156:159], v[196:199], v[106:109]
	v_mfma_f32_16x16x32_bf16 v[102:105], v[164:167], v[196:199], v[102:105]
	v_mfma_f32_16x16x32_bf16 v[90:93], v[156:159], v[204:207], v[90:93]
	v_mfma_f32_16x16x32_bf16 v[86:89], v[164:167], v[204:207], v[86:89]
	v_mfma_f32_16x16x32_bf16 v[74:77], v[156:159], v[212:215], v[74:77]
	v_mfma_f32_16x16x32_bf16 v[70:73], v[164:167], v[212:215], v[70:73]
	v_mfma_f32_16x16x32_bf16 v[126:129], v[168:171], v[184:187], 0
	v_mfma_f32_16x16x32_bf16 v[114:117], v[176:179], v[184:187], 0
	v_mfma_f32_16x16x32_bf16 v[110:113], v[168:171], v[192:195], 0
	v_mfma_f32_16x16x32_bf16 v[98:101], v[176:179], v[192:195], 0
	v_mfma_f32_16x16x32_bf16 v[94:97], v[168:171], v[200:203], 0
	v_mfma_f32_16x16x32_bf16 v[82:85], v[176:179], v[200:203], 0
	v_mfma_f32_16x16x32_bf16 v[78:81], v[168:171], v[208:211], 0
	v_mfma_f32_16x16x32_bf16 v[66:69], v[176:179], v[208:211], 0
	v_mfma_f32_16x16x32_bf16 v[126:129], v[172:175], v[188:191], v[126:129]
	v_mfma_f32_16x16x32_bf16 v[114:117], v[180:183], v[188:191], v[114:117]
	v_mfma_f32_16x16x32_bf16 v[110:113], v[172:175], v[196:199], v[110:113]
	v_mfma_f32_16x16x32_bf16 v[98:101], v[180:183], v[196:199], v[98:101]
	v_mfma_f32_16x16x32_bf16 v[94:97], v[172:175], v[204:207], v[94:97]
	v_mfma_f32_16x16x32_bf16 v[82:85], v[180:183], v[204:207], v[82:85]
	v_mfma_f32_16x16x32_bf16 v[78:81], v[172:175], v[212:215], v[78:81]
	v_mfma_f32_16x16x32_bf16 v[66:69], v[180:183], v[212:215], v[66:69]
	s_barrier
	s_add_i32 s55, s44, s33
	s_mov_b32 m0, s55
	ds_read_b128 v[184:187], v150 offset:16384
	ds_read_b128 v[188:191], v150 offset:17408
	ds_read_b128 v[192:195], v150 offset:18432
	ds_read_b128 v[196:199], v150 offset:19456
	ds_read_b128 v[200:203], v150 offset:20480
	ds_read_b128 v[204:207], v150 offset:21504
	ds_read_b128 v[208:211], v150 offset:22528
	ds_read_b128 v[212:215], v150 offset:23552
	global_load_lds_dwordx4 v134, s[30:31]
	s_add_i32 m0, s55, 0x2000
	s_add_u32 s56, s30, 0x4000
	s_addc_u32 s57, s31, 0
	s_add_i32 s55, s45, s33
	global_load_lds_dwordx4 v130, s[30:31]
	s_mov_b32 m0, s55
	s_nop 0
	global_load_lds_dwordx4 v134, s[56:57]
	s_add_i32 m0, s55, 0x2000
	s_nop 0
	global_load_lds_dwordx4 v130, s[56:57]
	s_mov_b32 m0, s21
	s_nop 0
	global_load_lds_dwordx4 v136, s[34:35]
	s_mov_b32 m0, s23
	s_nop 0
	global_load_lds_dwordx4 v132, s[34:35]
	s_waitcnt vmcnt(8) lgkmcnt(0)
	s_barrier
; #define PG8_STAGE(bufoff, gbase, voff) do { _Pragma("unroll") for (int _i = 0; _i < 2; ++_i) \
;         __builtin_amdgcn_global_load_lds((const unsigned*)((const char*)(gbase) + (voff)[_i]), (LAS unsigned*)(lds + (bufoff) + ldsw + _i * 8192), 16, 0, 0); } while (0)
; #define PG8_LDA(dst, b, h) do { _Pragma("unroll") for (int m = 0; m < 4; ++m) _Pragma("unroll") for (int k = 0; k < 2; ++k) dst[m][k] = *(const LAS bf16x8*)(lds + PG8_SA(b, h) + aoff + m * 2048 + k * 1024); } while (0)
; #define PG8_LDB(dst, b, h) do { _Pragma("unroll") for (int n = 0; n < 2; ++n) _Pragma("unroll") for (int k = 0; k < 2; ++k) dst[n][k] = *(const LAS bf16x8*)(lds + PG8_SB(b, h) + boff + n * 2048 + k * 1024); } while (0)
; #define PG8_MMA(ai, bj, At, Bt) do { __builtin_amdgcn_s_setprio(1); _Pragma("unroll") for (int m = 0; m < 4; ++m) _Pragma("unroll") for (int n = 0; n < 2; ++n) _Pragma("unroll") for (int k = 0; k < 2; ++k) \
;         acc[ai][bj][m][n] = __builtin_amdgcn_mfma_f32_16x16x32_bf16(Bt[n][k], At[m][k], acc[ai][bj][m][n], 0, 0, 0); __builtin_amdgcn_s_setprio(0); } while (0)
; #define PG8_WAIT_V(n) asm volatile("s_waitcnt vmcnt(" #n ")" ::: "memory")
; #define PG8_WAIT_L(n) asm volatile("s_waitcnt lgkmcnt(" #n ")" ::: "memory")
; #define PG8_BAR __builtin_amdgcn_s_barrier()
; #define PG8_SCHED __builtin_amdgcn_sched_barrier(0)
; template <class Epi, class Sched, bool ABLK = false, bool ALIGN_EPI = true, bool SP2 = true, bool BBLK = true>
; __device__ __forceinline__ void gemm_phase(LAS unsigned char* lds, const Gemm g, const Sched& S, const Epi& E) {
;     ...
;             PG8_WAIT_V(8); PG8_WAIT_L(0); PG8_BAR; PG8_MMA(1, 0, At, B0); PG8_MMA(1, 1, At, B1); PG8_BAR; PG8_SCHED;
;             PG8_LDB(B0, 1, 0); PG8_LDB(B1, 1, 1); PG8_SCHED; PG8_LDA(At, 1, 0); PG8_STAGE(PG8_SA(0, 1), a2 + hstepA, voffA);
;             PG8_WAIT_V(8); PG8_WAIT_L(0); PG8_BAR; PG8_MMA(0, 0, At, B0); PG8_MMA(0, 1, At, B1); PG8_BAR; PG8_SCHED;
	v_mfma_f32_16x16x32_bf16 v[58:61], v[152:155], v[184:187], 0
	v_mfma_f32_16x16x32_bf16 v[54:57], v[160:163], v[184:187], 0
	v_mfma_f32_16x16x32_bf16 v[42:45], v[152:155], v[192:195], 0
	v_mfma_f32_16x16x32_bf16 v[38:41], v[160:163], v[192:195], 0
	v_mfma_f32_16x16x32_bf16 v[26:29], v[152:155], v[200:203], 0
	v_mfma_f32_16x16x32_bf16 v[22:25], v[160:163], v[200:203], 0
	v_mfma_f32_16x16x32_bf16 v[10:13], v[152:155], v[208:211], 0
	v_mfma_f32_16x16x32_bf16 v[6:9], v[160:163], v[208:211], 0
	v_mfma_f32_16x16x32_bf16 v[58:61], v[156:159], v[188:191], v[58:61]
	v_mfma_f32_16x16x32_bf16 v[54:57], v[164:167], v[188:191], v[54:57]
	v_mfma_f32_16x16x32_bf16 v[42:45], v[156:159], v[196:199], v[42:45]
	v_mfma_f32_16x16x32_bf16 v[38:41], v[164:167], v[196:199], v[38:41]
	v_mfma_f32_16x16x32_bf16 v[26:29], v[156:159], v[204:207], v[26:29]
	v_mfma_f32_16x16x32_bf16 v[22:25], v[164:167], v[204:207], v[22:25]
	v_mfma_f32_16x16x32_bf16 v[10:13], v[156:159], v[212:215], v[10:13]
	v_mfma_f32_16x16x32_bf16 v[6:9], v[164:167], v[212:215], v[6:9]
	v_mfma_f32_16x16x32_bf16 v[62:65], v[168:171], v[184:187], 0
	v_mfma_f32_16x16x32_bf16 v[50:53], v[176:179], v[184:187], 0
	v_mfma_f32_16x16x32_bf16 v[46:49], v[168:171], v[192:195], 0
	v_mfma_f32_16x16x32_bf16 v[34:37], v[176:179], v[192:195], 0
	v_mfma_f32_16x16x32_bf16 v[30:33], v[168:171], v[200:203], 0
	v_mfma_f32_16x16x32_bf16 v[18:21], v[176:179], v[200:203], 0
	v_mfma_f32_16x16x32_bf16 v[14:17], v[168:171], v[208:211], 0
	v_mfma_f32_16x16x32_bf16 v[2:5], v[176:179], v[208:211], 0
	v_mfma_f32_16x16x32_bf16 v[62:65], v[172:175], v[188:191], v[62:65]
	v_mfma_f32_16x16x32_bf16 v[50:53], v[180:183], v[188:191], v[50:53]
	v_mfma_f32_16x16x32_bf16 v[46:49], v[172:175], v[196:199], v[46:49]
	v_mfma_f32_16x16x32_bf16 v[34:37], v[180:183], v[196:199], v[34:37]
	v_mfma_f32_16x16x32_bf16 v[30:33], v[172:175], v[204:207], v[30:33]
	v_mfma_f32_16x16x32_bf16 v[18:21], v[180:183], v[204:207], v[18:21]
	v_mfma_f32_16x16x32_bf16 v[14:17], v[172:175], v[212:215], v[14:17]
	v_mfma_f32_16x16x32_bf16 v[2:5], v[180:183], v[212:215], v[2:5]
	s_barrier
	s_add_i32 s55, 0, 0x18000
	v_add_u32_e32 v151, s55, v146
	s_add_i32 s56, 0, 0x1c000
	ds_read_b128 v[152:155], v151
	ds_read_b128 v[156:159], v151 offset:1024
	ds_read_b128 v[160:163], v151 offset:2048
	ds_read_b128 v[164:167], v151 offset:3072
	v_add_u32_e32 v151, s56, v146
	ds_read_b128 v[168:171], v151
	ds_read_b128 v[172:175], v151 offset:1024
	ds_read_b128 v[176:179], v151 offset:2048
	ds_read_b128 v[180:183], v151 offset:3072
	s_add_u32 s34, s34, 0x80000
	s_addc_u32 s35, s35, 0
	s_mov_b32 m0, s39
	ds_read_b128 v[184:187], v150 offset:32768
	ds_read_b128 v[188:191], v150 offset:33792
	ds_read_b128 v[192:195], v150 offset:34816
	ds_read_b128 v[196:199], v150 offset:35840
	ds_read_b128 v[200:203], v150 offset:36864
	ds_read_b128 v[204:207], v150 offset:37888
	ds_read_b128 v[208:211], v150 offset:38912
	ds_read_b128 v[212:215], v150 offset:39936
	global_load_lds_dwordx4 v136, s[34:35]
	s_mov_b32 m0, s40
	s_nop 0
	global_load_lds_dwordx4 v132, s[34:35]
	s_waitcnt vmcnt(8) lgkmcnt(0)
	s_barrier
	v_mfma_f32_16x16x32_bf16 v[122:125], v[152:155], v[184:187], v[122:125]
	v_mfma_f32_16x16x32_bf16 v[118:121], v[160:163], v[184:187], v[118:121]
	v_mfma_f32_16x16x32_bf16 v[106:109], v[152:155], v[192:195], v[106:109]
	v_mfma_f32_16x16x32_bf16 v[102:105], v[160:163], v[192:195], v[102:105]
	v_mfma_f32_16x16x32_bf16 v[90:93], v[152:155], v[200:203], v[90:93]
	v_mfma_f32_16x16x32_bf16 v[86:89], v[160:163], v[200:203], v[86:89]
	v_mfma_f32_16x16x32_bf16 v[74:77], v[152:155], v[208:211], v[74:77]
	v_mfma_f32_16x16x32_bf16 v[70:73], v[160:163], v[208:211], v[70:73]
	v_mfma_f32_16x16x32_bf16 v[122:125], v[156:159], v[188:191], v[122:125]
	v_mfma_f32_16x16x32_bf16 v[118:121], v[164:167], v[188:191], v[118:121]
	v_mfma_f32_16x16x32_bf16 v[106:109], v[156:159], v[196:199], v[106:109]
	v_mfma_f32_16x16x32_bf16 v[102:105], v[164:167], v[196:199], v[102:105]
	v_mfma_f32_16x16x32_bf16 v[90:93], v[156:159], v[204:207], v[90:93]
	v_mfma_f32_16x16x32_bf16 v[86:89], v[164:167], v[204:207], v[86:89]
	v_mfma_f32_16x16x32_bf16 v[74:77], v[156:159], v[212:215], v[74:77]
	v_mfma_f32_16x16x32_bf16 v[70:73], v[164:167], v[212:215], v[70:73]
	v_mfma_f32_16x16x32_bf16 v[126:129], v[168:171], v[184:187], v[126:129]
	v_mfma_f32_16x16x32_bf16 v[114:117], v[176:179], v[184:187], v[114:117]
	v_mfma_f32_16x16x32_bf16 v[110:113], v[168:171], v[192:195], v[110:113]
	v_mfma_f32_16x16x32_bf16 v[98:101], v[176:179], v[192:195], v[98:101]
	v_mfma_f32_16x16x32_bf16 v[94:97], v[168:171], v[200:203], v[94:97]
	v_mfma_f32_16x16x32_bf16 v[82:85], v[176:179], v[200:203], v[82:85]
	v_mfma_f32_16x16x32_bf16 v[78:81], v[168:171], v[208:211], v[78:81]
	v_mfma_f32_16x16x32_bf16 v[66:69], v[176:179], v[208:211], v[66:69]
	v_mfma_f32_16x16x32_bf16 v[126:129], v[172:175], v[188:191], v[126:129]
	v_mfma_f32_16x16x32_bf16 v[114:117], v[180:183], v[188:191], v[114:117]
	v_mfma_f32_16x16x32_bf16 v[110:113], v[172:175], v[196:199], v[110:113]
	v_mfma_f32_16x16x32_bf16 v[98:101], v[180:183], v[196:199], v[98:101]
	v_mfma_f32_16x16x32_bf16 v[94:97], v[172:175], v[204:207], v[94:97]
	v_mfma_f32_16x16x32_bf16 v[82:85], v[180:183], v[204:207], v[82:85]
	v_mfma_f32_16x16x32_bf16 v[78:81], v[172:175], v[212:215], v[78:81]
	v_mfma_f32_16x16x32_bf16 v[66:69], v[180:183], v[212:215], v[66:69]
	s_barrier
; #define PG8_STAGE(bufoff, gbase, voff) do { _Pragma("unroll") for (int _i = 0; _i < 2; ++_i) \
;         __builtin_amdgcn_global_load_lds((const unsigned*)((const char*)(gbase) + (voff)[_i]), (LAS unsigned*)(lds + (bufoff) + ldsw + _i * 8192), 16, 0, 0); } while (0)
; #define PG8_LDA(dst, b, h) do { _Pragma("unroll") for (int m = 0; m < 4; ++m) _Pragma("unroll") for (int k = 0; k < 2; ++k) dst[m][k] = *(const LAS bf16x8*)(lds + PG8_SA(b, h) + aoff + m * 2048 + k * 1024); } while (0)
; #define PG8_LDB(dst, b, h) do { _Pragma("unroll") for (int n = 0; n < 2; ++n) _Pragma("unroll") for (int k = 0; k < 2; ++k) dst[n][k] = *(const LAS bf16x8*)(lds + PG8_SB(b, h) + boff + n * 2048 + k * 1024); } while (0)
; #define PG8_WAIT_V(n) asm volatile("s_waitcnt vmcnt(" #n ")" ::: "memory")
; #define PG8_WAIT_L(n) asm volatile("s_waitcnt lgkmcnt(" #n ")" ::: "memory")
; #define PG8_BAR __builtin_amdgcn_s_barrier()
; #define PG8_SCHED __builtin_amdgcn_sched_barrier(0)
; template <class Epi, class Sched, bool ABLK = false, bool ALIGN_EPI = true, bool SP2 = true, bool BBLK = true>
; __device__ __forceinline__ void gemm_phase(LAS unsigned char* lds, const Gemm g, const Sched& S, const Epi& E) {
;     ...
;         for (int t = 0; t < nt; t += 2) {
;             const bool last = (t == nt - 2);
;             const char* a1 = a_tile(uA, tbA + t + 1);
;             const char* a2 = last ? a_tile(nuA, ntbA) : a_tile(uA, tbA + t + 2); const char* b2 = last ? nB : cB + (size_t)(t + 2) * kstepB;
;             const char* a3 = last ? a_tile(nuA, ntbA + 1) : a_tile(uA, tbA + t + 3); const char* b3 = b2 + kstepB;
;             if (last && has_next) S.a_ready(nxt);
;             if constexpr (SP2) {
;             PG8_LDB(B0, 0, 0); PG8_LDB(B1, 0, 1); PG8_SCHED; PG8_LDA(At, 0, 0); PG8_STAGE(PG8_SA(1, 1), a1 + hstepA, voffA);
;             PG8_WAIT_V(8); PG8_WAIT_L(0); PG8_BAR; PG8_MMA(0, 0, At, B0); PG8_MMA(0, 1, At, B1); PG8_BAR; PG8_SCHED;
;     ...
;             PG8_WAIT_V(8); PG8_WAIT_L(0); PG8_BAR; PG8_MMA(0, 0, At, B0); PG8_MMA(0, 1, At, B1); PG8_BAR; PG8_SCHED;
;             PG8_LDA(At, 1, 1); PG8_STAGE(PG8_SB(1, 0), b3, voffB); PG8_STAGE(PG8_SB(1, 1), b3 + hstepB, voffB); PG8_STAGE(PG8_SA(1, 0), a3, voffA);
;             PG8_WAIT_V(8); PG8_WAIT_L(0); PG8_BAR; PG8_MMA(1, 0, At, B0); PG8_MMA(1, 1, At, B1); PG8_BAR; PG8_SCHED;
	s_add_u32 s34, s30, 0x8000
	s_addc_u32 s35, s31, 0
	s_add_i32 s55, s55, s33
	s_mov_b32 m0, s55
	ds_read_b128 v[184:187], v150 offset:49152
	ds_read_b128 v[188:191], v150 offset:50176
	ds_read_b128 v[192:195], v150 offset:51200
	ds_read_b128 v[196:199], v150 offset:52224
	ds_read_b128 v[200:203], v150 offset:53248
	ds_read_b128 v[204:207], v150 offset:54272
	ds_read_b128 v[208:211], v150 offset:55296
	ds_read_b128 v[212:215], v150 offset:56320
	global_load_lds_dwordx4 v134, s[34:35]
	s_add_i32 m0, s55, 0x2000
	s_add_u32 s30, s30, 0xc000
	v_lshl_add_u64 v[216:217], s[34:35], 0, v[130:131]
	s_addc_u32 s31, s31, 0
	s_add_i32 s34, s56, s33
	global_load_lds_dwordx4 v[216:217], off
	s_mov_b32 m0, s34
	s_nop 0
	global_load_lds_dwordx4 v134, s[30:31]
	s_add_i32 m0, s34, 0x2000
	s_nop 0
	global_load_lds_dwordx4 v130, s[30:31]
	s_mov_b32 m0, s42
	s_nop 0
	global_load_lds_dwordx4 v136, s[28:29]
	s_mov_b32 m0, s43
	s_nop 0
	global_load_lds_dwordx4 v132, s[28:29]
	s_waitcnt vmcnt(8) lgkmcnt(0)
	s_barrier
	v_mfma_f32_16x16x32_bf16 v[58:61], v[152:155], v[184:187], v[58:61]
	v_mfma_f32_16x16x32_bf16 v[54:57], v[160:163], v[184:187], v[54:57]
	v_mfma_f32_16x16x32_bf16 v[42:45], v[152:155], v[192:195], v[42:45]
	v_mfma_f32_16x16x32_bf16 v[38:41], v[160:163], v[192:195], v[38:41]
	v_mfma_f32_16x16x32_bf16 v[26:29], v[152:155], v[200:203], v[26:29]
	v_mfma_f32_16x16x32_bf16 v[22:25], v[160:163], v[200:203], v[22:25]
	v_mfma_f32_16x16x32_bf16 v[10:13], v[152:155], v[208:211], v[10:13]
	v_mfma_f32_16x16x32_bf16 v[6:9], v[160:163], v[208:211], v[6:9]
	v_mfma_f32_16x16x32_bf16 v[58:61], v[156:159], v[188:191], v[58:61]
	v_mfma_f32_16x16x32_bf16 v[54:57], v[164:167], v[188:191], v[54:57]
	v_mfma_f32_16x16x32_bf16 v[42:45], v[156:159], v[196:199], v[42:45]
	v_mfma_f32_16x16x32_bf16 v[38:41], v[164:167], v[196:199], v[38:41]
	v_mfma_f32_16x16x32_bf16 v[26:29], v[156:159], v[204:207], v[26:29]
	v_mfma_f32_16x16x32_bf16 v[22:25], v[164:167], v[204:207], v[22:25]
	v_mfma_f32_16x16x32_bf16 v[10:13], v[156:159], v[212:215], v[10:13]
	v_mfma_f32_16x16x32_bf16 v[6:9], v[164:167], v[212:215], v[6:9]
	v_mfma_f32_16x16x32_bf16 v[62:65], v[168:171], v[184:187], v[62:65]
	v_mfma_f32_16x16x32_bf16 v[50:53], v[176:179], v[184:187], v[50:53]
	v_mfma_f32_16x16x32_bf16 v[46:49], v[168:171], v[192:195], v[46:49]
	v_mfma_f32_16x16x32_bf16 v[34:37], v[176:179], v[192:195], v[34:37]
	v_mfma_f32_16x16x32_bf16 v[30:33], v[168:171], v[200:203], v[30:33]
	v_mfma_f32_16x16x32_bf16 v[18:21], v[176:179], v[200:203], v[18:21]
	v_mfma_f32_16x16x32_bf16 v[14:17], v[168:171], v[208:211], v[14:17]
	v_mfma_f32_16x16x32_bf16 v[2:5], v[176:179], v[208:211], v[2:5]
	v_mfma_f32_16x16x32_bf16 v[62:65], v[172:175], v[188:191], v[62:65]
	v_mfma_f32_16x16x32_bf16 v[50:53], v[180:183], v[188:191], v[50:53]
	v_mfma_f32_16x16x32_bf16 v[46:49], v[172:175], v[196:199], v[46:49]
	v_mfma_f32_16x16x32_bf16 v[34:37], v[180:183], v[196:199], v[34:37]
	v_mfma_f32_16x16x32_bf16 v[30:33], v[172:175], v[204:207], v[30:33]
	v_mfma_f32_16x16x32_bf16 v[18:21], v[180:183], v[204:207], v[18:21]
	v_mfma_f32_16x16x32_bf16 v[14:17], v[172:175], v[212:215], v[14:17]
	v_mfma_f32_16x16x32_bf16 v[2:5], v[180:183], v[212:215], v[2:5]
	s_barrier
	s_add_i32 s54, s54, 2
	s_add_u32 s26, s26, 0x100
	s_addc_u32 s27, s27, 0
	s_add_u32 s52, s52, 0x10000
	s_addc_u32 s53, s53, 0
	s_cmp_gt_u32 s54, 29
.LBB0_350:
	ds_read_b128 v[152:155], v148
	ds_read_b128 v[156:159], v148 offset:1024
	ds_read_b128 v[160:163], v148 offset:2048
	ds_read_b128 v[164:167], v148 offset:3072
	ds_read_b128 v[168:171], v149
	ds_read_b128 v[172:175], v149 offset:1024
	ds_read_b128 v[176:179], v149 offset:2048
	ds_read_b128 v[180:183], v149 offset:3072
	s_add_u32 s28, s24, s26
	s_addc_u32 s29, s25, s27
	s_add_u32 s34, s28, 0x100
	s_addc_u32 s35, s29, 0
	s_add_u32 s28, s28, 0x180
	s_addc_u32 s29, s29, 0
	s_cmpk_eq_i32 s26, 0xf00
	s_cbranch_scc1 .Lksel_1
	s_mov_b64 s[30:31], s[52:53]
.Lksel_1_back:
	s_mov_b32 m0, s49
	v_lshl_add_u64 v[216:217], v[142:143], 0, s[26:27]
	ds_read_b128 v[184:187], v150
	ds_read_b128 v[188:191], v150 offset:1024
	ds_read_b128 v[192:195], v150 offset:2048
	ds_read_b128 v[196:199], v150 offset:3072
	ds_read_b128 v[200:203], v150 offset:4096
	ds_read_b128 v[204:207], v150 offset:5120
	ds_read_b128 v[208:211], v150 offset:6144
	ds_read_b128 v[212:215], v150 offset:7168
	global_load_lds_dwordx4 v[216:217], off
	v_lshl_add_u64 v[216:217], v[144:145], 0, s[26:27]
	s_add_i32 m0, s21, 0xe000
	s_nop 0
	global_load_lds_dwordx4 v[216:217], off
	s_waitcnt vmcnt(8) lgkmcnt(0)
	s_barrier
; #define PG8_STAGE(bufoff, gbase, voff) do { _Pragma("unroll") for (int _i = 0; _i < 2; ++_i) \
;         __builtin_amdgcn_global_load_lds((const unsigned*)((const char*)(gbase) + (voff)[_i]), (LAS unsigned*)(lds + (bufoff) + ldsw + _i * 8192), 16, 0, 0); } while (0)
; #define PG8_LDA(dst, b, h) do { _Pragma("unroll") for (int m = 0; m < 4; ++m) _Pragma("unroll") for (int k = 0; k < 2; ++k) dst[m][k] = *(const LAS bf16x8*)(lds + PG8_SA(b, h) + aoff + m * 2048 + k * 1024); } while (0)
; #define PG8_MMA(ai, bj, At, Bt) do { __builtin_amdgcn_s_setprio(1); _Pragma("unroll") for (int m = 0; m < 4; ++m) _Pragma("unroll") for (int n = 0; n < 2; ++n) _Pragma("unroll") for (int k = 0; k < 2; ++k) \
;         acc[ai][bj][m][n] = __builtin_amdgcn_mfma_f32_16x16x32_bf16(Bt[n][k], At[m][k], acc[ai][bj][m][n], 0, 0, 0); __builtin_amdgcn_s_setprio(0); } while (0)
; #define PG8_WAIT_V(n) asm volatile("s_waitcnt vmcnt(" #n ")" ::: "memory")
; #define PG8_WAIT_L(n) asm volatile("s_waitcnt lgkmcnt(" #n ")" ::: "memory")
; #define PG8_BAR __builtin_amdgcn_s_barrier()
; #define PG8_SCHED __builtin_amdgcn_sched_barrier(0)
; template <class Epi, class Sched, bool ABLK = false, bool ALIGN_EPI = true, bool SP2 = true, bool BBLK = true>
; __device__ __forceinline__ void gemm_phase(LAS unsigned char* lds, const Gemm g, const Sched& S, const Epi& E) {
;     ...
;             PG8_WAIT_V(8); PG8_WAIT_L(0); PG8_BAR; PG8_MMA(0, 0, At, B0); PG8_MMA(0, 1, At, B1); PG8_BAR; PG8_SCHED;
;             PG8_LDA(At, 0, 1); PG8_STAGE(PG8_SB(0, 0), b2, voffB); PG8_STAGE(PG8_SB(0, 1), b2 + hstepB, voffB); PG8_STAGE(PG8_SA(0, 0), a2, voffA);
;             PG8_WAIT_V(8); PG8_WAIT_L(0); PG8_BAR; PG8_MMA(1, 0, At, B0); PG8_MMA(1, 1, At, B1); PG8_BAR; PG8_SCHED;
	v_mfma_f32_16x16x32_bf16 v[122:125], v[152:155], v[184:187], v[122:125]
	v_mfma_f32_16x16x32_bf16 v[118:121], v[160:163], v[184:187], v[118:121]
	v_mfma_f32_16x16x32_bf16 v[106:109], v[152:155], v[192:195], v[106:109]
	v_mfma_f32_16x16x32_bf16 v[102:105], v[160:163], v[192:195], v[102:105]
	v_mfma_f32_16x16x32_bf16 v[90:93], v[152:155], v[200:203], v[90:93]
	v_mfma_f32_16x16x32_bf16 v[86:89], v[160:163], v[200:203], v[86:89]
	v_mfma_f32_16x16x32_bf16 v[74:77], v[152:155], v[208:211], v[74:77]
	v_mfma_f32_16x16x32_bf16 v[70:73], v[160:163], v[208:211], v[70:73]
	v_mfma_f32_16x16x32_bf16 v[122:125], v[156:159], v[188:191], v[122:125]
	v_mfma_f32_16x16x32_bf16 v[118:121], v[164:167], v[188:191], v[118:121]
	v_mfma_f32_16x16x32_bf16 v[106:109], v[156:159], v[196:199], v[106:109]
	v_mfma_f32_16x16x32_bf16 v[102:105], v[164:167], v[196:199], v[102:105]
	v_mfma_f32_16x16x32_bf16 v[90:93], v[156:159], v[204:207], v[90:93]
	v_mfma_f32_16x16x32_bf16 v[86:89], v[164:167], v[204:207], v[86:89]
	v_mfma_f32_16x16x32_bf16 v[74:77], v[156:159], v[212:215], v[74:77]
	v_mfma_f32_16x16x32_bf16 v[70:73], v[164:167], v[212:215], v[70:73]
	v_mfma_f32_16x16x32_bf16 v[126:129], v[168:171], v[184:187], v[126:129]
	v_mfma_f32_16x16x32_bf16 v[114:117], v[176:179], v[184:187], v[114:117]
	v_mfma_f32_16x16x32_bf16 v[110:113], v[168:171], v[192:195], v[110:113]
	v_mfma_f32_16x16x32_bf16 v[98:101], v[176:179], v[192:195], v[98:101]
	v_mfma_f32_16x16x32_bf16 v[94:97], v[168:171], v[200:203], v[94:97]
	v_mfma_f32_16x16x32_bf16 v[82:85], v[176:179], v[200:203], v[82:85]
	v_mfma_f32_16x16x32_bf16 v[78:81], v[168:171], v[208:211], v[78:81]
	v_mfma_f32_16x16x32_bf16 v[66:69], v[176:179], v[208:211], v[66:69]
	v_mfma_f32_16x16x32_bf16 v[126:129], v[172:175], v[188:191], v[126:129]
	v_mfma_f32_16x16x32_bf16 v[114:117], v[180:183], v[188:191], v[114:117]
	v_mfma_f32_16x16x32_bf16 v[110:113], v[172:175], v[196:199], v[110:113]
	v_mfma_f32_16x16x32_bf16 v[98:101], v[180:183], v[196:199], v[98:101]
	v_mfma_f32_16x16x32_bf16 v[94:97], v[172:175], v[204:207], v[94:97]
	v_mfma_f32_16x16x32_bf16 v[82:85], v[180:183], v[204:207], v[82:85]
	v_mfma_f32_16x16x32_bf16 v[78:81], v[172:175], v[212:215], v[78:81]
	v_mfma_f32_16x16x32_bf16 v[66:69], v[180:183], v[212:215], v[66:69]
	s_barrier
	s_add_i32 s55, s44, s33
	s_mov_b32 m0, s55
	ds_read_b128 v[184:187], v150 offset:16384
	ds_read_b128 v[188:191], v150 offset:17408
	ds_read_b128 v[192:195], v150 offset:18432
	ds_read_b128 v[196:199], v150 offset:19456
	ds_read_b128 v[200:203], v150 offset:20480
	ds_read_b128 v[204:207], v150 offset:21504
	ds_read_b128 v[208:211], v150 offset:22528
	ds_read_b128 v[212:215], v150 offset:23552
	global_load_lds_dwordx4 v134, s[30:31]
	s_add_i32 m0, s55, 0x2000
	s_add_u32 s56, s30, 0x4000
	s_addc_u32 s57, s31, 0
	s_add_i32 s55, s45, s33
	global_load_lds_dwordx4 v130, s[30:31]
	s_mov_b32 m0, s55
	s_nop 0
	global_load_lds_dwordx4 v134, s[56:57]
	s_add_i32 m0, s55, 0x2000
	s_nop 0
	global_load_lds_dwordx4 v130, s[56:57]
	s_mov_b32 m0, s21
	s_nop 0
	global_load_lds_dwordx4 v136, s[34:35]
	s_mov_b32 m0, s23
	s_nop 0
	global_load_lds_dwordx4 v132, s[34:35]
	s_waitcnt vmcnt(8) lgkmcnt(0)
	s_barrier
	v_mfma_f32_16x16x32_bf16 v[58:61], v[152:155], v[184:187], v[58:61]
	v_mfma_f32_16x16x32_bf16 v[54:57], v[160:163], v[184:187], v[54:57]
	v_mfma_f32_16x16x32_bf16 v[42:45], v[152:155], v[192:195], v[42:45]
	v_mfma_f32_16x16x32_bf16 v[38:41], v[160:163], v[192:195], v[38:41]
	v_mfma_f32_16x16x32_bf16 v[26:29], v[152:155], v[200:203], v[26:29]
	v_mfma_f32_16x16x32_bf16 v[22:25], v[160:163], v[200:203], v[22:25]
	v_mfma_f32_16x16x32_bf16 v[10:13], v[152:155], v[208:211], v[10:13]
	v_mfma_f32_16x16x32_bf16 v[6:9], v[160:163], v[208:211], v[6:9]
	v_mfma_f32_16x16x32_bf16 v[58:61], v[156:159], v[188:191], v[58:61]
	v_mfma_f32_16x16x32_bf16 v[54:57], v[164:167], v[188:191], v[54:57]
	v_mfma_f32_16x16x32_bf16 v[42:45], v[156:159], v[196:199], v[42:45]
	v_mfma_f32_16x16x32_bf16 v[38:41], v[164:167], v[196:199], v[38:41]
	v_mfma_f32_16x16x32_bf16 v[26:29], v[156:159], v[204:207], v[26:29]
	v_mfma_f32_16x16x32_bf16 v[22:25], v[164:167], v[204:207], v[22:25]
	v_mfma_f32_16x16x32_bf16 v[10:13], v[156:159], v[212:215], v[10:13]
	v_mfma_f32_16x16x32_bf16 v[6:9], v[164:167], v[212:215], v[6:9]
	v_mfma_f32_16x16x32_bf16 v[62:65], v[168:171], v[184:187], v[62:65]
	v_mfma_f32_16x16x32_bf16 v[50:53], v[176:179], v[184:187], v[50:53]
	v_mfma_f32_16x16x32_bf16 v[46:49], v[168:171], v[192:195], v[46:49]
	v_mfma_f32_16x16x32_bf16 v[34:37], v[176:179], v[192:195], v[34:37]
	v_mfma_f32_16x16x32_bf16 v[30:33], v[168:171], v[200:203], v[30:33]
	v_mfma_f32_16x16x32_bf16 v[18:21], v[176:179], v[200:203], v[18:21]
	v_mfma_f32_16x16x32_bf16 v[14:17], v[168:171], v[208:211], v[14:17]
	v_mfma_f32_16x16x32_bf16 v[2:5], v[176:179], v[208:211], v[2:5]
	v_mfma_f32_16x16x32_bf16 v[62:65], v[172:175], v[188:191], v[62:65]
	v_mfma_f32_16x16x32_bf16 v[50:53], v[180:183], v[188:191], v[50:53]
	v_mfma_f32_16x16x32_bf16 v[46:49], v[172:175], v[196:199], v[46:49]
	v_mfma_f32_16x16x32_bf16 v[34:37], v[180:183], v[196:199], v[34:37]
	v_mfma_f32_16x16x32_bf16 v[30:33], v[172:175], v[204:207], v[30:33]
	v_mfma_f32_16x16x32_bf16 v[18:21], v[180:183], v[204:207], v[18:21]
	v_mfma_f32_16x16x32_bf16 v[14:17], v[172:175], v[212:215], v[14:17]
	v_mfma_f32_16x16x32_bf16 v[2:5], v[180:183], v[212:215], v[2:5]
	s_barrier
; #define PG8_STAGE(bufoff, gbase, voff) do { _Pragma("unroll") for (int _i = 0; _i < 2; ++_i) \
;         __builtin_amdgcn_global_load_lds((const unsigned*)((const char*)(gbase) + (voff)[_i]), (LAS unsigned*)(lds + (bufoff) + ldsw + _i * 8192), 16, 0, 0); } while (0)
; #define PG8_LDA(dst, b, h) do { _Pragma("unroll") for (int m = 0; m < 4; ++m) _Pragma("unroll") for (int k = 0; k < 2; ++k) dst[m][k] = *(const LAS bf16x8*)(lds + PG8_SA(b, h) + aoff + m * 2048 + k * 1024); } while (0)
; #define PG8_LDB(dst, b, h) do { _Pragma("unroll") for (int n = 0; n < 2; ++n) _Pragma("unroll") for (int k = 0; k < 2; ++k) dst[n][k] = *(const LAS bf16x8*)(lds + PG8_SB(b, h) + boff + n * 2048 + k * 1024); } while (0)
; #define PG8_MMA(ai, bj, At, Bt) do { __builtin_amdgcn_s_setprio(1); _Pragma("unroll") for (int m = 0; m < 4; ++m) _Pragma("unroll") for (int n = 0; n < 2; ++n) _Pragma("unroll") for (int k = 0; k < 2; ++k) \
;         acc[ai][bj][m][n] = __builtin_amdgcn_mfma_f32_16x16x32_bf16(Bt[n][k], At[m][k], acc[ai][bj][m][n], 0, 0, 0); __builtin_amdgcn_s_setprio(0); } while (0)
; #define PG8_WAIT_V(n) asm volatile("s_waitcnt vmcnt(" #n ")" ::: "memory")
; #define PG8_WAIT_L(n) asm volatile("s_waitcnt lgkmcnt(" #n ")" ::: "memory")
; #define PG8_BAR __builtin_amdgcn_s_barrier()
; #define PG8_SCHED __builtin_amdgcn_sched_barrier(0)
; template <class Epi, class Sched, bool ABLK = false, bool ALIGN_EPI = true, bool SP2 = true, bool BBLK = true>
; __device__ __forceinline__ void gemm_phase(LAS unsigned char* lds, const Gemm g, const Sched& S, const Epi& E) {
;     ...
;             PG8_LDB(B0, 1, 0); PG8_LDB(B1, 1, 1); PG8_SCHED; PG8_LDA(At, 1, 0); PG8_STAGE(PG8_SA(0, 1), a2 + hstepA, voffA);
;             PG8_WAIT_V(8); PG8_WAIT_L(0); PG8_BAR; PG8_MMA(0, 0, At, B0); PG8_MMA(0, 1, At, B1); PG8_BAR; PG8_SCHED;
;             PG8_LDA(At, 1, 1); PG8_STAGE(PG8_SB(1, 0), b3, voffB); PG8_STAGE(PG8_SB(1, 1), b3 + hstepB, voffB); PG8_STAGE(PG8_SA(1, 0), a3, voffA);
;             PG8_WAIT_V(8); PG8_WAIT_L(0); PG8_BAR; PG8_MMA(1, 0, At, B0); PG8_MMA(1, 1, At, B1); PG8_BAR; PG8_SCHED;
	s_add_i32 s55, 0, 0x18000
	v_add_u32_e32 v151, s55, v146
	s_add_i32 s56, 0, 0x1c000
	ds_read_b128 v[152:155], v151
	ds_read_b128 v[156:159], v151 offset:1024
	ds_read_b128 v[160:163], v151 offset:2048
	ds_read_b128 v[164:167], v151 offset:3072
	v_add_u32_e32 v151, s56, v146
	ds_read_b128 v[168:171], v151
	ds_read_b128 v[172:175], v151 offset:1024
	ds_read_b128 v[176:179], v151 offset:2048
	ds_read_b128 v[180:183], v151 offset:3072
	s_add_u32 s34, s34, 0x80000
	s_addc_u32 s35, s35, 0
	s_mov_b32 m0, s39
	ds_read_b128 v[184:187], v150 offset:32768
	ds_read_b128 v[188:191], v150 offset:33792
	ds_read_b128 v[192:195], v150 offset:34816
	ds_read_b128 v[196:199], v150 offset:35840
	ds_read_b128 v[200:203], v150 offset:36864
	ds_read_b128 v[204:207], v150 offset:37888
	ds_read_b128 v[208:211], v150 offset:38912
	ds_read_b128 v[212:215], v150 offset:39936
	global_load_lds_dwordx4 v136, s[34:35]
	s_mov_b32 m0, s40
	s_nop 0
	global_load_lds_dwordx4 v132, s[34:35]
	s_waitcnt vmcnt(8) lgkmcnt(0)
	s_barrier
	v_mfma_f32_16x16x32_bf16 v[122:125], v[152:155], v[184:187], v[122:125]
	v_mfma_f32_16x16x32_bf16 v[118:121], v[160:163], v[184:187], v[118:121]
	v_mfma_f32_16x16x32_bf16 v[106:109], v[152:155], v[192:195], v[106:109]
	v_mfma_f32_16x16x32_bf16 v[102:105], v[160:163], v[192:195], v[102:105]
	v_mfma_f32_16x16x32_bf16 v[90:93], v[152:155], v[200:203], v[90:93]
	v_mfma_f32_16x16x32_bf16 v[86:89], v[160:163], v[200:203], v[86:89]
	v_mfma_f32_16x16x32_bf16 v[74:77], v[152:155], v[208:211], v[74:77]
	v_mfma_f32_16x16x32_bf16 v[70:73], v[160:163], v[208:211], v[70:73]
	v_mfma_f32_16x16x32_bf16 v[122:125], v[156:159], v[188:191], v[122:125]
	v_mfma_f32_16x16x32_bf16 v[118:121], v[164:167], v[188:191], v[118:121]
	v_mfma_f32_16x16x32_bf16 v[106:109], v[156:159], v[196:199], v[106:109]
	v_mfma_f32_16x16x32_bf16 v[102:105], v[164:167], v[196:199], v[102:105]
	v_mfma_f32_16x16x32_bf16 v[90:93], v[156:159], v[204:207], v[90:93]
	v_mfma_f32_16x16x32_bf16 v[86:89], v[164:167], v[204:207], v[86:89]
	v_mfma_f32_16x16x32_bf16 v[74:77], v[156:159], v[212:215], v[74:77]
	v_mfma_f32_16x16x32_bf16 v[70:73], v[164:167], v[212:215], v[70:73]
	v_mfma_f32_16x16x32_bf16 v[126:129], v[168:171], v[184:187], v[126:129]
	v_mfma_f32_16x16x32_bf16 v[114:117], v[176:179], v[184:187], v[114:117]
	v_mfma_f32_16x16x32_bf16 v[110:113], v[168:171], v[192:195], v[110:113]
	v_mfma_f32_16x16x32_bf16 v[98:101], v[176:179], v[192:195], v[98:101]
	v_mfma_f32_16x16x32_bf16 v[94:97], v[168:171], v[200:203], v[94:97]
	v_mfma_f32_16x16x32_bf16 v[82:85], v[176:179], v[200:203], v[82:85]
	v_mfma_f32_16x16x32_bf16 v[78:81], v[168:171], v[208:211], v[78:81]
	v_mfma_f32_16x16x32_bf16 v[66:69], v[176:179], v[208:211], v[66:69]
	v_mfma_f32_16x16x32_bf16 v[126:129], v[172:175], v[188:191], v[126:129]
	v_mfma_f32_16x16x32_bf16 v[114:117], v[180:183], v[188:191], v[114:117]
	v_mfma_f32_16x16x32_bf16 v[110:113], v[172:175], v[196:199], v[110:113]
	v_mfma_f32_16x16x32_bf16 v[98:101], v[180:183], v[196:199], v[98:101]
	v_mfma_f32_16x16x32_bf16 v[94:97], v[172:175], v[204:207], v[94:97]
	v_mfma_f32_16x16x32_bf16 v[82:85], v[180:183], v[204:207], v[82:85]
	v_mfma_f32_16x16x32_bf16 v[78:81], v[172:175], v[212:215], v[78:81]
	v_mfma_f32_16x16x32_bf16 v[66:69], v[180:183], v[212:215], v[66:69]
	s_barrier
	s_add_u32 s34, s30, 0x8000
	s_addc_u32 s35, s31, 0
	s_add_i32 s55, s55, s33
	s_mov_b32 m0, s55
	ds_read_b128 v[184:187], v150 offset:49152
	ds_read_b128 v[188:191], v150 offset:50176
	ds_read_b128 v[192:195], v150 offset:51200
	ds_read_b128 v[196:199], v150 offset:52224
	ds_read_b128 v[200:203], v150 offset:53248
	ds_read_b128 v[204:207], v150 offset:54272
	ds_read_b128 v[208:211], v150 offset:55296
	ds_read_b128 v[212:215], v150 offset:56320
	global_load_lds_dwordx4 v134, s[34:35]
	s_add_i32 m0, s55, 0x2000
	s_add_u32 s30, s30, 0xc000
	v_lshl_add_u64 v[216:217], s[34:35], 0, v[130:131]
	s_addc_u32 s31, s31, 0
	s_add_i32 s34, s56, s33
	global_load_lds_dwordx4 v[216:217], off
	s_mov_b32 m0, s34
	s_nop 0
	global_load_lds_dwordx4 v134, s[30:31]
	s_add_i32 m0, s34, 0x2000
	s_nop 0
	global_load_lds_dwordx4 v130, s[30:31]
	s_mov_b32 m0, s42
	s_nop 0
	global_load_lds_dwordx4 v136, s[28:29]
	s_mov_b32 m0, s43
	s_nop 0
	global_load_lds_dwordx4 v132, s[28:29]
	s_waitcnt vmcnt(8) lgkmcnt(0)
	s_barrier
	v_mfma_f32_16x16x32_bf16 v[58:61], v[152:155], v[184:187], v[58:61]
	v_mfma_f32_16x16x32_bf16 v[54:57], v[160:163], v[184:187], v[54:57]
	v_mfma_f32_16x16x32_bf16 v[42:45], v[152:155], v[192:195], v[42:45]
	v_mfma_f32_16x16x32_bf16 v[38:41], v[160:163], v[192:195], v[38:41]
	v_mfma_f32_16x16x32_bf16 v[26:29], v[152:155], v[200:203], v[26:29]
	v_mfma_f32_16x16x32_bf16 v[22:25], v[160:163], v[200:203], v[22:25]
	v_mfma_f32_16x16x32_bf16 v[10:13], v[152:155], v[208:211], v[10:13]
	v_mfma_f32_16x16x32_bf16 v[6:9], v[160:163], v[208:211], v[6:9]
	v_mfma_f32_16x16x32_bf16 v[58:61], v[156:159], v[188:191], v[58:61]
	v_mfma_f32_16x16x32_bf16 v[54:57], v[164:167], v[188:191], v[54:57]
	v_mfma_f32_16x16x32_bf16 v[42:45], v[156:159], v[196:199], v[42:45]
	v_mfma_f32_16x16x32_bf16 v[38:41], v[164:167], v[196:199], v[38:41]
	v_mfma_f32_16x16x32_bf16 v[26:29], v[156:159], v[204:207], v[26:29]
	v_mfma_f32_16x16x32_bf16 v[22:25], v[164:167], v[204:207], v[22:25]
	v_mfma_f32_16x16x32_bf16 v[10:13], v[156:159], v[212:215], v[10:13]
	v_mfma_f32_16x16x32_bf16 v[6:9], v[164:167], v[212:215], v[6:9]
	v_mfma_f32_16x16x32_bf16 v[62:65], v[168:171], v[184:187], v[62:65]
	v_mfma_f32_16x16x32_bf16 v[50:53], v[176:179], v[184:187], v[50:53]
	v_mfma_f32_16x16x32_bf16 v[46:49], v[168:171], v[192:195], v[46:49]
	v_mfma_f32_16x16x32_bf16 v[34:37], v[176:179], v[192:195], v[34:37]
	v_mfma_f32_16x16x32_bf16 v[30:33], v[168:171], v[200:203], v[30:33]
	v_mfma_f32_16x16x32_bf16 v[18:21], v[176:179], v[200:203], v[18:21]
	v_mfma_f32_16x16x32_bf16 v[14:17], v[168:171], v[208:211], v[14:17]
	v_mfma_f32_16x16x32_bf16 v[2:5], v[176:179], v[208:211], v[2:5]
	v_mfma_f32_16x16x32_bf16 v[62:65], v[172:175], v[188:191], v[62:65]
	v_mfma_f32_16x16x32_bf16 v[50:53], v[180:183], v[188:191], v[50:53]
	v_mfma_f32_16x16x32_bf16 v[46:49], v[172:175], v[196:199], v[46:49]
	v_mfma_f32_16x16x32_bf16 v[34:37], v[180:183], v[196:199], v[34:37]
	v_mfma_f32_16x16x32_bf16 v[30:33], v[172:175], v[204:207], v[30:33]
	v_mfma_f32_16x16x32_bf16 v[18:21], v[180:183], v[204:207], v[18:21]
	v_mfma_f32_16x16x32_bf16 v[14:17], v[172:175], v[212:215], v[14:17]
	v_mfma_f32_16x16x32_bf16 v[2:5], v[180:183], v[212:215], v[2:5]
	s_barrier
	s_add_i32 s54, s54, 2
	s_add_u32 s26, s26, 0x100
	s_addc_u32 s27, s27, 0
	s_add_u32 s52, s52, 0x10000
	s_addc_u32 s53, s53, 0
	s_cmp_gt_u32 s54, 29
	s_cbranch_scc0 .LBB0_350
	s_and_b64 vcc, exec, s[6:7]
	s_cbranch_vccz .LBB0_353
	s_barrier

; template <class Epi, class Sched, bool ABLK = false, bool ALIGN_EPI = true, bool SP2 = true, bool BBLK = true>
; __device__ __forceinline__ void gemm_phase(LAS unsigned char* lds, const Gemm g, const Sched& S, const Epi& E) {
;     ...
;             const char* a2 = last ? a_tile(nuA, ntbA) : a_tile(uA, tbA + t + 2); const char* b2 = last ? nB : cB + (size_t)(t + 2) * kstepB;
;             const char* a3 = last ? a_tile(nuA, ntbA + 1) : a_tile(uA, tbA + t + 3); const char* b3 = b2 + kstepB;
.Lksel_1:
	s_mov_b32 s29, s51
	s_mov_b32 s28, s50
	s_mov_b32 s31, s9
	s_mov_b32 s30, s11
	s_mov_b32 s35, s4
	s_mov_b32 s34, s5
	s_branch .Lksel_1_back

; #define PG8_STAGE(bufoff, gbase, voff) do { _Pragma("unroll") for (int _i = 0; _i < 2; ++_i) \
;         __builtin_amdgcn_global_load_lds((const unsigned*)((const char*)(gbase) + (voff)[_i]), (LAS unsigned*)(lds + (bufoff) + ldsw + _i * 8192), 16, 0, 0); } while (0)
; #define PG8_LDA(dst, b, h) do { _Pragma("unroll") for (int m = 0; m < 4; ++m) _Pragma("unroll") for (int k = 0; k < 2; ++k) dst[m][k] = *(const LAS bf16x8*)(lds + PG8_SA(b, h) + aoff + m * 2048 + k * 1024); } while (0)
; #define PG8_LDB(dst, b, h) do { _Pragma("unroll") for (int n = 0; n < 2; ++n) _Pragma("unroll") for (int k = 0; k < 2; ++k) dst[n][k] = *(const LAS bf16x8*)(lds + PG8_SB(b, h) + boff + n * 2048 + k * 1024); } while (0)
; #define PG8_WAIT_V(n) asm volatile("s_waitcnt vmcnt(" #n ")" ::: "memory")
; #define PG8_WAIT_L(n) asm volatile("s_waitcnt lgkmcnt(" #n ")" ::: "memory")
; template <class Epi, class Sched, bool ABLK = false, bool ALIGN_EPI = true, bool SP2 = true, bool BBLK = true>
; __device__ __forceinline__ void gemm_phase(LAS unsigned char* lds, const Gemm g, const Sched& S, const Epi& E) {
;     ...
;         const bool has_next = S.next(ui + 1, nxt);
;         const int nt = cur.nt;
;         const char* nuA = has_next ? a_unit(nxt) : uA; const int ntbA = has_next ? nxt.k0 / BK : tbA; const char* nB = has_next ? (const char*)g.Bt + (size_t)nxt.pn * tstepB + b_k0(nxt.k0) : cB;
;         for (int t = 0; t < nt; t += 2) {
;             const bool last = (t == nt - 2);
;             const char* a1 = a_tile(uA, tbA + t + 1);
;             const char* a2 = last ? a_tile(nuA, ntbA) : a_tile(uA, tbA + t + 2); const char* b2 = last ? nB : cB + (size_t)(t + 2) * kstepB;
;             const char* a3 = last ? a_tile(nuA, ntbA + 1) : a_tile(uA, tbA + t + 3); const char* b3 = b2 + kstepB;
;             if (last && has_next) S.a_ready(nxt);
;             if constexpr (SP2) {
;             PG8_LDB(B0, 0, 0); PG8_LDB(B1, 0, 1); PG8_SCHED; PG8_LDA(At, 0, 0); PG8_STAGE(PG8_SA(1, 1), a1 + hstepA, voffA);
;             PG8_WAIT_V(8); PG8_WAIT_L(0); PG8_BAR; PG8_MMA(0, 0, At, B0); PG8_MMA(0, 1, At, B1); PG8_BAR; PG8_SCHED;
;             PG8_LDA(At, 0, 1); PG8_STAGE(PG8_SB(0, 0), b2, voffB); PG8_STAGE(PG8_SB(0, 1), b2 + hstepB, voffB); PG8_STAGE(PG8_SA(0, 0), a2, voffA);
;             PG8_WAIT_V(8); PG8_WAIT_L(0); PG8_BAR; PG8_MMA(1, 0, At, B0); PG8_MMA(1, 1, At, B1); PG8_BAR; PG8_SCHED;
.LBB0_474:
	s_ashr_i32 s11, s10, 31
	s_lshl_b64 s[4:5], s[10:11], 20
	s_add_u32 s14, s41, s4
	s_addc_u32 s15, s42, s5
	s_and_b64 s[4:5], s[18:19], exec
	s_cselect_b32 s4, s15, s27
	s_cselect_b32 s5, s14, s26
	s_ashr_i32 s13, s12, 31
	s_lshl_b64 s[20:21], s[12:13], 20
	s_add_u32 s20, s0, s20
	s_addc_u32 s21, s39, s21
	s_and_b64 s[30:31], s[18:19], exec
	s_cselect_b32 s11, s21, s29
	s_cselect_b32 s13, s20, s28
	s_add_u32 s23, s5, 0x80
	s_addc_u32 s57, s4, 0
	s_add_u32 s58, s28, 0x10000
	v_mov_b32_e32 v2, 0
	s_addc_u32 s59, s29, 0
	v_lshl_add_u64 v[164:165], s[26:27], 0, v[160:161]
	v_lshl_add_u64 v[166:167], s[26:27], 0, v[162:163]
	s_mov_b32 s60, -2
	s_mov_b64 s[28:29], 0
	ds_read_b128 v[172:175], v168
	ds_read_b128 v[176:179], v168 offset:1024
	ds_read_b128 v[180:183], v168 offset:2048
	ds_read_b128 v[184:187], v168 offset:3072
	ds_read_b128 v[188:191], v169
	ds_read_b128 v[192:195], v169 offset:1024
	ds_read_b128 v[196:199], v169 offset:2048
	ds_read_b128 v[200:203], v169 offset:3072
	s_add_u32 s30, s26, s28
	s_addc_u32 s31, s27, s29
	s_add_u32 s36, s30, 0x100
	s_addc_u32 s37, s31, 0
	s_add_u32 s30, s30, 0x180
	s_addc_u32 s31, s31, 0
	s_mov_b64 s[34:35], s[58:59]
	s_mov_b32 m0, s53
	v_lshl_add_u64 v[236:237], v[164:165], 0, s[28:29]
	ds_read_b128 v[204:207], v170
	ds_read_b128 v[208:211], v170 offset:1024
	ds_read_b128 v[212:215], v170 offset:2048
	ds_read_b128 v[216:219], v170 offset:3072
	ds_read_b128 v[220:223], v170 offset:4096
	ds_read_b128 v[224:227], v170 offset:5120
	ds_read_b128 v[228:231], v170 offset:6144
	ds_read_b128 v[232:235], v170 offset:7168
	global_load_lds_dwordx4 v[236:237], off
	v_lshl_add_u64 v[236:237], v[166:167], 0, s[28:29]
	s_mov_b32 m0, s54
	s_nop 0
	global_load_lds_dwordx4 v[236:237], off
	s_waitcnt vmcnt(8) lgkmcnt(0)
	s_barrier
	v_mfma_f32_16x16x32_bf16 v[126:129], v[172:175], v[204:207], 0
	v_mfma_f32_16x16x32_bf16 v[122:125], v[180:183], v[204:207], 0
	v_mfma_f32_16x16x32_bf16 v[110:113], v[172:175], v[212:215], 0
	v_mfma_f32_16x16x32_bf16 v[106:109], v[180:183], v[212:215], 0
	v_mfma_f32_16x16x32_bf16 v[94:97], v[172:175], v[220:223], 0
	v_mfma_f32_16x16x32_bf16 v[90:93], v[180:183], v[220:223], 0
	v_mfma_f32_16x16x32_bf16 v[78:81], v[172:175], v[228:231], 0
	v_mfma_f32_16x16x32_bf16 v[74:77], v[180:183], v[228:231], 0
	v_mfma_f32_16x16x32_bf16 v[126:129], v[176:179], v[208:211], v[126:129]
	v_mfma_f32_16x16x32_bf16 v[122:125], v[184:187], v[208:211], v[122:125]
	v_mfma_f32_16x16x32_bf16 v[110:113], v[176:179], v[216:219], v[110:113]
	v_mfma_f32_16x16x32_bf16 v[106:109], v[184:187], v[216:219], v[106:109]
	v_mfma_f32_16x16x32_bf16 v[94:97], v[176:179], v[224:227], v[94:97]
	v_mfma_f32_16x16x32_bf16 v[90:93], v[184:187], v[224:227], v[90:93]
	v_mfma_f32_16x16x32_bf16 v[78:81], v[176:179], v[232:235], v[78:81]
	v_mfma_f32_16x16x32_bf16 v[74:77], v[184:187], v[232:235], v[74:77]
	v_mfma_f32_16x16x32_bf16 v[118:121], v[188:191], v[204:207], 0
	v_mfma_f32_16x16x32_bf16 v[114:117], v[196:199], v[204:207], 0
	v_mfma_f32_16x16x32_bf16 v[102:105], v[188:191], v[212:215], 0
	v_mfma_f32_16x16x32_bf16 v[98:101], v[196:199], v[212:215], 0
	v_mfma_f32_16x16x32_bf16 v[86:89], v[188:191], v[220:223], 0
	v_mfma_f32_16x16x32_bf16 v[82:85], v[196:199], v[220:223], 0
	v_mfma_f32_16x16x32_bf16 v[70:73], v[188:191], v[228:231], 0
	v_mfma_f32_16x16x32_bf16 v[66:69], v[196:199], v[228:231], 0
	v_mfma_f32_16x16x32_bf16 v[118:121], v[192:195], v[208:211], v[118:121]
	v_mfma_f32_16x16x32_bf16 v[114:117], v[200:203], v[208:211], v[114:117]
	v_mfma_f32_16x16x32_bf16 v[102:105], v[192:195], v[216:219], v[102:105]
	v_mfma_f32_16x16x32_bf16 v[98:101], v[200:203], v[216:219], v[98:101]
	v_mfma_f32_16x16x32_bf16 v[86:89], v[192:195], v[224:227], v[86:89]
	v_mfma_f32_16x16x32_bf16 v[82:85], v[200:203], v[224:227], v[82:85]
	v_mfma_f32_16x16x32_bf16 v[70:73], v[192:195], v[232:235], v[70:73]
	v_mfma_f32_16x16x32_bf16 v[66:69], v[200:203], v[232:235], v[66:69]
	s_barrier
	s_mov_b32 m0, s55
	s_add_u32 s62, s34, 0x4000
	ds_read_b128 v[204:207], v170 offset:16384
	ds_read_b128 v[208:211], v170 offset:17408
	ds_read_b128 v[212:215], v170 offset:18432
	ds_read_b128 v[216:219], v170 offset:19456
	ds_read_b128 v[220:223], v170 offset:20480
	ds_read_b128 v[224:227], v170 offset:21504
	ds_read_b128 v[228:231], v170 offset:22528
	ds_read_b128 v[232:235], v170 offset:23552
	global_load_lds_dwordx4 v134, s[34:35]
	s_mov_b32 m0, s56
	s_addc_u32 s63, s35, 0
	s_add_i32 s61, s52, s40
	global_load_lds_dwordx4 v130, s[34:35]
	s_mov_b32 m0, s61
	s_nop 0
	global_load_lds_dwordx4 v134, s[62:63]
	s_add_i32 m0, s61, 0x2000
	s_nop 0
	global_load_lds_dwordx4 v130, s[62:63]
	s_mov_b32 m0, s25
	s_nop 0
	global_load_lds_dwordx4 v136, s[36:37]
	s_mov_b32 m0, s43
	s_nop 0
	global_load_lds_dwordx4 v132, s[36:37]
	s_waitcnt vmcnt(8) lgkmcnt(0)
	s_barrier
; #define PG8_STAGE(bufoff, gbase, voff) do { _Pragma("unroll") for (int _i = 0; _i < 2; ++_i) \
;         __builtin_amdgcn_global_load_lds((const unsigned*)((const char*)(gbase) + (voff)[_i]), (LAS unsigned*)(lds + (bufoff) + ldsw + _i * 8192), 16, 0, 0); } while (0)
; #define PG8_LDA(dst, b, h) do { _Pragma("unroll") for (int m = 0; m < 4; ++m) _Pragma("unroll") for (int k = 0; k < 2; ++k) dst[m][k] = *(const LAS bf16x8*)(lds + PG8_SA(b, h) + aoff + m * 2048 + k * 1024); } while (0)
; #define PG8_LDB(dst, b, h) do { _Pragma("unroll") for (int n = 0; n < 2; ++n) _Pragma("unroll") for (int k = 0; k < 2; ++k) dst[n][k] = *(const LAS bf16x8*)(lds + PG8_SB(b, h) + boff + n * 2048 + k * 1024); } while (0)
; #define PG8_MMA(ai, bj, At, Bt) do { __builtin_amdgcn_s_setprio(1); _Pragma("unroll") for (int m = 0; m < 4; ++m) _Pragma("unroll") for (int n = 0; n < 2; ++n) _Pragma("unroll") for (int k = 0; k < 2; ++k) \
;         acc[ai][bj][m][n] = __builtin_amdgcn_mfma_f32_16x16x32_bf16(Bt[n][k], At[m][k], acc[ai][bj][m][n], 0, 0, 0); __builtin_amdgcn_s_setprio(0); } while (0)
; #define PG8_WAIT_V(n) asm volatile("s_waitcnt vmcnt(" #n ")" ::: "memory")
; #define PG8_WAIT_L(n) asm volatile("s_waitcnt lgkmcnt(" #n ")" ::: "memory")
; #define PG8_BAR __builtin_amdgcn_s_barrier()
; #define PG8_SCHED __builtin_amdgcn_sched_barrier(0)
; template <class Epi, class Sched, bool ABLK = false, bool ALIGN_EPI = true, bool SP2 = true, bool BBLK = true>
; __device__ __forceinline__ void gemm_phase(LAS unsigned char* lds, const Gemm g, const Sched& S, const Epi& E) {
;     ...
;             PG8_WAIT_V(8); PG8_WAIT_L(0); PG8_BAR; PG8_MMA(1, 0, At, B0); PG8_MMA(1, 1, At, B1); PG8_BAR; PG8_SCHED;
;             PG8_LDB(B0, 1, 0); PG8_LDB(B1, 1, 1); PG8_SCHED; PG8_LDA(At, 1, 0); PG8_STAGE(PG8_SA(0, 1), a2 + hstepA, voffA);
;             PG8_WAIT_V(8); PG8_WAIT_L(0); PG8_BAR; PG8_MMA(0, 0, At, B0); PG8_MMA(0, 1, At, B1); PG8_BAR; PG8_SCHED;
	v_mfma_f32_16x16x32_bf16 v[62:65], v[172:175], v[204:207], 0
	v_mfma_f32_16x16x32_bf16 v[58:61], v[180:183], v[204:207], 0
	v_mfma_f32_16x16x32_bf16 v[46:49], v[172:175], v[212:215], 0
	v_mfma_f32_16x16x32_bf16 v[42:45], v[180:183], v[212:215], 0
	v_mfma_f32_16x16x32_bf16 v[30:33], v[172:175], v[220:223], 0
	v_mfma_f32_16x16x32_bf16 v[26:29], v[180:183], v[220:223], 0
	v_mfma_f32_16x16x32_bf16 v[14:17], v[172:175], v[228:231], 0
	v_mfma_f32_16x16x32_bf16 v[10:13], v[180:183], v[228:231], 0
	v_mfma_f32_16x16x32_bf16 v[62:65], v[176:179], v[208:211], v[62:65]
	v_mfma_f32_16x16x32_bf16 v[58:61], v[184:187], v[208:211], v[58:61]
	v_mfma_f32_16x16x32_bf16 v[46:49], v[176:179], v[216:219], v[46:49]
	v_mfma_f32_16x16x32_bf16 v[42:45], v[184:187], v[216:219], v[42:45]
	v_mfma_f32_16x16x32_bf16 v[30:33], v[176:179], v[224:227], v[30:33]
	v_mfma_f32_16x16x32_bf16 v[26:29], v[184:187], v[224:227], v[26:29]
	v_mfma_f32_16x16x32_bf16 v[14:17], v[176:179], v[232:235], v[14:17]
	v_mfma_f32_16x16x32_bf16 v[10:13], v[184:187], v[232:235], v[10:13]
	v_mfma_f32_16x16x32_bf16 v[54:57], v[188:191], v[204:207], 0
	v_mfma_f32_16x16x32_bf16 v[50:53], v[196:199], v[204:207], 0
	v_mfma_f32_16x16x32_bf16 v[38:41], v[188:191], v[212:215], 0
	v_mfma_f32_16x16x32_bf16 v[34:37], v[196:199], v[212:215], 0
	v_mfma_f32_16x16x32_bf16 v[22:25], v[188:191], v[220:223], 0
	v_mfma_f32_16x16x32_bf16 v[18:21], v[196:199], v[220:223], 0
	v_mfma_f32_16x16x32_bf16 v[6:9], v[188:191], v[228:231], 0
	v_mfma_f32_16x16x32_bf16 v[2:5], v[196:199], v[228:231], 0
	v_mfma_f32_16x16x32_bf16 v[54:57], v[192:195], v[208:211], v[54:57]
	v_mfma_f32_16x16x32_bf16 v[50:53], v[200:203], v[208:211], v[50:53]
	v_mfma_f32_16x16x32_bf16 v[38:41], v[192:195], v[216:219], v[38:41]
	v_mfma_f32_16x16x32_bf16 v[34:37], v[200:203], v[216:219], v[34:37]
	v_mfma_f32_16x16x32_bf16 v[22:25], v[192:195], v[224:227], v[22:25]
	v_mfma_f32_16x16x32_bf16 v[18:21], v[200:203], v[224:227], v[18:21]
	v_mfma_f32_16x16x32_bf16 v[6:9], v[192:195], v[232:235], v[6:9]
	v_mfma_f32_16x16x32_bf16 v[2:5], v[200:203], v[232:235], v[2:5]
	s_barrier
	s_add_i32 s61, 0, 0x18000
	v_add_u32_e32 v171, s61, v1
	s_add_i32 s62, 0, 0x1c000
	ds_read_b128 v[172:175], v171
	ds_read_b128 v[176:179], v171 offset:1024
	ds_read_b128 v[180:183], v171 offset:2048
	ds_read_b128 v[184:187], v171 offset:3072
	v_add_u32_e32 v171, s62, v1
	ds_read_b128 v[188:191], v171
	ds_read_b128 v[192:195], v171 offset:1024
	ds_read_b128 v[196:199], v171 offset:2048
	ds_read_b128 v[200:203], v171 offset:3072
	s_add_u32 s36, s36, 0x80000
	s_addc_u32 s37, s37, 0
	s_mov_b32 m0, s46
	ds_read_b128 v[204:207], v170 offset:32768
	ds_read_b128 v[208:211], v170 offset:33792
	ds_read_b128 v[212:215], v170 offset:34816
	ds_read_b128 v[216:219], v170 offset:35840
	ds_read_b128 v[220:223], v170 offset:36864
	ds_read_b128 v[224:227], v170 offset:37888
	ds_read_b128 v[228:231], v170 offset:38912
	ds_read_b128 v[232:235], v170 offset:39936
	global_load_lds_dwordx4 v136, s[36:37]
	s_mov_b32 m0, s47
	s_nop 0
	global_load_lds_dwordx4 v132, s[36:37]
	s_waitcnt vmcnt(8) lgkmcnt(0)
	s_barrier
	v_mfma_f32_16x16x32_bf16 v[126:129], v[172:175], v[204:207], v[126:129]
	v_mfma_f32_16x16x32_bf16 v[122:125], v[180:183], v[204:207], v[122:125]
	v_mfma_f32_16x16x32_bf16 v[110:113], v[172:175], v[212:215], v[110:113]
	v_mfma_f32_16x16x32_bf16 v[106:109], v[180:183], v[212:215], v[106:109]
	v_mfma_f32_16x16x32_bf16 v[94:97], v[172:175], v[220:223], v[94:97]
	v_mfma_f32_16x16x32_bf16 v[90:93], v[180:183], v[220:223], v[90:93]
	v_mfma_f32_16x16x32_bf16 v[78:81], v[172:175], v[228:231], v[78:81]
	v_mfma_f32_16x16x32_bf16 v[74:77], v[180:183], v[228:231], v[74:77]
	v_mfma_f32_16x16x32_bf16 v[126:129], v[176:179], v[208:211], v[126:129]
	v_mfma_f32_16x16x32_bf16 v[122:125], v[184:187], v[208:211], v[122:125]
	v_mfma_f32_16x16x32_bf16 v[110:113], v[176:179], v[216:219], v[110:113]
	v_mfma_f32_16x16x32_bf16 v[106:109], v[184:187], v[216:219], v[106:109]
	v_mfma_f32_16x16x32_bf16 v[94:97], v[176:179], v[224:227], v[94:97]
	v_mfma_f32_16x16x32_bf16 v[90:93], v[184:187], v[224:227], v[90:93]
	v_mfma_f32_16x16x32_bf16 v[78:81], v[176:179], v[232:235], v[78:81]
	v_mfma_f32_16x16x32_bf16 v[74:77], v[184:187], v[232:235], v[74:77]
	v_mfma_f32_16x16x32_bf16 v[118:121], v[188:191], v[204:207], v[118:121]
	v_mfma_f32_16x16x32_bf16 v[114:117], v[196:199], v[204:207], v[114:117]
	v_mfma_f32_16x16x32_bf16 v[102:105], v[188:191], v[212:215], v[102:105]
	v_mfma_f32_16x16x32_bf16 v[98:101], v[196:199], v[212:215], v[98:101]
	v_mfma_f32_16x16x32_bf16 v[86:89], v[188:191], v[220:223], v[86:89]
	v_mfma_f32_16x16x32_bf16 v[82:85], v[196:199], v[220:223], v[82:85]
	v_mfma_f32_16x16x32_bf16 v[70:73], v[188:191], v[228:231], v[70:73]
	v_mfma_f32_16x16x32_bf16 v[66:69], v[196:199], v[228:231], v[66:69]
	v_mfma_f32_16x16x32_bf16 v[118:121], v[192:195], v[208:211], v[118:121]
	v_mfma_f32_16x16x32_bf16 v[114:117], v[200:203], v[208:211], v[114:117]
	v_mfma_f32_16x16x32_bf16 v[102:105], v[192:195], v[216:219], v[102:105]
	v_mfma_f32_16x16x32_bf16 v[98:101], v[200:203], v[216:219], v[98:101]
	v_mfma_f32_16x16x32_bf16 v[86:89], v[192:195], v[224:227], v[86:89]
	v_mfma_f32_16x16x32_bf16 v[82:85], v[200:203], v[224:227], v[82:85]
	v_mfma_f32_16x16x32_bf16 v[70:73], v[192:195], v[232:235], v[70:73]
	v_mfma_f32_16x16x32_bf16 v[66:69], v[200:203], v[232:235], v[66:69]
	s_barrier
; #define PG8_STAGE(bufoff, gbase, voff) do { _Pragma("unroll") for (int _i = 0; _i < 2; ++_i) \
;         __builtin_amdgcn_global_load_lds((const unsigned*)((const char*)(gbase) + (voff)[_i]), (LAS unsigned*)(lds + (bufoff) + ldsw + _i * 8192), 16, 0, 0); } while (0)
; #define PG8_LDA(dst, b, h) do { _Pragma("unroll") for (int m = 0; m < 4; ++m) _Pragma("unroll") for (int k = 0; k < 2; ++k) dst[m][k] = *(const LAS bf16x8*)(lds + PG8_SA(b, h) + aoff + m * 2048 + k * 1024); } while (0)
; #define PG8_WAIT_V(n) asm volatile("s_waitcnt vmcnt(" #n ")" ::: "memory")
; #define PG8_WAIT_L(n) asm volatile("s_waitcnt lgkmcnt(" #n ")" ::: "memory")
; template <class Epi, class Sched, bool ABLK = false, bool ALIGN_EPI = true, bool SP2 = true, bool BBLK = true>
; __device__ __forceinline__ void gemm_phase(LAS unsigned char* lds, const Gemm g, const Sched& S, const Epi& E) {
;     ...
;         for (int t = 0; t < nt; t += 2) {
;             const bool last = (t == nt - 2);
;             const char* a1 = a_tile(uA, tbA + t + 1);
;             const char* a2 = last ? a_tile(nuA, ntbA) : a_tile(uA, tbA + t + 2); const char* b2 = last ? nB : cB + (size_t)(t + 2) * kstepB;
;             const char* a3 = last ? a_tile(nuA, ntbA + 1) : a_tile(uA, tbA + t + 3); const char* b3 = b2 + kstepB;
;             if (last && has_next) S.a_ready(nxt);
;             if constexpr (SP2) {
;             PG8_LDB(B0, 0, 0); PG8_LDB(B1, 0, 1); PG8_SCHED; PG8_LDA(At, 0, 0); PG8_STAGE(PG8_SA(1, 1), a1 + hstepA, voffA);
;             PG8_WAIT_V(8); PG8_WAIT_L(0); PG8_BAR; PG8_MMA(0, 0, At, B0); PG8_MMA(0, 1, At, B1); PG8_BAR; PG8_SCHED;
;             PG8_LDA(At, 0, 1); PG8_STAGE(PG8_SB(0, 0), b2, voffB); PG8_STAGE(PG8_SB(0, 1), b2 + hstepB, voffB); PG8_STAGE(PG8_SA(0, 0), a2, voffA);
;             PG8_WAIT_V(8); PG8_WAIT_L(0); PG8_BAR; PG8_MMA(1, 0, At, B0); PG8_MMA(1, 1, At, B1); PG8_BAR; PG8_SCHED;
;             PG8_LDB(B0, 1, 0); PG8_LDB(B1, 1, 1); PG8_SCHED; PG8_LDA(At, 1, 0); PG8_STAGE(PG8_SA(0, 1), a2 + hstepA, voffA);
;             PG8_WAIT_V(8); PG8_WAIT_L(0); PG8_BAR; PG8_MMA(0, 0, At, B0); PG8_MMA(0, 1, At, B1); PG8_BAR; PG8_SCHED;
;             PG8_LDA(At, 1, 1); PG8_STAGE(PG8_SB(1, 0), b3, voffB); PG8_STAGE(PG8_SB(1, 1), b3 + hstepB, voffB); PG8_STAGE(PG8_SA(1, 0), a3, voffA);
;             PG8_WAIT_V(8); PG8_WAIT_L(0); PG8_BAR; PG8_MMA(1, 0, At, B0); PG8_MMA(1, 1, At, B1); PG8_BAR; PG8_SCHED;
	s_add_u32 s36, s34, 0x8000
	s_addc_u32 s37, s35, 0
	s_add_i32 s61, s61, s40
	s_mov_b32 m0, s61
	ds_read_b128 v[204:207], v170 offset:49152
	ds_read_b128 v[208:211], v170 offset:50176
	ds_read_b128 v[212:215], v170 offset:51200
	ds_read_b128 v[216:219], v170 offset:52224
	ds_read_b128 v[220:223], v170 offset:53248
	ds_read_b128 v[224:227], v170 offset:54272
	ds_read_b128 v[228:231], v170 offset:55296
	ds_read_b128 v[232:235], v170 offset:56320
	global_load_lds_dwordx4 v134, s[36:37]
	s_add_i32 m0, s61, 0x2000
	s_add_u32 s34, s34, 0xc000
	v_lshl_add_u64 v[236:237], s[36:37], 0, v[130:131]
	s_addc_u32 s35, s35, 0
	s_add_i32 s36, s62, s40
	global_load_lds_dwordx4 v[236:237], off
	s_mov_b32 m0, s36
	s_nop 0
	global_load_lds_dwordx4 v134, s[34:35]
	s_add_i32 m0, s36, 0x2000
	s_nop 0
	global_load_lds_dwordx4 v130, s[34:35]
	s_mov_b32 m0, s50
	s_nop 0
	global_load_lds_dwordx4 v136, s[30:31]
	s_mov_b32 m0, s51
	s_nop 0
	global_load_lds_dwordx4 v132, s[30:31]
	s_waitcnt vmcnt(8) lgkmcnt(0)
	s_barrier
	v_mfma_f32_16x16x32_bf16 v[62:65], v[172:175], v[204:207], v[62:65]
	v_mfma_f32_16x16x32_bf16 v[58:61], v[180:183], v[204:207], v[58:61]
	v_mfma_f32_16x16x32_bf16 v[46:49], v[172:175], v[212:215], v[46:49]
	v_mfma_f32_16x16x32_bf16 v[42:45], v[180:183], v[212:215], v[42:45]
	v_mfma_f32_16x16x32_bf16 v[30:33], v[172:175], v[220:223], v[30:33]
	v_mfma_f32_16x16x32_bf16 v[26:29], v[180:183], v[220:223], v[26:29]
	v_mfma_f32_16x16x32_bf16 v[14:17], v[172:175], v[228:231], v[14:17]
	v_mfma_f32_16x16x32_bf16 v[10:13], v[180:183], v[228:231], v[10:13]
	v_mfma_f32_16x16x32_bf16 v[62:65], v[176:179], v[208:211], v[62:65]
	v_mfma_f32_16x16x32_bf16 v[58:61], v[184:187], v[208:211], v[58:61]
	v_mfma_f32_16x16x32_bf16 v[46:49], v[176:179], v[216:219], v[46:49]
	v_mfma_f32_16x16x32_bf16 v[42:45], v[184:187], v[216:219], v[42:45]
	v_mfma_f32_16x16x32_bf16 v[30:33], v[176:179], v[224:227], v[30:33]
	v_mfma_f32_16x16x32_bf16 v[26:29], v[184:187], v[224:227], v[26:29]
	v_mfma_f32_16x16x32_bf16 v[14:17], v[176:179], v[232:235], v[14:17]
	v_mfma_f32_16x16x32_bf16 v[10:13], v[184:187], v[232:235], v[10:13]
	v_mfma_f32_16x16x32_bf16 v[54:57], v[188:191], v[204:207], v[54:57]
	v_mfma_f32_16x16x32_bf16 v[50:53], v[196:199], v[204:207], v[50:53]
	v_mfma_f32_16x16x32_bf16 v[38:41], v[188:191], v[212:215], v[38:41]
	v_mfma_f32_16x16x32_bf16 v[34:37], v[196:199], v[212:215], v[34:37]
	v_mfma_f32_16x16x32_bf16 v[22:25], v[188:191], v[220:223], v[22:25]
	v_mfma_f32_16x16x32_bf16 v[18:21], v[196:199], v[220:223], v[18:21]
	v_mfma_f32_16x16x32_bf16 v[6:9], v[188:191], v[228:231], v[6:9]
	v_mfma_f32_16x16x32_bf16 v[2:5], v[196:199], v[228:231], v[2:5]
	v_mfma_f32_16x16x32_bf16 v[54:57], v[192:195], v[208:211], v[54:57]
	v_mfma_f32_16x16x32_bf16 v[50:53], v[200:203], v[208:211], v[50:53]
	v_mfma_f32_16x16x32_bf16 v[38:41], v[192:195], v[216:219], v[38:41]
	v_mfma_f32_16x16x32_bf16 v[34:37], v[200:203], v[216:219], v[34:37]
	v_mfma_f32_16x16x32_bf16 v[22:25], v[192:195], v[224:227], v[22:25]
	v_mfma_f32_16x16x32_bf16 v[18:21], v[200:203], v[224:227], v[18:21]
	v_mfma_f32_16x16x32_bf16 v[6:9], v[192:195], v[232:235], v[6:9]
	v_mfma_f32_16x16x32_bf16 v[2:5], v[200:203], v[232:235], v[2:5]
	s_barrier
	s_add_i32 s60, s60, 2
	s_add_u32 s28, s28, 0x100
	s_addc_u32 s29, s29, 0
	s_add_u32 s58, s58, 0x10000
	s_addc_u32 s59, s59, 0
	s_cmp_gt_u32 s60, 29
.LBB0_475:
	ds_read_b128 v[172:175], v168
	ds_read_b128 v[176:179], v168 offset:1024
	ds_read_b128 v[180:183], v168 offset:2048
	ds_read_b128 v[184:187], v168 offset:3072
	ds_read_b128 v[188:191], v169
	ds_read_b128 v[192:195], v169 offset:1024
	ds_read_b128 v[196:199], v169 offset:2048
	ds_read_b128 v[200:203], v169 offset:3072
	s_add_u32 s30, s26, s28
	s_addc_u32 s31, s27, s29
	s_add_u32 s36, s30, 0x100
	s_addc_u32 s37, s31, 0
	s_add_u32 s30, s30, 0x180
	s_addc_u32 s31, s31, 0
	s_cmpk_eq_i32 s28, 0xf00
	s_cbranch_scc1 .Lksel_3
	s_mov_b64 s[34:35], s[58:59]
.Lksel_3_back:
	s_mov_b32 m0, s53
	v_lshl_add_u64 v[236:237], v[164:165], 0, s[28:29]
	ds_read_b128 v[204:207], v170
	ds_read_b128 v[208:211], v170 offset:1024
	ds_read_b128 v[212:215], v170 offset:2048
	ds_read_b128 v[216:219], v170 offset:3072
	ds_read_b128 v[220:223], v170 offset:4096
	ds_read_b128 v[224:227], v170 offset:5120
	ds_read_b128 v[228:231], v170 offset:6144
	ds_read_b128 v[232:235], v170 offset:7168
	global_load_lds_dwordx4 v[236:237], off
	v_lshl_add_u64 v[236:237], v[166:167], 0, s[28:29]
	s_mov_b32 m0, s54
	s_nop 0
	global_load_lds_dwordx4 v[236:237], off
	s_waitcnt vmcnt(8) lgkmcnt(0)
	s_barrier
; #define PG8_STAGE(bufoff, gbase, voff) do { _Pragma("unroll") for (int _i = 0; _i < 2; ++_i) \
;         __builtin_amdgcn_global_load_lds((const unsigned*)((const char*)(gbase) + (voff)[_i]), (LAS unsigned*)(lds + (bufoff) + ldsw + _i * 8192), 16, 0, 0); } while (0)
; #define PG8_LDA(dst, b, h) do { _Pragma("unroll") for (int m = 0; m < 4; ++m) _Pragma("unroll") for (int k = 0; k < 2; ++k) dst[m][k] = *(const LAS bf16x8*)(lds + PG8_SA(b, h) + aoff + m * 2048 + k * 1024); } while (0)
; #define PG8_LDB(dst, b, h) do { _Pragma("unroll") for (int n = 0; n < 2; ++n) _Pragma("unroll") for (int k = 0; k < 2; ++k) dst[n][k] = *(const LAS bf16x8*)(lds + PG8_SB(b, h) + boff + n * 2048 + k * 1024); } while (0)
; #define PG8_MMA(ai, bj, At, Bt) do { __builtin_amdgcn_s_setprio(1); _Pragma("unroll") for (int m = 0; m < 4; ++m) _Pragma("unroll") for (int n = 0; n < 2; ++n) _Pragma("unroll") for (int k = 0; k < 2; ++k) \
;         acc[ai][bj][m][n] = __builtin_amdgcn_mfma_f32_16x16x32_bf16(Bt[n][k], At[m][k], acc[ai][bj][m][n], 0, 0, 0); __builtin_amdgcn_s_setprio(0); } while (0)
; #define PG8_WAIT_V(n) asm volatile("s_waitcnt vmcnt(" #n ")" ::: "memory")
; #define PG8_WAIT_L(n) asm volatile("s_waitcnt lgkmcnt(" #n ")" ::: "memory")
; #define PG8_BAR __builtin_amdgcn_s_barrier()
; #define PG8_SCHED __builtin_amdgcn_sched_barrier(0)
; template <class Epi, class Sched, bool ABLK = false, bool ALIGN_EPI = true, bool SP2 = true, bool BBLK = true>
; __device__ __forceinline__ void gemm_phase(LAS unsigned char* lds, const Gemm g, const Sched& S, const Epi& E) {
;     ...
;             PG8_LDB(B0, 0, 0); PG8_LDB(B1, 0, 1); PG8_SCHED; PG8_LDA(At, 0, 0); PG8_STAGE(PG8_SA(1, 1), a1 + hstepA, voffA);
;             PG8_WAIT_V(8); PG8_WAIT_L(0); PG8_BAR; PG8_MMA(0, 0, At, B0); PG8_MMA(0, 1, At, B1); PG8_BAR; PG8_SCHED;
;             PG8_LDA(At, 0, 1); PG8_STAGE(PG8_SB(0, 0), b2, voffB); PG8_STAGE(PG8_SB(0, 1), b2 + hstepB, voffB); PG8_STAGE(PG8_SA(0, 0), a2, voffA);
;             PG8_WAIT_V(8); PG8_WAIT_L(0); PG8_BAR; PG8_MMA(1, 0, At, B0); PG8_MMA(1, 1, At, B1); PG8_BAR; PG8_SCHED;
;             PG8_LDB(B0, 1, 0); PG8_LDB(B1, 1, 1); PG8_SCHED; PG8_LDA(At, 1, 0); PG8_STAGE(PG8_SA(0, 1), a2 + hstepA, voffA);
;             PG8_WAIT_V(8); PG8_WAIT_L(0); PG8_BAR; PG8_MMA(0, 0, At, B0); PG8_MMA(0, 1, At, B1); PG8_BAR; PG8_SCHED;
	v_mfma_f32_16x16x32_bf16 v[126:129], v[172:175], v[204:207], v[126:129]
	v_mfma_f32_16x16x32_bf16 v[122:125], v[180:183], v[204:207], v[122:125]
	v_mfma_f32_16x16x32_bf16 v[110:113], v[172:175], v[212:215], v[110:113]
	v_mfma_f32_16x16x32_bf16 v[106:109], v[180:183], v[212:215], v[106:109]
	v_mfma_f32_16x16x32_bf16 v[94:97], v[172:175], v[220:223], v[94:97]
	v_mfma_f32_16x16x32_bf16 v[90:93], v[180:183], v[220:223], v[90:93]
	v_mfma_f32_16x16x32_bf16 v[78:81], v[172:175], v[228:231], v[78:81]
	v_mfma_f32_16x16x32_bf16 v[74:77], v[180:183], v[228:231], v[74:77]
	v_mfma_f32_16x16x32_bf16 v[126:129], v[176:179], v[208:211], v[126:129]
	v_mfma_f32_16x16x32_bf16 v[122:125], v[184:187], v[208:211], v[122:125]
	v_mfma_f32_16x16x32_bf16 v[110:113], v[176:179], v[216:219], v[110:113]
	v_mfma_f32_16x16x32_bf16 v[106:109], v[184:187], v[216:219], v[106:109]
	v_mfma_f32_16x16x32_bf16 v[94:97], v[176:179], v[224:227], v[94:97]
	v_mfma_f32_16x16x32_bf16 v[90:93], v[184:187], v[224:227], v[90:93]
	v_mfma_f32_16x16x32_bf16 v[78:81], v[176:179], v[232:235], v[78:81]
	v_mfma_f32_16x16x32_bf16 v[74:77], v[184:187], v[232:235], v[74:77]
	v_mfma_f32_16x16x32_bf16 v[118:121], v[188:191], v[204:207], v[118:121]
	v_mfma_f32_16x16x32_bf16 v[114:117], v[196:199], v[204:207], v[114:117]
	v_mfma_f32_16x16x32_bf16 v[102:105], v[188:191], v[212:215], v[102:105]
	v_mfma_f32_16x16x32_bf16 v[98:101], v[196:199], v[212:215], v[98:101]
	v_mfma_f32_16x16x32_bf16 v[86:89], v[188:191], v[220:223], v[86:89]
	v_mfma_f32_16x16x32_bf16 v[82:85], v[196:199], v[220:223], v[82:85]
	v_mfma_f32_16x16x32_bf16 v[70:73], v[188:191], v[228:231], v[70:73]
	v_mfma_f32_16x16x32_bf16 v[66:69], v[196:199], v[228:231], v[66:69]
	v_mfma_f32_16x16x32_bf16 v[118:121], v[192:195], v[208:211], v[118:121]
	v_mfma_f32_16x16x32_bf16 v[114:117], v[200:203], v[208:211], v[114:117]
	v_mfma_f32_16x16x32_bf16 v[102:105], v[192:195], v[216:219], v[102:105]
	v_mfma_f32_16x16x32_bf16 v[98:101], v[200:203], v[216:219], v[98:101]
	v_mfma_f32_16x16x32_bf16 v[86:89], v[192:195], v[224:227], v[86:89]
	v_mfma_f32_16x16x32_bf16 v[82:85], v[200:203], v[224:227], v[82:85]
	v_mfma_f32_16x16x32_bf16 v[70:73], v[192:195], v[232:235], v[70:73]
	v_mfma_f32_16x16x32_bf16 v[66:69], v[200:203], v[232:235], v[66:69]
	s_barrier
	s_mov_b32 m0, s55
	s_add_u32 s62, s34, 0x4000
	ds_read_b128 v[204:207], v170 offset:16384
	ds_read_b128 v[208:211], v170 offset:17408
	ds_read_b128 v[212:215], v170 offset:18432
	ds_read_b128 v[216:219], v170 offset:19456
	ds_read_b128 v[220:223], v170 offset:20480
	ds_read_b128 v[224:227], v170 offset:21504
	ds_read_b128 v[228:231], v170 offset:22528
	ds_read_b128 v[232:235], v170 offset:23552
	global_load_lds_dwordx4 v134, s[34:35]
	s_mov_b32 m0, s56
	s_addc_u32 s63, s35, 0
	s_add_i32 s61, s52, s40
	global_load_lds_dwordx4 v130, s[34:35]
	s_mov_b32 m0, s61
	s_nop 0
	global_load_lds_dwordx4 v134, s[62:63]
	s_add_i32 m0, s61, 0x2000
	s_nop 0
	global_load_lds_dwordx4 v130, s[62:63]
	s_mov_b32 m0, s25
	s_nop 0
	global_load_lds_dwordx4 v136, s[36:37]
	s_mov_b32 m0, s43
	s_nop 0
	global_load_lds_dwordx4 v132, s[36:37]
	s_waitcnt vmcnt(8) lgkmcnt(0)
	s_barrier
	v_mfma_f32_16x16x32_bf16 v[62:65], v[172:175], v[204:207], v[62:65]
	v_mfma_f32_16x16x32_bf16 v[58:61], v[180:183], v[204:207], v[58:61]
	v_mfma_f32_16x16x32_bf16 v[46:49], v[172:175], v[212:215], v[46:49]
	v_mfma_f32_16x16x32_bf16 v[42:45], v[180:183], v[212:215], v[42:45]
	v_mfma_f32_16x16x32_bf16 v[30:33], v[172:175], v[220:223], v[30:33]
	v_mfma_f32_16x16x32_bf16 v[26:29], v[180:183], v[220:223], v[26:29]
	v_mfma_f32_16x16x32_bf16 v[14:17], v[172:175], v[228:231], v[14:17]
	v_mfma_f32_16x16x32_bf16 v[10:13], v[180:183], v[228:231], v[10:13]
	v_mfma_f32_16x16x32_bf16 v[62:65], v[176:179], v[208:211], v[62:65]
	v_mfma_f32_16x16x32_bf16 v[58:61], v[184:187], v[208:211], v[58:61]
	v_mfma_f32_16x16x32_bf16 v[46:49], v[176:179], v[216:219], v[46:49]
	v_mfma_f32_16x16x32_bf16 v[42:45], v[184:187], v[216:219], v[42:45]
	v_mfma_f32_16x16x32_bf16 v[30:33], v[176:179], v[224:227], v[30:33]
	v_mfma_f32_16x16x32_bf16 v[26:29], v[184:187], v[224:227], v[26:29]
	v_mfma_f32_16x16x32_bf16 v[14:17], v[176:179], v[232:235], v[14:17]
	v_mfma_f32_16x16x32_bf16 v[10:13], v[184:187], v[232:235], v[10:13]
	v_mfma_f32_16x16x32_bf16 v[54:57], v[188:191], v[204:207], v[54:57]
	v_mfma_f32_16x16x32_bf16 v[50:53], v[196:199], v[204:207], v[50:53]
	v_mfma_f32_16x16x32_bf16 v[38:41], v[188:191], v[212:215], v[38:41]
	v_mfma_f32_16x16x32_bf16 v[34:37], v[196:199], v[212:215], v[34:37]
	v_mfma_f32_16x16x32_bf16 v[22:25], v[188:191], v[220:223], v[22:25]
	v_mfma_f32_16x16x32_bf16 v[18:21], v[196:199], v[220:223], v[18:21]
	v_mfma_f32_16x16x32_bf16 v[6:9], v[188:191], v[228:231], v[6:9]
	v_mfma_f32_16x16x32_bf16 v[2:5], v[196:199], v[228:231], v[2:5]
	v_mfma_f32_16x16x32_bf16 v[54:57], v[192:195], v[208:211], v[54:57]
	v_mfma_f32_16x16x32_bf16 v[50:53], v[200:203], v[208:211], v[50:53]
	v_mfma_f32_16x16x32_bf16 v[38:41], v[192:195], v[216:219], v[38:41]
	v_mfma_f32_16x16x32_bf16 v[34:37], v[200:203], v[216:219], v[34:37]
	v_mfma_f32_16x16x32_bf16 v[22:25], v[192:195], v[224:227], v[22:25]
	v_mfma_f32_16x16x32_bf16 v[18:21], v[200:203], v[224:227], v[18:21]
	v_mfma_f32_16x16x32_bf16 v[6:9], v[192:195], v[232:235], v[6:9]
	v_mfma_f32_16x16x32_bf16 v[2:5], v[200:203], v[232:235], v[2:5]
	s_barrier
; #define PG8_STAGE(bufoff, gbase, voff) do { _Pragma("unroll") for (int _i = 0; _i < 2; ++_i) \
;         __builtin_amdgcn_global_load_lds((const unsigned*)((const char*)(gbase) + (voff)[_i]), (LAS unsigned*)(lds + (bufoff) + ldsw + _i * 8192), 16, 0, 0); } while (0)
; #define PG8_LDA(dst, b, h) do { _Pragma("unroll") for (int m = 0; m < 4; ++m) _Pragma("unroll") for (int k = 0; k < 2; ++k) dst[m][k] = *(const LAS bf16x8*)(lds + PG8_SA(b, h) + aoff + m * 2048 + k * 1024); } while (0)
; #define PG8_LDB(dst, b, h) do { _Pragma("unroll") for (int n = 0; n < 2; ++n) _Pragma("unroll") for (int k = 0; k < 2; ++k) dst[n][k] = *(const LAS bf16x8*)(lds + PG8_SB(b, h) + boff + n * 2048 + k * 1024); } while (0)
; #define PG8_MMA(ai, bj, At, Bt) do { __builtin_amdgcn_s_setprio(1); _Pragma("unroll") for (int m = 0; m < 4; ++m) _Pragma("unroll") for (int n = 0; n < 2; ++n) _Pragma("unroll") for (int k = 0; k < 2; ++k) \
;         acc[ai][bj][m][n] = __builtin_amdgcn_mfma_f32_16x16x32_bf16(Bt[n][k], At[m][k], acc[ai][bj][m][n], 0, 0, 0); __builtin_amdgcn_s_setprio(0); } while (0)
; #define PG8_WAIT_V(n) asm volatile("s_waitcnt vmcnt(" #n ")" ::: "memory")
; #define PG8_WAIT_L(n) asm volatile("s_waitcnt lgkmcnt(" #n ")" ::: "memory")
; #define PG8_BAR __builtin_amdgcn_s_barrier()
; #define PG8_SCHED __builtin_amdgcn_sched_barrier(0)
; template <class Epi, class Sched, bool ABLK = false, bool ALIGN_EPI = true, bool SP2 = true, bool BBLK = true>
; __device__ __forceinline__ void gemm_phase(LAS unsigned char* lds, const Gemm g, const Sched& S, const Epi& E) {
;     ...
;             PG8_LDB(B0, 1, 0); PG8_LDB(B1, 1, 1); PG8_SCHED; PG8_LDA(At, 1, 0); PG8_STAGE(PG8_SA(0, 1), a2 + hstepA, voffA);
;             PG8_WAIT_V(8); PG8_WAIT_L(0); PG8_BAR; PG8_MMA(0, 0, At, B0); PG8_MMA(0, 1, At, B1); PG8_BAR; PG8_SCHED;
;             PG8_LDA(At, 1, 1); PG8_STAGE(PG8_SB(1, 0), b3, voffB); PG8_STAGE(PG8_SB(1, 1), b3 + hstepB, voffB); PG8_STAGE(PG8_SA(1, 0), a3, voffA);
;             PG8_WAIT_V(8); PG8_WAIT_L(0); PG8_BAR; PG8_MMA(1, 0, At, B0); PG8_MMA(1, 1, At, B1); PG8_BAR; PG8_SCHED;
	s_add_i32 s61, 0, 0x18000
	v_add_u32_e32 v171, s61, v1
	s_add_i32 s62, 0, 0x1c000
	ds_read_b128 v[172:175], v171
	ds_read_b128 v[176:179], v171 offset:1024
	ds_read_b128 v[180:183], v171 offset:2048
	ds_read_b128 v[184:187], v171 offset:3072
	v_add_u32_e32 v171, s62, v1
	ds_read_b128 v[188:191], v171
	ds_read_b128 v[192:195], v171 offset:1024
	ds_read_b128 v[196:199], v171 offset:2048
	ds_read_b128 v[200:203], v171 offset:3072
	s_add_u32 s36, s36, 0x80000
	s_addc_u32 s37, s37, 0
	s_mov_b32 m0, s46
	ds_read_b128 v[204:207], v170 offset:32768
	ds_read_b128 v[208:211], v170 offset:33792
	ds_read_b128 v[212:215], v170 offset:34816
	ds_read_b128 v[216:219], v170 offset:35840
	ds_read_b128 v[220:223], v170 offset:36864
	ds_read_b128 v[224:227], v170 offset:37888
	ds_read_b128 v[228:231], v170 offset:38912
	ds_read_b128 v[232:235], v170 offset:39936
	global_load_lds_dwordx4 v136, s[36:37]
	s_mov_b32 m0, s47
	s_nop 0
	global_load_lds_dwordx4 v132, s[36:37]
	s_waitcnt vmcnt(8) lgkmcnt(0)
	s_barrier
	v_mfma_f32_16x16x32_bf16 v[126:129], v[172:175], v[204:207], v[126:129]
	v_mfma_f32_16x16x32_bf16 v[122:125], v[180:183], v[204:207], v[122:125]
	v_mfma_f32_16x16x32_bf16 v[110:113], v[172:175], v[212:215], v[110:113]
	v_mfma_f32_16x16x32_bf16 v[106:109], v[180:183], v[212:215], v[106:109]
	v_mfma_f32_16x16x32_bf16 v[94:97], v[172:175], v[220:223], v[94:97]
	v_mfma_f32_16x16x32_bf16 v[90:93], v[180:183], v[220:223], v[90:93]
	v_mfma_f32_16x16x32_bf16 v[78:81], v[172:175], v[228:231], v[78:81]
	v_mfma_f32_16x16x32_bf16 v[74:77], v[180:183], v[228:231], v[74:77]
	v_mfma_f32_16x16x32_bf16 v[126:129], v[176:179], v[208:211], v[126:129]
	v_mfma_f32_16x16x32_bf16 v[122:125], v[184:187], v[208:211], v[122:125]
	v_mfma_f32_16x16x32_bf16 v[110:113], v[176:179], v[216:219], v[110:113]
	v_mfma_f32_16x16x32_bf16 v[106:109], v[184:187], v[216:219], v[106:109]
	v_mfma_f32_16x16x32_bf16 v[94:97], v[176:179], v[224:227], v[94:97]
	v_mfma_f32_16x16x32_bf16 v[90:93], v[184:187], v[224:227], v[90:93]
	v_mfma_f32_16x16x32_bf16 v[78:81], v[176:179], v[232:235], v[78:81]
	v_mfma_f32_16x16x32_bf16 v[74:77], v[184:187], v[232:235], v[74:77]
	v_mfma_f32_16x16x32_bf16 v[118:121], v[188:191], v[204:207], v[118:121]
	v_mfma_f32_16x16x32_bf16 v[114:117], v[196:199], v[204:207], v[114:117]
	v_mfma_f32_16x16x32_bf16 v[102:105], v[188:191], v[212:215], v[102:105]
	v_mfma_f32_16x16x32_bf16 v[98:101], v[196:199], v[212:215], v[98:101]
	v_mfma_f32_16x16x32_bf16 v[86:89], v[188:191], v[220:223], v[86:89]
	v_mfma_f32_16x16x32_bf16 v[82:85], v[196:199], v[220:223], v[82:85]
	v_mfma_f32_16x16x32_bf16 v[70:73], v[188:191], v[228:231], v[70:73]
	v_mfma_f32_16x16x32_bf16 v[66:69], v[196:199], v[228:231], v[66:69]
	v_mfma_f32_16x16x32_bf16 v[118:121], v[192:195], v[208:211], v[118:121]
	v_mfma_f32_16x16x32_bf16 v[114:117], v[200:203], v[208:211], v[114:117]
	v_mfma_f32_16x16x32_bf16 v[102:105], v[192:195], v[216:219], v[102:105]
	v_mfma_f32_16x16x32_bf16 v[98:101], v[200:203], v[216:219], v[98:101]
	v_mfma_f32_16x16x32_bf16 v[86:89], v[192:195], v[224:227], v[86:89]
	v_mfma_f32_16x16x32_bf16 v[82:85], v[200:203], v[224:227], v[82:85]
	v_mfma_f32_16x16x32_bf16 v[70:73], v[192:195], v[232:235], v[70:73]
	v_mfma_f32_16x16x32_bf16 v[66:69], v[200:203], v[232:235], v[66:69]
	s_barrier
	s_add_u32 s36, s34, 0x8000
	s_addc_u32 s37, s35, 0
	s_add_i32 s61, s61, s40
	s_mov_b32 m0, s61
	ds_read_b128 v[204:207], v170 offset:49152
	ds_read_b128 v[208:211], v170 offset:50176
	ds_read_b128 v[212:215], v170 offset:51200
	ds_read_b128 v[216:219], v170 offset:52224
	ds_read_b128 v[220:223], v170 offset:53248
	ds_read_b128 v[224:227], v170 offset:54272
	ds_read_b128 v[228:231], v170 offset:55296
	ds_read_b128 v[232:235], v170 offset:56320
	global_load_lds_dwordx4 v134, s[36:37]
	s_add_i32 m0, s61, 0x2000
	s_add_u32 s34, s34, 0xc000
	v_lshl_add_u64 v[236:237], s[36:37], 0, v[130:131]
	s_addc_u32 s35, s35, 0
	s_add_i32 s36, s62, s40
	global_load_lds_dwordx4 v[236:237], off
	s_mov_b32 m0, s36
	s_nop 0
	global_load_lds_dwordx4 v134, s[34:35]
	s_add_i32 m0, s36, 0x2000
	s_nop 0
	global_load_lds_dwordx4 v130, s[34:35]
	s_mov_b32 m0, s50
	s_nop 0
	global_load_lds_dwordx4 v136, s[30:31]
	s_mov_b32 m0, s51
	s_nop 0
	global_load_lds_dwordx4 v132, s[30:31]
	s_waitcnt vmcnt(8) lgkmcnt(0)
	s_barrier
	v_mfma_f32_16x16x32_bf16 v[62:65], v[172:175], v[204:207], v[62:65]
	v_mfma_f32_16x16x32_bf16 v[58:61], v[180:183], v[204:207], v[58:61]
	v_mfma_f32_16x16x32_bf16 v[46:49], v[172:175], v[212:215], v[46:49]
	v_mfma_f32_16x16x32_bf16 v[42:45], v[180:183], v[212:215], v[42:45]
	v_mfma_f32_16x16x32_bf16 v[30:33], v[172:175], v[220:223], v[30:33]
	v_mfma_f32_16x16x32_bf16 v[26:29], v[180:183], v[220:223], v[26:29]
	v_mfma_f32_16x16x32_bf16 v[14:17], v[172:175], v[228:231], v[14:17]
	v_mfma_f32_16x16x32_bf16 v[10:13], v[180:183], v[228:231], v[10:13]
	v_mfma_f32_16x16x32_bf16 v[62:65], v[176:179], v[208:211], v[62:65]
	v_mfma_f32_16x16x32_bf16 v[58:61], v[184:187], v[208:211], v[58:61]
	v_mfma_f32_16x16x32_bf16 v[46:49], v[176:179], v[216:219], v[46:49]
	v_mfma_f32_16x16x32_bf16 v[42:45], v[184:187], v[216:219], v[42:45]
	v_mfma_f32_16x16x32_bf16 v[30:33], v[176:179], v[224:227], v[30:33]
	v_mfma_f32_16x16x32_bf16 v[26:29], v[184:187], v[224:227], v[26:29]
	v_mfma_f32_16x16x32_bf16 v[14:17], v[176:179], v[232:235], v[14:17]
	v_mfma_f32_16x16x32_bf16 v[10:13], v[184:187], v[232:235], v[10:13]
	v_mfma_f32_16x16x32_bf16 v[54:57], v[188:191], v[204:207], v[54:57]
	v_mfma_f32_16x16x32_bf16 v[50:53], v[196:199], v[204:207], v[50:53]
	v_mfma_f32_16x16x32_bf16 v[38:41], v[188:191], v[212:215], v[38:41]
	v_mfma_f32_16x16x32_bf16 v[34:37], v[196:199], v[212:215], v[34:37]
	v_mfma_f32_16x16x32_bf16 v[22:25], v[188:191], v[220:223], v[22:25]
	v_mfma_f32_16x16x32_bf16 v[18:21], v[196:199], v[220:223], v[18:21]
	v_mfma_f32_16x16x32_bf16 v[6:9], v[188:191], v[228:231], v[6:9]
	v_mfma_f32_16x16x32_bf16 v[2:5], v[196:199], v[228:231], v[2:5]
	v_mfma_f32_16x16x32_bf16 v[54:57], v[192:195], v[208:211], v[54:57]
	v_mfma_f32_16x16x32_bf16 v[50:53], v[200:203], v[208:211], v[50:53]
	v_mfma_f32_16x16x32_bf16 v[38:41], v[192:195], v[216:219], v[38:41]
	v_mfma_f32_16x16x32_bf16 v[34:37], v[200:203], v[216:219], v[34:37]
	v_mfma_f32_16x16x32_bf16 v[22:25], v[192:195], v[224:227], v[22:25]
	v_mfma_f32_16x16x32_bf16 v[18:21], v[200:203], v[224:227], v[18:21]
	v_mfma_f32_16x16x32_bf16 v[6:9], v[192:195], v[232:235], v[6:9]
	v_mfma_f32_16x16x32_bf16 v[2:5], v[200:203], v[232:235], v[2:5]
	s_barrier
	s_add_i32 s60, s60, 2
	s_add_u32 s28, s28, 0x100
	s_addc_u32 s29, s29, 0
	s_add_u32 s58, s58, 0x10000
	s_addc_u32 s59, s59, 0
	s_cmp_gt_u32 s60, 29
	s_cbranch_scc0 .LBB0_475
	s_and_b64 vcc, exec, s[8:9]
	s_cbranch_vccz .LBB0_478
	s_barrier

; template <class Epi, class Sched, bool ABLK = false, bool ALIGN_EPI = true, bool SP2 = true, bool BBLK = true>
; __device__ __forceinline__ void gemm_phase(LAS unsigned char* lds, const Gemm g, const Sched& S, const Epi& E) {
;     ...
;             const char* a1 = a_tile(uA, tbA + t + 1);
;             const char* a2 = last ? a_tile(nuA, ntbA) : a_tile(uA, tbA + t + 2); const char* b2 = last ? nB : cB + (size_t)(t + 2) * kstepB;
;             const char* a3 = last ? a_tile(nuA, ntbA + 1) : a_tile(uA, tbA + t + 3); const char* b3 = b2 + kstepB;
.Lksel_3:
	s_mov_b32 s31, s57
	s_mov_b32 s30, s23
	s_mov_b32 s35, s11
	s_mov_b32 s34, s13
	s_mov_b32 s37, s4
	s_mov_b32 s36, s5
	s_branch .Lksel_3_back

; #define PG8_STAGE(bufoff, gbase, voff) do { _Pragma("unroll") for (int _i = 0; _i < 2; ++_i) \
;         __builtin_amdgcn_global_load_lds((const unsigned*)((const char*)(gbase) + (voff)[_i]), (LAS unsigned*)(lds + (bufoff) + ldsw + _i * 8192), 16, 0, 0); } while (0)
; #define PG8_LDA(dst, b, h) do { _Pragma("unroll") for (int m = 0; m < 4; ++m) _Pragma("unroll") for (int k = 0; k < 2; ++k) dst[m][k] = *(const LAS bf16x8*)(lds + PG8_SA(b, h) + aoff + m * 2048 + k * 1024); } while (0)
; #define PG8_LDB(dst, b, h) do { _Pragma("unroll") for (int n = 0; n < 2; ++n) _Pragma("unroll") for (int k = 0; k < 2; ++k) dst[n][k] = *(const LAS bf16x8*)(lds + PG8_SB(b, h) + boff + n * 2048 + k * 1024); } while (0)
; #define PG8_WAIT_V(n) asm volatile("s_waitcnt vmcnt(" #n ")" ::: "memory")
; #define PG8_WAIT_L(n) asm volatile("s_waitcnt lgkmcnt(" #n ")" ::: "memory")
; template <class Epi, class Sched, bool ABLK = false, bool ALIGN_EPI = true, bool SP2 = true, bool BBLK = true>
; __device__ __forceinline__ void gemm_phase(LAS unsigned char* lds, const Gemm g, const Sched& S, const Epi& E) {
;     ...
;         const bool has_next = S.next(ui + 1, nxt);
;         const int nt = cur.nt;
;         const char* nuA = has_next ? a_unit(nxt) : uA; const int ntbA = has_next ? nxt.k0 / BK : tbA; const char* nB = has_next ? (const char*)g.Bt + (size_t)nxt.pn * tstepB + b_k0(nxt.k0) : cB;
;         for (int t = 0; t < nt; t += 2) {
;             const bool last = (t == nt - 2);
;             const char* a1 = a_tile(uA, tbA + t + 1);
;             const char* a2 = last ? a_tile(nuA, ntbA) : a_tile(uA, tbA + t + 2); const char* b2 = last ? nB : cB + (size_t)(t + 2) * kstepB;
;             const char* a3 = last ? a_tile(nuA, ntbA + 1) : a_tile(uA, tbA + t + 3); const char* b3 = b2 + kstepB;
;             if (last && has_next) S.a_ready(nxt);
;             if constexpr (SP2) {
;             PG8_LDB(B0, 0, 0); PG8_LDB(B1, 0, 1); PG8_SCHED; PG8_LDA(At, 0, 0); PG8_STAGE(PG8_SA(1, 1), a1 + hstepA, voffA);
;             PG8_WAIT_V(8); PG8_WAIT_L(0); PG8_BAR; PG8_MMA(0, 0, At, B0); PG8_MMA(0, 1, At, B1); PG8_BAR; PG8_SCHED;
;             PG8_LDA(At, 0, 1); PG8_STAGE(PG8_SB(0, 0), b2, voffB); PG8_STAGE(PG8_SB(0, 1), b2 + hstepB, voffB); PG8_STAGE(PG8_SA(0, 0), a2, voffA);
;             PG8_WAIT_V(8); PG8_WAIT_L(0); PG8_BAR; PG8_MMA(1, 0, At, B0); PG8_MMA(1, 1, At, B1); PG8_BAR; PG8_SCHED;
.LBB0_539:
	s_ashr_i32 s81, s80, 31
	s_andn2_b64 vcc, exec, s[4:5]
	s_lshl_b64 s[30:31], s[80:81], 22
	s_add_u32 s30, s1, s30
	s_addc_u32 s31, s33, s31
	s_and_b64 s[34:35], s[4:5], exec
	s_cselect_b32 s47, s31, s43
	s_cselect_b32 s60, s30, s42
	s_ashr_i32 s34, s0, 31
	s_lshr_b32 s34, s34, 26
	s_add_i32 s34, s0, s34
	s_ashr_i32 s34, s34, 6
	s_and_b64 s[36:37], s[4:5], exec
	s_cselect_b32 s48, s34, s46
	s_ashr_i32 s79, s78, 31
	s_lshl_b64 s[36:37], s[78:79], 22
	s_add_u32 s49, s39, s36
	s_addc_u32 s61, s50, s37
	s_ashr_i32 s35, s34, 31
	s_lshl_b64 s[36:37], s[34:35], 15
	s_add_u32 s36, s49, s36
	s_addc_u32 s37, s61, s37
	v_cndmask_b32_e64 v2, 0, 1, s[4:5]
	s_and_b64 s[4:5], s[4:5], exec
	s_cselect_b32 s4, s37, s41
	s_cselect_b32 s5, s36, s40
	s_ashr_i32 s49, s48, 31
	s_lshl_b64 s[48:49], s[48:49], 15
	s_add_u32 s35, s60, s48
	s_addc_u32 s63, s47, s49
	s_add_u32 s64, s35, 0x8000
	s_addc_u32 s65, s63, 0
	s_add_u32 s66, s40, 0x10000
	s_addc_u32 s67, s41, 0
	s_ashr_i32 s47, s46, 31
	v_cmp_ne_u32_e64 s[8:9], 1, v2
	s_lshl_b64 s[40:41], s[46:47], 15
	v_lshl_add_u64 v[2:3], s[42:43], 0, v[138:139]
	s_add_u32 s75, s42, s40
	v_lshl_add_u64 v[142:143], v[2:3], 0, s[40:41]
	v_lshl_add_u64 v[2:3], s[42:43], 0, v[140:141]
	s_addc_u32 s76, s43, s41
	v_lshl_add_u64 v[144:145], v[2:3], 0, s[40:41]
	s_lshl_b32 s40, s59, 15
	s_add_i32 s40, s40, 0xfff00000
	v_mov_b32_e32 v2, 0
	s_add_u32 s77, s40, 0xf0000
	s_mov_b32 s79, 0
	s_mov_b64 s[40:41], 0
	ds_read_b128 v[152:155], v148
	ds_read_b128 v[156:159], v148 offset:1024
	ds_read_b128 v[160:163], v148 offset:2048
	ds_read_b128 v[164:167], v148 offset:3072
	ds_read_b128 v[168:171], v149
	ds_read_b128 v[172:175], v149 offset:1024
	ds_read_b128 v[176:179], v149 offset:2048
	ds_read_b128 v[180:183], v149 offset:3072
	s_add_u32 s42, s75, s40
	s_addc_u32 s43, s76, s41
	s_add_u32 s48, s42, 0x10000
	s_addc_u32 s49, s43, 0
	s_add_i32 s79, s79, 2
	s_add_u32 s46, s66, s40
	s_addc_u32 s47, s67, s41
	s_add_u32 s42, s42, 0x18000
	s_addc_u32 s43, s43, 0
	v_lshl_add_u64 v[216:217], v[142:143], 0, s[40:41]
	s_add_i32 m0, s52, 0xc000
	ds_read_b128 v[184:187], v150
	ds_read_b128 v[188:191], v150 offset:1024
	ds_read_b128 v[192:195], v150 offset:2048
	ds_read_b128 v[196:199], v150 offset:3072
	ds_read_b128 v[200:203], v150 offset:4096
	ds_read_b128 v[204:207], v150 offset:5120
	ds_read_b128 v[208:211], v150 offset:6144
	ds_read_b128 v[212:215], v150 offset:7168
	global_load_lds_dwordx4 v[216:217], off
	v_lshl_add_u64 v[216:217], v[144:145], 0, s[40:41]
	s_add_i32 m0, s52, 0xe000
	s_nop 0
	global_load_lds_dwordx4 v[216:217], off
	s_waitcnt vmcnt(8) lgkmcnt(0)
	s_barrier
	v_mfma_f32_16x16x32_bf16 v[126:129], v[152:155], v[184:187], 0
	v_mfma_f32_16x16x32_bf16 v[122:125], v[160:163], v[184:187], 0
	v_mfma_f32_16x16x32_bf16 v[110:113], v[152:155], v[192:195], 0
	v_mfma_f32_16x16x32_bf16 v[106:109], v[160:163], v[192:195], 0
	v_mfma_f32_16x16x32_bf16 v[94:97], v[152:155], v[200:203], 0
	v_mfma_f32_16x16x32_bf16 v[90:93], v[160:163], v[200:203], 0
	v_mfma_f32_16x16x32_bf16 v[78:81], v[152:155], v[208:211], 0
	v_mfma_f32_16x16x32_bf16 v[74:77], v[160:163], v[208:211], 0
	v_mfma_f32_16x16x32_bf16 v[126:129], v[156:159], v[188:191], v[126:129]
	v_mfma_f32_16x16x32_bf16 v[122:125], v[164:167], v[188:191], v[122:125]
	v_mfma_f32_16x16x32_bf16 v[110:113], v[156:159], v[196:199], v[110:113]
	v_mfma_f32_16x16x32_bf16 v[106:109], v[164:167], v[196:199], v[106:109]
	v_mfma_f32_16x16x32_bf16 v[94:97], v[156:159], v[204:207], v[94:97]
	v_mfma_f32_16x16x32_bf16 v[90:93], v[164:167], v[204:207], v[90:93]
	v_mfma_f32_16x16x32_bf16 v[78:81], v[156:159], v[212:215], v[78:81]
	v_mfma_f32_16x16x32_bf16 v[74:77], v[164:167], v[212:215], v[74:77]
	v_mfma_f32_16x16x32_bf16 v[118:121], v[168:171], v[184:187], 0
	v_mfma_f32_16x16x32_bf16 v[114:117], v[176:179], v[184:187], 0
	v_mfma_f32_16x16x32_bf16 v[102:105], v[168:171], v[192:195], 0
	v_mfma_f32_16x16x32_bf16 v[98:101], v[176:179], v[192:195], 0
	v_mfma_f32_16x16x32_bf16 v[86:89], v[168:171], v[200:203], 0
	v_mfma_f32_16x16x32_bf16 v[82:85], v[176:179], v[200:203], 0
	v_mfma_f32_16x16x32_bf16 v[70:73], v[168:171], v[208:211], 0
	v_mfma_f32_16x16x32_bf16 v[66:69], v[176:179], v[208:211], 0
	v_mfma_f32_16x16x32_bf16 v[118:121], v[172:175], v[188:191], v[118:121]
	v_mfma_f32_16x16x32_bf16 v[114:117], v[180:183], v[188:191], v[114:117]
	v_mfma_f32_16x16x32_bf16 v[102:105], v[172:175], v[196:199], v[102:105]
	v_mfma_f32_16x16x32_bf16 v[98:101], v[180:183], v[196:199], v[98:101]
	v_mfma_f32_16x16x32_bf16 v[86:89], v[172:175], v[204:207], v[86:89]
	v_mfma_f32_16x16x32_bf16 v[82:85], v[180:183], v[204:207], v[82:85]
	v_mfma_f32_16x16x32_bf16 v[70:73], v[172:175], v[212:215], v[70:73]
	v_mfma_f32_16x16x32_bf16 v[66:69], v[180:183], v[212:215], v[66:69]
	s_barrier
	s_add_i32 s60, s72, s51
	s_mov_b32 m0, s60
	ds_read_b128 v[184:187], v150 offset:16384
	ds_read_b128 v[188:191], v150 offset:17408
	ds_read_b128 v[192:195], v150 offset:18432
	ds_read_b128 v[196:199], v150 offset:19456
	ds_read_b128 v[200:203], v150 offset:20480
	ds_read_b128 v[204:207], v150 offset:21504
	ds_read_b128 v[208:211], v150 offset:22528
	ds_read_b128 v[212:215], v150 offset:23552
	global_load_lds_dwordx4 v130, s[46:47]
	s_add_i32 m0, s60, 0x2000
	s_add_u32 s60, s46, 0x4000
	s_addc_u32 s61, s47, 0
	s_add_i32 s81, s73, s51
	global_load_lds_dwordx4 v132, s[46:47]
	s_mov_b32 m0, s81
	s_nop 0
	global_load_lds_dwordx4 v130, s[60:61]
	s_add_i32 m0, s81, 0x2000
	s_nop 0
	global_load_lds_dwordx4 v132, s[60:61]
	s_mov_b32 m0, s52
	s_nop 0
	global_load_lds_dwordx4 v130, s[48:49]
	s_mov_b32 m0, s53
	s_nop 0
	global_load_lds_dwordx4 v132, s[48:49]
	s_waitcnt vmcnt(8) lgkmcnt(0)
	s_barrier
; #define PG8_STAGE(bufoff, gbase, voff) do { _Pragma("unroll") for (int _i = 0; _i < 2; ++_i) \
;         __builtin_amdgcn_global_load_lds((const unsigned*)((const char*)(gbase) + (voff)[_i]), (LAS unsigned*)(lds + (bufoff) + ldsw + _i * 8192), 16, 0, 0); } while (0)
; #define PG8_LDA(dst, b, h) do { _Pragma("unroll") for (int m = 0; m < 4; ++m) _Pragma("unroll") for (int k = 0; k < 2; ++k) dst[m][k] = *(const LAS bf16x8*)(lds + PG8_SA(b, h) + aoff + m * 2048 + k * 1024); } while (0)
; #define PG8_LDB(dst, b, h) do { _Pragma("unroll") for (int n = 0; n < 2; ++n) _Pragma("unroll") for (int k = 0; k < 2; ++k) dst[n][k] = *(const LAS bf16x8*)(lds + PG8_SB(b, h) + boff + n * 2048 + k * 1024); } while (0)
; #define PG8_MMA(ai, bj, At, Bt) do { __builtin_amdgcn_s_setprio(1); _Pragma("unroll") for (int m = 0; m < 4; ++m) _Pragma("unroll") for (int n = 0; n < 2; ++n) _Pragma("unroll") for (int k = 0; k < 2; ++k) \
;         acc[ai][bj][m][n] = __builtin_amdgcn_mfma_f32_16x16x32_bf16(Bt[n][k], At[m][k], acc[ai][bj][m][n], 0, 0, 0); __builtin_amdgcn_s_setprio(0); } while (0)
; #define PG8_WAIT_V(n) asm volatile("s_waitcnt vmcnt(" #n ")" ::: "memory")
; #define PG8_WAIT_L(n) asm volatile("s_waitcnt lgkmcnt(" #n ")" ::: "memory")
; #define PG8_BAR __builtin_amdgcn_s_barrier()
; #define PG8_SCHED __builtin_amdgcn_sched_barrier(0)
; template <class Epi, class Sched, bool ABLK = false, bool ALIGN_EPI = true, bool SP2 = true, bool BBLK = true>
; __device__ __forceinline__ void gemm_phase(LAS unsigned char* lds, const Gemm g, const Sched& S, const Epi& E) {
;     ...
;             PG8_WAIT_V(8); PG8_WAIT_L(0); PG8_BAR; PG8_MMA(1, 0, At, B0); PG8_MMA(1, 1, At, B1); PG8_BAR; PG8_SCHED;
;             PG8_LDB(B0, 1, 0); PG8_LDB(B1, 1, 1); PG8_SCHED; PG8_LDA(At, 1, 0); PG8_STAGE(PG8_SA(0, 1), a2 + hstepA, voffA);
;             PG8_WAIT_V(8); PG8_WAIT_L(0); PG8_BAR; PG8_MMA(0, 0, At, B0); PG8_MMA(0, 1, At, B1); PG8_BAR; PG8_SCHED;
;             PG8_LDA(At, 1, 1); PG8_STAGE(PG8_SB(1, 0), b3, voffB); PG8_STAGE(PG8_SB(1, 1), b3 + hstepB, voffB); PG8_STAGE(PG8_SA(1, 0), a3, voffA);
	v_mfma_f32_16x16x32_bf16 v[62:65], v[152:155], v[184:187], 0
	v_mfma_f32_16x16x32_bf16 v[58:61], v[160:163], v[184:187], 0
	v_mfma_f32_16x16x32_bf16 v[46:49], v[152:155], v[192:195], 0
	v_mfma_f32_16x16x32_bf16 v[42:45], v[160:163], v[192:195], 0
	v_mfma_f32_16x16x32_bf16 v[30:33], v[152:155], v[200:203], 0
	v_mfma_f32_16x16x32_bf16 v[26:29], v[160:163], v[200:203], 0
	v_mfma_f32_16x16x32_bf16 v[14:17], v[152:155], v[208:211], 0
	v_mfma_f32_16x16x32_bf16 v[10:13], v[160:163], v[208:211], 0
	v_mfma_f32_16x16x32_bf16 v[62:65], v[156:159], v[188:191], v[62:65]
	v_mfma_f32_16x16x32_bf16 v[58:61], v[164:167], v[188:191], v[58:61]
	v_mfma_f32_16x16x32_bf16 v[46:49], v[156:159], v[196:199], v[46:49]
	v_mfma_f32_16x16x32_bf16 v[42:45], v[164:167], v[196:199], v[42:45]
	v_mfma_f32_16x16x32_bf16 v[30:33], v[156:159], v[204:207], v[30:33]
	v_mfma_f32_16x16x32_bf16 v[26:29], v[164:167], v[204:207], v[26:29]
	v_mfma_f32_16x16x32_bf16 v[14:17], v[156:159], v[212:215], v[14:17]
	v_mfma_f32_16x16x32_bf16 v[10:13], v[164:167], v[212:215], v[10:13]
	v_mfma_f32_16x16x32_bf16 v[54:57], v[168:171], v[184:187], 0
	v_mfma_f32_16x16x32_bf16 v[50:53], v[176:179], v[184:187], 0
	v_mfma_f32_16x16x32_bf16 v[38:41], v[168:171], v[192:195], 0
	v_mfma_f32_16x16x32_bf16 v[34:37], v[176:179], v[192:195], 0
	v_mfma_f32_16x16x32_bf16 v[22:25], v[168:171], v[200:203], 0
	v_mfma_f32_16x16x32_bf16 v[18:21], v[176:179], v[200:203], 0
	v_mfma_f32_16x16x32_bf16 v[6:9], v[168:171], v[208:211], 0
	v_mfma_f32_16x16x32_bf16 v[2:5], v[176:179], v[208:211], 0
	v_mfma_f32_16x16x32_bf16 v[54:57], v[172:175], v[188:191], v[54:57]
	v_mfma_f32_16x16x32_bf16 v[50:53], v[180:183], v[188:191], v[50:53]
	v_mfma_f32_16x16x32_bf16 v[38:41], v[172:175], v[196:199], v[38:41]
	v_mfma_f32_16x16x32_bf16 v[34:37], v[180:183], v[196:199], v[34:37]
	v_mfma_f32_16x16x32_bf16 v[22:25], v[172:175], v[204:207], v[22:25]
	v_mfma_f32_16x16x32_bf16 v[18:21], v[180:183], v[204:207], v[18:21]
	v_mfma_f32_16x16x32_bf16 v[6:9], v[172:175], v[212:215], v[6:9]
	v_mfma_f32_16x16x32_bf16 v[2:5], v[180:183], v[212:215], v[2:5]
	s_barrier
	s_add_i32 s60, 0, 0x18000
	v_add_u32_e32 v151, s60, v146
	s_add_i32 s61, 0, 0x1c000
	ds_read_b128 v[152:155], v151
	ds_read_b128 v[156:159], v151 offset:1024
	ds_read_b128 v[160:163], v151 offset:2048
	ds_read_b128 v[164:167], v151 offset:3072
	v_add_u32_e32 v151, s61, v146
	ds_read_b128 v[168:171], v151
	ds_read_b128 v[172:175], v151 offset:1024
	ds_read_b128 v[176:179], v151 offset:2048
	ds_read_b128 v[180:183], v151 offset:3072
	s_add_u32 s48, s48, 0x4000
	s_addc_u32 s49, s49, 0
	s_mov_b32 m0, s54
	ds_read_b128 v[184:187], v150 offset:32768
	ds_read_b128 v[188:191], v150 offset:33792
	ds_read_b128 v[192:195], v150 offset:34816
	ds_read_b128 v[196:199], v150 offset:35840
	ds_read_b128 v[200:203], v150 offset:36864
	ds_read_b128 v[204:207], v150 offset:37888
	ds_read_b128 v[208:211], v150 offset:38912
	ds_read_b128 v[212:215], v150 offset:39936
	global_load_lds_dwordx4 v130, s[48:49]
	s_mov_b32 m0, s55
	s_nop 0
	global_load_lds_dwordx4 v132, s[48:49]
	s_waitcnt vmcnt(8) lgkmcnt(0)
	s_barrier
	v_mfma_f32_16x16x32_bf16 v[126:129], v[152:155], v[184:187], v[126:129]
	v_mfma_f32_16x16x32_bf16 v[122:125], v[160:163], v[184:187], v[122:125]
	v_mfma_f32_16x16x32_bf16 v[110:113], v[152:155], v[192:195], v[110:113]
	v_mfma_f32_16x16x32_bf16 v[106:109], v[160:163], v[192:195], v[106:109]
	v_mfma_f32_16x16x32_bf16 v[94:97], v[152:155], v[200:203], v[94:97]
	v_mfma_f32_16x16x32_bf16 v[90:93], v[160:163], v[200:203], v[90:93]
	v_mfma_f32_16x16x32_bf16 v[78:81], v[152:155], v[208:211], v[78:81]
	v_mfma_f32_16x16x32_bf16 v[74:77], v[160:163], v[208:211], v[74:77]
	v_mfma_f32_16x16x32_bf16 v[126:129], v[156:159], v[188:191], v[126:129]
	v_mfma_f32_16x16x32_bf16 v[122:125], v[164:167], v[188:191], v[122:125]
	v_mfma_f32_16x16x32_bf16 v[110:113], v[156:159], v[196:199], v[110:113]
	v_mfma_f32_16x16x32_bf16 v[106:109], v[164:167], v[196:199], v[106:109]
	v_mfma_f32_16x16x32_bf16 v[94:97], v[156:159], v[204:207], v[94:97]
	v_mfma_f32_16x16x32_bf16 v[90:93], v[164:167], v[204:207], v[90:93]
	v_mfma_f32_16x16x32_bf16 v[78:81], v[156:159], v[212:215], v[78:81]
	v_mfma_f32_16x16x32_bf16 v[74:77], v[164:167], v[212:215], v[74:77]
	v_mfma_f32_16x16x32_bf16 v[118:121], v[168:171], v[184:187], v[118:121]
	v_mfma_f32_16x16x32_bf16 v[114:117], v[176:179], v[184:187], v[114:117]
	v_mfma_f32_16x16x32_bf16 v[102:105], v[168:171], v[192:195], v[102:105]
	v_mfma_f32_16x16x32_bf16 v[98:101], v[176:179], v[192:195], v[98:101]
	v_mfma_f32_16x16x32_bf16 v[86:89], v[168:171], v[200:203], v[86:89]
	v_mfma_f32_16x16x32_bf16 v[82:85], v[176:179], v[200:203], v[82:85]
	v_mfma_f32_16x16x32_bf16 v[70:73], v[168:171], v[208:211], v[70:73]
	v_mfma_f32_16x16x32_bf16 v[66:69], v[176:179], v[208:211], v[66:69]
	v_mfma_f32_16x16x32_bf16 v[118:121], v[172:175], v[188:191], v[118:121]
	v_mfma_f32_16x16x32_bf16 v[114:117], v[180:183], v[188:191], v[114:117]
	v_mfma_f32_16x16x32_bf16 v[102:105], v[172:175], v[196:199], v[102:105]
	v_mfma_f32_16x16x32_bf16 v[98:101], v[180:183], v[196:199], v[98:101]
	v_mfma_f32_16x16x32_bf16 v[86:89], v[172:175], v[204:207], v[86:89]
	v_mfma_f32_16x16x32_bf16 v[82:85], v[180:183], v[204:207], v[82:85]
	v_mfma_f32_16x16x32_bf16 v[70:73], v[172:175], v[212:215], v[70:73]
	v_mfma_f32_16x16x32_bf16 v[66:69], v[180:183], v[212:215], v[66:69]
	s_barrier
; #define PG8_STAGE(bufoff, gbase, voff) do { _Pragma("unroll") for (int _i = 0; _i < 2; ++_i) \
;         __builtin_amdgcn_global_load_lds((const unsigned*)((const char*)(gbase) + (voff)[_i]), (LAS unsigned*)(lds + (bufoff) + ldsw + _i * 8192), 16, 0, 0); } while (0)
; #define PG8_LDA(dst, b, h) do { _Pragma("unroll") for (int m = 0; m < 4; ++m) _Pragma("unroll") for (int k = 0; k < 2; ++k) dst[m][k] = *(const LAS bf16x8*)(lds + PG8_SA(b, h) + aoff + m * 2048 + k * 1024); } while (0)
; #define PG8_WAIT_V(n) asm volatile("s_waitcnt vmcnt(" #n ")" ::: "memory")
; #define PG8_WAIT_L(n) asm volatile("s_waitcnt lgkmcnt(" #n ")" ::: "memory")
; template <class Epi, class Sched, bool ABLK = false, bool ALIGN_EPI = true, bool SP2 = true, bool BBLK = true>
; __device__ __forceinline__ void gemm_phase(LAS unsigned char* lds, const Gemm g, const Sched& S, const Epi& E) {
;     ...
;         for (int t = 0; t < nt; t += 2) {
;             const bool last = (t == nt - 2);
;             const char* a1 = a_tile(uA, tbA + t + 1);
;             const char* a2 = last ? a_tile(nuA, ntbA) : a_tile(uA, tbA + t + 2); const char* b2 = last ? nB : cB + (size_t)(t + 2) * kstepB;
;             const char* a3 = last ? a_tile(nuA, ntbA + 1) : a_tile(uA, tbA + t + 3); const char* b3 = b2 + kstepB;
;             if (last && has_next) S.a_ready(nxt);
;             if constexpr (SP2) {
;             PG8_LDB(B0, 0, 0); PG8_LDB(B1, 0, 1); PG8_SCHED; PG8_LDA(At, 0, 0); PG8_STAGE(PG8_SA(1, 1), a1 + hstepA, voffA);
;             PG8_WAIT_V(8); PG8_WAIT_L(0); PG8_BAR; PG8_MMA(0, 0, At, B0); PG8_MMA(0, 1, At, B1); PG8_BAR; PG8_SCHED;
;             PG8_LDA(At, 0, 1); PG8_STAGE(PG8_SB(0, 0), b2, voffB); PG8_STAGE(PG8_SB(0, 1), b2 + hstepB, voffB); PG8_STAGE(PG8_SA(0, 0), a2, voffA);
;             PG8_WAIT_V(8); PG8_WAIT_L(0); PG8_BAR; PG8_MMA(1, 0, At, B0); PG8_MMA(1, 1, At, B1); PG8_BAR; PG8_SCHED;
;             PG8_LDB(B0, 1, 0); PG8_LDB(B1, 1, 1); PG8_SCHED; PG8_LDA(At, 1, 0); PG8_STAGE(PG8_SA(0, 1), a2 + hstepA, voffA);
;             PG8_WAIT_V(8); PG8_WAIT_L(0); PG8_BAR; PG8_MMA(0, 0, At, B0); PG8_MMA(0, 1, At, B1); PG8_BAR; PG8_SCHED;
;             PG8_LDA(At, 1, 1); PG8_STAGE(PG8_SB(1, 0), b3, voffB); PG8_STAGE(PG8_SB(1, 1), b3 + hstepB, voffB); PG8_STAGE(PG8_SA(1, 0), a3, voffA);
;             PG8_WAIT_V(8); PG8_WAIT_L(0); PG8_BAR; PG8_MMA(1, 0, At, B0); PG8_MMA(1, 1, At, B1); PG8_BAR; PG8_SCHED;
	s_add_u32 s48, s46, 0x8000
	s_addc_u32 s49, s47, 0
	s_add_i32 s81, s60, s51
	s_mov_b32 m0, s81
	ds_read_b128 v[184:187], v150 offset:49152
	ds_read_b128 v[188:191], v150 offset:50176
	ds_read_b128 v[192:195], v150 offset:51200
	ds_read_b128 v[196:199], v150 offset:52224
	ds_read_b128 v[200:203], v150 offset:53248
	ds_read_b128 v[204:207], v150 offset:54272
	ds_read_b128 v[208:211], v150 offset:55296
	ds_read_b128 v[212:215], v150 offset:56320
	global_load_lds_dwordx4 v130, s[48:49]
	s_add_i32 m0, s81, 0x2000
	s_add_u32 s46, s46, 0xc000
	v_lshl_add_u64 v[216:217], s[48:49], 0, v[132:133]
	s_addc_u32 s47, s47, 0
	s_add_i32 s48, s61, s51
	global_load_lds_dwordx4 v[216:217], off
	s_mov_b32 m0, s48
	s_nop 0
	global_load_lds_dwordx4 v130, s[46:47]
	s_add_i32 m0, s48, 0x2000
	s_nop 0
	global_load_lds_dwordx4 v132, s[46:47]
	s_mov_b32 m0, s56
	s_nop 0
	global_load_lds_dwordx4 v130, s[42:43]
	s_mov_b32 m0, s57
	s_nop 0
	global_load_lds_dwordx4 v132, s[42:43]
	s_waitcnt vmcnt(8) lgkmcnt(0)
	s_barrier
	v_mfma_f32_16x16x32_bf16 v[62:65], v[152:155], v[184:187], v[62:65]
	v_mfma_f32_16x16x32_bf16 v[58:61], v[160:163], v[184:187], v[58:61]
	v_mfma_f32_16x16x32_bf16 v[46:49], v[152:155], v[192:195], v[46:49]
	v_mfma_f32_16x16x32_bf16 v[42:45], v[160:163], v[192:195], v[42:45]
	v_mfma_f32_16x16x32_bf16 v[30:33], v[152:155], v[200:203], v[30:33]
	v_mfma_f32_16x16x32_bf16 v[26:29], v[160:163], v[200:203], v[26:29]
	v_mfma_f32_16x16x32_bf16 v[14:17], v[152:155], v[208:211], v[14:17]
	v_mfma_f32_16x16x32_bf16 v[10:13], v[160:163], v[208:211], v[10:13]
	v_mfma_f32_16x16x32_bf16 v[62:65], v[156:159], v[188:191], v[62:65]
	v_mfma_f32_16x16x32_bf16 v[58:61], v[164:167], v[188:191], v[58:61]
	v_mfma_f32_16x16x32_bf16 v[46:49], v[156:159], v[196:199], v[46:49]
	v_mfma_f32_16x16x32_bf16 v[42:45], v[164:167], v[196:199], v[42:45]
	v_mfma_f32_16x16x32_bf16 v[30:33], v[156:159], v[204:207], v[30:33]
	v_mfma_f32_16x16x32_bf16 v[26:29], v[164:167], v[204:207], v[26:29]
	v_mfma_f32_16x16x32_bf16 v[14:17], v[156:159], v[212:215], v[14:17]
	v_mfma_f32_16x16x32_bf16 v[10:13], v[164:167], v[212:215], v[10:13]
	v_mfma_f32_16x16x32_bf16 v[54:57], v[168:171], v[184:187], v[54:57]
	v_mfma_f32_16x16x32_bf16 v[50:53], v[176:179], v[184:187], v[50:53]
	v_mfma_f32_16x16x32_bf16 v[38:41], v[168:171], v[192:195], v[38:41]
	v_mfma_f32_16x16x32_bf16 v[34:37], v[176:179], v[192:195], v[34:37]
	v_mfma_f32_16x16x32_bf16 v[22:25], v[168:171], v[200:203], v[22:25]
	v_mfma_f32_16x16x32_bf16 v[18:21], v[176:179], v[200:203], v[18:21]
	v_mfma_f32_16x16x32_bf16 v[6:9], v[168:171], v[208:211], v[6:9]
	v_mfma_f32_16x16x32_bf16 v[2:5], v[176:179], v[208:211], v[2:5]
	v_mfma_f32_16x16x32_bf16 v[54:57], v[172:175], v[188:191], v[54:57]
	v_mfma_f32_16x16x32_bf16 v[50:53], v[180:183], v[188:191], v[50:53]
	v_mfma_f32_16x16x32_bf16 v[38:41], v[172:175], v[196:199], v[38:41]
	v_mfma_f32_16x16x32_bf16 v[34:37], v[180:183], v[196:199], v[34:37]
	v_mfma_f32_16x16x32_bf16 v[22:25], v[172:175], v[204:207], v[22:25]
	v_mfma_f32_16x16x32_bf16 v[18:21], v[180:183], v[204:207], v[18:21]
	v_mfma_f32_16x16x32_bf16 v[6:9], v[172:175], v[212:215], v[6:9]
	v_mfma_f32_16x16x32_bf16 v[2:5], v[180:183], v[212:215], v[2:5]
	s_barrier
	s_add_u32 s40, s40, 0x10000
	s_addc_u32 s41, s41, 0
	s_cmp_ge_u32 s79, s59
.LBB0_540:
	ds_read_b128 v[152:155], v148
	ds_read_b128 v[156:159], v148 offset:1024
	ds_read_b128 v[160:163], v148 offset:2048
	ds_read_b128 v[164:167], v148 offset:3072
	ds_read_b128 v[168:171], v149
	ds_read_b128 v[172:175], v149 offset:1024
	ds_read_b128 v[176:179], v149 offset:2048
	ds_read_b128 v[180:183], v149 offset:3072
	s_add_u32 s42, s75, s40
	s_addc_u32 s43, s76, s41
	s_add_u32 s48, s42, 0x10000
	s_addc_u32 s49, s43, 0
	s_add_i32 s79, s79, 2
	s_add_u32 s46, s66, s40
	s_addc_u32 s47, s67, s41
	s_add_u32 s42, s42, 0x18000
	s_addc_u32 s43, s43, 0
	s_cmp_eq_u32 s77, s40
	s_cbranch_scc1 .Lksel_5
.Lksel_5_back:
	v_lshl_add_u64 v[216:217], v[142:143], 0, s[40:41]
	s_add_i32 m0, s52, 0xc000
	ds_read_b128 v[184:187], v150
	ds_read_b128 v[188:191], v150 offset:1024
	ds_read_b128 v[192:195], v150 offset:2048
	ds_read_b128 v[196:199], v150 offset:3072
	ds_read_b128 v[200:203], v150 offset:4096
	ds_read_b128 v[204:207], v150 offset:5120
	ds_read_b128 v[208:211], v150 offset:6144
	ds_read_b128 v[212:215], v150 offset:7168
	global_load_lds_dwordx4 v[216:217], off
	v_lshl_add_u64 v[216:217], v[144:145], 0, s[40:41]
	s_add_i32 m0, s52, 0xe000
	s_nop 0
	global_load_lds_dwordx4 v[216:217], off
	s_waitcnt vmcnt(8) lgkmcnt(0)
	s_barrier
; #define PG8_STAGE(bufoff, gbase, voff) do { _Pragma("unroll") for (int _i = 0; _i < 2; ++_i) \
;         __builtin_amdgcn_global_load_lds((const unsigned*)((const char*)(gbase) + (voff)[_i]), (LAS unsigned*)(lds + (bufoff) + ldsw + _i * 8192), 16, 0, 0); } while (0)
; #define PG8_LDA(dst, b, h) do { _Pragma("unroll") for (int m = 0; m < 4; ++m) _Pragma("unroll") for (int k = 0; k < 2; ++k) dst[m][k] = *(const LAS bf16x8*)(lds + PG8_SA(b, h) + aoff + m * 2048 + k * 1024); } while (0)
; #define PG8_LDB(dst, b, h) do { _Pragma("unroll") for (int n = 0; n < 2; ++n) _Pragma("unroll") for (int k = 0; k < 2; ++k) dst[n][k] = *(const LAS bf16x8*)(lds + PG8_SB(b, h) + boff + n * 2048 + k * 1024); } while (0)
; #define PG8_MMA(ai, bj, At, Bt) do { __builtin_amdgcn_s_setprio(1); _Pragma("unroll") for (int m = 0; m < 4; ++m) _Pragma("unroll") for (int n = 0; n < 2; ++n) _Pragma("unroll") for (int k = 0; k < 2; ++k) \
;         acc[ai][bj][m][n] = __builtin_amdgcn_mfma_f32_16x16x32_bf16(Bt[n][k], At[m][k], acc[ai][bj][m][n], 0, 0, 0); __builtin_amdgcn_s_setprio(0); } while (0)
; #define PG8_WAIT_V(n) asm volatile("s_waitcnt vmcnt(" #n ")" ::: "memory")
; #define PG8_WAIT_L(n) asm volatile("s_waitcnt lgkmcnt(" #n ")" ::: "memory")
; #define PG8_BAR __builtin_amdgcn_s_barrier()
; #define PG8_SCHED __builtin_amdgcn_sched_barrier(0)
; template <class Epi, class Sched, bool ABLK = false, bool ALIGN_EPI = true, bool SP2 = true, bool BBLK = true>
; __device__ __forceinline__ void gemm_phase(LAS unsigned char* lds, const Gemm g, const Sched& S, const Epi& E) {
;     ...
;             PG8_LDB(B0, 0, 0); PG8_LDB(B1, 0, 1); PG8_SCHED; PG8_LDA(At, 0, 0); PG8_STAGE(PG8_SA(1, 1), a1 + hstepA, voffA);
;             PG8_WAIT_V(8); PG8_WAIT_L(0); PG8_BAR; PG8_MMA(0, 0, At, B0); PG8_MMA(0, 1, At, B1); PG8_BAR; PG8_SCHED;
;             PG8_LDA(At, 0, 1); PG8_STAGE(PG8_SB(0, 0), b2, voffB); PG8_STAGE(PG8_SB(0, 1), b2 + hstepB, voffB); PG8_STAGE(PG8_SA(0, 0), a2, voffA);
;             PG8_WAIT_V(8); PG8_WAIT_L(0); PG8_BAR; PG8_MMA(1, 0, At, B0); PG8_MMA(1, 1, At, B1); PG8_BAR; PG8_SCHED;
;             PG8_LDB(B0, 1, 0); PG8_LDB(B1, 1, 1); PG8_SCHED; PG8_LDA(At, 1, 0); PG8_STAGE(PG8_SA(0, 1), a2 + hstepA, voffA);
;             PG8_WAIT_V(8); PG8_WAIT_L(0); PG8_BAR; PG8_MMA(0, 0, At, B0); PG8_MMA(0, 1, At, B1); PG8_BAR; PG8_SCHED;
	v_mfma_f32_16x16x32_bf16 v[126:129], v[152:155], v[184:187], v[126:129]
	v_mfma_f32_16x16x32_bf16 v[122:125], v[160:163], v[184:187], v[122:125]
	v_mfma_f32_16x16x32_bf16 v[110:113], v[152:155], v[192:195], v[110:113]
	v_mfma_f32_16x16x32_bf16 v[106:109], v[160:163], v[192:195], v[106:109]
	v_mfma_f32_16x16x32_bf16 v[94:97], v[152:155], v[200:203], v[94:97]
	v_mfma_f32_16x16x32_bf16 v[90:93], v[160:163], v[200:203], v[90:93]
	v_mfma_f32_16x16x32_bf16 v[78:81], v[152:155], v[208:211], v[78:81]
	v_mfma_f32_16x16x32_bf16 v[74:77], v[160:163], v[208:211], v[74:77]
	v_mfma_f32_16x16x32_bf16 v[126:129], v[156:159], v[188:191], v[126:129]
	v_mfma_f32_16x16x32_bf16 v[122:125], v[164:167], v[188:191], v[122:125]
	v_mfma_f32_16x16x32_bf16 v[110:113], v[156:159], v[196:199], v[110:113]
	v_mfma_f32_16x16x32_bf16 v[106:109], v[164:167], v[196:199], v[106:109]
	v_mfma_f32_16x16x32_bf16 v[94:97], v[156:159], v[204:207], v[94:97]
	v_mfma_f32_16x16x32_bf16 v[90:93], v[164:167], v[204:207], v[90:93]
	v_mfma_f32_16x16x32_bf16 v[78:81], v[156:159], v[212:215], v[78:81]
	v_mfma_f32_16x16x32_bf16 v[74:77], v[164:167], v[212:215], v[74:77]
	v_mfma_f32_16x16x32_bf16 v[118:121], v[168:171], v[184:187], v[118:121]
	v_mfma_f32_16x16x32_bf16 v[114:117], v[176:179], v[184:187], v[114:117]
	v_mfma_f32_16x16x32_bf16 v[102:105], v[168:171], v[192:195], v[102:105]
	v_mfma_f32_16x16x32_bf16 v[98:101], v[176:179], v[192:195], v[98:101]
	v_mfma_f32_16x16x32_bf16 v[86:89], v[168:171], v[200:203], v[86:89]
	v_mfma_f32_16x16x32_bf16 v[82:85], v[176:179], v[200:203], v[82:85]
	v_mfma_f32_16x16x32_bf16 v[70:73], v[168:171], v[208:211], v[70:73]
	v_mfma_f32_16x16x32_bf16 v[66:69], v[176:179], v[208:211], v[66:69]
	v_mfma_f32_16x16x32_bf16 v[118:121], v[172:175], v[188:191], v[118:121]
	v_mfma_f32_16x16x32_bf16 v[114:117], v[180:183], v[188:191], v[114:117]
	v_mfma_f32_16x16x32_bf16 v[102:105], v[172:175], v[196:199], v[102:105]
	v_mfma_f32_16x16x32_bf16 v[98:101], v[180:183], v[196:199], v[98:101]
	v_mfma_f32_16x16x32_bf16 v[86:89], v[172:175], v[204:207], v[86:89]
	v_mfma_f32_16x16x32_bf16 v[82:85], v[180:183], v[204:207], v[82:85]
	v_mfma_f32_16x16x32_bf16 v[70:73], v[172:175], v[212:215], v[70:73]
	v_mfma_f32_16x16x32_bf16 v[66:69], v[180:183], v[212:215], v[66:69]
	s_barrier
	s_add_i32 s60, s72, s51
	s_mov_b32 m0, s60
	ds_read_b128 v[184:187], v150 offset:16384
	ds_read_b128 v[188:191], v150 offset:17408
	ds_read_b128 v[192:195], v150 offset:18432
	ds_read_b128 v[196:199], v150 offset:19456
	ds_read_b128 v[200:203], v150 offset:20480
	ds_read_b128 v[204:207], v150 offset:21504
	ds_read_b128 v[208:211], v150 offset:22528
	ds_read_b128 v[212:215], v150 offset:23552
	global_load_lds_dwordx4 v130, s[46:47]
	s_add_i32 m0, s60, 0x2000
	s_add_u32 s60, s46, 0x4000
	s_addc_u32 s61, s47, 0
	s_add_i32 s81, s73, s51
	global_load_lds_dwordx4 v132, s[46:47]
	s_mov_b32 m0, s81
	s_nop 0
	global_load_lds_dwordx4 v130, s[60:61]
	s_add_i32 m0, s81, 0x2000
	s_nop 0
	global_load_lds_dwordx4 v132, s[60:61]
	s_mov_b32 m0, s52
	s_nop 0
	global_load_lds_dwordx4 v130, s[48:49]
	s_mov_b32 m0, s53
	s_nop 0
	global_load_lds_dwordx4 v132, s[48:49]
	s_waitcnt vmcnt(8) lgkmcnt(0)
	s_barrier
	v_mfma_f32_16x16x32_bf16 v[62:65], v[152:155], v[184:187], v[62:65]
	v_mfma_f32_16x16x32_bf16 v[58:61], v[160:163], v[184:187], v[58:61]
	v_mfma_f32_16x16x32_bf16 v[46:49], v[152:155], v[192:195], v[46:49]
	v_mfma_f32_16x16x32_bf16 v[42:45], v[160:163], v[192:195], v[42:45]
	v_mfma_f32_16x16x32_bf16 v[30:33], v[152:155], v[200:203], v[30:33]
	v_mfma_f32_16x16x32_bf16 v[26:29], v[160:163], v[200:203], v[26:29]
	v_mfma_f32_16x16x32_bf16 v[14:17], v[152:155], v[208:211], v[14:17]
	v_mfma_f32_16x16x32_bf16 v[10:13], v[160:163], v[208:211], v[10:13]
	v_mfma_f32_16x16x32_bf16 v[62:65], v[156:159], v[188:191], v[62:65]
	v_mfma_f32_16x16x32_bf16 v[58:61], v[164:167], v[188:191], v[58:61]
	v_mfma_f32_16x16x32_bf16 v[46:49], v[156:159], v[196:199], v[46:49]
	v_mfma_f32_16x16x32_bf16 v[42:45], v[164:167], v[196:199], v[42:45]
	v_mfma_f32_16x16x32_bf16 v[30:33], v[156:159], v[204:207], v[30:33]
	v_mfma_f32_16x16x32_bf16 v[26:29], v[164:167], v[204:207], v[26:29]
	v_mfma_f32_16x16x32_bf16 v[14:17], v[156:159], v[212:215], v[14:17]
	v_mfma_f32_16x16x32_bf16 v[10:13], v[164:167], v[212:215], v[10:13]
	v_mfma_f32_16x16x32_bf16 v[54:57], v[168:171], v[184:187], v[54:57]
	v_mfma_f32_16x16x32_bf16 v[50:53], v[176:179], v[184:187], v[50:53]
	v_mfma_f32_16x16x32_bf16 v[38:41], v[168:171], v[192:195], v[38:41]
	v_mfma_f32_16x16x32_bf16 v[34:37], v[176:179], v[192:195], v[34:37]
	v_mfma_f32_16x16x32_bf16 v[22:25], v[168:171], v[200:203], v[22:25]
	v_mfma_f32_16x16x32_bf16 v[18:21], v[176:179], v[200:203], v[18:21]
	v_mfma_f32_16x16x32_bf16 v[6:9], v[168:171], v[208:211], v[6:9]
	v_mfma_f32_16x16x32_bf16 v[2:5], v[176:179], v[208:211], v[2:5]
	v_mfma_f32_16x16x32_bf16 v[54:57], v[172:175], v[188:191], v[54:57]
	v_mfma_f32_16x16x32_bf16 v[50:53], v[180:183], v[188:191], v[50:53]
	v_mfma_f32_16x16x32_bf16 v[38:41], v[172:175], v[196:199], v[38:41]
	v_mfma_f32_16x16x32_bf16 v[34:37], v[180:183], v[196:199], v[34:37]
	v_mfma_f32_16x16x32_bf16 v[22:25], v[172:175], v[204:207], v[22:25]
	v_mfma_f32_16x16x32_bf16 v[18:21], v[180:183], v[204:207], v[18:21]
	v_mfma_f32_16x16x32_bf16 v[6:9], v[172:175], v[212:215], v[6:9]
	v_mfma_f32_16x16x32_bf16 v[2:5], v[180:183], v[212:215], v[2:5]
	s_barrier
; #define PG8_STAGE(bufoff, gbase, voff) do { _Pragma("unroll") for (int _i = 0; _i < 2; ++_i) \
;         __builtin_amdgcn_global_load_lds((const unsigned*)((const char*)(gbase) + (voff)[_i]), (LAS unsigned*)(lds + (bufoff) + ldsw + _i * 8192), 16, 0, 0); } while (0)
; #define PG8_LDA(dst, b, h) do { _Pragma("unroll") for (int m = 0; m < 4; ++m) _Pragma("unroll") for (int k = 0; k < 2; ++k) dst[m][k] = *(const LAS bf16x8*)(lds + PG8_SA(b, h) + aoff + m * 2048 + k * 1024); } while (0)
; #define PG8_LDB(dst, b, h) do { _Pragma("unroll") for (int n = 0; n < 2; ++n) _Pragma("unroll") for (int k = 0; k < 2; ++k) dst[n][k] = *(const LAS bf16x8*)(lds + PG8_SB(b, h) + boff + n * 2048 + k * 1024); } while (0)
; #define PG8_MMA(ai, bj, At, Bt) do { __builtin_amdgcn_s_setprio(1); _Pragma("unroll") for (int m = 0; m < 4; ++m) _Pragma("unroll") for (int n = 0; n < 2; ++n) _Pragma("unroll") for (int k = 0; k < 2; ++k) \
;         acc[ai][bj][m][n] = __builtin_amdgcn_mfma_f32_16x16x32_bf16(Bt[n][k], At[m][k], acc[ai][bj][m][n], 0, 0, 0); __builtin_amdgcn_s_setprio(0); } while (0)
; #define PG8_WAIT_V(n) asm volatile("s_waitcnt vmcnt(" #n ")" ::: "memory")
; #define PG8_WAIT_L(n) asm volatile("s_waitcnt lgkmcnt(" #n ")" ::: "memory")
; #define PG8_BAR __builtin_amdgcn_s_barrier()
; #define PG8_SCHED __builtin_amdgcn_sched_barrier(0)
; template <class Epi, class Sched, bool ABLK = false, bool ALIGN_EPI = true, bool SP2 = true, bool BBLK = true>
; __device__ __forceinline__ void gemm_phase(LAS unsigned char* lds, const Gemm g, const Sched& S, const Epi& E) {
;     ...
;             PG8_LDB(B0, 1, 0); PG8_LDB(B1, 1, 1); PG8_SCHED; PG8_LDA(At, 1, 0); PG8_STAGE(PG8_SA(0, 1), a2 + hstepA, voffA);
;             PG8_WAIT_V(8); PG8_WAIT_L(0); PG8_BAR; PG8_MMA(0, 0, At, B0); PG8_MMA(0, 1, At, B1); PG8_BAR; PG8_SCHED;
;             PG8_LDA(At, 1, 1); PG8_STAGE(PG8_SB(1, 0), b3, voffB); PG8_STAGE(PG8_SB(1, 1), b3 + hstepB, voffB); PG8_STAGE(PG8_SA(1, 0), a3, voffA);
;             PG8_WAIT_V(8); PG8_WAIT_L(0); PG8_BAR; PG8_MMA(1, 0, At, B0); PG8_MMA(1, 1, At, B1); PG8_BAR; PG8_SCHED;
	s_add_i32 s60, 0, 0x18000
	v_add_u32_e32 v151, s60, v146
	s_add_i32 s61, 0, 0x1c000
	ds_read_b128 v[152:155], v151
	ds_read_b128 v[156:159], v151 offset:1024
	ds_read_b128 v[160:163], v151 offset:2048
	ds_read_b128 v[164:167], v151 offset:3072
	v_add_u32_e32 v151, s61, v146
	ds_read_b128 v[168:171], v151
	ds_read_b128 v[172:175], v151 offset:1024
	ds_read_b128 v[176:179], v151 offset:2048
	ds_read_b128 v[180:183], v151 offset:3072
	s_add_u32 s48, s48, 0x4000
	s_addc_u32 s49, s49, 0
	s_mov_b32 m0, s54
	ds_read_b128 v[184:187], v150 offset:32768
	ds_read_b128 v[188:191], v150 offset:33792
	ds_read_b128 v[192:195], v150 offset:34816
	ds_read_b128 v[196:199], v150 offset:35840
	ds_read_b128 v[200:203], v150 offset:36864
	ds_read_b128 v[204:207], v150 offset:37888
	ds_read_b128 v[208:211], v150 offset:38912
	ds_read_b128 v[212:215], v150 offset:39936
	global_load_lds_dwordx4 v130, s[48:49]
	s_mov_b32 m0, s55
	s_nop 0
	global_load_lds_dwordx4 v132, s[48:49]
	s_waitcnt vmcnt(8) lgkmcnt(0)
	s_barrier
	v_mfma_f32_16x16x32_bf16 v[126:129], v[152:155], v[184:187], v[126:129]
	v_mfma_f32_16x16x32_bf16 v[122:125], v[160:163], v[184:187], v[122:125]
	v_mfma_f32_16x16x32_bf16 v[110:113], v[152:155], v[192:195], v[110:113]
	v_mfma_f32_16x16x32_bf16 v[106:109], v[160:163], v[192:195], v[106:109]
	v_mfma_f32_16x16x32_bf16 v[94:97], v[152:155], v[200:203], v[94:97]
	v_mfma_f32_16x16x32_bf16 v[90:93], v[160:163], v[200:203], v[90:93]
	v_mfma_f32_16x16x32_bf16 v[78:81], v[152:155], v[208:211], v[78:81]
	v_mfma_f32_16x16x32_bf16 v[74:77], v[160:163], v[208:211], v[74:77]
	v_mfma_f32_16x16x32_bf16 v[126:129], v[156:159], v[188:191], v[126:129]
	v_mfma_f32_16x16x32_bf16 v[122:125], v[164:167], v[188:191], v[122:125]
	v_mfma_f32_16x16x32_bf16 v[110:113], v[156:159], v[196:199], v[110:113]
	v_mfma_f32_16x16x32_bf16 v[106:109], v[164:167], v[196:199], v[106:109]
	v_mfma_f32_16x16x32_bf16 v[94:97], v[156:159], v[204:207], v[94:97]
	v_mfma_f32_16x16x32_bf16 v[90:93], v[164:167], v[204:207], v[90:93]
	v_mfma_f32_16x16x32_bf16 v[78:81], v[156:159], v[212:215], v[78:81]
	v_mfma_f32_16x16x32_bf16 v[74:77], v[164:167], v[212:215], v[74:77]
	v_mfma_f32_16x16x32_bf16 v[118:121], v[168:171], v[184:187], v[118:121]
	v_mfma_f32_16x16x32_bf16 v[114:117], v[176:179], v[184:187], v[114:117]
	v_mfma_f32_16x16x32_bf16 v[102:105], v[168:171], v[192:195], v[102:105]
	v_mfma_f32_16x16x32_bf16 v[98:101], v[176:179], v[192:195], v[98:101]
	v_mfma_f32_16x16x32_bf16 v[86:89], v[168:171], v[200:203], v[86:89]
	v_mfma_f32_16x16x32_bf16 v[82:85], v[176:179], v[200:203], v[82:85]
	v_mfma_f32_16x16x32_bf16 v[70:73], v[168:171], v[208:211], v[70:73]
	v_mfma_f32_16x16x32_bf16 v[66:69], v[176:179], v[208:211], v[66:69]
	v_mfma_f32_16x16x32_bf16 v[118:121], v[172:175], v[188:191], v[118:121]
	v_mfma_f32_16x16x32_bf16 v[114:117], v[180:183], v[188:191], v[114:117]
	v_mfma_f32_16x16x32_bf16 v[102:105], v[172:175], v[196:199], v[102:105]
	v_mfma_f32_16x16x32_bf16 v[98:101], v[180:183], v[196:199], v[98:101]
	v_mfma_f32_16x16x32_bf16 v[86:89], v[172:175], v[204:207], v[86:89]
	v_mfma_f32_16x16x32_bf16 v[82:85], v[180:183], v[204:207], v[82:85]
	v_mfma_f32_16x16x32_bf16 v[70:73], v[172:175], v[212:215], v[70:73]
	v_mfma_f32_16x16x32_bf16 v[66:69], v[180:183], v[212:215], v[66:69]
	s_barrier
	s_add_u32 s48, s46, 0x8000
	s_addc_u32 s49, s47, 0
	s_add_i32 s81, s60, s51
	s_mov_b32 m0, s81
	ds_read_b128 v[184:187], v150 offset:49152
	ds_read_b128 v[188:191], v150 offset:50176
	ds_read_b128 v[192:195], v150 offset:51200
	ds_read_b128 v[196:199], v150 offset:52224
	ds_read_b128 v[200:203], v150 offset:53248
	ds_read_b128 v[204:207], v150 offset:54272
	ds_read_b128 v[208:211], v150 offset:55296
	ds_read_b128 v[212:215], v150 offset:56320
	global_load_lds_dwordx4 v130, s[48:49]
	s_add_i32 m0, s81, 0x2000
	s_add_u32 s46, s46, 0xc000
	v_lshl_add_u64 v[216:217], s[48:49], 0, v[132:133]
	s_addc_u32 s47, s47, 0
	s_add_i32 s48, s61, s51
	global_load_lds_dwordx4 v[216:217], off
	s_mov_b32 m0, s48
	s_nop 0
	global_load_lds_dwordx4 v130, s[46:47]
	s_add_i32 m0, s48, 0x2000
	s_nop 0
	global_load_lds_dwordx4 v132, s[46:47]
	s_mov_b32 m0, s56
	s_nop 0
	global_load_lds_dwordx4 v130, s[42:43]
	s_mov_b32 m0, s57
	s_nop 0
	global_load_lds_dwordx4 v132, s[42:43]
	s_waitcnt vmcnt(8) lgkmcnt(0)
	s_barrier
	v_mfma_f32_16x16x32_bf16 v[62:65], v[152:155], v[184:187], v[62:65]
	v_mfma_f32_16x16x32_bf16 v[58:61], v[160:163], v[184:187], v[58:61]
	v_mfma_f32_16x16x32_bf16 v[46:49], v[152:155], v[192:195], v[46:49]
	v_mfma_f32_16x16x32_bf16 v[42:45], v[160:163], v[192:195], v[42:45]
	v_mfma_f32_16x16x32_bf16 v[30:33], v[152:155], v[200:203], v[30:33]
	v_mfma_f32_16x16x32_bf16 v[26:29], v[160:163], v[200:203], v[26:29]
	v_mfma_f32_16x16x32_bf16 v[14:17], v[152:155], v[208:211], v[14:17]
	v_mfma_f32_16x16x32_bf16 v[10:13], v[160:163], v[208:211], v[10:13]
	v_mfma_f32_16x16x32_bf16 v[62:65], v[156:159], v[188:191], v[62:65]
	v_mfma_f32_16x16x32_bf16 v[58:61], v[164:167], v[188:191], v[58:61]
	v_mfma_f32_16x16x32_bf16 v[46:49], v[156:159], v[196:199], v[46:49]
	v_mfma_f32_16x16x32_bf16 v[42:45], v[164:167], v[196:199], v[42:45]
	v_mfma_f32_16x16x32_bf16 v[30:33], v[156:159], v[204:207], v[30:33]
	v_mfma_f32_16x16x32_bf16 v[26:29], v[164:167], v[204:207], v[26:29]
	v_mfma_f32_16x16x32_bf16 v[14:17], v[156:159], v[212:215], v[14:17]
	v_mfma_f32_16x16x32_bf16 v[10:13], v[164:167], v[212:215], v[10:13]
	v_mfma_f32_16x16x32_bf16 v[54:57], v[168:171], v[184:187], v[54:57]
	v_mfma_f32_16x16x32_bf16 v[50:53], v[176:179], v[184:187], v[50:53]
	v_mfma_f32_16x16x32_bf16 v[38:41], v[168:171], v[192:195], v[38:41]
	v_mfma_f32_16x16x32_bf16 v[34:37], v[176:179], v[192:195], v[34:37]
	v_mfma_f32_16x16x32_bf16 v[22:25], v[168:171], v[200:203], v[22:25]
	v_mfma_f32_16x16x32_bf16 v[18:21], v[176:179], v[200:203], v[18:21]
	v_mfma_f32_16x16x32_bf16 v[6:9], v[168:171], v[208:211], v[6:9]
	v_mfma_f32_16x16x32_bf16 v[2:5], v[176:179], v[208:211], v[2:5]
	v_mfma_f32_16x16x32_bf16 v[54:57], v[172:175], v[188:191], v[54:57]
	v_mfma_f32_16x16x32_bf16 v[50:53], v[180:183], v[188:191], v[50:53]
	v_mfma_f32_16x16x32_bf16 v[38:41], v[172:175], v[196:199], v[38:41]
	v_mfma_f32_16x16x32_bf16 v[34:37], v[180:183], v[196:199], v[34:37]
	v_mfma_f32_16x16x32_bf16 v[22:25], v[172:175], v[204:207], v[22:25]
	v_mfma_f32_16x16x32_bf16 v[18:21], v[180:183], v[204:207], v[18:21]
	v_mfma_f32_16x16x32_bf16 v[6:9], v[172:175], v[212:215], v[6:9]
	v_mfma_f32_16x16x32_bf16 v[2:5], v[180:183], v[212:215], v[2:5]
	s_barrier
	s_add_u32 s40, s40, 0x10000
	s_addc_u32 s41, s41, 0
	s_cmp_ge_u32 s79, s59
	s_cbranch_scc0 .LBB0_540
	s_and_b64 vcc, exec, s[12:13]
	s_cbranch_vccz .LBB0_543
	s_barrier

; template <class Epi, class Sched, bool ABLK = false, bool ALIGN_EPI = true, bool SP2 = true, bool BBLK = true>
; __device__ __forceinline__ void gemm_phase(LAS unsigned char* lds, const Gemm g, const Sched& S, const Epi& E) {
;     ...
;             const char* a1 = a_tile(uA, tbA + t + 1);
;             const char* a2 = last ? a_tile(nuA, ntbA) : a_tile(uA, tbA + t + 2); const char* b2 = last ? nB : cB + (size_t)(t + 2) * kstepB;
;             const char* a3 = last ? a_tile(nuA, ntbA + 1) : a_tile(uA, tbA + t + 3); const char* b3 = b2 + kstepB;
.Lksel_5:
	s_mov_b32 s43, s65
	s_mov_b32 s42, s64
	s_mov_b32 s47, s4
	s_mov_b32 s46, s5
	s_mov_b32 s49, s63
	s_mov_b32 s48, s35
	s_branch .Lksel_5_back

; #define PG8_STAGE(bufoff, gbase, voff) do { _Pragma("unroll") for (int _i = 0; _i < 2; ++_i) \
;         __builtin_amdgcn_global_load_lds((const unsigned*)((const char*)(gbase) + (voff)[_i]), (LAS unsigned*)(lds + (bufoff) + ldsw + _i * 8192), 16, 0, 0); } while (0)
; #define PG8_LDA(dst, b, h) do { _Pragma("unroll") for (int m = 0; m < 4; ++m) _Pragma("unroll") for (int k = 0; k < 2; ++k) dst[m][k] = *(const LAS bf16x8*)(lds + PG8_SA(b, h) + aoff + m * 2048 + k * 1024); } while (0)
; #define PG8_LDB(dst, b, h) do { _Pragma("unroll") for (int n = 0; n < 2; ++n) _Pragma("unroll") for (int k = 0; k < 2; ++k) dst[n][k] = *(const LAS bf16x8*)(lds + PG8_SB(b, h) + boff + n * 2048 + k * 1024); } while (0)
; #define PG8_WAIT_V(n) asm volatile("s_waitcnt vmcnt(" #n ")" ::: "memory")
; #define PG8_WAIT_L(n) asm volatile("s_waitcnt lgkmcnt(" #n ")" ::: "memory")
; template <class Epi, class Sched, bool ABLK = false, bool ALIGN_EPI = true, bool SP2 = true, bool BBLK = true>
; __device__ __forceinline__ void gemm_phase(LAS unsigned char* lds, const Gemm g, const Sched& S, const Epi& E) {
;     ...
;         const bool has_next = S.next(ui + 1, nxt);
;         const int nt = cur.nt;
;         const char* nuA = has_next ? a_unit(nxt) : uA; const int ntbA = has_next ? nxt.k0 / BK : tbA; const char* nB = has_next ? (const char*)g.Bt + (size_t)nxt.pn * tstepB + b_k0(nxt.k0) : cB;
;         for (int t = 0; t < nt; t += 2) {
;             const bool last = (t == nt - 2);
;             const char* a1 = a_tile(uA, tbA + t + 1);
;             const char* a2 = last ? a_tile(nuA, ntbA) : a_tile(uA, tbA + t + 2); const char* b2 = last ? nB : cB + (size_t)(t + 2) * kstepB;
;             const char* a3 = last ? a_tile(nuA, ntbA + 1) : a_tile(uA, tbA + t + 3); const char* b3 = b2 + kstepB;
;             if (last && has_next) S.a_ready(nxt);
;             if constexpr (SP2) {
;             PG8_LDB(B0, 0, 0); PG8_LDB(B1, 0, 1); PG8_SCHED; PG8_LDA(At, 0, 0); PG8_STAGE(PG8_SA(1, 1), a1 + hstepA, voffA);
;             PG8_WAIT_V(8); PG8_WAIT_L(0); PG8_BAR; PG8_MMA(0, 0, At, B0); PG8_MMA(0, 1, At, B1); PG8_BAR; PG8_SCHED;
;             PG8_LDA(At, 0, 1); PG8_STAGE(PG8_SB(0, 0), b2, voffB); PG8_STAGE(PG8_SB(0, 1), b2 + hstepB, voffB); PG8_STAGE(PG8_SA(0, 0), a2, voffA);
;             PG8_WAIT_V(8); PG8_WAIT_L(0); PG8_BAR; PG8_MMA(1, 0, At, B0); PG8_MMA(1, 1, At, B1); PG8_BAR; PG8_SCHED;
.LBB0_667:
	s_ashr_i32 s15, s14, 31
	s_lshl_b64 s[4:5], s[14:15], 20
	s_add_u32 s18, s59, s4
	s_addc_u32 s19, s62, s5
	s_and_b64 s[4:5], s[20:21], exec
	s_cselect_b32 s2, s19, s27
	s_cselect_b32 s4, s18, s26
	s_ashr_i32 s17, s16, 31
	s_lshl_b64 s[22:23], s[16:17], 20
	s_add_u32 s22, s39, s22
	s_addc_u32 s23, s40, s23
	s_and_b64 s[30:31], s[20:21], exec
	s_cselect_b32 s5, s23, s29
	s_cselect_b32 s9, s22, s28
	s_add_u32 s15, s4, 0x80
	s_addc_u32 s17, s2, 0
	s_add_u32 s52, s28, 0x10000
	v_mov_b32_e32 v2, 0
	s_addc_u32 s53, s29, 0
	v_lshl_add_u64 v[180:181], s[26:27], 0, v[176:177]
	v_lshl_add_u64 v[182:183], s[26:27], 0, v[178:179]
	s_mov_b32 s54, -2
	s_mov_b64 s[28:29], 0
	ds_read_b128 v[184:187], v153
	ds_read_b128 v[188:191], v153 offset:1024
	ds_read_b128 v[192:195], v153 offset:2048
	ds_read_b128 v[196:199], v153 offset:3072
	ds_read_b128 v[200:203], v157
	ds_read_b128 v[204:207], v157 offset:1024
	ds_read_b128 v[208:211], v157 offset:2048
	ds_read_b128 v[212:215], v157 offset:3072
	s_add_u32 s30, s26, s28
	s_addc_u32 s31, s27, s29
	s_add_u32 s36, s30, 0x100
	s_addc_u32 s37, s31, 0
	s_add_u32 s30, s30, 0x180
	s_addc_u32 s31, s31, 0
	s_mov_b64 s[34:35], s[52:53]
	v_lshl_add_u64 v[248:249], v[180:181], 0, s[28:29]
	s_add_i32 m0, s25, 0xc000
	ds_read_b128 v[216:219], v149
	ds_read_b128 v[220:223], v149 offset:1024
	ds_read_b128 v[224:227], v149 offset:2048
	ds_read_b128 v[228:231], v149 offset:3072
	ds_read_b128 v[232:235], v149 offset:4096
	ds_read_b128 v[236:239], v149 offset:5120
	ds_read_b128 v[240:243], v149 offset:6144
	ds_read_b128 v[244:247], v149 offset:7168
	global_load_lds_dwordx4 v[248:249], off
	v_lshl_add_u64 v[248:249], v[182:183], 0, s[28:29]
	s_add_i32 m0, s25, 0xe000
	s_nop 0
	global_load_lds_dwordx4 v[248:249], off
	s_waitcnt vmcnt(8) lgkmcnt(0)
	s_barrier
	v_mfma_f32_16x16x32_bf16 v[126:129], v[184:187], v[216:219], 0
	v_mfma_f32_16x16x32_bf16 v[122:125], v[192:195], v[216:219], 0
	v_mfma_f32_16x16x32_bf16 v[110:113], v[184:187], v[224:227], 0
	v_mfma_f32_16x16x32_bf16 v[106:109], v[192:195], v[224:227], 0
	v_mfma_f32_16x16x32_bf16 v[94:97], v[184:187], v[232:235], 0
	v_mfma_f32_16x16x32_bf16 v[90:93], v[192:195], v[232:235], 0
	v_mfma_f32_16x16x32_bf16 v[78:81], v[184:187], v[240:243], 0
	v_mfma_f32_16x16x32_bf16 v[74:77], v[192:195], v[240:243], 0
	v_mfma_f32_16x16x32_bf16 v[126:129], v[188:191], v[220:223], v[126:129]
	v_mfma_f32_16x16x32_bf16 v[122:125], v[196:199], v[220:223], v[122:125]
	v_mfma_f32_16x16x32_bf16 v[110:113], v[188:191], v[228:231], v[110:113]
	v_mfma_f32_16x16x32_bf16 v[106:109], v[196:199], v[228:231], v[106:109]
	v_mfma_f32_16x16x32_bf16 v[94:97], v[188:191], v[236:239], v[94:97]
	v_mfma_f32_16x16x32_bf16 v[90:93], v[196:199], v[236:239], v[90:93]
	v_mfma_f32_16x16x32_bf16 v[78:81], v[188:191], v[244:247], v[78:81]
	v_mfma_f32_16x16x32_bf16 v[74:77], v[196:199], v[244:247], v[74:77]
	v_mfma_f32_16x16x32_bf16 v[118:121], v[200:203], v[216:219], 0
	v_mfma_f32_16x16x32_bf16 v[114:117], v[208:211], v[216:219], 0
	v_mfma_f32_16x16x32_bf16 v[102:105], v[200:203], v[224:227], 0
	v_mfma_f32_16x16x32_bf16 v[98:101], v[208:211], v[224:227], 0
	v_mfma_f32_16x16x32_bf16 v[86:89], v[200:203], v[232:235], 0
	v_mfma_f32_16x16x32_bf16 v[82:85], v[208:211], v[232:235], 0
	v_mfma_f32_16x16x32_bf16 v[70:73], v[200:203], v[240:243], 0
	v_mfma_f32_16x16x32_bf16 v[66:69], v[208:211], v[240:243], 0
	v_mfma_f32_16x16x32_bf16 v[118:121], v[204:207], v[220:223], v[118:121]
	v_mfma_f32_16x16x32_bf16 v[114:117], v[212:215], v[220:223], v[114:117]
	v_mfma_f32_16x16x32_bf16 v[102:105], v[204:207], v[228:231], v[102:105]
	v_mfma_f32_16x16x32_bf16 v[98:101], v[212:215], v[228:231], v[98:101]
	v_mfma_f32_16x16x32_bf16 v[86:89], v[204:207], v[236:239], v[86:89]
	v_mfma_f32_16x16x32_bf16 v[82:85], v[212:215], v[236:239], v[82:85]
	v_mfma_f32_16x16x32_bf16 v[70:73], v[204:207], v[244:247], v[70:73]
	v_mfma_f32_16x16x32_bf16 v[66:69], v[212:215], v[244:247], v[66:69]
	s_barrier
	s_add_i32 s55, s72, s41
	s_mov_b32 m0, s55
	ds_read_b128 v[216:219], v149 offset:16384
	ds_read_b128 v[220:223], v149 offset:17408
	ds_read_b128 v[224:227], v149 offset:18432
	ds_read_b128 v[228:231], v149 offset:19456
	ds_read_b128 v[232:235], v149 offset:20480
	ds_read_b128 v[236:239], v149 offset:21504
	ds_read_b128 v[240:243], v149 offset:22528
	ds_read_b128 v[244:247], v149 offset:23552
	global_load_lds_dwordx4 v132, s[34:35]
	s_add_i32 m0, s55, 0x2000
	s_add_u32 s56, s34, 0x4000
	s_addc_u32 s57, s35, 0
	s_add_i32 s55, s73, s41
	global_load_lds_dwordx4 v136, s[34:35]
	s_mov_b32 m0, s55
	s_nop 0
	global_load_lds_dwordx4 v132, s[56:57]
	s_add_i32 m0, s55, 0x2000
	s_nop 0
	global_load_lds_dwordx4 v136, s[56:57]
	s_mov_b32 m0, s25
	s_nop 0
	global_load_lds_dwordx4 v130, s[36:37]
	s_mov_b32 m0, s42
	s_nop 0
	global_load_lds_dwordx4 v134, s[36:37]
	s_waitcnt vmcnt(8) lgkmcnt(0)
	s_barrier
; #define PG8_STAGE(bufoff, gbase, voff) do { _Pragma("unroll") for (int _i = 0; _i < 2; ++_i) \
;         __builtin_amdgcn_global_load_lds((const unsigned*)((const char*)(gbase) + (voff)[_i]), (LAS unsigned*)(lds + (bufoff) + ldsw + _i * 8192), 16, 0, 0); } while (0)
; #define PG8_LDA(dst, b, h) do { _Pragma("unroll") for (int m = 0; m < 4; ++m) _Pragma("unroll") for (int k = 0; k < 2; ++k) dst[m][k] = *(const LAS bf16x8*)(lds + PG8_SA(b, h) + aoff + m * 2048 + k * 1024); } while (0)
; #define PG8_LDB(dst, b, h) do { _Pragma("unroll") for (int n = 0; n < 2; ++n) _Pragma("unroll") for (int k = 0; k < 2; ++k) dst[n][k] = *(const LAS bf16x8*)(lds + PG8_SB(b, h) + boff + n * 2048 + k * 1024); } while (0)
; #define PG8_MMA(ai, bj, At, Bt) do { __builtin_amdgcn_s_setprio(1); _Pragma("unroll") for (int m = 0; m < 4; ++m) _Pragma("unroll") for (int n = 0; n < 2; ++n) _Pragma("unroll") for (int k = 0; k < 2; ++k) \
;         acc[ai][bj][m][n] = __builtin_amdgcn_mfma_f32_16x16x32_bf16(Bt[n][k], At[m][k], acc[ai][bj][m][n], 0, 0, 0); __builtin_amdgcn_s_setprio(0); } while (0)
; #define PG8_WAIT_V(n) asm volatile("s_waitcnt vmcnt(" #n ")" ::: "memory")
; #define PG8_WAIT_L(n) asm volatile("s_waitcnt lgkmcnt(" #n ")" ::: "memory")
; #define PG8_BAR __builtin_amdgcn_s_barrier()
; #define PG8_SCHED __builtin_amdgcn_sched_barrier(0)
; template <class Epi, class Sched, bool ABLK = false, bool ALIGN_EPI = true, bool SP2 = true, bool BBLK = true>
; __device__ __forceinline__ void gemm_phase(LAS unsigned char* lds, const Gemm g, const Sched& S, const Epi& E) {
;     ...
;             PG8_WAIT_V(8); PG8_WAIT_L(0); PG8_BAR; PG8_MMA(1, 0, At, B0); PG8_MMA(1, 1, At, B1); PG8_BAR; PG8_SCHED;
;             PG8_LDB(B0, 1, 0); PG8_LDB(B1, 1, 1); PG8_SCHED; PG8_LDA(At, 1, 0); PG8_STAGE(PG8_SA(0, 1), a2 + hstepA, voffA);
;             PG8_WAIT_V(8); PG8_WAIT_L(0); PG8_BAR; PG8_MMA(0, 0, At, B0); PG8_MMA(0, 1, At, B1); PG8_BAR; PG8_SCHED;
;             PG8_LDA(At, 1, 1); PG8_STAGE(PG8_SB(1, 0), b3, voffB); PG8_STAGE(PG8_SB(1, 1), b3 + hstepB, voffB); PG8_STAGE(PG8_SA(1, 0), a3, voffA);
	v_mfma_f32_16x16x32_bf16 v[62:65], v[184:187], v[216:219], 0
	v_mfma_f32_16x16x32_bf16 v[58:61], v[192:195], v[216:219], 0
	v_mfma_f32_16x16x32_bf16 v[46:49], v[184:187], v[224:227], 0
	v_mfma_f32_16x16x32_bf16 v[42:45], v[192:195], v[224:227], 0
	v_mfma_f32_16x16x32_bf16 v[30:33], v[184:187], v[232:235], 0
	v_mfma_f32_16x16x32_bf16 v[26:29], v[192:195], v[232:235], 0
	v_mfma_f32_16x16x32_bf16 v[14:17], v[184:187], v[240:243], 0
	v_mfma_f32_16x16x32_bf16 v[10:13], v[192:195], v[240:243], 0
	v_mfma_f32_16x16x32_bf16 v[62:65], v[188:191], v[220:223], v[62:65]
	v_mfma_f32_16x16x32_bf16 v[58:61], v[196:199], v[220:223], v[58:61]
	v_mfma_f32_16x16x32_bf16 v[46:49], v[188:191], v[228:231], v[46:49]
	v_mfma_f32_16x16x32_bf16 v[42:45], v[196:199], v[228:231], v[42:45]
	v_mfma_f32_16x16x32_bf16 v[30:33], v[188:191], v[236:239], v[30:33]
	v_mfma_f32_16x16x32_bf16 v[26:29], v[196:199], v[236:239], v[26:29]
	v_mfma_f32_16x16x32_bf16 v[14:17], v[188:191], v[244:247], v[14:17]
	v_mfma_f32_16x16x32_bf16 v[10:13], v[196:199], v[244:247], v[10:13]
	v_mfma_f32_16x16x32_bf16 v[54:57], v[200:203], v[216:219], 0
	v_mfma_f32_16x16x32_bf16 v[50:53], v[208:211], v[216:219], 0
	v_mfma_f32_16x16x32_bf16 v[38:41], v[200:203], v[224:227], 0
	v_mfma_f32_16x16x32_bf16 v[34:37], v[208:211], v[224:227], 0
	v_mfma_f32_16x16x32_bf16 v[22:25], v[200:203], v[232:235], 0
	v_mfma_f32_16x16x32_bf16 v[18:21], v[208:211], v[232:235], 0
	v_mfma_f32_16x16x32_bf16 v[6:9], v[200:203], v[240:243], 0
	v_mfma_f32_16x16x32_bf16 v[2:5], v[208:211], v[240:243], 0
	v_mfma_f32_16x16x32_bf16 v[54:57], v[204:207], v[220:223], v[54:57]
	v_mfma_f32_16x16x32_bf16 v[50:53], v[212:215], v[220:223], v[50:53]
	v_mfma_f32_16x16x32_bf16 v[38:41], v[204:207], v[228:231], v[38:41]
	v_mfma_f32_16x16x32_bf16 v[34:37], v[212:215], v[228:231], v[34:37]
	v_mfma_f32_16x16x32_bf16 v[22:25], v[204:207], v[236:239], v[22:25]
	v_mfma_f32_16x16x32_bf16 v[18:21], v[212:215], v[236:239], v[18:21]
	v_mfma_f32_16x16x32_bf16 v[6:9], v[204:207], v[244:247], v[6:9]
	v_mfma_f32_16x16x32_bf16 v[2:5], v[212:215], v[244:247], v[2:5]
	s_barrier
	v_add_u32_e32 v138, s60, v1
	ds_read_b128 v[184:187], v138
	ds_read_b128 v[188:191], v138 offset:1024
	ds_read_b128 v[192:195], v138 offset:2048
	ds_read_b128 v[196:199], v138 offset:3072
	v_add_u32_e32 v138, s61, v1
	ds_read_b128 v[200:203], v138
	ds_read_b128 v[204:207], v138 offset:1024
	ds_read_b128 v[208:211], v138 offset:2048
	ds_read_b128 v[212:215], v138 offset:3072
	s_add_u32 s36, s36, 0x80000
	s_addc_u32 s37, s37, 0
	s_mov_b32 m0, s43
	ds_read_b128 v[216:219], v149 offset:32768
	ds_read_b128 v[220:223], v149 offset:33792
	ds_read_b128 v[224:227], v149 offset:34816
	ds_read_b128 v[228:231], v149 offset:35840
	ds_read_b128 v[232:235], v149 offset:36864
	ds_read_b128 v[236:239], v149 offset:37888
	ds_read_b128 v[240:243], v149 offset:38912
	ds_read_b128 v[244:247], v149 offset:39936
	global_load_lds_dwordx4 v130, s[36:37]
	s_mov_b32 m0, s46
	s_nop 0
	global_load_lds_dwordx4 v134, s[36:37]
	s_waitcnt vmcnt(8) lgkmcnt(0)
	s_barrier
	v_mfma_f32_16x16x32_bf16 v[126:129], v[184:187], v[216:219], v[126:129]
	v_mfma_f32_16x16x32_bf16 v[122:125], v[192:195], v[216:219], v[122:125]
	v_mfma_f32_16x16x32_bf16 v[110:113], v[184:187], v[224:227], v[110:113]
	v_mfma_f32_16x16x32_bf16 v[106:109], v[192:195], v[224:227], v[106:109]
	v_mfma_f32_16x16x32_bf16 v[94:97], v[184:187], v[232:235], v[94:97]
	v_mfma_f32_16x16x32_bf16 v[90:93], v[192:195], v[232:235], v[90:93]
	v_mfma_f32_16x16x32_bf16 v[78:81], v[184:187], v[240:243], v[78:81]
	v_mfma_f32_16x16x32_bf16 v[74:77], v[192:195], v[240:243], v[74:77]
	v_mfma_f32_16x16x32_bf16 v[126:129], v[188:191], v[220:223], v[126:129]
	v_mfma_f32_16x16x32_bf16 v[122:125], v[196:199], v[220:223], v[122:125]
	v_mfma_f32_16x16x32_bf16 v[110:113], v[188:191], v[228:231], v[110:113]
	v_mfma_f32_16x16x32_bf16 v[106:109], v[196:199], v[228:231], v[106:109]
	v_mfma_f32_16x16x32_bf16 v[94:97], v[188:191], v[236:239], v[94:97]
	v_mfma_f32_16x16x32_bf16 v[90:93], v[196:199], v[236:239], v[90:93]
	v_mfma_f32_16x16x32_bf16 v[78:81], v[188:191], v[244:247], v[78:81]
	v_mfma_f32_16x16x32_bf16 v[74:77], v[196:199], v[244:247], v[74:77]
	v_mfma_f32_16x16x32_bf16 v[118:121], v[200:203], v[216:219], v[118:121]
	v_mfma_f32_16x16x32_bf16 v[114:117], v[208:211], v[216:219], v[114:117]
	v_mfma_f32_16x16x32_bf16 v[102:105], v[200:203], v[224:227], v[102:105]
	v_mfma_f32_16x16x32_bf16 v[98:101], v[208:211], v[224:227], v[98:101]
	v_mfma_f32_16x16x32_bf16 v[86:89], v[200:203], v[232:235], v[86:89]
	v_mfma_f32_16x16x32_bf16 v[82:85], v[208:211], v[232:235], v[82:85]
	v_mfma_f32_16x16x32_bf16 v[70:73], v[200:203], v[240:243], v[70:73]
	v_mfma_f32_16x16x32_bf16 v[66:69], v[208:211], v[240:243], v[66:69]
	v_mfma_f32_16x16x32_bf16 v[118:121], v[204:207], v[220:223], v[118:121]
	v_mfma_f32_16x16x32_bf16 v[114:117], v[212:215], v[220:223], v[114:117]
	v_mfma_f32_16x16x32_bf16 v[102:105], v[204:207], v[228:231], v[102:105]
	v_mfma_f32_16x16x32_bf16 v[98:101], v[212:215], v[228:231], v[98:101]
	v_mfma_f32_16x16x32_bf16 v[86:89], v[204:207], v[236:239], v[86:89]
	v_mfma_f32_16x16x32_bf16 v[82:85], v[212:215], v[236:239], v[82:85]
	v_mfma_f32_16x16x32_bf16 v[70:73], v[204:207], v[244:247], v[70:73]
	v_mfma_f32_16x16x32_bf16 v[66:69], v[212:215], v[244:247], v[66:69]
	s_barrier
; #define PG8_STAGE(bufoff, gbase, voff) do { _Pragma("unroll") for (int _i = 0; _i < 2; ++_i) \
;         __builtin_amdgcn_global_load_lds((const unsigned*)((const char*)(gbase) + (voff)[_i]), (LAS unsigned*)(lds + (bufoff) + ldsw + _i * 8192), 16, 0, 0); } while (0)
; #define PG8_LDA(dst, b, h) do { _Pragma("unroll") for (int m = 0; m < 4; ++m) _Pragma("unroll") for (int k = 0; k < 2; ++k) dst[m][k] = *(const LAS bf16x8*)(lds + PG8_SA(b, h) + aoff + m * 2048 + k * 1024); } while (0)
; #define PG8_WAIT_V(n) asm volatile("s_waitcnt vmcnt(" #n ")" ::: "memory")
; #define PG8_WAIT_L(n) asm volatile("s_waitcnt lgkmcnt(" #n ")" ::: "memory")
; template <class Epi, class Sched, bool ABLK = false, bool ALIGN_EPI = true, bool SP2 = true, bool BBLK = true>
; __device__ __forceinline__ void gemm_phase(LAS unsigned char* lds, const Gemm g, const Sched& S, const Epi& E) {
;     ...
;         for (int t = 0; t < nt; t += 2) {
;             const bool last = (t == nt - 2);
;             const char* a1 = a_tile(uA, tbA + t + 1);
;             const char* a2 = last ? a_tile(nuA, ntbA) : a_tile(uA, tbA + t + 2); const char* b2 = last ? nB : cB + (size_t)(t + 2) * kstepB;
;             const char* a3 = last ? a_tile(nuA, ntbA + 1) : a_tile(uA, tbA + t + 3); const char* b3 = b2 + kstepB;
;             if (last && has_next) S.a_ready(nxt);
;             if constexpr (SP2) {
;             PG8_LDB(B0, 0, 0); PG8_LDB(B1, 0, 1); PG8_SCHED; PG8_LDA(At, 0, 0); PG8_STAGE(PG8_SA(1, 1), a1 + hstepA, voffA);
;             PG8_WAIT_V(8); PG8_WAIT_L(0); PG8_BAR; PG8_MMA(0, 0, At, B0); PG8_MMA(0, 1, At, B1); PG8_BAR; PG8_SCHED;
;             PG8_LDA(At, 0, 1); PG8_STAGE(PG8_SB(0, 0), b2, voffB); PG8_STAGE(PG8_SB(0, 1), b2 + hstepB, voffB); PG8_STAGE(PG8_SA(0, 0), a2, voffA);
;             PG8_WAIT_V(8); PG8_WAIT_L(0); PG8_BAR; PG8_MMA(1, 0, At, B0); PG8_MMA(1, 1, At, B1); PG8_BAR; PG8_SCHED;
;             PG8_LDB(B0, 1, 0); PG8_LDB(B1, 1, 1); PG8_SCHED; PG8_LDA(At, 1, 0); PG8_STAGE(PG8_SA(0, 1), a2 + hstepA, voffA);
;             PG8_WAIT_V(8); PG8_WAIT_L(0); PG8_BAR; PG8_MMA(0, 0, At, B0); PG8_MMA(0, 1, At, B1); PG8_BAR; PG8_SCHED;
;             PG8_LDA(At, 1, 1); PG8_STAGE(PG8_SB(1, 0), b3, voffB); PG8_STAGE(PG8_SB(1, 1), b3 + hstepB, voffB); PG8_STAGE(PG8_SA(1, 0), a3, voffA);
;             PG8_WAIT_V(8); PG8_WAIT_L(0); PG8_BAR; PG8_MMA(1, 0, At, B0); PG8_MMA(1, 1, At, B1); PG8_BAR; PG8_SCHED;
	s_add_u32 s36, s34, 0x8000
	s_addc_u32 s37, s35, 0
	s_add_i32 s55, s60, s41
	s_mov_b32 m0, s55
	ds_read_b128 v[216:219], v149 offset:49152
	ds_read_b128 v[220:223], v149 offset:50176
	ds_read_b128 v[224:227], v149 offset:51200
	ds_read_b128 v[228:231], v149 offset:52224
	ds_read_b128 v[232:235], v149 offset:53248
	ds_read_b128 v[236:239], v149 offset:54272
	ds_read_b128 v[240:243], v149 offset:55296
	ds_read_b128 v[244:247], v149 offset:56320
	global_load_lds_dwordx4 v132, s[36:37]
	s_add_i32 m0, s55, 0x2000
	s_add_u32 s34, s34, 0xc000
	v_lshl_add_u64 v[248:249], s[36:37], 0, v[136:137]
	s_addc_u32 s35, s35, 0
	s_add_i32 s36, s61, s41
	global_load_lds_dwordx4 v[248:249], off
	s_mov_b32 m0, s36
	s_nop 0
	global_load_lds_dwordx4 v132, s[34:35]
	s_add_i32 m0, s36, 0x2000
	s_nop 0
	global_load_lds_dwordx4 v136, s[34:35]
	s_mov_b32 m0, s47
	s_nop 0
	global_load_lds_dwordx4 v130, s[30:31]
	s_mov_b32 m0, s48
	s_nop 0
	global_load_lds_dwordx4 v134, s[30:31]
	s_waitcnt vmcnt(8) lgkmcnt(0)
	s_barrier
	v_mfma_f32_16x16x32_bf16 v[62:65], v[184:187], v[216:219], v[62:65]
	v_mfma_f32_16x16x32_bf16 v[58:61], v[192:195], v[216:219], v[58:61]
	v_mfma_f32_16x16x32_bf16 v[46:49], v[184:187], v[224:227], v[46:49]
	v_mfma_f32_16x16x32_bf16 v[42:45], v[192:195], v[224:227], v[42:45]
	v_mfma_f32_16x16x32_bf16 v[30:33], v[184:187], v[232:235], v[30:33]
	v_mfma_f32_16x16x32_bf16 v[26:29], v[192:195], v[232:235], v[26:29]
	v_mfma_f32_16x16x32_bf16 v[14:17], v[184:187], v[240:243], v[14:17]
	v_mfma_f32_16x16x32_bf16 v[10:13], v[192:195], v[240:243], v[10:13]
	v_mfma_f32_16x16x32_bf16 v[62:65], v[188:191], v[220:223], v[62:65]
	v_mfma_f32_16x16x32_bf16 v[58:61], v[196:199], v[220:223], v[58:61]
	v_mfma_f32_16x16x32_bf16 v[46:49], v[188:191], v[228:231], v[46:49]
	v_mfma_f32_16x16x32_bf16 v[42:45], v[196:199], v[228:231], v[42:45]
	v_mfma_f32_16x16x32_bf16 v[30:33], v[188:191], v[236:239], v[30:33]
	v_mfma_f32_16x16x32_bf16 v[26:29], v[196:199], v[236:239], v[26:29]
	v_mfma_f32_16x16x32_bf16 v[14:17], v[188:191], v[244:247], v[14:17]
	v_mfma_f32_16x16x32_bf16 v[10:13], v[196:199], v[244:247], v[10:13]
	v_mfma_f32_16x16x32_bf16 v[54:57], v[200:203], v[216:219], v[54:57]
	v_mfma_f32_16x16x32_bf16 v[50:53], v[208:211], v[216:219], v[50:53]
	v_mfma_f32_16x16x32_bf16 v[38:41], v[200:203], v[224:227], v[38:41]
	v_mfma_f32_16x16x32_bf16 v[34:37], v[208:211], v[224:227], v[34:37]
	v_mfma_f32_16x16x32_bf16 v[22:25], v[200:203], v[232:235], v[22:25]
	v_mfma_f32_16x16x32_bf16 v[18:21], v[208:211], v[232:235], v[18:21]
	v_mfma_f32_16x16x32_bf16 v[6:9], v[200:203], v[240:243], v[6:9]
	v_mfma_f32_16x16x32_bf16 v[2:5], v[208:211], v[240:243], v[2:5]
	v_mfma_f32_16x16x32_bf16 v[54:57], v[204:207], v[220:223], v[54:57]
	v_mfma_f32_16x16x32_bf16 v[50:53], v[212:215], v[220:223], v[50:53]
	v_mfma_f32_16x16x32_bf16 v[38:41], v[204:207], v[228:231], v[38:41]
	v_mfma_f32_16x16x32_bf16 v[34:37], v[212:215], v[228:231], v[34:37]
	v_mfma_f32_16x16x32_bf16 v[22:25], v[204:207], v[236:239], v[22:25]
	v_mfma_f32_16x16x32_bf16 v[18:21], v[212:215], v[236:239], v[18:21]
	v_mfma_f32_16x16x32_bf16 v[6:9], v[204:207], v[244:247], v[6:9]
	v_mfma_f32_16x16x32_bf16 v[2:5], v[212:215], v[244:247], v[2:5]
	s_barrier
	s_add_i32 s54, s54, 2
	s_add_u32 s28, s28, 0x100
	s_addc_u32 s29, s29, 0
	s_add_u32 s52, s52, 0x10000
	s_addc_u32 s53, s53, 0
	s_cmp_gt_u32 s54, 29
.LBB0_668:
	ds_read_b128 v[184:187], v153
	ds_read_b128 v[188:191], v153 offset:1024
	ds_read_b128 v[192:195], v153 offset:2048
	ds_read_b128 v[196:199], v153 offset:3072
	ds_read_b128 v[200:203], v157
	ds_read_b128 v[204:207], v157 offset:1024
	ds_read_b128 v[208:211], v157 offset:2048
	ds_read_b128 v[212:215], v157 offset:3072
	s_add_u32 s30, s26, s28
	s_addc_u32 s31, s27, s29
	s_add_u32 s36, s30, 0x100
	s_addc_u32 s37, s31, 0
	s_add_u32 s30, s30, 0x180
	s_addc_u32 s31, s31, 0
	s_cmpk_eq_i32 s28, 0xf00
	s_cbranch_scc1 .Lksel_7
	s_mov_b64 s[34:35], s[52:53]
.Lksel_7_back:
	v_lshl_add_u64 v[248:249], v[180:181], 0, s[28:29]
	s_add_i32 m0, s25, 0xc000
	ds_read_b128 v[216:219], v149
	ds_read_b128 v[220:223], v149 offset:1024
	ds_read_b128 v[224:227], v149 offset:2048
	ds_read_b128 v[228:231], v149 offset:3072
	ds_read_b128 v[232:235], v149 offset:4096
	ds_read_b128 v[236:239], v149 offset:5120
	ds_read_b128 v[240:243], v149 offset:6144
	ds_read_b128 v[244:247], v149 offset:7168
	global_load_lds_dwordx4 v[248:249], off
	v_lshl_add_u64 v[248:249], v[182:183], 0, s[28:29]
	s_add_i32 m0, s25, 0xe000
	s_nop 0
	global_load_lds_dwordx4 v[248:249], off
	s_waitcnt vmcnt(8) lgkmcnt(0)
	s_barrier
; #define PG8_STAGE(bufoff, gbase, voff) do { _Pragma("unroll") for (int _i = 0; _i < 2; ++_i) \
;         __builtin_amdgcn_global_load_lds((const unsigned*)((const char*)(gbase) + (voff)[_i]), (LAS unsigned*)(lds + (bufoff) + ldsw + _i * 8192), 16, 0, 0); } while (0)
; #define PG8_LDA(dst, b, h) do { _Pragma("unroll") for (int m = 0; m < 4; ++m) _Pragma("unroll") for (int k = 0; k < 2; ++k) dst[m][k] = *(const LAS bf16x8*)(lds + PG8_SA(b, h) + aoff + m * 2048 + k * 1024); } while (0)
; #define PG8_LDB(dst, b, h) do { _Pragma("unroll") for (int n = 0; n < 2; ++n) _Pragma("unroll") for (int k = 0; k < 2; ++k) dst[n][k] = *(const LAS bf16x8*)(lds + PG8_SB(b, h) + boff + n * 2048 + k * 1024); } while (0)
; #define PG8_MMA(ai, bj, At, Bt) do { __builtin_amdgcn_s_setprio(1); _Pragma("unroll") for (int m = 0; m < 4; ++m) _Pragma("unroll") for (int n = 0; n < 2; ++n) _Pragma("unroll") for (int k = 0; k < 2; ++k) \
;         acc[ai][bj][m][n] = __builtin_amdgcn_mfma_f32_16x16x32_bf16(Bt[n][k], At[m][k], acc[ai][bj][m][n], 0, 0, 0); __builtin_amdgcn_s_setprio(0); } while (0)
; #define PG8_WAIT_V(n) asm volatile("s_waitcnt vmcnt(" #n ")" ::: "memory")
; #define PG8_WAIT_L(n) asm volatile("s_waitcnt lgkmcnt(" #n ")" ::: "memory")
; #define PG8_BAR __builtin_amdgcn_s_barrier()
; #define PG8_SCHED __builtin_amdgcn_sched_barrier(0)
; template <class Epi, class Sched, bool ABLK = false, bool ALIGN_EPI = true, bool SP2 = true, bool BBLK = true>
; __device__ __forceinline__ void gemm_phase(LAS unsigned char* lds, const Gemm g, const Sched& S, const Epi& E) {
;     ...
;             PG8_LDB(B0, 0, 0); PG8_LDB(B1, 0, 1); PG8_SCHED; PG8_LDA(At, 0, 0); PG8_STAGE(PG8_SA(1, 1), a1 + hstepA, voffA);
;             PG8_WAIT_V(8); PG8_WAIT_L(0); PG8_BAR; PG8_MMA(0, 0, At, B0); PG8_MMA(0, 1, At, B1); PG8_BAR; PG8_SCHED;
;             PG8_LDA(At, 0, 1); PG8_STAGE(PG8_SB(0, 0), b2, voffB); PG8_STAGE(PG8_SB(0, 1), b2 + hstepB, voffB); PG8_STAGE(PG8_SA(0, 0), a2, voffA);
;             PG8_WAIT_V(8); PG8_WAIT_L(0); PG8_BAR; PG8_MMA(1, 0, At, B0); PG8_MMA(1, 1, At, B1); PG8_BAR; PG8_SCHED;
;             PG8_LDB(B0, 1, 0); PG8_LDB(B1, 1, 1); PG8_SCHED; PG8_LDA(At, 1, 0); PG8_STAGE(PG8_SA(0, 1), a2 + hstepA, voffA);
;             PG8_WAIT_V(8); PG8_WAIT_L(0); PG8_BAR; PG8_MMA(0, 0, At, B0); PG8_MMA(0, 1, At, B1); PG8_BAR; PG8_SCHED;
	v_mfma_f32_16x16x32_bf16 v[126:129], v[184:187], v[216:219], v[126:129]
	v_mfma_f32_16x16x32_bf16 v[122:125], v[192:195], v[216:219], v[122:125]
	v_mfma_f32_16x16x32_bf16 v[110:113], v[184:187], v[224:227], v[110:113]
	v_mfma_f32_16x16x32_bf16 v[106:109], v[192:195], v[224:227], v[106:109]
	v_mfma_f32_16x16x32_bf16 v[94:97], v[184:187], v[232:235], v[94:97]
	v_mfma_f32_16x16x32_bf16 v[90:93], v[192:195], v[232:235], v[90:93]
	v_mfma_f32_16x16x32_bf16 v[78:81], v[184:187], v[240:243], v[78:81]
	v_mfma_f32_16x16x32_bf16 v[74:77], v[192:195], v[240:243], v[74:77]
	v_mfma_f32_16x16x32_bf16 v[126:129], v[188:191], v[220:223], v[126:129]
	v_mfma_f32_16x16x32_bf16 v[122:125], v[196:199], v[220:223], v[122:125]
	v_mfma_f32_16x16x32_bf16 v[110:113], v[188:191], v[228:231], v[110:113]
	v_mfma_f32_16x16x32_bf16 v[106:109], v[196:199], v[228:231], v[106:109]
	v_mfma_f32_16x16x32_bf16 v[94:97], v[188:191], v[236:239], v[94:97]
	v_mfma_f32_16x16x32_bf16 v[90:93], v[196:199], v[236:239], v[90:93]
	v_mfma_f32_16x16x32_bf16 v[78:81], v[188:191], v[244:247], v[78:81]
	v_mfma_f32_16x16x32_bf16 v[74:77], v[196:199], v[244:247], v[74:77]
	v_mfma_f32_16x16x32_bf16 v[118:121], v[200:203], v[216:219], v[118:121]
	v_mfma_f32_16x16x32_bf16 v[114:117], v[208:211], v[216:219], v[114:117]
	v_mfma_f32_16x16x32_bf16 v[102:105], v[200:203], v[224:227], v[102:105]
	v_mfma_f32_16x16x32_bf16 v[98:101], v[208:211], v[224:227], v[98:101]
	v_mfma_f32_16x16x32_bf16 v[86:89], v[200:203], v[232:235], v[86:89]
	v_mfma_f32_16x16x32_bf16 v[82:85], v[208:211], v[232:235], v[82:85]
	v_mfma_f32_16x16x32_bf16 v[70:73], v[200:203], v[240:243], v[70:73]
	v_mfma_f32_16x16x32_bf16 v[66:69], v[208:211], v[240:243], v[66:69]
	v_mfma_f32_16x16x32_bf16 v[118:121], v[204:207], v[220:223], v[118:121]
	v_mfma_f32_16x16x32_bf16 v[114:117], v[212:215], v[220:223], v[114:117]
	v_mfma_f32_16x16x32_bf16 v[102:105], v[204:207], v[228:231], v[102:105]
	v_mfma_f32_16x16x32_bf16 v[98:101], v[212:215], v[228:231], v[98:101]
	v_mfma_f32_16x16x32_bf16 v[86:89], v[204:207], v[236:239], v[86:89]
	v_mfma_f32_16x16x32_bf16 v[82:85], v[212:215], v[236:239], v[82:85]
	v_mfma_f32_16x16x32_bf16 v[70:73], v[204:207], v[244:247], v[70:73]
	v_mfma_f32_16x16x32_bf16 v[66:69], v[212:215], v[244:247], v[66:69]
	s_barrier
	s_add_i32 s55, s72, s41
	s_mov_b32 m0, s55
	ds_read_b128 v[216:219], v149 offset:16384
	ds_read_b128 v[220:223], v149 offset:17408
	ds_read_b128 v[224:227], v149 offset:18432
	ds_read_b128 v[228:231], v149 offset:19456
	ds_read_b128 v[232:235], v149 offset:20480
	ds_read_b128 v[236:239], v149 offset:21504
	ds_read_b128 v[240:243], v149 offset:22528
	ds_read_b128 v[244:247], v149 offset:23552
	global_load_lds_dwordx4 v132, s[34:35]
	s_add_i32 m0, s55, 0x2000
	s_add_u32 s56, s34, 0x4000
	s_addc_u32 s57, s35, 0
	s_add_i32 s55, s73, s41
	global_load_lds_dwordx4 v136, s[34:35]
	s_mov_b32 m0, s55
	s_nop 0
	global_load_lds_dwordx4 v132, s[56:57]
	s_add_i32 m0, s55, 0x2000
	s_nop 0
	global_load_lds_dwordx4 v136, s[56:57]
	s_mov_b32 m0, s25
	s_nop 0
	global_load_lds_dwordx4 v130, s[36:37]
	s_mov_b32 m0, s42
	s_nop 0
	global_load_lds_dwordx4 v134, s[36:37]
	s_waitcnt vmcnt(8) lgkmcnt(0)
	s_barrier
	v_mfma_f32_16x16x32_bf16 v[62:65], v[184:187], v[216:219], v[62:65]
	v_mfma_f32_16x16x32_bf16 v[58:61], v[192:195], v[216:219], v[58:61]
	v_mfma_f32_16x16x32_bf16 v[46:49], v[184:187], v[224:227], v[46:49]
	v_mfma_f32_16x16x32_bf16 v[42:45], v[192:195], v[224:227], v[42:45]
	v_mfma_f32_16x16x32_bf16 v[30:33], v[184:187], v[232:235], v[30:33]
	v_mfma_f32_16x16x32_bf16 v[26:29], v[192:195], v[232:235], v[26:29]
	v_mfma_f32_16x16x32_bf16 v[14:17], v[184:187], v[240:243], v[14:17]
	v_mfma_f32_16x16x32_bf16 v[10:13], v[192:195], v[240:243], v[10:13]
	v_mfma_f32_16x16x32_bf16 v[62:65], v[188:191], v[220:223], v[62:65]
	v_mfma_f32_16x16x32_bf16 v[58:61], v[196:199], v[220:223], v[58:61]
	v_mfma_f32_16x16x32_bf16 v[46:49], v[188:191], v[228:231], v[46:49]
	v_mfma_f32_16x16x32_bf16 v[42:45], v[196:199], v[228:231], v[42:45]
	v_mfma_f32_16x16x32_bf16 v[30:33], v[188:191], v[236:239], v[30:33]
	v_mfma_f32_16x16x32_bf16 v[26:29], v[196:199], v[236:239], v[26:29]
	v_mfma_f32_16x16x32_bf16 v[14:17], v[188:191], v[244:247], v[14:17]
	v_mfma_f32_16x16x32_bf16 v[10:13], v[196:199], v[244:247], v[10:13]
	v_mfma_f32_16x16x32_bf16 v[54:57], v[200:203], v[216:219], v[54:57]
	v_mfma_f32_16x16x32_bf16 v[50:53], v[208:211], v[216:219], v[50:53]
	v_mfma_f32_16x16x32_bf16 v[38:41], v[200:203], v[224:227], v[38:41]
	v_mfma_f32_16x16x32_bf16 v[34:37], v[208:211], v[224:227], v[34:37]
	v_mfma_f32_16x16x32_bf16 v[22:25], v[200:203], v[232:235], v[22:25]
	v_mfma_f32_16x16x32_bf16 v[18:21], v[208:211], v[232:235], v[18:21]
	v_mfma_f32_16x16x32_bf16 v[6:9], v[200:203], v[240:243], v[6:9]
	v_mfma_f32_16x16x32_bf16 v[2:5], v[208:211], v[240:243], v[2:5]
	v_mfma_f32_16x16x32_bf16 v[54:57], v[204:207], v[220:223], v[54:57]
	v_mfma_f32_16x16x32_bf16 v[50:53], v[212:215], v[220:223], v[50:53]
	v_mfma_f32_16x16x32_bf16 v[38:41], v[204:207], v[228:231], v[38:41]
	v_mfma_f32_16x16x32_bf16 v[34:37], v[212:215], v[228:231], v[34:37]
	v_mfma_f32_16x16x32_bf16 v[22:25], v[204:207], v[236:239], v[22:25]
	v_mfma_f32_16x16x32_bf16 v[18:21], v[212:215], v[236:239], v[18:21]
	v_mfma_f32_16x16x32_bf16 v[6:9], v[204:207], v[244:247], v[6:9]
	v_mfma_f32_16x16x32_bf16 v[2:5], v[212:215], v[244:247], v[2:5]
	s_barrier
; #define PG8_STAGE(bufoff, gbase, voff) do { _Pragma("unroll") for (int _i = 0; _i < 2; ++_i) \
;         __builtin_amdgcn_global_load_lds((const unsigned*)((const char*)(gbase) + (voff)[_i]), (LAS unsigned*)(lds + (bufoff) + ldsw + _i * 8192), 16, 0, 0); } while (0)
; #define PG8_LDA(dst, b, h) do { _Pragma("unroll") for (int m = 0; m < 4; ++m) _Pragma("unroll") for (int k = 0; k < 2; ++k) dst[m][k] = *(const LAS bf16x8*)(lds + PG8_SA(b, h) + aoff + m * 2048 + k * 1024); } while (0)
; #define PG8_LDB(dst, b, h) do { _Pragma("unroll") for (int n = 0; n < 2; ++n) _Pragma("unroll") for (int k = 0; k < 2; ++k) dst[n][k] = *(const LAS bf16x8*)(lds + PG8_SB(b, h) + boff + n * 2048 + k * 1024); } while (0)
; #define PG8_MMA(ai, bj, At, Bt) do { __builtin_amdgcn_s_setprio(1); _Pragma("unroll") for (int m = 0; m < 4; ++m) _Pragma("unroll") for (int n = 0; n < 2; ++n) _Pragma("unroll") for (int k = 0; k < 2; ++k) \
;         acc[ai][bj][m][n] = __builtin_amdgcn_mfma_f32_16x16x32_bf16(Bt[n][k], At[m][k], acc[ai][bj][m][n], 0, 0, 0); __builtin_amdgcn_s_setprio(0); } while (0)
; #define PG8_WAIT_V(n) asm volatile("s_waitcnt vmcnt(" #n ")" ::: "memory")
; #define PG8_WAIT_L(n) asm volatile("s_waitcnt lgkmcnt(" #n ")" ::: "memory")
; #define PG8_BAR __builtin_amdgcn_s_barrier()
; #define PG8_SCHED __builtin_amdgcn_sched_barrier(0)
; template <class Epi, class Sched, bool ABLK = false, bool ALIGN_EPI = true, bool SP2 = true, bool BBLK = true>
; __device__ __forceinline__ void gemm_phase(LAS unsigned char* lds, const Gemm g, const Sched& S, const Epi& E) {
;     ...
;             PG8_LDB(B0, 1, 0); PG8_LDB(B1, 1, 1); PG8_SCHED; PG8_LDA(At, 1, 0); PG8_STAGE(PG8_SA(0, 1), a2 + hstepA, voffA);
;             PG8_WAIT_V(8); PG8_WAIT_L(0); PG8_BAR; PG8_MMA(0, 0, At, B0); PG8_MMA(0, 1, At, B1); PG8_BAR; PG8_SCHED;
;             PG8_LDA(At, 1, 1); PG8_STAGE(PG8_SB(1, 0), b3, voffB); PG8_STAGE(PG8_SB(1, 1), b3 + hstepB, voffB); PG8_STAGE(PG8_SA(1, 0), a3, voffA);
;             PG8_WAIT_V(8); PG8_WAIT_L(0); PG8_BAR; PG8_MMA(1, 0, At, B0); PG8_MMA(1, 1, At, B1); PG8_BAR; PG8_SCHED;
	v_add_u32_e32 v138, s60, v1
	ds_read_b128 v[184:187], v138
	ds_read_b128 v[188:191], v138 offset:1024
	ds_read_b128 v[192:195], v138 offset:2048
	ds_read_b128 v[196:199], v138 offset:3072
	v_add_u32_e32 v138, s61, v1
	ds_read_b128 v[200:203], v138
	ds_read_b128 v[204:207], v138 offset:1024
	ds_read_b128 v[208:211], v138 offset:2048
	ds_read_b128 v[212:215], v138 offset:3072
	s_add_u32 s36, s36, 0x80000
	s_addc_u32 s37, s37, 0
	s_mov_b32 m0, s43
	ds_read_b128 v[216:219], v149 offset:32768
	ds_read_b128 v[220:223], v149 offset:33792
	ds_read_b128 v[224:227], v149 offset:34816
	ds_read_b128 v[228:231], v149 offset:35840
	ds_read_b128 v[232:235], v149 offset:36864
	ds_read_b128 v[236:239], v149 offset:37888
	ds_read_b128 v[240:243], v149 offset:38912
	ds_read_b128 v[244:247], v149 offset:39936
	global_load_lds_dwordx4 v130, s[36:37]
	s_mov_b32 m0, s46
	s_nop 0
	global_load_lds_dwordx4 v134, s[36:37]
	s_waitcnt vmcnt(8) lgkmcnt(0)
	s_barrier
	v_mfma_f32_16x16x32_bf16 v[126:129], v[184:187], v[216:219], v[126:129]
	v_mfma_f32_16x16x32_bf16 v[122:125], v[192:195], v[216:219], v[122:125]
	v_mfma_f32_16x16x32_bf16 v[110:113], v[184:187], v[224:227], v[110:113]
	v_mfma_f32_16x16x32_bf16 v[106:109], v[192:195], v[224:227], v[106:109]
	v_mfma_f32_16x16x32_bf16 v[94:97], v[184:187], v[232:235], v[94:97]
	v_mfma_f32_16x16x32_bf16 v[90:93], v[192:195], v[232:235], v[90:93]
	v_mfma_f32_16x16x32_bf16 v[78:81], v[184:187], v[240:243], v[78:81]
	v_mfma_f32_16x16x32_bf16 v[74:77], v[192:195], v[240:243], v[74:77]
	v_mfma_f32_16x16x32_bf16 v[126:129], v[188:191], v[220:223], v[126:129]
	v_mfma_f32_16x16x32_bf16 v[122:125], v[196:199], v[220:223], v[122:125]
	v_mfma_f32_16x16x32_bf16 v[110:113], v[188:191], v[228:231], v[110:113]
	v_mfma_f32_16x16x32_bf16 v[106:109], v[196:199], v[228:231], v[106:109]
	v_mfma_f32_16x16x32_bf16 v[94:97], v[188:191], v[236:239], v[94:97]
	v_mfma_f32_16x16x32_bf16 v[90:93], v[196:199], v[236:239], v[90:93]
	v_mfma_f32_16x16x32_bf16 v[78:81], v[188:191], v[244:247], v[78:81]
	v_mfma_f32_16x16x32_bf16 v[74:77], v[196:199], v[244:247], v[74:77]
	v_mfma_f32_16x16x32_bf16 v[118:121], v[200:203], v[216:219], v[118:121]
	v_mfma_f32_16x16x32_bf16 v[114:117], v[208:211], v[216:219], v[114:117]
	v_mfma_f32_16x16x32_bf16 v[102:105], v[200:203], v[224:227], v[102:105]
	v_mfma_f32_16x16x32_bf16 v[98:101], v[208:211], v[224:227], v[98:101]
	v_mfma_f32_16x16x32_bf16 v[86:89], v[200:203], v[232:235], v[86:89]
	v_mfma_f32_16x16x32_bf16 v[82:85], v[208:211], v[232:235], v[82:85]
	v_mfma_f32_16x16x32_bf16 v[70:73], v[200:203], v[240:243], v[70:73]
	v_mfma_f32_16x16x32_bf16 v[66:69], v[208:211], v[240:243], v[66:69]
	v_mfma_f32_16x16x32_bf16 v[118:121], v[204:207], v[220:223], v[118:121]
	v_mfma_f32_16x16x32_bf16 v[114:117], v[212:215], v[220:223], v[114:117]
	v_mfma_f32_16x16x32_bf16 v[102:105], v[204:207], v[228:231], v[102:105]
	v_mfma_f32_16x16x32_bf16 v[98:101], v[212:215], v[228:231], v[98:101]
	v_mfma_f32_16x16x32_bf16 v[86:89], v[204:207], v[236:239], v[86:89]
	v_mfma_f32_16x16x32_bf16 v[82:85], v[212:215], v[236:239], v[82:85]
	v_mfma_f32_16x16x32_bf16 v[70:73], v[204:207], v[244:247], v[70:73]
	v_mfma_f32_16x16x32_bf16 v[66:69], v[212:215], v[244:247], v[66:69]
	s_barrier
	s_add_u32 s36, s34, 0x8000
	s_addc_u32 s37, s35, 0
	s_add_i32 s55, s60, s41
	s_mov_b32 m0, s55
	ds_read_b128 v[216:219], v149 offset:49152
	ds_read_b128 v[220:223], v149 offset:50176
	ds_read_b128 v[224:227], v149 offset:51200
	ds_read_b128 v[228:231], v149 offset:52224
	ds_read_b128 v[232:235], v149 offset:53248
	ds_read_b128 v[236:239], v149 offset:54272
	ds_read_b128 v[240:243], v149 offset:55296
	ds_read_b128 v[244:247], v149 offset:56320
	global_load_lds_dwordx4 v132, s[36:37]
	s_add_i32 m0, s55, 0x2000
	s_add_u32 s34, s34, 0xc000
	v_lshl_add_u64 v[248:249], s[36:37], 0, v[136:137]
	s_addc_u32 s35, s35, 0
	s_add_i32 s36, s61, s41
	global_load_lds_dwordx4 v[248:249], off
	s_mov_b32 m0, s36
	s_nop 0
	global_load_lds_dwordx4 v132, s[34:35]
	s_add_i32 m0, s36, 0x2000
	s_nop 0
	global_load_lds_dwordx4 v136, s[34:35]
	s_mov_b32 m0, s47
	s_nop 0
	global_load_lds_dwordx4 v130, s[30:31]
	s_mov_b32 m0, s48
	s_nop 0
	global_load_lds_dwordx4 v134, s[30:31]
	s_waitcnt vmcnt(8) lgkmcnt(0)
	s_barrier
	v_mfma_f32_16x16x32_bf16 v[62:65], v[184:187], v[216:219], v[62:65]
	v_mfma_f32_16x16x32_bf16 v[58:61], v[192:195], v[216:219], v[58:61]
	v_mfma_f32_16x16x32_bf16 v[46:49], v[184:187], v[224:227], v[46:49]
	v_mfma_f32_16x16x32_bf16 v[42:45], v[192:195], v[224:227], v[42:45]
	v_mfma_f32_16x16x32_bf16 v[30:33], v[184:187], v[232:235], v[30:33]
	v_mfma_f32_16x16x32_bf16 v[26:29], v[192:195], v[232:235], v[26:29]
	v_mfma_f32_16x16x32_bf16 v[14:17], v[184:187], v[240:243], v[14:17]
	v_mfma_f32_16x16x32_bf16 v[10:13], v[192:195], v[240:243], v[10:13]
	v_mfma_f32_16x16x32_bf16 v[62:65], v[188:191], v[220:223], v[62:65]
	v_mfma_f32_16x16x32_bf16 v[58:61], v[196:199], v[220:223], v[58:61]
	v_mfma_f32_16x16x32_bf16 v[46:49], v[188:191], v[228:231], v[46:49]
	v_mfma_f32_16x16x32_bf16 v[42:45], v[196:199], v[228:231], v[42:45]
	v_mfma_f32_16x16x32_bf16 v[30:33], v[188:191], v[236:239], v[30:33]
	v_mfma_f32_16x16x32_bf16 v[26:29], v[196:199], v[236:239], v[26:29]
	v_mfma_f32_16x16x32_bf16 v[14:17], v[188:191], v[244:247], v[14:17]
	v_mfma_f32_16x16x32_bf16 v[10:13], v[196:199], v[244:247], v[10:13]
	v_mfma_f32_16x16x32_bf16 v[54:57], v[200:203], v[216:219], v[54:57]
	v_mfma_f32_16x16x32_bf16 v[50:53], v[208:211], v[216:219], v[50:53]
	v_mfma_f32_16x16x32_bf16 v[38:41], v[200:203], v[224:227], v[38:41]
	v_mfma_f32_16x16x32_bf16 v[34:37], v[208:211], v[224:227], v[34:37]
	v_mfma_f32_16x16x32_bf16 v[22:25], v[200:203], v[232:235], v[22:25]
	v_mfma_f32_16x16x32_bf16 v[18:21], v[208:211], v[232:235], v[18:21]
	v_mfma_f32_16x16x32_bf16 v[6:9], v[200:203], v[240:243], v[6:9]
	v_mfma_f32_16x16x32_bf16 v[2:5], v[208:211], v[240:243], v[2:5]
	v_mfma_f32_16x16x32_bf16 v[54:57], v[204:207], v[220:223], v[54:57]
	v_mfma_f32_16x16x32_bf16 v[50:53], v[212:215], v[220:223], v[50:53]
	v_mfma_f32_16x16x32_bf16 v[38:41], v[204:207], v[228:231], v[38:41]
	v_mfma_f32_16x16x32_bf16 v[34:37], v[212:215], v[228:231], v[34:37]
	v_mfma_f32_16x16x32_bf16 v[22:25], v[204:207], v[236:239], v[22:25]
	v_mfma_f32_16x16x32_bf16 v[18:21], v[212:215], v[236:239], v[18:21]
	v_mfma_f32_16x16x32_bf16 v[6:9], v[204:207], v[244:247], v[6:9]
	v_mfma_f32_16x16x32_bf16 v[2:5], v[212:215], v[244:247], v[2:5]
	s_barrier
	s_add_i32 s54, s54, 2
	s_add_u32 s28, s28, 0x100
	s_addc_u32 s29, s29, 0
	s_add_u32 s52, s52, 0x10000
	s_addc_u32 s53, s53, 0
	s_cmp_gt_u32 s54, 29
	s_cbranch_scc0 .LBB0_668
	s_and_b64 vcc, exec, s[12:13]
	s_cbranch_vccz .LBB0_671
	s_barrier

; template <class Epi, class Sched, bool ABLK = false, bool ALIGN_EPI = true, bool SP2 = true, bool BBLK = true>
; __device__ __forceinline__ void gemm_phase(LAS unsigned char* lds, const Gemm g, const Sched& S, const Epi& E) {
;     ...
;             const char* a1 = a_tile(uA, tbA + t + 1);
;             const char* a2 = last ? a_tile(nuA, ntbA) : a_tile(uA, tbA + t + 2); const char* b2 = last ? nB : cB + (size_t)(t + 2) * kstepB;
;             const char* a3 = last ? a_tile(nuA, ntbA + 1) : a_tile(uA, tbA + t + 3); const char* b3 = b2 + kstepB;
.Lksel_7:
	s_mov_b32 s31, s17
	s_mov_b32 s30, s15
	s_mov_b32 s35, s5
	s_mov_b32 s34, s9
	s_mov_b32 s37, s2
	s_mov_b32 s36, s4
	s_branch .Lksel_7_back

; #define PG8_STAGE(bufoff, gbase, voff) do { _Pragma("unroll") for (int _i = 0; _i < 2; ++_i) \
;         __builtin_amdgcn_global_load_lds((const unsigned*)((const char*)(gbase) + (voff)[_i]), (LAS unsigned*)(lds + (bufoff) + ldsw + _i * 8192), 16, 0, 0); } while (0)
; #define PG8_LDA(dst, b, h) do { _Pragma("unroll") for (int m = 0; m < 4; ++m) _Pragma("unroll") for (int k = 0; k < 2; ++k) dst[m][k] = *(const LAS bf16x8*)(lds + PG8_SA(b, h) + aoff + m * 2048 + k * 1024); } while (0)
; #define PG8_LDB(dst, b, h) do { _Pragma("unroll") for (int n = 0; n < 2; ++n) _Pragma("unroll") for (int k = 0; k < 2; ++k) dst[n][k] = *(const LAS bf16x8*)(lds + PG8_SB(b, h) + boff + n * 2048 + k * 1024); } while (0)
; #define PG8_WAIT_V(n) asm volatile("s_waitcnt vmcnt(" #n ")" ::: "memory")
; #define PG8_WAIT_L(n) asm volatile("s_waitcnt lgkmcnt(" #n ")" ::: "memory")
; template <class Epi, class Sched, bool ABLK = false, bool ALIGN_EPI = true, bool SP2 = true, bool BBLK = true>
; __device__ __forceinline__ void gemm_phase(LAS unsigned char* lds, const Gemm g, const Sched& S, const Epi& E) {
;     ...
;         const bool has_next = S.next(ui + 1, nxt);
;         const int nt = cur.nt;
;         const char* nuA = has_next ? a_unit(nxt) : uA; const int ntbA = has_next ? nxt.k0 / BK : tbA; const char* nB = has_next ? (const char*)g.Bt + (size_t)nxt.pn * tstepB + b_k0(nxt.k0) : cB;
;         for (int t = 0; t < nt; t += 2) {
;             const bool last = (t == nt - 2);
;             const char* a1 = a_tile(uA, tbA + t + 1);
;             const char* a2 = last ? a_tile(nuA, ntbA) : a_tile(uA, tbA + t + 2); const char* b2 = last ? nB : cB + (size_t)(t + 2) * kstepB;
;             const char* a3 = last ? a_tile(nuA, ntbA + 1) : a_tile(uA, tbA + t + 3); const char* b3 = b2 + kstepB;
;             if (last && has_next) S.a_ready(nxt);
;             if constexpr (SP2) {
;             PG8_LDB(B0, 0, 0); PG8_LDB(B1, 0, 1); PG8_SCHED; PG8_LDA(At, 0, 0); PG8_STAGE(PG8_SA(1, 1), a1 + hstepA, voffA);
;             PG8_WAIT_V(8); PG8_WAIT_L(0); PG8_BAR; PG8_MMA(0, 0, At, B0); PG8_MMA(0, 1, At, B1); PG8_BAR; PG8_SCHED;
;             PG8_LDA(At, 0, 1); PG8_STAGE(PG8_SB(0, 0), b2, voffB); PG8_STAGE(PG8_SB(0, 1), b2 + hstepB, voffB); PG8_STAGE(PG8_SA(0, 0), a2, voffA);
;             PG8_WAIT_V(8); PG8_WAIT_L(0); PG8_BAR; PG8_MMA(1, 0, At, B0); PG8_MMA(1, 1, At, B1); PG8_BAR; PG8_SCHED;
.LBB0_1037:
	s_ashr_i32 s81, s80, 31
	s_andn2_b64 vcc, exec, s[4:5]
	s_lshl_b64 s[14:15], s[80:81], 20
	s_add_u32 s14, s28, s14
	s_addc_u32 s15, s29, s15
	s_and_b64 s[16:17], s[4:5], exec
	s_cselect_b32 s25, s15, s23
	s_cselect_b32 s48, s14, s22
	s_ashr_i32 s16, s63, 31
	s_lshr_b32 s16, s16, 26
	s_add_i32 s16, s63, s16
	s_ashr_i32 s16, s16, 6
	s_and_b64 s[18:19], s[4:5], exec
	s_cselect_b32 s26, s16, s24
	s_ashr_i32 s79, s78, 31
	s_lshl_b64 s[18:19], s[78:79], 20
	s_add_u32 s27, s30, s18
	s_addc_u32 s49, s31, s19
	s_ashr_i32 s17, s16, 31
	s_lshl_b64 s[18:19], s[16:17], 15
	s_add_u32 s18, s27, s18
	s_addc_u32 s19, s49, s19
	v_cndmask_b32_e64 v2, 0, 1, s[4:5]
	s_and_b64 s[4:5], s[4:5], exec
	s_cselect_b32 s4, s19, s21
	s_cselect_b32 s5, s18, s20
	s_ashr_i32 s27, s26, 31
	s_lshl_b64 s[26:27], s[26:27], 7
	s_add_u32 s17, s48, s26
	s_addc_u32 s48, s25, s27
	s_add_u32 s49, s17, 0x80
	s_addc_u32 s50, s48, 0
	s_add_u32 s51, s20, 0x10000
	s_addc_u32 s55, s21, 0
	s_ashr_i32 s25, s24, 31
	v_cmp_ne_u32_e64 s[8:9], 1, v2
	s_lshl_b64 s[20:21], s[24:25], 7
	v_lshl_add_u64 v[2:3], s[22:23], 0, v[142:143]
	s_add_u32 s56, s22, s20
	v_lshl_add_u64 v[146:147], v[2:3], 0, s[20:21]
	v_lshl_add_u64 v[2:3], s[22:23], 0, v[144:145]
	s_addc_u32 s57, s23, s21
	v_lshl_add_u64 v[148:149], v[2:3], 0, s[20:21]
	s_lshl_b32 s20, s46, 7
	s_addk_i32 s20, 0xfc00
	v_mov_b32_e32 v2, 0
	s_add_u32 s64, s20, 0x300
	s_mov_b32 s65, 0
	s_mov_b64 s[20:21], 0
	ds_read_b128 v[156:159], v153
	ds_read_b128 v[160:163], v153 offset:1024
	ds_read_b128 v[164:167], v153 offset:2048
	ds_read_b128 v[168:171], v153 offset:3072
	ds_read_b128 v[172:175], v154
	ds_read_b128 v[176:179], v154 offset:1024
	ds_read_b128 v[180:183], v154 offset:2048
	ds_read_b128 v[184:187], v154 offset:3072
	s_add_u32 s22, s56, s20
	s_addc_u32 s23, s57, s21
	s_add_u32 s26, s22, 0x100
	s_addc_u32 s27, s23, 0
	s_add_i32 s65, s65, 2
	s_add_u32 s22, s22, 0x180
	s_addc_u32 s23, s23, 0
	s_mov_b32 s25, s55
	s_mov_b32 s24, s51
	v_lshl_add_u64 v[220:221], v[146:147], 0, s[20:21]
	s_add_i32 m0, s35, 0xc000
	ds_read_b128 v[188:191], v155
	ds_read_b128 v[192:195], v155 offset:1024
	ds_read_b128 v[196:199], v155 offset:2048
	ds_read_b128 v[200:203], v155 offset:3072
	ds_read_b128 v[204:207], v155 offset:4096
	ds_read_b128 v[208:211], v155 offset:5120
	ds_read_b128 v[212:215], v155 offset:6144
	ds_read_b128 v[216:219], v155 offset:7168
	global_load_lds_dwordx4 v[220:221], off
	v_lshl_add_u64 v[220:221], v[148:149], 0, s[20:21]
	s_add_i32 m0, s35, 0xe000
	s_nop 0
	global_load_lds_dwordx4 v[220:221], off
	s_waitcnt vmcnt(8) lgkmcnt(0)
	s_barrier
	v_mfma_f32_16x16x32_bf16 v[126:129], v[156:159], v[188:191], 0
	v_mfma_f32_16x16x32_bf16 v[122:125], v[164:167], v[188:191], 0
	v_mfma_f32_16x16x32_bf16 v[110:113], v[156:159], v[196:199], 0
	v_mfma_f32_16x16x32_bf16 v[106:109], v[164:167], v[196:199], 0
	v_mfma_f32_16x16x32_bf16 v[94:97], v[156:159], v[204:207], 0
	v_mfma_f32_16x16x32_bf16 v[90:93], v[164:167], v[204:207], 0
	v_mfma_f32_16x16x32_bf16 v[78:81], v[156:159], v[212:215], 0
	v_mfma_f32_16x16x32_bf16 v[74:77], v[164:167], v[212:215], 0
	v_mfma_f32_16x16x32_bf16 v[126:129], v[160:163], v[192:195], v[126:129]
	v_mfma_f32_16x16x32_bf16 v[122:125], v[168:171], v[192:195], v[122:125]
	v_mfma_f32_16x16x32_bf16 v[110:113], v[160:163], v[200:203], v[110:113]
	v_mfma_f32_16x16x32_bf16 v[106:109], v[168:171], v[200:203], v[106:109]
	v_mfma_f32_16x16x32_bf16 v[94:97], v[160:163], v[208:211], v[94:97]
	v_mfma_f32_16x16x32_bf16 v[90:93], v[168:171], v[208:211], v[90:93]
	v_mfma_f32_16x16x32_bf16 v[78:81], v[160:163], v[216:219], v[78:81]
	v_mfma_f32_16x16x32_bf16 v[74:77], v[168:171], v[216:219], v[74:77]
	v_mfma_f32_16x16x32_bf16 v[118:121], v[172:175], v[188:191], 0
	v_mfma_f32_16x16x32_bf16 v[114:117], v[180:183], v[188:191], 0
	v_mfma_f32_16x16x32_bf16 v[102:105], v[172:175], v[196:199], 0
	v_mfma_f32_16x16x32_bf16 v[98:101], v[180:183], v[196:199], 0
	v_mfma_f32_16x16x32_bf16 v[86:89], v[172:175], v[204:207], 0
	v_mfma_f32_16x16x32_bf16 v[82:85], v[180:183], v[204:207], 0
	v_mfma_f32_16x16x32_bf16 v[70:73], v[172:175], v[212:215], 0
	v_mfma_f32_16x16x32_bf16 v[66:69], v[180:183], v[212:215], 0
	v_mfma_f32_16x16x32_bf16 v[118:121], v[176:179], v[192:195], v[118:121]
	v_mfma_f32_16x16x32_bf16 v[114:117], v[184:187], v[192:195], v[114:117]
	v_mfma_f32_16x16x32_bf16 v[102:105], v[176:179], v[200:203], v[102:105]
	v_mfma_f32_16x16x32_bf16 v[98:101], v[184:187], v[200:203], v[98:101]
	v_mfma_f32_16x16x32_bf16 v[86:89], v[176:179], v[208:211], v[86:89]
	v_mfma_f32_16x16x32_bf16 v[82:85], v[184:187], v[208:211], v[82:85]
	v_mfma_f32_16x16x32_bf16 v[70:73], v[176:179], v[216:219], v[70:73]
	v_mfma_f32_16x16x32_bf16 v[66:69], v[184:187], v[216:219], v[66:69]
	s_barrier
	s_add_i32 s66, s72, s34
	s_mov_b32 m0, s66
	ds_read_b128 v[188:191], v155 offset:16384
	ds_read_b128 v[192:195], v155 offset:17408
	ds_read_b128 v[196:199], v155 offset:18432
	ds_read_b128 v[200:203], v155 offset:19456
	ds_read_b128 v[204:207], v155 offset:20480
	ds_read_b128 v[208:211], v155 offset:21504
	ds_read_b128 v[212:215], v155 offset:22528
	ds_read_b128 v[216:219], v155 offset:23552
	global_load_lds_dwordx4 v132, s[24:25]
	s_add_i32 m0, s66, 0x2000
	s_add_u32 s66, s24, 0x4000
	s_addc_u32 s67, s25, 0
	s_add_i32 s75, s73, s34
	global_load_lds_dwordx4 v136, s[24:25]
	s_mov_b32 m0, s75
	s_nop 0
	global_load_lds_dwordx4 v132, s[66:67]
	s_add_i32 m0, s75, 0x2000
	s_nop 0
	global_load_lds_dwordx4 v136, s[66:67]
	s_mov_b32 m0, s35
	s_nop 0
	global_load_lds_dwordx4 v130, s[26:27]
	s_mov_b32 m0, s36
	s_nop 0
	global_load_lds_dwordx4 v134, s[26:27]
	s_waitcnt vmcnt(8) lgkmcnt(0)
	s_barrier
; #define PG8_STAGE(bufoff, gbase, voff) do { _Pragma("unroll") for (int _i = 0; _i < 2; ++_i) \
;         __builtin_amdgcn_global_load_lds((const unsigned*)((const char*)(gbase) + (voff)[_i]), (LAS unsigned*)(lds + (bufoff) + ldsw + _i * 8192), 16, 0, 0); } while (0)
; #define PG8_LDA(dst, b, h) do { _Pragma("unroll") for (int m = 0; m < 4; ++m) _Pragma("unroll") for (int k = 0; k < 2; ++k) dst[m][k] = *(const LAS bf16x8*)(lds + PG8_SA(b, h) + aoff + m * 2048 + k * 1024); } while (0)
; #define PG8_LDB(dst, b, h) do { _Pragma("unroll") for (int n = 0; n < 2; ++n) _Pragma("unroll") for (int k = 0; k < 2; ++k) dst[n][k] = *(const LAS bf16x8*)(lds + PG8_SB(b, h) + boff + n * 2048 + k * 1024); } while (0)
; #define PG8_MMA(ai, bj, At, Bt) do { __builtin_amdgcn_s_setprio(1); _Pragma("unroll") for (int m = 0; m < 4; ++m) _Pragma("unroll") for (int n = 0; n < 2; ++n) _Pragma("unroll") for (int k = 0; k < 2; ++k) \
;         acc[ai][bj][m][n] = __builtin_amdgcn_mfma_f32_16x16x32_bf16(Bt[n][k], At[m][k], acc[ai][bj][m][n], 0, 0, 0); __builtin_amdgcn_s_setprio(0); } while (0)
; #define PG8_WAIT_V(n) asm volatile("s_waitcnt vmcnt(" #n ")" ::: "memory")
; #define PG8_WAIT_L(n) asm volatile("s_waitcnt lgkmcnt(" #n ")" ::: "memory")
; #define PG8_BAR __builtin_amdgcn_s_barrier()
; #define PG8_SCHED __builtin_amdgcn_sched_barrier(0)
; template <class Epi, class Sched, bool ABLK = false, bool ALIGN_EPI = true, bool SP2 = true, bool BBLK = true>
; __device__ __forceinline__ void gemm_phase(LAS unsigned char* lds, const Gemm g, const Sched& S, const Epi& E) {
;     ...
;             PG8_WAIT_V(8); PG8_WAIT_L(0); PG8_BAR; PG8_MMA(1, 0, At, B0); PG8_MMA(1, 1, At, B1); PG8_BAR; PG8_SCHED;
;             PG8_LDB(B0, 1, 0); PG8_LDB(B1, 1, 1); PG8_SCHED; PG8_LDA(At, 1, 0); PG8_STAGE(PG8_SA(0, 1), a2 + hstepA, voffA);
;             PG8_WAIT_V(8); PG8_WAIT_L(0); PG8_BAR; PG8_MMA(0, 0, At, B0); PG8_MMA(0, 1, At, B1); PG8_BAR; PG8_SCHED;
;             PG8_LDA(At, 1, 1); PG8_STAGE(PG8_SB(1, 0), b3, voffB); PG8_STAGE(PG8_SB(1, 1), b3 + hstepB, voffB); PG8_STAGE(PG8_SA(1, 0), a3, voffA);
	v_mfma_f32_16x16x32_bf16 v[62:65], v[156:159], v[188:191], 0
	v_mfma_f32_16x16x32_bf16 v[58:61], v[164:167], v[188:191], 0
	v_mfma_f32_16x16x32_bf16 v[46:49], v[156:159], v[196:199], 0
	v_mfma_f32_16x16x32_bf16 v[42:45], v[164:167], v[196:199], 0
	v_mfma_f32_16x16x32_bf16 v[30:33], v[156:159], v[204:207], 0
	v_mfma_f32_16x16x32_bf16 v[26:29], v[164:167], v[204:207], 0
	v_mfma_f32_16x16x32_bf16 v[14:17], v[156:159], v[212:215], 0
	v_mfma_f32_16x16x32_bf16 v[10:13], v[164:167], v[212:215], 0
	v_mfma_f32_16x16x32_bf16 v[62:65], v[160:163], v[192:195], v[62:65]
	v_mfma_f32_16x16x32_bf16 v[58:61], v[168:171], v[192:195], v[58:61]
	v_mfma_f32_16x16x32_bf16 v[46:49], v[160:163], v[200:203], v[46:49]
	v_mfma_f32_16x16x32_bf16 v[42:45], v[168:171], v[200:203], v[42:45]
	v_mfma_f32_16x16x32_bf16 v[30:33], v[160:163], v[208:211], v[30:33]
	v_mfma_f32_16x16x32_bf16 v[26:29], v[168:171], v[208:211], v[26:29]
	v_mfma_f32_16x16x32_bf16 v[14:17], v[160:163], v[216:219], v[14:17]
	v_mfma_f32_16x16x32_bf16 v[10:13], v[168:171], v[216:219], v[10:13]
	v_mfma_f32_16x16x32_bf16 v[54:57], v[172:175], v[188:191], 0
	v_mfma_f32_16x16x32_bf16 v[50:53], v[180:183], v[188:191], 0
	v_mfma_f32_16x16x32_bf16 v[38:41], v[172:175], v[196:199], 0
	v_mfma_f32_16x16x32_bf16 v[34:37], v[180:183], v[196:199], 0
	v_mfma_f32_16x16x32_bf16 v[22:25], v[172:175], v[204:207], 0
	v_mfma_f32_16x16x32_bf16 v[18:21], v[180:183], v[204:207], 0
	v_mfma_f32_16x16x32_bf16 v[6:9], v[172:175], v[212:215], 0
	v_mfma_f32_16x16x32_bf16 v[2:5], v[180:183], v[212:215], 0
	v_mfma_f32_16x16x32_bf16 v[54:57], v[176:179], v[192:195], v[54:57]
	v_mfma_f32_16x16x32_bf16 v[50:53], v[184:187], v[192:195], v[50:53]
	v_mfma_f32_16x16x32_bf16 v[38:41], v[176:179], v[200:203], v[38:41]
	v_mfma_f32_16x16x32_bf16 v[34:37], v[184:187], v[200:203], v[34:37]
	v_mfma_f32_16x16x32_bf16 v[22:25], v[176:179], v[208:211], v[22:25]
	v_mfma_f32_16x16x32_bf16 v[18:21], v[184:187], v[208:211], v[18:21]
	v_mfma_f32_16x16x32_bf16 v[6:9], v[176:179], v[216:219], v[6:9]
	v_mfma_f32_16x16x32_bf16 v[2:5], v[184:187], v[216:219], v[2:5]
	s_barrier
	v_add_u32_e32 v168, s60, v151
	v_add_u32_e32 v184, s61, v151
	ds_read_b128 v[156:159], v168
	ds_read_b128 v[160:163], v168 offset:1024
	ds_read_b128 v[164:167], v168 offset:2048
	ds_read_b128 v[168:171], v168 offset:3072
	ds_read_b128 v[172:175], v184
	ds_read_b128 v[176:179], v184 offset:1024
	ds_read_b128 v[180:183], v184 offset:2048
	ds_read_b128 v[184:187], v184 offset:3072
	s_add_u32 s26, s26, 0x80000
	s_addc_u32 s27, s27, 0
	s_mov_b32 m0, s37
	ds_read_b128 v[188:191], v155 offset:32768
	ds_read_b128 v[192:195], v155 offset:33792
	ds_read_b128 v[196:199], v155 offset:34816
	ds_read_b128 v[200:203], v155 offset:35840
	ds_read_b128 v[204:207], v155 offset:36864
	ds_read_b128 v[208:211], v155 offset:37888
	ds_read_b128 v[212:215], v155 offset:38912
	ds_read_b128 v[216:219], v155 offset:39936
	global_load_lds_dwordx4 v130, s[26:27]
	s_mov_b32 m0, s40
	s_nop 0
	global_load_lds_dwordx4 v134, s[26:27]
	s_waitcnt vmcnt(8) lgkmcnt(0)
	s_barrier
	v_mfma_f32_16x16x32_bf16 v[126:129], v[156:159], v[188:191], v[126:129]
	v_mfma_f32_16x16x32_bf16 v[122:125], v[164:167], v[188:191], v[122:125]
	v_mfma_f32_16x16x32_bf16 v[110:113], v[156:159], v[196:199], v[110:113]
	v_mfma_f32_16x16x32_bf16 v[106:109], v[164:167], v[196:199], v[106:109]
	v_mfma_f32_16x16x32_bf16 v[94:97], v[156:159], v[204:207], v[94:97]
	v_mfma_f32_16x16x32_bf16 v[90:93], v[164:167], v[204:207], v[90:93]
	v_mfma_f32_16x16x32_bf16 v[78:81], v[156:159], v[212:215], v[78:81]
	v_mfma_f32_16x16x32_bf16 v[74:77], v[164:167], v[212:215], v[74:77]
	v_mfma_f32_16x16x32_bf16 v[126:129], v[160:163], v[192:195], v[126:129]
	v_mfma_f32_16x16x32_bf16 v[122:125], v[168:171], v[192:195], v[122:125]
	v_mfma_f32_16x16x32_bf16 v[110:113], v[160:163], v[200:203], v[110:113]
	v_mfma_f32_16x16x32_bf16 v[106:109], v[168:171], v[200:203], v[106:109]
	v_mfma_f32_16x16x32_bf16 v[94:97], v[160:163], v[208:211], v[94:97]
	v_mfma_f32_16x16x32_bf16 v[90:93], v[168:171], v[208:211], v[90:93]
	v_mfma_f32_16x16x32_bf16 v[78:81], v[160:163], v[216:219], v[78:81]
	v_mfma_f32_16x16x32_bf16 v[74:77], v[168:171], v[216:219], v[74:77]
	v_mfma_f32_16x16x32_bf16 v[118:121], v[172:175], v[188:191], v[118:121]
	v_mfma_f32_16x16x32_bf16 v[114:117], v[180:183], v[188:191], v[114:117]
	v_mfma_f32_16x16x32_bf16 v[102:105], v[172:175], v[196:199], v[102:105]
	v_mfma_f32_16x16x32_bf16 v[98:101], v[180:183], v[196:199], v[98:101]
	v_mfma_f32_16x16x32_bf16 v[86:89], v[172:175], v[204:207], v[86:89]
	v_mfma_f32_16x16x32_bf16 v[82:85], v[180:183], v[204:207], v[82:85]
	v_mfma_f32_16x16x32_bf16 v[70:73], v[172:175], v[212:215], v[70:73]
	v_mfma_f32_16x16x32_bf16 v[66:69], v[180:183], v[212:215], v[66:69]
	v_mfma_f32_16x16x32_bf16 v[118:121], v[176:179], v[192:195], v[118:121]
	v_mfma_f32_16x16x32_bf16 v[114:117], v[184:187], v[192:195], v[114:117]
	v_mfma_f32_16x16x32_bf16 v[102:105], v[176:179], v[200:203], v[102:105]
	v_mfma_f32_16x16x32_bf16 v[98:101], v[184:187], v[200:203], v[98:101]
	v_mfma_f32_16x16x32_bf16 v[86:89], v[176:179], v[208:211], v[86:89]
	v_mfma_f32_16x16x32_bf16 v[82:85], v[184:187], v[208:211], v[82:85]
	v_mfma_f32_16x16x32_bf16 v[70:73], v[176:179], v[216:219], v[70:73]
	v_mfma_f32_16x16x32_bf16 v[66:69], v[184:187], v[216:219], v[66:69]
	s_barrier
; #define PG8_STAGE(bufoff, gbase, voff) do { _Pragma("unroll") for (int _i = 0; _i < 2; ++_i) \
;         __builtin_amdgcn_global_load_lds((const unsigned*)((const char*)(gbase) + (voff)[_i]), (LAS unsigned*)(lds + (bufoff) + ldsw + _i * 8192), 16, 0, 0); } while (0)
; #define PG8_LDA(dst, b, h) do { _Pragma("unroll") for (int m = 0; m < 4; ++m) _Pragma("unroll") for (int k = 0; k < 2; ++k) dst[m][k] = *(const LAS bf16x8*)(lds + PG8_SA(b, h) + aoff + m * 2048 + k * 1024); } while (0)
; #define PG8_WAIT_V(n) asm volatile("s_waitcnt vmcnt(" #n ")" ::: "memory")
; #define PG8_WAIT_L(n) asm volatile("s_waitcnt lgkmcnt(" #n ")" ::: "memory")
; template <class Epi, class Sched, bool ABLK = false, bool ALIGN_EPI = true, bool SP2 = true, bool BBLK = true>
; __device__ __forceinline__ void gemm_phase(LAS unsigned char* lds, const Gemm g, const Sched& S, const Epi& E) {
;     ...
;         for (int t = 0; t < nt; t += 2) {
;             const bool last = (t == nt - 2);
;             const char* a1 = a_tile(uA, tbA + t + 1);
;             const char* a2 = last ? a_tile(nuA, ntbA) : a_tile(uA, tbA + t + 2); const char* b2 = last ? nB : cB + (size_t)(t + 2) * kstepB;
;             const char* a3 = last ? a_tile(nuA, ntbA + 1) : a_tile(uA, tbA + t + 3); const char* b3 = b2 + kstepB;
;             if (last && has_next) S.a_ready(nxt);
;             if constexpr (SP2) {
;             PG8_LDB(B0, 0, 0); PG8_LDB(B1, 0, 1); PG8_SCHED; PG8_LDA(At, 0, 0); PG8_STAGE(PG8_SA(1, 1), a1 + hstepA, voffA);
;             PG8_WAIT_V(8); PG8_WAIT_L(0); PG8_BAR; PG8_MMA(0, 0, At, B0); PG8_MMA(0, 1, At, B1); PG8_BAR; PG8_SCHED;
;             PG8_LDA(At, 0, 1); PG8_STAGE(PG8_SB(0, 0), b2, voffB); PG8_STAGE(PG8_SB(0, 1), b2 + hstepB, voffB); PG8_STAGE(PG8_SA(0, 0), a2, voffA);
;             PG8_WAIT_V(8); PG8_WAIT_L(0); PG8_BAR; PG8_MMA(1, 0, At, B0); PG8_MMA(1, 1, At, B1); PG8_BAR; PG8_SCHED;
;             PG8_LDB(B0, 1, 0); PG8_LDB(B1, 1, 1); PG8_SCHED; PG8_LDA(At, 1, 0); PG8_STAGE(PG8_SA(0, 1), a2 + hstepA, voffA);
;             PG8_WAIT_V(8); PG8_WAIT_L(0); PG8_BAR; PG8_MMA(0, 0, At, B0); PG8_MMA(0, 1, At, B1); PG8_BAR; PG8_SCHED;
;             PG8_LDA(At, 1, 1); PG8_STAGE(PG8_SB(1, 0), b3, voffB); PG8_STAGE(PG8_SB(1, 1), b3 + hstepB, voffB); PG8_STAGE(PG8_SA(1, 0), a3, voffA);
;             PG8_WAIT_V(8); PG8_WAIT_L(0); PG8_BAR; PG8_MMA(1, 0, At, B0); PG8_MMA(1, 1, At, B1); PG8_BAR; PG8_SCHED;
	s_add_u32 s26, s24, 0x8000
	s_addc_u32 s27, s25, 0
	s_add_i32 s66, s60, s34
	s_mov_b32 m0, s66
	ds_read_b128 v[188:191], v155 offset:49152
	ds_read_b128 v[192:195], v155 offset:50176
	ds_read_b128 v[196:199], v155 offset:51200
	ds_read_b128 v[200:203], v155 offset:52224
	ds_read_b128 v[204:207], v155 offset:53248
	ds_read_b128 v[208:211], v155 offset:54272
	ds_read_b128 v[212:215], v155 offset:55296
	ds_read_b128 v[216:219], v155 offset:56320
	global_load_lds_dwordx4 v132, s[26:27]
	s_add_i32 m0, s66, 0x2000
	s_add_u32 s24, s24, 0xc000
	v_lshl_add_u64 v[220:221], s[26:27], 0, v[136:137]
	s_addc_u32 s25, s25, 0
	s_add_i32 s26, s61, s34
	global_load_lds_dwordx4 v[220:221], off
	s_mov_b32 m0, s26
	s_nop 0
	global_load_lds_dwordx4 v132, s[24:25]
	s_add_i32 m0, s26, 0x2000
	s_nop 0
	global_load_lds_dwordx4 v136, s[24:25]
	s_mov_b32 m0, s41
	s_nop 0
	global_load_lds_dwordx4 v130, s[22:23]
	s_mov_b32 m0, s42
	s_nop 0
	global_load_lds_dwordx4 v134, s[22:23]
	s_waitcnt vmcnt(8) lgkmcnt(0)
	s_barrier
	v_mfma_f32_16x16x32_bf16 v[62:65], v[156:159], v[188:191], v[62:65]
	v_mfma_f32_16x16x32_bf16 v[58:61], v[164:167], v[188:191], v[58:61]
	v_mfma_f32_16x16x32_bf16 v[46:49], v[156:159], v[196:199], v[46:49]
	v_mfma_f32_16x16x32_bf16 v[42:45], v[164:167], v[196:199], v[42:45]
	v_mfma_f32_16x16x32_bf16 v[30:33], v[156:159], v[204:207], v[30:33]
	v_mfma_f32_16x16x32_bf16 v[26:29], v[164:167], v[204:207], v[26:29]
	v_mfma_f32_16x16x32_bf16 v[14:17], v[156:159], v[212:215], v[14:17]
	v_mfma_f32_16x16x32_bf16 v[10:13], v[164:167], v[212:215], v[10:13]
	v_mfma_f32_16x16x32_bf16 v[62:65], v[160:163], v[192:195], v[62:65]
	v_mfma_f32_16x16x32_bf16 v[58:61], v[168:171], v[192:195], v[58:61]
	v_mfma_f32_16x16x32_bf16 v[46:49], v[160:163], v[200:203], v[46:49]
	v_mfma_f32_16x16x32_bf16 v[42:45], v[168:171], v[200:203], v[42:45]
	v_mfma_f32_16x16x32_bf16 v[30:33], v[160:163], v[208:211], v[30:33]
	v_mfma_f32_16x16x32_bf16 v[26:29], v[168:171], v[208:211], v[26:29]
	v_mfma_f32_16x16x32_bf16 v[14:17], v[160:163], v[216:219], v[14:17]
	v_mfma_f32_16x16x32_bf16 v[10:13], v[168:171], v[216:219], v[10:13]
	v_mfma_f32_16x16x32_bf16 v[54:57], v[172:175], v[188:191], v[54:57]
	v_mfma_f32_16x16x32_bf16 v[50:53], v[180:183], v[188:191], v[50:53]
	v_mfma_f32_16x16x32_bf16 v[38:41], v[172:175], v[196:199], v[38:41]
	v_mfma_f32_16x16x32_bf16 v[34:37], v[180:183], v[196:199], v[34:37]
	v_mfma_f32_16x16x32_bf16 v[22:25], v[172:175], v[204:207], v[22:25]
	v_mfma_f32_16x16x32_bf16 v[18:21], v[180:183], v[204:207], v[18:21]
	v_mfma_f32_16x16x32_bf16 v[6:9], v[172:175], v[212:215], v[6:9]
	v_mfma_f32_16x16x32_bf16 v[2:5], v[180:183], v[212:215], v[2:5]
	v_mfma_f32_16x16x32_bf16 v[54:57], v[176:179], v[192:195], v[54:57]
	v_mfma_f32_16x16x32_bf16 v[50:53], v[184:187], v[192:195], v[50:53]
	v_mfma_f32_16x16x32_bf16 v[38:41], v[176:179], v[200:203], v[38:41]
	v_mfma_f32_16x16x32_bf16 v[34:37], v[184:187], v[200:203], v[34:37]
	v_mfma_f32_16x16x32_bf16 v[22:25], v[176:179], v[208:211], v[22:25]
	v_mfma_f32_16x16x32_bf16 v[18:21], v[184:187], v[208:211], v[18:21]
	v_mfma_f32_16x16x32_bf16 v[6:9], v[176:179], v[216:219], v[6:9]
	v_mfma_f32_16x16x32_bf16 v[2:5], v[184:187], v[216:219], v[2:5]
	s_barrier
	s_add_u32 s51, s51, 0x10000
	s_addc_u32 s55, s55, 0
	s_add_u32 s20, s20, 0x100
	s_addc_u32 s21, s21, 0
	s_cmp_ge_u32 s65, s46
.LBB0_1038:
	ds_read_b128 v[156:159], v153
	ds_read_b128 v[160:163], v153 offset:1024
	ds_read_b128 v[164:167], v153 offset:2048
	ds_read_b128 v[168:171], v153 offset:3072
	ds_read_b128 v[172:175], v154
	ds_read_b128 v[176:179], v154 offset:1024
	ds_read_b128 v[180:183], v154 offset:2048
	ds_read_b128 v[184:187], v154 offset:3072
	s_add_u32 s22, s56, s20
	s_addc_u32 s23, s57, s21
	s_add_u32 s26, s22, 0x100
	s_addc_u32 s27, s23, 0
	s_add_i32 s65, s65, 2
	s_add_u32 s22, s22, 0x180
	s_addc_u32 s23, s23, 0
	s_cmp_eq_u32 s64, s20
	s_cbranch_scc1 .Lksel_9
	s_mov_b32 s25, s55
	s_mov_b32 s24, s51
.Lksel_9_back:
	v_lshl_add_u64 v[220:221], v[146:147], 0, s[20:21]
	s_add_i32 m0, s35, 0xc000
	ds_read_b128 v[188:191], v155
	ds_read_b128 v[192:195], v155 offset:1024
	ds_read_b128 v[196:199], v155 offset:2048
	ds_read_b128 v[200:203], v155 offset:3072
	ds_read_b128 v[204:207], v155 offset:4096
	ds_read_b128 v[208:211], v155 offset:5120
	ds_read_b128 v[212:215], v155 offset:6144
	ds_read_b128 v[216:219], v155 offset:7168
	global_load_lds_dwordx4 v[220:221], off
	v_lshl_add_u64 v[220:221], v[148:149], 0, s[20:21]
	s_add_i32 m0, s35, 0xe000
	s_nop 0
	global_load_lds_dwordx4 v[220:221], off
	s_waitcnt vmcnt(8) lgkmcnt(0)
	s_barrier
; #define PG8_STAGE(bufoff, gbase, voff) do { _Pragma("unroll") for (int _i = 0; _i < 2; ++_i) \
;         __builtin_amdgcn_global_load_lds((const unsigned*)((const char*)(gbase) + (voff)[_i]), (LAS unsigned*)(lds + (bufoff) + ldsw + _i * 8192), 16, 0, 0); } while (0)
; #define PG8_LDA(dst, b, h) do { _Pragma("unroll") for (int m = 0; m < 4; ++m) _Pragma("unroll") for (int k = 0; k < 2; ++k) dst[m][k] = *(const LAS bf16x8*)(lds + PG8_SA(b, h) + aoff + m * 2048 + k * 1024); } while (0)
; #define PG8_LDB(dst, b, h) do { _Pragma("unroll") for (int n = 0; n < 2; ++n) _Pragma("unroll") for (int k = 0; k < 2; ++k) dst[n][k] = *(const LAS bf16x8*)(lds + PG8_SB(b, h) + boff + n * 2048 + k * 1024); } while (0)
; #define PG8_MMA(ai, bj, At, Bt) do { __builtin_amdgcn_s_setprio(1); _Pragma("unroll") for (int m = 0; m < 4; ++m) _Pragma("unroll") for (int n = 0; n < 2; ++n) _Pragma("unroll") for (int k = 0; k < 2; ++k) \
;         acc[ai][bj][m][n] = __builtin_amdgcn_mfma_f32_16x16x32_bf16(Bt[n][k], At[m][k], acc[ai][bj][m][n], 0, 0, 0); __builtin_amdgcn_s_setprio(0); } while (0)
; #define PG8_WAIT_V(n) asm volatile("s_waitcnt vmcnt(" #n ")" ::: "memory")
; #define PG8_WAIT_L(n) asm volatile("s_waitcnt lgkmcnt(" #n ")" ::: "memory")
; #define PG8_BAR __builtin_amdgcn_s_barrier()
; #define PG8_SCHED __builtin_amdgcn_sched_barrier(0)
; template <class Epi, class Sched, bool ABLK = false, bool ALIGN_EPI = true, bool SP2 = true, bool BBLK = true>
; __device__ __forceinline__ void gemm_phase(LAS unsigned char* lds, const Gemm g, const Sched& S, const Epi& E) {
;     ...
;             PG8_LDB(B0, 0, 0); PG8_LDB(B1, 0, 1); PG8_SCHED; PG8_LDA(At, 0, 0); PG8_STAGE(PG8_SA(1, 1), a1 + hstepA, voffA);
;             PG8_WAIT_V(8); PG8_WAIT_L(0); PG8_BAR; PG8_MMA(0, 0, At, B0); PG8_MMA(0, 1, At, B1); PG8_BAR; PG8_SCHED;
;             PG8_LDA(At, 0, 1); PG8_STAGE(PG8_SB(0, 0), b2, voffB); PG8_STAGE(PG8_SB(0, 1), b2 + hstepB, voffB); PG8_STAGE(PG8_SA(0, 0), a2, voffA);
;             PG8_WAIT_V(8); PG8_WAIT_L(0); PG8_BAR; PG8_MMA(1, 0, At, B0); PG8_MMA(1, 1, At, B1); PG8_BAR; PG8_SCHED;
;             PG8_LDB(B0, 1, 0); PG8_LDB(B1, 1, 1); PG8_SCHED; PG8_LDA(At, 1, 0); PG8_STAGE(PG8_SA(0, 1), a2 + hstepA, voffA);
;             PG8_WAIT_V(8); PG8_WAIT_L(0); PG8_BAR; PG8_MMA(0, 0, At, B0); PG8_MMA(0, 1, At, B1); PG8_BAR; PG8_SCHED;
	v_mfma_f32_16x16x32_bf16 v[126:129], v[156:159], v[188:191], v[126:129]
	v_mfma_f32_16x16x32_bf16 v[122:125], v[164:167], v[188:191], v[122:125]
	v_mfma_f32_16x16x32_bf16 v[110:113], v[156:159], v[196:199], v[110:113]
	v_mfma_f32_16x16x32_bf16 v[106:109], v[164:167], v[196:199], v[106:109]
	v_mfma_f32_16x16x32_bf16 v[94:97], v[156:159], v[204:207], v[94:97]
	v_mfma_f32_16x16x32_bf16 v[90:93], v[164:167], v[204:207], v[90:93]
	v_mfma_f32_16x16x32_bf16 v[78:81], v[156:159], v[212:215], v[78:81]
	v_mfma_f32_16x16x32_bf16 v[74:77], v[164:167], v[212:215], v[74:77]
	v_mfma_f32_16x16x32_bf16 v[126:129], v[160:163], v[192:195], v[126:129]
	v_mfma_f32_16x16x32_bf16 v[122:125], v[168:171], v[192:195], v[122:125]
	v_mfma_f32_16x16x32_bf16 v[110:113], v[160:163], v[200:203], v[110:113]
	v_mfma_f32_16x16x32_bf16 v[106:109], v[168:171], v[200:203], v[106:109]
	v_mfma_f32_16x16x32_bf16 v[94:97], v[160:163], v[208:211], v[94:97]
	v_mfma_f32_16x16x32_bf16 v[90:93], v[168:171], v[208:211], v[90:93]
	v_mfma_f32_16x16x32_bf16 v[78:81], v[160:163], v[216:219], v[78:81]
	v_mfma_f32_16x16x32_bf16 v[74:77], v[168:171], v[216:219], v[74:77]
	v_mfma_f32_16x16x32_bf16 v[118:121], v[172:175], v[188:191], v[118:121]
	v_mfma_f32_16x16x32_bf16 v[114:117], v[180:183], v[188:191], v[114:117]
	v_mfma_f32_16x16x32_bf16 v[102:105], v[172:175], v[196:199], v[102:105]
	v_mfma_f32_16x16x32_bf16 v[98:101], v[180:183], v[196:199], v[98:101]
	v_mfma_f32_16x16x32_bf16 v[86:89], v[172:175], v[204:207], v[86:89]
	v_mfma_f32_16x16x32_bf16 v[82:85], v[180:183], v[204:207], v[82:85]
	v_mfma_f32_16x16x32_bf16 v[70:73], v[172:175], v[212:215], v[70:73]
	v_mfma_f32_16x16x32_bf16 v[66:69], v[180:183], v[212:215], v[66:69]
	v_mfma_f32_16x16x32_bf16 v[118:121], v[176:179], v[192:195], v[118:121]
	v_mfma_f32_16x16x32_bf16 v[114:117], v[184:187], v[192:195], v[114:117]
	v_mfma_f32_16x16x32_bf16 v[102:105], v[176:179], v[200:203], v[102:105]
	v_mfma_f32_16x16x32_bf16 v[98:101], v[184:187], v[200:203], v[98:101]
	v_mfma_f32_16x16x32_bf16 v[86:89], v[176:179], v[208:211], v[86:89]
	v_mfma_f32_16x16x32_bf16 v[82:85], v[184:187], v[208:211], v[82:85]
	v_mfma_f32_16x16x32_bf16 v[70:73], v[176:179], v[216:219], v[70:73]
	v_mfma_f32_16x16x32_bf16 v[66:69], v[184:187], v[216:219], v[66:69]
	s_barrier
	s_add_i32 s66, s72, s34
	s_mov_b32 m0, s66
	ds_read_b128 v[188:191], v155 offset:16384
	ds_read_b128 v[192:195], v155 offset:17408
	ds_read_b128 v[196:199], v155 offset:18432
	ds_read_b128 v[200:203], v155 offset:19456
	ds_read_b128 v[204:207], v155 offset:20480
	ds_read_b128 v[208:211], v155 offset:21504
	ds_read_b128 v[212:215], v155 offset:22528
	ds_read_b128 v[216:219], v155 offset:23552
	global_load_lds_dwordx4 v132, s[24:25]
	s_add_i32 m0, s66, 0x2000
	s_add_u32 s66, s24, 0x4000
	s_addc_u32 s67, s25, 0
	s_add_i32 s75, s73, s34
	global_load_lds_dwordx4 v136, s[24:25]
	s_mov_b32 m0, s75
	s_nop 0
	global_load_lds_dwordx4 v132, s[66:67]
	s_add_i32 m0, s75, 0x2000
	s_nop 0
	global_load_lds_dwordx4 v136, s[66:67]
	s_mov_b32 m0, s35
	s_nop 0
	global_load_lds_dwordx4 v130, s[26:27]
	s_mov_b32 m0, s36
	s_nop 0
	global_load_lds_dwordx4 v134, s[26:27]
	s_waitcnt vmcnt(8) lgkmcnt(0)
	s_barrier
	v_mfma_f32_16x16x32_bf16 v[62:65], v[156:159], v[188:191], v[62:65]
	v_mfma_f32_16x16x32_bf16 v[58:61], v[164:167], v[188:191], v[58:61]
	v_mfma_f32_16x16x32_bf16 v[46:49], v[156:159], v[196:199], v[46:49]
	v_mfma_f32_16x16x32_bf16 v[42:45], v[164:167], v[196:199], v[42:45]
	v_mfma_f32_16x16x32_bf16 v[30:33], v[156:159], v[204:207], v[30:33]
	v_mfma_f32_16x16x32_bf16 v[26:29], v[164:167], v[204:207], v[26:29]
	v_mfma_f32_16x16x32_bf16 v[14:17], v[156:159], v[212:215], v[14:17]
	v_mfma_f32_16x16x32_bf16 v[10:13], v[164:167], v[212:215], v[10:13]
	v_mfma_f32_16x16x32_bf16 v[62:65], v[160:163], v[192:195], v[62:65]
	v_mfma_f32_16x16x32_bf16 v[58:61], v[168:171], v[192:195], v[58:61]
	v_mfma_f32_16x16x32_bf16 v[46:49], v[160:163], v[200:203], v[46:49]
	v_mfma_f32_16x16x32_bf16 v[42:45], v[168:171], v[200:203], v[42:45]
	v_mfma_f32_16x16x32_bf16 v[30:33], v[160:163], v[208:211], v[30:33]
	v_mfma_f32_16x16x32_bf16 v[26:29], v[168:171], v[208:211], v[26:29]
	v_mfma_f32_16x16x32_bf16 v[14:17], v[160:163], v[216:219], v[14:17]
	v_mfma_f32_16x16x32_bf16 v[10:13], v[168:171], v[216:219], v[10:13]
	v_mfma_f32_16x16x32_bf16 v[54:57], v[172:175], v[188:191], v[54:57]
	v_mfma_f32_16x16x32_bf16 v[50:53], v[180:183], v[188:191], v[50:53]
	v_mfma_f32_16x16x32_bf16 v[38:41], v[172:175], v[196:199], v[38:41]
	v_mfma_f32_16x16x32_bf16 v[34:37], v[180:183], v[196:199], v[34:37]
	v_mfma_f32_16x16x32_bf16 v[22:25], v[172:175], v[204:207], v[22:25]
	v_mfma_f32_16x16x32_bf16 v[18:21], v[180:183], v[204:207], v[18:21]
	v_mfma_f32_16x16x32_bf16 v[6:9], v[172:175], v[212:215], v[6:9]
	v_mfma_f32_16x16x32_bf16 v[2:5], v[180:183], v[212:215], v[2:5]
	v_mfma_f32_16x16x32_bf16 v[54:57], v[176:179], v[192:195], v[54:57]
	v_mfma_f32_16x16x32_bf16 v[50:53], v[184:187], v[192:195], v[50:53]
	v_mfma_f32_16x16x32_bf16 v[38:41], v[176:179], v[200:203], v[38:41]
	v_mfma_f32_16x16x32_bf16 v[34:37], v[184:187], v[200:203], v[34:37]
	v_mfma_f32_16x16x32_bf16 v[22:25], v[176:179], v[208:211], v[22:25]
	v_mfma_f32_16x16x32_bf16 v[18:21], v[184:187], v[208:211], v[18:21]
	v_mfma_f32_16x16x32_bf16 v[6:9], v[176:179], v[216:219], v[6:9]
	v_mfma_f32_16x16x32_bf16 v[2:5], v[184:187], v[216:219], v[2:5]
	s_barrier
; #define PG8_STAGE(bufoff, gbase, voff) do { _Pragma("unroll") for (int _i = 0; _i < 2; ++_i) \
;         __builtin_amdgcn_global_load_lds((const unsigned*)((const char*)(gbase) + (voff)[_i]), (LAS unsigned*)(lds + (bufoff) + ldsw + _i * 8192), 16, 0, 0); } while (0)
; #define PG8_LDA(dst, b, h) do { _Pragma("unroll") for (int m = 0; m < 4; ++m) _Pragma("unroll") for (int k = 0; k < 2; ++k) dst[m][k] = *(const LAS bf16x8*)(lds + PG8_SA(b, h) + aoff + m * 2048 + k * 1024); } while (0)
; #define PG8_LDB(dst, b, h) do { _Pragma("unroll") for (int n = 0; n < 2; ++n) _Pragma("unroll") for (int k = 0; k < 2; ++k) dst[n][k] = *(const LAS bf16x8*)(lds + PG8_SB(b, h) + boff + n * 2048 + k * 1024); } while (0)
; #define PG8_MMA(ai, bj, At, Bt) do { __builtin_amdgcn_s_setprio(1); _Pragma("unroll") for (int m = 0; m < 4; ++m) _Pragma("unroll") for (int n = 0; n < 2; ++n) _Pragma("unroll") for (int k = 0; k < 2; ++k) \
;         acc[ai][bj][m][n] = __builtin_amdgcn_mfma_f32_16x16x32_bf16(Bt[n][k], At[m][k], acc[ai][bj][m][n], 0, 0, 0); __builtin_amdgcn_s_setprio(0); } while (0)
; #define PG8_WAIT_V(n) asm volatile("s_waitcnt vmcnt(" #n ")" ::: "memory")
; #define PG8_WAIT_L(n) asm volatile("s_waitcnt lgkmcnt(" #n ")" ::: "memory")
; #define PG8_BAR __builtin_amdgcn_s_barrier()
; #define PG8_SCHED __builtin_amdgcn_sched_barrier(0)
; template <class Epi, class Sched, bool ABLK = false, bool ALIGN_EPI = true, bool SP2 = true, bool BBLK = true>
; __device__ __forceinline__ void gemm_phase(LAS unsigned char* lds, const Gemm g, const Sched& S, const Epi& E) {
;     ...
;             PG8_LDB(B0, 1, 0); PG8_LDB(B1, 1, 1); PG8_SCHED; PG8_LDA(At, 1, 0); PG8_STAGE(PG8_SA(0, 1), a2 + hstepA, voffA);
;             PG8_WAIT_V(8); PG8_WAIT_L(0); PG8_BAR; PG8_MMA(0, 0, At, B0); PG8_MMA(0, 1, At, B1); PG8_BAR; PG8_SCHED;
;             PG8_LDA(At, 1, 1); PG8_STAGE(PG8_SB(1, 0), b3, voffB); PG8_STAGE(PG8_SB(1, 1), b3 + hstepB, voffB); PG8_STAGE(PG8_SA(1, 0), a3, voffA);
;             PG8_WAIT_V(8); PG8_WAIT_L(0); PG8_BAR; PG8_MMA(1, 0, At, B0); PG8_MMA(1, 1, At, B1); PG8_BAR; PG8_SCHED;
	v_add_u32_e32 v168, s60, v151
	v_add_u32_e32 v184, s61, v151
	ds_read_b128 v[156:159], v168
	ds_read_b128 v[160:163], v168 offset:1024
	ds_read_b128 v[164:167], v168 offset:2048
	ds_read_b128 v[168:171], v168 offset:3072
	ds_read_b128 v[172:175], v184
	ds_read_b128 v[176:179], v184 offset:1024
	ds_read_b128 v[180:183], v184 offset:2048
	ds_read_b128 v[184:187], v184 offset:3072
	s_add_u32 s26, s26, 0x80000
	s_addc_u32 s27, s27, 0
	s_mov_b32 m0, s37
	ds_read_b128 v[188:191], v155 offset:32768
	ds_read_b128 v[192:195], v155 offset:33792
	ds_read_b128 v[196:199], v155 offset:34816
	ds_read_b128 v[200:203], v155 offset:35840
	ds_read_b128 v[204:207], v155 offset:36864
	ds_read_b128 v[208:211], v155 offset:37888
	ds_read_b128 v[212:215], v155 offset:38912
	ds_read_b128 v[216:219], v155 offset:39936
	global_load_lds_dwordx4 v130, s[26:27]
	s_mov_b32 m0, s40
	s_nop 0
	global_load_lds_dwordx4 v134, s[26:27]
	s_waitcnt vmcnt(8) lgkmcnt(0)
	s_barrier
	v_mfma_f32_16x16x32_bf16 v[126:129], v[156:159], v[188:191], v[126:129]
	v_mfma_f32_16x16x32_bf16 v[122:125], v[164:167], v[188:191], v[122:125]
	v_mfma_f32_16x16x32_bf16 v[110:113], v[156:159], v[196:199], v[110:113]
	v_mfma_f32_16x16x32_bf16 v[106:109], v[164:167], v[196:199], v[106:109]
	v_mfma_f32_16x16x32_bf16 v[94:97], v[156:159], v[204:207], v[94:97]
	v_mfma_f32_16x16x32_bf16 v[90:93], v[164:167], v[204:207], v[90:93]
	v_mfma_f32_16x16x32_bf16 v[78:81], v[156:159], v[212:215], v[78:81]
	v_mfma_f32_16x16x32_bf16 v[74:77], v[164:167], v[212:215], v[74:77]
	v_mfma_f32_16x16x32_bf16 v[126:129], v[160:163], v[192:195], v[126:129]
	v_mfma_f32_16x16x32_bf16 v[122:125], v[168:171], v[192:195], v[122:125]
	v_mfma_f32_16x16x32_bf16 v[110:113], v[160:163], v[200:203], v[110:113]
	v_mfma_f32_16x16x32_bf16 v[106:109], v[168:171], v[200:203], v[106:109]
	v_mfma_f32_16x16x32_bf16 v[94:97], v[160:163], v[208:211], v[94:97]
	v_mfma_f32_16x16x32_bf16 v[90:93], v[168:171], v[208:211], v[90:93]
	v_mfma_f32_16x16x32_bf16 v[78:81], v[160:163], v[216:219], v[78:81]
	v_mfma_f32_16x16x32_bf16 v[74:77], v[168:171], v[216:219], v[74:77]
	v_mfma_f32_16x16x32_bf16 v[118:121], v[172:175], v[188:191], v[118:121]
	v_mfma_f32_16x16x32_bf16 v[114:117], v[180:183], v[188:191], v[114:117]
	v_mfma_f32_16x16x32_bf16 v[102:105], v[172:175], v[196:199], v[102:105]
	v_mfma_f32_16x16x32_bf16 v[98:101], v[180:183], v[196:199], v[98:101]
	v_mfma_f32_16x16x32_bf16 v[86:89], v[172:175], v[204:207], v[86:89]
	v_mfma_f32_16x16x32_bf16 v[82:85], v[180:183], v[204:207], v[82:85]
	v_mfma_f32_16x16x32_bf16 v[70:73], v[172:175], v[212:215], v[70:73]
	v_mfma_f32_16x16x32_bf16 v[66:69], v[180:183], v[212:215], v[66:69]
	v_mfma_f32_16x16x32_bf16 v[118:121], v[176:179], v[192:195], v[118:121]
	v_mfma_f32_16x16x32_bf16 v[114:117], v[184:187], v[192:195], v[114:117]
	v_mfma_f32_16x16x32_bf16 v[102:105], v[176:179], v[200:203], v[102:105]
	v_mfma_f32_16x16x32_bf16 v[98:101], v[184:187], v[200:203], v[98:101]
	v_mfma_f32_16x16x32_bf16 v[86:89], v[176:179], v[208:211], v[86:89]
	v_mfma_f32_16x16x32_bf16 v[82:85], v[184:187], v[208:211], v[82:85]
	v_mfma_f32_16x16x32_bf16 v[70:73], v[176:179], v[216:219], v[70:73]
	v_mfma_f32_16x16x32_bf16 v[66:69], v[184:187], v[216:219], v[66:69]
	s_barrier
	s_add_u32 s26, s24, 0x8000
	s_addc_u32 s27, s25, 0
	s_add_i32 s66, s60, s34
	s_mov_b32 m0, s66
	ds_read_b128 v[188:191], v155 offset:49152
	ds_read_b128 v[192:195], v155 offset:50176
	ds_read_b128 v[196:199], v155 offset:51200
	ds_read_b128 v[200:203], v155 offset:52224
	ds_read_b128 v[204:207], v155 offset:53248
	ds_read_b128 v[208:211], v155 offset:54272
	ds_read_b128 v[212:215], v155 offset:55296
	ds_read_b128 v[216:219], v155 offset:56320
	global_load_lds_dwordx4 v132, s[26:27]
	s_add_i32 m0, s66, 0x2000
	s_add_u32 s24, s24, 0xc000
	v_lshl_add_u64 v[220:221], s[26:27], 0, v[136:137]
	s_addc_u32 s25, s25, 0
	s_add_i32 s26, s61, s34
	global_load_lds_dwordx4 v[220:221], off
	s_mov_b32 m0, s26
	s_nop 0
	global_load_lds_dwordx4 v132, s[24:25]
	s_add_i32 m0, s26, 0x2000
	s_nop 0
	global_load_lds_dwordx4 v136, s[24:25]
	s_mov_b32 m0, s41
	s_nop 0
	global_load_lds_dwordx4 v130, s[22:23]
	s_mov_b32 m0, s42
	s_nop 0
	global_load_lds_dwordx4 v134, s[22:23]
	s_waitcnt vmcnt(8) lgkmcnt(0)
	s_barrier
	v_mfma_f32_16x16x32_bf16 v[62:65], v[156:159], v[188:191], v[62:65]
	v_mfma_f32_16x16x32_bf16 v[58:61], v[164:167], v[188:191], v[58:61]
	v_mfma_f32_16x16x32_bf16 v[46:49], v[156:159], v[196:199], v[46:49]
	v_mfma_f32_16x16x32_bf16 v[42:45], v[164:167], v[196:199], v[42:45]
	v_mfma_f32_16x16x32_bf16 v[30:33], v[156:159], v[204:207], v[30:33]
	v_mfma_f32_16x16x32_bf16 v[26:29], v[164:167], v[204:207], v[26:29]
	v_mfma_f32_16x16x32_bf16 v[14:17], v[156:159], v[212:215], v[14:17]
	v_mfma_f32_16x16x32_bf16 v[10:13], v[164:167], v[212:215], v[10:13]
	v_mfma_f32_16x16x32_bf16 v[62:65], v[160:163], v[192:195], v[62:65]
	v_mfma_f32_16x16x32_bf16 v[58:61], v[168:171], v[192:195], v[58:61]
	v_mfma_f32_16x16x32_bf16 v[46:49], v[160:163], v[200:203], v[46:49]
	v_mfma_f32_16x16x32_bf16 v[42:45], v[168:171], v[200:203], v[42:45]
	v_mfma_f32_16x16x32_bf16 v[30:33], v[160:163], v[208:211], v[30:33]
	v_mfma_f32_16x16x32_bf16 v[26:29], v[168:171], v[208:211], v[26:29]
	v_mfma_f32_16x16x32_bf16 v[14:17], v[160:163], v[216:219], v[14:17]
	v_mfma_f32_16x16x32_bf16 v[10:13], v[168:171], v[216:219], v[10:13]
	v_mfma_f32_16x16x32_bf16 v[54:57], v[172:175], v[188:191], v[54:57]
	v_mfma_f32_16x16x32_bf16 v[50:53], v[180:183], v[188:191], v[50:53]
	v_mfma_f32_16x16x32_bf16 v[38:41], v[172:175], v[196:199], v[38:41]
	v_mfma_f32_16x16x32_bf16 v[34:37], v[180:183], v[196:199], v[34:37]
	v_mfma_f32_16x16x32_bf16 v[22:25], v[172:175], v[204:207], v[22:25]
	v_mfma_f32_16x16x32_bf16 v[18:21], v[180:183], v[204:207], v[18:21]
	v_mfma_f32_16x16x32_bf16 v[6:9], v[172:175], v[212:215], v[6:9]
	v_mfma_f32_16x16x32_bf16 v[2:5], v[180:183], v[212:215], v[2:5]
	v_mfma_f32_16x16x32_bf16 v[54:57], v[176:179], v[192:195], v[54:57]
	v_mfma_f32_16x16x32_bf16 v[50:53], v[184:187], v[192:195], v[50:53]
	v_mfma_f32_16x16x32_bf16 v[38:41], v[176:179], v[200:203], v[38:41]
	v_mfma_f32_16x16x32_bf16 v[34:37], v[184:187], v[200:203], v[34:37]
	v_mfma_f32_16x16x32_bf16 v[22:25], v[176:179], v[208:211], v[22:25]
	v_mfma_f32_16x16x32_bf16 v[18:21], v[184:187], v[208:211], v[18:21]
	v_mfma_f32_16x16x32_bf16 v[6:9], v[176:179], v[216:219], v[6:9]
	v_mfma_f32_16x16x32_bf16 v[2:5], v[184:187], v[216:219], v[2:5]
	s_barrier
	s_add_u32 s51, s51, 0x10000
	s_addc_u32 s55, s55, 0
	s_add_u32 s20, s20, 0x100
	s_addc_u32 s21, s21, 0
	s_cmp_ge_u32 s65, s46
	s_cbranch_scc0 .LBB0_1038
	s_and_b64 vcc, exec, s[10:11]
	s_cbranch_vccz .LBB0_1041
	s_barrier

; template <class Epi, class Sched, bool ABLK = false, bool ALIGN_EPI = true, bool SP2 = true, bool BBLK = true>
; __device__ __forceinline__ void gemm_phase(LAS unsigned char* lds, const Gemm g, const Sched& S, const Epi& E) {
;     ...
;             const char* a1 = a_tile(uA, tbA + t + 1);
;             const char* a2 = last ? a_tile(nuA, ntbA) : a_tile(uA, tbA + t + 2); const char* b2 = last ? nB : cB + (size_t)(t + 2) * kstepB;
;             const char* a3 = last ? a_tile(nuA, ntbA + 1) : a_tile(uA, tbA + t + 3); const char* b3 = b2 + kstepB;
.Lksel_9:
	s_mov_b32 s23, s50
	s_mov_b32 s22, s49
	s_mov_b32 s25, s4
	s_mov_b32 s24, s5
	s_mov_b32 s27, s48
	s_mov_b32 s26, s17
	s_branch .Lksel_9_back

; #define PG8_STAGE(bufoff, gbase, voff) do { _Pragma("unroll") for (int _i = 0; _i < 2; ++_i) \
;         __builtin_amdgcn_global_load_lds((const unsigned*)((const char*)(gbase) + (voff)[_i]), (LAS unsigned*)(lds + (bufoff) + ldsw + _i * 8192), 16, 0, 0); } while (0)
; #define PG8_LDA(dst, b, h) do { _Pragma("unroll") for (int m = 0; m < 4; ++m) _Pragma("unroll") for (int k = 0; k < 2; ++k) dst[m][k] = *(const LAS bf16x8*)(lds + PG8_SA(b, h) + aoff + m * 2048 + k * 1024); } while (0)
; #define PG8_LDB(dst, b, h) do { _Pragma("unroll") for (int n = 0; n < 2; ++n) _Pragma("unroll") for (int k = 0; k < 2; ++k) dst[n][k] = *(const LAS bf16x8*)(lds + PG8_SB(b, h) + boff + n * 2048 + k * 1024); } while (0)
; #define PG8_WAIT_V(n) asm volatile("s_waitcnt vmcnt(" #n ")" ::: "memory")
; #define PG8_WAIT_L(n) asm volatile("s_waitcnt lgkmcnt(" #n ")" ::: "memory")
; template <class Epi, class Sched, bool ABLK = false, bool ALIGN_EPI = true, bool SP2 = true, bool BBLK = true>
; __device__ __forceinline__ void gemm_phase(LAS unsigned char* lds, const Gemm g, const Sched& S, const Epi& E) {
;     ...
;         const bool has_next = S.next(ui + 1, nxt);
;         const int nt = cur.nt;
;         const char* nuA = has_next ? a_unit(nxt) : uA; const int ntbA = has_next ? nxt.k0 / BK : tbA; const char* nB = has_next ? (const char*)g.Bt + (size_t)nxt.pn * tstepB + b_k0(nxt.k0) : cB;
;         for (int t = 0; t < nt; t += 2) {
;             const bool last = (t == nt - 2);
;             const char* a1 = a_tile(uA, tbA + t + 1);
;             const char* a2 = last ? a_tile(nuA, ntbA) : a_tile(uA, tbA + t + 2); const char* b2 = last ? nB : cB + (size_t)(t + 2) * kstepB;
;             const char* a3 = last ? a_tile(nuA, ntbA + 1) : a_tile(uA, tbA + t + 3); const char* b3 = b2 + kstepB;
;             if (last && has_next) S.a_ready(nxt);
;             if constexpr (SP2) {
;             PG8_LDB(B0, 0, 0); PG8_LDB(B1, 0, 1); PG8_SCHED; PG8_LDA(At, 0, 0); PG8_STAGE(PG8_SA(1, 1), a1 + hstepA, voffA);
;             PG8_WAIT_V(8); PG8_WAIT_L(0); PG8_BAR; PG8_MMA(0, 0, At, B0); PG8_MMA(0, 1, At, B1); PG8_BAR; PG8_SCHED;
;             PG8_LDA(At, 0, 1); PG8_STAGE(PG8_SB(0, 0), b2, voffB); PG8_STAGE(PG8_SB(0, 1), b2 + hstepB, voffB); PG8_STAGE(PG8_SA(0, 0), a2, voffA);
;             PG8_WAIT_V(8); PG8_WAIT_L(0); PG8_BAR; PG8_MMA(1, 0, At, B0); PG8_MMA(1, 1, At, B1); PG8_BAR; PG8_SCHED;
.LBB0_1163:
	s_ashr_i32 s11, s10, 31
	s_lshl_b64 s[4:5], s[10:11], 20
	s_add_u32 s16, s59, s4
	s_addc_u32 s17, s62, s5
	s_and_b64 s[4:5], s[18:19], exec
	s_cselect_b32 s4, s17, s27
	s_cselect_b32 s5, s16, s26
	s_ashr_i32 s15, s14, 31
	s_lshl_b64 s[20:21], s[14:15], 20
	s_add_u32 s20, s40, s20
	s_addc_u32 s21, s41, s21
	s_and_b64 s[30:31], s[18:19], exec
	s_cselect_b32 s11, s21, s29
	s_cselect_b32 s15, s20, s28
	s_add_u32 s23, s5, 0x80
	s_addc_u32 s57, s4, 0
	s_add_u32 s64, s28, 0x10000
	v_mov_b32_e32 v2, 0
	s_addc_u32 s65, s29, 0
	v_lshl_add_u64 v[164:165], s[26:27], 0, v[160:161]
	v_lshl_add_u64 v[166:167], s[26:27], 0, v[162:163]
	s_mov_b32 s66, -2
	s_mov_b64 s[28:29], 0
	ds_read_b128 v[172:175], v169
	ds_read_b128 v[176:179], v169 offset:1024
	ds_read_b128 v[180:183], v169 offset:2048
	ds_read_b128 v[184:187], v169 offset:3072
	ds_read_b128 v[188:191], v170
	ds_read_b128 v[192:195], v170 offset:1024
	ds_read_b128 v[196:199], v170 offset:2048
	ds_read_b128 v[200:203], v170 offset:3072
	s_add_u32 s30, s26, s28
	s_addc_u32 s31, s27, s29
	s_add_u32 s36, s30, 0x100
	s_addc_u32 s37, s31, 0
	s_add_u32 s30, s30, 0x180
	s_addc_u32 s31, s31, 0
	s_mov_b64 s[34:35], s[64:65]
	s_mov_b32 m0, s50
	v_lshl_add_u64 v[236:237], v[164:165], 0, s[28:29]
	ds_read_b128 v[204:207], v171
	ds_read_b128 v[208:211], v171 offset:1024
	ds_read_b128 v[212:215], v171 offset:2048
	ds_read_b128 v[216:219], v171 offset:3072
	ds_read_b128 v[220:223], v171 offset:4096
	ds_read_b128 v[224:227], v171 offset:5120
	ds_read_b128 v[228:231], v171 offset:6144
	ds_read_b128 v[232:235], v171 offset:7168
	global_load_lds_dwordx4 v[236:237], off
	v_lshl_add_u64 v[236:237], v[166:167], 0, s[28:29]
	s_mov_b32 m0, s51
	s_nop 0
	global_load_lds_dwordx4 v[236:237], off
	s_waitcnt vmcnt(8) lgkmcnt(0)
	s_barrier
	v_mfma_f32_16x16x32_bf16 v[126:129], v[172:175], v[204:207], 0
	v_mfma_f32_16x16x32_bf16 v[122:125], v[180:183], v[204:207], 0
	v_mfma_f32_16x16x32_bf16 v[110:113], v[172:175], v[212:215], 0
	v_mfma_f32_16x16x32_bf16 v[106:109], v[180:183], v[212:215], 0
	v_mfma_f32_16x16x32_bf16 v[94:97], v[172:175], v[220:223], 0
	v_mfma_f32_16x16x32_bf16 v[90:93], v[180:183], v[220:223], 0
	v_mfma_f32_16x16x32_bf16 v[78:81], v[172:175], v[228:231], 0
	v_mfma_f32_16x16x32_bf16 v[74:77], v[180:183], v[228:231], 0
	v_mfma_f32_16x16x32_bf16 v[126:129], v[176:179], v[208:211], v[126:129]
	v_mfma_f32_16x16x32_bf16 v[122:125], v[184:187], v[208:211], v[122:125]
	v_mfma_f32_16x16x32_bf16 v[110:113], v[176:179], v[216:219], v[110:113]
	v_mfma_f32_16x16x32_bf16 v[106:109], v[184:187], v[216:219], v[106:109]
	v_mfma_f32_16x16x32_bf16 v[94:97], v[176:179], v[224:227], v[94:97]
	v_mfma_f32_16x16x32_bf16 v[90:93], v[184:187], v[224:227], v[90:93]
	v_mfma_f32_16x16x32_bf16 v[78:81], v[176:179], v[232:235], v[78:81]
	v_mfma_f32_16x16x32_bf16 v[74:77], v[184:187], v[232:235], v[74:77]
	v_mfma_f32_16x16x32_bf16 v[118:121], v[188:191], v[204:207], 0
	v_mfma_f32_16x16x32_bf16 v[114:117], v[196:199], v[204:207], 0
	v_mfma_f32_16x16x32_bf16 v[102:105], v[188:191], v[212:215], 0
	v_mfma_f32_16x16x32_bf16 v[98:101], v[196:199], v[212:215], 0
	v_mfma_f32_16x16x32_bf16 v[86:89], v[188:191], v[220:223], 0
	v_mfma_f32_16x16x32_bf16 v[82:85], v[196:199], v[220:223], 0
	v_mfma_f32_16x16x32_bf16 v[70:73], v[188:191], v[228:231], 0
	v_mfma_f32_16x16x32_bf16 v[66:69], v[196:199], v[228:231], 0
	v_mfma_f32_16x16x32_bf16 v[118:121], v[192:195], v[208:211], v[118:121]
	v_mfma_f32_16x16x32_bf16 v[114:117], v[200:203], v[208:211], v[114:117]
	v_mfma_f32_16x16x32_bf16 v[102:105], v[192:195], v[216:219], v[102:105]
	v_mfma_f32_16x16x32_bf16 v[98:101], v[200:203], v[216:219], v[98:101]
	v_mfma_f32_16x16x32_bf16 v[86:89], v[192:195], v[224:227], v[86:89]
	v_mfma_f32_16x16x32_bf16 v[82:85], v[200:203], v[224:227], v[82:85]
	v_mfma_f32_16x16x32_bf16 v[70:73], v[192:195], v[232:235], v[70:73]
	v_mfma_f32_16x16x32_bf16 v[66:69], v[200:203], v[232:235], v[66:69]
	s_barrier
	s_mov_b32 m0, s55
	s_add_u32 s76, s34, 0x4000
	ds_read_b128 v[204:207], v171 offset:16384
	ds_read_b128 v[208:211], v171 offset:17408
	ds_read_b128 v[212:215], v171 offset:18432
	ds_read_b128 v[216:219], v171 offset:19456
	ds_read_b128 v[220:223], v171 offset:20480
	ds_read_b128 v[224:227], v171 offset:21504
	ds_read_b128 v[228:231], v171 offset:22528
	ds_read_b128 v[232:235], v171 offset:23552
	global_load_lds_dwordx4 v134, s[34:35]
	s_mov_b32 m0, s56
	s_addc_u32 s77, s35, 0
	s_add_i32 s67, s73, s42
	global_load_lds_dwordx4 v130, s[34:35]
	s_mov_b32 m0, s67
	s_nop 0
	global_load_lds_dwordx4 v134, s[76:77]
	s_add_i32 m0, s67, 0x2000
	s_nop 0
	global_load_lds_dwordx4 v130, s[76:77]
	s_mov_b32 m0, s25
	s_nop 0
	global_load_lds_dwordx4 v136, s[36:37]
	s_mov_b32 m0, s43
	s_nop 0
	global_load_lds_dwordx4 v132, s[36:37]
	s_waitcnt vmcnt(8) lgkmcnt(0)
	s_barrier
; #define PG8_STAGE(bufoff, gbase, voff) do { _Pragma("unroll") for (int _i = 0; _i < 2; ++_i) \
;         __builtin_amdgcn_global_load_lds((const unsigned*)((const char*)(gbase) + (voff)[_i]), (LAS unsigned*)(lds + (bufoff) + ldsw + _i * 8192), 16, 0, 0); } while (0)
; #define PG8_LDA(dst, b, h) do { _Pragma("unroll") for (int m = 0; m < 4; ++m) _Pragma("unroll") for (int k = 0; k < 2; ++k) dst[m][k] = *(const LAS bf16x8*)(lds + PG8_SA(b, h) + aoff + m * 2048 + k * 1024); } while (0)
; #define PG8_LDB(dst, b, h) do { _Pragma("unroll") for (int n = 0; n < 2; ++n) _Pragma("unroll") for (int k = 0; k < 2; ++k) dst[n][k] = *(const LAS bf16x8*)(lds + PG8_SB(b, h) + boff + n * 2048 + k * 1024); } while (0)
; #define PG8_MMA(ai, bj, At, Bt) do { __builtin_amdgcn_s_setprio(1); _Pragma("unroll") for (int m = 0; m < 4; ++m) _Pragma("unroll") for (int n = 0; n < 2; ++n) _Pragma("unroll") for (int k = 0; k < 2; ++k) \
;         acc[ai][bj][m][n] = __builtin_amdgcn_mfma_f32_16x16x32_bf16(Bt[n][k], At[m][k], acc[ai][bj][m][n], 0, 0, 0); __builtin_amdgcn_s_setprio(0); } while (0)
; #define PG8_WAIT_V(n) asm volatile("s_waitcnt vmcnt(" #n ")" ::: "memory")
; #define PG8_WAIT_L(n) asm volatile("s_waitcnt lgkmcnt(" #n ")" ::: "memory")
; #define PG8_BAR __builtin_amdgcn_s_barrier()
; #define PG8_SCHED __builtin_amdgcn_sched_barrier(0)
; template <class Epi, class Sched, bool ABLK = false, bool ALIGN_EPI = true, bool SP2 = true, bool BBLK = true>
; __device__ __forceinline__ void gemm_phase(LAS unsigned char* lds, const Gemm g, const Sched& S, const Epi& E) {
;     ...
;             PG8_WAIT_V(8); PG8_WAIT_L(0); PG8_BAR; PG8_MMA(1, 0, At, B0); PG8_MMA(1, 1, At, B1); PG8_BAR; PG8_SCHED;
;             PG8_LDB(B0, 1, 0); PG8_LDB(B1, 1, 1); PG8_SCHED; PG8_LDA(At, 1, 0); PG8_STAGE(PG8_SA(0, 1), a2 + hstepA, voffA);
;             PG8_WAIT_V(8); PG8_WAIT_L(0); PG8_BAR; PG8_MMA(0, 0, At, B0); PG8_MMA(0, 1, At, B1); PG8_BAR; PG8_SCHED;
;             PG8_LDA(At, 1, 1); PG8_STAGE(PG8_SB(1, 0), b3, voffB); PG8_STAGE(PG8_SB(1, 1), b3 + hstepB, voffB); PG8_STAGE(PG8_SA(1, 0), a3, voffA);
	v_mfma_f32_16x16x32_bf16 v[62:65], v[172:175], v[204:207], 0
	v_mfma_f32_16x16x32_bf16 v[58:61], v[180:183], v[204:207], 0
	v_mfma_f32_16x16x32_bf16 v[46:49], v[172:175], v[212:215], 0
	v_mfma_f32_16x16x32_bf16 v[42:45], v[180:183], v[212:215], 0
	v_mfma_f32_16x16x32_bf16 v[30:33], v[172:175], v[220:223], 0
	v_mfma_f32_16x16x32_bf16 v[26:29], v[180:183], v[220:223], 0
	v_mfma_f32_16x16x32_bf16 v[14:17], v[172:175], v[228:231], 0
	v_mfma_f32_16x16x32_bf16 v[10:13], v[180:183], v[228:231], 0
	v_mfma_f32_16x16x32_bf16 v[62:65], v[176:179], v[208:211], v[62:65]
	v_mfma_f32_16x16x32_bf16 v[58:61], v[184:187], v[208:211], v[58:61]
	v_mfma_f32_16x16x32_bf16 v[46:49], v[176:179], v[216:219], v[46:49]
	v_mfma_f32_16x16x32_bf16 v[42:45], v[184:187], v[216:219], v[42:45]
	v_mfma_f32_16x16x32_bf16 v[30:33], v[176:179], v[224:227], v[30:33]
	v_mfma_f32_16x16x32_bf16 v[26:29], v[184:187], v[224:227], v[26:29]
	v_mfma_f32_16x16x32_bf16 v[14:17], v[176:179], v[232:235], v[14:17]
	v_mfma_f32_16x16x32_bf16 v[10:13], v[184:187], v[232:235], v[10:13]
	v_mfma_f32_16x16x32_bf16 v[54:57], v[188:191], v[204:207], 0
	v_mfma_f32_16x16x32_bf16 v[50:53], v[196:199], v[204:207], 0
	v_mfma_f32_16x16x32_bf16 v[38:41], v[188:191], v[212:215], 0
	v_mfma_f32_16x16x32_bf16 v[34:37], v[196:199], v[212:215], 0
	v_mfma_f32_16x16x32_bf16 v[22:25], v[188:191], v[220:223], 0
	v_mfma_f32_16x16x32_bf16 v[18:21], v[196:199], v[220:223], 0
	v_mfma_f32_16x16x32_bf16 v[6:9], v[188:191], v[228:231], 0
	v_mfma_f32_16x16x32_bf16 v[2:5], v[196:199], v[228:231], 0
	v_mfma_f32_16x16x32_bf16 v[54:57], v[192:195], v[208:211], v[54:57]
	v_mfma_f32_16x16x32_bf16 v[50:53], v[200:203], v[208:211], v[50:53]
	v_mfma_f32_16x16x32_bf16 v[38:41], v[192:195], v[216:219], v[38:41]
	v_mfma_f32_16x16x32_bf16 v[34:37], v[200:203], v[216:219], v[34:37]
	v_mfma_f32_16x16x32_bf16 v[22:25], v[192:195], v[224:227], v[22:25]
	v_mfma_f32_16x16x32_bf16 v[18:21], v[200:203], v[224:227], v[18:21]
	v_mfma_f32_16x16x32_bf16 v[6:9], v[192:195], v[232:235], v[6:9]
	v_mfma_f32_16x16x32_bf16 v[2:5], v[200:203], v[232:235], v[2:5]
	s_barrier
	v_add_u32_e32 v184, s60, v168
	v_add_u32_e32 v200, s61, v168
	ds_read_b128 v[172:175], v184
	ds_read_b128 v[176:179], v184 offset:1024
	ds_read_b128 v[180:183], v184 offset:2048
	ds_read_b128 v[184:187], v184 offset:3072
	ds_read_b128 v[188:191], v200
	ds_read_b128 v[192:195], v200 offset:1024
	ds_read_b128 v[196:199], v200 offset:2048
	ds_read_b128 v[200:203], v200 offset:3072
	s_add_u32 s36, s36, 0x80000
	s_addc_u32 s37, s37, 0
	s_mov_b32 m0, s44
	ds_read_b128 v[204:207], v171 offset:32768
	ds_read_b128 v[208:211], v171 offset:33792
	ds_read_b128 v[212:215], v171 offset:34816
	ds_read_b128 v[216:219], v171 offset:35840
	ds_read_b128 v[220:223], v171 offset:36864
	ds_read_b128 v[224:227], v171 offset:37888
	ds_read_b128 v[228:231], v171 offset:38912
	ds_read_b128 v[232:235], v171 offset:39936
	global_load_lds_dwordx4 v136, s[36:37]
	s_mov_b32 m0, s45
	s_nop 0
	global_load_lds_dwordx4 v132, s[36:37]
	s_waitcnt vmcnt(8) lgkmcnt(0)
	s_barrier
	v_mfma_f32_16x16x32_bf16 v[126:129], v[172:175], v[204:207], v[126:129]
	v_mfma_f32_16x16x32_bf16 v[122:125], v[180:183], v[204:207], v[122:125]
	v_mfma_f32_16x16x32_bf16 v[110:113], v[172:175], v[212:215], v[110:113]
	v_mfma_f32_16x16x32_bf16 v[106:109], v[180:183], v[212:215], v[106:109]
	v_mfma_f32_16x16x32_bf16 v[94:97], v[172:175], v[220:223], v[94:97]
	v_mfma_f32_16x16x32_bf16 v[90:93], v[180:183], v[220:223], v[90:93]
	v_mfma_f32_16x16x32_bf16 v[78:81], v[172:175], v[228:231], v[78:81]
	v_mfma_f32_16x16x32_bf16 v[74:77], v[180:183], v[228:231], v[74:77]
	v_mfma_f32_16x16x32_bf16 v[126:129], v[176:179], v[208:211], v[126:129]
	v_mfma_f32_16x16x32_bf16 v[122:125], v[184:187], v[208:211], v[122:125]
	v_mfma_f32_16x16x32_bf16 v[110:113], v[176:179], v[216:219], v[110:113]
	v_mfma_f32_16x16x32_bf16 v[106:109], v[184:187], v[216:219], v[106:109]
	v_mfma_f32_16x16x32_bf16 v[94:97], v[176:179], v[224:227], v[94:97]
	v_mfma_f32_16x16x32_bf16 v[90:93], v[184:187], v[224:227], v[90:93]
	v_mfma_f32_16x16x32_bf16 v[78:81], v[176:179], v[232:235], v[78:81]
	v_mfma_f32_16x16x32_bf16 v[74:77], v[184:187], v[232:235], v[74:77]
	v_mfma_f32_16x16x32_bf16 v[118:121], v[188:191], v[204:207], v[118:121]
	v_mfma_f32_16x16x32_bf16 v[114:117], v[196:199], v[204:207], v[114:117]
	v_mfma_f32_16x16x32_bf16 v[102:105], v[188:191], v[212:215], v[102:105]
	v_mfma_f32_16x16x32_bf16 v[98:101], v[196:199], v[212:215], v[98:101]
	v_mfma_f32_16x16x32_bf16 v[86:89], v[188:191], v[220:223], v[86:89]
	v_mfma_f32_16x16x32_bf16 v[82:85], v[196:199], v[220:223], v[82:85]
	v_mfma_f32_16x16x32_bf16 v[70:73], v[188:191], v[228:231], v[70:73]
	v_mfma_f32_16x16x32_bf16 v[66:69], v[196:199], v[228:231], v[66:69]
	v_mfma_f32_16x16x32_bf16 v[118:121], v[192:195], v[208:211], v[118:121]
	v_mfma_f32_16x16x32_bf16 v[114:117], v[200:203], v[208:211], v[114:117]
	v_mfma_f32_16x16x32_bf16 v[102:105], v[192:195], v[216:219], v[102:105]
	v_mfma_f32_16x16x32_bf16 v[98:101], v[200:203], v[216:219], v[98:101]
	v_mfma_f32_16x16x32_bf16 v[86:89], v[192:195], v[224:227], v[86:89]
	v_mfma_f32_16x16x32_bf16 v[82:85], v[200:203], v[224:227], v[82:85]
	v_mfma_f32_16x16x32_bf16 v[70:73], v[192:195], v[232:235], v[70:73]
	v_mfma_f32_16x16x32_bf16 v[66:69], v[200:203], v[232:235], v[66:69]
	s_barrier
; #define PG8_STAGE(bufoff, gbase, voff) do { _Pragma("unroll") for (int _i = 0; _i < 2; ++_i) \
;         __builtin_amdgcn_global_load_lds((const unsigned*)((const char*)(gbase) + (voff)[_i]), (LAS unsigned*)(lds + (bufoff) + ldsw + _i * 8192), 16, 0, 0); } while (0)
; #define PG8_LDA(dst, b, h) do { _Pragma("unroll") for (int m = 0; m < 4; ++m) _Pragma("unroll") for (int k = 0; k < 2; ++k) dst[m][k] = *(const LAS bf16x8*)(lds + PG8_SA(b, h) + aoff + m * 2048 + k * 1024); } while (0)
; #define PG8_WAIT_V(n) asm volatile("s_waitcnt vmcnt(" #n ")" ::: "memory")
; #define PG8_WAIT_L(n) asm volatile("s_waitcnt lgkmcnt(" #n ")" ::: "memory")
; template <class Epi, class Sched, bool ABLK = false, bool ALIGN_EPI = true, bool SP2 = true, bool BBLK = true>
; __device__ __forceinline__ void gemm_phase(LAS unsigned char* lds, const Gemm g, const Sched& S, const Epi& E) {
;     ...
;         for (int t = 0; t < nt; t += 2) {
;             const bool last = (t == nt - 2);
;             const char* a1 = a_tile(uA, tbA + t + 1);
;             const char* a2 = last ? a_tile(nuA, ntbA) : a_tile(uA, tbA + t + 2); const char* b2 = last ? nB : cB + (size_t)(t + 2) * kstepB;
;             const char* a3 = last ? a_tile(nuA, ntbA + 1) : a_tile(uA, tbA + t + 3); const char* b3 = b2 + kstepB;
;             if (last && has_next) S.a_ready(nxt);
;             if constexpr (SP2) {
;             PG8_LDB(B0, 0, 0); PG8_LDB(B1, 0, 1); PG8_SCHED; PG8_LDA(At, 0, 0); PG8_STAGE(PG8_SA(1, 1), a1 + hstepA, voffA);
;             PG8_WAIT_V(8); PG8_WAIT_L(0); PG8_BAR; PG8_MMA(0, 0, At, B0); PG8_MMA(0, 1, At, B1); PG8_BAR; PG8_SCHED;
;             PG8_LDA(At, 0, 1); PG8_STAGE(PG8_SB(0, 0), b2, voffB); PG8_STAGE(PG8_SB(0, 1), b2 + hstepB, voffB); PG8_STAGE(PG8_SA(0, 0), a2, voffA);
;             PG8_WAIT_V(8); PG8_WAIT_L(0); PG8_BAR; PG8_MMA(1, 0, At, B0); PG8_MMA(1, 1, At, B1); PG8_BAR; PG8_SCHED;
;             PG8_LDB(B0, 1, 0); PG8_LDB(B1, 1, 1); PG8_SCHED; PG8_LDA(At, 1, 0); PG8_STAGE(PG8_SA(0, 1), a2 + hstepA, voffA);
;             PG8_WAIT_V(8); PG8_WAIT_L(0); PG8_BAR; PG8_MMA(0, 0, At, B0); PG8_MMA(0, 1, At, B1); PG8_BAR; PG8_SCHED;
;             PG8_LDA(At, 1, 1); PG8_STAGE(PG8_SB(1, 0), b3, voffB); PG8_STAGE(PG8_SB(1, 1), b3 + hstepB, voffB); PG8_STAGE(PG8_SA(1, 0), a3, voffA);
;             PG8_WAIT_V(8); PG8_WAIT_L(0); PG8_BAR; PG8_MMA(1, 0, At, B0); PG8_MMA(1, 1, At, B1); PG8_BAR; PG8_SCHED;
	s_add_u32 s36, s34, 0x8000
	s_addc_u32 s37, s35, 0
	s_add_i32 s67, s60, s42
	s_mov_b32 m0, s67
	ds_read_b128 v[204:207], v171 offset:49152
	ds_read_b128 v[208:211], v171 offset:50176
	ds_read_b128 v[212:215], v171 offset:51200
	ds_read_b128 v[216:219], v171 offset:52224
	ds_read_b128 v[220:223], v171 offset:53248
	ds_read_b128 v[224:227], v171 offset:54272
	ds_read_b128 v[228:231], v171 offset:55296
	ds_read_b128 v[232:235], v171 offset:56320
	global_load_lds_dwordx4 v134, s[36:37]
	s_add_i32 m0, s67, 0x2000
	s_add_u32 s34, s34, 0xc000
	v_lshl_add_u64 v[236:237], s[36:37], 0, v[130:131]
	s_addc_u32 s35, s35, 0
	s_add_i32 s36, s61, s42
	global_load_lds_dwordx4 v[236:237], off
	s_mov_b32 m0, s36
	s_nop 0
	global_load_lds_dwordx4 v134, s[34:35]
	s_add_i32 m0, s36, 0x2000
	s_nop 0
	global_load_lds_dwordx4 v130, s[34:35]
	s_mov_b32 m0, s48
	s_nop 0
	global_load_lds_dwordx4 v136, s[30:31]
	s_mov_b32 m0, s49
	s_nop 0
	global_load_lds_dwordx4 v132, s[30:31]
	s_waitcnt vmcnt(8) lgkmcnt(0)
	s_barrier
	v_mfma_f32_16x16x32_bf16 v[62:65], v[172:175], v[204:207], v[62:65]
	v_mfma_f32_16x16x32_bf16 v[58:61], v[180:183], v[204:207], v[58:61]
	v_mfma_f32_16x16x32_bf16 v[46:49], v[172:175], v[212:215], v[46:49]
	v_mfma_f32_16x16x32_bf16 v[42:45], v[180:183], v[212:215], v[42:45]
	v_mfma_f32_16x16x32_bf16 v[30:33], v[172:175], v[220:223], v[30:33]
	v_mfma_f32_16x16x32_bf16 v[26:29], v[180:183], v[220:223], v[26:29]
	v_mfma_f32_16x16x32_bf16 v[14:17], v[172:175], v[228:231], v[14:17]
	v_mfma_f32_16x16x32_bf16 v[10:13], v[180:183], v[228:231], v[10:13]
	v_mfma_f32_16x16x32_bf16 v[62:65], v[176:179], v[208:211], v[62:65]
	v_mfma_f32_16x16x32_bf16 v[58:61], v[184:187], v[208:211], v[58:61]
	v_mfma_f32_16x16x32_bf16 v[46:49], v[176:179], v[216:219], v[46:49]
	v_mfma_f32_16x16x32_bf16 v[42:45], v[184:187], v[216:219], v[42:45]
	v_mfma_f32_16x16x32_bf16 v[30:33], v[176:179], v[224:227], v[30:33]
	v_mfma_f32_16x16x32_bf16 v[26:29], v[184:187], v[224:227], v[26:29]
	v_mfma_f32_16x16x32_bf16 v[14:17], v[176:179], v[232:235], v[14:17]
	v_mfma_f32_16x16x32_bf16 v[10:13], v[184:187], v[232:235], v[10:13]
	v_mfma_f32_16x16x32_bf16 v[54:57], v[188:191], v[204:207], v[54:57]
	v_mfma_f32_16x16x32_bf16 v[50:53], v[196:199], v[204:207], v[50:53]
	v_mfma_f32_16x16x32_bf16 v[38:41], v[188:191], v[212:215], v[38:41]
	v_mfma_f32_16x16x32_bf16 v[34:37], v[196:199], v[212:215], v[34:37]
	v_mfma_f32_16x16x32_bf16 v[22:25], v[188:191], v[220:223], v[22:25]
	v_mfma_f32_16x16x32_bf16 v[18:21], v[196:199], v[220:223], v[18:21]
	v_mfma_f32_16x16x32_bf16 v[6:9], v[188:191], v[228:231], v[6:9]
	v_mfma_f32_16x16x32_bf16 v[2:5], v[196:199], v[228:231], v[2:5]
	v_mfma_f32_16x16x32_bf16 v[54:57], v[192:195], v[208:211], v[54:57]
	v_mfma_f32_16x16x32_bf16 v[50:53], v[200:203], v[208:211], v[50:53]
	v_mfma_f32_16x16x32_bf16 v[38:41], v[192:195], v[216:219], v[38:41]
	v_mfma_f32_16x16x32_bf16 v[34:37], v[200:203], v[216:219], v[34:37]
	v_mfma_f32_16x16x32_bf16 v[22:25], v[192:195], v[224:227], v[22:25]
	v_mfma_f32_16x16x32_bf16 v[18:21], v[200:203], v[224:227], v[18:21]
	v_mfma_f32_16x16x32_bf16 v[6:9], v[192:195], v[232:235], v[6:9]
	v_mfma_f32_16x16x32_bf16 v[2:5], v[200:203], v[232:235], v[2:5]
	s_barrier
	s_add_i32 s66, s66, 2
	s_add_u32 s28, s28, 0x100
	s_addc_u32 s29, s29, 0
	s_add_u32 s64, s64, 0x10000
	s_addc_u32 s65, s65, 0
	s_cmp_gt_u32 s66, 29
.LBB0_1164:
	ds_read_b128 v[172:175], v169
	ds_read_b128 v[176:179], v169 offset:1024
	ds_read_b128 v[180:183], v169 offset:2048
	ds_read_b128 v[184:187], v169 offset:3072
	ds_read_b128 v[188:191], v170
	ds_read_b128 v[192:195], v170 offset:1024
	ds_read_b128 v[196:199], v170 offset:2048
	ds_read_b128 v[200:203], v170 offset:3072
	s_add_u32 s30, s26, s28
	s_addc_u32 s31, s27, s29
	s_add_u32 s36, s30, 0x100
	s_addc_u32 s37, s31, 0
	s_add_u32 s30, s30, 0x180
	s_addc_u32 s31, s31, 0
	s_cmpk_eq_i32 s28, 0xf00
	s_cbranch_scc1 .Lksel_11
	s_mov_b64 s[34:35], s[64:65]
.Lksel_11_back:
	s_mov_b32 m0, s50
	v_lshl_add_u64 v[236:237], v[164:165], 0, s[28:29]
	ds_read_b128 v[204:207], v171
	ds_read_b128 v[208:211], v171 offset:1024
	ds_read_b128 v[212:215], v171 offset:2048
	ds_read_b128 v[216:219], v171 offset:3072
	ds_read_b128 v[220:223], v171 offset:4096
	ds_read_b128 v[224:227], v171 offset:5120
	ds_read_b128 v[228:231], v171 offset:6144
	ds_read_b128 v[232:235], v171 offset:7168
	global_load_lds_dwordx4 v[236:237], off
	v_lshl_add_u64 v[236:237], v[166:167], 0, s[28:29]
	s_mov_b32 m0, s51
	s_nop 0
	global_load_lds_dwordx4 v[236:237], off
	s_waitcnt vmcnt(8) lgkmcnt(0)
	s_barrier
; #define PG8_STAGE(bufoff, gbase, voff) do { _Pragma("unroll") for (int _i = 0; _i < 2; ++_i) \
;         __builtin_amdgcn_global_load_lds((const unsigned*)((const char*)(gbase) + (voff)[_i]), (LAS unsigned*)(lds + (bufoff) + ldsw + _i * 8192), 16, 0, 0); } while (0)
; #define PG8_LDA(dst, b, h) do { _Pragma("unroll") for (int m = 0; m < 4; ++m) _Pragma("unroll") for (int k = 0; k < 2; ++k) dst[m][k] = *(const LAS bf16x8*)(lds + PG8_SA(b, h) + aoff + m * 2048 + k * 1024); } while (0)
; #define PG8_LDB(dst, b, h) do { _Pragma("unroll") for (int n = 0; n < 2; ++n) _Pragma("unroll") for (int k = 0; k < 2; ++k) dst[n][k] = *(const LAS bf16x8*)(lds + PG8_SB(b, h) + boff + n * 2048 + k * 1024); } while (0)
; #define PG8_MMA(ai, bj, At, Bt) do { __builtin_amdgcn_s_setprio(1); _Pragma("unroll") for (int m = 0; m < 4; ++m) _Pragma("unroll") for (int n = 0; n < 2; ++n) _Pragma("unroll") for (int k = 0; k < 2; ++k) \
;         acc[ai][bj][m][n] = __builtin_amdgcn_mfma_f32_16x16x32_bf16(Bt[n][k], At[m][k], acc[ai][bj][m][n], 0, 0, 0); __builtin_amdgcn_s_setprio(0); } while (0)
; #define PG8_WAIT_V(n) asm volatile("s_waitcnt vmcnt(" #n ")" ::: "memory")
; #define PG8_WAIT_L(n) asm volatile("s_waitcnt lgkmcnt(" #n ")" ::: "memory")
; #define PG8_BAR __builtin_amdgcn_s_barrier()
; #define PG8_SCHED __builtin_amdgcn_sched_barrier(0)
; template <class Epi, class Sched, bool ABLK = false, bool ALIGN_EPI = true, bool SP2 = true, bool BBLK = true>
; __device__ __forceinline__ void gemm_phase(LAS unsigned char* lds, const Gemm g, const Sched& S, const Epi& E) {
;     ...
;             PG8_LDB(B0, 0, 0); PG8_LDB(B1, 0, 1); PG8_SCHED; PG8_LDA(At, 0, 0); PG8_STAGE(PG8_SA(1, 1), a1 + hstepA, voffA);
;             PG8_WAIT_V(8); PG8_WAIT_L(0); PG8_BAR; PG8_MMA(0, 0, At, B0); PG8_MMA(0, 1, At, B1); PG8_BAR; PG8_SCHED;
;             PG8_LDA(At, 0, 1); PG8_STAGE(PG8_SB(0, 0), b2, voffB); PG8_STAGE(PG8_SB(0, 1), b2 + hstepB, voffB); PG8_STAGE(PG8_SA(0, 0), a2, voffA);
;             PG8_WAIT_V(8); PG8_WAIT_L(0); PG8_BAR; PG8_MMA(1, 0, At, B0); PG8_MMA(1, 1, At, B1); PG8_BAR; PG8_SCHED;
;             PG8_LDB(B0, 1, 0); PG8_LDB(B1, 1, 1); PG8_SCHED; PG8_LDA(At, 1, 0); PG8_STAGE(PG8_SA(0, 1), a2 + hstepA, voffA);
;             PG8_WAIT_V(8); PG8_WAIT_L(0); PG8_BAR; PG8_MMA(0, 0, At, B0); PG8_MMA(0, 1, At, B1); PG8_BAR; PG8_SCHED;
	v_mfma_f32_16x16x32_bf16 v[126:129], v[172:175], v[204:207], v[126:129]
	v_mfma_f32_16x16x32_bf16 v[122:125], v[180:183], v[204:207], v[122:125]
	v_mfma_f32_16x16x32_bf16 v[110:113], v[172:175], v[212:215], v[110:113]
	v_mfma_f32_16x16x32_bf16 v[106:109], v[180:183], v[212:215], v[106:109]
	v_mfma_f32_16x16x32_bf16 v[94:97], v[172:175], v[220:223], v[94:97]
	v_mfma_f32_16x16x32_bf16 v[90:93], v[180:183], v[220:223], v[90:93]
	v_mfma_f32_16x16x32_bf16 v[78:81], v[172:175], v[228:231], v[78:81]
	v_mfma_f32_16x16x32_bf16 v[74:77], v[180:183], v[228:231], v[74:77]
	v_mfma_f32_16x16x32_bf16 v[126:129], v[176:179], v[208:211], v[126:129]
	v_mfma_f32_16x16x32_bf16 v[122:125], v[184:187], v[208:211], v[122:125]
	v_mfma_f32_16x16x32_bf16 v[110:113], v[176:179], v[216:219], v[110:113]
	v_mfma_f32_16x16x32_bf16 v[106:109], v[184:187], v[216:219], v[106:109]
	v_mfma_f32_16x16x32_bf16 v[94:97], v[176:179], v[224:227], v[94:97]
	v_mfma_f32_16x16x32_bf16 v[90:93], v[184:187], v[224:227], v[90:93]
	v_mfma_f32_16x16x32_bf16 v[78:81], v[176:179], v[232:235], v[78:81]
	v_mfma_f32_16x16x32_bf16 v[74:77], v[184:187], v[232:235], v[74:77]
	v_mfma_f32_16x16x32_bf16 v[118:121], v[188:191], v[204:207], v[118:121]
	v_mfma_f32_16x16x32_bf16 v[114:117], v[196:199], v[204:207], v[114:117]
	v_mfma_f32_16x16x32_bf16 v[102:105], v[188:191], v[212:215], v[102:105]
	v_mfma_f32_16x16x32_bf16 v[98:101], v[196:199], v[212:215], v[98:101]
	v_mfma_f32_16x16x32_bf16 v[86:89], v[188:191], v[220:223], v[86:89]
	v_mfma_f32_16x16x32_bf16 v[82:85], v[196:199], v[220:223], v[82:85]
	v_mfma_f32_16x16x32_bf16 v[70:73], v[188:191], v[228:231], v[70:73]
	v_mfma_f32_16x16x32_bf16 v[66:69], v[196:199], v[228:231], v[66:69]
	v_mfma_f32_16x16x32_bf16 v[118:121], v[192:195], v[208:211], v[118:121]
	v_mfma_f32_16x16x32_bf16 v[114:117], v[200:203], v[208:211], v[114:117]
	v_mfma_f32_16x16x32_bf16 v[102:105], v[192:195], v[216:219], v[102:105]
	v_mfma_f32_16x16x32_bf16 v[98:101], v[200:203], v[216:219], v[98:101]
	v_mfma_f32_16x16x32_bf16 v[86:89], v[192:195], v[224:227], v[86:89]
	v_mfma_f32_16x16x32_bf16 v[82:85], v[200:203], v[224:227], v[82:85]
	v_mfma_f32_16x16x32_bf16 v[70:73], v[192:195], v[232:235], v[70:73]
	v_mfma_f32_16x16x32_bf16 v[66:69], v[200:203], v[232:235], v[66:69]
	s_barrier
	s_mov_b32 m0, s55
	s_add_u32 s76, s34, 0x4000
	ds_read_b128 v[204:207], v171 offset:16384
	ds_read_b128 v[208:211], v171 offset:17408
	ds_read_b128 v[212:215], v171 offset:18432
	ds_read_b128 v[216:219], v171 offset:19456
	ds_read_b128 v[220:223], v171 offset:20480
	ds_read_b128 v[224:227], v171 offset:21504
	ds_read_b128 v[228:231], v171 offset:22528
	ds_read_b128 v[232:235], v171 offset:23552
	global_load_lds_dwordx4 v134, s[34:35]
	s_mov_b32 m0, s56
	s_addc_u32 s77, s35, 0
	s_add_i32 s67, s73, s42
	global_load_lds_dwordx4 v130, s[34:35]
	s_mov_b32 m0, s67
	s_nop 0
	global_load_lds_dwordx4 v134, s[76:77]
	s_add_i32 m0, s67, 0x2000
	s_nop 0
	global_load_lds_dwordx4 v130, s[76:77]
	s_mov_b32 m0, s25
	s_nop 0
	global_load_lds_dwordx4 v136, s[36:37]
	s_mov_b32 m0, s43
	s_nop 0
	global_load_lds_dwordx4 v132, s[36:37]
	s_waitcnt vmcnt(8) lgkmcnt(0)
	s_barrier
	v_mfma_f32_16x16x32_bf16 v[62:65], v[172:175], v[204:207], v[62:65]
	v_mfma_f32_16x16x32_bf16 v[58:61], v[180:183], v[204:207], v[58:61]
	v_mfma_f32_16x16x32_bf16 v[46:49], v[172:175], v[212:215], v[46:49]
	v_mfma_f32_16x16x32_bf16 v[42:45], v[180:183], v[212:215], v[42:45]
	v_mfma_f32_16x16x32_bf16 v[30:33], v[172:175], v[220:223], v[30:33]
	v_mfma_f32_16x16x32_bf16 v[26:29], v[180:183], v[220:223], v[26:29]
	v_mfma_f32_16x16x32_bf16 v[14:17], v[172:175], v[228:231], v[14:17]
	v_mfma_f32_16x16x32_bf16 v[10:13], v[180:183], v[228:231], v[10:13]
	v_mfma_f32_16x16x32_bf16 v[62:65], v[176:179], v[208:211], v[62:65]
	v_mfma_f32_16x16x32_bf16 v[58:61], v[184:187], v[208:211], v[58:61]
	v_mfma_f32_16x16x32_bf16 v[46:49], v[176:179], v[216:219], v[46:49]
	v_mfma_f32_16x16x32_bf16 v[42:45], v[184:187], v[216:219], v[42:45]
	v_mfma_f32_16x16x32_bf16 v[30:33], v[176:179], v[224:227], v[30:33]
	v_mfma_f32_16x16x32_bf16 v[26:29], v[184:187], v[224:227], v[26:29]
	v_mfma_f32_16x16x32_bf16 v[14:17], v[176:179], v[232:235], v[14:17]
	v_mfma_f32_16x16x32_bf16 v[10:13], v[184:187], v[232:235], v[10:13]
	v_mfma_f32_16x16x32_bf16 v[54:57], v[188:191], v[204:207], v[54:57]
	v_mfma_f32_16x16x32_bf16 v[50:53], v[196:199], v[204:207], v[50:53]
	v_mfma_f32_16x16x32_bf16 v[38:41], v[188:191], v[212:215], v[38:41]
	v_mfma_f32_16x16x32_bf16 v[34:37], v[196:199], v[212:215], v[34:37]
	v_mfma_f32_16x16x32_bf16 v[22:25], v[188:191], v[220:223], v[22:25]
	v_mfma_f32_16x16x32_bf16 v[18:21], v[196:199], v[220:223], v[18:21]
	v_mfma_f32_16x16x32_bf16 v[6:9], v[188:191], v[228:231], v[6:9]
	v_mfma_f32_16x16x32_bf16 v[2:5], v[196:199], v[228:231], v[2:5]
	v_mfma_f32_16x16x32_bf16 v[54:57], v[192:195], v[208:211], v[54:57]
	v_mfma_f32_16x16x32_bf16 v[50:53], v[200:203], v[208:211], v[50:53]
	v_mfma_f32_16x16x32_bf16 v[38:41], v[192:195], v[216:219], v[38:41]
	v_mfma_f32_16x16x32_bf16 v[34:37], v[200:203], v[216:219], v[34:37]
	v_mfma_f32_16x16x32_bf16 v[22:25], v[192:195], v[224:227], v[22:25]
	v_mfma_f32_16x16x32_bf16 v[18:21], v[200:203], v[224:227], v[18:21]
	v_mfma_f32_16x16x32_bf16 v[6:9], v[192:195], v[232:235], v[6:9]
	v_mfma_f32_16x16x32_bf16 v[2:5], v[200:203], v[232:235], v[2:5]
	s_barrier
; #define PG8_STAGE(bufoff, gbase, voff) do { _Pragma("unroll") for (int _i = 0; _i < 2; ++_i) \
;         __builtin_amdgcn_global_load_lds((const unsigned*)((const char*)(gbase) + (voff)[_i]), (LAS unsigned*)(lds + (bufoff) + ldsw + _i * 8192), 16, 0, 0); } while (0)
; #define PG8_LDA(dst, b, h) do { _Pragma("unroll") for (int m = 0; m < 4; ++m) _Pragma("unroll") for (int k = 0; k < 2; ++k) dst[m][k] = *(const LAS bf16x8*)(lds + PG8_SA(b, h) + aoff + m * 2048 + k * 1024); } while (0)
; #define PG8_LDB(dst, b, h) do { _Pragma("unroll") for (int n = 0; n < 2; ++n) _Pragma("unroll") for (int k = 0; k < 2; ++k) dst[n][k] = *(const LAS bf16x8*)(lds + PG8_SB(b, h) + boff + n * 2048 + k * 1024); } while (0)
; #define PG8_WAIT_V(n) asm volatile("s_waitcnt vmcnt(" #n ")" ::: "memory")
; #define PG8_WAIT_L(n) asm volatile("s_waitcnt lgkmcnt(" #n ")" ::: "memory")
; #define PG8_BAR __builtin_amdgcn_s_barrier()
; #define PG8_SCHED __builtin_amdgcn_sched_barrier(0)
; template <class Epi, class Sched, bool ABLK = false, bool ALIGN_EPI = true, bool SP2 = true, bool BBLK = true>
; __device__ __forceinline__ void gemm_phase(LAS unsigned char* lds, const Gemm g, const Sched& S, const Epi& E) {
;     ...
;             PG8_LDB(B0, 0, 0); PG8_LDB(B1, 0, 1); PG8_SCHED; PG8_LDA(At, 0, 0); PG8_STAGE(PG8_SA(1, 1), a1 + hstepA, voffA);
;             PG8_WAIT_V(8); PG8_WAIT_L(0); PG8_BAR; PG8_MMA(0, 0, At, B0); PG8_MMA(0, 1, At, B1); PG8_BAR; PG8_SCHED;
;             PG8_LDA(At, 0, 1); PG8_STAGE(PG8_SB(0, 0), b2, voffB); PG8_STAGE(PG8_SB(0, 1), b2 + hstepB, voffB); PG8_STAGE(PG8_SA(0, 0), a2, voffA);
;             PG8_WAIT_V(8); PG8_WAIT_L(0); PG8_BAR; PG8_MMA(1, 0, At, B0); PG8_MMA(1, 1, At, B1); PG8_BAR; PG8_SCHED;
;             PG8_LDB(B0, 1, 0); PG8_LDB(B1, 1, 1); PG8_SCHED; PG8_LDA(At, 1, 0); PG8_STAGE(PG8_SA(0, 1), a2 + hstepA, voffA);
;             PG8_WAIT_V(8); PG8_WAIT_L(0); PG8_BAR; PG8_MMA(0, 0, At, B0); PG8_MMA(0, 1, At, B1); PG8_BAR; PG8_SCHED;
;             PG8_LDA(At, 1, 1); PG8_STAGE(PG8_SB(1, 0), b3, voffB); PG8_STAGE(PG8_SB(1, 1), b3 + hstepB, voffB); PG8_STAGE(PG8_SA(1, 0), a3, voffA);
;             PG8_WAIT_V(8); PG8_WAIT_L(0); PG8_BAR; PG8_MMA(1, 0, At, B0); PG8_MMA(1, 1, At, B1); PG8_BAR; PG8_SCHED;
;     ...
;         if constexpr (ALIGN_EPI) { if (wr == 0) PG8_BAR; }
	v_add_u32_e32 v184, s60, v168
	v_add_u32_e32 v200, s61, v168
	ds_read_b128 v[172:175], v184
	ds_read_b128 v[176:179], v184 offset:1024
	ds_read_b128 v[180:183], v184 offset:2048
	ds_read_b128 v[184:187], v184 offset:3072
	ds_read_b128 v[188:191], v200
	ds_read_b128 v[192:195], v200 offset:1024
	ds_read_b128 v[196:199], v200 offset:2048
	ds_read_b128 v[200:203], v200 offset:3072
	s_add_u32 s36, s36, 0x80000
	s_addc_u32 s37, s37, 0
	s_mov_b32 m0, s44
	ds_read_b128 v[204:207], v171 offset:32768
	ds_read_b128 v[208:211], v171 offset:33792
	ds_read_b128 v[212:215], v171 offset:34816
	ds_read_b128 v[216:219], v171 offset:35840
	ds_read_b128 v[220:223], v171 offset:36864
	ds_read_b128 v[224:227], v171 offset:37888
	ds_read_b128 v[228:231], v171 offset:38912
	ds_read_b128 v[232:235], v171 offset:39936
	global_load_lds_dwordx4 v136, s[36:37]
	s_mov_b32 m0, s45
	s_nop 0
	global_load_lds_dwordx4 v132, s[36:37]
	s_waitcnt vmcnt(8) lgkmcnt(0)
	s_barrier
	v_mfma_f32_16x16x32_bf16 v[126:129], v[172:175], v[204:207], v[126:129]
	v_mfma_f32_16x16x32_bf16 v[122:125], v[180:183], v[204:207], v[122:125]
	v_mfma_f32_16x16x32_bf16 v[110:113], v[172:175], v[212:215], v[110:113]
	v_mfma_f32_16x16x32_bf16 v[106:109], v[180:183], v[212:215], v[106:109]
	v_mfma_f32_16x16x32_bf16 v[94:97], v[172:175], v[220:223], v[94:97]
	v_mfma_f32_16x16x32_bf16 v[90:93], v[180:183], v[220:223], v[90:93]
	v_mfma_f32_16x16x32_bf16 v[78:81], v[172:175], v[228:231], v[78:81]
	v_mfma_f32_16x16x32_bf16 v[74:77], v[180:183], v[228:231], v[74:77]
	v_mfma_f32_16x16x32_bf16 v[126:129], v[176:179], v[208:211], v[126:129]
	v_mfma_f32_16x16x32_bf16 v[122:125], v[184:187], v[208:211], v[122:125]
	v_mfma_f32_16x16x32_bf16 v[110:113], v[176:179], v[216:219], v[110:113]
	v_mfma_f32_16x16x32_bf16 v[106:109], v[184:187], v[216:219], v[106:109]
	v_mfma_f32_16x16x32_bf16 v[94:97], v[176:179], v[224:227], v[94:97]
	v_mfma_f32_16x16x32_bf16 v[90:93], v[184:187], v[224:227], v[90:93]
	v_mfma_f32_16x16x32_bf16 v[78:81], v[176:179], v[232:235], v[78:81]
	v_mfma_f32_16x16x32_bf16 v[74:77], v[184:187], v[232:235], v[74:77]
	v_mfma_f32_16x16x32_bf16 v[118:121], v[188:191], v[204:207], v[118:121]
	v_mfma_f32_16x16x32_bf16 v[114:117], v[196:199], v[204:207], v[114:117]
	v_mfma_f32_16x16x32_bf16 v[102:105], v[188:191], v[212:215], v[102:105]
	v_mfma_f32_16x16x32_bf16 v[98:101], v[196:199], v[212:215], v[98:101]
	v_mfma_f32_16x16x32_bf16 v[86:89], v[188:191], v[220:223], v[86:89]
	v_mfma_f32_16x16x32_bf16 v[82:85], v[196:199], v[220:223], v[82:85]
	v_mfma_f32_16x16x32_bf16 v[70:73], v[188:191], v[228:231], v[70:73]
	v_mfma_f32_16x16x32_bf16 v[66:69], v[196:199], v[228:231], v[66:69]
	v_mfma_f32_16x16x32_bf16 v[118:121], v[192:195], v[208:211], v[118:121]
	v_mfma_f32_16x16x32_bf16 v[114:117], v[200:203], v[208:211], v[114:117]
	v_mfma_f32_16x16x32_bf16 v[102:105], v[192:195], v[216:219], v[102:105]
	v_mfma_f32_16x16x32_bf16 v[98:101], v[200:203], v[216:219], v[98:101]
	v_mfma_f32_16x16x32_bf16 v[86:89], v[192:195], v[224:227], v[86:89]
	v_mfma_f32_16x16x32_bf16 v[82:85], v[200:203], v[224:227], v[82:85]
	v_mfma_f32_16x16x32_bf16 v[70:73], v[192:195], v[232:235], v[70:73]
	v_mfma_f32_16x16x32_bf16 v[66:69], v[200:203], v[232:235], v[66:69]
	s_barrier
	s_add_u32 s36, s34, 0x8000
	s_addc_u32 s37, s35, 0
	s_add_i32 s67, s60, s42
	s_mov_b32 m0, s67
	ds_read_b128 v[204:207], v171 offset:49152
	ds_read_b128 v[208:211], v171 offset:50176
	ds_read_b128 v[212:215], v171 offset:51200
	ds_read_b128 v[216:219], v171 offset:52224
	ds_read_b128 v[220:223], v171 offset:53248
	ds_read_b128 v[224:227], v171 offset:54272
	ds_read_b128 v[228:231], v171 offset:55296
	ds_read_b128 v[232:235], v171 offset:56320
	global_load_lds_dwordx4 v134, s[36:37]
	s_add_i32 m0, s67, 0x2000
	s_add_u32 s34, s34, 0xc000
	v_lshl_add_u64 v[236:237], s[36:37], 0, v[130:131]
	s_addc_u32 s35, s35, 0
	s_add_i32 s36, s61, s42
	global_load_lds_dwordx4 v[236:237], off
	s_mov_b32 m0, s36
	s_nop 0
	global_load_lds_dwordx4 v134, s[34:35]
	s_add_i32 m0, s36, 0x2000
	s_nop 0
	global_load_lds_dwordx4 v130, s[34:35]
	s_mov_b32 m0, s48
	s_nop 0
	global_load_lds_dwordx4 v136, s[30:31]
	s_mov_b32 m0, s49
	s_nop 0
	global_load_lds_dwordx4 v132, s[30:31]
	s_waitcnt vmcnt(8) lgkmcnt(0)
	s_barrier
	v_mfma_f32_16x16x32_bf16 v[62:65], v[172:175], v[204:207], v[62:65]
	v_mfma_f32_16x16x32_bf16 v[58:61], v[180:183], v[204:207], v[58:61]
	v_mfma_f32_16x16x32_bf16 v[46:49], v[172:175], v[212:215], v[46:49]
	v_mfma_f32_16x16x32_bf16 v[42:45], v[180:183], v[212:215], v[42:45]
	v_mfma_f32_16x16x32_bf16 v[30:33], v[172:175], v[220:223], v[30:33]
	v_mfma_f32_16x16x32_bf16 v[26:29], v[180:183], v[220:223], v[26:29]
	v_mfma_f32_16x16x32_bf16 v[14:17], v[172:175], v[228:231], v[14:17]
	v_mfma_f32_16x16x32_bf16 v[10:13], v[180:183], v[228:231], v[10:13]
	v_mfma_f32_16x16x32_bf16 v[62:65], v[176:179], v[208:211], v[62:65]
	v_mfma_f32_16x16x32_bf16 v[58:61], v[184:187], v[208:211], v[58:61]
	v_mfma_f32_16x16x32_bf16 v[46:49], v[176:179], v[216:219], v[46:49]
	v_mfma_f32_16x16x32_bf16 v[42:45], v[184:187], v[216:219], v[42:45]
	v_mfma_f32_16x16x32_bf16 v[30:33], v[176:179], v[224:227], v[30:33]
	v_mfma_f32_16x16x32_bf16 v[26:29], v[184:187], v[224:227], v[26:29]
	v_mfma_f32_16x16x32_bf16 v[14:17], v[176:179], v[232:235], v[14:17]
	v_mfma_f32_16x16x32_bf16 v[10:13], v[184:187], v[232:235], v[10:13]
	v_mfma_f32_16x16x32_bf16 v[54:57], v[188:191], v[204:207], v[54:57]
	v_mfma_f32_16x16x32_bf16 v[50:53], v[196:199], v[204:207], v[50:53]
	v_mfma_f32_16x16x32_bf16 v[38:41], v[188:191], v[212:215], v[38:41]
	v_mfma_f32_16x16x32_bf16 v[34:37], v[196:199], v[212:215], v[34:37]
	v_mfma_f32_16x16x32_bf16 v[22:25], v[188:191], v[220:223], v[22:25]
	v_mfma_f32_16x16x32_bf16 v[18:21], v[196:199], v[220:223], v[18:21]
	v_mfma_f32_16x16x32_bf16 v[6:9], v[188:191], v[228:231], v[6:9]
	v_mfma_f32_16x16x32_bf16 v[2:5], v[196:199], v[228:231], v[2:5]
	v_mfma_f32_16x16x32_bf16 v[54:57], v[192:195], v[208:211], v[54:57]
	v_mfma_f32_16x16x32_bf16 v[50:53], v[200:203], v[208:211], v[50:53]
	v_mfma_f32_16x16x32_bf16 v[38:41], v[192:195], v[216:219], v[38:41]
	v_mfma_f32_16x16x32_bf16 v[34:37], v[200:203], v[216:219], v[34:37]
	v_mfma_f32_16x16x32_bf16 v[22:25], v[192:195], v[224:227], v[22:25]
	v_mfma_f32_16x16x32_bf16 v[18:21], v[200:203], v[224:227], v[18:21]
	v_mfma_f32_16x16x32_bf16 v[6:9], v[192:195], v[232:235], v[6:9]
	v_mfma_f32_16x16x32_bf16 v[2:5], v[200:203], v[232:235], v[2:5]
	s_barrier
	s_add_i32 s66, s66, 2
	s_add_u32 s28, s28, 0x100
	s_addc_u32 s29, s29, 0
	s_add_u32 s64, s64, 0x10000
	s_addc_u32 s65, s65, 0
	s_cmp_gt_u32 s66, 29
	s_cbranch_scc0 .LBB0_1164
	s_and_b64 vcc, exec, s[6:7]
	s_cbranch_vccz .LBB0_1167
	s_barrier

; template <class Epi, class Sched, bool ABLK = false, bool ALIGN_EPI = true, bool SP2 = true, bool BBLK = true>
; __device__ __forceinline__ void gemm_phase(LAS unsigned char* lds, const Gemm g, const Sched& S, const Epi& E) {
;     ...
;             const char* a2 = last ? a_tile(nuA, ntbA) : a_tile(uA, tbA + t + 2); const char* b2 = last ? nB : cB + (size_t)(t + 2) * kstepB;
;             const char* a3 = last ? a_tile(nuA, ntbA + 1) : a_tile(uA, tbA + t + 3); const char* b3 = b2 + kstepB;
.Lksel_11:
	s_mov_b32 s31, s57
	s_mov_b32 s30, s23
	s_mov_b32 s35, s11
	s_mov_b32 s34, s15
	s_mov_b32 s37, s4
	s_mov_b32 s36, s5
	s_branch .Lksel_11_back

; template <class Epi, class Sched, bool ABLK = false, bool ALIGN_EPI = true, bool SP2 = true, bool BBLK = true>
; __device__ __forceinline__ void gemm_phase(LAS unsigned char* lds, const Gemm g, const Sched& S, const Epi& E) {
;     ...
;     auto a_unit = [&](const Unit& u) -> const char* { return ABLK ? (const char*)g.A + (size_t)u.pm * ((size_t)g.lda / 64) * 32768 : (const char*)g.A + (size_t)u.pm * 2 * hstepA; };
;     auto a_tile = [&](const char* ub, int tau) -> const char* { return ub + (size_t)tau * (ABLK ? (size_t)32768 : kstep); };
;     const char* uA = a_unit(cur); int tbA = cur.k0 / BK;
;     const char* cA = a_tile(uA, tbA); const char* cB = (const char*)g.Bt + (size_t)cur.pn * tstepB + b_k0(cur.k0);
;     S.a_ready(cur);
;     if constexpr (SP2) {
;         PG8_STAGE(PG8_SB(0, 0), cB, voffB); PG8_STAGE(PG8_SB(0, 1), cB + hstepB, voffB); PG8_STAGE(PG8_SA(0, 0), cA, voffA); PG8_STAGE(PG8_SA(0, 1), cA + hstepA, voffA);
;         if (wr == 1) PG8_BAR;
;         PG8_WAIT_V(2); PG8_BAR;
;         PG8_STAGE(PG8_SB(1, 0), cB + kstepB, voffB); PG8_STAGE(PG8_SA(1, 0), a_tile(uA, tbA + 1), voffA); PG8_STAGE(PG8_SB(1, 1), cB + hstepB + kstepB, voffB);
;         PG8_WAIT_V(6); PG8_BAR;
;     } else {
;         PG8_STAGE(PG8_SB(0, 0), cB, voffB); PG8_STAGE(PG8_SA(0, 0), cA, voffA); PG8_STAGE(PG8_SB(0, 1), cB + hstepB, voffB); PG8_STAGE(PG8_SA(0, 1), cA + hstepA, voffA);
;         if (wr == 1) PG8_BAR;
;         PG8_WAIT_V(4); PG8_BAR;
;         PG8_STAGE(PG8_SB(1, 0), cB + kstepB, voffB); PG8_STAGE(PG8_SA(1, 0), a_tile(uA, tbA + 1), voffA); PG8_STAGE(PG8_SB(1, 1), cB + hstepB + kstepB, voffB);
;         PG8_WAIT_V(6); PG8_BAR;
;     }
;     for (;;) {
;         const bool has_next = S.next(ui + 1, nxt);
;         const int nt = cur.nt;
;         const char* nuA = has_next ? a_unit(nxt) : uA; const int ntbA = has_next ? nxt.k0 / BK : tbA; const char* nB = has_next ? (const char*)g.Bt + (size_t)nxt.pn * tstepB + b_k0(nxt.k0) : cB;
;         for (int t = 0; t < nt; t += 2) {
;             const bool last = (t == nt - 2);
;             const char* a1 = a_tile(uA, tbA + t + 1);
;             const char* a2 = last ? a_tile(nuA, ntbA) : a_tile(uA, tbA + t + 2); const char* b2 = last ? nB : cB + (size_t)(t + 2) * kstepB;
;             const char* a3 = last ? a_tile(nuA, ntbA + 1) : a_tile(uA, tbA + t + 3); const char* b3 = b2 + kstepB;
.LBB0_1228:
	s_ashr_i32 s81, s80, 31
	s_andn2_b64 vcc, exec, s[4:5]
	s_lshl_b64 s[16:17], s[80:81], 22
	s_add_u32 s16, s1, s16
	s_addc_u32 s17, s33, s17
	s_and_b64 s[18:19], s[4:5], exec
	s_cselect_b32 s27, s17, s25
	s_cselect_b32 s46, s16, s24
	s_ashr_i32 s18, s0, 31
	s_lshr_b32 s18, s18, 26
	s_add_i32 s18, s0, s18
	s_ashr_i32 s18, s18, 6
	s_and_b64 s[20:21], s[4:5], exec
	s_cselect_b32 s28, s18, s26
	s_ashr_i32 s79, s78, 31
	s_lshl_b64 s[20:21], s[78:79], 22
	s_add_u32 s29, s30, s20
	s_addc_u32 s47, s31, s21
	s_ashr_i32 s19, s18, 31
	s_lshl_b64 s[20:21], s[18:19], 15
	s_add_u32 s20, s29, s20
	s_addc_u32 s21, s47, s21
	v_cndmask_b32_e64 v2, 0, 1, s[4:5]
	s_and_b64 s[4:5], s[4:5], exec
	s_cselect_b32 s4, s21, s23
	s_cselect_b32 s5, s20, s22
	s_ashr_i32 s29, s28, 31
	s_lshl_b64 s[28:29], s[28:29], 15
	s_add_u32 s19, s46, s28
	s_addc_u32 s46, s27, s29
	s_add_u32 s47, s19, 0x8000
	s_addc_u32 s48, s46, 0
	s_add_u32 s49, s22, 0x10000
	s_addc_u32 s50, s23, 0
	s_ashr_i32 s27, s26, 31
	v_cmp_ne_u32_e64 s[10:11], 1, v2
	s_lshl_b64 s[22:23], s[26:27], 15
	v_lshl_add_u64 v[2:3], s[24:25], 0, v[138:139]
	s_add_u32 s51, s24, s22
	v_lshl_add_u64 v[142:143], v[2:3], 0, s[22:23]
	v_lshl_add_u64 v[2:3], s[24:25], 0, v[140:141]
	s_addc_u32 s55, s25, s23
	v_lshl_add_u64 v[144:145], v[2:3], 0, s[22:23]
	s_lshl_b32 s22, s44, 15
	s_add_i32 s22, s22, 0xfff00000
	v_mov_b32_e32 v2, 0
	s_add_u32 s56, s22, 0xf0000
	s_mov_b32 s57, 0
	s_mov_b64 s[22:23], 0
	ds_read_b128 v[152:155], v149
	ds_read_b128 v[156:159], v149 offset:1024
	ds_read_b128 v[160:163], v149 offset:2048
	ds_read_b128 v[164:167], v149 offset:3072
	ds_read_b128 v[168:171], v150
	ds_read_b128 v[172:175], v150 offset:1024
	ds_read_b128 v[176:179], v150 offset:2048
	ds_read_b128 v[180:183], v150 offset:3072
	s_add_u32 s24, s51, s22
	s_addc_u32 s25, s55, s23
	s_add_u32 s28, s24, 0x10000
	s_addc_u32 s29, s25, 0
	s_add_i32 s57, s57, 2
	s_add_u32 s26, s49, s22
	s_addc_u32 s27, s50, s23
	s_add_u32 s24, s24, 0x18000
	s_addc_u32 s25, s25, 0
	v_lshl_add_u64 v[216:217], v[142:143], 0, s[22:23]
	s_add_i32 m0, s35, 0xc000
	ds_read_b128 v[184:187], v151
	ds_read_b128 v[188:191], v151 offset:1024
	ds_read_b128 v[192:195], v151 offset:2048
	ds_read_b128 v[196:199], v151 offset:3072
	ds_read_b128 v[200:203], v151 offset:4096
	ds_read_b128 v[204:207], v151 offset:5120
	ds_read_b128 v[208:211], v151 offset:6144
	ds_read_b128 v[212:215], v151 offset:7168
	global_load_lds_dwordx4 v[216:217], off
	v_lshl_add_u64 v[216:217], v[144:145], 0, s[22:23]
	s_add_i32 m0, s35, 0xe000
	s_nop 0
	global_load_lds_dwordx4 v[216:217], off
	s_waitcnt vmcnt(8) lgkmcnt(0)
	s_barrier
	v_mfma_f32_16x16x32_bf16 v[126:129], v[152:155], v[184:187], 0
	v_mfma_f32_16x16x32_bf16 v[122:125], v[160:163], v[184:187], 0
	v_mfma_f32_16x16x32_bf16 v[110:113], v[152:155], v[192:195], 0
	v_mfma_f32_16x16x32_bf16 v[106:109], v[160:163], v[192:195], 0
	v_mfma_f32_16x16x32_bf16 v[94:97], v[152:155], v[200:203], 0
	v_mfma_f32_16x16x32_bf16 v[90:93], v[160:163], v[200:203], 0
	v_mfma_f32_16x16x32_bf16 v[78:81], v[152:155], v[208:211], 0
	v_mfma_f32_16x16x32_bf16 v[74:77], v[160:163], v[208:211], 0
	v_mfma_f32_16x16x32_bf16 v[126:129], v[156:159], v[188:191], v[126:129]
	v_mfma_f32_16x16x32_bf16 v[122:125], v[164:167], v[188:191], v[122:125]
	v_mfma_f32_16x16x32_bf16 v[110:113], v[156:159], v[196:199], v[110:113]
	v_mfma_f32_16x16x32_bf16 v[106:109], v[164:167], v[196:199], v[106:109]
	v_mfma_f32_16x16x32_bf16 v[94:97], v[156:159], v[204:207], v[94:97]
	v_mfma_f32_16x16x32_bf16 v[90:93], v[164:167], v[204:207], v[90:93]
	v_mfma_f32_16x16x32_bf16 v[78:81], v[156:159], v[212:215], v[78:81]
	v_mfma_f32_16x16x32_bf16 v[74:77], v[164:167], v[212:215], v[74:77]
	v_mfma_f32_16x16x32_bf16 v[118:121], v[168:171], v[184:187], 0
	v_mfma_f32_16x16x32_bf16 v[114:117], v[176:179], v[184:187], 0
	v_mfma_f32_16x16x32_bf16 v[102:105], v[168:171], v[192:195], 0
	v_mfma_f32_16x16x32_bf16 v[98:101], v[176:179], v[192:195], 0
	v_mfma_f32_16x16x32_bf16 v[86:89], v[168:171], v[200:203], 0
	v_mfma_f32_16x16x32_bf16 v[82:85], v[176:179], v[200:203], 0
	v_mfma_f32_16x16x32_bf16 v[70:73], v[168:171], v[208:211], 0
	v_mfma_f32_16x16x32_bf16 v[66:69], v[176:179], v[208:211], 0
	v_mfma_f32_16x16x32_bf16 v[118:121], v[172:175], v[188:191], v[118:121]
	v_mfma_f32_16x16x32_bf16 v[114:117], v[180:183], v[188:191], v[114:117]
	v_mfma_f32_16x16x32_bf16 v[102:105], v[172:175], v[196:199], v[102:105]
	v_mfma_f32_16x16x32_bf16 v[98:101], v[180:183], v[196:199], v[98:101]
	v_mfma_f32_16x16x32_bf16 v[86:89], v[172:175], v[204:207], v[86:89]
	v_mfma_f32_16x16x32_bf16 v[82:85], v[180:183], v[204:207], v[82:85]
	v_mfma_f32_16x16x32_bf16 v[70:73], v[172:175], v[212:215], v[70:73]
	v_mfma_f32_16x16x32_bf16 v[66:69], v[180:183], v[212:215], v[66:69]
	s_barrier
	s_add_i32 s59, s72, s34
	s_mov_b32 m0, s59
	ds_read_b128 v[184:187], v151 offset:16384
	ds_read_b128 v[188:191], v151 offset:17408
	ds_read_b128 v[192:195], v151 offset:18432
	ds_read_b128 v[196:199], v151 offset:19456
	ds_read_b128 v[200:203], v151 offset:20480
	ds_read_b128 v[204:207], v151 offset:21504
	ds_read_b128 v[208:211], v151 offset:22528
	ds_read_b128 v[212:215], v151 offset:23552
	global_load_lds_dwordx4 v130, s[26:27]
	s_add_i32 m0, s59, 0x2000
	s_add_u32 s64, s26, 0x4000
	s_addc_u32 s65, s27, 0
	s_add_i32 s59, s73, s34
	global_load_lds_dwordx4 v132, s[26:27]
	s_mov_b32 m0, s59
	s_nop 0
	global_load_lds_dwordx4 v130, s[64:65]
	s_add_i32 m0, s59, 0x2000
	s_nop 0
	global_load_lds_dwordx4 v132, s[64:65]
	s_mov_b32 m0, s35
	s_nop 0
	global_load_lds_dwordx4 v130, s[28:29]
	s_mov_b32 m0, s36
	s_nop 0
	global_load_lds_dwordx4 v132, s[28:29]
	s_waitcnt vmcnt(8) lgkmcnt(0)
	s_barrier
; #define PG8_STAGE(bufoff, gbase, voff) do { _Pragma("unroll") for (int _i = 0; _i < 2; ++_i) \
;         __builtin_amdgcn_global_load_lds((const unsigned*)((const char*)(gbase) + (voff)[_i]), (LAS unsigned*)(lds + (bufoff) + ldsw + _i * 8192), 16, 0, 0); } while (0)
; #define PG8_LDA(dst, b, h) do { _Pragma("unroll") for (int m = 0; m < 4; ++m) _Pragma("unroll") for (int k = 0; k < 2; ++k) dst[m][k] = *(const LAS bf16x8*)(lds + PG8_SA(b, h) + aoff + m * 2048 + k * 1024); } while (0)
; #define PG8_LDB(dst, b, h) do { _Pragma("unroll") for (int n = 0; n < 2; ++n) _Pragma("unroll") for (int k = 0; k < 2; ++k) dst[n][k] = *(const LAS bf16x8*)(lds + PG8_SB(b, h) + boff + n * 2048 + k * 1024); } while (0)
; #define PG8_MMA(ai, bj, At, Bt) do { __builtin_amdgcn_s_setprio(1); _Pragma("unroll") for (int m = 0; m < 4; ++m) _Pragma("unroll") for (int n = 0; n < 2; ++n) _Pragma("unroll") for (int k = 0; k < 2; ++k) \
;         acc[ai][bj][m][n] = __builtin_amdgcn_mfma_f32_16x16x32_bf16(Bt[n][k], At[m][k], acc[ai][bj][m][n], 0, 0, 0); __builtin_amdgcn_s_setprio(0); } while (0)
; #define PG8_WAIT_V(n) asm volatile("s_waitcnt vmcnt(" #n ")" ::: "memory")
; #define PG8_WAIT_L(n) asm volatile("s_waitcnt lgkmcnt(" #n ")" ::: "memory")
; #define PG8_BAR __builtin_amdgcn_s_barrier()
; #define PG8_SCHED __builtin_amdgcn_sched_barrier(0)
; template <class Epi, class Sched, bool ABLK = false, bool ALIGN_EPI = true, bool SP2 = true, bool BBLK = true>
; __device__ __forceinline__ void gemm_phase(LAS unsigned char* lds, const Gemm g, const Sched& S, const Epi& E) {
;     ...
;             PG8_WAIT_V(8); PG8_WAIT_L(0); PG8_BAR; PG8_MMA(1, 0, At, B0); PG8_MMA(1, 1, At, B1); PG8_BAR; PG8_SCHED;
;             PG8_LDB(B0, 1, 0); PG8_LDB(B1, 1, 1); PG8_SCHED; PG8_LDA(At, 1, 0); PG8_STAGE(PG8_SA(0, 1), a2 + hstepA, voffA);
;             PG8_WAIT_V(8); PG8_WAIT_L(0); PG8_BAR; PG8_MMA(0, 0, At, B0); PG8_MMA(0, 1, At, B1); PG8_BAR; PG8_SCHED;
	v_mfma_f32_16x16x32_bf16 v[62:65], v[152:155], v[184:187], 0
	v_mfma_f32_16x16x32_bf16 v[58:61], v[160:163], v[184:187], 0
	v_mfma_f32_16x16x32_bf16 v[46:49], v[152:155], v[192:195], 0
	v_mfma_f32_16x16x32_bf16 v[42:45], v[160:163], v[192:195], 0
	v_mfma_f32_16x16x32_bf16 v[30:33], v[152:155], v[200:203], 0
	v_mfma_f32_16x16x32_bf16 v[26:29], v[160:163], v[200:203], 0
	v_mfma_f32_16x16x32_bf16 v[14:17], v[152:155], v[208:211], 0
	v_mfma_f32_16x16x32_bf16 v[10:13], v[160:163], v[208:211], 0
	v_mfma_f32_16x16x32_bf16 v[62:65], v[156:159], v[188:191], v[62:65]
	v_mfma_f32_16x16x32_bf16 v[58:61], v[164:167], v[188:191], v[58:61]
	v_mfma_f32_16x16x32_bf16 v[46:49], v[156:159], v[196:199], v[46:49]
	v_mfma_f32_16x16x32_bf16 v[42:45], v[164:167], v[196:199], v[42:45]
	v_mfma_f32_16x16x32_bf16 v[30:33], v[156:159], v[204:207], v[30:33]
	v_mfma_f32_16x16x32_bf16 v[26:29], v[164:167], v[204:207], v[26:29]
	v_mfma_f32_16x16x32_bf16 v[14:17], v[156:159], v[212:215], v[14:17]
	v_mfma_f32_16x16x32_bf16 v[10:13], v[164:167], v[212:215], v[10:13]
	v_mfma_f32_16x16x32_bf16 v[54:57], v[168:171], v[184:187], 0
	v_mfma_f32_16x16x32_bf16 v[50:53], v[176:179], v[184:187], 0
	v_mfma_f32_16x16x32_bf16 v[38:41], v[168:171], v[192:195], 0
	v_mfma_f32_16x16x32_bf16 v[34:37], v[176:179], v[192:195], 0
	v_mfma_f32_16x16x32_bf16 v[22:25], v[168:171], v[200:203], 0
	v_mfma_f32_16x16x32_bf16 v[18:21], v[176:179], v[200:203], 0
	v_mfma_f32_16x16x32_bf16 v[6:9], v[168:171], v[208:211], 0
	v_mfma_f32_16x16x32_bf16 v[2:5], v[176:179], v[208:211], 0
	v_mfma_f32_16x16x32_bf16 v[54:57], v[172:175], v[188:191], v[54:57]
	v_mfma_f32_16x16x32_bf16 v[50:53], v[180:183], v[188:191], v[50:53]
	v_mfma_f32_16x16x32_bf16 v[38:41], v[172:175], v[196:199], v[38:41]
	v_mfma_f32_16x16x32_bf16 v[34:37], v[180:183], v[196:199], v[34:37]
	v_mfma_f32_16x16x32_bf16 v[22:25], v[172:175], v[204:207], v[22:25]
	v_mfma_f32_16x16x32_bf16 v[18:21], v[180:183], v[204:207], v[18:21]
	v_mfma_f32_16x16x32_bf16 v[6:9], v[172:175], v[212:215], v[6:9]
	v_mfma_f32_16x16x32_bf16 v[2:5], v[180:183], v[212:215], v[2:5]
	s_barrier
	v_add_u32_e32 v164, s60, v147
	v_add_u32_e32 v180, s61, v147
	ds_read_b128 v[152:155], v164
	ds_read_b128 v[156:159], v164 offset:1024
	ds_read_b128 v[160:163], v164 offset:2048
	ds_read_b128 v[164:167], v164 offset:3072
	ds_read_b128 v[168:171], v180
	ds_read_b128 v[172:175], v180 offset:1024
	ds_read_b128 v[176:179], v180 offset:2048
	ds_read_b128 v[180:183], v180 offset:3072
	s_add_u32 s28, s28, 0x4000
	s_addc_u32 s29, s29, 0
	s_mov_b32 m0, s37
	ds_read_b128 v[184:187], v151 offset:32768
	ds_read_b128 v[188:191], v151 offset:33792
	ds_read_b128 v[192:195], v151 offset:34816
	ds_read_b128 v[196:199], v151 offset:35840
	ds_read_b128 v[200:203], v151 offset:36864
	ds_read_b128 v[204:207], v151 offset:37888
	ds_read_b128 v[208:211], v151 offset:38912
	ds_read_b128 v[212:215], v151 offset:39936
	global_load_lds_dwordx4 v130, s[28:29]
	s_mov_b32 m0, s40
	s_nop 0
	global_load_lds_dwordx4 v132, s[28:29]
	s_waitcnt vmcnt(8) lgkmcnt(0)
	s_barrier
	v_mfma_f32_16x16x32_bf16 v[126:129], v[152:155], v[184:187], v[126:129]
	v_mfma_f32_16x16x32_bf16 v[122:125], v[160:163], v[184:187], v[122:125]
	v_mfma_f32_16x16x32_bf16 v[110:113], v[152:155], v[192:195], v[110:113]
	v_mfma_f32_16x16x32_bf16 v[106:109], v[160:163], v[192:195], v[106:109]
	v_mfma_f32_16x16x32_bf16 v[94:97], v[152:155], v[200:203], v[94:97]
	v_mfma_f32_16x16x32_bf16 v[90:93], v[160:163], v[200:203], v[90:93]
	v_mfma_f32_16x16x32_bf16 v[78:81], v[152:155], v[208:211], v[78:81]
	v_mfma_f32_16x16x32_bf16 v[74:77], v[160:163], v[208:211], v[74:77]
	v_mfma_f32_16x16x32_bf16 v[126:129], v[156:159], v[188:191], v[126:129]
	v_mfma_f32_16x16x32_bf16 v[122:125], v[164:167], v[188:191], v[122:125]
	v_mfma_f32_16x16x32_bf16 v[110:113], v[156:159], v[196:199], v[110:113]
	v_mfma_f32_16x16x32_bf16 v[106:109], v[164:167], v[196:199], v[106:109]
	v_mfma_f32_16x16x32_bf16 v[94:97], v[156:159], v[204:207], v[94:97]
	v_mfma_f32_16x16x32_bf16 v[90:93], v[164:167], v[204:207], v[90:93]
	v_mfma_f32_16x16x32_bf16 v[78:81], v[156:159], v[212:215], v[78:81]
	v_mfma_f32_16x16x32_bf16 v[74:77], v[164:167], v[212:215], v[74:77]
	v_mfma_f32_16x16x32_bf16 v[118:121], v[168:171], v[184:187], v[118:121]
	v_mfma_f32_16x16x32_bf16 v[114:117], v[176:179], v[184:187], v[114:117]
	v_mfma_f32_16x16x32_bf16 v[102:105], v[168:171], v[192:195], v[102:105]
	v_mfma_f32_16x16x32_bf16 v[98:101], v[176:179], v[192:195], v[98:101]
	v_mfma_f32_16x16x32_bf16 v[86:89], v[168:171], v[200:203], v[86:89]
	v_mfma_f32_16x16x32_bf16 v[82:85], v[176:179], v[200:203], v[82:85]
	v_mfma_f32_16x16x32_bf16 v[70:73], v[168:171], v[208:211], v[70:73]
	v_mfma_f32_16x16x32_bf16 v[66:69], v[176:179], v[208:211], v[66:69]
	v_mfma_f32_16x16x32_bf16 v[118:121], v[172:175], v[188:191], v[118:121]
	v_mfma_f32_16x16x32_bf16 v[114:117], v[180:183], v[188:191], v[114:117]
	v_mfma_f32_16x16x32_bf16 v[102:105], v[172:175], v[196:199], v[102:105]
	v_mfma_f32_16x16x32_bf16 v[98:101], v[180:183], v[196:199], v[98:101]
	v_mfma_f32_16x16x32_bf16 v[86:89], v[172:175], v[204:207], v[86:89]
	v_mfma_f32_16x16x32_bf16 v[82:85], v[180:183], v[204:207], v[82:85]
	v_mfma_f32_16x16x32_bf16 v[70:73], v[172:175], v[212:215], v[70:73]
	v_mfma_f32_16x16x32_bf16 v[66:69], v[180:183], v[212:215], v[66:69]
	s_barrier
; #define PG8_STAGE(bufoff, gbase, voff) do { _Pragma("unroll") for (int _i = 0; _i < 2; ++_i) \
;         __builtin_amdgcn_global_load_lds((const unsigned*)((const char*)(gbase) + (voff)[_i]), (LAS unsigned*)(lds + (bufoff) + ldsw + _i * 8192), 16, 0, 0); } while (0)
; #define PG8_LDA(dst, b, h) do { _Pragma("unroll") for (int m = 0; m < 4; ++m) _Pragma("unroll") for (int k = 0; k < 2; ++k) dst[m][k] = *(const LAS bf16x8*)(lds + PG8_SA(b, h) + aoff + m * 2048 + k * 1024); } while (0)
; #define PG8_WAIT_V(n) asm volatile("s_waitcnt vmcnt(" #n ")" ::: "memory")
; #define PG8_WAIT_L(n) asm volatile("s_waitcnt lgkmcnt(" #n ")" ::: "memory")
; template <class Epi, class Sched, bool ABLK = false, bool ALIGN_EPI = true, bool SP2 = true, bool BBLK = true>
; __device__ __forceinline__ void gemm_phase(LAS unsigned char* lds, const Gemm g, const Sched& S, const Epi& E) {
;     ...
;         for (int t = 0; t < nt; t += 2) {
;             const bool last = (t == nt - 2);
;             const char* a1 = a_tile(uA, tbA + t + 1);
;             const char* a2 = last ? a_tile(nuA, ntbA) : a_tile(uA, tbA + t + 2); const char* b2 = last ? nB : cB + (size_t)(t + 2) * kstepB;
;             const char* a3 = last ? a_tile(nuA, ntbA + 1) : a_tile(uA, tbA + t + 3); const char* b3 = b2 + kstepB;
;             if (last && has_next) S.a_ready(nxt);
;             if constexpr (SP2) {
;             PG8_LDB(B0, 0, 0); PG8_LDB(B1, 0, 1); PG8_SCHED; PG8_LDA(At, 0, 0); PG8_STAGE(PG8_SA(1, 1), a1 + hstepA, voffA);
;             PG8_WAIT_V(8); PG8_WAIT_L(0); PG8_BAR; PG8_MMA(0, 0, At, B0); PG8_MMA(0, 1, At, B1); PG8_BAR; PG8_SCHED;
;             PG8_LDA(At, 0, 1); PG8_STAGE(PG8_SB(0, 0), b2, voffB); PG8_STAGE(PG8_SB(0, 1), b2 + hstepB, voffB); PG8_STAGE(PG8_SA(0, 0), a2, voffA);
;             PG8_WAIT_V(8); PG8_WAIT_L(0); PG8_BAR; PG8_MMA(1, 0, At, B0); PG8_MMA(1, 1, At, B1); PG8_BAR; PG8_SCHED;
;             PG8_LDB(B0, 1, 0); PG8_LDB(B1, 1, 1); PG8_SCHED; PG8_LDA(At, 1, 0); PG8_STAGE(PG8_SA(0, 1), a2 + hstepA, voffA);
;             PG8_WAIT_V(8); PG8_WAIT_L(0); PG8_BAR; PG8_MMA(0, 0, At, B0); PG8_MMA(0, 1, At, B1); PG8_BAR; PG8_SCHED;
;             PG8_LDA(At, 1, 1); PG8_STAGE(PG8_SB(1, 0), b3, voffB); PG8_STAGE(PG8_SB(1, 1), b3 + hstepB, voffB); PG8_STAGE(PG8_SA(1, 0), a3, voffA);
;             PG8_WAIT_V(8); PG8_WAIT_L(0); PG8_BAR; PG8_MMA(1, 0, At, B0); PG8_MMA(1, 1, At, B1); PG8_BAR; PG8_SCHED;
	s_add_u32 s28, s26, 0x8000
	s_addc_u32 s29, s27, 0
	s_add_i32 s59, s60, s34
	s_mov_b32 m0, s59
	ds_read_b128 v[184:187], v151 offset:49152
	ds_read_b128 v[188:191], v151 offset:50176
	ds_read_b128 v[192:195], v151 offset:51200
	ds_read_b128 v[196:199], v151 offset:52224
	ds_read_b128 v[200:203], v151 offset:53248
	ds_read_b128 v[204:207], v151 offset:54272
	ds_read_b128 v[208:211], v151 offset:55296
	ds_read_b128 v[212:215], v151 offset:56320
	global_load_lds_dwordx4 v130, s[28:29]
	s_add_i32 m0, s59, 0x2000
	s_add_u32 s26, s26, 0xc000
	v_lshl_add_u64 v[216:217], s[28:29], 0, v[132:133]
	s_addc_u32 s27, s27, 0
	s_add_i32 s28, s61, s34
	global_load_lds_dwordx4 v[216:217], off
	s_mov_b32 m0, s28
	s_nop 0
	global_load_lds_dwordx4 v130, s[26:27]
	s_add_i32 m0, s28, 0x2000
	s_nop 0
	global_load_lds_dwordx4 v132, s[26:27]
	s_mov_b32 m0, s41
	s_nop 0
	global_load_lds_dwordx4 v130, s[24:25]
	s_mov_b32 m0, s42
	s_nop 0
	global_load_lds_dwordx4 v132, s[24:25]
	s_waitcnt vmcnt(8) lgkmcnt(0)
	s_barrier
	v_mfma_f32_16x16x32_bf16 v[62:65], v[152:155], v[184:187], v[62:65]
	v_mfma_f32_16x16x32_bf16 v[58:61], v[160:163], v[184:187], v[58:61]
	v_mfma_f32_16x16x32_bf16 v[46:49], v[152:155], v[192:195], v[46:49]
	v_mfma_f32_16x16x32_bf16 v[42:45], v[160:163], v[192:195], v[42:45]
	v_mfma_f32_16x16x32_bf16 v[30:33], v[152:155], v[200:203], v[30:33]
	v_mfma_f32_16x16x32_bf16 v[26:29], v[160:163], v[200:203], v[26:29]
	v_mfma_f32_16x16x32_bf16 v[14:17], v[152:155], v[208:211], v[14:17]
	v_mfma_f32_16x16x32_bf16 v[10:13], v[160:163], v[208:211], v[10:13]
	v_mfma_f32_16x16x32_bf16 v[62:65], v[156:159], v[188:191], v[62:65]
	v_mfma_f32_16x16x32_bf16 v[58:61], v[164:167], v[188:191], v[58:61]
	v_mfma_f32_16x16x32_bf16 v[46:49], v[156:159], v[196:199], v[46:49]
	v_mfma_f32_16x16x32_bf16 v[42:45], v[164:167], v[196:199], v[42:45]
	v_mfma_f32_16x16x32_bf16 v[30:33], v[156:159], v[204:207], v[30:33]
	v_mfma_f32_16x16x32_bf16 v[26:29], v[164:167], v[204:207], v[26:29]
	v_mfma_f32_16x16x32_bf16 v[14:17], v[156:159], v[212:215], v[14:17]
	v_mfma_f32_16x16x32_bf16 v[10:13], v[164:167], v[212:215], v[10:13]
	v_mfma_f32_16x16x32_bf16 v[54:57], v[168:171], v[184:187], v[54:57]
	v_mfma_f32_16x16x32_bf16 v[50:53], v[176:179], v[184:187], v[50:53]
	v_mfma_f32_16x16x32_bf16 v[38:41], v[168:171], v[192:195], v[38:41]
	v_mfma_f32_16x16x32_bf16 v[34:37], v[176:179], v[192:195], v[34:37]
	v_mfma_f32_16x16x32_bf16 v[22:25], v[168:171], v[200:203], v[22:25]
	v_mfma_f32_16x16x32_bf16 v[18:21], v[176:179], v[200:203], v[18:21]
	v_mfma_f32_16x16x32_bf16 v[6:9], v[168:171], v[208:211], v[6:9]
	v_mfma_f32_16x16x32_bf16 v[2:5], v[176:179], v[208:211], v[2:5]
	v_mfma_f32_16x16x32_bf16 v[54:57], v[172:175], v[188:191], v[54:57]
	v_mfma_f32_16x16x32_bf16 v[50:53], v[180:183], v[188:191], v[50:53]
	v_mfma_f32_16x16x32_bf16 v[38:41], v[172:175], v[196:199], v[38:41]
	v_mfma_f32_16x16x32_bf16 v[34:37], v[180:183], v[196:199], v[34:37]
	v_mfma_f32_16x16x32_bf16 v[22:25], v[172:175], v[204:207], v[22:25]
	v_mfma_f32_16x16x32_bf16 v[18:21], v[180:183], v[204:207], v[18:21]
	v_mfma_f32_16x16x32_bf16 v[6:9], v[172:175], v[212:215], v[6:9]
	v_mfma_f32_16x16x32_bf16 v[2:5], v[180:183], v[212:215], v[2:5]
	s_barrier
	s_add_u32 s22, s22, 0x10000
	s_addc_u32 s23, s23, 0
	s_cmp_ge_u32 s57, s44
.LBB0_1229:
	ds_read_b128 v[152:155], v149
	ds_read_b128 v[156:159], v149 offset:1024
	ds_read_b128 v[160:163], v149 offset:2048
	ds_read_b128 v[164:167], v149 offset:3072
	ds_read_b128 v[168:171], v150
	ds_read_b128 v[172:175], v150 offset:1024
	ds_read_b128 v[176:179], v150 offset:2048
	ds_read_b128 v[180:183], v150 offset:3072
	s_add_u32 s24, s51, s22
	s_addc_u32 s25, s55, s23
	s_add_u32 s28, s24, 0x10000
	s_addc_u32 s29, s25, 0
	s_add_i32 s57, s57, 2
	s_add_u32 s26, s49, s22
	s_addc_u32 s27, s50, s23
	s_add_u32 s24, s24, 0x18000
	s_addc_u32 s25, s25, 0
	s_cmp_eq_u32 s56, s22
	s_cbranch_scc1 .Lksel_13
.Lksel_13_back:
	v_lshl_add_u64 v[216:217], v[142:143], 0, s[22:23]
	s_add_i32 m0, s35, 0xc000
	ds_read_b128 v[184:187], v151
	ds_read_b128 v[188:191], v151 offset:1024
	ds_read_b128 v[192:195], v151 offset:2048
	ds_read_b128 v[196:199], v151 offset:3072
	ds_read_b128 v[200:203], v151 offset:4096
	ds_read_b128 v[204:207], v151 offset:5120
	ds_read_b128 v[208:211], v151 offset:6144
	ds_read_b128 v[212:215], v151 offset:7168
	global_load_lds_dwordx4 v[216:217], off
	v_lshl_add_u64 v[216:217], v[144:145], 0, s[22:23]
	s_add_i32 m0, s35, 0xe000
	s_nop 0
	global_load_lds_dwordx4 v[216:217], off
	s_waitcnt vmcnt(8) lgkmcnt(0)
	s_barrier
; #define PG8_STAGE(bufoff, gbase, voff) do { _Pragma("unroll") for (int _i = 0; _i < 2; ++_i) \
;         __builtin_amdgcn_global_load_lds((const unsigned*)((const char*)(gbase) + (voff)[_i]), (LAS unsigned*)(lds + (bufoff) + ldsw + _i * 8192), 16, 0, 0); } while (0)
; #define PG8_LDA(dst, b, h) do { _Pragma("unroll") for (int m = 0; m < 4; ++m) _Pragma("unroll") for (int k = 0; k < 2; ++k) dst[m][k] = *(const LAS bf16x8*)(lds + PG8_SA(b, h) + aoff + m * 2048 + k * 1024); } while (0)
; #define PG8_LDB(dst, b, h) do { _Pragma("unroll") for (int n = 0; n < 2; ++n) _Pragma("unroll") for (int k = 0; k < 2; ++k) dst[n][k] = *(const LAS bf16x8*)(lds + PG8_SB(b, h) + boff + n * 2048 + k * 1024); } while (0)
; #define PG8_MMA(ai, bj, At, Bt) do { __builtin_amdgcn_s_setprio(1); _Pragma("unroll") for (int m = 0; m < 4; ++m) _Pragma("unroll") for (int n = 0; n < 2; ++n) _Pragma("unroll") for (int k = 0; k < 2; ++k) \
;         acc[ai][bj][m][n] = __builtin_amdgcn_mfma_f32_16x16x32_bf16(Bt[n][k], At[m][k], acc[ai][bj][m][n], 0, 0, 0); __builtin_amdgcn_s_setprio(0); } while (0)
; #define PG8_WAIT_V(n) asm volatile("s_waitcnt vmcnt(" #n ")" ::: "memory")
; #define PG8_WAIT_L(n) asm volatile("s_waitcnt lgkmcnt(" #n ")" ::: "memory")
; #define PG8_BAR __builtin_amdgcn_s_barrier()
; #define PG8_SCHED __builtin_amdgcn_sched_barrier(0)
; template <class Epi, class Sched, bool ABLK = false, bool ALIGN_EPI = true, bool SP2 = true, bool BBLK = true>
; __device__ __forceinline__ void gemm_phase(LAS unsigned char* lds, const Gemm g, const Sched& S, const Epi& E) {
;     ...
;             PG8_LDB(B0, 0, 0); PG8_LDB(B1, 0, 1); PG8_SCHED; PG8_LDA(At, 0, 0); PG8_STAGE(PG8_SA(1, 1), a1 + hstepA, voffA);
;             PG8_WAIT_V(8); PG8_WAIT_L(0); PG8_BAR; PG8_MMA(0, 0, At, B0); PG8_MMA(0, 1, At, B1); PG8_BAR; PG8_SCHED;
;             PG8_LDA(At, 0, 1); PG8_STAGE(PG8_SB(0, 0), b2, voffB); PG8_STAGE(PG8_SB(0, 1), b2 + hstepB, voffB); PG8_STAGE(PG8_SA(0, 0), a2, voffA);
;             PG8_WAIT_V(8); PG8_WAIT_L(0); PG8_BAR; PG8_MMA(1, 0, At, B0); PG8_MMA(1, 1, At, B1); PG8_BAR; PG8_SCHED;
;             PG8_LDB(B0, 1, 0); PG8_LDB(B1, 1, 1); PG8_SCHED; PG8_LDA(At, 1, 0); PG8_STAGE(PG8_SA(0, 1), a2 + hstepA, voffA);
;             PG8_WAIT_V(8); PG8_WAIT_L(0); PG8_BAR; PG8_MMA(0, 0, At, B0); PG8_MMA(0, 1, At, B1); PG8_BAR; PG8_SCHED;
	v_mfma_f32_16x16x32_bf16 v[126:129], v[152:155], v[184:187], v[126:129]
	v_mfma_f32_16x16x32_bf16 v[122:125], v[160:163], v[184:187], v[122:125]
	v_mfma_f32_16x16x32_bf16 v[110:113], v[152:155], v[192:195], v[110:113]
	v_mfma_f32_16x16x32_bf16 v[106:109], v[160:163], v[192:195], v[106:109]
	v_mfma_f32_16x16x32_bf16 v[94:97], v[152:155], v[200:203], v[94:97]
	v_mfma_f32_16x16x32_bf16 v[90:93], v[160:163], v[200:203], v[90:93]
	v_mfma_f32_16x16x32_bf16 v[78:81], v[152:155], v[208:211], v[78:81]
	v_mfma_f32_16x16x32_bf16 v[74:77], v[160:163], v[208:211], v[74:77]
	v_mfma_f32_16x16x32_bf16 v[126:129], v[156:159], v[188:191], v[126:129]
	v_mfma_f32_16x16x32_bf16 v[122:125], v[164:167], v[188:191], v[122:125]
	v_mfma_f32_16x16x32_bf16 v[110:113], v[156:159], v[196:199], v[110:113]
	v_mfma_f32_16x16x32_bf16 v[106:109], v[164:167], v[196:199], v[106:109]
	v_mfma_f32_16x16x32_bf16 v[94:97], v[156:159], v[204:207], v[94:97]
	v_mfma_f32_16x16x32_bf16 v[90:93], v[164:167], v[204:207], v[90:93]
	v_mfma_f32_16x16x32_bf16 v[78:81], v[156:159], v[212:215], v[78:81]
	v_mfma_f32_16x16x32_bf16 v[74:77], v[164:167], v[212:215], v[74:77]
	v_mfma_f32_16x16x32_bf16 v[118:121], v[168:171], v[184:187], v[118:121]
	v_mfma_f32_16x16x32_bf16 v[114:117], v[176:179], v[184:187], v[114:117]
	v_mfma_f32_16x16x32_bf16 v[102:105], v[168:171], v[192:195], v[102:105]
	v_mfma_f32_16x16x32_bf16 v[98:101], v[176:179], v[192:195], v[98:101]
	v_mfma_f32_16x16x32_bf16 v[86:89], v[168:171], v[200:203], v[86:89]
	v_mfma_f32_16x16x32_bf16 v[82:85], v[176:179], v[200:203], v[82:85]
	v_mfma_f32_16x16x32_bf16 v[70:73], v[168:171], v[208:211], v[70:73]
	v_mfma_f32_16x16x32_bf16 v[66:69], v[176:179], v[208:211], v[66:69]
	v_mfma_f32_16x16x32_bf16 v[118:121], v[172:175], v[188:191], v[118:121]
	v_mfma_f32_16x16x32_bf16 v[114:117], v[180:183], v[188:191], v[114:117]
	v_mfma_f32_16x16x32_bf16 v[102:105], v[172:175], v[196:199], v[102:105]
	v_mfma_f32_16x16x32_bf16 v[98:101], v[180:183], v[196:199], v[98:101]
	v_mfma_f32_16x16x32_bf16 v[86:89], v[172:175], v[204:207], v[86:89]
	v_mfma_f32_16x16x32_bf16 v[82:85], v[180:183], v[204:207], v[82:85]
	v_mfma_f32_16x16x32_bf16 v[70:73], v[172:175], v[212:215], v[70:73]
	v_mfma_f32_16x16x32_bf16 v[66:69], v[180:183], v[212:215], v[66:69]
	s_barrier
	s_add_i32 s59, s72, s34
	s_mov_b32 m0, s59
	ds_read_b128 v[184:187], v151 offset:16384
	ds_read_b128 v[188:191], v151 offset:17408
	ds_read_b128 v[192:195], v151 offset:18432
	ds_read_b128 v[196:199], v151 offset:19456
	ds_read_b128 v[200:203], v151 offset:20480
	ds_read_b128 v[204:207], v151 offset:21504
	ds_read_b128 v[208:211], v151 offset:22528
	ds_read_b128 v[212:215], v151 offset:23552
	global_load_lds_dwordx4 v130, s[26:27]
	s_add_i32 m0, s59, 0x2000
	s_add_u32 s64, s26, 0x4000
	s_addc_u32 s65, s27, 0
	s_add_i32 s59, s73, s34
	global_load_lds_dwordx4 v132, s[26:27]
	s_mov_b32 m0, s59
	s_nop 0
	global_load_lds_dwordx4 v130, s[64:65]
	s_add_i32 m0, s59, 0x2000
	s_nop 0
	global_load_lds_dwordx4 v132, s[64:65]
	s_mov_b32 m0, s35
	s_nop 0
	global_load_lds_dwordx4 v130, s[28:29]
	s_mov_b32 m0, s36
	s_nop 0
	global_load_lds_dwordx4 v132, s[28:29]
	s_waitcnt vmcnt(8) lgkmcnt(0)
	s_barrier
	v_mfma_f32_16x16x32_bf16 v[62:65], v[152:155], v[184:187], v[62:65]
	v_mfma_f32_16x16x32_bf16 v[58:61], v[160:163], v[184:187], v[58:61]
	v_mfma_f32_16x16x32_bf16 v[46:49], v[152:155], v[192:195], v[46:49]
	v_mfma_f32_16x16x32_bf16 v[42:45], v[160:163], v[192:195], v[42:45]
	v_mfma_f32_16x16x32_bf16 v[30:33], v[152:155], v[200:203], v[30:33]
	v_mfma_f32_16x16x32_bf16 v[26:29], v[160:163], v[200:203], v[26:29]
	v_mfma_f32_16x16x32_bf16 v[14:17], v[152:155], v[208:211], v[14:17]
	v_mfma_f32_16x16x32_bf16 v[10:13], v[160:163], v[208:211], v[10:13]
	v_mfma_f32_16x16x32_bf16 v[62:65], v[156:159], v[188:191], v[62:65]
	v_mfma_f32_16x16x32_bf16 v[58:61], v[164:167], v[188:191], v[58:61]
	v_mfma_f32_16x16x32_bf16 v[46:49], v[156:159], v[196:199], v[46:49]
	v_mfma_f32_16x16x32_bf16 v[42:45], v[164:167], v[196:199], v[42:45]
	v_mfma_f32_16x16x32_bf16 v[30:33], v[156:159], v[204:207], v[30:33]
	v_mfma_f32_16x16x32_bf16 v[26:29], v[164:167], v[204:207], v[26:29]
	v_mfma_f32_16x16x32_bf16 v[14:17], v[156:159], v[212:215], v[14:17]
	v_mfma_f32_16x16x32_bf16 v[10:13], v[164:167], v[212:215], v[10:13]
	v_mfma_f32_16x16x32_bf16 v[54:57], v[168:171], v[184:187], v[54:57]
	v_mfma_f32_16x16x32_bf16 v[50:53], v[176:179], v[184:187], v[50:53]
	v_mfma_f32_16x16x32_bf16 v[38:41], v[168:171], v[192:195], v[38:41]
	v_mfma_f32_16x16x32_bf16 v[34:37], v[176:179], v[192:195], v[34:37]
	v_mfma_f32_16x16x32_bf16 v[22:25], v[168:171], v[200:203], v[22:25]
	v_mfma_f32_16x16x32_bf16 v[18:21], v[176:179], v[200:203], v[18:21]
	v_mfma_f32_16x16x32_bf16 v[6:9], v[168:171], v[208:211], v[6:9]
	v_mfma_f32_16x16x32_bf16 v[2:5], v[176:179], v[208:211], v[2:5]
	v_mfma_f32_16x16x32_bf16 v[54:57], v[172:175], v[188:191], v[54:57]
	v_mfma_f32_16x16x32_bf16 v[50:53], v[180:183], v[188:191], v[50:53]
	v_mfma_f32_16x16x32_bf16 v[38:41], v[172:175], v[196:199], v[38:41]
	v_mfma_f32_16x16x32_bf16 v[34:37], v[180:183], v[196:199], v[34:37]
	v_mfma_f32_16x16x32_bf16 v[22:25], v[172:175], v[204:207], v[22:25]
	v_mfma_f32_16x16x32_bf16 v[18:21], v[180:183], v[204:207], v[18:21]
	v_mfma_f32_16x16x32_bf16 v[6:9], v[172:175], v[212:215], v[6:9]
	v_mfma_f32_16x16x32_bf16 v[2:5], v[180:183], v[212:215], v[2:5]
	s_barrier
; #define PG8_STAGE(bufoff, gbase, voff) do { _Pragma("unroll") for (int _i = 0; _i < 2; ++_i) \
;         __builtin_amdgcn_global_load_lds((const unsigned*)((const char*)(gbase) + (voff)[_i]), (LAS unsigned*)(lds + (bufoff) + ldsw + _i * 8192), 16, 0, 0); } while (0)
; #define PG8_LDA(dst, b, h) do { _Pragma("unroll") for (int m = 0; m < 4; ++m) _Pragma("unroll") for (int k = 0; k < 2; ++k) dst[m][k] = *(const LAS bf16x8*)(lds + PG8_SA(b, h) + aoff + m * 2048 + k * 1024); } while (0)
; #define PG8_LDB(dst, b, h) do { _Pragma("unroll") for (int n = 0; n < 2; ++n) _Pragma("unroll") for (int k = 0; k < 2; ++k) dst[n][k] = *(const LAS bf16x8*)(lds + PG8_SB(b, h) + boff + n * 2048 + k * 1024); } while (0)
; #define PG8_MMA(ai, bj, At, Bt) do { __builtin_amdgcn_s_setprio(1); _Pragma("unroll") for (int m = 0; m < 4; ++m) _Pragma("unroll") for (int n = 0; n < 2; ++n) _Pragma("unroll") for (int k = 0; k < 2; ++k) \
;         acc[ai][bj][m][n] = __builtin_amdgcn_mfma_f32_16x16x32_bf16(Bt[n][k], At[m][k], acc[ai][bj][m][n], 0, 0, 0); __builtin_amdgcn_s_setprio(0); } while (0)
; #define PG8_WAIT_V(n) asm volatile("s_waitcnt vmcnt(" #n ")" ::: "memory")
; #define PG8_WAIT_L(n) asm volatile("s_waitcnt lgkmcnt(" #n ")" ::: "memory")
; #define PG8_BAR __builtin_amdgcn_s_barrier()
; #define PG8_SCHED __builtin_amdgcn_sched_barrier(0)
; template <class Epi, class Sched, bool ABLK = false, bool ALIGN_EPI = true, bool SP2 = true, bool BBLK = true>
; __device__ __forceinline__ void gemm_phase(LAS unsigned char* lds, const Gemm g, const Sched& S, const Epi& E) {
;     ...
;             PG8_LDB(B0, 1, 0); PG8_LDB(B1, 1, 1); PG8_SCHED; PG8_LDA(At, 1, 0); PG8_STAGE(PG8_SA(0, 1), a2 + hstepA, voffA);
;             PG8_WAIT_V(8); PG8_WAIT_L(0); PG8_BAR; PG8_MMA(0, 0, At, B0); PG8_MMA(0, 1, At, B1); PG8_BAR; PG8_SCHED;
;             PG8_LDA(At, 1, 1); PG8_STAGE(PG8_SB(1, 0), b3, voffB); PG8_STAGE(PG8_SB(1, 1), b3 + hstepB, voffB); PG8_STAGE(PG8_SA(1, 0), a3, voffA);
;             PG8_WAIT_V(8); PG8_WAIT_L(0); PG8_BAR; PG8_MMA(1, 0, At, B0); PG8_MMA(1, 1, At, B1); PG8_BAR; PG8_SCHED;
;     ...
;         if constexpr (ALIGN_EPI) { if (wr == 0) PG8_BAR; }
;         E(acc, cur, wr, wc, fr, fq); S.done(cur);
;         if (!has_next) break;
	v_add_u32_e32 v164, s60, v147
	v_add_u32_e32 v180, s61, v147
	ds_read_b128 v[152:155], v164
	ds_read_b128 v[156:159], v164 offset:1024
	ds_read_b128 v[160:163], v164 offset:2048
	ds_read_b128 v[164:167], v164 offset:3072
	ds_read_b128 v[168:171], v180
	ds_read_b128 v[172:175], v180 offset:1024
	ds_read_b128 v[176:179], v180 offset:2048
	ds_read_b128 v[180:183], v180 offset:3072
	s_add_u32 s28, s28, 0x4000
	s_addc_u32 s29, s29, 0
	s_mov_b32 m0, s37
	ds_read_b128 v[184:187], v151 offset:32768
	ds_read_b128 v[188:191], v151 offset:33792
	ds_read_b128 v[192:195], v151 offset:34816
	ds_read_b128 v[196:199], v151 offset:35840
	ds_read_b128 v[200:203], v151 offset:36864
	ds_read_b128 v[204:207], v151 offset:37888
	ds_read_b128 v[208:211], v151 offset:38912
	ds_read_b128 v[212:215], v151 offset:39936
	global_load_lds_dwordx4 v130, s[28:29]
	s_mov_b32 m0, s40
	s_nop 0
	global_load_lds_dwordx4 v132, s[28:29]
	s_waitcnt vmcnt(8) lgkmcnt(0)
	s_barrier
	v_mfma_f32_16x16x32_bf16 v[126:129], v[152:155], v[184:187], v[126:129]
	v_mfma_f32_16x16x32_bf16 v[122:125], v[160:163], v[184:187], v[122:125]
	v_mfma_f32_16x16x32_bf16 v[110:113], v[152:155], v[192:195], v[110:113]
	v_mfma_f32_16x16x32_bf16 v[106:109], v[160:163], v[192:195], v[106:109]
	v_mfma_f32_16x16x32_bf16 v[94:97], v[152:155], v[200:203], v[94:97]
	v_mfma_f32_16x16x32_bf16 v[90:93], v[160:163], v[200:203], v[90:93]
	v_mfma_f32_16x16x32_bf16 v[78:81], v[152:155], v[208:211], v[78:81]
	v_mfma_f32_16x16x32_bf16 v[74:77], v[160:163], v[208:211], v[74:77]
	v_mfma_f32_16x16x32_bf16 v[126:129], v[156:159], v[188:191], v[126:129]
	v_mfma_f32_16x16x32_bf16 v[122:125], v[164:167], v[188:191], v[122:125]
	v_mfma_f32_16x16x32_bf16 v[110:113], v[156:159], v[196:199], v[110:113]
	v_mfma_f32_16x16x32_bf16 v[106:109], v[164:167], v[196:199], v[106:109]
	v_mfma_f32_16x16x32_bf16 v[94:97], v[156:159], v[204:207], v[94:97]
	v_mfma_f32_16x16x32_bf16 v[90:93], v[164:167], v[204:207], v[90:93]
	v_mfma_f32_16x16x32_bf16 v[78:81], v[156:159], v[212:215], v[78:81]
	v_mfma_f32_16x16x32_bf16 v[74:77], v[164:167], v[212:215], v[74:77]
	v_mfma_f32_16x16x32_bf16 v[118:121], v[168:171], v[184:187], v[118:121]
	v_mfma_f32_16x16x32_bf16 v[114:117], v[176:179], v[184:187], v[114:117]
	v_mfma_f32_16x16x32_bf16 v[102:105], v[168:171], v[192:195], v[102:105]
	v_mfma_f32_16x16x32_bf16 v[98:101], v[176:179], v[192:195], v[98:101]
	v_mfma_f32_16x16x32_bf16 v[86:89], v[168:171], v[200:203], v[86:89]
	v_mfma_f32_16x16x32_bf16 v[82:85], v[176:179], v[200:203], v[82:85]
	v_mfma_f32_16x16x32_bf16 v[70:73], v[168:171], v[208:211], v[70:73]
	v_mfma_f32_16x16x32_bf16 v[66:69], v[176:179], v[208:211], v[66:69]
	v_mfma_f32_16x16x32_bf16 v[118:121], v[172:175], v[188:191], v[118:121]
	v_mfma_f32_16x16x32_bf16 v[114:117], v[180:183], v[188:191], v[114:117]
	v_mfma_f32_16x16x32_bf16 v[102:105], v[172:175], v[196:199], v[102:105]
	v_mfma_f32_16x16x32_bf16 v[98:101], v[180:183], v[196:199], v[98:101]
	v_mfma_f32_16x16x32_bf16 v[86:89], v[172:175], v[204:207], v[86:89]
	v_mfma_f32_16x16x32_bf16 v[82:85], v[180:183], v[204:207], v[82:85]
	v_mfma_f32_16x16x32_bf16 v[70:73], v[172:175], v[212:215], v[70:73]
	v_mfma_f32_16x16x32_bf16 v[66:69], v[180:183], v[212:215], v[66:69]
	s_barrier
	s_add_u32 s28, s26, 0x8000
	s_addc_u32 s29, s27, 0
	s_add_i32 s59, s60, s34
	s_mov_b32 m0, s59
	ds_read_b128 v[184:187], v151 offset:49152
	ds_read_b128 v[188:191], v151 offset:50176
	ds_read_b128 v[192:195], v151 offset:51200
	ds_read_b128 v[196:199], v151 offset:52224
	ds_read_b128 v[200:203], v151 offset:53248
	ds_read_b128 v[204:207], v151 offset:54272
	ds_read_b128 v[208:211], v151 offset:55296
	ds_read_b128 v[212:215], v151 offset:56320
	global_load_lds_dwordx4 v130, s[28:29]
	s_add_i32 m0, s59, 0x2000
	s_add_u32 s26, s26, 0xc000
	v_lshl_add_u64 v[216:217], s[28:29], 0, v[132:133]
	s_addc_u32 s27, s27, 0
	s_add_i32 s28, s61, s34
	global_load_lds_dwordx4 v[216:217], off
	s_mov_b32 m0, s28
	s_nop 0
	global_load_lds_dwordx4 v130, s[26:27]
	s_add_i32 m0, s28, 0x2000
	s_nop 0
	global_load_lds_dwordx4 v132, s[26:27]
	s_mov_b32 m0, s41
	s_nop 0
	global_load_lds_dwordx4 v130, s[24:25]
	s_mov_b32 m0, s42
	s_nop 0
	global_load_lds_dwordx4 v132, s[24:25]
	s_waitcnt vmcnt(8) lgkmcnt(0)
	s_barrier
	v_mfma_f32_16x16x32_bf16 v[62:65], v[152:155], v[184:187], v[62:65]
	v_mfma_f32_16x16x32_bf16 v[58:61], v[160:163], v[184:187], v[58:61]
	v_mfma_f32_16x16x32_bf16 v[46:49], v[152:155], v[192:195], v[46:49]
	v_mfma_f32_16x16x32_bf16 v[42:45], v[160:163], v[192:195], v[42:45]
	v_mfma_f32_16x16x32_bf16 v[30:33], v[152:155], v[200:203], v[30:33]
	v_mfma_f32_16x16x32_bf16 v[26:29], v[160:163], v[200:203], v[26:29]
	v_mfma_f32_16x16x32_bf16 v[14:17], v[152:155], v[208:211], v[14:17]
	v_mfma_f32_16x16x32_bf16 v[10:13], v[160:163], v[208:211], v[10:13]
	v_mfma_f32_16x16x32_bf16 v[62:65], v[156:159], v[188:191], v[62:65]
	v_mfma_f32_16x16x32_bf16 v[58:61], v[164:167], v[188:191], v[58:61]
	v_mfma_f32_16x16x32_bf16 v[46:49], v[156:159], v[196:199], v[46:49]
	v_mfma_f32_16x16x32_bf16 v[42:45], v[164:167], v[196:199], v[42:45]
	v_mfma_f32_16x16x32_bf16 v[30:33], v[156:159], v[204:207], v[30:33]
	v_mfma_f32_16x16x32_bf16 v[26:29], v[164:167], v[204:207], v[26:29]
	v_mfma_f32_16x16x32_bf16 v[14:17], v[156:159], v[212:215], v[14:17]
	v_mfma_f32_16x16x32_bf16 v[10:13], v[164:167], v[212:215], v[10:13]
	v_mfma_f32_16x16x32_bf16 v[54:57], v[168:171], v[184:187], v[54:57]
	v_mfma_f32_16x16x32_bf16 v[50:53], v[176:179], v[184:187], v[50:53]
	v_mfma_f32_16x16x32_bf16 v[38:41], v[168:171], v[192:195], v[38:41]
	v_mfma_f32_16x16x32_bf16 v[34:37], v[176:179], v[192:195], v[34:37]
	v_mfma_f32_16x16x32_bf16 v[22:25], v[168:171], v[200:203], v[22:25]
	v_mfma_f32_16x16x32_bf16 v[18:21], v[176:179], v[200:203], v[18:21]
	v_mfma_f32_16x16x32_bf16 v[6:9], v[168:171], v[208:211], v[6:9]
	v_mfma_f32_16x16x32_bf16 v[2:5], v[176:179], v[208:211], v[2:5]
	v_mfma_f32_16x16x32_bf16 v[54:57], v[172:175], v[188:191], v[54:57]
	v_mfma_f32_16x16x32_bf16 v[50:53], v[180:183], v[188:191], v[50:53]
	v_mfma_f32_16x16x32_bf16 v[38:41], v[172:175], v[196:199], v[38:41]
	v_mfma_f32_16x16x32_bf16 v[34:37], v[180:183], v[196:199], v[34:37]
	v_mfma_f32_16x16x32_bf16 v[22:25], v[172:175], v[204:207], v[22:25]
	v_mfma_f32_16x16x32_bf16 v[18:21], v[180:183], v[204:207], v[18:21]
	v_mfma_f32_16x16x32_bf16 v[6:9], v[172:175], v[212:215], v[6:9]
	v_mfma_f32_16x16x32_bf16 v[2:5], v[180:183], v[212:215], v[2:5]
	s_barrier
	s_add_u32 s22, s22, 0x10000
	s_addc_u32 s23, s23, 0
	s_cmp_ge_u32 s57, s44
	s_cbranch_scc0 .LBB0_1229
	s_and_b64 vcc, exec, s[6:7]
	s_cbranch_vccz .LBB0_1232
	s_barrier

; template <class Epi, class Sched, bool ABLK = false, bool ALIGN_EPI = true, bool SP2 = true, bool BBLK = true>
; __device__ __forceinline__ void gemm_phase(LAS unsigned char* lds, const Gemm g, const Sched& S, const Epi& E) {
;     ...
;             const char* a2 = last ? a_tile(nuA, ntbA) : a_tile(uA, tbA + t + 2); const char* b2 = last ? nB : cB + (size_t)(t + 2) * kstepB;
;             const char* a3 = last ? a_tile(nuA, ntbA + 1) : a_tile(uA, tbA + t + 3); const char* b3 = b2 + kstepB;
.Lksel_13:
	s_mov_b32 s25, s48
	s_mov_b32 s24, s47
	s_mov_b32 s27, s4
	s_mov_b32 s26, s5
	s_mov_b32 s29, s46
	s_mov_b32 s28, s19
	s_branch .Lksel_13_back

; #define PG8_STAGE(bufoff, gbase, voff) do { _Pragma("unroll") for (int _i = 0; _i < 2; ++_i) \
;         __builtin_amdgcn_global_load_lds((const unsigned*)((const char*)(gbase) + (voff)[_i]), (LAS unsigned*)(lds + (bufoff) + ldsw + _i * 8192), 16, 0, 0); } while (0)
; #define PG8_LDA(dst, b, h) do { _Pragma("unroll") for (int m = 0; m < 4; ++m) _Pragma("unroll") for (int k = 0; k < 2; ++k) dst[m][k] = *(const LAS bf16x8*)(lds + PG8_SA(b, h) + aoff + m * 2048 + k * 1024); } while (0)
; #define PG8_LDB(dst, b, h) do { _Pragma("unroll") for (int n = 0; n < 2; ++n) _Pragma("unroll") for (int k = 0; k < 2; ++k) dst[n][k] = *(const LAS bf16x8*)(lds + PG8_SB(b, h) + boff + n * 2048 + k * 1024); } while (0)
; #define PG8_WAIT_V(n) asm volatile("s_waitcnt vmcnt(" #n ")" ::: "memory")
; #define PG8_WAIT_L(n) asm volatile("s_waitcnt lgkmcnt(" #n ")" ::: "memory")
; template <class Epi, class Sched, bool ABLK = false, bool ALIGN_EPI = true, bool SP2 = true, bool BBLK = true>
; __device__ __forceinline__ void gemm_phase(LAS unsigned char* lds, const Gemm g, const Sched& S, const Epi& E) {
;     ...
;         const bool has_next = S.next(ui + 1, nxt);
;         const int nt = cur.nt;
;         const char* nuA = has_next ? a_unit(nxt) : uA; const int ntbA = has_next ? nxt.k0 / BK : tbA; const char* nB = has_next ? (const char*)g.Bt + (size_t)nxt.pn * tstepB + b_k0(nxt.k0) : cB;
;         for (int t = 0; t < nt; t += 2) {
;             const bool last = (t == nt - 2);
;             const char* a1 = a_tile(uA, tbA + t + 1);
;             const char* a2 = last ? a_tile(nuA, ntbA) : a_tile(uA, tbA + t + 2); const char* b2 = last ? nB : cB + (size_t)(t + 2) * kstepB;
;             const char* a3 = last ? a_tile(nuA, ntbA + 1) : a_tile(uA, tbA + t + 3); const char* b3 = b2 + kstepB;
;             if (last && has_next) S.a_ready(nxt);
;             if constexpr (SP2) {
;             PG8_LDB(B0, 0, 0); PG8_LDB(B1, 0, 1); PG8_SCHED; PG8_LDA(At, 0, 0); PG8_STAGE(PG8_SA(1, 1), a1 + hstepA, voffA);
;             PG8_WAIT_V(8); PG8_WAIT_L(0); PG8_BAR; PG8_MMA(0, 0, At, B0); PG8_MMA(0, 1, At, B1); PG8_BAR; PG8_SCHED;
;             PG8_LDA(At, 0, 1); PG8_STAGE(PG8_SB(0, 0), b2, voffB); PG8_STAGE(PG8_SB(0, 1), b2 + hstepB, voffB); PG8_STAGE(PG8_SA(0, 0), a2, voffA);
;             PG8_WAIT_V(8); PG8_WAIT_L(0); PG8_BAR; PG8_MMA(1, 0, At, B0); PG8_MMA(1, 1, At, B1); PG8_BAR; PG8_SCHED;
.LBB0_1354:
	s_ashr_i32 s21, s20, 31
	s_lshl_b64 s[4:5], s[20:21], 20
	s_add_u32 s24, s76, s4
	s_addc_u32 s25, s33, s5
	s_and_b64 s[4:5], s[26:27], exec
	s_cselect_b32 s4, s25, s37
	s_cselect_b32 s5, s24, s36
	s_ashr_i32 s23, s22, 31
	s_lshl_b64 s[28:29], s[22:23], 20
	s_add_u32 s28, s1, s28
	s_addc_u32 s29, s48, s29
	s_and_b64 s[42:43], s[26:27], exec
	s_cselect_b32 s21, s29, s41
	s_cselect_b32 s23, s28, s40
	s_add_u32 s56, s5, 0x80
	s_addc_u32 s57, s4, 0
	s_add_u32 s59, s40, 0x10000
	v_mov_b32_e32 v2, 0
	s_addc_u32 s64, s41, 0
	v_lshl_add_u64 v[148:149], s[36:37], 0, v[144:145]
	v_lshl_add_u64 v[150:151], s[36:37], 0, v[146:147]
	s_mov_b32 s65, -2
	s_mov_b64 s[40:41], 0
	ds_read_b128 v[152:155], v163
	ds_read_b128 v[156:159], v163 offset:1024
	ds_read_b128 v[166:169], v163 offset:2048
	ds_read_b128 v[170:173], v163 offset:3072
	ds_read_b128 v[174:177], v164
	ds_read_b128 v[178:181], v164 offset:1024
	ds_read_b128 v[182:185], v164 offset:2048
	ds_read_b128 v[186:189], v164 offset:3072
	s_add_u32 s42, s36, s40
	s_addc_u32 s43, s37, s41
	s_add_u32 s46, s42, 0x100
	s_addc_u32 s47, s43, 0
	s_add_u32 s42, s42, 0x180
	s_addc_u32 s43, s43, 0
	s_mov_b32 s45, s64
	s_mov_b32 s44, s59
	v_lshl_add_u64 v[222:223], v[148:149], 0, s[40:41]
	s_add_i32 m0, s31, 0xc000
	ds_read_b128 v[190:193], v165
	ds_read_b128 v[194:197], v165 offset:1024
	ds_read_b128 v[198:201], v165 offset:2048
	ds_read_b128 v[202:205], v165 offset:3072
	ds_read_b128 v[206:209], v165 offset:4096
	ds_read_b128 v[210:213], v165 offset:5120
	ds_read_b128 v[214:217], v165 offset:6144
	ds_read_b128 v[218:221], v165 offset:7168
	global_load_lds_dwordx4 v[222:223], off
	v_lshl_add_u64 v[222:223], v[150:151], 0, s[40:41]
	s_add_i32 m0, s31, 0xe000
	s_nop 0
	global_load_lds_dwordx4 v[222:223], off
	s_waitcnt vmcnt(8) lgkmcnt(0)
	s_barrier
	v_mfma_f32_16x16x32_bf16 v[126:129], v[152:155], v[190:193], 0
	v_mfma_f32_16x16x32_bf16 v[122:125], v[166:169], v[190:193], 0
	v_mfma_f32_16x16x32_bf16 v[110:113], v[152:155], v[198:201], 0
	v_mfma_f32_16x16x32_bf16 v[106:109], v[166:169], v[198:201], 0
	v_mfma_f32_16x16x32_bf16 v[94:97], v[152:155], v[206:209], 0
	v_mfma_f32_16x16x32_bf16 v[90:93], v[166:169], v[206:209], 0
	v_mfma_f32_16x16x32_bf16 v[78:81], v[152:155], v[214:217], 0
	v_mfma_f32_16x16x32_bf16 v[74:77], v[166:169], v[214:217], 0
	v_mfma_f32_16x16x32_bf16 v[126:129], v[156:159], v[194:197], v[126:129]
	v_mfma_f32_16x16x32_bf16 v[122:125], v[170:173], v[194:197], v[122:125]
	v_mfma_f32_16x16x32_bf16 v[110:113], v[156:159], v[202:205], v[110:113]
	v_mfma_f32_16x16x32_bf16 v[106:109], v[170:173], v[202:205], v[106:109]
	v_mfma_f32_16x16x32_bf16 v[94:97], v[156:159], v[210:213], v[94:97]
	v_mfma_f32_16x16x32_bf16 v[90:93], v[170:173], v[210:213], v[90:93]
	v_mfma_f32_16x16x32_bf16 v[78:81], v[156:159], v[218:221], v[78:81]
	v_mfma_f32_16x16x32_bf16 v[74:77], v[170:173], v[218:221], v[74:77]
	v_mfma_f32_16x16x32_bf16 v[118:121], v[174:177], v[190:193], 0
	v_mfma_f32_16x16x32_bf16 v[114:117], v[182:185], v[190:193], 0
	v_mfma_f32_16x16x32_bf16 v[102:105], v[174:177], v[198:201], 0
	v_mfma_f32_16x16x32_bf16 v[98:101], v[182:185], v[198:201], 0
	v_mfma_f32_16x16x32_bf16 v[86:89], v[174:177], v[206:209], 0
	v_mfma_f32_16x16x32_bf16 v[82:85], v[182:185], v[206:209], 0
	v_mfma_f32_16x16x32_bf16 v[70:73], v[174:177], v[214:217], 0
	v_mfma_f32_16x16x32_bf16 v[66:69], v[182:185], v[214:217], 0
	v_mfma_f32_16x16x32_bf16 v[118:121], v[178:181], v[194:197], v[118:121]
	v_mfma_f32_16x16x32_bf16 v[114:117], v[186:189], v[194:197], v[114:117]
	v_mfma_f32_16x16x32_bf16 v[102:105], v[178:181], v[202:205], v[102:105]
	v_mfma_f32_16x16x32_bf16 v[98:101], v[186:189], v[202:205], v[98:101]
	v_mfma_f32_16x16x32_bf16 v[86:89], v[178:181], v[210:213], v[86:89]
	v_mfma_f32_16x16x32_bf16 v[82:85], v[186:189], v[210:213], v[82:85]
	v_mfma_f32_16x16x32_bf16 v[70:73], v[178:181], v[218:221], v[70:73]
	v_mfma_f32_16x16x32_bf16 v[66:69], v[186:189], v[218:221], v[66:69]
	s_barrier
	s_add_i32 s66, s72, s49
	s_mov_b32 m0, s66
	ds_read_b128 v[190:193], v165 offset:16384
	ds_read_b128 v[194:197], v165 offset:17408
	ds_read_b128 v[198:201], v165 offset:18432
	ds_read_b128 v[202:205], v165 offset:19456
	ds_read_b128 v[206:209], v165 offset:20480
	ds_read_b128 v[210:213], v165 offset:21504
	ds_read_b128 v[214:217], v165 offset:22528
	ds_read_b128 v[218:221], v165 offset:23552
	global_load_lds_dwordx4 v134, s[44:45]
	s_add_i32 m0, s66, 0x2000
	s_add_u32 s66, s44, 0x4000
	s_addc_u32 s67, s45, 0
	s_add_i32 s75, s73, s49
	global_load_lds_dwordx4 v130, s[44:45]
	s_mov_b32 m0, s75
	s_nop 0
	global_load_lds_dwordx4 v134, s[66:67]
	s_add_i32 m0, s75, 0x2000
	s_nop 0
	global_load_lds_dwordx4 v130, s[66:67]
	s_mov_b32 m0, s31
	s_nop 0
	global_load_lds_dwordx4 v136, s[46:47]
	s_mov_b32 m0, s35
	s_nop 0
	global_load_lds_dwordx4 v132, s[46:47]
	s_waitcnt vmcnt(8) lgkmcnt(0)
	s_barrier
; #define PG8_STAGE(bufoff, gbase, voff) do { _Pragma("unroll") for (int _i = 0; _i < 2; ++_i) \
;         __builtin_amdgcn_global_load_lds((const unsigned*)((const char*)(gbase) + (voff)[_i]), (LAS unsigned*)(lds + (bufoff) + ldsw + _i * 8192), 16, 0, 0); } while (0)
; #define PG8_LDA(dst, b, h) do { _Pragma("unroll") for (int m = 0; m < 4; ++m) _Pragma("unroll") for (int k = 0; k < 2; ++k) dst[m][k] = *(const LAS bf16x8*)(lds + PG8_SA(b, h) + aoff + m * 2048 + k * 1024); } while (0)
; #define PG8_LDB(dst, b, h) do { _Pragma("unroll") for (int n = 0; n < 2; ++n) _Pragma("unroll") for (int k = 0; k < 2; ++k) dst[n][k] = *(const LAS bf16x8*)(lds + PG8_SB(b, h) + boff + n * 2048 + k * 1024); } while (0)
; #define PG8_MMA(ai, bj, At, Bt) do { __builtin_amdgcn_s_setprio(1); _Pragma("unroll") for (int m = 0; m < 4; ++m) _Pragma("unroll") for (int n = 0; n < 2; ++n) _Pragma("unroll") for (int k = 0; k < 2; ++k) \
;         acc[ai][bj][m][n] = __builtin_amdgcn_mfma_f32_16x16x32_bf16(Bt[n][k], At[m][k], acc[ai][bj][m][n], 0, 0, 0); __builtin_amdgcn_s_setprio(0); } while (0)
; #define PG8_WAIT_V(n) asm volatile("s_waitcnt vmcnt(" #n ")" ::: "memory")
; #define PG8_WAIT_L(n) asm volatile("s_waitcnt lgkmcnt(" #n ")" ::: "memory")
; #define PG8_BAR __builtin_amdgcn_s_barrier()
; #define PG8_SCHED __builtin_amdgcn_sched_barrier(0)
; template <class Epi, class Sched, bool ABLK = false, bool ALIGN_EPI = true, bool SP2 = true, bool BBLK = true>
; __device__ __forceinline__ void gemm_phase(LAS unsigned char* lds, const Gemm g, const Sched& S, const Epi& E) {
;     ...
;             PG8_WAIT_V(8); PG8_WAIT_L(0); PG8_BAR; PG8_MMA(1, 0, At, B0); PG8_MMA(1, 1, At, B1); PG8_BAR; PG8_SCHED;
;             PG8_LDB(B0, 1, 0); PG8_LDB(B1, 1, 1); PG8_SCHED; PG8_LDA(At, 1, 0); PG8_STAGE(PG8_SA(0, 1), a2 + hstepA, voffA);
;             PG8_WAIT_V(8); PG8_WAIT_L(0); PG8_BAR; PG8_MMA(0, 0, At, B0); PG8_MMA(0, 1, At, B1); PG8_BAR; PG8_SCHED;
	v_mfma_f32_16x16x32_bf16 v[62:65], v[152:155], v[190:193], 0
	v_mfma_f32_16x16x32_bf16 v[58:61], v[166:169], v[190:193], 0
	v_mfma_f32_16x16x32_bf16 v[46:49], v[152:155], v[198:201], 0
	v_mfma_f32_16x16x32_bf16 v[42:45], v[166:169], v[198:201], 0
	v_mfma_f32_16x16x32_bf16 v[30:33], v[152:155], v[206:209], 0
	v_mfma_f32_16x16x32_bf16 v[26:29], v[166:169], v[206:209], 0
	v_mfma_f32_16x16x32_bf16 v[14:17], v[152:155], v[214:217], 0
	v_mfma_f32_16x16x32_bf16 v[10:13], v[166:169], v[214:217], 0
	v_mfma_f32_16x16x32_bf16 v[62:65], v[156:159], v[194:197], v[62:65]
	v_mfma_f32_16x16x32_bf16 v[58:61], v[170:173], v[194:197], v[58:61]
	v_mfma_f32_16x16x32_bf16 v[46:49], v[156:159], v[202:205], v[46:49]
	v_mfma_f32_16x16x32_bf16 v[42:45], v[170:173], v[202:205], v[42:45]
	v_mfma_f32_16x16x32_bf16 v[30:33], v[156:159], v[210:213], v[30:33]
	v_mfma_f32_16x16x32_bf16 v[26:29], v[170:173], v[210:213], v[26:29]
	v_mfma_f32_16x16x32_bf16 v[14:17], v[156:159], v[218:221], v[14:17]
	v_mfma_f32_16x16x32_bf16 v[10:13], v[170:173], v[218:221], v[10:13]
	v_mfma_f32_16x16x32_bf16 v[54:57], v[174:177], v[190:193], 0
	v_mfma_f32_16x16x32_bf16 v[50:53], v[182:185], v[190:193], 0
	v_mfma_f32_16x16x32_bf16 v[38:41], v[174:177], v[198:201], 0
	v_mfma_f32_16x16x32_bf16 v[34:37], v[182:185], v[198:201], 0
	v_mfma_f32_16x16x32_bf16 v[22:25], v[174:177], v[206:209], 0
	v_mfma_f32_16x16x32_bf16 v[18:21], v[182:185], v[206:209], 0
	v_mfma_f32_16x16x32_bf16 v[6:9], v[174:177], v[214:217], 0
	v_mfma_f32_16x16x32_bf16 v[2:5], v[182:185], v[214:217], 0
	v_mfma_f32_16x16x32_bf16 v[54:57], v[178:181], v[194:197], v[54:57]
	v_mfma_f32_16x16x32_bf16 v[50:53], v[186:189], v[194:197], v[50:53]
	v_mfma_f32_16x16x32_bf16 v[38:41], v[178:181], v[202:205], v[38:41]
	v_mfma_f32_16x16x32_bf16 v[34:37], v[186:189], v[202:205], v[34:37]
	v_mfma_f32_16x16x32_bf16 v[22:25], v[178:181], v[210:213], v[22:25]
	v_mfma_f32_16x16x32_bf16 v[18:21], v[186:189], v[210:213], v[18:21]
	v_mfma_f32_16x16x32_bf16 v[6:9], v[178:181], v[218:221], v[6:9]
	v_mfma_f32_16x16x32_bf16 v[2:5], v[186:189], v[218:221], v[2:5]
	s_barrier
	v_add_u32_e32 v138, s60, v161
	ds_read_b128 v[152:155], v138
	ds_read_b128 v[156:159], v138 offset:1024
	ds_read_b128 v[166:169], v138 offset:2048
	ds_read_b128 v[170:173], v138 offset:3072
	v_add_u32_e32 v138, s61, v161
	ds_read_b128 v[174:177], v138
	ds_read_b128 v[178:181], v138 offset:1024
	ds_read_b128 v[182:185], v138 offset:2048
	ds_read_b128 v[186:189], v138 offset:3072
	s_add_u32 s46, s46, 0x80000
	s_addc_u32 s47, s47, 0
	s_mov_b32 m0, s50
	ds_read_b128 v[190:193], v165 offset:32768
	ds_read_b128 v[194:197], v165 offset:33792
	ds_read_b128 v[198:201], v165 offset:34816
	ds_read_b128 v[202:205], v165 offset:35840
	ds_read_b128 v[206:209], v165 offset:36864
	ds_read_b128 v[210:213], v165 offset:37888
	ds_read_b128 v[214:217], v165 offset:38912
	ds_read_b128 v[218:221], v165 offset:39936
	global_load_lds_dwordx4 v136, s[46:47]
	s_mov_b32 m0, s51
	s_nop 0
	global_load_lds_dwordx4 v132, s[46:47]
	s_waitcnt vmcnt(8) lgkmcnt(0)
	s_barrier
	v_mfma_f32_16x16x32_bf16 v[126:129], v[152:155], v[190:193], v[126:129]
	v_mfma_f32_16x16x32_bf16 v[122:125], v[166:169], v[190:193], v[122:125]
	v_mfma_f32_16x16x32_bf16 v[110:113], v[152:155], v[198:201], v[110:113]
	v_mfma_f32_16x16x32_bf16 v[106:109], v[166:169], v[198:201], v[106:109]
	v_mfma_f32_16x16x32_bf16 v[94:97], v[152:155], v[206:209], v[94:97]
	v_mfma_f32_16x16x32_bf16 v[90:93], v[166:169], v[206:209], v[90:93]
	v_mfma_f32_16x16x32_bf16 v[78:81], v[152:155], v[214:217], v[78:81]
	v_mfma_f32_16x16x32_bf16 v[74:77], v[166:169], v[214:217], v[74:77]
	v_mfma_f32_16x16x32_bf16 v[126:129], v[156:159], v[194:197], v[126:129]
	v_mfma_f32_16x16x32_bf16 v[122:125], v[170:173], v[194:197], v[122:125]
	v_mfma_f32_16x16x32_bf16 v[110:113], v[156:159], v[202:205], v[110:113]
	v_mfma_f32_16x16x32_bf16 v[106:109], v[170:173], v[202:205], v[106:109]
	v_mfma_f32_16x16x32_bf16 v[94:97], v[156:159], v[210:213], v[94:97]
	v_mfma_f32_16x16x32_bf16 v[90:93], v[170:173], v[210:213], v[90:93]
	v_mfma_f32_16x16x32_bf16 v[78:81], v[156:159], v[218:221], v[78:81]
	v_mfma_f32_16x16x32_bf16 v[74:77], v[170:173], v[218:221], v[74:77]
	v_mfma_f32_16x16x32_bf16 v[118:121], v[174:177], v[190:193], v[118:121]
	v_mfma_f32_16x16x32_bf16 v[114:117], v[182:185], v[190:193], v[114:117]
	v_mfma_f32_16x16x32_bf16 v[102:105], v[174:177], v[198:201], v[102:105]
	v_mfma_f32_16x16x32_bf16 v[98:101], v[182:185], v[198:201], v[98:101]
	v_mfma_f32_16x16x32_bf16 v[86:89], v[174:177], v[206:209], v[86:89]
	v_mfma_f32_16x16x32_bf16 v[82:85], v[182:185], v[206:209], v[82:85]
	v_mfma_f32_16x16x32_bf16 v[70:73], v[174:177], v[214:217], v[70:73]
	v_mfma_f32_16x16x32_bf16 v[66:69], v[182:185], v[214:217], v[66:69]
	v_mfma_f32_16x16x32_bf16 v[118:121], v[178:181], v[194:197], v[118:121]
	v_mfma_f32_16x16x32_bf16 v[114:117], v[186:189], v[194:197], v[114:117]
	v_mfma_f32_16x16x32_bf16 v[102:105], v[178:181], v[202:205], v[102:105]
	v_mfma_f32_16x16x32_bf16 v[98:101], v[186:189], v[202:205], v[98:101]
	v_mfma_f32_16x16x32_bf16 v[86:89], v[178:181], v[210:213], v[86:89]
	v_mfma_f32_16x16x32_bf16 v[82:85], v[186:189], v[210:213], v[82:85]
	v_mfma_f32_16x16x32_bf16 v[70:73], v[178:181], v[218:221], v[70:73]
	v_mfma_f32_16x16x32_bf16 v[66:69], v[186:189], v[218:221], v[66:69]
	s_barrier
; #define PG8_STAGE(bufoff, gbase, voff) do { _Pragma("unroll") for (int _i = 0; _i < 2; ++_i) \
;         __builtin_amdgcn_global_load_lds((const unsigned*)((const char*)(gbase) + (voff)[_i]), (LAS unsigned*)(lds + (bufoff) + ldsw + _i * 8192), 16, 0, 0); } while (0)
; #define PG8_LDA(dst, b, h) do { _Pragma("unroll") for (int m = 0; m < 4; ++m) _Pragma("unroll") for (int k = 0; k < 2; ++k) dst[m][k] = *(const LAS bf16x8*)(lds + PG8_SA(b, h) + aoff + m * 2048 + k * 1024); } while (0)
; #define PG8_WAIT_V(n) asm volatile("s_waitcnt vmcnt(" #n ")" ::: "memory")
; #define PG8_WAIT_L(n) asm volatile("s_waitcnt lgkmcnt(" #n ")" ::: "memory")
; template <class Epi, class Sched, bool ABLK = false, bool ALIGN_EPI = true, bool SP2 = true, bool BBLK = true>
; __device__ __forceinline__ void gemm_phase(LAS unsigned char* lds, const Gemm g, const Sched& S, const Epi& E) {
;     ...
;         for (int t = 0; t < nt; t += 2) {
;             const bool last = (t == nt - 2);
;             const char* a1 = a_tile(uA, tbA + t + 1);
;             const char* a2 = last ? a_tile(nuA, ntbA) : a_tile(uA, tbA + t + 2); const char* b2 = last ? nB : cB + (size_t)(t + 2) * kstepB;
;             const char* a3 = last ? a_tile(nuA, ntbA + 1) : a_tile(uA, tbA + t + 3); const char* b3 = b2 + kstepB;
;             if (last && has_next) S.a_ready(nxt);
;             if constexpr (SP2) {
;             PG8_LDB(B0, 0, 0); PG8_LDB(B1, 0, 1); PG8_SCHED; PG8_LDA(At, 0, 0); PG8_STAGE(PG8_SA(1, 1), a1 + hstepA, voffA);
;             PG8_WAIT_V(8); PG8_WAIT_L(0); PG8_BAR; PG8_MMA(0, 0, At, B0); PG8_MMA(0, 1, At, B1); PG8_BAR; PG8_SCHED;
;             PG8_LDA(At, 0, 1); PG8_STAGE(PG8_SB(0, 0), b2, voffB); PG8_STAGE(PG8_SB(0, 1), b2 + hstepB, voffB); PG8_STAGE(PG8_SA(0, 0), a2, voffA);
;             PG8_WAIT_V(8); PG8_WAIT_L(0); PG8_BAR; PG8_MMA(1, 0, At, B0); PG8_MMA(1, 1, At, B1); PG8_BAR; PG8_SCHED;
;             PG8_LDB(B0, 1, 0); PG8_LDB(B1, 1, 1); PG8_SCHED; PG8_LDA(At, 1, 0); PG8_STAGE(PG8_SA(0, 1), a2 + hstepA, voffA);
;             PG8_WAIT_V(8); PG8_WAIT_L(0); PG8_BAR; PG8_MMA(0, 0, At, B0); PG8_MMA(0, 1, At, B1); PG8_BAR; PG8_SCHED;
;             PG8_LDA(At, 1, 1); PG8_STAGE(PG8_SB(1, 0), b3, voffB); PG8_STAGE(PG8_SB(1, 1), b3 + hstepB, voffB); PG8_STAGE(PG8_SA(1, 0), a3, voffA);
;             PG8_WAIT_V(8); PG8_WAIT_L(0); PG8_BAR; PG8_MMA(1, 0, At, B0); PG8_MMA(1, 1, At, B1); PG8_BAR; PG8_SCHED;
	s_add_u32 s46, s44, 0x8000
	s_addc_u32 s47, s45, 0
	s_add_i32 s66, s60, s49
	s_mov_b32 m0, s66
	ds_read_b128 v[190:193], v165 offset:49152
	ds_read_b128 v[194:197], v165 offset:50176
	ds_read_b128 v[198:201], v165 offset:51200
	ds_read_b128 v[202:205], v165 offset:52224
	ds_read_b128 v[206:209], v165 offset:53248
	ds_read_b128 v[210:213], v165 offset:54272
	ds_read_b128 v[214:217], v165 offset:55296
	ds_read_b128 v[218:221], v165 offset:56320
	global_load_lds_dwordx4 v134, s[46:47]
	s_add_i32 m0, s66, 0x2000
	s_add_u32 s44, s44, 0xc000
	v_lshl_add_u64 v[222:223], s[46:47], 0, v[130:131]
	s_addc_u32 s45, s45, 0
	s_add_i32 s46, s61, s49
	global_load_lds_dwordx4 v[222:223], off
	s_mov_b32 m0, s46
	s_nop 0
	global_load_lds_dwordx4 v134, s[44:45]
	s_add_i32 m0, s46, 0x2000
	s_nop 0
	global_load_lds_dwordx4 v130, s[44:45]
	s_mov_b32 m0, s54
	s_nop 0
	global_load_lds_dwordx4 v136, s[42:43]
	s_mov_b32 m0, s55
	s_nop 0
	global_load_lds_dwordx4 v132, s[42:43]
	s_waitcnt vmcnt(8) lgkmcnt(0)
	s_barrier
	v_mfma_f32_16x16x32_bf16 v[62:65], v[152:155], v[190:193], v[62:65]
	v_mfma_f32_16x16x32_bf16 v[58:61], v[166:169], v[190:193], v[58:61]
	v_mfma_f32_16x16x32_bf16 v[46:49], v[152:155], v[198:201], v[46:49]
	v_mfma_f32_16x16x32_bf16 v[42:45], v[166:169], v[198:201], v[42:45]
	v_mfma_f32_16x16x32_bf16 v[30:33], v[152:155], v[206:209], v[30:33]
	v_mfma_f32_16x16x32_bf16 v[26:29], v[166:169], v[206:209], v[26:29]
	v_mfma_f32_16x16x32_bf16 v[14:17], v[152:155], v[214:217], v[14:17]
	v_mfma_f32_16x16x32_bf16 v[10:13], v[166:169], v[214:217], v[10:13]
	v_mfma_f32_16x16x32_bf16 v[62:65], v[156:159], v[194:197], v[62:65]
	v_mfma_f32_16x16x32_bf16 v[58:61], v[170:173], v[194:197], v[58:61]
	v_mfma_f32_16x16x32_bf16 v[46:49], v[156:159], v[202:205], v[46:49]
	v_mfma_f32_16x16x32_bf16 v[42:45], v[170:173], v[202:205], v[42:45]
	v_mfma_f32_16x16x32_bf16 v[30:33], v[156:159], v[210:213], v[30:33]
	v_mfma_f32_16x16x32_bf16 v[26:29], v[170:173], v[210:213], v[26:29]
	v_mfma_f32_16x16x32_bf16 v[14:17], v[156:159], v[218:221], v[14:17]
	v_mfma_f32_16x16x32_bf16 v[10:13], v[170:173], v[218:221], v[10:13]
	v_mfma_f32_16x16x32_bf16 v[54:57], v[174:177], v[190:193], v[54:57]
	v_mfma_f32_16x16x32_bf16 v[50:53], v[182:185], v[190:193], v[50:53]
	v_mfma_f32_16x16x32_bf16 v[38:41], v[174:177], v[198:201], v[38:41]
	v_mfma_f32_16x16x32_bf16 v[34:37], v[182:185], v[198:201], v[34:37]
	v_mfma_f32_16x16x32_bf16 v[22:25], v[174:177], v[206:209], v[22:25]
	v_mfma_f32_16x16x32_bf16 v[18:21], v[182:185], v[206:209], v[18:21]
	v_mfma_f32_16x16x32_bf16 v[6:9], v[174:177], v[214:217], v[6:9]
	v_mfma_f32_16x16x32_bf16 v[2:5], v[182:185], v[214:217], v[2:5]
	v_mfma_f32_16x16x32_bf16 v[54:57], v[178:181], v[194:197], v[54:57]
	v_mfma_f32_16x16x32_bf16 v[50:53], v[186:189], v[194:197], v[50:53]
	v_mfma_f32_16x16x32_bf16 v[38:41], v[178:181], v[202:205], v[38:41]
	v_mfma_f32_16x16x32_bf16 v[34:37], v[186:189], v[202:205], v[34:37]
	v_mfma_f32_16x16x32_bf16 v[22:25], v[178:181], v[210:213], v[22:25]
	v_mfma_f32_16x16x32_bf16 v[18:21], v[186:189], v[210:213], v[18:21]
	v_mfma_f32_16x16x32_bf16 v[6:9], v[178:181], v[218:221], v[6:9]
	v_mfma_f32_16x16x32_bf16 v[2:5], v[186:189], v[218:221], v[2:5]
	s_barrier
	s_add_i32 s65, s65, 2
	s_add_u32 s40, s40, 0x100
	s_addc_u32 s41, s41, 0
	s_add_u32 s59, s59, 0x10000
	s_addc_u32 s64, s64, 0
	s_cmp_gt_u32 s65, 29
.LBB0_1355:
	ds_read_b128 v[152:155], v163
	ds_read_b128 v[156:159], v163 offset:1024
	ds_read_b128 v[166:169], v163 offset:2048
	ds_read_b128 v[170:173], v163 offset:3072
	ds_read_b128 v[174:177], v164
	ds_read_b128 v[178:181], v164 offset:1024
	ds_read_b128 v[182:185], v164 offset:2048
	ds_read_b128 v[186:189], v164 offset:3072
	s_add_u32 s42, s36, s40
	s_addc_u32 s43, s37, s41
	s_add_u32 s46, s42, 0x100
	s_addc_u32 s47, s43, 0
	s_add_u32 s42, s42, 0x180
	s_addc_u32 s43, s43, 0
	s_cmpk_eq_i32 s40, 0xf00
	s_cbranch_scc1 .Lksel_15
	s_mov_b32 s45, s64
	s_mov_b32 s44, s59
.Lksel_15_back:
	v_lshl_add_u64 v[222:223], v[148:149], 0, s[40:41]
	s_add_i32 m0, s31, 0xc000
	ds_read_b128 v[190:193], v165
	ds_read_b128 v[194:197], v165 offset:1024
	ds_read_b128 v[198:201], v165 offset:2048
	ds_read_b128 v[202:205], v165 offset:3072
	ds_read_b128 v[206:209], v165 offset:4096
	ds_read_b128 v[210:213], v165 offset:5120
	ds_read_b128 v[214:217], v165 offset:6144
	ds_read_b128 v[218:221], v165 offset:7168
	global_load_lds_dwordx4 v[222:223], off
	v_lshl_add_u64 v[222:223], v[150:151], 0, s[40:41]
	s_add_i32 m0, s31, 0xe000
	s_nop 0
	global_load_lds_dwordx4 v[222:223], off
	s_waitcnt vmcnt(8) lgkmcnt(0)
	s_barrier
; #define PG8_STAGE(bufoff, gbase, voff) do { _Pragma("unroll") for (int _i = 0; _i < 2; ++_i) \
;         __builtin_amdgcn_global_load_lds((const unsigned*)((const char*)(gbase) + (voff)[_i]), (LAS unsigned*)(lds + (bufoff) + ldsw + _i * 8192), 16, 0, 0); } while (0)
; #define PG8_LDA(dst, b, h) do { _Pragma("unroll") for (int m = 0; m < 4; ++m) _Pragma("unroll") for (int k = 0; k < 2; ++k) dst[m][k] = *(const LAS bf16x8*)(lds + PG8_SA(b, h) + aoff + m * 2048 + k * 1024); } while (0)
; #define PG8_LDB(dst, b, h) do { _Pragma("unroll") for (int n = 0; n < 2; ++n) _Pragma("unroll") for (int k = 0; k < 2; ++k) dst[n][k] = *(const LAS bf16x8*)(lds + PG8_SB(b, h) + boff + n * 2048 + k * 1024); } while (0)
; #define PG8_MMA(ai, bj, At, Bt) do { __builtin_amdgcn_s_setprio(1); _Pragma("unroll") for (int m = 0; m < 4; ++m) _Pragma("unroll") for (int n = 0; n < 2; ++n) _Pragma("unroll") for (int k = 0; k < 2; ++k) \
;         acc[ai][bj][m][n] = __builtin_amdgcn_mfma_f32_16x16x32_bf16(Bt[n][k], At[m][k], acc[ai][bj][m][n], 0, 0, 0); __builtin_amdgcn_s_setprio(0); } while (0)
; #define PG8_WAIT_V(n) asm volatile("s_waitcnt vmcnt(" #n ")" ::: "memory")
; #define PG8_WAIT_L(n) asm volatile("s_waitcnt lgkmcnt(" #n ")" ::: "memory")
; #define PG8_BAR __builtin_amdgcn_s_barrier()
; #define PG8_SCHED __builtin_amdgcn_sched_barrier(0)
; template <class Epi, class Sched, bool ABLK = false, bool ALIGN_EPI = true, bool SP2 = true, bool BBLK = true>
; __device__ __forceinline__ void gemm_phase(LAS unsigned char* lds, const Gemm g, const Sched& S, const Epi& E) {
;     ...
;             PG8_LDB(B0, 0, 0); PG8_LDB(B1, 0, 1); PG8_SCHED; PG8_LDA(At, 0, 0); PG8_STAGE(PG8_SA(1, 1), a1 + hstepA, voffA);
;             PG8_WAIT_V(8); PG8_WAIT_L(0); PG8_BAR; PG8_MMA(0, 0, At, B0); PG8_MMA(0, 1, At, B1); PG8_BAR; PG8_SCHED;
;             PG8_LDA(At, 0, 1); PG8_STAGE(PG8_SB(0, 0), b2, voffB); PG8_STAGE(PG8_SB(0, 1), b2 + hstepB, voffB); PG8_STAGE(PG8_SA(0, 0), a2, voffA);
;             PG8_WAIT_V(8); PG8_WAIT_L(0); PG8_BAR; PG8_MMA(1, 0, At, B0); PG8_MMA(1, 1, At, B1); PG8_BAR; PG8_SCHED;
;             PG8_LDB(B0, 1, 0); PG8_LDB(B1, 1, 1); PG8_SCHED; PG8_LDA(At, 1, 0); PG8_STAGE(PG8_SA(0, 1), a2 + hstepA, voffA);
;             PG8_WAIT_V(8); PG8_WAIT_L(0); PG8_BAR; PG8_MMA(0, 0, At, B0); PG8_MMA(0, 1, At, B1); PG8_BAR; PG8_SCHED;
	v_mfma_f32_16x16x32_bf16 v[126:129], v[152:155], v[190:193], v[126:129]
	v_mfma_f32_16x16x32_bf16 v[122:125], v[166:169], v[190:193], v[122:125]
	v_mfma_f32_16x16x32_bf16 v[110:113], v[152:155], v[198:201], v[110:113]
	v_mfma_f32_16x16x32_bf16 v[106:109], v[166:169], v[198:201], v[106:109]
	v_mfma_f32_16x16x32_bf16 v[94:97], v[152:155], v[206:209], v[94:97]
	v_mfma_f32_16x16x32_bf16 v[90:93], v[166:169], v[206:209], v[90:93]
	v_mfma_f32_16x16x32_bf16 v[78:81], v[152:155], v[214:217], v[78:81]
	v_mfma_f32_16x16x32_bf16 v[74:77], v[166:169], v[214:217], v[74:77]
	v_mfma_f32_16x16x32_bf16 v[126:129], v[156:159], v[194:197], v[126:129]
	v_mfma_f32_16x16x32_bf16 v[122:125], v[170:173], v[194:197], v[122:125]
	v_mfma_f32_16x16x32_bf16 v[110:113], v[156:159], v[202:205], v[110:113]
	v_mfma_f32_16x16x32_bf16 v[106:109], v[170:173], v[202:205], v[106:109]
	v_mfma_f32_16x16x32_bf16 v[94:97], v[156:159], v[210:213], v[94:97]
	v_mfma_f32_16x16x32_bf16 v[90:93], v[170:173], v[210:213], v[90:93]
	v_mfma_f32_16x16x32_bf16 v[78:81], v[156:159], v[218:221], v[78:81]
	v_mfma_f32_16x16x32_bf16 v[74:77], v[170:173], v[218:221], v[74:77]
	v_mfma_f32_16x16x32_bf16 v[118:121], v[174:177], v[190:193], v[118:121]
	v_mfma_f32_16x16x32_bf16 v[114:117], v[182:185], v[190:193], v[114:117]
	v_mfma_f32_16x16x32_bf16 v[102:105], v[174:177], v[198:201], v[102:105]
	v_mfma_f32_16x16x32_bf16 v[98:101], v[182:185], v[198:201], v[98:101]
	v_mfma_f32_16x16x32_bf16 v[86:89], v[174:177], v[206:209], v[86:89]
	v_mfma_f32_16x16x32_bf16 v[82:85], v[182:185], v[206:209], v[82:85]
	v_mfma_f32_16x16x32_bf16 v[70:73], v[174:177], v[214:217], v[70:73]
	v_mfma_f32_16x16x32_bf16 v[66:69], v[182:185], v[214:217], v[66:69]
	v_mfma_f32_16x16x32_bf16 v[118:121], v[178:181], v[194:197], v[118:121]
	v_mfma_f32_16x16x32_bf16 v[114:117], v[186:189], v[194:197], v[114:117]
	v_mfma_f32_16x16x32_bf16 v[102:105], v[178:181], v[202:205], v[102:105]
	v_mfma_f32_16x16x32_bf16 v[98:101], v[186:189], v[202:205], v[98:101]
	v_mfma_f32_16x16x32_bf16 v[86:89], v[178:181], v[210:213], v[86:89]
	v_mfma_f32_16x16x32_bf16 v[82:85], v[186:189], v[210:213], v[82:85]
	v_mfma_f32_16x16x32_bf16 v[70:73], v[178:181], v[218:221], v[70:73]
	v_mfma_f32_16x16x32_bf16 v[66:69], v[186:189], v[218:221], v[66:69]
	s_barrier
	s_add_i32 s66, s72, s49
	s_mov_b32 m0, s66
	ds_read_b128 v[190:193], v165 offset:16384
	ds_read_b128 v[194:197], v165 offset:17408
	ds_read_b128 v[198:201], v165 offset:18432
	ds_read_b128 v[202:205], v165 offset:19456
	ds_read_b128 v[206:209], v165 offset:20480
	ds_read_b128 v[210:213], v165 offset:21504
	ds_read_b128 v[214:217], v165 offset:22528
	ds_read_b128 v[218:221], v165 offset:23552
	global_load_lds_dwordx4 v134, s[44:45]
	s_add_i32 m0, s66, 0x2000
	s_add_u32 s66, s44, 0x4000
	s_addc_u32 s67, s45, 0
	s_add_i32 s75, s73, s49
	global_load_lds_dwordx4 v130, s[44:45]
	s_mov_b32 m0, s75
	s_nop 0
	global_load_lds_dwordx4 v134, s[66:67]
	s_add_i32 m0, s75, 0x2000
	s_nop 0
	global_load_lds_dwordx4 v130, s[66:67]
	s_mov_b32 m0, s31
	s_nop 0
	global_load_lds_dwordx4 v136, s[46:47]
	s_mov_b32 m0, s35
	s_nop 0
	global_load_lds_dwordx4 v132, s[46:47]
	s_waitcnt vmcnt(8) lgkmcnt(0)
	s_barrier
	v_mfma_f32_16x16x32_bf16 v[62:65], v[152:155], v[190:193], v[62:65]
	v_mfma_f32_16x16x32_bf16 v[58:61], v[166:169], v[190:193], v[58:61]
	v_mfma_f32_16x16x32_bf16 v[46:49], v[152:155], v[198:201], v[46:49]
	v_mfma_f32_16x16x32_bf16 v[42:45], v[166:169], v[198:201], v[42:45]
	v_mfma_f32_16x16x32_bf16 v[30:33], v[152:155], v[206:209], v[30:33]
	v_mfma_f32_16x16x32_bf16 v[26:29], v[166:169], v[206:209], v[26:29]
	v_mfma_f32_16x16x32_bf16 v[14:17], v[152:155], v[214:217], v[14:17]
	v_mfma_f32_16x16x32_bf16 v[10:13], v[166:169], v[214:217], v[10:13]
	v_mfma_f32_16x16x32_bf16 v[62:65], v[156:159], v[194:197], v[62:65]
	v_mfma_f32_16x16x32_bf16 v[58:61], v[170:173], v[194:197], v[58:61]
	v_mfma_f32_16x16x32_bf16 v[46:49], v[156:159], v[202:205], v[46:49]
	v_mfma_f32_16x16x32_bf16 v[42:45], v[170:173], v[202:205], v[42:45]
	v_mfma_f32_16x16x32_bf16 v[30:33], v[156:159], v[210:213], v[30:33]
	v_mfma_f32_16x16x32_bf16 v[26:29], v[170:173], v[210:213], v[26:29]
	v_mfma_f32_16x16x32_bf16 v[14:17], v[156:159], v[218:221], v[14:17]
	v_mfma_f32_16x16x32_bf16 v[10:13], v[170:173], v[218:221], v[10:13]
	v_mfma_f32_16x16x32_bf16 v[54:57], v[174:177], v[190:193], v[54:57]
	v_mfma_f32_16x16x32_bf16 v[50:53], v[182:185], v[190:193], v[50:53]
	v_mfma_f32_16x16x32_bf16 v[38:41], v[174:177], v[198:201], v[38:41]
	v_mfma_f32_16x16x32_bf16 v[34:37], v[182:185], v[198:201], v[34:37]
	v_mfma_f32_16x16x32_bf16 v[22:25], v[174:177], v[206:209], v[22:25]
	v_mfma_f32_16x16x32_bf16 v[18:21], v[182:185], v[206:209], v[18:21]
	v_mfma_f32_16x16x32_bf16 v[6:9], v[174:177], v[214:217], v[6:9]
	v_mfma_f32_16x16x32_bf16 v[2:5], v[182:185], v[214:217], v[2:5]
	v_mfma_f32_16x16x32_bf16 v[54:57], v[178:181], v[194:197], v[54:57]
	v_mfma_f32_16x16x32_bf16 v[50:53], v[186:189], v[194:197], v[50:53]
	v_mfma_f32_16x16x32_bf16 v[38:41], v[178:181], v[202:205], v[38:41]
	v_mfma_f32_16x16x32_bf16 v[34:37], v[186:189], v[202:205], v[34:37]
	v_mfma_f32_16x16x32_bf16 v[22:25], v[178:181], v[210:213], v[22:25]
	v_mfma_f32_16x16x32_bf16 v[18:21], v[186:189], v[210:213], v[18:21]
	v_mfma_f32_16x16x32_bf16 v[6:9], v[178:181], v[218:221], v[6:9]
	v_mfma_f32_16x16x32_bf16 v[2:5], v[186:189], v[218:221], v[2:5]
	s_barrier
; #define PG8_STAGE(bufoff, gbase, voff) do { _Pragma("unroll") for (int _i = 0; _i < 2; ++_i) \
;         __builtin_amdgcn_global_load_lds((const unsigned*)((const char*)(gbase) + (voff)[_i]), (LAS unsigned*)(lds + (bufoff) + ldsw + _i * 8192), 16, 0, 0); } while (0)
; #define PG8_LDA(dst, b, h) do { _Pragma("unroll") for (int m = 0; m < 4; ++m) _Pragma("unroll") for (int k = 0; k < 2; ++k) dst[m][k] = *(const LAS bf16x8*)(lds + PG8_SA(b, h) + aoff + m * 2048 + k * 1024); } while (0)
; #define PG8_LDB(dst, b, h) do { _Pragma("unroll") for (int n = 0; n < 2; ++n) _Pragma("unroll") for (int k = 0; k < 2; ++k) dst[n][k] = *(const LAS bf16x8*)(lds + PG8_SB(b, h) + boff + n * 2048 + k * 1024); } while (0)
; #define PG8_MMA(ai, bj, At, Bt) do { __builtin_amdgcn_s_setprio(1); _Pragma("unroll") for (int m = 0; m < 4; ++m) _Pragma("unroll") for (int n = 0; n < 2; ++n) _Pragma("unroll") for (int k = 0; k < 2; ++k) \
;         acc[ai][bj][m][n] = __builtin_amdgcn_mfma_f32_16x16x32_bf16(Bt[n][k], At[m][k], acc[ai][bj][m][n], 0, 0, 0); __builtin_amdgcn_s_setprio(0); } while (0)
; #define PG8_WAIT_V(n) asm volatile("s_waitcnt vmcnt(" #n ")" ::: "memory")
; #define PG8_WAIT_L(n) asm volatile("s_waitcnt lgkmcnt(" #n ")" ::: "memory")
; #define PG8_BAR __builtin_amdgcn_s_barrier()
; #define PG8_SCHED __builtin_amdgcn_sched_barrier(0)
; template <class Epi, class Sched, bool ABLK = false, bool ALIGN_EPI = true, bool SP2 = true, bool BBLK = true>
; __device__ __forceinline__ void gemm_phase(LAS unsigned char* lds, const Gemm g, const Sched& S, const Epi& E) {
;     ...
;             PG8_LDB(B0, 1, 0); PG8_LDB(B1, 1, 1); PG8_SCHED; PG8_LDA(At, 1, 0); PG8_STAGE(PG8_SA(0, 1), a2 + hstepA, voffA);
;             PG8_WAIT_V(8); PG8_WAIT_L(0); PG8_BAR; PG8_MMA(0, 0, At, B0); PG8_MMA(0, 1, At, B1); PG8_BAR; PG8_SCHED;
;             PG8_LDA(At, 1, 1); PG8_STAGE(PG8_SB(1, 0), b3, voffB); PG8_STAGE(PG8_SB(1, 1), b3 + hstepB, voffB); PG8_STAGE(PG8_SA(1, 0), a3, voffA);
;             PG8_WAIT_V(8); PG8_WAIT_L(0); PG8_BAR; PG8_MMA(1, 0, At, B0); PG8_MMA(1, 1, At, B1); PG8_BAR; PG8_SCHED;
;     ...
;         if constexpr (ALIGN_EPI) { if (wr == 0) PG8_BAR; }
;         E(acc, cur, wr, wc, fr, fq); S.done(cur);
;         if (!has_next) break;
	v_add_u32_e32 v138, s60, v161
	ds_read_b128 v[152:155], v138
	ds_read_b128 v[156:159], v138 offset:1024
	ds_read_b128 v[166:169], v138 offset:2048
	ds_read_b128 v[170:173], v138 offset:3072
	v_add_u32_e32 v138, s61, v161
	ds_read_b128 v[174:177], v138
	ds_read_b128 v[178:181], v138 offset:1024
	ds_read_b128 v[182:185], v138 offset:2048
	ds_read_b128 v[186:189], v138 offset:3072
	s_add_u32 s46, s46, 0x80000
	s_addc_u32 s47, s47, 0
	s_mov_b32 m0, s50
	ds_read_b128 v[190:193], v165 offset:32768
	ds_read_b128 v[194:197], v165 offset:33792
	ds_read_b128 v[198:201], v165 offset:34816
	ds_read_b128 v[202:205], v165 offset:35840
	ds_read_b128 v[206:209], v165 offset:36864
	ds_read_b128 v[210:213], v165 offset:37888
	ds_read_b128 v[214:217], v165 offset:38912
	ds_read_b128 v[218:221], v165 offset:39936
	global_load_lds_dwordx4 v136, s[46:47]
	s_mov_b32 m0, s51
	s_nop 0
	global_load_lds_dwordx4 v132, s[46:47]
	s_waitcnt vmcnt(8) lgkmcnt(0)
	s_barrier
	v_mfma_f32_16x16x32_bf16 v[126:129], v[152:155], v[190:193], v[126:129]
	v_mfma_f32_16x16x32_bf16 v[122:125], v[166:169], v[190:193], v[122:125]
	v_mfma_f32_16x16x32_bf16 v[110:113], v[152:155], v[198:201], v[110:113]
	v_mfma_f32_16x16x32_bf16 v[106:109], v[166:169], v[198:201], v[106:109]
	v_mfma_f32_16x16x32_bf16 v[94:97], v[152:155], v[206:209], v[94:97]
	v_mfma_f32_16x16x32_bf16 v[90:93], v[166:169], v[206:209], v[90:93]
	v_mfma_f32_16x16x32_bf16 v[78:81], v[152:155], v[214:217], v[78:81]
	v_mfma_f32_16x16x32_bf16 v[74:77], v[166:169], v[214:217], v[74:77]
	v_mfma_f32_16x16x32_bf16 v[126:129], v[156:159], v[194:197], v[126:129]
	v_mfma_f32_16x16x32_bf16 v[122:125], v[170:173], v[194:197], v[122:125]
	v_mfma_f32_16x16x32_bf16 v[110:113], v[156:159], v[202:205], v[110:113]
	v_mfma_f32_16x16x32_bf16 v[106:109], v[170:173], v[202:205], v[106:109]
	v_mfma_f32_16x16x32_bf16 v[94:97], v[156:159], v[210:213], v[94:97]
	v_mfma_f32_16x16x32_bf16 v[90:93], v[170:173], v[210:213], v[90:93]
	v_mfma_f32_16x16x32_bf16 v[78:81], v[156:159], v[218:221], v[78:81]
	v_mfma_f32_16x16x32_bf16 v[74:77], v[170:173], v[218:221], v[74:77]
	v_mfma_f32_16x16x32_bf16 v[118:121], v[174:177], v[190:193], v[118:121]
	v_mfma_f32_16x16x32_bf16 v[114:117], v[182:185], v[190:193], v[114:117]
	v_mfma_f32_16x16x32_bf16 v[102:105], v[174:177], v[198:201], v[102:105]
	v_mfma_f32_16x16x32_bf16 v[98:101], v[182:185], v[198:201], v[98:101]
	v_mfma_f32_16x16x32_bf16 v[86:89], v[174:177], v[206:209], v[86:89]
	v_mfma_f32_16x16x32_bf16 v[82:85], v[182:185], v[206:209], v[82:85]
	v_mfma_f32_16x16x32_bf16 v[70:73], v[174:177], v[214:217], v[70:73]
	v_mfma_f32_16x16x32_bf16 v[66:69], v[182:185], v[214:217], v[66:69]
	v_mfma_f32_16x16x32_bf16 v[118:121], v[178:181], v[194:197], v[118:121]
	v_mfma_f32_16x16x32_bf16 v[114:117], v[186:189], v[194:197], v[114:117]
	v_mfma_f32_16x16x32_bf16 v[102:105], v[178:181], v[202:205], v[102:105]
	v_mfma_f32_16x16x32_bf16 v[98:101], v[186:189], v[202:205], v[98:101]
	v_mfma_f32_16x16x32_bf16 v[86:89], v[178:181], v[210:213], v[86:89]
	v_mfma_f32_16x16x32_bf16 v[82:85], v[186:189], v[210:213], v[82:85]
	v_mfma_f32_16x16x32_bf16 v[70:73], v[178:181], v[218:221], v[70:73]
	v_mfma_f32_16x16x32_bf16 v[66:69], v[186:189], v[218:221], v[66:69]
	s_barrier
	s_add_u32 s46, s44, 0x8000
	s_addc_u32 s47, s45, 0
	s_add_i32 s66, s60, s49
	s_mov_b32 m0, s66
	ds_read_b128 v[190:193], v165 offset:49152
	ds_read_b128 v[194:197], v165 offset:50176
	ds_read_b128 v[198:201], v165 offset:51200
	ds_read_b128 v[202:205], v165 offset:52224
	ds_read_b128 v[206:209], v165 offset:53248
	ds_read_b128 v[210:213], v165 offset:54272
	ds_read_b128 v[214:217], v165 offset:55296
	ds_read_b128 v[218:221], v165 offset:56320
	global_load_lds_dwordx4 v134, s[46:47]
	s_add_i32 m0, s66, 0x2000
	s_add_u32 s44, s44, 0xc000
	v_lshl_add_u64 v[222:223], s[46:47], 0, v[130:131]
	s_addc_u32 s45, s45, 0
	s_add_i32 s46, s61, s49
	global_load_lds_dwordx4 v[222:223], off
	s_mov_b32 m0, s46
	s_nop 0
	global_load_lds_dwordx4 v134, s[44:45]
	s_add_i32 m0, s46, 0x2000
	s_nop 0
	global_load_lds_dwordx4 v130, s[44:45]
	s_mov_b32 m0, s54
	s_nop 0
	global_load_lds_dwordx4 v136, s[42:43]
	s_mov_b32 m0, s55
	s_nop 0
	global_load_lds_dwordx4 v132, s[42:43]
	s_waitcnt vmcnt(8) lgkmcnt(0)
	s_barrier
	v_mfma_f32_16x16x32_bf16 v[62:65], v[152:155], v[190:193], v[62:65]
	v_mfma_f32_16x16x32_bf16 v[58:61], v[166:169], v[190:193], v[58:61]
	v_mfma_f32_16x16x32_bf16 v[46:49], v[152:155], v[198:201], v[46:49]
	v_mfma_f32_16x16x32_bf16 v[42:45], v[166:169], v[198:201], v[42:45]
	v_mfma_f32_16x16x32_bf16 v[30:33], v[152:155], v[206:209], v[30:33]
	v_mfma_f32_16x16x32_bf16 v[26:29], v[166:169], v[206:209], v[26:29]
	v_mfma_f32_16x16x32_bf16 v[14:17], v[152:155], v[214:217], v[14:17]
	v_mfma_f32_16x16x32_bf16 v[10:13], v[166:169], v[214:217], v[10:13]
	v_mfma_f32_16x16x32_bf16 v[62:65], v[156:159], v[194:197], v[62:65]
	v_mfma_f32_16x16x32_bf16 v[58:61], v[170:173], v[194:197], v[58:61]
	v_mfma_f32_16x16x32_bf16 v[46:49], v[156:159], v[202:205], v[46:49]
	v_mfma_f32_16x16x32_bf16 v[42:45], v[170:173], v[202:205], v[42:45]
	v_mfma_f32_16x16x32_bf16 v[30:33], v[156:159], v[210:213], v[30:33]
	v_mfma_f32_16x16x32_bf16 v[26:29], v[170:173], v[210:213], v[26:29]
	v_mfma_f32_16x16x32_bf16 v[14:17], v[156:159], v[218:221], v[14:17]
	v_mfma_f32_16x16x32_bf16 v[10:13], v[170:173], v[218:221], v[10:13]
	v_mfma_f32_16x16x32_bf16 v[54:57], v[174:177], v[190:193], v[54:57]
	v_mfma_f32_16x16x32_bf16 v[50:53], v[182:185], v[190:193], v[50:53]
	v_mfma_f32_16x16x32_bf16 v[38:41], v[174:177], v[198:201], v[38:41]
	v_mfma_f32_16x16x32_bf16 v[34:37], v[182:185], v[198:201], v[34:37]
	v_mfma_f32_16x16x32_bf16 v[22:25], v[174:177], v[206:209], v[22:25]
	v_mfma_f32_16x16x32_bf16 v[18:21], v[182:185], v[206:209], v[18:21]
	v_mfma_f32_16x16x32_bf16 v[6:9], v[174:177], v[214:217], v[6:9]
	v_mfma_f32_16x16x32_bf16 v[2:5], v[182:185], v[214:217], v[2:5]
	v_mfma_f32_16x16x32_bf16 v[54:57], v[178:181], v[194:197], v[54:57]
	v_mfma_f32_16x16x32_bf16 v[50:53], v[186:189], v[194:197], v[50:53]
	v_mfma_f32_16x16x32_bf16 v[38:41], v[178:181], v[202:205], v[38:41]
	v_mfma_f32_16x16x32_bf16 v[34:37], v[186:189], v[202:205], v[34:37]
	v_mfma_f32_16x16x32_bf16 v[22:25], v[178:181], v[210:213], v[22:25]
	v_mfma_f32_16x16x32_bf16 v[18:21], v[186:189], v[210:213], v[18:21]
	v_mfma_f32_16x16x32_bf16 v[6:9], v[178:181], v[218:221], v[6:9]
	v_mfma_f32_16x16x32_bf16 v[2:5], v[186:189], v[218:221], v[2:5]
	s_barrier
	s_add_i32 s65, s65, 2
	s_add_u32 s40, s40, 0x100
	s_addc_u32 s41, s41, 0
	s_add_u32 s59, s59, 0x10000
	s_addc_u32 s64, s64, 0
	s_cmp_gt_u32 s65, 29
	s_cbranch_scc0 .LBB0_1355
	s_and_b64 vcc, exec, s[12:13]
	s_cbranch_vccz .LBB0_1358
	s_barrier

; template <class Epi, class Sched, bool ABLK = false, bool ALIGN_EPI = true, bool SP2 = true, bool BBLK = true>
; __device__ __forceinline__ void gemm_phase(LAS unsigned char* lds, const Gemm g, const Sched& S, const Epi& E) {
;     ...
;             const char* a2 = last ? a_tile(nuA, ntbA) : a_tile(uA, tbA + t + 2); const char* b2 = last ? nB : cB + (size_t)(t + 2) * kstepB;
;             const char* a3 = last ? a_tile(nuA, ntbA + 1) : a_tile(uA, tbA + t + 3); const char* b3 = b2 + kstepB;
.Lksel_15:
	s_mov_b32 s43, s57
	s_mov_b32 s42, s56
	s_mov_b32 s45, s21
	s_mov_b32 s44, s23
	s_mov_b32 s47, s4
	s_mov_b32 s46, s5
	s_branch .Lksel_15_back

; template <class Epi, class Sched, bool ABLK = false, bool ALIGN_EPI = true, bool SP2 = true, bool BBLK = true>
; __device__ __forceinline__ void gemm_phase(LAS unsigned char* lds, const Gemm g, const Sched& S, const Epi& E) {
;     ...
;     auto a_unit = [&](const Unit& u) -> const char* { return ABLK ? (const char*)g.A + (size_t)u.pm * ((size_t)g.lda / 64) * 32768 : (const char*)g.A + (size_t)u.pm * 2 * hstepA; };
;     auto a_tile = [&](const char* ub, int tau) -> const char* { return ub + (size_t)tau * (ABLK ? (size_t)32768 : kstep); };
;     const char* uA = a_unit(cur); int tbA = cur.k0 / BK;
;     const char* cA = a_tile(uA, tbA); const char* cB = (const char*)g.Bt + (size_t)cur.pn * tstepB + b_k0(cur.k0);
;     S.a_ready(cur);
;     if constexpr (SP2) {
;         PG8_STAGE(PG8_SB(0, 0), cB, voffB); PG8_STAGE(PG8_SB(0, 1), cB + hstepB, voffB); PG8_STAGE(PG8_SA(0, 0), cA, voffA); PG8_STAGE(PG8_SA(0, 1), cA + hstepA, voffA);
;         if (wr == 1) PG8_BAR;
;         PG8_WAIT_V(2); PG8_BAR;
;         PG8_STAGE(PG8_SB(1, 0), cB + kstepB, voffB); PG8_STAGE(PG8_SA(1, 0), a_tile(uA, tbA + 1), voffA); PG8_STAGE(PG8_SB(1, 1), cB + hstepB + kstepB, voffB);
;         PG8_WAIT_V(6); PG8_BAR;
;     } else {
;         PG8_STAGE(PG8_SB(0, 0), cB, voffB); PG8_STAGE(PG8_SA(0, 0), cA, voffA); PG8_STAGE(PG8_SB(0, 1), cB + hstepB, voffB); PG8_STAGE(PG8_SA(0, 1), cA + hstepA, voffA);
;         if (wr == 1) PG8_BAR;
;         PG8_WAIT_V(4); PG8_BAR;
;         PG8_STAGE(PG8_SB(1, 0), cB + kstepB, voffB); PG8_STAGE(PG8_SA(1, 0), a_tile(uA, tbA + 1), voffA); PG8_STAGE(PG8_SB(1, 1), cB + hstepB + kstepB, voffB);
;         PG8_WAIT_V(6); PG8_BAR;
;     }
;     for (;;) {
;         const bool has_next = S.next(ui + 1, nxt);
;         const int nt = cur.nt;
;         const char* nuA = has_next ? a_unit(nxt) : uA; const int ntbA = has_next ? nxt.k0 / BK : tbA; const char* nB = has_next ? (const char*)g.Bt + (size_t)nxt.pn * tstepB + b_k0(nxt.k0) : cB;
;         for (int t = 0; t < nt; t += 2) {
;             const bool last = (t == nt - 2);
;             const char* a1 = a_tile(uA, tbA + t + 1);
;             const char* a2 = last ? a_tile(nuA, ntbA) : a_tile(uA, tbA + t + 2); const char* b2 = last ? nB : cB + (size_t)(t + 2) * kstepB;
;             const char* a3 = last ? a_tile(nuA, ntbA + 1) : a_tile(uA, tbA + t + 3); const char* b3 = b2 + kstepB;
.LBB0_1715:
	s_ashr_i32 s81, s80, 31
	s_andn2_b64 vcc, exec, s[4:5]
	s_lshl_b64 s[20:21], s[80:81], 20
	s_add_u32 s20, s1, s20
	s_addc_u32 s21, s36, s21
	s_and_b64 s[22:23], s[4:5], exec
	s_cselect_b32 s31, s21, s29
	s_cselect_b32 s49, s20, s28
	s_ashr_i32 s22, s63, 31
	s_lshr_b32 s22, s22, 26
	s_add_i32 s22, s63, s22
	s_ashr_i32 s22, s22, 6
	s_and_b64 s[24:25], s[4:5], exec
	s_cselect_b32 s34, s22, s30
	s_ashr_i32 s79, s78, 31
	s_lshl_b64 s[24:25], s[78:79], 20
	s_add_u32 s35, s37, s24
	s_addc_u32 s50, s38, s25
	s_ashr_i32 s23, s22, 31
	s_lshl_b64 s[24:25], s[22:23], 15
	s_add_u32 s24, s35, s24
	s_addc_u32 s25, s50, s25
	v_cndmask_b32_e64 v2, 0, 1, s[4:5]
	s_and_b64 s[4:5], s[4:5], exec
	s_cselect_b32 s4, s25, s27
	s_cselect_b32 s5, s24, s26
	s_ashr_i32 s35, s34, 31
	s_lshl_b64 s[34:35], s[34:35], 7
	s_add_u32 s23, s49, s34
	s_addc_u32 s49, s31, s35
	s_add_u32 s50, s23, 0x80
	s_addc_u32 s51, s49, 0
	s_add_u32 s52, s26, 0x10000
	s_addc_u32 s53, s27, 0
	s_ashr_i32 s31, s30, 31
	v_cmp_ne_u32_e64 s[10:11], 1, v2
	s_lshl_b64 s[26:27], s[30:31], 7
	v_lshl_add_u64 v[2:3], s[28:29], 0, v[142:143]
	s_add_u32 s54, s28, s26
	v_lshl_add_u64 v[146:147], v[2:3], 0, s[26:27]
	v_lshl_add_u64 v[2:3], s[28:29], 0, v[144:145]
	s_addc_u32 s55, s29, s27
	v_lshl_add_u64 v[148:149], v[2:3], 0, s[26:27]
	s_lshl_b32 s26, s47, 7
	s_addk_i32 s26, 0xfc00
	v_mov_b32_e32 v2, 0
	s_add_u32 s56, s26, 0x300
	s_mov_b32 s57, 0
	s_mov_b64 s[26:27], 0
	ds_read_b128 v[156:159], v152
	ds_read_b128 v[160:163], v152 offset:1024
	ds_read_b128 v[164:167], v152 offset:2048
	ds_read_b128 v[168:171], v152 offset:3072
	ds_read_b128 v[172:175], v153
	ds_read_b128 v[176:179], v153 offset:1024
	ds_read_b128 v[180:183], v153 offset:2048
	ds_read_b128 v[184:187], v153 offset:3072
	s_add_u32 s28, s54, s26
	s_addc_u32 s29, s55, s27
	s_add_u32 s34, s28, 0x100
	s_addc_u32 s35, s29, 0
	s_add_i32 s57, s57, 2
	s_add_u32 s28, s28, 0x180
	s_addc_u32 s29, s29, 0
	s_mov_b64 s[30:31], s[52:53]
	v_lshl_add_u64 v[220:221], v[146:147], 0, s[26:27]
	s_add_i32 m0, s40, 0xc000
	ds_read_b128 v[188:191], v154
	ds_read_b128 v[192:195], v154 offset:1024
	ds_read_b128 v[196:199], v154 offset:2048
	ds_read_b128 v[200:203], v154 offset:3072
	ds_read_b128 v[204:207], v154 offset:4096
	ds_read_b128 v[208:211], v154 offset:5120
	ds_read_b128 v[212:215], v154 offset:6144
	ds_read_b128 v[216:219], v154 offset:7168
	global_load_lds_dwordx4 v[220:221], off
	v_lshl_add_u64 v[220:221], v[148:149], 0, s[26:27]
	s_add_i32 m0, s40, 0xe000
	s_nop 0
	global_load_lds_dwordx4 v[220:221], off
	s_waitcnt vmcnt(8) lgkmcnt(0)
	s_barrier
	v_mfma_f32_16x16x32_bf16 v[126:129], v[156:159], v[188:191], 0
	v_mfma_f32_16x16x32_bf16 v[122:125], v[164:167], v[188:191], 0
	v_mfma_f32_16x16x32_bf16 v[110:113], v[156:159], v[196:199], 0
	v_mfma_f32_16x16x32_bf16 v[106:109], v[164:167], v[196:199], 0
	v_mfma_f32_16x16x32_bf16 v[94:97], v[156:159], v[204:207], 0
	v_mfma_f32_16x16x32_bf16 v[90:93], v[164:167], v[204:207], 0
	v_mfma_f32_16x16x32_bf16 v[78:81], v[156:159], v[212:215], 0
	v_mfma_f32_16x16x32_bf16 v[74:77], v[164:167], v[212:215], 0
	v_mfma_f32_16x16x32_bf16 v[126:129], v[160:163], v[192:195], v[126:129]
	v_mfma_f32_16x16x32_bf16 v[122:125], v[168:171], v[192:195], v[122:125]
	v_mfma_f32_16x16x32_bf16 v[110:113], v[160:163], v[200:203], v[110:113]
	v_mfma_f32_16x16x32_bf16 v[106:109], v[168:171], v[200:203], v[106:109]
	v_mfma_f32_16x16x32_bf16 v[94:97], v[160:163], v[208:211], v[94:97]
	v_mfma_f32_16x16x32_bf16 v[90:93], v[168:171], v[208:211], v[90:93]
	v_mfma_f32_16x16x32_bf16 v[78:81], v[160:163], v[216:219], v[78:81]
	v_mfma_f32_16x16x32_bf16 v[74:77], v[168:171], v[216:219], v[74:77]
	v_mfma_f32_16x16x32_bf16 v[118:121], v[172:175], v[188:191], 0
	v_mfma_f32_16x16x32_bf16 v[114:117], v[180:183], v[188:191], 0
	v_mfma_f32_16x16x32_bf16 v[102:105], v[172:175], v[196:199], 0
	v_mfma_f32_16x16x32_bf16 v[98:101], v[180:183], v[196:199], 0
	v_mfma_f32_16x16x32_bf16 v[86:89], v[172:175], v[204:207], 0
	v_mfma_f32_16x16x32_bf16 v[82:85], v[180:183], v[204:207], 0
	v_mfma_f32_16x16x32_bf16 v[70:73], v[172:175], v[212:215], 0
	v_mfma_f32_16x16x32_bf16 v[66:69], v[180:183], v[212:215], 0
	v_mfma_f32_16x16x32_bf16 v[118:121], v[176:179], v[192:195], v[118:121]
	v_mfma_f32_16x16x32_bf16 v[114:117], v[184:187], v[192:195], v[114:117]
	v_mfma_f32_16x16x32_bf16 v[102:105], v[176:179], v[200:203], v[102:105]
	v_mfma_f32_16x16x32_bf16 v[98:101], v[184:187], v[200:203], v[98:101]
	v_mfma_f32_16x16x32_bf16 v[86:89], v[176:179], v[208:211], v[86:89]
	v_mfma_f32_16x16x32_bf16 v[82:85], v[184:187], v[208:211], v[82:85]
	v_mfma_f32_16x16x32_bf16 v[70:73], v[176:179], v[216:219], v[70:73]
	v_mfma_f32_16x16x32_bf16 v[66:69], v[184:187], v[216:219], v[66:69]
	s_barrier
	s_add_i32 s58, s72, s39
	s_mov_b32 m0, s58
	ds_read_b128 v[188:191], v154 offset:16384
	ds_read_b128 v[192:195], v154 offset:17408
	ds_read_b128 v[196:199], v154 offset:18432
	ds_read_b128 v[200:203], v154 offset:19456
	ds_read_b128 v[204:207], v154 offset:20480
	ds_read_b128 v[208:211], v154 offset:21504
	ds_read_b128 v[212:215], v154 offset:22528
	ds_read_b128 v[216:219], v154 offset:23552
	global_load_lds_dwordx4 v132, s[30:31]
	s_add_i32 m0, s58, 0x2000
	s_add_u32 s58, s30, 0x4000
	s_addc_u32 s59, s31, 0
	s_add_i32 s64, s73, s39
	global_load_lds_dwordx4 v136, s[30:31]
	s_mov_b32 m0, s64
	s_nop 0
	global_load_lds_dwordx4 v132, s[58:59]
	s_add_i32 m0, s64, 0x2000
	s_nop 0
	global_load_lds_dwordx4 v136, s[58:59]
	s_mov_b32 m0, s40
	s_nop 0
	global_load_lds_dwordx4 v130, s[34:35]
	s_mov_b32 m0, s41
	s_nop 0
	global_load_lds_dwordx4 v134, s[34:35]
	s_waitcnt vmcnt(8) lgkmcnt(0)
	s_barrier
; #define PG8_STAGE(bufoff, gbase, voff) do { _Pragma("unroll") for (int _i = 0; _i < 2; ++_i) \
;         __builtin_amdgcn_global_load_lds((const unsigned*)((const char*)(gbase) + (voff)[_i]), (LAS unsigned*)(lds + (bufoff) + ldsw + _i * 8192), 16, 0, 0); } while (0)
; #define PG8_LDA(dst, b, h) do { _Pragma("unroll") for (int m = 0; m < 4; ++m) _Pragma("unroll") for (int k = 0; k < 2; ++k) dst[m][k] = *(const LAS bf16x8*)(lds + PG8_SA(b, h) + aoff + m * 2048 + k * 1024); } while (0)
; #define PG8_LDB(dst, b, h) do { _Pragma("unroll") for (int n = 0; n < 2; ++n) _Pragma("unroll") for (int k = 0; k < 2; ++k) dst[n][k] = *(const LAS bf16x8*)(lds + PG8_SB(b, h) + boff + n * 2048 + k * 1024); } while (0)
; #define PG8_MMA(ai, bj, At, Bt) do { __builtin_amdgcn_s_setprio(1); _Pragma("unroll") for (int m = 0; m < 4; ++m) _Pragma("unroll") for (int n = 0; n < 2; ++n) _Pragma("unroll") for (int k = 0; k < 2; ++k) \
;         acc[ai][bj][m][n] = __builtin_amdgcn_mfma_f32_16x16x32_bf16(Bt[n][k], At[m][k], acc[ai][bj][m][n], 0, 0, 0); __builtin_amdgcn_s_setprio(0); } while (0)
; #define PG8_WAIT_V(n) asm volatile("s_waitcnt vmcnt(" #n ")" ::: "memory")
; #define PG8_WAIT_L(n) asm volatile("s_waitcnt lgkmcnt(" #n ")" ::: "memory")
; #define PG8_BAR __builtin_amdgcn_s_barrier()
; #define PG8_SCHED __builtin_amdgcn_sched_barrier(0)
; template <class Epi, class Sched, bool ABLK = false, bool ALIGN_EPI = true, bool SP2 = true, bool BBLK = true>
; __device__ __forceinline__ void gemm_phase(LAS unsigned char* lds, const Gemm g, const Sched& S, const Epi& E) {
;     ...
;             PG8_WAIT_V(8); PG8_WAIT_L(0); PG8_BAR; PG8_MMA(1, 0, At, B0); PG8_MMA(1, 1, At, B1); PG8_BAR; PG8_SCHED;
;             PG8_LDB(B0, 1, 0); PG8_LDB(B1, 1, 1); PG8_SCHED; PG8_LDA(At, 1, 0); PG8_STAGE(PG8_SA(0, 1), a2 + hstepA, voffA);
;             PG8_WAIT_V(8); PG8_WAIT_L(0); PG8_BAR; PG8_MMA(0, 0, At, B0); PG8_MMA(0, 1, At, B1); PG8_BAR; PG8_SCHED;
	v_mfma_f32_16x16x32_bf16 v[62:65], v[156:159], v[188:191], 0
	v_mfma_f32_16x16x32_bf16 v[58:61], v[164:167], v[188:191], 0
	v_mfma_f32_16x16x32_bf16 v[46:49], v[156:159], v[196:199], 0
	v_mfma_f32_16x16x32_bf16 v[42:45], v[164:167], v[196:199], 0
	v_mfma_f32_16x16x32_bf16 v[30:33], v[156:159], v[204:207], 0
	v_mfma_f32_16x16x32_bf16 v[26:29], v[164:167], v[204:207], 0
	v_mfma_f32_16x16x32_bf16 v[14:17], v[156:159], v[212:215], 0
	v_mfma_f32_16x16x32_bf16 v[10:13], v[164:167], v[212:215], 0
	v_mfma_f32_16x16x32_bf16 v[62:65], v[160:163], v[192:195], v[62:65]
	v_mfma_f32_16x16x32_bf16 v[58:61], v[168:171], v[192:195], v[58:61]
	v_mfma_f32_16x16x32_bf16 v[46:49], v[160:163], v[200:203], v[46:49]
	v_mfma_f32_16x16x32_bf16 v[42:45], v[168:171], v[200:203], v[42:45]
	v_mfma_f32_16x16x32_bf16 v[30:33], v[160:163], v[208:211], v[30:33]
	v_mfma_f32_16x16x32_bf16 v[26:29], v[168:171], v[208:211], v[26:29]
	v_mfma_f32_16x16x32_bf16 v[14:17], v[160:163], v[216:219], v[14:17]
	v_mfma_f32_16x16x32_bf16 v[10:13], v[168:171], v[216:219], v[10:13]
	v_mfma_f32_16x16x32_bf16 v[54:57], v[172:175], v[188:191], 0
	v_mfma_f32_16x16x32_bf16 v[50:53], v[180:183], v[188:191], 0
	v_mfma_f32_16x16x32_bf16 v[38:41], v[172:175], v[196:199], 0
	v_mfma_f32_16x16x32_bf16 v[34:37], v[180:183], v[196:199], 0
	v_mfma_f32_16x16x32_bf16 v[22:25], v[172:175], v[204:207], 0
	v_mfma_f32_16x16x32_bf16 v[18:21], v[180:183], v[204:207], 0
	v_mfma_f32_16x16x32_bf16 v[6:9], v[172:175], v[212:215], 0
	v_mfma_f32_16x16x32_bf16 v[2:5], v[180:183], v[212:215], 0
	v_mfma_f32_16x16x32_bf16 v[54:57], v[176:179], v[192:195], v[54:57]
	v_mfma_f32_16x16x32_bf16 v[50:53], v[184:187], v[192:195], v[50:53]
	v_mfma_f32_16x16x32_bf16 v[38:41], v[176:179], v[200:203], v[38:41]
	v_mfma_f32_16x16x32_bf16 v[34:37], v[184:187], v[200:203], v[34:37]
	v_mfma_f32_16x16x32_bf16 v[22:25], v[176:179], v[208:211], v[22:25]
	v_mfma_f32_16x16x32_bf16 v[18:21], v[184:187], v[208:211], v[18:21]
	v_mfma_f32_16x16x32_bf16 v[6:9], v[176:179], v[216:219], v[6:9]
	v_mfma_f32_16x16x32_bf16 v[2:5], v[184:187], v[216:219], v[2:5]
	s_barrier
	v_add_u32_e32 v155, s60, v150
	ds_read_b128 v[156:159], v155
	ds_read_b128 v[160:163], v155 offset:1024
	ds_read_b128 v[164:167], v155 offset:2048
	ds_read_b128 v[168:171], v155 offset:3072
	v_add_u32_e32 v155, s61, v150
	ds_read_b128 v[172:175], v155
	ds_read_b128 v[176:179], v155 offset:1024
	ds_read_b128 v[180:183], v155 offset:2048
	ds_read_b128 v[184:187], v155 offset:3072
	s_add_u32 s34, s34, 0x80000
	s_addc_u32 s35, s35, 0
	s_mov_b32 m0, s42
	ds_read_b128 v[188:191], v154 offset:32768
	ds_read_b128 v[192:195], v154 offset:33792
	ds_read_b128 v[196:199], v154 offset:34816
	ds_read_b128 v[200:203], v154 offset:35840
	ds_read_b128 v[204:207], v154 offset:36864
	ds_read_b128 v[208:211], v154 offset:37888
	ds_read_b128 v[212:215], v154 offset:38912
	ds_read_b128 v[216:219], v154 offset:39936
	global_load_lds_dwordx4 v130, s[34:35]
	s_mov_b32 m0, s43
	s_nop 0
	global_load_lds_dwordx4 v134, s[34:35]
	s_waitcnt vmcnt(8) lgkmcnt(0)
	s_barrier
	v_mfma_f32_16x16x32_bf16 v[126:129], v[156:159], v[188:191], v[126:129]
	v_mfma_f32_16x16x32_bf16 v[122:125], v[164:167], v[188:191], v[122:125]
	v_mfma_f32_16x16x32_bf16 v[110:113], v[156:159], v[196:199], v[110:113]
	v_mfma_f32_16x16x32_bf16 v[106:109], v[164:167], v[196:199], v[106:109]
	v_mfma_f32_16x16x32_bf16 v[94:97], v[156:159], v[204:207], v[94:97]
	v_mfma_f32_16x16x32_bf16 v[90:93], v[164:167], v[204:207], v[90:93]
	v_mfma_f32_16x16x32_bf16 v[78:81], v[156:159], v[212:215], v[78:81]
	v_mfma_f32_16x16x32_bf16 v[74:77], v[164:167], v[212:215], v[74:77]
	v_mfma_f32_16x16x32_bf16 v[126:129], v[160:163], v[192:195], v[126:129]
	v_mfma_f32_16x16x32_bf16 v[122:125], v[168:171], v[192:195], v[122:125]
	v_mfma_f32_16x16x32_bf16 v[110:113], v[160:163], v[200:203], v[110:113]
	v_mfma_f32_16x16x32_bf16 v[106:109], v[168:171], v[200:203], v[106:109]
	v_mfma_f32_16x16x32_bf16 v[94:97], v[160:163], v[208:211], v[94:97]
	v_mfma_f32_16x16x32_bf16 v[90:93], v[168:171], v[208:211], v[90:93]
	v_mfma_f32_16x16x32_bf16 v[78:81], v[160:163], v[216:219], v[78:81]
	v_mfma_f32_16x16x32_bf16 v[74:77], v[168:171], v[216:219], v[74:77]
	v_mfma_f32_16x16x32_bf16 v[118:121], v[172:175], v[188:191], v[118:121]
	v_mfma_f32_16x16x32_bf16 v[114:117], v[180:183], v[188:191], v[114:117]
	v_mfma_f32_16x16x32_bf16 v[102:105], v[172:175], v[196:199], v[102:105]
	v_mfma_f32_16x16x32_bf16 v[98:101], v[180:183], v[196:199], v[98:101]
	v_mfma_f32_16x16x32_bf16 v[86:89], v[172:175], v[204:207], v[86:89]
	v_mfma_f32_16x16x32_bf16 v[82:85], v[180:183], v[204:207], v[82:85]
	v_mfma_f32_16x16x32_bf16 v[70:73], v[172:175], v[212:215], v[70:73]
	v_mfma_f32_16x16x32_bf16 v[66:69], v[180:183], v[212:215], v[66:69]
	v_mfma_f32_16x16x32_bf16 v[118:121], v[176:179], v[192:195], v[118:121]
	v_mfma_f32_16x16x32_bf16 v[114:117], v[184:187], v[192:195], v[114:117]
	v_mfma_f32_16x16x32_bf16 v[102:105], v[176:179], v[200:203], v[102:105]
	v_mfma_f32_16x16x32_bf16 v[98:101], v[184:187], v[200:203], v[98:101]
	v_mfma_f32_16x16x32_bf16 v[86:89], v[176:179], v[208:211], v[86:89]
	v_mfma_f32_16x16x32_bf16 v[82:85], v[184:187], v[208:211], v[82:85]
	v_mfma_f32_16x16x32_bf16 v[70:73], v[176:179], v[216:219], v[70:73]
	v_mfma_f32_16x16x32_bf16 v[66:69], v[184:187], v[216:219], v[66:69]
	s_barrier
; #define PG8_STAGE(bufoff, gbase, voff) do { _Pragma("unroll") for (int _i = 0; _i < 2; ++_i) \
;         __builtin_amdgcn_global_load_lds((const unsigned*)((const char*)(gbase) + (voff)[_i]), (LAS unsigned*)(lds + (bufoff) + ldsw + _i * 8192), 16, 0, 0); } while (0)
; #define PG8_LDA(dst, b, h) do { _Pragma("unroll") for (int m = 0; m < 4; ++m) _Pragma("unroll") for (int k = 0; k < 2; ++k) dst[m][k] = *(const LAS bf16x8*)(lds + PG8_SA(b, h) + aoff + m * 2048 + k * 1024); } while (0)
; #define PG8_WAIT_V(n) asm volatile("s_waitcnt vmcnt(" #n ")" ::: "memory")
; #define PG8_WAIT_L(n) asm volatile("s_waitcnt lgkmcnt(" #n ")" ::: "memory")
; template <class Epi, class Sched, bool ABLK = false, bool ALIGN_EPI = true, bool SP2 = true, bool BBLK = true>
; __device__ __forceinline__ void gemm_phase(LAS unsigned char* lds, const Gemm g, const Sched& S, const Epi& E) {
;     ...
;         for (int t = 0; t < nt; t += 2) {
;             const bool last = (t == nt - 2);
;             const char* a1 = a_tile(uA, tbA + t + 1);
;             const char* a2 = last ? a_tile(nuA, ntbA) : a_tile(uA, tbA + t + 2); const char* b2 = last ? nB : cB + (size_t)(t + 2) * kstepB;
;             const char* a3 = last ? a_tile(nuA, ntbA + 1) : a_tile(uA, tbA + t + 3); const char* b3 = b2 + kstepB;
;             if (last && has_next) S.a_ready(nxt);
;             if constexpr (SP2) {
;             PG8_LDB(B0, 0, 0); PG8_LDB(B1, 0, 1); PG8_SCHED; PG8_LDA(At, 0, 0); PG8_STAGE(PG8_SA(1, 1), a1 + hstepA, voffA);
;             PG8_WAIT_V(8); PG8_WAIT_L(0); PG8_BAR; PG8_MMA(0, 0, At, B0); PG8_MMA(0, 1, At, B1); PG8_BAR; PG8_SCHED;
;             PG8_LDA(At, 0, 1); PG8_STAGE(PG8_SB(0, 0), b2, voffB); PG8_STAGE(PG8_SB(0, 1), b2 + hstepB, voffB); PG8_STAGE(PG8_SA(0, 0), a2, voffA);
;             PG8_WAIT_V(8); PG8_WAIT_L(0); PG8_BAR; PG8_MMA(1, 0, At, B0); PG8_MMA(1, 1, At, B1); PG8_BAR; PG8_SCHED;
;             PG8_LDB(B0, 1, 0); PG8_LDB(B1, 1, 1); PG8_SCHED; PG8_LDA(At, 1, 0); PG8_STAGE(PG8_SA(0, 1), a2 + hstepA, voffA);
;             PG8_WAIT_V(8); PG8_WAIT_L(0); PG8_BAR; PG8_MMA(0, 0, At, B0); PG8_MMA(0, 1, At, B1); PG8_BAR; PG8_SCHED;
;             PG8_LDA(At, 1, 1); PG8_STAGE(PG8_SB(1, 0), b3, voffB); PG8_STAGE(PG8_SB(1, 1), b3 + hstepB, voffB); PG8_STAGE(PG8_SA(1, 0), a3, voffA);
;             PG8_WAIT_V(8); PG8_WAIT_L(0); PG8_BAR; PG8_MMA(1, 0, At, B0); PG8_MMA(1, 1, At, B1); PG8_BAR; PG8_SCHED;
	s_add_u32 s34, s30, 0x8000
	s_addc_u32 s35, s31, 0
	s_add_i32 s58, s60, s39
	s_mov_b32 m0, s58
	ds_read_b128 v[188:191], v154 offset:49152
	ds_read_b128 v[192:195], v154 offset:50176
	ds_read_b128 v[196:199], v154 offset:51200
	ds_read_b128 v[200:203], v154 offset:52224
	ds_read_b128 v[204:207], v154 offset:53248
	ds_read_b128 v[208:211], v154 offset:54272
	ds_read_b128 v[212:215], v154 offset:55296
	ds_read_b128 v[216:219], v154 offset:56320
	global_load_lds_dwordx4 v132, s[34:35]
	s_add_i32 m0, s58, 0x2000
	s_add_u32 s30, s30, 0xc000
	v_lshl_add_u64 v[220:221], s[34:35], 0, v[136:137]
	s_addc_u32 s31, s31, 0
	s_add_i32 s34, s61, s39
	global_load_lds_dwordx4 v[220:221], off
	s_mov_b32 m0, s34
	s_nop 0
	global_load_lds_dwordx4 v132, s[30:31]
	s_add_i32 m0, s34, 0x2000
	s_nop 0
	global_load_lds_dwordx4 v136, s[30:31]
	s_mov_b32 m0, s44
	s_nop 0
	global_load_lds_dwordx4 v130, s[28:29]
	s_mov_b32 m0, s45
	s_nop 0
	global_load_lds_dwordx4 v134, s[28:29]
	s_waitcnt vmcnt(8) lgkmcnt(0)
	s_barrier
	v_mfma_f32_16x16x32_bf16 v[62:65], v[156:159], v[188:191], v[62:65]
	v_mfma_f32_16x16x32_bf16 v[58:61], v[164:167], v[188:191], v[58:61]
	v_mfma_f32_16x16x32_bf16 v[46:49], v[156:159], v[196:199], v[46:49]
	v_mfma_f32_16x16x32_bf16 v[42:45], v[164:167], v[196:199], v[42:45]
	v_mfma_f32_16x16x32_bf16 v[30:33], v[156:159], v[204:207], v[30:33]
	v_mfma_f32_16x16x32_bf16 v[26:29], v[164:167], v[204:207], v[26:29]
	v_mfma_f32_16x16x32_bf16 v[14:17], v[156:159], v[212:215], v[14:17]
	v_mfma_f32_16x16x32_bf16 v[10:13], v[164:167], v[212:215], v[10:13]
	v_mfma_f32_16x16x32_bf16 v[62:65], v[160:163], v[192:195], v[62:65]
	v_mfma_f32_16x16x32_bf16 v[58:61], v[168:171], v[192:195], v[58:61]
	v_mfma_f32_16x16x32_bf16 v[46:49], v[160:163], v[200:203], v[46:49]
	v_mfma_f32_16x16x32_bf16 v[42:45], v[168:171], v[200:203], v[42:45]
	v_mfma_f32_16x16x32_bf16 v[30:33], v[160:163], v[208:211], v[30:33]
	v_mfma_f32_16x16x32_bf16 v[26:29], v[168:171], v[208:211], v[26:29]
	v_mfma_f32_16x16x32_bf16 v[14:17], v[160:163], v[216:219], v[14:17]
	v_mfma_f32_16x16x32_bf16 v[10:13], v[168:171], v[216:219], v[10:13]
	v_mfma_f32_16x16x32_bf16 v[54:57], v[172:175], v[188:191], v[54:57]
	v_mfma_f32_16x16x32_bf16 v[50:53], v[180:183], v[188:191], v[50:53]
	v_mfma_f32_16x16x32_bf16 v[38:41], v[172:175], v[196:199], v[38:41]
	v_mfma_f32_16x16x32_bf16 v[34:37], v[180:183], v[196:199], v[34:37]
	v_mfma_f32_16x16x32_bf16 v[22:25], v[172:175], v[204:207], v[22:25]
	v_mfma_f32_16x16x32_bf16 v[18:21], v[180:183], v[204:207], v[18:21]
	v_mfma_f32_16x16x32_bf16 v[6:9], v[172:175], v[212:215], v[6:9]
	v_mfma_f32_16x16x32_bf16 v[2:5], v[180:183], v[212:215], v[2:5]
	v_mfma_f32_16x16x32_bf16 v[54:57], v[176:179], v[192:195], v[54:57]
	v_mfma_f32_16x16x32_bf16 v[50:53], v[184:187], v[192:195], v[50:53]
	v_mfma_f32_16x16x32_bf16 v[38:41], v[176:179], v[200:203], v[38:41]
	v_mfma_f32_16x16x32_bf16 v[34:37], v[184:187], v[200:203], v[34:37]
	v_mfma_f32_16x16x32_bf16 v[22:25], v[176:179], v[208:211], v[22:25]
	v_mfma_f32_16x16x32_bf16 v[18:21], v[184:187], v[208:211], v[18:21]
	v_mfma_f32_16x16x32_bf16 v[6:9], v[176:179], v[216:219], v[6:9]
	v_mfma_f32_16x16x32_bf16 v[2:5], v[184:187], v[216:219], v[2:5]
	s_barrier
	s_add_u32 s52, s52, 0x10000
	s_addc_u32 s53, s53, 0
	s_add_u32 s26, s26, 0x100
	s_addc_u32 s27, s27, 0
	s_cmp_ge_u32 s57, s47
.LBB0_1716:
	ds_read_b128 v[156:159], v152
	ds_read_b128 v[160:163], v152 offset:1024
	ds_read_b128 v[164:167], v152 offset:2048
	ds_read_b128 v[168:171], v152 offset:3072
	ds_read_b128 v[172:175], v153
	ds_read_b128 v[176:179], v153 offset:1024
	ds_read_b128 v[180:183], v153 offset:2048
	ds_read_b128 v[184:187], v153 offset:3072
	s_add_u32 s28, s54, s26
	s_addc_u32 s29, s55, s27
	s_add_u32 s34, s28, 0x100
	s_addc_u32 s35, s29, 0
	s_add_i32 s57, s57, 2
	s_add_u32 s28, s28, 0x180
	s_addc_u32 s29, s29, 0
	s_cmp_eq_u32 s56, s26
	s_cbranch_scc1 .Lksel_17
	s_mov_b64 s[30:31], s[52:53]
.Lksel_17_back:
	v_lshl_add_u64 v[220:221], v[146:147], 0, s[26:27]
	s_add_i32 m0, s40, 0xc000
	ds_read_b128 v[188:191], v154
	ds_read_b128 v[192:195], v154 offset:1024
	ds_read_b128 v[196:199], v154 offset:2048
	ds_read_b128 v[200:203], v154 offset:3072
	ds_read_b128 v[204:207], v154 offset:4096
	ds_read_b128 v[208:211], v154 offset:5120
	ds_read_b128 v[212:215], v154 offset:6144
	ds_read_b128 v[216:219], v154 offset:7168
	global_load_lds_dwordx4 v[220:221], off
	v_lshl_add_u64 v[220:221], v[148:149], 0, s[26:27]
	s_add_i32 m0, s40, 0xe000
	s_nop 0
	global_load_lds_dwordx4 v[220:221], off
	s_waitcnt vmcnt(8) lgkmcnt(0)
	s_barrier
; #define PG8_STAGE(bufoff, gbase, voff) do { _Pragma("unroll") for (int _i = 0; _i < 2; ++_i) \
;         __builtin_amdgcn_global_load_lds((const unsigned*)((const char*)(gbase) + (voff)[_i]), (LAS unsigned*)(lds + (bufoff) + ldsw + _i * 8192), 16, 0, 0); } while (0)
; #define PG8_LDA(dst, b, h) do { _Pragma("unroll") for (int m = 0; m < 4; ++m) _Pragma("unroll") for (int k = 0; k < 2; ++k) dst[m][k] = *(const LAS bf16x8*)(lds + PG8_SA(b, h) + aoff + m * 2048 + k * 1024); } while (0)
; #define PG8_LDB(dst, b, h) do { _Pragma("unroll") for (int n = 0; n < 2; ++n) _Pragma("unroll") for (int k = 0; k < 2; ++k) dst[n][k] = *(const LAS bf16x8*)(lds + PG8_SB(b, h) + boff + n * 2048 + k * 1024); } while (0)
; #define PG8_MMA(ai, bj, At, Bt) do { __builtin_amdgcn_s_setprio(1); _Pragma("unroll") for (int m = 0; m < 4; ++m) _Pragma("unroll") for (int n = 0; n < 2; ++n) _Pragma("unroll") for (int k = 0; k < 2; ++k) \
;         acc[ai][bj][m][n] = __builtin_amdgcn_mfma_f32_16x16x32_bf16(Bt[n][k], At[m][k], acc[ai][bj][m][n], 0, 0, 0); __builtin_amdgcn_s_setprio(0); } while (0)
; #define PG8_WAIT_V(n) asm volatile("s_waitcnt vmcnt(" #n ")" ::: "memory")
; #define PG8_WAIT_L(n) asm volatile("s_waitcnt lgkmcnt(" #n ")" ::: "memory")
; #define PG8_BAR __builtin_amdgcn_s_barrier()
; #define PG8_SCHED __builtin_amdgcn_sched_barrier(0)
; template <class Epi, class Sched, bool ABLK = false, bool ALIGN_EPI = true, bool SP2 = true, bool BBLK = true>
; __device__ __forceinline__ void gemm_phase(LAS unsigned char* lds, const Gemm g, const Sched& S, const Epi& E) {
;     ...
;             PG8_LDB(B0, 0, 0); PG8_LDB(B1, 0, 1); PG8_SCHED; PG8_LDA(At, 0, 0); PG8_STAGE(PG8_SA(1, 1), a1 + hstepA, voffA);
;             PG8_WAIT_V(8); PG8_WAIT_L(0); PG8_BAR; PG8_MMA(0, 0, At, B0); PG8_MMA(0, 1, At, B1); PG8_BAR; PG8_SCHED;
;             PG8_LDA(At, 0, 1); PG8_STAGE(PG8_SB(0, 0), b2, voffB); PG8_STAGE(PG8_SB(0, 1), b2 + hstepB, voffB); PG8_STAGE(PG8_SA(0, 0), a2, voffA);
;             PG8_WAIT_V(8); PG8_WAIT_L(0); PG8_BAR; PG8_MMA(1, 0, At, B0); PG8_MMA(1, 1, At, B1); PG8_BAR; PG8_SCHED;
;             PG8_LDB(B0, 1, 0); PG8_LDB(B1, 1, 1); PG8_SCHED; PG8_LDA(At, 1, 0); PG8_STAGE(PG8_SA(0, 1), a2 + hstepA, voffA);
;             PG8_WAIT_V(8); PG8_WAIT_L(0); PG8_BAR; PG8_MMA(0, 0, At, B0); PG8_MMA(0, 1, At, B1); PG8_BAR; PG8_SCHED;
	v_mfma_f32_16x16x32_bf16 v[126:129], v[156:159], v[188:191], v[126:129]
	v_mfma_f32_16x16x32_bf16 v[122:125], v[164:167], v[188:191], v[122:125]
	v_mfma_f32_16x16x32_bf16 v[110:113], v[156:159], v[196:199], v[110:113]
	v_mfma_f32_16x16x32_bf16 v[106:109], v[164:167], v[196:199], v[106:109]
	v_mfma_f32_16x16x32_bf16 v[94:97], v[156:159], v[204:207], v[94:97]
	v_mfma_f32_16x16x32_bf16 v[90:93], v[164:167], v[204:207], v[90:93]
	v_mfma_f32_16x16x32_bf16 v[78:81], v[156:159], v[212:215], v[78:81]
	v_mfma_f32_16x16x32_bf16 v[74:77], v[164:167], v[212:215], v[74:77]
	v_mfma_f32_16x16x32_bf16 v[126:129], v[160:163], v[192:195], v[126:129]
	v_mfma_f32_16x16x32_bf16 v[122:125], v[168:171], v[192:195], v[122:125]
	v_mfma_f32_16x16x32_bf16 v[110:113], v[160:163], v[200:203], v[110:113]
	v_mfma_f32_16x16x32_bf16 v[106:109], v[168:171], v[200:203], v[106:109]
	v_mfma_f32_16x16x32_bf16 v[94:97], v[160:163], v[208:211], v[94:97]
	v_mfma_f32_16x16x32_bf16 v[90:93], v[168:171], v[208:211], v[90:93]
	v_mfma_f32_16x16x32_bf16 v[78:81], v[160:163], v[216:219], v[78:81]
	v_mfma_f32_16x16x32_bf16 v[74:77], v[168:171], v[216:219], v[74:77]
	v_mfma_f32_16x16x32_bf16 v[118:121], v[172:175], v[188:191], v[118:121]
	v_mfma_f32_16x16x32_bf16 v[114:117], v[180:183], v[188:191], v[114:117]
	v_mfma_f32_16x16x32_bf16 v[102:105], v[172:175], v[196:199], v[102:105]
	v_mfma_f32_16x16x32_bf16 v[98:101], v[180:183], v[196:199], v[98:101]
	v_mfma_f32_16x16x32_bf16 v[86:89], v[172:175], v[204:207], v[86:89]
	v_mfma_f32_16x16x32_bf16 v[82:85], v[180:183], v[204:207], v[82:85]
	v_mfma_f32_16x16x32_bf16 v[70:73], v[172:175], v[212:215], v[70:73]
	v_mfma_f32_16x16x32_bf16 v[66:69], v[180:183], v[212:215], v[66:69]
	v_mfma_f32_16x16x32_bf16 v[118:121], v[176:179], v[192:195], v[118:121]
	v_mfma_f32_16x16x32_bf16 v[114:117], v[184:187], v[192:195], v[114:117]
	v_mfma_f32_16x16x32_bf16 v[102:105], v[176:179], v[200:203], v[102:105]
	v_mfma_f32_16x16x32_bf16 v[98:101], v[184:187], v[200:203], v[98:101]
	v_mfma_f32_16x16x32_bf16 v[86:89], v[176:179], v[208:211], v[86:89]
	v_mfma_f32_16x16x32_bf16 v[82:85], v[184:187], v[208:211], v[82:85]
	v_mfma_f32_16x16x32_bf16 v[70:73], v[176:179], v[216:219], v[70:73]
	v_mfma_f32_16x16x32_bf16 v[66:69], v[184:187], v[216:219], v[66:69]
	s_barrier
	s_add_i32 s58, s72, s39
	s_mov_b32 m0, s58
	ds_read_b128 v[188:191], v154 offset:16384
	ds_read_b128 v[192:195], v154 offset:17408
	ds_read_b128 v[196:199], v154 offset:18432
	ds_read_b128 v[200:203], v154 offset:19456
	ds_read_b128 v[204:207], v154 offset:20480
	ds_read_b128 v[208:211], v154 offset:21504
	ds_read_b128 v[212:215], v154 offset:22528
	ds_read_b128 v[216:219], v154 offset:23552
	global_load_lds_dwordx4 v132, s[30:31]
	s_add_i32 m0, s58, 0x2000
	s_add_u32 s58, s30, 0x4000
	s_addc_u32 s59, s31, 0
	s_add_i32 s64, s73, s39
	global_load_lds_dwordx4 v136, s[30:31]
	s_mov_b32 m0, s64
	s_nop 0
	global_load_lds_dwordx4 v132, s[58:59]
	s_add_i32 m0, s64, 0x2000
	s_nop 0
	global_load_lds_dwordx4 v136, s[58:59]
	s_mov_b32 m0, s40
	s_nop 0
	global_load_lds_dwordx4 v130, s[34:35]
	s_mov_b32 m0, s41
	s_nop 0
	global_load_lds_dwordx4 v134, s[34:35]
	s_waitcnt vmcnt(8) lgkmcnt(0)
	s_barrier
	v_mfma_f32_16x16x32_bf16 v[62:65], v[156:159], v[188:191], v[62:65]
	v_mfma_f32_16x16x32_bf16 v[58:61], v[164:167], v[188:191], v[58:61]
	v_mfma_f32_16x16x32_bf16 v[46:49], v[156:159], v[196:199], v[46:49]
	v_mfma_f32_16x16x32_bf16 v[42:45], v[164:167], v[196:199], v[42:45]
	v_mfma_f32_16x16x32_bf16 v[30:33], v[156:159], v[204:207], v[30:33]
	v_mfma_f32_16x16x32_bf16 v[26:29], v[164:167], v[204:207], v[26:29]
	v_mfma_f32_16x16x32_bf16 v[14:17], v[156:159], v[212:215], v[14:17]
	v_mfma_f32_16x16x32_bf16 v[10:13], v[164:167], v[212:215], v[10:13]
	v_mfma_f32_16x16x32_bf16 v[62:65], v[160:163], v[192:195], v[62:65]
	v_mfma_f32_16x16x32_bf16 v[58:61], v[168:171], v[192:195], v[58:61]
	v_mfma_f32_16x16x32_bf16 v[46:49], v[160:163], v[200:203], v[46:49]
	v_mfma_f32_16x16x32_bf16 v[42:45], v[168:171], v[200:203], v[42:45]
	v_mfma_f32_16x16x32_bf16 v[30:33], v[160:163], v[208:211], v[30:33]
	v_mfma_f32_16x16x32_bf16 v[26:29], v[168:171], v[208:211], v[26:29]
	v_mfma_f32_16x16x32_bf16 v[14:17], v[160:163], v[216:219], v[14:17]
	v_mfma_f32_16x16x32_bf16 v[10:13], v[168:171], v[216:219], v[10:13]
	v_mfma_f32_16x16x32_bf16 v[54:57], v[172:175], v[188:191], v[54:57]
	v_mfma_f32_16x16x32_bf16 v[50:53], v[180:183], v[188:191], v[50:53]
	v_mfma_f32_16x16x32_bf16 v[38:41], v[172:175], v[196:199], v[38:41]
	v_mfma_f32_16x16x32_bf16 v[34:37], v[180:183], v[196:199], v[34:37]
	v_mfma_f32_16x16x32_bf16 v[22:25], v[172:175], v[204:207], v[22:25]
	v_mfma_f32_16x16x32_bf16 v[18:21], v[180:183], v[204:207], v[18:21]
	v_mfma_f32_16x16x32_bf16 v[6:9], v[172:175], v[212:215], v[6:9]
	v_mfma_f32_16x16x32_bf16 v[2:5], v[180:183], v[212:215], v[2:5]
	v_mfma_f32_16x16x32_bf16 v[54:57], v[176:179], v[192:195], v[54:57]
	v_mfma_f32_16x16x32_bf16 v[50:53], v[184:187], v[192:195], v[50:53]
	v_mfma_f32_16x16x32_bf16 v[38:41], v[176:179], v[200:203], v[38:41]
	v_mfma_f32_16x16x32_bf16 v[34:37], v[184:187], v[200:203], v[34:37]
	v_mfma_f32_16x16x32_bf16 v[22:25], v[176:179], v[208:211], v[22:25]
	v_mfma_f32_16x16x32_bf16 v[18:21], v[184:187], v[208:211], v[18:21]
	v_mfma_f32_16x16x32_bf16 v[6:9], v[176:179], v[216:219], v[6:9]
	v_mfma_f32_16x16x32_bf16 v[2:5], v[184:187], v[216:219], v[2:5]
	s_barrier
; #define PG8_STAGE(bufoff, gbase, voff) do { _Pragma("unroll") for (int _i = 0; _i < 2; ++_i) \
;         __builtin_amdgcn_global_load_lds((const unsigned*)((const char*)(gbase) + (voff)[_i]), (LAS unsigned*)(lds + (bufoff) + ldsw + _i * 8192), 16, 0, 0); } while (0)
; #define PG8_LDA(dst, b, h) do { _Pragma("unroll") for (int m = 0; m < 4; ++m) _Pragma("unroll") for (int k = 0; k < 2; ++k) dst[m][k] = *(const LAS bf16x8*)(lds + PG8_SA(b, h) + aoff + m * 2048 + k * 1024); } while (0)
; #define PG8_LDB(dst, b, h) do { _Pragma("unroll") for (int n = 0; n < 2; ++n) _Pragma("unroll") for (int k = 0; k < 2; ++k) dst[n][k] = *(const LAS bf16x8*)(lds + PG8_SB(b, h) + boff + n * 2048 + k * 1024); } while (0)
; #define PG8_MMA(ai, bj, At, Bt) do { __builtin_amdgcn_s_setprio(1); _Pragma("unroll") for (int m = 0; m < 4; ++m) _Pragma("unroll") for (int n = 0; n < 2; ++n) _Pragma("unroll") for (int k = 0; k < 2; ++k) \
;         acc[ai][bj][m][n] = __builtin_amdgcn_mfma_f32_16x16x32_bf16(Bt[n][k], At[m][k], acc[ai][bj][m][n], 0, 0, 0); __builtin_amdgcn_s_setprio(0); } while (0)
; #define PG8_WAIT_V(n) asm volatile("s_waitcnt vmcnt(" #n ")" ::: "memory")
; #define PG8_WAIT_L(n) asm volatile("s_waitcnt lgkmcnt(" #n ")" ::: "memory")
; #define PG8_BAR __builtin_amdgcn_s_barrier()
; #define PG8_SCHED __builtin_amdgcn_sched_barrier(0)
; template <class Epi, class Sched, bool ABLK = false, bool ALIGN_EPI = true, bool SP2 = true, bool BBLK = true>
; __device__ __forceinline__ void gemm_phase(LAS unsigned char* lds, const Gemm g, const Sched& S, const Epi& E) {
;     ...
;             PG8_LDB(B0, 1, 0); PG8_LDB(B1, 1, 1); PG8_SCHED; PG8_LDA(At, 1, 0); PG8_STAGE(PG8_SA(0, 1), a2 + hstepA, voffA);
;             PG8_WAIT_V(8); PG8_WAIT_L(0); PG8_BAR; PG8_MMA(0, 0, At, B0); PG8_MMA(0, 1, At, B1); PG8_BAR; PG8_SCHED;
;             PG8_LDA(At, 1, 1); PG8_STAGE(PG8_SB(1, 0), b3, voffB); PG8_STAGE(PG8_SB(1, 1), b3 + hstepB, voffB); PG8_STAGE(PG8_SA(1, 0), a3, voffA);
;             PG8_WAIT_V(8); PG8_WAIT_L(0); PG8_BAR; PG8_MMA(1, 0, At, B0); PG8_MMA(1, 1, At, B1); PG8_BAR; PG8_SCHED;
;     ...
;         if constexpr (ALIGN_EPI) { if (wr == 0) PG8_BAR; }
;         E(acc, cur, wr, wc, fr, fq); S.done(cur);
;         if (!has_next) break;
	v_add_u32_e32 v155, s60, v150
	ds_read_b128 v[156:159], v155
	ds_read_b128 v[160:163], v155 offset:1024
	ds_read_b128 v[164:167], v155 offset:2048
	ds_read_b128 v[168:171], v155 offset:3072
	v_add_u32_e32 v155, s61, v150
	ds_read_b128 v[172:175], v155
	ds_read_b128 v[176:179], v155 offset:1024
	ds_read_b128 v[180:183], v155 offset:2048
	ds_read_b128 v[184:187], v155 offset:3072
	s_add_u32 s34, s34, 0x80000
	s_addc_u32 s35, s35, 0
	s_mov_b32 m0, s42
	ds_read_b128 v[188:191], v154 offset:32768
	ds_read_b128 v[192:195], v154 offset:33792
	ds_read_b128 v[196:199], v154 offset:34816
	ds_read_b128 v[200:203], v154 offset:35840
	ds_read_b128 v[204:207], v154 offset:36864
	ds_read_b128 v[208:211], v154 offset:37888
	ds_read_b128 v[212:215], v154 offset:38912
	ds_read_b128 v[216:219], v154 offset:39936
	global_load_lds_dwordx4 v130, s[34:35]
	s_mov_b32 m0, s43
	s_nop 0
	global_load_lds_dwordx4 v134, s[34:35]
	s_waitcnt vmcnt(8) lgkmcnt(0)
	s_barrier
	v_mfma_f32_16x16x32_bf16 v[126:129], v[156:159], v[188:191], v[126:129]
	v_mfma_f32_16x16x32_bf16 v[122:125], v[164:167], v[188:191], v[122:125]
	v_mfma_f32_16x16x32_bf16 v[110:113], v[156:159], v[196:199], v[110:113]
	v_mfma_f32_16x16x32_bf16 v[106:109], v[164:167], v[196:199], v[106:109]
	v_mfma_f32_16x16x32_bf16 v[94:97], v[156:159], v[204:207], v[94:97]
	v_mfma_f32_16x16x32_bf16 v[90:93], v[164:167], v[204:207], v[90:93]
	v_mfma_f32_16x16x32_bf16 v[78:81], v[156:159], v[212:215], v[78:81]
	v_mfma_f32_16x16x32_bf16 v[74:77], v[164:167], v[212:215], v[74:77]
	v_mfma_f32_16x16x32_bf16 v[126:129], v[160:163], v[192:195], v[126:129]
	v_mfma_f32_16x16x32_bf16 v[122:125], v[168:171], v[192:195], v[122:125]
	v_mfma_f32_16x16x32_bf16 v[110:113], v[160:163], v[200:203], v[110:113]
	v_mfma_f32_16x16x32_bf16 v[106:109], v[168:171], v[200:203], v[106:109]
	v_mfma_f32_16x16x32_bf16 v[94:97], v[160:163], v[208:211], v[94:97]
	v_mfma_f32_16x16x32_bf16 v[90:93], v[168:171], v[208:211], v[90:93]
	v_mfma_f32_16x16x32_bf16 v[78:81], v[160:163], v[216:219], v[78:81]
	v_mfma_f32_16x16x32_bf16 v[74:77], v[168:171], v[216:219], v[74:77]
	v_mfma_f32_16x16x32_bf16 v[118:121], v[172:175], v[188:191], v[118:121]
	v_mfma_f32_16x16x32_bf16 v[114:117], v[180:183], v[188:191], v[114:117]
	v_mfma_f32_16x16x32_bf16 v[102:105], v[172:175], v[196:199], v[102:105]
	v_mfma_f32_16x16x32_bf16 v[98:101], v[180:183], v[196:199], v[98:101]
	v_mfma_f32_16x16x32_bf16 v[86:89], v[172:175], v[204:207], v[86:89]
	v_mfma_f32_16x16x32_bf16 v[82:85], v[180:183], v[204:207], v[82:85]
	v_mfma_f32_16x16x32_bf16 v[70:73], v[172:175], v[212:215], v[70:73]
	v_mfma_f32_16x16x32_bf16 v[66:69], v[180:183], v[212:215], v[66:69]
	v_mfma_f32_16x16x32_bf16 v[118:121], v[176:179], v[192:195], v[118:121]
	v_mfma_f32_16x16x32_bf16 v[114:117], v[184:187], v[192:195], v[114:117]
	v_mfma_f32_16x16x32_bf16 v[102:105], v[176:179], v[200:203], v[102:105]
	v_mfma_f32_16x16x32_bf16 v[98:101], v[184:187], v[200:203], v[98:101]
	v_mfma_f32_16x16x32_bf16 v[86:89], v[176:179], v[208:211], v[86:89]
	v_mfma_f32_16x16x32_bf16 v[82:85], v[184:187], v[208:211], v[82:85]
	v_mfma_f32_16x16x32_bf16 v[70:73], v[176:179], v[216:219], v[70:73]
	v_mfma_f32_16x16x32_bf16 v[66:69], v[184:187], v[216:219], v[66:69]
	s_barrier
	s_add_u32 s34, s30, 0x8000
	s_addc_u32 s35, s31, 0
	s_add_i32 s58, s60, s39
	s_mov_b32 m0, s58
	ds_read_b128 v[188:191], v154 offset:49152
	ds_read_b128 v[192:195], v154 offset:50176
	ds_read_b128 v[196:199], v154 offset:51200
	ds_read_b128 v[200:203], v154 offset:52224
	ds_read_b128 v[204:207], v154 offset:53248
	ds_read_b128 v[208:211], v154 offset:54272
	ds_read_b128 v[212:215], v154 offset:55296
	ds_read_b128 v[216:219], v154 offset:56320
	global_load_lds_dwordx4 v132, s[34:35]
	s_add_i32 m0, s58, 0x2000
	s_add_u32 s30, s30, 0xc000
	v_lshl_add_u64 v[220:221], s[34:35], 0, v[136:137]
	s_addc_u32 s31, s31, 0
	s_add_i32 s34, s61, s39
	global_load_lds_dwordx4 v[220:221], off
	s_mov_b32 m0, s34
	s_nop 0
	global_load_lds_dwordx4 v132, s[30:31]
	s_add_i32 m0, s34, 0x2000
	s_nop 0
	global_load_lds_dwordx4 v136, s[30:31]
	s_mov_b32 m0, s44
	s_nop 0
	global_load_lds_dwordx4 v130, s[28:29]
	s_mov_b32 m0, s45
	s_nop 0
	global_load_lds_dwordx4 v134, s[28:29]
	s_waitcnt vmcnt(8) lgkmcnt(0)
	s_barrier
	v_mfma_f32_16x16x32_bf16 v[62:65], v[156:159], v[188:191], v[62:65]
	v_mfma_f32_16x16x32_bf16 v[58:61], v[164:167], v[188:191], v[58:61]
	v_mfma_f32_16x16x32_bf16 v[46:49], v[156:159], v[196:199], v[46:49]
	v_mfma_f32_16x16x32_bf16 v[42:45], v[164:167], v[196:199], v[42:45]
	v_mfma_f32_16x16x32_bf16 v[30:33], v[156:159], v[204:207], v[30:33]
	v_mfma_f32_16x16x32_bf16 v[26:29], v[164:167], v[204:207], v[26:29]
	v_mfma_f32_16x16x32_bf16 v[14:17], v[156:159], v[212:215], v[14:17]
	v_mfma_f32_16x16x32_bf16 v[10:13], v[164:167], v[212:215], v[10:13]
	v_mfma_f32_16x16x32_bf16 v[62:65], v[160:163], v[192:195], v[62:65]
	v_mfma_f32_16x16x32_bf16 v[58:61], v[168:171], v[192:195], v[58:61]
	v_mfma_f32_16x16x32_bf16 v[46:49], v[160:163], v[200:203], v[46:49]
	v_mfma_f32_16x16x32_bf16 v[42:45], v[168:171], v[200:203], v[42:45]
	v_mfma_f32_16x16x32_bf16 v[30:33], v[160:163], v[208:211], v[30:33]
	v_mfma_f32_16x16x32_bf16 v[26:29], v[168:171], v[208:211], v[26:29]
	v_mfma_f32_16x16x32_bf16 v[14:17], v[160:163], v[216:219], v[14:17]
	v_mfma_f32_16x16x32_bf16 v[10:13], v[168:171], v[216:219], v[10:13]
	v_mfma_f32_16x16x32_bf16 v[54:57], v[172:175], v[188:191], v[54:57]
	v_mfma_f32_16x16x32_bf16 v[50:53], v[180:183], v[188:191], v[50:53]
	v_mfma_f32_16x16x32_bf16 v[38:41], v[172:175], v[196:199], v[38:41]
	v_mfma_f32_16x16x32_bf16 v[34:37], v[180:183], v[196:199], v[34:37]
	v_mfma_f32_16x16x32_bf16 v[22:25], v[172:175], v[204:207], v[22:25]
	v_mfma_f32_16x16x32_bf16 v[18:21], v[180:183], v[204:207], v[18:21]
	v_mfma_f32_16x16x32_bf16 v[6:9], v[172:175], v[212:215], v[6:9]
	v_mfma_f32_16x16x32_bf16 v[2:5], v[180:183], v[212:215], v[2:5]
	v_mfma_f32_16x16x32_bf16 v[54:57], v[176:179], v[192:195], v[54:57]
	v_mfma_f32_16x16x32_bf16 v[50:53], v[184:187], v[192:195], v[50:53]
	v_mfma_f32_16x16x32_bf16 v[38:41], v[176:179], v[200:203], v[38:41]
	v_mfma_f32_16x16x32_bf16 v[34:37], v[184:187], v[200:203], v[34:37]
	v_mfma_f32_16x16x32_bf16 v[22:25], v[176:179], v[208:211], v[22:25]
	v_mfma_f32_16x16x32_bf16 v[18:21], v[184:187], v[208:211], v[18:21]
	v_mfma_f32_16x16x32_bf16 v[6:9], v[176:179], v[216:219], v[6:9]
	v_mfma_f32_16x16x32_bf16 v[2:5], v[184:187], v[216:219], v[2:5]
	s_barrier
	s_add_u32 s52, s52, 0x10000
	s_addc_u32 s53, s53, 0
	s_add_u32 s26, s26, 0x100
	s_addc_u32 s27, s27, 0
	s_cmp_ge_u32 s57, s47
	s_cbranch_scc0 .LBB0_1716
	s_and_b64 vcc, exec, s[6:7]
	s_cbranch_vccz .LBB0_1719
	s_barrier

; template <class Epi, class Sched, bool ABLK = false, bool ALIGN_EPI = true, bool SP2 = true, bool BBLK = true>
; __device__ __forceinline__ void gemm_phase(LAS unsigned char* lds, const Gemm g, const Sched& S, const Epi& E) {
;     ...
;             const char* a2 = last ? a_tile(nuA, ntbA) : a_tile(uA, tbA + t + 2); const char* b2 = last ? nB : cB + (size_t)(t + 2) * kstepB;
;             const char* a3 = last ? a_tile(nuA, ntbA + 1) : a_tile(uA, tbA + t + 3); const char* b3 = b2 + kstepB;
.Lksel_17:
	s_mov_b32 s29, s51
	s_mov_b32 s28, s50
	s_mov_b32 s31, s4
	s_mov_b32 s30, s5
	s_mov_b32 s35, s49
	s_mov_b32 s34, s23
	s_branch .Lksel_17_back

; #define PG8_STAGE(bufoff, gbase, voff) do { _Pragma("unroll") for (int _i = 0; _i < 2; ++_i) \
;         __builtin_amdgcn_global_load_lds((const unsigned*)((const char*)(gbase) + (voff)[_i]), (LAS unsigned*)(lds + (bufoff) + ldsw + _i * 8192), 16, 0, 0); } while (0)
; #define PG8_LDA(dst, b, h) do { _Pragma("unroll") for (int m = 0; m < 4; ++m) _Pragma("unroll") for (int k = 0; k < 2; ++k) dst[m][k] = *(const LAS bf16x8*)(lds + PG8_SA(b, h) + aoff + m * 2048 + k * 1024); } while (0)
; #define PG8_LDB(dst, b, h) do { _Pragma("unroll") for (int n = 0; n < 2; ++n) _Pragma("unroll") for (int k = 0; k < 2; ++k) dst[n][k] = *(const LAS bf16x8*)(lds + PG8_SB(b, h) + boff + n * 2048 + k * 1024); } while (0)
; #define PG8_WAIT_V(n) asm volatile("s_waitcnt vmcnt(" #n ")" ::: "memory")
; #define PG8_WAIT_L(n) asm volatile("s_waitcnt lgkmcnt(" #n ")" ::: "memory")
; template <class Epi, class Sched, bool ABLK = false, bool ALIGN_EPI = true, bool SP2 = true, bool BBLK = true>
; __device__ __forceinline__ void gemm_phase(LAS unsigned char* lds, const Gemm g, const Sched& S, const Epi& E) {
;     ...
;         const bool has_next = S.next(ui + 1, nxt);
;         const int nt = cur.nt;
;         const char* nuA = has_next ? a_unit(nxt) : uA; const int ntbA = has_next ? nxt.k0 / BK : tbA; const char* nB = has_next ? (const char*)g.Bt + (size_t)nxt.pn * tstepB + b_k0(nxt.k0) : cB;
;         for (int t = 0; t < nt; t += 2) {
;             const bool last = (t == nt - 2);
;             const char* a1 = a_tile(uA, tbA + t + 1);
;             const char* a2 = last ? a_tile(nuA, ntbA) : a_tile(uA, tbA + t + 2); const char* b2 = last ? nB : cB + (size_t)(t + 2) * kstepB;
;             const char* a3 = last ? a_tile(nuA, ntbA + 1) : a_tile(uA, tbA + t + 3); const char* b3 = b2 + kstepB;
;             if (last && has_next) S.a_ready(nxt);
;             if constexpr (SP2) {
;             PG8_LDB(B0, 0, 0); PG8_LDB(B1, 0, 1); PG8_SCHED; PG8_LDA(At, 0, 0); PG8_STAGE(PG8_SA(1, 1), a1 + hstepA, voffA);
;             PG8_WAIT_V(8); PG8_WAIT_L(0); PG8_BAR; PG8_MMA(0, 0, At, B0); PG8_MMA(0, 1, At, B1); PG8_BAR; PG8_SCHED;
;             PG8_LDA(At, 0, 1); PG8_STAGE(PG8_SB(0, 0), b2, voffB); PG8_STAGE(PG8_SB(0, 1), b2 + hstepB, voffB); PG8_STAGE(PG8_SA(0, 0), a2, voffA);
;             PG8_WAIT_V(8); PG8_WAIT_L(0); PG8_BAR; PG8_MMA(1, 0, At, B0); PG8_MMA(1, 1, At, B1); PG8_BAR; PG8_SCHED;
.LBB0_1841:
	s_ashr_i32 s11, s10, 31
	s_lshl_b64 s[4:5], s[10:11], 20
	s_add_u32 s16, s76, s4
	s_addc_u32 s17, s33, s5
	s_and_b64 s[4:5], s[18:19], exec
	s_cselect_b32 s4, s17, s27
	s_cselect_b32 s5, s16, s26
	s_ashr_i32 s15, s14, 31
	s_lshl_b64 s[20:21], s[14:15], 20
	s_add_u32 s20, s1, s20
	s_addc_u32 s21, s38, s21
	s_and_b64 s[30:31], s[18:19], exec
	s_cselect_b32 s11, s21, s29
	s_cselect_b32 s15, s20, s28
	s_add_u32 s23, s5, 0x80
	s_addc_u32 s51, s4, 0
	s_add_u32 s52, s28, 0x10000
	v_mov_b32_e32 v2, 0
	s_addc_u32 s53, s29, 0
	v_lshl_add_u64 v[164:165], s[26:27], 0, v[160:161]
	v_lshl_add_u64 v[166:167], s[26:27], 0, v[162:163]
	s_mov_b32 s54, -2
	s_mov_b64 s[28:29], 0
	ds_read_b128 v[172:175], v168
	ds_read_b128 v[176:179], v168 offset:1024
	ds_read_b128 v[180:183], v168 offset:2048
	ds_read_b128 v[184:187], v168 offset:3072
	ds_read_b128 v[188:191], v169
	ds_read_b128 v[192:195], v169 offset:1024
	ds_read_b128 v[196:199], v169 offset:2048
	ds_read_b128 v[200:203], v169 offset:3072
	s_add_u32 s30, s26, s28
	s_addc_u32 s31, s27, s29
	s_add_u32 s36, s30, 0x100
	s_addc_u32 s37, s31, 0
	s_add_u32 s30, s30, 0x180
	s_addc_u32 s31, s31, 0
	s_mov_b64 s[34:35], s[52:53]
	s_mov_b32 m0, s47
	v_lshl_add_u64 v[236:237], v[164:165], 0, s[28:29]
	ds_read_b128 v[204:207], v170
	ds_read_b128 v[208:211], v170 offset:1024
	ds_read_b128 v[212:215], v170 offset:2048
	ds_read_b128 v[216:219], v170 offset:3072
	ds_read_b128 v[220:223], v170 offset:4096
	ds_read_b128 v[224:227], v170 offset:5120
	ds_read_b128 v[228:231], v170 offset:6144
	ds_read_b128 v[232:235], v170 offset:7168
	global_load_lds_dwordx4 v[236:237], off
	v_lshl_add_u64 v[236:237], v[166:167], 0, s[28:29]
	s_mov_b32 m0, s48
	s_nop 0
	global_load_lds_dwordx4 v[236:237], off
	s_waitcnt vmcnt(8) lgkmcnt(0)
	s_barrier
	v_mfma_f32_16x16x32_bf16 v[126:129], v[172:175], v[204:207], 0
	v_mfma_f32_16x16x32_bf16 v[122:125], v[180:183], v[204:207], 0
	v_mfma_f32_16x16x32_bf16 v[110:113], v[172:175], v[212:215], 0
	v_mfma_f32_16x16x32_bf16 v[106:109], v[180:183], v[212:215], 0
	v_mfma_f32_16x16x32_bf16 v[94:97], v[172:175], v[220:223], 0
	v_mfma_f32_16x16x32_bf16 v[90:93], v[180:183], v[220:223], 0
	v_mfma_f32_16x16x32_bf16 v[78:81], v[172:175], v[228:231], 0
	v_mfma_f32_16x16x32_bf16 v[74:77], v[180:183], v[228:231], 0
	v_mfma_f32_16x16x32_bf16 v[126:129], v[176:179], v[208:211], v[126:129]
	v_mfma_f32_16x16x32_bf16 v[122:125], v[184:187], v[208:211], v[122:125]
	v_mfma_f32_16x16x32_bf16 v[110:113], v[176:179], v[216:219], v[110:113]
	v_mfma_f32_16x16x32_bf16 v[106:109], v[184:187], v[216:219], v[106:109]
	v_mfma_f32_16x16x32_bf16 v[94:97], v[176:179], v[224:227], v[94:97]
	v_mfma_f32_16x16x32_bf16 v[90:93], v[184:187], v[224:227], v[90:93]
	v_mfma_f32_16x16x32_bf16 v[78:81], v[176:179], v[232:235], v[78:81]
	v_mfma_f32_16x16x32_bf16 v[74:77], v[184:187], v[232:235], v[74:77]
	v_mfma_f32_16x16x32_bf16 v[118:121], v[188:191], v[204:207], 0
	v_mfma_f32_16x16x32_bf16 v[114:117], v[196:199], v[204:207], 0
	v_mfma_f32_16x16x32_bf16 v[102:105], v[188:191], v[212:215], 0
	v_mfma_f32_16x16x32_bf16 v[98:101], v[196:199], v[212:215], 0
	v_mfma_f32_16x16x32_bf16 v[86:89], v[188:191], v[220:223], 0
	v_mfma_f32_16x16x32_bf16 v[82:85], v[196:199], v[220:223], 0
	v_mfma_f32_16x16x32_bf16 v[70:73], v[188:191], v[228:231], 0
	v_mfma_f32_16x16x32_bf16 v[66:69], v[196:199], v[228:231], 0
	v_mfma_f32_16x16x32_bf16 v[118:121], v[192:195], v[208:211], v[118:121]
	v_mfma_f32_16x16x32_bf16 v[114:117], v[200:203], v[208:211], v[114:117]
	v_mfma_f32_16x16x32_bf16 v[102:105], v[192:195], v[216:219], v[102:105]
	v_mfma_f32_16x16x32_bf16 v[98:101], v[200:203], v[216:219], v[98:101]
	v_mfma_f32_16x16x32_bf16 v[86:89], v[192:195], v[224:227], v[86:89]
	v_mfma_f32_16x16x32_bf16 v[82:85], v[200:203], v[224:227], v[82:85]
	v_mfma_f32_16x16x32_bf16 v[70:73], v[192:195], v[232:235], v[70:73]
	v_mfma_f32_16x16x32_bf16 v[66:69], v[200:203], v[232:235], v[66:69]
	s_barrier
	s_mov_b32 m0, s49
	s_add_u32 s56, s34, 0x4000
	ds_read_b128 v[204:207], v170 offset:16384
	ds_read_b128 v[208:211], v170 offset:17408
	ds_read_b128 v[212:215], v170 offset:18432
	ds_read_b128 v[216:219], v170 offset:19456
	ds_read_b128 v[220:223], v170 offset:20480
	ds_read_b128 v[224:227], v170 offset:21504
	ds_read_b128 v[228:231], v170 offset:22528
	ds_read_b128 v[232:235], v170 offset:23552
	global_load_lds_dwordx4 v134, s[34:35]
	s_mov_b32 m0, s50
	s_addc_u32 s57, s35, 0
	s_add_i32 s55, s73, s39
	global_load_lds_dwordx4 v130, s[34:35]
	s_mov_b32 m0, s55
	s_nop 0
	global_load_lds_dwordx4 v134, s[56:57]
	s_add_i32 m0, s55, 0x2000
	s_nop 0
	global_load_lds_dwordx4 v130, s[56:57]
	s_mov_b32 m0, s25
	s_nop 0
	global_load_lds_dwordx4 v136, s[36:37]
	s_mov_b32 m0, s40
	s_nop 0
	global_load_lds_dwordx4 v132, s[36:37]
	s_waitcnt vmcnt(8) lgkmcnt(0)
	s_barrier
; #define PG8_STAGE(bufoff, gbase, voff) do { _Pragma("unroll") for (int _i = 0; _i < 2; ++_i) \
;         __builtin_amdgcn_global_load_lds((const unsigned*)((const char*)(gbase) + (voff)[_i]), (LAS unsigned*)(lds + (bufoff) + ldsw + _i * 8192), 16, 0, 0); } while (0)
; #define PG8_LDA(dst, b, h) do { _Pragma("unroll") for (int m = 0; m < 4; ++m) _Pragma("unroll") for (int k = 0; k < 2; ++k) dst[m][k] = *(const LAS bf16x8*)(lds + PG8_SA(b, h) + aoff + m * 2048 + k * 1024); } while (0)
; #define PG8_LDB(dst, b, h) do { _Pragma("unroll") for (int n = 0; n < 2; ++n) _Pragma("unroll") for (int k = 0; k < 2; ++k) dst[n][k] = *(const LAS bf16x8*)(lds + PG8_SB(b, h) + boff + n * 2048 + k * 1024); } while (0)
; #define PG8_MMA(ai, bj, At, Bt) do { __builtin_amdgcn_s_setprio(1); _Pragma("unroll") for (int m = 0; m < 4; ++m) _Pragma("unroll") for (int n = 0; n < 2; ++n) _Pragma("unroll") for (int k = 0; k < 2; ++k) \
;         acc[ai][bj][m][n] = __builtin_amdgcn_mfma_f32_16x16x32_bf16(Bt[n][k], At[m][k], acc[ai][bj][m][n], 0, 0, 0); __builtin_amdgcn_s_setprio(0); } while (0)
; #define PG8_WAIT_V(n) asm volatile("s_waitcnt vmcnt(" #n ")" ::: "memory")
; #define PG8_WAIT_L(n) asm volatile("s_waitcnt lgkmcnt(" #n ")" ::: "memory")
; #define PG8_BAR __builtin_amdgcn_s_barrier()
; #define PG8_SCHED __builtin_amdgcn_sched_barrier(0)
; template <class Epi, class Sched, bool ABLK = false, bool ALIGN_EPI = true, bool SP2 = true, bool BBLK = true>
; __device__ __forceinline__ void gemm_phase(LAS unsigned char* lds, const Gemm g, const Sched& S, const Epi& E) {
;     ...
;             PG8_WAIT_V(8); PG8_WAIT_L(0); PG8_BAR; PG8_MMA(1, 0, At, B0); PG8_MMA(1, 1, At, B1); PG8_BAR; PG8_SCHED;
;             PG8_LDB(B0, 1, 0); PG8_LDB(B1, 1, 1); PG8_SCHED; PG8_LDA(At, 1, 0); PG8_STAGE(PG8_SA(0, 1), a2 + hstepA, voffA);
;             PG8_WAIT_V(8); PG8_WAIT_L(0); PG8_BAR; PG8_MMA(0, 0, At, B0); PG8_MMA(0, 1, At, B1); PG8_BAR; PG8_SCHED;
	v_mfma_f32_16x16x32_bf16 v[62:65], v[172:175], v[204:207], 0
	v_mfma_f32_16x16x32_bf16 v[58:61], v[180:183], v[204:207], 0
	v_mfma_f32_16x16x32_bf16 v[46:49], v[172:175], v[212:215], 0
	v_mfma_f32_16x16x32_bf16 v[42:45], v[180:183], v[212:215], 0
	v_mfma_f32_16x16x32_bf16 v[30:33], v[172:175], v[220:223], 0
	v_mfma_f32_16x16x32_bf16 v[26:29], v[180:183], v[220:223], 0
	v_mfma_f32_16x16x32_bf16 v[14:17], v[172:175], v[228:231], 0
	v_mfma_f32_16x16x32_bf16 v[10:13], v[180:183], v[228:231], 0
	v_mfma_f32_16x16x32_bf16 v[62:65], v[176:179], v[208:211], v[62:65]
	v_mfma_f32_16x16x32_bf16 v[58:61], v[184:187], v[208:211], v[58:61]
	v_mfma_f32_16x16x32_bf16 v[46:49], v[176:179], v[216:219], v[46:49]
	v_mfma_f32_16x16x32_bf16 v[42:45], v[184:187], v[216:219], v[42:45]
	v_mfma_f32_16x16x32_bf16 v[30:33], v[176:179], v[224:227], v[30:33]
	v_mfma_f32_16x16x32_bf16 v[26:29], v[184:187], v[224:227], v[26:29]
	v_mfma_f32_16x16x32_bf16 v[14:17], v[176:179], v[232:235], v[14:17]
	v_mfma_f32_16x16x32_bf16 v[10:13], v[184:187], v[232:235], v[10:13]
	v_mfma_f32_16x16x32_bf16 v[54:57], v[188:191], v[204:207], 0
	v_mfma_f32_16x16x32_bf16 v[50:53], v[196:199], v[204:207], 0
	v_mfma_f32_16x16x32_bf16 v[38:41], v[188:191], v[212:215], 0
	v_mfma_f32_16x16x32_bf16 v[34:37], v[196:199], v[212:215], 0
	v_mfma_f32_16x16x32_bf16 v[22:25], v[188:191], v[220:223], 0
	v_mfma_f32_16x16x32_bf16 v[18:21], v[196:199], v[220:223], 0
	v_mfma_f32_16x16x32_bf16 v[6:9], v[188:191], v[228:231], 0
	v_mfma_f32_16x16x32_bf16 v[2:5], v[196:199], v[228:231], 0
	v_mfma_f32_16x16x32_bf16 v[54:57], v[192:195], v[208:211], v[54:57]
	v_mfma_f32_16x16x32_bf16 v[50:53], v[200:203], v[208:211], v[50:53]
	v_mfma_f32_16x16x32_bf16 v[38:41], v[192:195], v[216:219], v[38:41]
	v_mfma_f32_16x16x32_bf16 v[34:37], v[200:203], v[216:219], v[34:37]
	v_mfma_f32_16x16x32_bf16 v[22:25], v[192:195], v[224:227], v[22:25]
	v_mfma_f32_16x16x32_bf16 v[18:21], v[200:203], v[224:227], v[18:21]
	v_mfma_f32_16x16x32_bf16 v[6:9], v[192:195], v[232:235], v[6:9]
	v_mfma_f32_16x16x32_bf16 v[2:5], v[200:203], v[232:235], v[2:5]
	s_barrier
	v_add_u32_e32 v171, s60, v1
	ds_read_b128 v[172:175], v171
	ds_read_b128 v[176:179], v171 offset:1024
	ds_read_b128 v[180:183], v171 offset:2048
	ds_read_b128 v[184:187], v171 offset:3072
	v_add_u32_e32 v171, s61, v1
	ds_read_b128 v[188:191], v171
	ds_read_b128 v[192:195], v171 offset:1024
	ds_read_b128 v[196:199], v171 offset:2048
	ds_read_b128 v[200:203], v171 offset:3072
	s_add_u32 s36, s36, 0x80000
	s_addc_u32 s37, s37, 0
	s_mov_b32 m0, s41
	ds_read_b128 v[204:207], v170 offset:32768
	ds_read_b128 v[208:211], v170 offset:33792
	ds_read_b128 v[212:215], v170 offset:34816
	ds_read_b128 v[216:219], v170 offset:35840
	ds_read_b128 v[220:223], v170 offset:36864
	ds_read_b128 v[224:227], v170 offset:37888
	ds_read_b128 v[228:231], v170 offset:38912
	ds_read_b128 v[232:235], v170 offset:39936
	global_load_lds_dwordx4 v136, s[36:37]
	s_mov_b32 m0, s42
	s_nop 0
	global_load_lds_dwordx4 v132, s[36:37]
	s_waitcnt vmcnt(8) lgkmcnt(0)
	s_barrier
	v_mfma_f32_16x16x32_bf16 v[126:129], v[172:175], v[204:207], v[126:129]
	v_mfma_f32_16x16x32_bf16 v[122:125], v[180:183], v[204:207], v[122:125]
	v_mfma_f32_16x16x32_bf16 v[110:113], v[172:175], v[212:215], v[110:113]
	v_mfma_f32_16x16x32_bf16 v[106:109], v[180:183], v[212:215], v[106:109]
	v_mfma_f32_16x16x32_bf16 v[94:97], v[172:175], v[220:223], v[94:97]
	v_mfma_f32_16x16x32_bf16 v[90:93], v[180:183], v[220:223], v[90:93]
	v_mfma_f32_16x16x32_bf16 v[78:81], v[172:175], v[228:231], v[78:81]
	v_mfma_f32_16x16x32_bf16 v[74:77], v[180:183], v[228:231], v[74:77]
	v_mfma_f32_16x16x32_bf16 v[126:129], v[176:179], v[208:211], v[126:129]
	v_mfma_f32_16x16x32_bf16 v[122:125], v[184:187], v[208:211], v[122:125]
	v_mfma_f32_16x16x32_bf16 v[110:113], v[176:179], v[216:219], v[110:113]
	v_mfma_f32_16x16x32_bf16 v[106:109], v[184:187], v[216:219], v[106:109]
	v_mfma_f32_16x16x32_bf16 v[94:97], v[176:179], v[224:227], v[94:97]
	v_mfma_f32_16x16x32_bf16 v[90:93], v[184:187], v[224:227], v[90:93]
	v_mfma_f32_16x16x32_bf16 v[78:81], v[176:179], v[232:235], v[78:81]
	v_mfma_f32_16x16x32_bf16 v[74:77], v[184:187], v[232:235], v[74:77]
	v_mfma_f32_16x16x32_bf16 v[118:121], v[188:191], v[204:207], v[118:121]
	v_mfma_f32_16x16x32_bf16 v[114:117], v[196:199], v[204:207], v[114:117]
	v_mfma_f32_16x16x32_bf16 v[102:105], v[188:191], v[212:215], v[102:105]
	v_mfma_f32_16x16x32_bf16 v[98:101], v[196:199], v[212:215], v[98:101]
	v_mfma_f32_16x16x32_bf16 v[86:89], v[188:191], v[220:223], v[86:89]
	v_mfma_f32_16x16x32_bf16 v[82:85], v[196:199], v[220:223], v[82:85]
	v_mfma_f32_16x16x32_bf16 v[70:73], v[188:191], v[228:231], v[70:73]
	v_mfma_f32_16x16x32_bf16 v[66:69], v[196:199], v[228:231], v[66:69]
	v_mfma_f32_16x16x32_bf16 v[118:121], v[192:195], v[208:211], v[118:121]
	v_mfma_f32_16x16x32_bf16 v[114:117], v[200:203], v[208:211], v[114:117]
	v_mfma_f32_16x16x32_bf16 v[102:105], v[192:195], v[216:219], v[102:105]
	v_mfma_f32_16x16x32_bf16 v[98:101], v[200:203], v[216:219], v[98:101]
	v_mfma_f32_16x16x32_bf16 v[86:89], v[192:195], v[224:227], v[86:89]
	v_mfma_f32_16x16x32_bf16 v[82:85], v[200:203], v[224:227], v[82:85]
	v_mfma_f32_16x16x32_bf16 v[70:73], v[192:195], v[232:235], v[70:73]
	v_mfma_f32_16x16x32_bf16 v[66:69], v[200:203], v[232:235], v[66:69]
	s_barrier
; #define PG8_STAGE(bufoff, gbase, voff) do { _Pragma("unroll") for (int _i = 0; _i < 2; ++_i) \
;         __builtin_amdgcn_global_load_lds((const unsigned*)((const char*)(gbase) + (voff)[_i]), (LAS unsigned*)(lds + (bufoff) + ldsw + _i * 8192), 16, 0, 0); } while (0)
; #define PG8_LDA(dst, b, h) do { _Pragma("unroll") for (int m = 0; m < 4; ++m) _Pragma("unroll") for (int k = 0; k < 2; ++k) dst[m][k] = *(const LAS bf16x8*)(lds + PG8_SA(b, h) + aoff + m * 2048 + k * 1024); } while (0)
; #define PG8_WAIT_V(n) asm volatile("s_waitcnt vmcnt(" #n ")" ::: "memory")
; #define PG8_WAIT_L(n) asm volatile("s_waitcnt lgkmcnt(" #n ")" ::: "memory")
; template <class Epi, class Sched, bool ABLK = false, bool ALIGN_EPI = true, bool SP2 = true, bool BBLK = true>
; __device__ __forceinline__ void gemm_phase(LAS unsigned char* lds, const Gemm g, const Sched& S, const Epi& E) {
;     ...
;         for (int t = 0; t < nt; t += 2) {
;             const bool last = (t == nt - 2);
;             const char* a1 = a_tile(uA, tbA + t + 1);
;             const char* a2 = last ? a_tile(nuA, ntbA) : a_tile(uA, tbA + t + 2); const char* b2 = last ? nB : cB + (size_t)(t + 2) * kstepB;
;             const char* a3 = last ? a_tile(nuA, ntbA + 1) : a_tile(uA, tbA + t + 3); const char* b3 = b2 + kstepB;
;             if (last && has_next) S.a_ready(nxt);
;             if constexpr (SP2) {
;             PG8_LDB(B0, 0, 0); PG8_LDB(B1, 0, 1); PG8_SCHED; PG8_LDA(At, 0, 0); PG8_STAGE(PG8_SA(1, 1), a1 + hstepA, voffA);
;             PG8_WAIT_V(8); PG8_WAIT_L(0); PG8_BAR; PG8_MMA(0, 0, At, B0); PG8_MMA(0, 1, At, B1); PG8_BAR; PG8_SCHED;
;             PG8_LDA(At, 0, 1); PG8_STAGE(PG8_SB(0, 0), b2, voffB); PG8_STAGE(PG8_SB(0, 1), b2 + hstepB, voffB); PG8_STAGE(PG8_SA(0, 0), a2, voffA);
;             PG8_WAIT_V(8); PG8_WAIT_L(0); PG8_BAR; PG8_MMA(1, 0, At, B0); PG8_MMA(1, 1, At, B1); PG8_BAR; PG8_SCHED;
;             PG8_LDB(B0, 1, 0); PG8_LDB(B1, 1, 1); PG8_SCHED; PG8_LDA(At, 1, 0); PG8_STAGE(PG8_SA(0, 1), a2 + hstepA, voffA);
;             PG8_WAIT_V(8); PG8_WAIT_L(0); PG8_BAR; PG8_MMA(0, 0, At, B0); PG8_MMA(0, 1, At, B1); PG8_BAR; PG8_SCHED;
;             PG8_LDA(At, 1, 1); PG8_STAGE(PG8_SB(1, 0), b3, voffB); PG8_STAGE(PG8_SB(1, 1), b3 + hstepB, voffB); PG8_STAGE(PG8_SA(1, 0), a3, voffA);
;             PG8_WAIT_V(8); PG8_WAIT_L(0); PG8_BAR; PG8_MMA(1, 0, At, B0); PG8_MMA(1, 1, At, B1); PG8_BAR; PG8_SCHED;
	s_add_u32 s36, s34, 0x8000
	s_addc_u32 s37, s35, 0
	s_add_i32 s55, s60, s39
	s_mov_b32 m0, s55
	ds_read_b128 v[204:207], v170 offset:49152
	ds_read_b128 v[208:211], v170 offset:50176
	ds_read_b128 v[212:215], v170 offset:51200
	ds_read_b128 v[216:219], v170 offset:52224
	ds_read_b128 v[220:223], v170 offset:53248
	ds_read_b128 v[224:227], v170 offset:54272
	ds_read_b128 v[228:231], v170 offset:55296
	ds_read_b128 v[232:235], v170 offset:56320
	global_load_lds_dwordx4 v134, s[36:37]
	s_add_i32 m0, s55, 0x2000
	s_add_u32 s34, s34, 0xc000
	v_lshl_add_u64 v[236:237], s[36:37], 0, v[130:131]
	s_addc_u32 s35, s35, 0
	s_add_i32 s36, s61, s39
	global_load_lds_dwordx4 v[236:237], off
	s_mov_b32 m0, s36
	s_nop 0
	global_load_lds_dwordx4 v134, s[34:35]
	s_add_i32 m0, s36, 0x2000
	s_nop 0
	global_load_lds_dwordx4 v130, s[34:35]
	s_mov_b32 m0, s45
	s_nop 0
	global_load_lds_dwordx4 v136, s[30:31]
	s_mov_b32 m0, s46
	s_nop 0
	global_load_lds_dwordx4 v132, s[30:31]
	s_waitcnt vmcnt(8) lgkmcnt(0)
	s_barrier
	v_mfma_f32_16x16x32_bf16 v[62:65], v[172:175], v[204:207], v[62:65]
	v_mfma_f32_16x16x32_bf16 v[58:61], v[180:183], v[204:207], v[58:61]
	v_mfma_f32_16x16x32_bf16 v[46:49], v[172:175], v[212:215], v[46:49]
	v_mfma_f32_16x16x32_bf16 v[42:45], v[180:183], v[212:215], v[42:45]
	v_mfma_f32_16x16x32_bf16 v[30:33], v[172:175], v[220:223], v[30:33]
	v_mfma_f32_16x16x32_bf16 v[26:29], v[180:183], v[220:223], v[26:29]
	v_mfma_f32_16x16x32_bf16 v[14:17], v[172:175], v[228:231], v[14:17]
	v_mfma_f32_16x16x32_bf16 v[10:13], v[180:183], v[228:231], v[10:13]
	v_mfma_f32_16x16x32_bf16 v[62:65], v[176:179], v[208:211], v[62:65]
	v_mfma_f32_16x16x32_bf16 v[58:61], v[184:187], v[208:211], v[58:61]
	v_mfma_f32_16x16x32_bf16 v[46:49], v[176:179], v[216:219], v[46:49]
	v_mfma_f32_16x16x32_bf16 v[42:45], v[184:187], v[216:219], v[42:45]
	v_mfma_f32_16x16x32_bf16 v[30:33], v[176:179], v[224:227], v[30:33]
	v_mfma_f32_16x16x32_bf16 v[26:29], v[184:187], v[224:227], v[26:29]
	v_mfma_f32_16x16x32_bf16 v[14:17], v[176:179], v[232:235], v[14:17]
	v_mfma_f32_16x16x32_bf16 v[10:13], v[184:187], v[232:235], v[10:13]
	v_mfma_f32_16x16x32_bf16 v[54:57], v[188:191], v[204:207], v[54:57]
	v_mfma_f32_16x16x32_bf16 v[50:53], v[196:199], v[204:207], v[50:53]
	v_mfma_f32_16x16x32_bf16 v[38:41], v[188:191], v[212:215], v[38:41]
	v_mfma_f32_16x16x32_bf16 v[34:37], v[196:199], v[212:215], v[34:37]
	v_mfma_f32_16x16x32_bf16 v[22:25], v[188:191], v[220:223], v[22:25]
	v_mfma_f32_16x16x32_bf16 v[18:21], v[196:199], v[220:223], v[18:21]
	v_mfma_f32_16x16x32_bf16 v[6:9], v[188:191], v[228:231], v[6:9]
	v_mfma_f32_16x16x32_bf16 v[2:5], v[196:199], v[228:231], v[2:5]
	v_mfma_f32_16x16x32_bf16 v[54:57], v[192:195], v[208:211], v[54:57]
	v_mfma_f32_16x16x32_bf16 v[50:53], v[200:203], v[208:211], v[50:53]
	v_mfma_f32_16x16x32_bf16 v[38:41], v[192:195], v[216:219], v[38:41]
	v_mfma_f32_16x16x32_bf16 v[34:37], v[200:203], v[216:219], v[34:37]
	v_mfma_f32_16x16x32_bf16 v[22:25], v[192:195], v[224:227], v[22:25]
	v_mfma_f32_16x16x32_bf16 v[18:21], v[200:203], v[224:227], v[18:21]
	v_mfma_f32_16x16x32_bf16 v[6:9], v[192:195], v[232:235], v[6:9]
	v_mfma_f32_16x16x32_bf16 v[2:5], v[200:203], v[232:235], v[2:5]
	s_barrier
	s_add_i32 s54, s54, 2
	s_add_u32 s28, s28, 0x100
	s_addc_u32 s29, s29, 0
	s_add_u32 s52, s52, 0x10000
	s_addc_u32 s53, s53, 0
	s_cmp_gt_u32 s54, 29
.LBB0_1842:
	ds_read_b128 v[172:175], v168
	ds_read_b128 v[176:179], v168 offset:1024
	ds_read_b128 v[180:183], v168 offset:2048
	ds_read_b128 v[184:187], v168 offset:3072
	ds_read_b128 v[188:191], v169
	ds_read_b128 v[192:195], v169 offset:1024
	ds_read_b128 v[196:199], v169 offset:2048
	ds_read_b128 v[200:203], v169 offset:3072
	s_add_u32 s30, s26, s28
	s_addc_u32 s31, s27, s29
	s_add_u32 s36, s30, 0x100
	s_addc_u32 s37, s31, 0
	s_add_u32 s30, s30, 0x180
	s_addc_u32 s31, s31, 0
	s_cmpk_eq_i32 s28, 0xf00
	s_cbranch_scc1 .Lksel_19
	s_mov_b64 s[34:35], s[52:53]
.Lksel_19_back:
	s_mov_b32 m0, s47
	v_lshl_add_u64 v[236:237], v[164:165], 0, s[28:29]
	ds_read_b128 v[204:207], v170
	ds_read_b128 v[208:211], v170 offset:1024
	ds_read_b128 v[212:215], v170 offset:2048
	ds_read_b128 v[216:219], v170 offset:3072
	ds_read_b128 v[220:223], v170 offset:4096
	ds_read_b128 v[224:227], v170 offset:5120
	ds_read_b128 v[228:231], v170 offset:6144
	ds_read_b128 v[232:235], v170 offset:7168
	global_load_lds_dwordx4 v[236:237], off
	v_lshl_add_u64 v[236:237], v[166:167], 0, s[28:29]
	s_mov_b32 m0, s48
	s_nop 0
	global_load_lds_dwordx4 v[236:237], off
	s_waitcnt vmcnt(8) lgkmcnt(0)
	s_barrier
; #define PG8_STAGE(bufoff, gbase, voff) do { _Pragma("unroll") for (int _i = 0; _i < 2; ++_i) \
;         __builtin_amdgcn_global_load_lds((const unsigned*)((const char*)(gbase) + (voff)[_i]), (LAS unsigned*)(lds + (bufoff) + ldsw + _i * 8192), 16, 0, 0); } while (0)
; #define PG8_LDA(dst, b, h) do { _Pragma("unroll") for (int m = 0; m < 4; ++m) _Pragma("unroll") for (int k = 0; k < 2; ++k) dst[m][k] = *(const LAS bf16x8*)(lds + PG8_SA(b, h) + aoff + m * 2048 + k * 1024); } while (0)
; #define PG8_LDB(dst, b, h) do { _Pragma("unroll") for (int n = 0; n < 2; ++n) _Pragma("unroll") for (int k = 0; k < 2; ++k) dst[n][k] = *(const LAS bf16x8*)(lds + PG8_SB(b, h) + boff + n * 2048 + k * 1024); } while (0)
; #define PG8_MMA(ai, bj, At, Bt) do { __builtin_amdgcn_s_setprio(1); _Pragma("unroll") for (int m = 0; m < 4; ++m) _Pragma("unroll") for (int n = 0; n < 2; ++n) _Pragma("unroll") for (int k = 0; k < 2; ++k) \
;         acc[ai][bj][m][n] = __builtin_amdgcn_mfma_f32_16x16x32_bf16(Bt[n][k], At[m][k], acc[ai][bj][m][n], 0, 0, 0); __builtin_amdgcn_s_setprio(0); } while (0)
; #define PG8_WAIT_V(n) asm volatile("s_waitcnt vmcnt(" #n ")" ::: "memory")
; #define PG8_WAIT_L(n) asm volatile("s_waitcnt lgkmcnt(" #n ")" ::: "memory")
; #define PG8_BAR __builtin_amdgcn_s_barrier()
; #define PG8_SCHED __builtin_amdgcn_sched_barrier(0)
; template <class Epi, class Sched, bool ABLK = false, bool ALIGN_EPI = true, bool SP2 = true, bool BBLK = true>
; __device__ __forceinline__ void gemm_phase(LAS unsigned char* lds, const Gemm g, const Sched& S, const Epi& E) {
;     ...
;             PG8_LDB(B0, 0, 0); PG8_LDB(B1, 0, 1); PG8_SCHED; PG8_LDA(At, 0, 0); PG8_STAGE(PG8_SA(1, 1), a1 + hstepA, voffA);
;             PG8_WAIT_V(8); PG8_WAIT_L(0); PG8_BAR; PG8_MMA(0, 0, At, B0); PG8_MMA(0, 1, At, B1); PG8_BAR; PG8_SCHED;
;             PG8_LDA(At, 0, 1); PG8_STAGE(PG8_SB(0, 0), b2, voffB); PG8_STAGE(PG8_SB(0, 1), b2 + hstepB, voffB); PG8_STAGE(PG8_SA(0, 0), a2, voffA);
;             PG8_WAIT_V(8); PG8_WAIT_L(0); PG8_BAR; PG8_MMA(1, 0, At, B0); PG8_MMA(1, 1, At, B1); PG8_BAR; PG8_SCHED;
;             PG8_LDB(B0, 1, 0); PG8_LDB(B1, 1, 1); PG8_SCHED; PG8_LDA(At, 1, 0); PG8_STAGE(PG8_SA(0, 1), a2 + hstepA, voffA);
;             PG8_WAIT_V(8); PG8_WAIT_L(0); PG8_BAR; PG8_MMA(0, 0, At, B0); PG8_MMA(0, 1, At, B1); PG8_BAR; PG8_SCHED;
	v_mfma_f32_16x16x32_bf16 v[126:129], v[172:175], v[204:207], v[126:129]
	v_mfma_f32_16x16x32_bf16 v[122:125], v[180:183], v[204:207], v[122:125]
	v_mfma_f32_16x16x32_bf16 v[110:113], v[172:175], v[212:215], v[110:113]
	v_mfma_f32_16x16x32_bf16 v[106:109], v[180:183], v[212:215], v[106:109]
	v_mfma_f32_16x16x32_bf16 v[94:97], v[172:175], v[220:223], v[94:97]
	v_mfma_f32_16x16x32_bf16 v[90:93], v[180:183], v[220:223], v[90:93]
	v_mfma_f32_16x16x32_bf16 v[78:81], v[172:175], v[228:231], v[78:81]
	v_mfma_f32_16x16x32_bf16 v[74:77], v[180:183], v[228:231], v[74:77]
	v_mfma_f32_16x16x32_bf16 v[126:129], v[176:179], v[208:211], v[126:129]
	v_mfma_f32_16x16x32_bf16 v[122:125], v[184:187], v[208:211], v[122:125]
	v_mfma_f32_16x16x32_bf16 v[110:113], v[176:179], v[216:219], v[110:113]
	v_mfma_f32_16x16x32_bf16 v[106:109], v[184:187], v[216:219], v[106:109]
	v_mfma_f32_16x16x32_bf16 v[94:97], v[176:179], v[224:227], v[94:97]
	v_mfma_f32_16x16x32_bf16 v[90:93], v[184:187], v[224:227], v[90:93]
	v_mfma_f32_16x16x32_bf16 v[78:81], v[176:179], v[232:235], v[78:81]
	v_mfma_f32_16x16x32_bf16 v[74:77], v[184:187], v[232:235], v[74:77]
	v_mfma_f32_16x16x32_bf16 v[118:121], v[188:191], v[204:207], v[118:121]
	v_mfma_f32_16x16x32_bf16 v[114:117], v[196:199], v[204:207], v[114:117]
	v_mfma_f32_16x16x32_bf16 v[102:105], v[188:191], v[212:215], v[102:105]
	v_mfma_f32_16x16x32_bf16 v[98:101], v[196:199], v[212:215], v[98:101]
	v_mfma_f32_16x16x32_bf16 v[86:89], v[188:191], v[220:223], v[86:89]
	v_mfma_f32_16x16x32_bf16 v[82:85], v[196:199], v[220:223], v[82:85]
	v_mfma_f32_16x16x32_bf16 v[70:73], v[188:191], v[228:231], v[70:73]
	v_mfma_f32_16x16x32_bf16 v[66:69], v[196:199], v[228:231], v[66:69]
	v_mfma_f32_16x16x32_bf16 v[118:121], v[192:195], v[208:211], v[118:121]
	v_mfma_f32_16x16x32_bf16 v[114:117], v[200:203], v[208:211], v[114:117]
	v_mfma_f32_16x16x32_bf16 v[102:105], v[192:195], v[216:219], v[102:105]
	v_mfma_f32_16x16x32_bf16 v[98:101], v[200:203], v[216:219], v[98:101]
	v_mfma_f32_16x16x32_bf16 v[86:89], v[192:195], v[224:227], v[86:89]
	v_mfma_f32_16x16x32_bf16 v[82:85], v[200:203], v[224:227], v[82:85]
	v_mfma_f32_16x16x32_bf16 v[70:73], v[192:195], v[232:235], v[70:73]
	v_mfma_f32_16x16x32_bf16 v[66:69], v[200:203], v[232:235], v[66:69]
	s_barrier
	s_mov_b32 m0, s49
	s_add_u32 s56, s34, 0x4000
	ds_read_b128 v[204:207], v170 offset:16384
	ds_read_b128 v[208:211], v170 offset:17408
	ds_read_b128 v[212:215], v170 offset:18432
	ds_read_b128 v[216:219], v170 offset:19456
	ds_read_b128 v[220:223], v170 offset:20480
	ds_read_b128 v[224:227], v170 offset:21504
	ds_read_b128 v[228:231], v170 offset:22528
	ds_read_b128 v[232:235], v170 offset:23552
	global_load_lds_dwordx4 v134, s[34:35]
	s_mov_b32 m0, s50
	s_addc_u32 s57, s35, 0
	s_add_i32 s55, s73, s39
	global_load_lds_dwordx4 v130, s[34:35]
	s_mov_b32 m0, s55
	s_nop 0
	global_load_lds_dwordx4 v134, s[56:57]
	s_add_i32 m0, s55, 0x2000
	s_nop 0
	global_load_lds_dwordx4 v130, s[56:57]
	s_mov_b32 m0, s25
	s_nop 0
	global_load_lds_dwordx4 v136, s[36:37]
	s_mov_b32 m0, s40
	s_nop 0
	global_load_lds_dwordx4 v132, s[36:37]
	s_waitcnt vmcnt(8) lgkmcnt(0)
	s_barrier
	v_mfma_f32_16x16x32_bf16 v[62:65], v[172:175], v[204:207], v[62:65]
	v_mfma_f32_16x16x32_bf16 v[58:61], v[180:183], v[204:207], v[58:61]
	v_mfma_f32_16x16x32_bf16 v[46:49], v[172:175], v[212:215], v[46:49]
	v_mfma_f32_16x16x32_bf16 v[42:45], v[180:183], v[212:215], v[42:45]
	v_mfma_f32_16x16x32_bf16 v[30:33], v[172:175], v[220:223], v[30:33]
	v_mfma_f32_16x16x32_bf16 v[26:29], v[180:183], v[220:223], v[26:29]
	v_mfma_f32_16x16x32_bf16 v[14:17], v[172:175], v[228:231], v[14:17]
	v_mfma_f32_16x16x32_bf16 v[10:13], v[180:183], v[228:231], v[10:13]
	v_mfma_f32_16x16x32_bf16 v[62:65], v[176:179], v[208:211], v[62:65]
	v_mfma_f32_16x16x32_bf16 v[58:61], v[184:187], v[208:211], v[58:61]
	v_mfma_f32_16x16x32_bf16 v[46:49], v[176:179], v[216:219], v[46:49]
	v_mfma_f32_16x16x32_bf16 v[42:45], v[184:187], v[216:219], v[42:45]
	v_mfma_f32_16x16x32_bf16 v[30:33], v[176:179], v[224:227], v[30:33]
	v_mfma_f32_16x16x32_bf16 v[26:29], v[184:187], v[224:227], v[26:29]
	v_mfma_f32_16x16x32_bf16 v[14:17], v[176:179], v[232:235], v[14:17]
	v_mfma_f32_16x16x32_bf16 v[10:13], v[184:187], v[232:235], v[10:13]
	v_mfma_f32_16x16x32_bf16 v[54:57], v[188:191], v[204:207], v[54:57]
	v_mfma_f32_16x16x32_bf16 v[50:53], v[196:199], v[204:207], v[50:53]
	v_mfma_f32_16x16x32_bf16 v[38:41], v[188:191], v[212:215], v[38:41]
	v_mfma_f32_16x16x32_bf16 v[34:37], v[196:199], v[212:215], v[34:37]
	v_mfma_f32_16x16x32_bf16 v[22:25], v[188:191], v[220:223], v[22:25]
	v_mfma_f32_16x16x32_bf16 v[18:21], v[196:199], v[220:223], v[18:21]
	v_mfma_f32_16x16x32_bf16 v[6:9], v[188:191], v[228:231], v[6:9]
	v_mfma_f32_16x16x32_bf16 v[2:5], v[196:199], v[228:231], v[2:5]
	v_mfma_f32_16x16x32_bf16 v[54:57], v[192:195], v[208:211], v[54:57]
	v_mfma_f32_16x16x32_bf16 v[50:53], v[200:203], v[208:211], v[50:53]
	v_mfma_f32_16x16x32_bf16 v[38:41], v[192:195], v[216:219], v[38:41]
	v_mfma_f32_16x16x32_bf16 v[34:37], v[200:203], v[216:219], v[34:37]
	v_mfma_f32_16x16x32_bf16 v[22:25], v[192:195], v[224:227], v[22:25]
	v_mfma_f32_16x16x32_bf16 v[18:21], v[200:203], v[224:227], v[18:21]
	v_mfma_f32_16x16x32_bf16 v[6:9], v[192:195], v[232:235], v[6:9]
	v_mfma_f32_16x16x32_bf16 v[2:5], v[200:203], v[232:235], v[2:5]
	s_barrier
; #define PG8_STAGE(bufoff, gbase, voff) do { _Pragma("unroll") for (int _i = 0; _i < 2; ++_i) \
;         __builtin_amdgcn_global_load_lds((const unsigned*)((const char*)(gbase) + (voff)[_i]), (LAS unsigned*)(lds + (bufoff) + ldsw + _i * 8192), 16, 0, 0); } while (0)
; #define PG8_LDA(dst, b, h) do { _Pragma("unroll") for (int m = 0; m < 4; ++m) _Pragma("unroll") for (int k = 0; k < 2; ++k) dst[m][k] = *(const LAS bf16x8*)(lds + PG8_SA(b, h) + aoff + m * 2048 + k * 1024); } while (0)
; #define PG8_LDB(dst, b, h) do { _Pragma("unroll") for (int n = 0; n < 2; ++n) _Pragma("unroll") for (int k = 0; k < 2; ++k) dst[n][k] = *(const LAS bf16x8*)(lds + PG8_SB(b, h) + boff + n * 2048 + k * 1024); } while (0)
; #define PG8_MMA(ai, bj, At, Bt) do { __builtin_amdgcn_s_setprio(1); _Pragma("unroll") for (int m = 0; m < 4; ++m) _Pragma("unroll") for (int n = 0; n < 2; ++n) _Pragma("unroll") for (int k = 0; k < 2; ++k) \
;         acc[ai][bj][m][n] = __builtin_amdgcn_mfma_f32_16x16x32_bf16(Bt[n][k], At[m][k], acc[ai][bj][m][n], 0, 0, 0); __builtin_amdgcn_s_setprio(0); } while (0)
; #define PG8_WAIT_V(n) asm volatile("s_waitcnt vmcnt(" #n ")" ::: "memory")
; #define PG8_WAIT_L(n) asm volatile("s_waitcnt lgkmcnt(" #n ")" ::: "memory")
; #define PG8_BAR __builtin_amdgcn_s_barrier()
; #define PG8_SCHED __builtin_amdgcn_sched_barrier(0)
; template <class Epi, class Sched, bool ABLK = false, bool ALIGN_EPI = true, bool SP2 = true, bool BBLK = true>
; __device__ __forceinline__ void gemm_phase(LAS unsigned char* lds, const Gemm g, const Sched& S, const Epi& E) {
;     ...
;             PG8_LDB(B0, 1, 0); PG8_LDB(B1, 1, 1); PG8_SCHED; PG8_LDA(At, 1, 0); PG8_STAGE(PG8_SA(0, 1), a2 + hstepA, voffA);
;             PG8_WAIT_V(8); PG8_WAIT_L(0); PG8_BAR; PG8_MMA(0, 0, At, B0); PG8_MMA(0, 1, At, B1); PG8_BAR; PG8_SCHED;
;             PG8_LDA(At, 1, 1); PG8_STAGE(PG8_SB(1, 0), b3, voffB); PG8_STAGE(PG8_SB(1, 1), b3 + hstepB, voffB); PG8_STAGE(PG8_SA(1, 0), a3, voffA);
;             PG8_WAIT_V(8); PG8_WAIT_L(0); PG8_BAR; PG8_MMA(1, 0, At, B0); PG8_MMA(1, 1, At, B1); PG8_BAR; PG8_SCHED;
;     ...
;         if constexpr (ALIGN_EPI) { if (wr == 0) PG8_BAR; }
;         E(acc, cur, wr, wc, fr, fq); S.done(cur);
;         if (!has_next) break;
	v_add_u32_e32 v171, s60, v1
	ds_read_b128 v[172:175], v171
	ds_read_b128 v[176:179], v171 offset:1024
	ds_read_b128 v[180:183], v171 offset:2048
	ds_read_b128 v[184:187], v171 offset:3072
	v_add_u32_e32 v171, s61, v1
	ds_read_b128 v[188:191], v171
	ds_read_b128 v[192:195], v171 offset:1024
	ds_read_b128 v[196:199], v171 offset:2048
	ds_read_b128 v[200:203], v171 offset:3072
	s_add_u32 s36, s36, 0x80000
	s_addc_u32 s37, s37, 0
	s_mov_b32 m0, s41
	ds_read_b128 v[204:207], v170 offset:32768
	ds_read_b128 v[208:211], v170 offset:33792
	ds_read_b128 v[212:215], v170 offset:34816
	ds_read_b128 v[216:219], v170 offset:35840
	ds_read_b128 v[220:223], v170 offset:36864
	ds_read_b128 v[224:227], v170 offset:37888
	ds_read_b128 v[228:231], v170 offset:38912
	ds_read_b128 v[232:235], v170 offset:39936
	global_load_lds_dwordx4 v136, s[36:37]
	s_mov_b32 m0, s42
	s_nop 0
	global_load_lds_dwordx4 v132, s[36:37]
	s_waitcnt vmcnt(8) lgkmcnt(0)
	s_barrier
	v_mfma_f32_16x16x32_bf16 v[126:129], v[172:175], v[204:207], v[126:129]
	v_mfma_f32_16x16x32_bf16 v[122:125], v[180:183], v[204:207], v[122:125]
	v_mfma_f32_16x16x32_bf16 v[110:113], v[172:175], v[212:215], v[110:113]
	v_mfma_f32_16x16x32_bf16 v[106:109], v[180:183], v[212:215], v[106:109]
	v_mfma_f32_16x16x32_bf16 v[94:97], v[172:175], v[220:223], v[94:97]
	v_mfma_f32_16x16x32_bf16 v[90:93], v[180:183], v[220:223], v[90:93]
	v_mfma_f32_16x16x32_bf16 v[78:81], v[172:175], v[228:231], v[78:81]
	v_mfma_f32_16x16x32_bf16 v[74:77], v[180:183], v[228:231], v[74:77]
	v_mfma_f32_16x16x32_bf16 v[126:129], v[176:179], v[208:211], v[126:129]
	v_mfma_f32_16x16x32_bf16 v[122:125], v[184:187], v[208:211], v[122:125]
	v_mfma_f32_16x16x32_bf16 v[110:113], v[176:179], v[216:219], v[110:113]
	v_mfma_f32_16x16x32_bf16 v[106:109], v[184:187], v[216:219], v[106:109]
	v_mfma_f32_16x16x32_bf16 v[94:97], v[176:179], v[224:227], v[94:97]
	v_mfma_f32_16x16x32_bf16 v[90:93], v[184:187], v[224:227], v[90:93]
	v_mfma_f32_16x16x32_bf16 v[78:81], v[176:179], v[232:235], v[78:81]
	v_mfma_f32_16x16x32_bf16 v[74:77], v[184:187], v[232:235], v[74:77]
	v_mfma_f32_16x16x32_bf16 v[118:121], v[188:191], v[204:207], v[118:121]
	v_mfma_f32_16x16x32_bf16 v[114:117], v[196:199], v[204:207], v[114:117]
	v_mfma_f32_16x16x32_bf16 v[102:105], v[188:191], v[212:215], v[102:105]
	v_mfma_f32_16x16x32_bf16 v[98:101], v[196:199], v[212:215], v[98:101]
	v_mfma_f32_16x16x32_bf16 v[86:89], v[188:191], v[220:223], v[86:89]
	v_mfma_f32_16x16x32_bf16 v[82:85], v[196:199], v[220:223], v[82:85]
	v_mfma_f32_16x16x32_bf16 v[70:73], v[188:191], v[228:231], v[70:73]
	v_mfma_f32_16x16x32_bf16 v[66:69], v[196:199], v[228:231], v[66:69]
	v_mfma_f32_16x16x32_bf16 v[118:121], v[192:195], v[208:211], v[118:121]
	v_mfma_f32_16x16x32_bf16 v[114:117], v[200:203], v[208:211], v[114:117]
	v_mfma_f32_16x16x32_bf16 v[102:105], v[192:195], v[216:219], v[102:105]
	v_mfma_f32_16x16x32_bf16 v[98:101], v[200:203], v[216:219], v[98:101]
	v_mfma_f32_16x16x32_bf16 v[86:89], v[192:195], v[224:227], v[86:89]
	v_mfma_f32_16x16x32_bf16 v[82:85], v[200:203], v[224:227], v[82:85]
	v_mfma_f32_16x16x32_bf16 v[70:73], v[192:195], v[232:235], v[70:73]
	v_mfma_f32_16x16x32_bf16 v[66:69], v[200:203], v[232:235], v[66:69]
	s_barrier
	s_add_u32 s36, s34, 0x8000
	s_addc_u32 s37, s35, 0
	s_add_i32 s55, s60, s39
	s_mov_b32 m0, s55
	ds_read_b128 v[204:207], v170 offset:49152
	ds_read_b128 v[208:211], v170 offset:50176
	ds_read_b128 v[212:215], v170 offset:51200
	ds_read_b128 v[216:219], v170 offset:52224
	ds_read_b128 v[220:223], v170 offset:53248
	ds_read_b128 v[224:227], v170 offset:54272
	ds_read_b128 v[228:231], v170 offset:55296
	ds_read_b128 v[232:235], v170 offset:56320
	global_load_lds_dwordx4 v134, s[36:37]
	s_add_i32 m0, s55, 0x2000
	s_add_u32 s34, s34, 0xc000
	v_lshl_add_u64 v[236:237], s[36:37], 0, v[130:131]
	s_addc_u32 s35, s35, 0
	s_add_i32 s36, s61, s39
	global_load_lds_dwordx4 v[236:237], off
	s_mov_b32 m0, s36
	s_nop 0
	global_load_lds_dwordx4 v134, s[34:35]
	s_add_i32 m0, s36, 0x2000
	s_nop 0
	global_load_lds_dwordx4 v130, s[34:35]
	s_mov_b32 m0, s45
	s_nop 0
	global_load_lds_dwordx4 v136, s[30:31]
	s_mov_b32 m0, s46
	s_nop 0
	global_load_lds_dwordx4 v132, s[30:31]
	s_waitcnt vmcnt(8) lgkmcnt(0)
	s_barrier
	v_mfma_f32_16x16x32_bf16 v[62:65], v[172:175], v[204:207], v[62:65]
	v_mfma_f32_16x16x32_bf16 v[58:61], v[180:183], v[204:207], v[58:61]
	v_mfma_f32_16x16x32_bf16 v[46:49], v[172:175], v[212:215], v[46:49]
	v_mfma_f32_16x16x32_bf16 v[42:45], v[180:183], v[212:215], v[42:45]
	v_mfma_f32_16x16x32_bf16 v[30:33], v[172:175], v[220:223], v[30:33]
	v_mfma_f32_16x16x32_bf16 v[26:29], v[180:183], v[220:223], v[26:29]
	v_mfma_f32_16x16x32_bf16 v[14:17], v[172:175], v[228:231], v[14:17]
	v_mfma_f32_16x16x32_bf16 v[10:13], v[180:183], v[228:231], v[10:13]
	v_mfma_f32_16x16x32_bf16 v[62:65], v[176:179], v[208:211], v[62:65]
	v_mfma_f32_16x16x32_bf16 v[58:61], v[184:187], v[208:211], v[58:61]
	v_mfma_f32_16x16x32_bf16 v[46:49], v[176:179], v[216:219], v[46:49]
	v_mfma_f32_16x16x32_bf16 v[42:45], v[184:187], v[216:219], v[42:45]
	v_mfma_f32_16x16x32_bf16 v[30:33], v[176:179], v[224:227], v[30:33]
	v_mfma_f32_16x16x32_bf16 v[26:29], v[184:187], v[224:227], v[26:29]
	v_mfma_f32_16x16x32_bf16 v[14:17], v[176:179], v[232:235], v[14:17]
	v_mfma_f32_16x16x32_bf16 v[10:13], v[184:187], v[232:235], v[10:13]
	v_mfma_f32_16x16x32_bf16 v[54:57], v[188:191], v[204:207], v[54:57]
	v_mfma_f32_16x16x32_bf16 v[50:53], v[196:199], v[204:207], v[50:53]
	v_mfma_f32_16x16x32_bf16 v[38:41], v[188:191], v[212:215], v[38:41]
	v_mfma_f32_16x16x32_bf16 v[34:37], v[196:199], v[212:215], v[34:37]
	v_mfma_f32_16x16x32_bf16 v[22:25], v[188:191], v[220:223], v[22:25]
	v_mfma_f32_16x16x32_bf16 v[18:21], v[196:199], v[220:223], v[18:21]
	v_mfma_f32_16x16x32_bf16 v[6:9], v[188:191], v[228:231], v[6:9]
	v_mfma_f32_16x16x32_bf16 v[2:5], v[196:199], v[228:231], v[2:5]
	v_mfma_f32_16x16x32_bf16 v[54:57], v[192:195], v[208:211], v[54:57]
	v_mfma_f32_16x16x32_bf16 v[50:53], v[200:203], v[208:211], v[50:53]
	v_mfma_f32_16x16x32_bf16 v[38:41], v[192:195], v[216:219], v[38:41]
	v_mfma_f32_16x16x32_bf16 v[34:37], v[200:203], v[216:219], v[34:37]
	v_mfma_f32_16x16x32_bf16 v[22:25], v[192:195], v[224:227], v[22:25]
	v_mfma_f32_16x16x32_bf16 v[18:21], v[200:203], v[224:227], v[18:21]
	v_mfma_f32_16x16x32_bf16 v[6:9], v[192:195], v[232:235], v[6:9]
	v_mfma_f32_16x16x32_bf16 v[2:5], v[200:203], v[232:235], v[2:5]
	s_barrier
	s_add_i32 s54, s54, 2
	s_add_u32 s28, s28, 0x100
	s_addc_u32 s29, s29, 0
	s_add_u32 s52, s52, 0x10000
	s_addc_u32 s53, s53, 0
	s_cmp_gt_u32 s54, 29
	s_cbranch_scc0 .LBB0_1842
	s_and_b64 vcc, exec, s[6:7]
	s_cbranch_vccz .LBB0_1845
	s_barrier

; template <class Epi, class Sched, bool ABLK = false, bool ALIGN_EPI = true, bool SP2 = true, bool BBLK = true>
; __device__ __forceinline__ void gemm_phase(LAS unsigned char* lds, const Gemm g, const Sched& S, const Epi& E) {
;     ...
;             const char* a2 = last ? a_tile(nuA, ntbA) : a_tile(uA, tbA + t + 2); const char* b2 = last ? nB : cB + (size_t)(t + 2) * kstepB;
;             const char* a3 = last ? a_tile(nuA, ntbA + 1) : a_tile(uA, tbA + t + 3); const char* b3 = b2 + kstepB;
.Lksel_19:
	s_mov_b32 s31, s51
	s_mov_b32 s30, s23
	s_mov_b32 s35, s11
	s_mov_b32 s34, s15
	s_mov_b32 s37, s4
	s_mov_b32 s36, s5
	s_branch .Lksel_19_back

; template <class Epi, class Sched, bool ABLK = false, bool ALIGN_EPI = true, bool SP2 = true, bool BBLK = true>
; __device__ __forceinline__ void gemm_phase(LAS unsigned char* lds, const Gemm g, const Sched& S, const Epi& E) {
;     ...
;     auto a_unit = [&](const Unit& u) -> const char* { return ABLK ? (const char*)g.A + (size_t)u.pm * ((size_t)g.lda / 64) * 32768 : (const char*)g.A + (size_t)u.pm * 2 * hstepA; };
;     auto a_tile = [&](const char* ub, int tau) -> const char* { return ub + (size_t)tau * (ABLK ? (size_t)32768 : kstep); };
;     const char* uA = a_unit(cur); int tbA = cur.k0 / BK;
;     const char* cA = a_tile(uA, tbA); const char* cB = (const char*)g.Bt + (size_t)cur.pn * tstepB + b_k0(cur.k0);
;     S.a_ready(cur);
;     if constexpr (SP2) {
;         PG8_STAGE(PG8_SB(0, 0), cB, voffB); PG8_STAGE(PG8_SB(0, 1), cB + hstepB, voffB); PG8_STAGE(PG8_SA(0, 0), cA, voffA); PG8_STAGE(PG8_SA(0, 1), cA + hstepA, voffA);
;         if (wr == 1) PG8_BAR;
;         PG8_WAIT_V(2); PG8_BAR;
;         PG8_STAGE(PG8_SB(1, 0), cB + kstepB, voffB); PG8_STAGE(PG8_SA(1, 0), a_tile(uA, tbA + 1), voffA); PG8_STAGE(PG8_SB(1, 1), cB + hstepB + kstepB, voffB);
;         PG8_WAIT_V(6); PG8_BAR;
;     } else {
;         PG8_STAGE(PG8_SB(0, 0), cB, voffB); PG8_STAGE(PG8_SA(0, 0), cA, voffA); PG8_STAGE(PG8_SB(0, 1), cB + hstepB, voffB); PG8_STAGE(PG8_SA(0, 1), cA + hstepA, voffA);
;         if (wr == 1) PG8_BAR;
;         PG8_WAIT_V(4); PG8_BAR;
;         PG8_STAGE(PG8_SB(1, 0), cB + kstepB, voffB); PG8_STAGE(PG8_SA(1, 0), a_tile(uA, tbA + 1), voffA); PG8_STAGE(PG8_SB(1, 1), cB + hstepB + kstepB, voffB);
;         PG8_WAIT_V(6); PG8_BAR;
;     }
;     for (;;) {
;         const bool has_next = S.next(ui + 1, nxt);
;         const int nt = cur.nt;
;         const char* nuA = has_next ? a_unit(nxt) : uA; const int ntbA = has_next ? nxt.k0 / BK : tbA; const char* nB = has_next ? (const char*)g.Bt + (size_t)nxt.pn * tstepB + b_k0(nxt.k0) : cB;
;         for (int t = 0; t < nt; t += 2) {
;             const bool last = (t == nt - 2);
;             const char* a1 = a_tile(uA, tbA + t + 1);
;             const char* a2 = last ? a_tile(nuA, ntbA) : a_tile(uA, tbA + t + 2); const char* b2 = last ? nB : cB + (size_t)(t + 2) * kstepB;
;             const char* a3 = last ? a_tile(nuA, ntbA + 1) : a_tile(uA, tbA + t + 3); const char* b3 = b2 + kstepB;
.LBB0_1906:
	s_ashr_i32 s81, s80, 31
	s_andn2_b64 vcc, exec, s[4:5]
	s_lshl_b64 s[24:25], s[80:81], 22
	s_add_u32 s24, s62, s24
	s_addc_u32 s25, s83, s25
	s_and_b64 s[26:27], s[4:5], exec
	s_cselect_b32 s37, s25, s35
	s_cselect_b32 s50, s24, s34
	s_ashr_i32 s26, s0, 31
	s_lshr_b32 s26, s26, 26
	s_add_i32 s26, s0, s26
	s_ashr_i32 s26, s26, 6
	s_and_b64 s[28:29], s[4:5], exec
	s_cselect_b32 s38, s26, s36
	s_ashr_i32 s79, s78, 31
	s_lshl_b64 s[28:29], s[78:79], 22
	s_add_u32 s39, s1, s28
	s_addc_u32 s51, s33, s29
	s_ashr_i32 s27, s26, 31
	s_lshl_b64 s[28:29], s[26:27], 15
	s_add_u32 s28, s39, s28
	s_addc_u32 s29, s51, s29
	v_cndmask_b32_e64 v2, 0, 1, s[4:5]
	s_and_b64 s[4:5], s[4:5], exec
	s_cselect_b32 s4, s29, s31
	s_cselect_b32 s5, s28, s30
	s_ashr_i32 s39, s38, 31
	s_lshl_b64 s[38:39], s[38:39], 15
	s_add_u32 s27, s50, s38
	s_addc_u32 s50, s37, s39
	s_add_u32 s51, s27, 0x8000
	s_addc_u32 s52, s50, 0
	s_add_u32 s53, s30, 0x10000
	s_addc_u32 s54, s31, 0
	s_ashr_i32 s37, s36, 31
	v_cmp_ne_u32_e64 s[10:11], 1, v2
	s_lshl_b64 s[30:31], s[36:37], 15
	v_lshl_add_u64 v[2:3], s[34:35], 0, v[138:139]
	s_add_u32 s55, s34, s30
	v_lshl_add_u64 v[142:143], v[2:3], 0, s[30:31]
	v_lshl_add_u64 v[2:3], s[34:35], 0, v[140:141]
	s_addc_u32 s56, s35, s31
	v_lshl_add_u64 v[144:145], v[2:3], 0, s[30:31]
	s_lshl_b32 s30, s48, 15
	s_add_i32 s30, s30, 0xfff00000
	v_mov_b32_e32 v2, 0
	s_add_u32 s57, s30, 0xf0000
	s_mov_b32 s58, 0
	s_mov_b64 s[30:31], 0
	ds_read_b128 v[152:155], v148
	ds_read_b128 v[156:159], v148 offset:1024
	ds_read_b128 v[160:163], v148 offset:2048
	ds_read_b128 v[164:167], v148 offset:3072
	ds_read_b128 v[168:171], v149
	ds_read_b128 v[172:175], v149 offset:1024
	ds_read_b128 v[176:179], v149 offset:2048
	ds_read_b128 v[180:183], v149 offset:3072
	s_add_u32 s34, s55, s30
	s_addc_u32 s35, s56, s31
	s_add_u32 s38, s34, 0x10000
	s_addc_u32 s39, s35, 0
	s_add_i32 s58, s58, 2
	s_add_u32 s36, s53, s30
	s_addc_u32 s37, s54, s31
	s_add_u32 s34, s34, 0x18000
	s_addc_u32 s35, s35, 0
	v_lshl_add_u64 v[216:217], v[142:143], 0, s[30:31]
	s_add_i32 m0, s41, 0xc000
	ds_read_b128 v[184:187], v150
	ds_read_b128 v[188:191], v150 offset:1024
	ds_read_b128 v[192:195], v150 offset:2048
	ds_read_b128 v[196:199], v150 offset:3072
	ds_read_b128 v[200:203], v150 offset:4096
	ds_read_b128 v[204:207], v150 offset:5120
	ds_read_b128 v[208:211], v150 offset:6144
	ds_read_b128 v[212:215], v150 offset:7168
	global_load_lds_dwordx4 v[216:217], off
	v_lshl_add_u64 v[216:217], v[144:145], 0, s[30:31]
	s_add_i32 m0, s41, 0xe000
	s_nop 0
	global_load_lds_dwordx4 v[216:217], off
	s_waitcnt vmcnt(8) lgkmcnt(0)
	s_barrier
	v_mfma_f32_16x16x32_bf16 v[126:129], v[152:155], v[184:187], 0
	v_mfma_f32_16x16x32_bf16 v[122:125], v[160:163], v[184:187], 0
	v_mfma_f32_16x16x32_bf16 v[110:113], v[152:155], v[192:195], 0
	v_mfma_f32_16x16x32_bf16 v[106:109], v[160:163], v[192:195], 0
	v_mfma_f32_16x16x32_bf16 v[94:97], v[152:155], v[200:203], 0
	v_mfma_f32_16x16x32_bf16 v[90:93], v[160:163], v[200:203], 0
	v_mfma_f32_16x16x32_bf16 v[78:81], v[152:155], v[208:211], 0
	v_mfma_f32_16x16x32_bf16 v[74:77], v[160:163], v[208:211], 0
	v_mfma_f32_16x16x32_bf16 v[126:129], v[156:159], v[188:191], v[126:129]
	v_mfma_f32_16x16x32_bf16 v[122:125], v[164:167], v[188:191], v[122:125]
	v_mfma_f32_16x16x32_bf16 v[110:113], v[156:159], v[196:199], v[110:113]
	v_mfma_f32_16x16x32_bf16 v[106:109], v[164:167], v[196:199], v[106:109]
	v_mfma_f32_16x16x32_bf16 v[94:97], v[156:159], v[204:207], v[94:97]
	v_mfma_f32_16x16x32_bf16 v[90:93], v[164:167], v[204:207], v[90:93]
	v_mfma_f32_16x16x32_bf16 v[78:81], v[156:159], v[212:215], v[78:81]
	v_mfma_f32_16x16x32_bf16 v[74:77], v[164:167], v[212:215], v[74:77]
	v_mfma_f32_16x16x32_bf16 v[118:121], v[168:171], v[184:187], 0
	v_mfma_f32_16x16x32_bf16 v[114:117], v[176:179], v[184:187], 0
	v_mfma_f32_16x16x32_bf16 v[102:105], v[168:171], v[192:195], 0
	v_mfma_f32_16x16x32_bf16 v[98:101], v[176:179], v[192:195], 0
	v_mfma_f32_16x16x32_bf16 v[86:89], v[168:171], v[200:203], 0
	v_mfma_f32_16x16x32_bf16 v[82:85], v[176:179], v[200:203], 0
	v_mfma_f32_16x16x32_bf16 v[70:73], v[168:171], v[208:211], 0
	v_mfma_f32_16x16x32_bf16 v[66:69], v[176:179], v[208:211], 0
	v_mfma_f32_16x16x32_bf16 v[118:121], v[172:175], v[188:191], v[118:121]
	v_mfma_f32_16x16x32_bf16 v[114:117], v[180:183], v[188:191], v[114:117]
	v_mfma_f32_16x16x32_bf16 v[102:105], v[172:175], v[196:199], v[102:105]
	v_mfma_f32_16x16x32_bf16 v[98:101], v[180:183], v[196:199], v[98:101]
	v_mfma_f32_16x16x32_bf16 v[86:89], v[172:175], v[204:207], v[86:89]
	v_mfma_f32_16x16x32_bf16 v[82:85], v[180:183], v[204:207], v[82:85]
	v_mfma_f32_16x16x32_bf16 v[70:73], v[172:175], v[212:215], v[70:73]
	v_mfma_f32_16x16x32_bf16 v[66:69], v[180:183], v[212:215], v[66:69]
	s_barrier
	s_add_i32 s59, s72, s40
	s_mov_b32 m0, s59
	ds_read_b128 v[184:187], v150 offset:16384
	ds_read_b128 v[188:191], v150 offset:17408
	ds_read_b128 v[192:195], v150 offset:18432
	ds_read_b128 v[196:199], v150 offset:19456
	ds_read_b128 v[200:203], v150 offset:20480
	ds_read_b128 v[204:207], v150 offset:21504
	ds_read_b128 v[208:211], v150 offset:22528
	ds_read_b128 v[212:215], v150 offset:23552
	global_load_lds_dwordx4 v130, s[36:37]
	s_add_i32 m0, s59, 0x2000
	s_add_u32 s64, s36, 0x4000
	s_addc_u32 s65, s37, 0
	s_add_i32 s59, s73, s40
	global_load_lds_dwordx4 v132, s[36:37]
	s_mov_b32 m0, s59
	s_nop 0
	global_load_lds_dwordx4 v130, s[64:65]
	s_add_i32 m0, s59, 0x2000
	s_nop 0
	global_load_lds_dwordx4 v132, s[64:65]
	s_mov_b32 m0, s41
	s_nop 0
	global_load_lds_dwordx4 v130, s[38:39]
	s_mov_b32 m0, s42
	s_nop 0
	global_load_lds_dwordx4 v132, s[38:39]
	s_waitcnt vmcnt(8) lgkmcnt(0)
	s_barrier
; #define PG8_STAGE(bufoff, gbase, voff) do { _Pragma("unroll") for (int _i = 0; _i < 2; ++_i) \
;         __builtin_amdgcn_global_load_lds((const unsigned*)((const char*)(gbase) + (voff)[_i]), (LAS unsigned*)(lds + (bufoff) + ldsw + _i * 8192), 16, 0, 0); } while (0)
; #define PG8_LDA(dst, b, h) do { _Pragma("unroll") for (int m = 0; m < 4; ++m) _Pragma("unroll") for (int k = 0; k < 2; ++k) dst[m][k] = *(const LAS bf16x8*)(lds + PG8_SA(b, h) + aoff + m * 2048 + k * 1024); } while (0)
; #define PG8_LDB(dst, b, h) do { _Pragma("unroll") for (int n = 0; n < 2; ++n) _Pragma("unroll") for (int k = 0; k < 2; ++k) dst[n][k] = *(const LAS bf16x8*)(lds + PG8_SB(b, h) + boff + n * 2048 + k * 1024); } while (0)
; #define PG8_MMA(ai, bj, At, Bt) do { __builtin_amdgcn_s_setprio(1); _Pragma("unroll") for (int m = 0; m < 4; ++m) _Pragma("unroll") for (int n = 0; n < 2; ++n) _Pragma("unroll") for (int k = 0; k < 2; ++k) \
;         acc[ai][bj][m][n] = __builtin_amdgcn_mfma_f32_16x16x32_bf16(Bt[n][k], At[m][k], acc[ai][bj][m][n], 0, 0, 0); __builtin_amdgcn_s_setprio(0); } while (0)
; #define PG8_BAR __builtin_amdgcn_s_barrier()
; template <class Epi, class Sched, bool ABLK = false, bool ALIGN_EPI = true, bool SP2 = true, bool BBLK = true>
; __device__ __forceinline__ void gemm_phase(LAS unsigned char* lds, const Gemm g, const Sched& S, const Epi& E) {
;     ...
;             PG8_LDB(B0, 0, 0); PG8_LDB(B1, 0, 1); PG8_SCHED; PG8_LDA(At, 0, 0); PG8_STAGE(PG8_SA(1, 1), a1 + hstepA, voffA);
;             PG8_WAIT_V(8); PG8_WAIT_L(0); PG8_BAR; PG8_MMA(0, 0, At, B0); PG8_MMA(0, 1, At, B1); PG8_BAR; PG8_SCHED;
;             PG8_LDA(At, 0, 1); PG8_STAGE(PG8_SB(0, 0), b2, voffB); PG8_STAGE(PG8_SB(0, 1), b2 + hstepB, voffB); PG8_STAGE(PG8_SA(0, 0), a2, voffA);
;             PG8_WAIT_V(8); PG8_WAIT_L(0); PG8_BAR; PG8_MMA(1, 0, At, B0); PG8_MMA(1, 1, At, B1); PG8_BAR; PG8_SCHED;
;             PG8_LDB(B0, 1, 0); PG8_LDB(B1, 1, 1); PG8_SCHED; PG8_LDA(At, 1, 0); PG8_STAGE(PG8_SA(0, 1), a2 + hstepA, voffA);
;             PG8_WAIT_V(8); PG8_WAIT_L(0); PG8_BAR; PG8_MMA(0, 0, At, B0); PG8_MMA(0, 1, At, B1); PG8_BAR; PG8_SCHED;
;             PG8_LDA(At, 1, 1); PG8_STAGE(PG8_SB(1, 0), b3, voffB); PG8_STAGE(PG8_SB(1, 1), b3 + hstepB, voffB); PG8_STAGE(PG8_SA(1, 0), a3, voffA);
;             PG8_WAIT_V(8); PG8_WAIT_L(0); PG8_BAR; PG8_MMA(1, 0, At, B0); PG8_MMA(1, 1, At, B1); PG8_BAR; PG8_SCHED;
	v_mfma_f32_16x16x32_bf16 v[62:65], v[152:155], v[184:187], 0
	v_mfma_f32_16x16x32_bf16 v[58:61], v[160:163], v[184:187], 0
	v_mfma_f32_16x16x32_bf16 v[46:49], v[152:155], v[192:195], 0
	v_mfma_f32_16x16x32_bf16 v[42:45], v[160:163], v[192:195], 0
	v_mfma_f32_16x16x32_bf16 v[30:33], v[152:155], v[200:203], 0
	v_mfma_f32_16x16x32_bf16 v[26:29], v[160:163], v[200:203], 0
	v_mfma_f32_16x16x32_bf16 v[14:17], v[152:155], v[208:211], 0
	v_mfma_f32_16x16x32_bf16 v[10:13], v[160:163], v[208:211], 0
	v_mfma_f32_16x16x32_bf16 v[62:65], v[156:159], v[188:191], v[62:65]
	v_mfma_f32_16x16x32_bf16 v[58:61], v[164:167], v[188:191], v[58:61]
	v_mfma_f32_16x16x32_bf16 v[46:49], v[156:159], v[196:199], v[46:49]
	v_mfma_f32_16x16x32_bf16 v[42:45], v[164:167], v[196:199], v[42:45]
	v_mfma_f32_16x16x32_bf16 v[30:33], v[156:159], v[204:207], v[30:33]
	v_mfma_f32_16x16x32_bf16 v[26:29], v[164:167], v[204:207], v[26:29]
	v_mfma_f32_16x16x32_bf16 v[14:17], v[156:159], v[212:215], v[14:17]
	v_mfma_f32_16x16x32_bf16 v[10:13], v[164:167], v[212:215], v[10:13]
	v_mfma_f32_16x16x32_bf16 v[54:57], v[168:171], v[184:187], 0
	v_mfma_f32_16x16x32_bf16 v[50:53], v[176:179], v[184:187], 0
	v_mfma_f32_16x16x32_bf16 v[38:41], v[168:171], v[192:195], 0
	v_mfma_f32_16x16x32_bf16 v[34:37], v[176:179], v[192:195], 0
	v_mfma_f32_16x16x32_bf16 v[22:25], v[168:171], v[200:203], 0
	v_mfma_f32_16x16x32_bf16 v[18:21], v[176:179], v[200:203], 0
	v_mfma_f32_16x16x32_bf16 v[6:9], v[168:171], v[208:211], 0
	v_mfma_f32_16x16x32_bf16 v[2:5], v[176:179], v[208:211], 0
	v_mfma_f32_16x16x32_bf16 v[54:57], v[172:175], v[188:191], v[54:57]
	v_mfma_f32_16x16x32_bf16 v[50:53], v[180:183], v[188:191], v[50:53]
	v_mfma_f32_16x16x32_bf16 v[38:41], v[172:175], v[196:199], v[38:41]
	v_mfma_f32_16x16x32_bf16 v[34:37], v[180:183], v[196:199], v[34:37]
	v_mfma_f32_16x16x32_bf16 v[22:25], v[172:175], v[204:207], v[22:25]
	v_mfma_f32_16x16x32_bf16 v[18:21], v[180:183], v[204:207], v[18:21]
	v_mfma_f32_16x16x32_bf16 v[6:9], v[172:175], v[212:215], v[6:9]
	v_mfma_f32_16x16x32_bf16 v[2:5], v[180:183], v[212:215], v[2:5]
	s_barrier
	v_add_u32_e32 v151, s60, v146
	ds_read_b128 v[152:155], v151
	ds_read_b128 v[156:159], v151 offset:1024
	ds_read_b128 v[160:163], v151 offset:2048
	ds_read_b128 v[164:167], v151 offset:3072
	v_add_u32_e32 v151, s61, v146
	ds_read_b128 v[168:171], v151
	ds_read_b128 v[172:175], v151 offset:1024
	ds_read_b128 v[176:179], v151 offset:2048
	ds_read_b128 v[180:183], v151 offset:3072
	s_add_u32 s38, s38, 0x4000
	s_addc_u32 s39, s39, 0
	s_mov_b32 m0, s43
	ds_read_b128 v[184:187], v150 offset:32768
	ds_read_b128 v[188:191], v150 offset:33792
	ds_read_b128 v[192:195], v150 offset:34816
	ds_read_b128 v[196:199], v150 offset:35840
	ds_read_b128 v[200:203], v150 offset:36864
	ds_read_b128 v[204:207], v150 offset:37888
	ds_read_b128 v[208:211], v150 offset:38912
	ds_read_b128 v[212:215], v150 offset:39936
	global_load_lds_dwordx4 v130, s[38:39]
	s_mov_b32 m0, s44
	s_nop 0
	global_load_lds_dwordx4 v132, s[38:39]
	s_waitcnt vmcnt(8) lgkmcnt(0)
	s_barrier
	v_mfma_f32_16x16x32_bf16 v[126:129], v[152:155], v[184:187], v[126:129]
	v_mfma_f32_16x16x32_bf16 v[122:125], v[160:163], v[184:187], v[122:125]
	v_mfma_f32_16x16x32_bf16 v[110:113], v[152:155], v[192:195], v[110:113]
	v_mfma_f32_16x16x32_bf16 v[106:109], v[160:163], v[192:195], v[106:109]
	v_mfma_f32_16x16x32_bf16 v[94:97], v[152:155], v[200:203], v[94:97]
	v_mfma_f32_16x16x32_bf16 v[90:93], v[160:163], v[200:203], v[90:93]
	v_mfma_f32_16x16x32_bf16 v[78:81], v[152:155], v[208:211], v[78:81]
	v_mfma_f32_16x16x32_bf16 v[74:77], v[160:163], v[208:211], v[74:77]
	v_mfma_f32_16x16x32_bf16 v[126:129], v[156:159], v[188:191], v[126:129]
	v_mfma_f32_16x16x32_bf16 v[122:125], v[164:167], v[188:191], v[122:125]
	v_mfma_f32_16x16x32_bf16 v[110:113], v[156:159], v[196:199], v[110:113]
	v_mfma_f32_16x16x32_bf16 v[106:109], v[164:167], v[196:199], v[106:109]
	v_mfma_f32_16x16x32_bf16 v[94:97], v[156:159], v[204:207], v[94:97]
	v_mfma_f32_16x16x32_bf16 v[90:93], v[164:167], v[204:207], v[90:93]
	v_mfma_f32_16x16x32_bf16 v[78:81], v[156:159], v[212:215], v[78:81]
	v_mfma_f32_16x16x32_bf16 v[74:77], v[164:167], v[212:215], v[74:77]
	v_mfma_f32_16x16x32_bf16 v[118:121], v[168:171], v[184:187], v[118:121]
	v_mfma_f32_16x16x32_bf16 v[114:117], v[176:179], v[184:187], v[114:117]
	v_mfma_f32_16x16x32_bf16 v[102:105], v[168:171], v[192:195], v[102:105]
	v_mfma_f32_16x16x32_bf16 v[98:101], v[176:179], v[192:195], v[98:101]
	v_mfma_f32_16x16x32_bf16 v[86:89], v[168:171], v[200:203], v[86:89]
	v_mfma_f32_16x16x32_bf16 v[82:85], v[176:179], v[200:203], v[82:85]
	v_mfma_f32_16x16x32_bf16 v[70:73], v[168:171], v[208:211], v[70:73]
	v_mfma_f32_16x16x32_bf16 v[66:69], v[176:179], v[208:211], v[66:69]
	v_mfma_f32_16x16x32_bf16 v[118:121], v[172:175], v[188:191], v[118:121]
	v_mfma_f32_16x16x32_bf16 v[114:117], v[180:183], v[188:191], v[114:117]
	v_mfma_f32_16x16x32_bf16 v[102:105], v[172:175], v[196:199], v[102:105]
	v_mfma_f32_16x16x32_bf16 v[98:101], v[180:183], v[196:199], v[98:101]
	v_mfma_f32_16x16x32_bf16 v[86:89], v[172:175], v[204:207], v[86:89]
	v_mfma_f32_16x16x32_bf16 v[82:85], v[180:183], v[204:207], v[82:85]
	v_mfma_f32_16x16x32_bf16 v[70:73], v[172:175], v[212:215], v[70:73]
	v_mfma_f32_16x16x32_bf16 v[66:69], v[180:183], v[212:215], v[66:69]
	s_barrier
; #define PG8_STAGE(bufoff, gbase, voff) do { _Pragma("unroll") for (int _i = 0; _i < 2; ++_i) \
;         __builtin_amdgcn_global_load_lds((const unsigned*)((const char*)(gbase) + (voff)[_i]), (LAS unsigned*)(lds + (bufoff) + ldsw + _i * 8192), 16, 0, 0); } while (0)
; #define PG8_LDA(dst, b, h) do { _Pragma("unroll") for (int m = 0; m < 4; ++m) _Pragma("unroll") for (int k = 0; k < 2; ++k) dst[m][k] = *(const LAS bf16x8*)(lds + PG8_SA(b, h) + aoff + m * 2048 + k * 1024); } while (0)
; #define PG8_WAIT_V(n) asm volatile("s_waitcnt vmcnt(" #n ")" ::: "memory")
; #define PG8_WAIT_L(n) asm volatile("s_waitcnt lgkmcnt(" #n ")" ::: "memory")
; template <class Epi, class Sched, bool ABLK = false, bool ALIGN_EPI = true, bool SP2 = true, bool BBLK = true>
; __device__ __forceinline__ void gemm_phase(LAS unsigned char* lds, const Gemm g, const Sched& S, const Epi& E) {
;     ...
;         for (int t = 0; t < nt; t += 2) {
;             const bool last = (t == nt - 2);
;             const char* a1 = a_tile(uA, tbA + t + 1);
;             const char* a2 = last ? a_tile(nuA, ntbA) : a_tile(uA, tbA + t + 2); const char* b2 = last ? nB : cB + (size_t)(t + 2) * kstepB;
;             const char* a3 = last ? a_tile(nuA, ntbA + 1) : a_tile(uA, tbA + t + 3); const char* b3 = b2 + kstepB;
;             if (last && has_next) S.a_ready(nxt);
;             if constexpr (SP2) {
;             PG8_LDB(B0, 0, 0); PG8_LDB(B1, 0, 1); PG8_SCHED; PG8_LDA(At, 0, 0); PG8_STAGE(PG8_SA(1, 1), a1 + hstepA, voffA);
;             PG8_WAIT_V(8); PG8_WAIT_L(0); PG8_BAR; PG8_MMA(0, 0, At, B0); PG8_MMA(0, 1, At, B1); PG8_BAR; PG8_SCHED;
;             PG8_LDA(At, 0, 1); PG8_STAGE(PG8_SB(0, 0), b2, voffB); PG8_STAGE(PG8_SB(0, 1), b2 + hstepB, voffB); PG8_STAGE(PG8_SA(0, 0), a2, voffA);
;             PG8_WAIT_V(8); PG8_WAIT_L(0); PG8_BAR; PG8_MMA(1, 0, At, B0); PG8_MMA(1, 1, At, B1); PG8_BAR; PG8_SCHED;
;             PG8_LDB(B0, 1, 0); PG8_LDB(B1, 1, 1); PG8_SCHED; PG8_LDA(At, 1, 0); PG8_STAGE(PG8_SA(0, 1), a2 + hstepA, voffA);
;             PG8_WAIT_V(8); PG8_WAIT_L(0); PG8_BAR; PG8_MMA(0, 0, At, B0); PG8_MMA(0, 1, At, B1); PG8_BAR; PG8_SCHED;
;             PG8_LDA(At, 1, 1); PG8_STAGE(PG8_SB(1, 0), b3, voffB); PG8_STAGE(PG8_SB(1, 1), b3 + hstepB, voffB); PG8_STAGE(PG8_SA(1, 0), a3, voffA);
;             PG8_WAIT_V(8); PG8_WAIT_L(0); PG8_BAR; PG8_MMA(1, 0, At, B0); PG8_MMA(1, 1, At, B1); PG8_BAR; PG8_SCHED;
	s_add_u32 s38, s36, 0x8000
	s_addc_u32 s39, s37, 0
	s_add_i32 s59, s60, s40
	s_mov_b32 m0, s59
	ds_read_b128 v[184:187], v150 offset:49152
	ds_read_b128 v[188:191], v150 offset:50176
	ds_read_b128 v[192:195], v150 offset:51200
	ds_read_b128 v[196:199], v150 offset:52224
	ds_read_b128 v[200:203], v150 offset:53248
	ds_read_b128 v[204:207], v150 offset:54272
	ds_read_b128 v[208:211], v150 offset:55296
	ds_read_b128 v[212:215], v150 offset:56320
	global_load_lds_dwordx4 v130, s[38:39]
	s_add_i32 m0, s59, 0x2000
	s_add_u32 s36, s36, 0xc000
	v_lshl_add_u64 v[216:217], s[38:39], 0, v[132:133]
	s_addc_u32 s37, s37, 0
	s_add_i32 s38, s61, s40
	global_load_lds_dwordx4 v[216:217], off
	s_mov_b32 m0, s38
	s_nop 0
	global_load_lds_dwordx4 v130, s[36:37]
	s_add_i32 m0, s38, 0x2000
	s_nop 0
	global_load_lds_dwordx4 v132, s[36:37]
	s_mov_b32 m0, s45
	s_nop 0
	global_load_lds_dwordx4 v130, s[34:35]
	s_mov_b32 m0, s46
	s_nop 0
	global_load_lds_dwordx4 v132, s[34:35]
	s_waitcnt vmcnt(8) lgkmcnt(0)
	s_barrier
	v_mfma_f32_16x16x32_bf16 v[62:65], v[152:155], v[184:187], v[62:65]
	v_mfma_f32_16x16x32_bf16 v[58:61], v[160:163], v[184:187], v[58:61]
	v_mfma_f32_16x16x32_bf16 v[46:49], v[152:155], v[192:195], v[46:49]
	v_mfma_f32_16x16x32_bf16 v[42:45], v[160:163], v[192:195], v[42:45]
	v_mfma_f32_16x16x32_bf16 v[30:33], v[152:155], v[200:203], v[30:33]
	v_mfma_f32_16x16x32_bf16 v[26:29], v[160:163], v[200:203], v[26:29]
	v_mfma_f32_16x16x32_bf16 v[14:17], v[152:155], v[208:211], v[14:17]
	v_mfma_f32_16x16x32_bf16 v[10:13], v[160:163], v[208:211], v[10:13]
	v_mfma_f32_16x16x32_bf16 v[62:65], v[156:159], v[188:191], v[62:65]
	v_mfma_f32_16x16x32_bf16 v[58:61], v[164:167], v[188:191], v[58:61]
	v_mfma_f32_16x16x32_bf16 v[46:49], v[156:159], v[196:199], v[46:49]
	v_mfma_f32_16x16x32_bf16 v[42:45], v[164:167], v[196:199], v[42:45]
	v_mfma_f32_16x16x32_bf16 v[30:33], v[156:159], v[204:207], v[30:33]
	v_mfma_f32_16x16x32_bf16 v[26:29], v[164:167], v[204:207], v[26:29]
	v_mfma_f32_16x16x32_bf16 v[14:17], v[156:159], v[212:215], v[14:17]
	v_mfma_f32_16x16x32_bf16 v[10:13], v[164:167], v[212:215], v[10:13]
	v_mfma_f32_16x16x32_bf16 v[54:57], v[168:171], v[184:187], v[54:57]
	v_mfma_f32_16x16x32_bf16 v[50:53], v[176:179], v[184:187], v[50:53]
	v_mfma_f32_16x16x32_bf16 v[38:41], v[168:171], v[192:195], v[38:41]
	v_mfma_f32_16x16x32_bf16 v[34:37], v[176:179], v[192:195], v[34:37]
	v_mfma_f32_16x16x32_bf16 v[22:25], v[168:171], v[200:203], v[22:25]
	v_mfma_f32_16x16x32_bf16 v[18:21], v[176:179], v[200:203], v[18:21]
	v_mfma_f32_16x16x32_bf16 v[6:9], v[168:171], v[208:211], v[6:9]
	v_mfma_f32_16x16x32_bf16 v[2:5], v[176:179], v[208:211], v[2:5]
	v_mfma_f32_16x16x32_bf16 v[54:57], v[172:175], v[188:191], v[54:57]
	v_mfma_f32_16x16x32_bf16 v[50:53], v[180:183], v[188:191], v[50:53]
	v_mfma_f32_16x16x32_bf16 v[38:41], v[172:175], v[196:199], v[38:41]
	v_mfma_f32_16x16x32_bf16 v[34:37], v[180:183], v[196:199], v[34:37]
	v_mfma_f32_16x16x32_bf16 v[22:25], v[172:175], v[204:207], v[22:25]
	v_mfma_f32_16x16x32_bf16 v[18:21], v[180:183], v[204:207], v[18:21]
	v_mfma_f32_16x16x32_bf16 v[6:9], v[172:175], v[212:215], v[6:9]
	v_mfma_f32_16x16x32_bf16 v[2:5], v[180:183], v[212:215], v[2:5]
	s_barrier
	s_add_u32 s30, s30, 0x10000
	s_addc_u32 s31, s31, 0
	s_cmp_ge_u32 s58, s48
.LBB0_1907:
	ds_read_b128 v[152:155], v148
	ds_read_b128 v[156:159], v148 offset:1024
	ds_read_b128 v[160:163], v148 offset:2048
	ds_read_b128 v[164:167], v148 offset:3072
	ds_read_b128 v[168:171], v149
	ds_read_b128 v[172:175], v149 offset:1024
	ds_read_b128 v[176:179], v149 offset:2048
	ds_read_b128 v[180:183], v149 offset:3072
	s_add_u32 s34, s55, s30
	s_addc_u32 s35, s56, s31
	s_add_u32 s38, s34, 0x10000
	s_addc_u32 s39, s35, 0
	s_add_i32 s58, s58, 2
	s_add_u32 s36, s53, s30
	s_addc_u32 s37, s54, s31
	s_add_u32 s34, s34, 0x18000
	s_addc_u32 s35, s35, 0
	s_cmp_eq_u32 s57, s30
	s_cbranch_scc1 .Lksel_21
.Lksel_21_back:
	v_lshl_add_u64 v[216:217], v[142:143], 0, s[30:31]
	s_add_i32 m0, s41, 0xc000
	ds_read_b128 v[184:187], v150
	ds_read_b128 v[188:191], v150 offset:1024
	ds_read_b128 v[192:195], v150 offset:2048
	ds_read_b128 v[196:199], v150 offset:3072
	ds_read_b128 v[200:203], v150 offset:4096
	ds_read_b128 v[204:207], v150 offset:5120
	ds_read_b128 v[208:211], v150 offset:6144
	ds_read_b128 v[212:215], v150 offset:7168
	global_load_lds_dwordx4 v[216:217], off
	v_lshl_add_u64 v[216:217], v[144:145], 0, s[30:31]
	s_add_i32 m0, s41, 0xe000
	s_nop 0
	global_load_lds_dwordx4 v[216:217], off
	s_waitcnt vmcnt(8) lgkmcnt(0)
	s_barrier
; #define PG8_STAGE(bufoff, gbase, voff) do { _Pragma("unroll") for (int _i = 0; _i < 2; ++_i) \
;         __builtin_amdgcn_global_load_lds((const unsigned*)((const char*)(gbase) + (voff)[_i]), (LAS unsigned*)(lds + (bufoff) + ldsw + _i * 8192), 16, 0, 0); } while (0)
; #define PG8_LDA(dst, b, h) do { _Pragma("unroll") for (int m = 0; m < 4; ++m) _Pragma("unroll") for (int k = 0; k < 2; ++k) dst[m][k] = *(const LAS bf16x8*)(lds + PG8_SA(b, h) + aoff + m * 2048 + k * 1024); } while (0)
; #define PG8_LDB(dst, b, h) do { _Pragma("unroll") for (int n = 0; n < 2; ++n) _Pragma("unroll") for (int k = 0; k < 2; ++k) dst[n][k] = *(const LAS bf16x8*)(lds + PG8_SB(b, h) + boff + n * 2048 + k * 1024); } while (0)
; #define PG8_MMA(ai, bj, At, Bt) do { __builtin_amdgcn_s_setprio(1); _Pragma("unroll") for (int m = 0; m < 4; ++m) _Pragma("unroll") for (int n = 0; n < 2; ++n) _Pragma("unroll") for (int k = 0; k < 2; ++k) \
;         acc[ai][bj][m][n] = __builtin_amdgcn_mfma_f32_16x16x32_bf16(Bt[n][k], At[m][k], acc[ai][bj][m][n], 0, 0, 0); __builtin_amdgcn_s_setprio(0); } while (0)
; #define PG8_WAIT_V(n) asm volatile("s_waitcnt vmcnt(" #n ")" ::: "memory")
; #define PG8_WAIT_L(n) asm volatile("s_waitcnt lgkmcnt(" #n ")" ::: "memory")
; #define PG8_BAR __builtin_amdgcn_s_barrier()
; #define PG8_SCHED __builtin_amdgcn_sched_barrier(0)
; template <class Epi, class Sched, bool ABLK = false, bool ALIGN_EPI = true, bool SP2 = true, bool BBLK = true>
; __device__ __forceinline__ void gemm_phase(LAS unsigned char* lds, const Gemm g, const Sched& S, const Epi& E) {
;     ...
;             PG8_LDB(B0, 0, 0); PG8_LDB(B1, 0, 1); PG8_SCHED; PG8_LDA(At, 0, 0); PG8_STAGE(PG8_SA(1, 1), a1 + hstepA, voffA);
;             PG8_WAIT_V(8); PG8_WAIT_L(0); PG8_BAR; PG8_MMA(0, 0, At, B0); PG8_MMA(0, 1, At, B1); PG8_BAR; PG8_SCHED;
;             PG8_LDA(At, 0, 1); PG8_STAGE(PG8_SB(0, 0), b2, voffB); PG8_STAGE(PG8_SB(0, 1), b2 + hstepB, voffB); PG8_STAGE(PG8_SA(0, 0), a2, voffA);
;             PG8_WAIT_V(8); PG8_WAIT_L(0); PG8_BAR; PG8_MMA(1, 0, At, B0); PG8_MMA(1, 1, At, B1); PG8_BAR; PG8_SCHED;
	v_mfma_f32_16x16x32_bf16 v[126:129], v[152:155], v[184:187], v[126:129]
	v_mfma_f32_16x16x32_bf16 v[122:125], v[160:163], v[184:187], v[122:125]
	v_mfma_f32_16x16x32_bf16 v[110:113], v[152:155], v[192:195], v[110:113]
	v_mfma_f32_16x16x32_bf16 v[106:109], v[160:163], v[192:195], v[106:109]
	v_mfma_f32_16x16x32_bf16 v[94:97], v[152:155], v[200:203], v[94:97]
	v_mfma_f32_16x16x32_bf16 v[90:93], v[160:163], v[200:203], v[90:93]
	v_mfma_f32_16x16x32_bf16 v[78:81], v[152:155], v[208:211], v[78:81]
	v_mfma_f32_16x16x32_bf16 v[74:77], v[160:163], v[208:211], v[74:77]
	v_mfma_f32_16x16x32_bf16 v[126:129], v[156:159], v[188:191], v[126:129]
	v_mfma_f32_16x16x32_bf16 v[122:125], v[164:167], v[188:191], v[122:125]
	v_mfma_f32_16x16x32_bf16 v[110:113], v[156:159], v[196:199], v[110:113]
	v_mfma_f32_16x16x32_bf16 v[106:109], v[164:167], v[196:199], v[106:109]
	v_mfma_f32_16x16x32_bf16 v[94:97], v[156:159], v[204:207], v[94:97]
	v_mfma_f32_16x16x32_bf16 v[90:93], v[164:167], v[204:207], v[90:93]
	v_mfma_f32_16x16x32_bf16 v[78:81], v[156:159], v[212:215], v[78:81]
	v_mfma_f32_16x16x32_bf16 v[74:77], v[164:167], v[212:215], v[74:77]
	v_mfma_f32_16x16x32_bf16 v[118:121], v[168:171], v[184:187], v[118:121]
	v_mfma_f32_16x16x32_bf16 v[114:117], v[176:179], v[184:187], v[114:117]
	v_mfma_f32_16x16x32_bf16 v[102:105], v[168:171], v[192:195], v[102:105]
	v_mfma_f32_16x16x32_bf16 v[98:101], v[176:179], v[192:195], v[98:101]
	v_mfma_f32_16x16x32_bf16 v[86:89], v[168:171], v[200:203], v[86:89]
	v_mfma_f32_16x16x32_bf16 v[82:85], v[176:179], v[200:203], v[82:85]
	v_mfma_f32_16x16x32_bf16 v[70:73], v[168:171], v[208:211], v[70:73]
	v_mfma_f32_16x16x32_bf16 v[66:69], v[176:179], v[208:211], v[66:69]
	v_mfma_f32_16x16x32_bf16 v[118:121], v[172:175], v[188:191], v[118:121]
	v_mfma_f32_16x16x32_bf16 v[114:117], v[180:183], v[188:191], v[114:117]
	v_mfma_f32_16x16x32_bf16 v[102:105], v[172:175], v[196:199], v[102:105]
	v_mfma_f32_16x16x32_bf16 v[98:101], v[180:183], v[196:199], v[98:101]
	v_mfma_f32_16x16x32_bf16 v[86:89], v[172:175], v[204:207], v[86:89]
	v_mfma_f32_16x16x32_bf16 v[82:85], v[180:183], v[204:207], v[82:85]
	v_mfma_f32_16x16x32_bf16 v[70:73], v[172:175], v[212:215], v[70:73]
	v_mfma_f32_16x16x32_bf16 v[66:69], v[180:183], v[212:215], v[66:69]
	s_barrier
	s_add_i32 s59, s72, s40
	s_mov_b32 m0, s59
	ds_read_b128 v[184:187], v150 offset:16384
	ds_read_b128 v[188:191], v150 offset:17408
	ds_read_b128 v[192:195], v150 offset:18432
	ds_read_b128 v[196:199], v150 offset:19456
	ds_read_b128 v[200:203], v150 offset:20480
	ds_read_b128 v[204:207], v150 offset:21504
	ds_read_b128 v[208:211], v150 offset:22528
	ds_read_b128 v[212:215], v150 offset:23552
	global_load_lds_dwordx4 v130, s[36:37]
	s_add_i32 m0, s59, 0x2000
	s_add_u32 s64, s36, 0x4000
	s_addc_u32 s65, s37, 0
	s_add_i32 s59, s73, s40
	global_load_lds_dwordx4 v132, s[36:37]
	s_mov_b32 m0, s59
	s_nop 0
	global_load_lds_dwordx4 v130, s[64:65]
	s_add_i32 m0, s59, 0x2000
	s_nop 0
	global_load_lds_dwordx4 v132, s[64:65]
	s_mov_b32 m0, s41
	s_nop 0
	global_load_lds_dwordx4 v130, s[38:39]
	s_mov_b32 m0, s42
	s_nop 0
	global_load_lds_dwordx4 v132, s[38:39]
	s_waitcnt vmcnt(8) lgkmcnt(0)
	s_barrier
	v_mfma_f32_16x16x32_bf16 v[62:65], v[152:155], v[184:187], v[62:65]
	v_mfma_f32_16x16x32_bf16 v[58:61], v[160:163], v[184:187], v[58:61]
	v_mfma_f32_16x16x32_bf16 v[46:49], v[152:155], v[192:195], v[46:49]
	v_mfma_f32_16x16x32_bf16 v[42:45], v[160:163], v[192:195], v[42:45]
	v_mfma_f32_16x16x32_bf16 v[30:33], v[152:155], v[200:203], v[30:33]
	v_mfma_f32_16x16x32_bf16 v[26:29], v[160:163], v[200:203], v[26:29]
	v_mfma_f32_16x16x32_bf16 v[14:17], v[152:155], v[208:211], v[14:17]
	v_mfma_f32_16x16x32_bf16 v[10:13], v[160:163], v[208:211], v[10:13]
	v_mfma_f32_16x16x32_bf16 v[62:65], v[156:159], v[188:191], v[62:65]
	v_mfma_f32_16x16x32_bf16 v[58:61], v[164:167], v[188:191], v[58:61]
	v_mfma_f32_16x16x32_bf16 v[46:49], v[156:159], v[196:199], v[46:49]
	v_mfma_f32_16x16x32_bf16 v[42:45], v[164:167], v[196:199], v[42:45]
	v_mfma_f32_16x16x32_bf16 v[30:33], v[156:159], v[204:207], v[30:33]
	v_mfma_f32_16x16x32_bf16 v[26:29], v[164:167], v[204:207], v[26:29]
	v_mfma_f32_16x16x32_bf16 v[14:17], v[156:159], v[212:215], v[14:17]
	v_mfma_f32_16x16x32_bf16 v[10:13], v[164:167], v[212:215], v[10:13]
	v_mfma_f32_16x16x32_bf16 v[54:57], v[168:171], v[184:187], v[54:57]
	v_mfma_f32_16x16x32_bf16 v[50:53], v[176:179], v[184:187], v[50:53]
	v_mfma_f32_16x16x32_bf16 v[38:41], v[168:171], v[192:195], v[38:41]
	v_mfma_f32_16x16x32_bf16 v[34:37], v[176:179], v[192:195], v[34:37]
	v_mfma_f32_16x16x32_bf16 v[22:25], v[168:171], v[200:203], v[22:25]
	v_mfma_f32_16x16x32_bf16 v[18:21], v[176:179], v[200:203], v[18:21]
	v_mfma_f32_16x16x32_bf16 v[6:9], v[168:171], v[208:211], v[6:9]
	v_mfma_f32_16x16x32_bf16 v[2:5], v[176:179], v[208:211], v[2:5]
	v_mfma_f32_16x16x32_bf16 v[54:57], v[172:175], v[188:191], v[54:57]
	v_mfma_f32_16x16x32_bf16 v[50:53], v[180:183], v[188:191], v[50:53]
	v_mfma_f32_16x16x32_bf16 v[38:41], v[172:175], v[196:199], v[38:41]
	v_mfma_f32_16x16x32_bf16 v[34:37], v[180:183], v[196:199], v[34:37]
	v_mfma_f32_16x16x32_bf16 v[22:25], v[172:175], v[204:207], v[22:25]
	v_mfma_f32_16x16x32_bf16 v[18:21], v[180:183], v[204:207], v[18:21]
	v_mfma_f32_16x16x32_bf16 v[6:9], v[172:175], v[212:215], v[6:9]
	v_mfma_f32_16x16x32_bf16 v[2:5], v[180:183], v[212:215], v[2:5]
	s_barrier
; #define PG8_STAGE(bufoff, gbase, voff) do { _Pragma("unroll") for (int _i = 0; _i < 2; ++_i) \
;         __builtin_amdgcn_global_load_lds((const unsigned*)((const char*)(gbase) + (voff)[_i]), (LAS unsigned*)(lds + (bufoff) + ldsw + _i * 8192), 16, 0, 0); } while (0)
; #define PG8_LDA(dst, b, h) do { _Pragma("unroll") for (int m = 0; m < 4; ++m) _Pragma("unroll") for (int k = 0; k < 2; ++k) dst[m][k] = *(const LAS bf16x8*)(lds + PG8_SA(b, h) + aoff + m * 2048 + k * 1024); } while (0)
; #define PG8_LDB(dst, b, h) do { _Pragma("unroll") for (int n = 0; n < 2; ++n) _Pragma("unroll") for (int k = 0; k < 2; ++k) dst[n][k] = *(const LAS bf16x8*)(lds + PG8_SB(b, h) + boff + n * 2048 + k * 1024); } while (0)
; #define PG8_MMA(ai, bj, At, Bt) do { __builtin_amdgcn_s_setprio(1); _Pragma("unroll") for (int m = 0; m < 4; ++m) _Pragma("unroll") for (int n = 0; n < 2; ++n) _Pragma("unroll") for (int k = 0; k < 2; ++k) \
;         acc[ai][bj][m][n] = __builtin_amdgcn_mfma_f32_16x16x32_bf16(Bt[n][k], At[m][k], acc[ai][bj][m][n], 0, 0, 0); __builtin_amdgcn_s_setprio(0); } while (0)
; #define PG8_WAIT_V(n) asm volatile("s_waitcnt vmcnt(" #n ")" ::: "memory")
; #define PG8_WAIT_L(n) asm volatile("s_waitcnt lgkmcnt(" #n ")" ::: "memory")
; #define PG8_BAR __builtin_amdgcn_s_barrier()
; #define PG8_SCHED __builtin_amdgcn_sched_barrier(0)
; template <class Epi, class Sched, bool ABLK = false, bool ALIGN_EPI = true, bool SP2 = true, bool BBLK = true>
; __device__ __forceinline__ void gemm_phase(LAS unsigned char* lds, const Gemm g, const Sched& S, const Epi& E) {
;     ...
;             PG8_LDB(B0, 1, 0); PG8_LDB(B1, 1, 1); PG8_SCHED; PG8_LDA(At, 1, 0); PG8_STAGE(PG8_SA(0, 1), a2 + hstepA, voffA);
;             PG8_WAIT_V(8); PG8_WAIT_L(0); PG8_BAR; PG8_MMA(0, 0, At, B0); PG8_MMA(0, 1, At, B1); PG8_BAR; PG8_SCHED;
;             PG8_LDA(At, 1, 1); PG8_STAGE(PG8_SB(1, 0), b3, voffB); PG8_STAGE(PG8_SB(1, 1), b3 + hstepB, voffB); PG8_STAGE(PG8_SA(1, 0), a3, voffA);
;             PG8_WAIT_V(8); PG8_WAIT_L(0); PG8_BAR; PG8_MMA(1, 0, At, B0); PG8_MMA(1, 1, At, B1); PG8_BAR; PG8_SCHED;
	v_add_u32_e32 v151, s60, v146
	ds_read_b128 v[152:155], v151
	ds_read_b128 v[156:159], v151 offset:1024
	ds_read_b128 v[160:163], v151 offset:2048
	ds_read_b128 v[164:167], v151 offset:3072
	v_add_u32_e32 v151, s61, v146
	ds_read_b128 v[168:171], v151
	ds_read_b128 v[172:175], v151 offset:1024
	ds_read_b128 v[176:179], v151 offset:2048
	ds_read_b128 v[180:183], v151 offset:3072
	s_add_u32 s38, s38, 0x4000
	s_addc_u32 s39, s39, 0
	s_mov_b32 m0, s43
	ds_read_b128 v[184:187], v150 offset:32768
	ds_read_b128 v[188:191], v150 offset:33792
	ds_read_b128 v[192:195], v150 offset:34816
	ds_read_b128 v[196:199], v150 offset:35840
	ds_read_b128 v[200:203], v150 offset:36864
	ds_read_b128 v[204:207], v150 offset:37888
	ds_read_b128 v[208:211], v150 offset:38912
	ds_read_b128 v[212:215], v150 offset:39936
	global_load_lds_dwordx4 v130, s[38:39]
	s_mov_b32 m0, s44
	s_nop 0
	global_load_lds_dwordx4 v132, s[38:39]
	s_waitcnt vmcnt(8) lgkmcnt(0)
	s_barrier
	v_mfma_f32_16x16x32_bf16 v[126:129], v[152:155], v[184:187], v[126:129]
	v_mfma_f32_16x16x32_bf16 v[122:125], v[160:163], v[184:187], v[122:125]
	v_mfma_f32_16x16x32_bf16 v[110:113], v[152:155], v[192:195], v[110:113]
	v_mfma_f32_16x16x32_bf16 v[106:109], v[160:163], v[192:195], v[106:109]
	v_mfma_f32_16x16x32_bf16 v[94:97], v[152:155], v[200:203], v[94:97]
	v_mfma_f32_16x16x32_bf16 v[90:93], v[160:163], v[200:203], v[90:93]
	v_mfma_f32_16x16x32_bf16 v[78:81], v[152:155], v[208:211], v[78:81]
	v_mfma_f32_16x16x32_bf16 v[74:77], v[160:163], v[208:211], v[74:77]
	v_mfma_f32_16x16x32_bf16 v[126:129], v[156:159], v[188:191], v[126:129]
	v_mfma_f32_16x16x32_bf16 v[122:125], v[164:167], v[188:191], v[122:125]
	v_mfma_f32_16x16x32_bf16 v[110:113], v[156:159], v[196:199], v[110:113]
	v_mfma_f32_16x16x32_bf16 v[106:109], v[164:167], v[196:199], v[106:109]
	v_mfma_f32_16x16x32_bf16 v[94:97], v[156:159], v[204:207], v[94:97]
	v_mfma_f32_16x16x32_bf16 v[90:93], v[164:167], v[204:207], v[90:93]
	v_mfma_f32_16x16x32_bf16 v[78:81], v[156:159], v[212:215], v[78:81]
	v_mfma_f32_16x16x32_bf16 v[74:77], v[164:167], v[212:215], v[74:77]
	v_mfma_f32_16x16x32_bf16 v[118:121], v[168:171], v[184:187], v[118:121]
	v_mfma_f32_16x16x32_bf16 v[114:117], v[176:179], v[184:187], v[114:117]
	v_mfma_f32_16x16x32_bf16 v[102:105], v[168:171], v[192:195], v[102:105]
	v_mfma_f32_16x16x32_bf16 v[98:101], v[176:179], v[192:195], v[98:101]
	v_mfma_f32_16x16x32_bf16 v[86:89], v[168:171], v[200:203], v[86:89]
	v_mfma_f32_16x16x32_bf16 v[82:85], v[176:179], v[200:203], v[82:85]
	v_mfma_f32_16x16x32_bf16 v[70:73], v[168:171], v[208:211], v[70:73]
	v_mfma_f32_16x16x32_bf16 v[66:69], v[176:179], v[208:211], v[66:69]
	v_mfma_f32_16x16x32_bf16 v[118:121], v[172:175], v[188:191], v[118:121]
	v_mfma_f32_16x16x32_bf16 v[114:117], v[180:183], v[188:191], v[114:117]
	v_mfma_f32_16x16x32_bf16 v[102:105], v[172:175], v[196:199], v[102:105]
	v_mfma_f32_16x16x32_bf16 v[98:101], v[180:183], v[196:199], v[98:101]
	v_mfma_f32_16x16x32_bf16 v[86:89], v[172:175], v[204:207], v[86:89]
	v_mfma_f32_16x16x32_bf16 v[82:85], v[180:183], v[204:207], v[82:85]
	v_mfma_f32_16x16x32_bf16 v[70:73], v[172:175], v[212:215], v[70:73]
	v_mfma_f32_16x16x32_bf16 v[66:69], v[180:183], v[212:215], v[66:69]
	s_barrier
	s_add_u32 s38, s36, 0x8000
	s_addc_u32 s39, s37, 0
	s_add_i32 s59, s60, s40
	s_mov_b32 m0, s59
	ds_read_b128 v[184:187], v150 offset:49152
	ds_read_b128 v[188:191], v150 offset:50176
	ds_read_b128 v[192:195], v150 offset:51200
	ds_read_b128 v[196:199], v150 offset:52224
	ds_read_b128 v[200:203], v150 offset:53248
	ds_read_b128 v[204:207], v150 offset:54272
	ds_read_b128 v[208:211], v150 offset:55296
	ds_read_b128 v[212:215], v150 offset:56320
	global_load_lds_dwordx4 v130, s[38:39]
	s_add_i32 m0, s59, 0x2000
	s_add_u32 s36, s36, 0xc000
	v_lshl_add_u64 v[216:217], s[38:39], 0, v[132:133]
	s_addc_u32 s37, s37, 0
	s_add_i32 s38, s61, s40
	global_load_lds_dwordx4 v[216:217], off
	s_mov_b32 m0, s38
	s_nop 0
	global_load_lds_dwordx4 v130, s[36:37]
	s_add_i32 m0, s38, 0x2000
	s_nop 0
	global_load_lds_dwordx4 v132, s[36:37]
	s_mov_b32 m0, s45
	s_nop 0
	global_load_lds_dwordx4 v130, s[34:35]
	s_mov_b32 m0, s46
	s_nop 0
	global_load_lds_dwordx4 v132, s[34:35]
	s_waitcnt vmcnt(8) lgkmcnt(0)
	s_barrier
	v_mfma_f32_16x16x32_bf16 v[62:65], v[152:155], v[184:187], v[62:65]
	v_mfma_f32_16x16x32_bf16 v[58:61], v[160:163], v[184:187], v[58:61]
	v_mfma_f32_16x16x32_bf16 v[46:49], v[152:155], v[192:195], v[46:49]
	v_mfma_f32_16x16x32_bf16 v[42:45], v[160:163], v[192:195], v[42:45]
	v_mfma_f32_16x16x32_bf16 v[30:33], v[152:155], v[200:203], v[30:33]
	v_mfma_f32_16x16x32_bf16 v[26:29], v[160:163], v[200:203], v[26:29]
	v_mfma_f32_16x16x32_bf16 v[14:17], v[152:155], v[208:211], v[14:17]
	v_mfma_f32_16x16x32_bf16 v[10:13], v[160:163], v[208:211], v[10:13]
	v_mfma_f32_16x16x32_bf16 v[62:65], v[156:159], v[188:191], v[62:65]
	v_mfma_f32_16x16x32_bf16 v[58:61], v[164:167], v[188:191], v[58:61]
	v_mfma_f32_16x16x32_bf16 v[46:49], v[156:159], v[196:199], v[46:49]
	v_mfma_f32_16x16x32_bf16 v[42:45], v[164:167], v[196:199], v[42:45]
	v_mfma_f32_16x16x32_bf16 v[30:33], v[156:159], v[204:207], v[30:33]
	v_mfma_f32_16x16x32_bf16 v[26:29], v[164:167], v[204:207], v[26:29]
	v_mfma_f32_16x16x32_bf16 v[14:17], v[156:159], v[212:215], v[14:17]
	v_mfma_f32_16x16x32_bf16 v[10:13], v[164:167], v[212:215], v[10:13]
	v_mfma_f32_16x16x32_bf16 v[54:57], v[168:171], v[184:187], v[54:57]
	v_mfma_f32_16x16x32_bf16 v[50:53], v[176:179], v[184:187], v[50:53]
	v_mfma_f32_16x16x32_bf16 v[38:41], v[168:171], v[192:195], v[38:41]
	v_mfma_f32_16x16x32_bf16 v[34:37], v[176:179], v[192:195], v[34:37]
	v_mfma_f32_16x16x32_bf16 v[22:25], v[168:171], v[200:203], v[22:25]
	v_mfma_f32_16x16x32_bf16 v[18:21], v[176:179], v[200:203], v[18:21]
	v_mfma_f32_16x16x32_bf16 v[6:9], v[168:171], v[208:211], v[6:9]
	v_mfma_f32_16x16x32_bf16 v[2:5], v[176:179], v[208:211], v[2:5]
	v_mfma_f32_16x16x32_bf16 v[54:57], v[172:175], v[188:191], v[54:57]
	v_mfma_f32_16x16x32_bf16 v[50:53], v[180:183], v[188:191], v[50:53]
	v_mfma_f32_16x16x32_bf16 v[38:41], v[172:175], v[196:199], v[38:41]
	v_mfma_f32_16x16x32_bf16 v[34:37], v[180:183], v[196:199], v[34:37]
	v_mfma_f32_16x16x32_bf16 v[22:25], v[172:175], v[204:207], v[22:25]
	v_mfma_f32_16x16x32_bf16 v[18:21], v[180:183], v[204:207], v[18:21]
	v_mfma_f32_16x16x32_bf16 v[6:9], v[172:175], v[212:215], v[6:9]
	v_mfma_f32_16x16x32_bf16 v[2:5], v[180:183], v[212:215], v[2:5]
	s_barrier
	s_add_u32 s30, s30, 0x10000
	s_addc_u32 s31, s31, 0
	s_cmp_ge_u32 s58, s48
	s_cbranch_scc0 .LBB0_1907
	s_and_b64 vcc, exec, s[6:7]
	s_cbranch_vccz .LBB0_1910
	s_barrier

; template <class Epi, class Sched, bool ABLK = false, bool ALIGN_EPI = true, bool SP2 = true, bool BBLK = true>
; __device__ __forceinline__ void gemm_phase(LAS unsigned char* lds, const Gemm g, const Sched& S, const Epi& E) {
;     ...
;             const char* a1 = a_tile(uA, tbA + t + 1);
;             const char* a2 = last ? a_tile(nuA, ntbA) : a_tile(uA, tbA + t + 2); const char* b2 = last ? nB : cB + (size_t)(t + 2) * kstepB;
;             const char* a3 = last ? a_tile(nuA, ntbA + 1) : a_tile(uA, tbA + t + 3); const char* b3 = b2 + kstepB;
.Lksel_21:
	s_mov_b32 s35, s52
	s_mov_b32 s34, s51
	s_mov_b32 s37, s4
	s_mov_b32 s36, s5
	s_mov_b32 s39, s50
	s_mov_b32 s38, s27
	s_branch .Lksel_21_back

; #define PG8_STAGE(bufoff, gbase, voff) do { _Pragma("unroll") for (int _i = 0; _i < 2; ++_i) \
;         __builtin_amdgcn_global_load_lds((const unsigned*)((const char*)(gbase) + (voff)[_i]), (LAS unsigned*)(lds + (bufoff) + ldsw + _i * 8192), 16, 0, 0); } while (0)
; #define PG8_WAIT_V(n) asm volatile("s_waitcnt vmcnt(" #n ")" ::: "memory")
; template <class Epi, class Sched, bool ABLK = false, bool ALIGN_EPI = true, bool SP2 = true, bool BBLK = true>
; __device__ __forceinline__ void gemm_phase(LAS unsigned char* lds, const Gemm g, const Sched& S, const Epi& E) {
;     ...
;     for (;;) {
;         const bool has_next = S.next(ui + 1, nxt);
;         const int nt = cur.nt;
;         const char* nuA = has_next ? a_unit(nxt) : uA; const int ntbA = has_next ? nxt.k0 / BK : tbA; const char* nB = has_next ? (const char*)g.Bt + (size_t)nxt.pn * tstepB + b_k0(nxt.k0) : cB;
;         for (int t = 0; t < nt; t += 2) {
;             const bool last = (t == nt - 2);
;             const char* a1 = a_tile(uA, tbA + t + 1);
;             const char* a2 = last ? a_tile(nuA, ntbA) : a_tile(uA, tbA + t + 2); const char* b2 = last ? nB : cB + (size_t)(t + 2) * kstepB;
;             const char* a3 = last ? a_tile(nuA, ntbA + 1) : a_tile(uA, tbA + t + 3); const char* b3 = b2 + kstepB;
;             if (last && has_next) S.a_ready(nxt);
;             if constexpr (SP2) {
;             PG8_LDB(B0, 0, 0); PG8_LDB(B1, 0, 1); PG8_SCHED; PG8_LDA(At, 0, 0); PG8_STAGE(PG8_SA(1, 1), a1 + hstepA, voffA);
;             PG8_WAIT_V(8); PG8_WAIT_L(0); PG8_BAR; PG8_MMA(0, 0, At, B0); PG8_MMA(0, 1, At, B1); PG8_BAR; PG8_SCHED;
;             PG8_LDA(At, 0, 1); PG8_STAGE(PG8_SB(0, 0), b2, voffB); PG8_STAGE(PG8_SB(0, 1), b2 + hstepB, voffB); PG8_STAGE(PG8_SA(0, 0), a2, voffA);
;             PG8_WAIT_V(8); PG8_WAIT_L(0); PG8_BAR; PG8_MMA(1, 0, At, B0); PG8_MMA(1, 1, At, B1); PG8_BAR; PG8_SCHED;
;             PG8_LDB(B0, 1, 0); PG8_LDB(B1, 1, 1); PG8_SCHED; PG8_LDA(At, 1, 0); PG8_STAGE(PG8_SA(0, 1), a2 + hstepA, voffA);
;             PG8_WAIT_V(8); PG8_WAIT_L(0); PG8_BAR; PG8_MMA(0, 0, At, B0); PG8_MMA(0, 1, At, B1); PG8_BAR; PG8_SCHED;
;             PG8_LDA(At, 1, 1); PG8_STAGE(PG8_SB(1, 0), b3, voffB); PG8_STAGE(PG8_SB(1, 1), b3 + hstepB, voffB); PG8_STAGE(PG8_SA(1, 0), a3, voffA);
;             PG8_WAIT_V(8); PG8_WAIT_L(0); PG8_BAR; PG8_MMA(1, 0, At, B0); PG8_MMA(1, 1, At, B1); PG8_BAR; PG8_SCHED;
.LBB0_2137:
	s_ashr_i32 s11, s10, 31
	s_lshl_b64 s[4:5], s[10:11], 20
	s_add_u32 s14, s37, s4
	s_addc_u32 s15, s38, s5
	s_and_b64 s[4:5], s[16:17], exec
	s_cselect_b32 s4, s15, s25
	s_cselect_b32 s5, s14, s24
	s_ashr_i32 s13, s12, 31
	s_lshl_b64 s[18:19], s[12:13], 20
	s_add_u32 s18, s1, s18
	s_addc_u32 s19, s33, s19
	s_and_b64 s[28:29], s[16:17], exec
	s_cselect_b32 s11, s19, s27
	s_cselect_b32 s13, s18, s26
	s_add_u32 s48, s5, 0x80
	s_addc_u32 s49, s4, 0
	s_add_u32 s50, s26, 0x10000
	v_mov_b32_e32 v2, 0
	s_addc_u32 s51, s27, 0
	v_lshl_add_u64 v[142:143], s[24:25], 0, v[138:139]
	v_lshl_add_u64 v[144:145], s[24:25], 0, v[140:141]
	s_mov_b32 s52, -2
	s_mov_b64 s[26:27], 0
	ds_read_b128 v[152:155], v148
	ds_read_b128 v[156:159], v148 offset:1024
	ds_read_b128 v[160:163], v148 offset:2048
	ds_read_b128 v[164:167], v148 offset:3072
	ds_read_b128 v[168:171], v149
	ds_read_b128 v[172:175], v149 offset:1024
	ds_read_b128 v[176:179], v149 offset:2048
	ds_read_b128 v[180:183], v149 offset:3072
	s_add_u32 s28, s24, s26
	s_addc_u32 s29, s25, s27
	s_add_u32 s34, s28, 0x100
	s_addc_u32 s35, s29, 0
	s_add_u32 s28, s28, 0x180
	s_addc_u32 s29, s29, 0
	s_mov_b64 s[30:31], s[50:51]
	s_mov_b32 m0, s47
	v_lshl_add_u64 v[216:217], v[142:143], 0, s[26:27]
	ds_read_b128 v[184:187], v150
	ds_read_b128 v[188:191], v150 offset:1024
	ds_read_b128 v[192:195], v150 offset:2048
	ds_read_b128 v[196:199], v150 offset:3072
	ds_read_b128 v[200:203], v150 offset:4096
	ds_read_b128 v[204:207], v150 offset:5120
	ds_read_b128 v[208:211], v150 offset:6144
	ds_read_b128 v[212:215], v150 offset:7168
	global_load_lds_dwordx4 v[216:217], off
	v_lshl_add_u64 v[216:217], v[144:145], 0, s[26:27]
	s_add_i32 m0, s21, 0xe000
	s_nop 0
	global_load_lds_dwordx4 v[216:217], off
	s_waitcnt vmcnt(8) lgkmcnt(0)
	s_barrier
	v_mfma_f32_16x16x32_bf16 v[122:125], v[152:155], v[184:187], 0
	v_mfma_f32_16x16x32_bf16 v[118:121], v[160:163], v[184:187], 0
	v_mfma_f32_16x16x32_bf16 v[106:109], v[152:155], v[192:195], 0
	v_mfma_f32_16x16x32_bf16 v[102:105], v[160:163], v[192:195], 0
	v_mfma_f32_16x16x32_bf16 v[90:93], v[152:155], v[200:203], 0
	v_mfma_f32_16x16x32_bf16 v[86:89], v[160:163], v[200:203], 0
	v_mfma_f32_16x16x32_bf16 v[74:77], v[152:155], v[208:211], 0
	v_mfma_f32_16x16x32_bf16 v[70:73], v[160:163], v[208:211], 0
	v_mfma_f32_16x16x32_bf16 v[122:125], v[156:159], v[188:191], v[122:125]
	v_mfma_f32_16x16x32_bf16 v[118:121], v[164:167], v[188:191], v[118:121]
	v_mfma_f32_16x16x32_bf16 v[106:109], v[156:159], v[196:199], v[106:109]
	v_mfma_f32_16x16x32_bf16 v[102:105], v[164:167], v[196:199], v[102:105]
	v_mfma_f32_16x16x32_bf16 v[90:93], v[156:159], v[204:207], v[90:93]
	v_mfma_f32_16x16x32_bf16 v[86:89], v[164:167], v[204:207], v[86:89]
	v_mfma_f32_16x16x32_bf16 v[74:77], v[156:159], v[212:215], v[74:77]
	v_mfma_f32_16x16x32_bf16 v[70:73], v[164:167], v[212:215], v[70:73]
	v_mfma_f32_16x16x32_bf16 v[126:129], v[168:171], v[184:187], 0
	v_mfma_f32_16x16x32_bf16 v[114:117], v[176:179], v[184:187], 0
	v_mfma_f32_16x16x32_bf16 v[110:113], v[168:171], v[192:195], 0
	v_mfma_f32_16x16x32_bf16 v[98:101], v[176:179], v[192:195], 0
	v_mfma_f32_16x16x32_bf16 v[94:97], v[168:171], v[200:203], 0
	v_mfma_f32_16x16x32_bf16 v[82:85], v[176:179], v[200:203], 0
	v_mfma_f32_16x16x32_bf16 v[78:81], v[168:171], v[208:211], 0
	v_mfma_f32_16x16x32_bf16 v[66:69], v[176:179], v[208:211], 0
	v_mfma_f32_16x16x32_bf16 v[126:129], v[172:175], v[188:191], v[126:129]
	v_mfma_f32_16x16x32_bf16 v[114:117], v[180:183], v[188:191], v[114:117]
	v_mfma_f32_16x16x32_bf16 v[110:113], v[172:175], v[196:199], v[110:113]
	v_mfma_f32_16x16x32_bf16 v[98:101], v[180:183], v[196:199], v[98:101]
	v_mfma_f32_16x16x32_bf16 v[94:97], v[172:175], v[204:207], v[94:97]
	v_mfma_f32_16x16x32_bf16 v[82:85], v[180:183], v[204:207], v[82:85]
	v_mfma_f32_16x16x32_bf16 v[78:81], v[172:175], v[212:215], v[78:81]
	v_mfma_f32_16x16x32_bf16 v[66:69], v[180:183], v[212:215], v[66:69]
	s_barrier
	s_add_i32 s53, s72, s36
	s_mov_b32 m0, s53
	ds_read_b128 v[184:187], v150 offset:16384
	ds_read_b128 v[188:191], v150 offset:17408
	ds_read_b128 v[192:195], v150 offset:18432
	ds_read_b128 v[196:199], v150 offset:19456
	ds_read_b128 v[200:203], v150 offset:20480
	ds_read_b128 v[204:207], v150 offset:21504
	ds_read_b128 v[208:211], v150 offset:22528
	ds_read_b128 v[212:215], v150 offset:23552
	global_load_lds_dwordx4 v134, s[30:31]
	s_add_i32 m0, s53, 0x2000
	s_add_u32 s54, s30, 0x4000
	s_addc_u32 s55, s31, 0
	s_add_i32 s53, s73, s36
	global_load_lds_dwordx4 v130, s[30:31]
	s_mov_b32 m0, s53
	s_nop 0
	global_load_lds_dwordx4 v134, s[54:55]
	s_add_i32 m0, s53, 0x2000
	s_nop 0
	global_load_lds_dwordx4 v130, s[54:55]
	s_mov_b32 m0, s21
	s_nop 0
	global_load_lds_dwordx4 v136, s[34:35]
	s_mov_b32 m0, s23
	s_nop 0
	global_load_lds_dwordx4 v132, s[34:35]
	s_waitcnt vmcnt(8) lgkmcnt(0)
	s_barrier
; #define PG8_STAGE(bufoff, gbase, voff) do { _Pragma("unroll") for (int _i = 0; _i < 2; ++_i) \
;         __builtin_amdgcn_global_load_lds((const unsigned*)((const char*)(gbase) + (voff)[_i]), (LAS unsigned*)(lds + (bufoff) + ldsw + _i * 8192), 16, 0, 0); } while (0)
; #define PG8_LDA(dst, b, h) do { _Pragma("unroll") for (int m = 0; m < 4; ++m) _Pragma("unroll") for (int k = 0; k < 2; ++k) dst[m][k] = *(const LAS bf16x8*)(lds + PG8_SA(b, h) + aoff + m * 2048 + k * 1024); } while (0)
; #define PG8_LDB(dst, b, h) do { _Pragma("unroll") for (int n = 0; n < 2; ++n) _Pragma("unroll") for (int k = 0; k < 2; ++k) dst[n][k] = *(const LAS bf16x8*)(lds + PG8_SB(b, h) + boff + n * 2048 + k * 1024); } while (0)
; #define PG8_MMA(ai, bj, At, Bt) do { __builtin_amdgcn_s_setprio(1); _Pragma("unroll") for (int m = 0; m < 4; ++m) _Pragma("unroll") for (int n = 0; n < 2; ++n) _Pragma("unroll") for (int k = 0; k < 2; ++k) \
;         acc[ai][bj][m][n] = __builtin_amdgcn_mfma_f32_16x16x32_bf16(Bt[n][k], At[m][k], acc[ai][bj][m][n], 0, 0, 0); __builtin_amdgcn_s_setprio(0); } while (0)
; #define PG8_BAR __builtin_amdgcn_s_barrier()
; template <class Epi, class Sched, bool ABLK = false, bool ALIGN_EPI = true, bool SP2 = true, bool BBLK = true>
; __device__ __forceinline__ void gemm_phase(LAS unsigned char* lds, const Gemm g, const Sched& S, const Epi& E) {
;     ...
;             PG8_LDB(B0, 0, 0); PG8_LDB(B1, 0, 1); PG8_SCHED; PG8_LDA(At, 0, 0); PG8_STAGE(PG8_SA(1, 1), a1 + hstepA, voffA);
;             PG8_WAIT_V(8); PG8_WAIT_L(0); PG8_BAR; PG8_MMA(0, 0, At, B0); PG8_MMA(0, 1, At, B1); PG8_BAR; PG8_SCHED;
;             PG8_LDA(At, 0, 1); PG8_STAGE(PG8_SB(0, 0), b2, voffB); PG8_STAGE(PG8_SB(0, 1), b2 + hstepB, voffB); PG8_STAGE(PG8_SA(0, 0), a2, voffA);
;             PG8_WAIT_V(8); PG8_WAIT_L(0); PG8_BAR; PG8_MMA(1, 0, At, B0); PG8_MMA(1, 1, At, B1); PG8_BAR; PG8_SCHED;
;             PG8_LDB(B0, 1, 0); PG8_LDB(B1, 1, 1); PG8_SCHED; PG8_LDA(At, 1, 0); PG8_STAGE(PG8_SA(0, 1), a2 + hstepA, voffA);
;             PG8_WAIT_V(8); PG8_WAIT_L(0); PG8_BAR; PG8_MMA(0, 0, At, B0); PG8_MMA(0, 1, At, B1); PG8_BAR; PG8_SCHED;
;             PG8_LDA(At, 1, 1); PG8_STAGE(PG8_SB(1, 0), b3, voffB); PG8_STAGE(PG8_SB(1, 1), b3 + hstepB, voffB); PG8_STAGE(PG8_SA(1, 0), a3, voffA);
;             PG8_WAIT_V(8); PG8_WAIT_L(0); PG8_BAR; PG8_MMA(1, 0, At, B0); PG8_MMA(1, 1, At, B1); PG8_BAR; PG8_SCHED;
	v_mfma_f32_16x16x32_bf16 v[58:61], v[152:155], v[184:187], 0
	v_mfma_f32_16x16x32_bf16 v[54:57], v[160:163], v[184:187], 0
	v_mfma_f32_16x16x32_bf16 v[42:45], v[152:155], v[192:195], 0
	v_mfma_f32_16x16x32_bf16 v[38:41], v[160:163], v[192:195], 0
	v_mfma_f32_16x16x32_bf16 v[26:29], v[152:155], v[200:203], 0
	v_mfma_f32_16x16x32_bf16 v[22:25], v[160:163], v[200:203], 0
	v_mfma_f32_16x16x32_bf16 v[10:13], v[152:155], v[208:211], 0
	v_mfma_f32_16x16x32_bf16 v[6:9], v[160:163], v[208:211], 0
	v_mfma_f32_16x16x32_bf16 v[58:61], v[156:159], v[188:191], v[58:61]
	v_mfma_f32_16x16x32_bf16 v[54:57], v[164:167], v[188:191], v[54:57]
	v_mfma_f32_16x16x32_bf16 v[42:45], v[156:159], v[196:199], v[42:45]
	v_mfma_f32_16x16x32_bf16 v[38:41], v[164:167], v[196:199], v[38:41]
	v_mfma_f32_16x16x32_bf16 v[26:29], v[156:159], v[204:207], v[26:29]
	v_mfma_f32_16x16x32_bf16 v[22:25], v[164:167], v[204:207], v[22:25]
	v_mfma_f32_16x16x32_bf16 v[10:13], v[156:159], v[212:215], v[10:13]
	v_mfma_f32_16x16x32_bf16 v[6:9], v[164:167], v[212:215], v[6:9]
	v_mfma_f32_16x16x32_bf16 v[62:65], v[168:171], v[184:187], 0
	v_mfma_f32_16x16x32_bf16 v[50:53], v[176:179], v[184:187], 0
	v_mfma_f32_16x16x32_bf16 v[46:49], v[168:171], v[192:195], 0
	v_mfma_f32_16x16x32_bf16 v[34:37], v[176:179], v[192:195], 0
	v_mfma_f32_16x16x32_bf16 v[30:33], v[168:171], v[200:203], 0
	v_mfma_f32_16x16x32_bf16 v[18:21], v[176:179], v[200:203], 0
	v_mfma_f32_16x16x32_bf16 v[14:17], v[168:171], v[208:211], 0
	v_mfma_f32_16x16x32_bf16 v[2:5], v[176:179], v[208:211], 0
	v_mfma_f32_16x16x32_bf16 v[62:65], v[172:175], v[188:191], v[62:65]
	v_mfma_f32_16x16x32_bf16 v[50:53], v[180:183], v[188:191], v[50:53]
	v_mfma_f32_16x16x32_bf16 v[46:49], v[172:175], v[196:199], v[46:49]
	v_mfma_f32_16x16x32_bf16 v[34:37], v[180:183], v[196:199], v[34:37]
	v_mfma_f32_16x16x32_bf16 v[30:33], v[172:175], v[204:207], v[30:33]
	v_mfma_f32_16x16x32_bf16 v[18:21], v[180:183], v[204:207], v[18:21]
	v_mfma_f32_16x16x32_bf16 v[14:17], v[172:175], v[212:215], v[14:17]
	v_mfma_f32_16x16x32_bf16 v[2:5], v[180:183], v[212:215], v[2:5]
	s_barrier
	v_add_u32_e32 v151, s60, v146
	ds_read_b128 v[152:155], v151
	ds_read_b128 v[156:159], v151 offset:1024
	ds_read_b128 v[160:163], v151 offset:2048
	ds_read_b128 v[164:167], v151 offset:3072
	v_add_u32_e32 v151, s61, v146
	ds_read_b128 v[168:171], v151
	ds_read_b128 v[172:175], v151 offset:1024
	ds_read_b128 v[176:179], v151 offset:2048
	ds_read_b128 v[180:183], v151 offset:3072
	s_add_u32 s34, s34, 0x80000
	s_addc_u32 s35, s35, 0
	s_mov_b32 m0, s39
	ds_read_b128 v[184:187], v150 offset:32768
	ds_read_b128 v[188:191], v150 offset:33792
	ds_read_b128 v[192:195], v150 offset:34816
	ds_read_b128 v[196:199], v150 offset:35840
	ds_read_b128 v[200:203], v150 offset:36864
	ds_read_b128 v[204:207], v150 offset:37888
	ds_read_b128 v[208:211], v150 offset:38912
	ds_read_b128 v[212:215], v150 offset:39936
	global_load_lds_dwordx4 v136, s[34:35]
	s_mov_b32 m0, s40
	s_nop 0
	global_load_lds_dwordx4 v132, s[34:35]
	s_waitcnt vmcnt(8) lgkmcnt(0)
	s_barrier
	v_mfma_f32_16x16x32_bf16 v[122:125], v[152:155], v[184:187], v[122:125]
	v_mfma_f32_16x16x32_bf16 v[118:121], v[160:163], v[184:187], v[118:121]
	v_mfma_f32_16x16x32_bf16 v[106:109], v[152:155], v[192:195], v[106:109]
	v_mfma_f32_16x16x32_bf16 v[102:105], v[160:163], v[192:195], v[102:105]
	v_mfma_f32_16x16x32_bf16 v[90:93], v[152:155], v[200:203], v[90:93]
	v_mfma_f32_16x16x32_bf16 v[86:89], v[160:163], v[200:203], v[86:89]
	v_mfma_f32_16x16x32_bf16 v[74:77], v[152:155], v[208:211], v[74:77]
	v_mfma_f32_16x16x32_bf16 v[70:73], v[160:163], v[208:211], v[70:73]
	v_mfma_f32_16x16x32_bf16 v[122:125], v[156:159], v[188:191], v[122:125]
	v_mfma_f32_16x16x32_bf16 v[118:121], v[164:167], v[188:191], v[118:121]
	v_mfma_f32_16x16x32_bf16 v[106:109], v[156:159], v[196:199], v[106:109]
	v_mfma_f32_16x16x32_bf16 v[102:105], v[164:167], v[196:199], v[102:105]
	v_mfma_f32_16x16x32_bf16 v[90:93], v[156:159], v[204:207], v[90:93]
	v_mfma_f32_16x16x32_bf16 v[86:89], v[164:167], v[204:207], v[86:89]
	v_mfma_f32_16x16x32_bf16 v[74:77], v[156:159], v[212:215], v[74:77]
	v_mfma_f32_16x16x32_bf16 v[70:73], v[164:167], v[212:215], v[70:73]
	v_mfma_f32_16x16x32_bf16 v[126:129], v[168:171], v[184:187], v[126:129]
	v_mfma_f32_16x16x32_bf16 v[114:117], v[176:179], v[184:187], v[114:117]
	v_mfma_f32_16x16x32_bf16 v[110:113], v[168:171], v[192:195], v[110:113]
	v_mfma_f32_16x16x32_bf16 v[98:101], v[176:179], v[192:195], v[98:101]
	v_mfma_f32_16x16x32_bf16 v[94:97], v[168:171], v[200:203], v[94:97]
	v_mfma_f32_16x16x32_bf16 v[82:85], v[176:179], v[200:203], v[82:85]
	v_mfma_f32_16x16x32_bf16 v[78:81], v[168:171], v[208:211], v[78:81]
	v_mfma_f32_16x16x32_bf16 v[66:69], v[176:179], v[208:211], v[66:69]
	v_mfma_f32_16x16x32_bf16 v[126:129], v[172:175], v[188:191], v[126:129]
	v_mfma_f32_16x16x32_bf16 v[114:117], v[180:183], v[188:191], v[114:117]
	v_mfma_f32_16x16x32_bf16 v[110:113], v[172:175], v[196:199], v[110:113]
	v_mfma_f32_16x16x32_bf16 v[98:101], v[180:183], v[196:199], v[98:101]
	v_mfma_f32_16x16x32_bf16 v[94:97], v[172:175], v[204:207], v[94:97]
	v_mfma_f32_16x16x32_bf16 v[82:85], v[180:183], v[204:207], v[82:85]
	v_mfma_f32_16x16x32_bf16 v[78:81], v[172:175], v[212:215], v[78:81]
	v_mfma_f32_16x16x32_bf16 v[66:69], v[180:183], v[212:215], v[66:69]
	s_barrier
; #define PG8_STAGE(bufoff, gbase, voff) do { _Pragma("unroll") for (int _i = 0; _i < 2; ++_i) \
;         __builtin_amdgcn_global_load_lds((const unsigned*)((const char*)(gbase) + (voff)[_i]), (LAS unsigned*)(lds + (bufoff) + ldsw + _i * 8192), 16, 0, 0); } while (0)
; #define PG8_LDA(dst, b, h) do { _Pragma("unroll") for (int m = 0; m < 4; ++m) _Pragma("unroll") for (int k = 0; k < 2; ++k) dst[m][k] = *(const LAS bf16x8*)(lds + PG8_SA(b, h) + aoff + m * 2048 + k * 1024); } while (0)
; #define PG8_WAIT_V(n) asm volatile("s_waitcnt vmcnt(" #n ")" ::: "memory")
; #define PG8_WAIT_L(n) asm volatile("s_waitcnt lgkmcnt(" #n ")" ::: "memory")
; template <class Epi, class Sched, bool ABLK = false, bool ALIGN_EPI = true, bool SP2 = true, bool BBLK = true>
; __device__ __forceinline__ void gemm_phase(LAS unsigned char* lds, const Gemm g, const Sched& S, const Epi& E) {
;     ...
;         for (int t = 0; t < nt; t += 2) {
;             const bool last = (t == nt - 2);
;             const char* a1 = a_tile(uA, tbA + t + 1);
;             const char* a2 = last ? a_tile(nuA, ntbA) : a_tile(uA, tbA + t + 2); const char* b2 = last ? nB : cB + (size_t)(t + 2) * kstepB;
;             const char* a3 = last ? a_tile(nuA, ntbA + 1) : a_tile(uA, tbA + t + 3); const char* b3 = b2 + kstepB;
;             if (last && has_next) S.a_ready(nxt);
;             if constexpr (SP2) {
;             PG8_LDB(B0, 0, 0); PG8_LDB(B1, 0, 1); PG8_SCHED; PG8_LDA(At, 0, 0); PG8_STAGE(PG8_SA(1, 1), a1 + hstepA, voffA);
;             PG8_WAIT_V(8); PG8_WAIT_L(0); PG8_BAR; PG8_MMA(0, 0, At, B0); PG8_MMA(0, 1, At, B1); PG8_BAR; PG8_SCHED;
;             PG8_LDA(At, 0, 1); PG8_STAGE(PG8_SB(0, 0), b2, voffB); PG8_STAGE(PG8_SB(0, 1), b2 + hstepB, voffB); PG8_STAGE(PG8_SA(0, 0), a2, voffA);
;             PG8_WAIT_V(8); PG8_WAIT_L(0); PG8_BAR; PG8_MMA(1, 0, At, B0); PG8_MMA(1, 1, At, B1); PG8_BAR; PG8_SCHED;
;             PG8_LDB(B0, 1, 0); PG8_LDB(B1, 1, 1); PG8_SCHED; PG8_LDA(At, 1, 0); PG8_STAGE(PG8_SA(0, 1), a2 + hstepA, voffA);
;             PG8_WAIT_V(8); PG8_WAIT_L(0); PG8_BAR; PG8_MMA(0, 0, At, B0); PG8_MMA(0, 1, At, B1); PG8_BAR; PG8_SCHED;
;             PG8_LDA(At, 1, 1); PG8_STAGE(PG8_SB(1, 0), b3, voffB); PG8_STAGE(PG8_SB(1, 1), b3 + hstepB, voffB); PG8_STAGE(PG8_SA(1, 0), a3, voffA);
;             PG8_WAIT_V(8); PG8_WAIT_L(0); PG8_BAR; PG8_MMA(1, 0, At, B0); PG8_MMA(1, 1, At, B1); PG8_BAR; PG8_SCHED;
	s_add_u32 s34, s30, 0x8000
	s_addc_u32 s35, s31, 0
	s_add_i32 s53, s60, s36
	s_mov_b32 m0, s53
	ds_read_b128 v[184:187], v150 offset:49152
	ds_read_b128 v[188:191], v150 offset:50176
	ds_read_b128 v[192:195], v150 offset:51200
	ds_read_b128 v[196:199], v150 offset:52224
	ds_read_b128 v[200:203], v150 offset:53248
	ds_read_b128 v[204:207], v150 offset:54272
	ds_read_b128 v[208:211], v150 offset:55296
	ds_read_b128 v[212:215], v150 offset:56320
	global_load_lds_dwordx4 v134, s[34:35]
	s_add_i32 m0, s53, 0x2000
	s_add_u32 s30, s30, 0xc000
	v_lshl_add_u64 v[216:217], s[34:35], 0, v[130:131]
	s_addc_u32 s31, s31, 0
	s_add_i32 s34, s61, s36
	global_load_lds_dwordx4 v[216:217], off
	s_mov_b32 m0, s34
	s_nop 0
	global_load_lds_dwordx4 v134, s[30:31]
	s_add_i32 m0, s34, 0x2000
	s_nop 0
	global_load_lds_dwordx4 v130, s[30:31]
	s_mov_b32 m0, s42
	s_nop 0
	global_load_lds_dwordx4 v136, s[28:29]
	s_mov_b32 m0, s43
	s_nop 0
	global_load_lds_dwordx4 v132, s[28:29]
	s_waitcnt vmcnt(8) lgkmcnt(0)
	s_barrier
	v_mfma_f32_16x16x32_bf16 v[58:61], v[152:155], v[184:187], v[58:61]
	v_mfma_f32_16x16x32_bf16 v[54:57], v[160:163], v[184:187], v[54:57]
	v_mfma_f32_16x16x32_bf16 v[42:45], v[152:155], v[192:195], v[42:45]
	v_mfma_f32_16x16x32_bf16 v[38:41], v[160:163], v[192:195], v[38:41]
	v_mfma_f32_16x16x32_bf16 v[26:29], v[152:155], v[200:203], v[26:29]
	v_mfma_f32_16x16x32_bf16 v[22:25], v[160:163], v[200:203], v[22:25]
	v_mfma_f32_16x16x32_bf16 v[10:13], v[152:155], v[208:211], v[10:13]
	v_mfma_f32_16x16x32_bf16 v[6:9], v[160:163], v[208:211], v[6:9]
	v_mfma_f32_16x16x32_bf16 v[58:61], v[156:159], v[188:191], v[58:61]
	v_mfma_f32_16x16x32_bf16 v[54:57], v[164:167], v[188:191], v[54:57]
	v_mfma_f32_16x16x32_bf16 v[42:45], v[156:159], v[196:199], v[42:45]
	v_mfma_f32_16x16x32_bf16 v[38:41], v[164:167], v[196:199], v[38:41]
	v_mfma_f32_16x16x32_bf16 v[26:29], v[156:159], v[204:207], v[26:29]
	v_mfma_f32_16x16x32_bf16 v[22:25], v[164:167], v[204:207], v[22:25]
	v_mfma_f32_16x16x32_bf16 v[10:13], v[156:159], v[212:215], v[10:13]
	v_mfma_f32_16x16x32_bf16 v[6:9], v[164:167], v[212:215], v[6:9]
	v_mfma_f32_16x16x32_bf16 v[62:65], v[168:171], v[184:187], v[62:65]
	v_mfma_f32_16x16x32_bf16 v[50:53], v[176:179], v[184:187], v[50:53]
	v_mfma_f32_16x16x32_bf16 v[46:49], v[168:171], v[192:195], v[46:49]
	v_mfma_f32_16x16x32_bf16 v[34:37], v[176:179], v[192:195], v[34:37]
	v_mfma_f32_16x16x32_bf16 v[30:33], v[168:171], v[200:203], v[30:33]
	v_mfma_f32_16x16x32_bf16 v[18:21], v[176:179], v[200:203], v[18:21]
	v_mfma_f32_16x16x32_bf16 v[14:17], v[168:171], v[208:211], v[14:17]
	v_mfma_f32_16x16x32_bf16 v[2:5], v[176:179], v[208:211], v[2:5]
	v_mfma_f32_16x16x32_bf16 v[62:65], v[172:175], v[188:191], v[62:65]
	v_mfma_f32_16x16x32_bf16 v[50:53], v[180:183], v[188:191], v[50:53]
	v_mfma_f32_16x16x32_bf16 v[46:49], v[172:175], v[196:199], v[46:49]
	v_mfma_f32_16x16x32_bf16 v[34:37], v[180:183], v[196:199], v[34:37]
	v_mfma_f32_16x16x32_bf16 v[30:33], v[172:175], v[204:207], v[30:33]
	v_mfma_f32_16x16x32_bf16 v[18:21], v[180:183], v[204:207], v[18:21]
	v_mfma_f32_16x16x32_bf16 v[14:17], v[172:175], v[212:215], v[14:17]
	v_mfma_f32_16x16x32_bf16 v[2:5], v[180:183], v[212:215], v[2:5]
	s_barrier
	s_add_i32 s52, s52, 2
	s_add_u32 s26, s26, 0x100
	s_addc_u32 s27, s27, 0
	s_add_u32 s50, s50, 0x10000
	s_addc_u32 s51, s51, 0
	s_cmp_gt_u32 s52, 29
.LBB0_2138:
	ds_read_b128 v[152:155], v148
	ds_read_b128 v[156:159], v148 offset:1024
	ds_read_b128 v[160:163], v148 offset:2048
	ds_read_b128 v[164:167], v148 offset:3072
	ds_read_b128 v[168:171], v149
	ds_read_b128 v[172:175], v149 offset:1024
	ds_read_b128 v[176:179], v149 offset:2048
	ds_read_b128 v[180:183], v149 offset:3072
	s_add_u32 s28, s24, s26
	s_addc_u32 s29, s25, s27
	s_add_u32 s34, s28, 0x100
	s_addc_u32 s35, s29, 0
	s_add_u32 s28, s28, 0x180
	s_addc_u32 s29, s29, 0
	s_cmpk_eq_i32 s26, 0xf00
	s_cbranch_scc1 .Lksel_23
	s_mov_b64 s[30:31], s[50:51]
.Lksel_23_back:
	s_mov_b32 m0, s47
	v_lshl_add_u64 v[216:217], v[142:143], 0, s[26:27]
	ds_read_b128 v[184:187], v150
	ds_read_b128 v[188:191], v150 offset:1024
	ds_read_b128 v[192:195], v150 offset:2048
	ds_read_b128 v[196:199], v150 offset:3072
	ds_read_b128 v[200:203], v150 offset:4096
	ds_read_b128 v[204:207], v150 offset:5120
	ds_read_b128 v[208:211], v150 offset:6144
	ds_read_b128 v[212:215], v150 offset:7168
	global_load_lds_dwordx4 v[216:217], off
	v_lshl_add_u64 v[216:217], v[144:145], 0, s[26:27]
	s_add_i32 m0, s21, 0xe000
	s_nop 0
	global_load_lds_dwordx4 v[216:217], off
	s_waitcnt vmcnt(8) lgkmcnt(0)
	s_barrier
; #define PG8_STAGE(bufoff, gbase, voff) do { _Pragma("unroll") for (int _i = 0; _i < 2; ++_i) \
;         __builtin_amdgcn_global_load_lds((const unsigned*)((const char*)(gbase) + (voff)[_i]), (LAS unsigned*)(lds + (bufoff) + ldsw + _i * 8192), 16, 0, 0); } while (0)
; #define PG8_LDA(dst, b, h) do { _Pragma("unroll") for (int m = 0; m < 4; ++m) _Pragma("unroll") for (int k = 0; k < 2; ++k) dst[m][k] = *(const LAS bf16x8*)(lds + PG8_SA(b, h) + aoff + m * 2048 + k * 1024); } while (0)
; #define PG8_LDB(dst, b, h) do { _Pragma("unroll") for (int n = 0; n < 2; ++n) _Pragma("unroll") for (int k = 0; k < 2; ++k) dst[n][k] = *(const LAS bf16x8*)(lds + PG8_SB(b, h) + boff + n * 2048 + k * 1024); } while (0)
; #define PG8_MMA(ai, bj, At, Bt) do { __builtin_amdgcn_s_setprio(1); _Pragma("unroll") for (int m = 0; m < 4; ++m) _Pragma("unroll") for (int n = 0; n < 2; ++n) _Pragma("unroll") for (int k = 0; k < 2; ++k) \
;         acc[ai][bj][m][n] = __builtin_amdgcn_mfma_f32_16x16x32_bf16(Bt[n][k], At[m][k], acc[ai][bj][m][n], 0, 0, 0); __builtin_amdgcn_s_setprio(0); } while (0)
; #define PG8_WAIT_V(n) asm volatile("s_waitcnt vmcnt(" #n ")" ::: "memory")
; #define PG8_WAIT_L(n) asm volatile("s_waitcnt lgkmcnt(" #n ")" ::: "memory")
; #define PG8_BAR __builtin_amdgcn_s_barrier()
; #define PG8_SCHED __builtin_amdgcn_sched_barrier(0)
; template <class Epi, class Sched, bool ABLK = false, bool ALIGN_EPI = true, bool SP2 = true, bool BBLK = true>
; __device__ __forceinline__ void gemm_phase(LAS unsigned char* lds, const Gemm g, const Sched& S, const Epi& E) {
;     ...
;             PG8_LDB(B0, 0, 0); PG8_LDB(B1, 0, 1); PG8_SCHED; PG8_LDA(At, 0, 0); PG8_STAGE(PG8_SA(1, 1), a1 + hstepA, voffA);
;             PG8_WAIT_V(8); PG8_WAIT_L(0); PG8_BAR; PG8_MMA(0, 0, At, B0); PG8_MMA(0, 1, At, B1); PG8_BAR; PG8_SCHED;
;             PG8_LDA(At, 0, 1); PG8_STAGE(PG8_SB(0, 0), b2, voffB); PG8_STAGE(PG8_SB(0, 1), b2 + hstepB, voffB); PG8_STAGE(PG8_SA(0, 0), a2, voffA);
;             PG8_WAIT_V(8); PG8_WAIT_L(0); PG8_BAR; PG8_MMA(1, 0, At, B0); PG8_MMA(1, 1, At, B1); PG8_BAR; PG8_SCHED;
	v_mfma_f32_16x16x32_bf16 v[122:125], v[152:155], v[184:187], v[122:125]
	v_mfma_f32_16x16x32_bf16 v[118:121], v[160:163], v[184:187], v[118:121]
	v_mfma_f32_16x16x32_bf16 v[106:109], v[152:155], v[192:195], v[106:109]
	v_mfma_f32_16x16x32_bf16 v[102:105], v[160:163], v[192:195], v[102:105]
	v_mfma_f32_16x16x32_bf16 v[90:93], v[152:155], v[200:203], v[90:93]
	v_mfma_f32_16x16x32_bf16 v[86:89], v[160:163], v[200:203], v[86:89]
	v_mfma_f32_16x16x32_bf16 v[74:77], v[152:155], v[208:211], v[74:77]
	v_mfma_f32_16x16x32_bf16 v[70:73], v[160:163], v[208:211], v[70:73]
	v_mfma_f32_16x16x32_bf16 v[122:125], v[156:159], v[188:191], v[122:125]
	v_mfma_f32_16x16x32_bf16 v[118:121], v[164:167], v[188:191], v[118:121]
	v_mfma_f32_16x16x32_bf16 v[106:109], v[156:159], v[196:199], v[106:109]
	v_mfma_f32_16x16x32_bf16 v[102:105], v[164:167], v[196:199], v[102:105]
	v_mfma_f32_16x16x32_bf16 v[90:93], v[156:159], v[204:207], v[90:93]
	v_mfma_f32_16x16x32_bf16 v[86:89], v[164:167], v[204:207], v[86:89]
	v_mfma_f32_16x16x32_bf16 v[74:77], v[156:159], v[212:215], v[74:77]
	v_mfma_f32_16x16x32_bf16 v[70:73], v[164:167], v[212:215], v[70:73]
	v_mfma_f32_16x16x32_bf16 v[126:129], v[168:171], v[184:187], v[126:129]
	v_mfma_f32_16x16x32_bf16 v[114:117], v[176:179], v[184:187], v[114:117]
	v_mfma_f32_16x16x32_bf16 v[110:113], v[168:171], v[192:195], v[110:113]
	v_mfma_f32_16x16x32_bf16 v[98:101], v[176:179], v[192:195], v[98:101]
	v_mfma_f32_16x16x32_bf16 v[94:97], v[168:171], v[200:203], v[94:97]
	v_mfma_f32_16x16x32_bf16 v[82:85], v[176:179], v[200:203], v[82:85]
	v_mfma_f32_16x16x32_bf16 v[78:81], v[168:171], v[208:211], v[78:81]
	v_mfma_f32_16x16x32_bf16 v[66:69], v[176:179], v[208:211], v[66:69]
	v_mfma_f32_16x16x32_bf16 v[126:129], v[172:175], v[188:191], v[126:129]
	v_mfma_f32_16x16x32_bf16 v[114:117], v[180:183], v[188:191], v[114:117]
	v_mfma_f32_16x16x32_bf16 v[110:113], v[172:175], v[196:199], v[110:113]
	v_mfma_f32_16x16x32_bf16 v[98:101], v[180:183], v[196:199], v[98:101]
	v_mfma_f32_16x16x32_bf16 v[94:97], v[172:175], v[204:207], v[94:97]
	v_mfma_f32_16x16x32_bf16 v[82:85], v[180:183], v[204:207], v[82:85]
	v_mfma_f32_16x16x32_bf16 v[78:81], v[172:175], v[212:215], v[78:81]
	v_mfma_f32_16x16x32_bf16 v[66:69], v[180:183], v[212:215], v[66:69]
	s_barrier
	s_add_i32 s53, s72, s36
	s_mov_b32 m0, s53
	ds_read_b128 v[184:187], v150 offset:16384
	ds_read_b128 v[188:191], v150 offset:17408
	ds_read_b128 v[192:195], v150 offset:18432
	ds_read_b128 v[196:199], v150 offset:19456
	ds_read_b128 v[200:203], v150 offset:20480
	ds_read_b128 v[204:207], v150 offset:21504
	ds_read_b128 v[208:211], v150 offset:22528
	ds_read_b128 v[212:215], v150 offset:23552
	global_load_lds_dwordx4 v134, s[30:31]
	s_add_i32 m0, s53, 0x2000
	s_add_u32 s54, s30, 0x4000
	s_addc_u32 s55, s31, 0
	s_add_i32 s53, s73, s36
	global_load_lds_dwordx4 v130, s[30:31]
	s_mov_b32 m0, s53
	s_nop 0
	global_load_lds_dwordx4 v134, s[54:55]
	s_add_i32 m0, s53, 0x2000
	s_nop 0
	global_load_lds_dwordx4 v130, s[54:55]
	s_mov_b32 m0, s21
	s_nop 0
	global_load_lds_dwordx4 v136, s[34:35]
	s_mov_b32 m0, s23
	s_nop 0
	global_load_lds_dwordx4 v132, s[34:35]
	s_waitcnt vmcnt(8) lgkmcnt(0)
	s_barrier
	v_mfma_f32_16x16x32_bf16 v[58:61], v[152:155], v[184:187], v[58:61]
	v_mfma_f32_16x16x32_bf16 v[54:57], v[160:163], v[184:187], v[54:57]
	v_mfma_f32_16x16x32_bf16 v[42:45], v[152:155], v[192:195], v[42:45]
	v_mfma_f32_16x16x32_bf16 v[38:41], v[160:163], v[192:195], v[38:41]
	v_mfma_f32_16x16x32_bf16 v[26:29], v[152:155], v[200:203], v[26:29]
	v_mfma_f32_16x16x32_bf16 v[22:25], v[160:163], v[200:203], v[22:25]
	v_mfma_f32_16x16x32_bf16 v[10:13], v[152:155], v[208:211], v[10:13]
	v_mfma_f32_16x16x32_bf16 v[6:9], v[160:163], v[208:211], v[6:9]
	v_mfma_f32_16x16x32_bf16 v[58:61], v[156:159], v[188:191], v[58:61]
	v_mfma_f32_16x16x32_bf16 v[54:57], v[164:167], v[188:191], v[54:57]
	v_mfma_f32_16x16x32_bf16 v[42:45], v[156:159], v[196:199], v[42:45]
	v_mfma_f32_16x16x32_bf16 v[38:41], v[164:167], v[196:199], v[38:41]
	v_mfma_f32_16x16x32_bf16 v[26:29], v[156:159], v[204:207], v[26:29]
	v_mfma_f32_16x16x32_bf16 v[22:25], v[164:167], v[204:207], v[22:25]
	v_mfma_f32_16x16x32_bf16 v[10:13], v[156:159], v[212:215], v[10:13]
	v_mfma_f32_16x16x32_bf16 v[6:9], v[164:167], v[212:215], v[6:9]
	v_mfma_f32_16x16x32_bf16 v[62:65], v[168:171], v[184:187], v[62:65]
	v_mfma_f32_16x16x32_bf16 v[50:53], v[176:179], v[184:187], v[50:53]
	v_mfma_f32_16x16x32_bf16 v[46:49], v[168:171], v[192:195], v[46:49]
	v_mfma_f32_16x16x32_bf16 v[34:37], v[176:179], v[192:195], v[34:37]
	v_mfma_f32_16x16x32_bf16 v[30:33], v[168:171], v[200:203], v[30:33]
	v_mfma_f32_16x16x32_bf16 v[18:21], v[176:179], v[200:203], v[18:21]
	v_mfma_f32_16x16x32_bf16 v[14:17], v[168:171], v[208:211], v[14:17]
	v_mfma_f32_16x16x32_bf16 v[2:5], v[176:179], v[208:211], v[2:5]
	v_mfma_f32_16x16x32_bf16 v[62:65], v[172:175], v[188:191], v[62:65]
	v_mfma_f32_16x16x32_bf16 v[50:53], v[180:183], v[188:191], v[50:53]
	v_mfma_f32_16x16x32_bf16 v[46:49], v[172:175], v[196:199], v[46:49]
	v_mfma_f32_16x16x32_bf16 v[34:37], v[180:183], v[196:199], v[34:37]
	v_mfma_f32_16x16x32_bf16 v[30:33], v[172:175], v[204:207], v[30:33]
	v_mfma_f32_16x16x32_bf16 v[18:21], v[180:183], v[204:207], v[18:21]
	v_mfma_f32_16x16x32_bf16 v[14:17], v[172:175], v[212:215], v[14:17]
	v_mfma_f32_16x16x32_bf16 v[2:5], v[180:183], v[212:215], v[2:5]
	s_barrier
; #define PG8_STAGE(bufoff, gbase, voff) do { _Pragma("unroll") for (int _i = 0; _i < 2; ++_i) \
;         __builtin_amdgcn_global_load_lds((const unsigned*)((const char*)(gbase) + (voff)[_i]), (LAS unsigned*)(lds + (bufoff) + ldsw + _i * 8192), 16, 0, 0); } while (0)
; #define PG8_LDA(dst, b, h) do { _Pragma("unroll") for (int m = 0; m < 4; ++m) _Pragma("unroll") for (int k = 0; k < 2; ++k) dst[m][k] = *(const LAS bf16x8*)(lds + PG8_SA(b, h) + aoff + m * 2048 + k * 1024); } while (0)
; #define PG8_LDB(dst, b, h) do { _Pragma("unroll") for (int n = 0; n < 2; ++n) _Pragma("unroll") for (int k = 0; k < 2; ++k) dst[n][k] = *(const LAS bf16x8*)(lds + PG8_SB(b, h) + boff + n * 2048 + k * 1024); } while (0)
; #define PG8_MMA(ai, bj, At, Bt) do { __builtin_amdgcn_s_setprio(1); _Pragma("unroll") for (int m = 0; m < 4; ++m) _Pragma("unroll") for (int n = 0; n < 2; ++n) _Pragma("unroll") for (int k = 0; k < 2; ++k) \
;         acc[ai][bj][m][n] = __builtin_amdgcn_mfma_f32_16x16x32_bf16(Bt[n][k], At[m][k], acc[ai][bj][m][n], 0, 0, 0); __builtin_amdgcn_s_setprio(0); } while (0)
; #define PG8_WAIT_V(n) asm volatile("s_waitcnt vmcnt(" #n ")" ::: "memory")
; #define PG8_WAIT_L(n) asm volatile("s_waitcnt lgkmcnt(" #n ")" ::: "memory")
; #define PG8_BAR __builtin_amdgcn_s_barrier()
; #define PG8_SCHED __builtin_amdgcn_sched_barrier(0)
; template <class Epi, class Sched, bool ABLK = false, bool ALIGN_EPI = true, bool SP2 = true, bool BBLK = true>
; __device__ __forceinline__ void gemm_phase(LAS unsigned char* lds, const Gemm g, const Sched& S, const Epi& E) {
;     ...
;             PG8_LDB(B0, 1, 0); PG8_LDB(B1, 1, 1); PG8_SCHED; PG8_LDA(At, 1, 0); PG8_STAGE(PG8_SA(0, 1), a2 + hstepA, voffA);
;             PG8_WAIT_V(8); PG8_WAIT_L(0); PG8_BAR; PG8_MMA(0, 0, At, B0); PG8_MMA(0, 1, At, B1); PG8_BAR; PG8_SCHED;
;             PG8_LDA(At, 1, 1); PG8_STAGE(PG8_SB(1, 0), b3, voffB); PG8_STAGE(PG8_SB(1, 1), b3 + hstepB, voffB); PG8_STAGE(PG8_SA(1, 0), a3, voffA);
;             PG8_WAIT_V(8); PG8_WAIT_L(0); PG8_BAR; PG8_MMA(1, 0, At, B0); PG8_MMA(1, 1, At, B1); PG8_BAR; PG8_SCHED;
	v_add_u32_e32 v151, s60, v146
	ds_read_b128 v[152:155], v151
	ds_read_b128 v[156:159], v151 offset:1024
	ds_read_b128 v[160:163], v151 offset:2048
	ds_read_b128 v[164:167], v151 offset:3072
	v_add_u32_e32 v151, s61, v146
	ds_read_b128 v[168:171], v151
	ds_read_b128 v[172:175], v151 offset:1024
	ds_read_b128 v[176:179], v151 offset:2048
	ds_read_b128 v[180:183], v151 offset:3072
	s_add_u32 s34, s34, 0x80000
	s_addc_u32 s35, s35, 0
	s_mov_b32 m0, s39
	ds_read_b128 v[184:187], v150 offset:32768
	ds_read_b128 v[188:191], v150 offset:33792
	ds_read_b128 v[192:195], v150 offset:34816
	ds_read_b128 v[196:199], v150 offset:35840
	ds_read_b128 v[200:203], v150 offset:36864
	ds_read_b128 v[204:207], v150 offset:37888
	ds_read_b128 v[208:211], v150 offset:38912
	ds_read_b128 v[212:215], v150 offset:39936
	global_load_lds_dwordx4 v136, s[34:35]
	s_mov_b32 m0, s40
	s_nop 0
	global_load_lds_dwordx4 v132, s[34:35]
	s_waitcnt vmcnt(8) lgkmcnt(0)
	s_barrier
	v_mfma_f32_16x16x32_bf16 v[122:125], v[152:155], v[184:187], v[122:125]
	v_mfma_f32_16x16x32_bf16 v[118:121], v[160:163], v[184:187], v[118:121]
	v_mfma_f32_16x16x32_bf16 v[106:109], v[152:155], v[192:195], v[106:109]
	v_mfma_f32_16x16x32_bf16 v[102:105], v[160:163], v[192:195], v[102:105]
	v_mfma_f32_16x16x32_bf16 v[90:93], v[152:155], v[200:203], v[90:93]
	v_mfma_f32_16x16x32_bf16 v[86:89], v[160:163], v[200:203], v[86:89]
	v_mfma_f32_16x16x32_bf16 v[74:77], v[152:155], v[208:211], v[74:77]
	v_mfma_f32_16x16x32_bf16 v[70:73], v[160:163], v[208:211], v[70:73]
	v_mfma_f32_16x16x32_bf16 v[122:125], v[156:159], v[188:191], v[122:125]
	v_mfma_f32_16x16x32_bf16 v[118:121], v[164:167], v[188:191], v[118:121]
	v_mfma_f32_16x16x32_bf16 v[106:109], v[156:159], v[196:199], v[106:109]
	v_mfma_f32_16x16x32_bf16 v[102:105], v[164:167], v[196:199], v[102:105]
	v_mfma_f32_16x16x32_bf16 v[90:93], v[156:159], v[204:207], v[90:93]
	v_mfma_f32_16x16x32_bf16 v[86:89], v[164:167], v[204:207], v[86:89]
	v_mfma_f32_16x16x32_bf16 v[74:77], v[156:159], v[212:215], v[74:77]
	v_mfma_f32_16x16x32_bf16 v[70:73], v[164:167], v[212:215], v[70:73]
	v_mfma_f32_16x16x32_bf16 v[126:129], v[168:171], v[184:187], v[126:129]
	v_mfma_f32_16x16x32_bf16 v[114:117], v[176:179], v[184:187], v[114:117]
	v_mfma_f32_16x16x32_bf16 v[110:113], v[168:171], v[192:195], v[110:113]
	v_mfma_f32_16x16x32_bf16 v[98:101], v[176:179], v[192:195], v[98:101]
	v_mfma_f32_16x16x32_bf16 v[94:97], v[168:171], v[200:203], v[94:97]
	v_mfma_f32_16x16x32_bf16 v[82:85], v[176:179], v[200:203], v[82:85]
	v_mfma_f32_16x16x32_bf16 v[78:81], v[168:171], v[208:211], v[78:81]
	v_mfma_f32_16x16x32_bf16 v[66:69], v[176:179], v[208:211], v[66:69]
	v_mfma_f32_16x16x32_bf16 v[126:129], v[172:175], v[188:191], v[126:129]
	v_mfma_f32_16x16x32_bf16 v[114:117], v[180:183], v[188:191], v[114:117]
	v_mfma_f32_16x16x32_bf16 v[110:113], v[172:175], v[196:199], v[110:113]
	v_mfma_f32_16x16x32_bf16 v[98:101], v[180:183], v[196:199], v[98:101]
	v_mfma_f32_16x16x32_bf16 v[94:97], v[172:175], v[204:207], v[94:97]
	v_mfma_f32_16x16x32_bf16 v[82:85], v[180:183], v[204:207], v[82:85]
	v_mfma_f32_16x16x32_bf16 v[78:81], v[172:175], v[212:215], v[78:81]
	v_mfma_f32_16x16x32_bf16 v[66:69], v[180:183], v[212:215], v[66:69]
	s_barrier
	s_add_u32 s34, s30, 0x8000
	s_addc_u32 s35, s31, 0
	s_add_i32 s53, s60, s36
	s_mov_b32 m0, s53
	ds_read_b128 v[184:187], v150 offset:49152
	ds_read_b128 v[188:191], v150 offset:50176
	ds_read_b128 v[192:195], v150 offset:51200
	ds_read_b128 v[196:199], v150 offset:52224
	ds_read_b128 v[200:203], v150 offset:53248
	ds_read_b128 v[204:207], v150 offset:54272
	ds_read_b128 v[208:211], v150 offset:55296
	ds_read_b128 v[212:215], v150 offset:56320
	global_load_lds_dwordx4 v134, s[34:35]
	s_add_i32 m0, s53, 0x2000
	s_add_u32 s30, s30, 0xc000
	v_lshl_add_u64 v[216:217], s[34:35], 0, v[130:131]
	s_addc_u32 s31, s31, 0
	s_add_i32 s34, s61, s36
	global_load_lds_dwordx4 v[216:217], off
	s_mov_b32 m0, s34
	s_nop 0
	global_load_lds_dwordx4 v134, s[30:31]
	s_add_i32 m0, s34, 0x2000
	s_nop 0
	global_load_lds_dwordx4 v130, s[30:31]
	s_mov_b32 m0, s42
	s_nop 0
	global_load_lds_dwordx4 v136, s[28:29]
	s_mov_b32 m0, s43
	s_nop 0
	global_load_lds_dwordx4 v132, s[28:29]
	s_waitcnt vmcnt(8) lgkmcnt(0)
	s_barrier
	v_mfma_f32_16x16x32_bf16 v[58:61], v[152:155], v[184:187], v[58:61]
	v_mfma_f32_16x16x32_bf16 v[54:57], v[160:163], v[184:187], v[54:57]
	v_mfma_f32_16x16x32_bf16 v[42:45], v[152:155], v[192:195], v[42:45]
	v_mfma_f32_16x16x32_bf16 v[38:41], v[160:163], v[192:195], v[38:41]
	v_mfma_f32_16x16x32_bf16 v[26:29], v[152:155], v[200:203], v[26:29]
	v_mfma_f32_16x16x32_bf16 v[22:25], v[160:163], v[200:203], v[22:25]
	v_mfma_f32_16x16x32_bf16 v[10:13], v[152:155], v[208:211], v[10:13]
	v_mfma_f32_16x16x32_bf16 v[6:9], v[160:163], v[208:211], v[6:9]
	v_mfma_f32_16x16x32_bf16 v[58:61], v[156:159], v[188:191], v[58:61]
	v_mfma_f32_16x16x32_bf16 v[54:57], v[164:167], v[188:191], v[54:57]
	v_mfma_f32_16x16x32_bf16 v[42:45], v[156:159], v[196:199], v[42:45]
	v_mfma_f32_16x16x32_bf16 v[38:41], v[164:167], v[196:199], v[38:41]
	v_mfma_f32_16x16x32_bf16 v[26:29], v[156:159], v[204:207], v[26:29]
	v_mfma_f32_16x16x32_bf16 v[22:25], v[164:167], v[204:207], v[22:25]
	v_mfma_f32_16x16x32_bf16 v[10:13], v[156:159], v[212:215], v[10:13]
	v_mfma_f32_16x16x32_bf16 v[6:9], v[164:167], v[212:215], v[6:9]
	v_mfma_f32_16x16x32_bf16 v[62:65], v[168:171], v[184:187], v[62:65]
	v_mfma_f32_16x16x32_bf16 v[50:53], v[176:179], v[184:187], v[50:53]
	v_mfma_f32_16x16x32_bf16 v[46:49], v[168:171], v[192:195], v[46:49]
	v_mfma_f32_16x16x32_bf16 v[34:37], v[176:179], v[192:195], v[34:37]
	v_mfma_f32_16x16x32_bf16 v[30:33], v[168:171], v[200:203], v[30:33]
	v_mfma_f32_16x16x32_bf16 v[18:21], v[176:179], v[200:203], v[18:21]
	v_mfma_f32_16x16x32_bf16 v[14:17], v[168:171], v[208:211], v[14:17]
	v_mfma_f32_16x16x32_bf16 v[2:5], v[176:179], v[208:211], v[2:5]
	v_mfma_f32_16x16x32_bf16 v[62:65], v[172:175], v[188:191], v[62:65]
	v_mfma_f32_16x16x32_bf16 v[50:53], v[180:183], v[188:191], v[50:53]
	v_mfma_f32_16x16x32_bf16 v[46:49], v[172:175], v[196:199], v[46:49]
	v_mfma_f32_16x16x32_bf16 v[34:37], v[180:183], v[196:199], v[34:37]
	v_mfma_f32_16x16x32_bf16 v[30:33], v[172:175], v[204:207], v[30:33]
	v_mfma_f32_16x16x32_bf16 v[18:21], v[180:183], v[204:207], v[18:21]
	v_mfma_f32_16x16x32_bf16 v[14:17], v[172:175], v[212:215], v[14:17]
	v_mfma_f32_16x16x32_bf16 v[2:5], v[180:183], v[212:215], v[2:5]
	s_barrier
	s_add_i32 s52, s52, 2
	s_add_u32 s26, s26, 0x100
	s_addc_u32 s27, s27, 0
	s_add_u32 s50, s50, 0x10000
	s_addc_u32 s51, s51, 0
	s_cmp_gt_u32 s52, 29
	s_cbranch_scc0 .LBB0_2138
	s_and_b64 vcc, exec, s[6:7]
	s_cbranch_vccz .LBB0_2141
	s_barrier

; template <class Epi, class Sched, bool ABLK = false, bool ALIGN_EPI = true, bool SP2 = true, bool BBLK = true>
; __device__ __forceinline__ void gemm_phase(LAS unsigned char* lds, const Gemm g, const Sched& S, const Epi& E) {
;     ...
;             const char* a1 = a_tile(uA, tbA + t + 1);
;             const char* a2 = last ? a_tile(nuA, ntbA) : a_tile(uA, tbA + t + 2); const char* b2 = last ? nB : cB + (size_t)(t + 2) * kstepB;
;             const char* a3 = last ? a_tile(nuA, ntbA + 1) : a_tile(uA, tbA + t + 3); const char* b3 = b2 + kstepB;
.Lksel_23:
	s_mov_b32 s29, s49
	s_mov_b32 s28, s48
	s_mov_b32 s31, s11
	s_mov_b32 s30, s13
	s_mov_b32 s35, s4
	s_mov_b32 s34, s5
	s_branch .Lksel_23_back

; #define PG8_STAGE(bufoff, gbase, voff) do { _Pragma("unroll") for (int _i = 0; _i < 2; ++_i) \
;         __builtin_amdgcn_global_load_lds((const unsigned*)((const char*)(gbase) + (voff)[_i]), (LAS unsigned*)(lds + (bufoff) + ldsw + _i * 8192), 16, 0, 0); } while (0)
; #define PG8_WAIT_V(n) asm volatile("s_waitcnt vmcnt(" #n ")" ::: "memory")
; template <class Epi, class Sched, bool ABLK = false, bool ALIGN_EPI = true, bool SP2 = true, bool BBLK = true>
; __device__ __forceinline__ void gemm_phase(LAS unsigned char* lds, const Gemm g, const Sched& S, const Epi& E) {
;     ...
;     for (;;) {
;         const bool has_next = S.next(ui + 1, nxt);
;         const int nt = cur.nt;
;         const char* nuA = has_next ? a_unit(nxt) : uA; const int ntbA = has_next ? nxt.k0 / BK : tbA; const char* nB = has_next ? (const char*)g.Bt + (size_t)nxt.pn * tstepB + b_k0(nxt.k0) : cB;
;         for (int t = 0; t < nt; t += 2) {
;             const bool last = (t == nt - 2);
;             const char* a1 = a_tile(uA, tbA + t + 1);
;             const char* a2 = last ? a_tile(nuA, ntbA) : a_tile(uA, tbA + t + 2); const char* b2 = last ? nB : cB + (size_t)(t + 2) * kstepB;
;             const char* a3 = last ? a_tile(nuA, ntbA + 1) : a_tile(uA, tbA + t + 3); const char* b3 = b2 + kstepB;
;             if (last && has_next) S.a_ready(nxt);
;             if constexpr (SP2) {
;             PG8_LDB(B0, 0, 0); PG8_LDB(B1, 0, 1); PG8_SCHED; PG8_LDA(At, 0, 0); PG8_STAGE(PG8_SA(1, 1), a1 + hstepA, voffA);
;             PG8_WAIT_V(8); PG8_WAIT_L(0); PG8_BAR; PG8_MMA(0, 0, At, B0); PG8_MMA(0, 1, At, B1); PG8_BAR; PG8_SCHED;
;             PG8_LDA(At, 0, 1); PG8_STAGE(PG8_SB(0, 0), b2, voffB); PG8_STAGE(PG8_SB(0, 1), b2 + hstepB, voffB); PG8_STAGE(PG8_SA(0, 0), a2, voffA);
;             PG8_WAIT_V(8); PG8_WAIT_L(0); PG8_BAR; PG8_MMA(1, 0, At, B0); PG8_MMA(1, 1, At, B1); PG8_BAR; PG8_SCHED;
;             PG8_LDB(B0, 1, 0); PG8_LDB(B1, 1, 1); PG8_SCHED; PG8_LDA(At, 1, 0); PG8_STAGE(PG8_SA(0, 1), a2 + hstepA, voffA);
;             PG8_WAIT_V(8); PG8_WAIT_L(0); PG8_BAR; PG8_MMA(0, 0, At, B0); PG8_MMA(0, 1, At, B1); PG8_BAR; PG8_SCHED;
;             PG8_LDA(At, 1, 1); PG8_STAGE(PG8_SB(1, 0), b3, voffB); PG8_STAGE(PG8_SB(1, 1), b3 + hstepB, voffB); PG8_STAGE(PG8_SA(1, 0), a3, voffA);
;             PG8_WAIT_V(8); PG8_WAIT_L(0); PG8_BAR; PG8_MMA(1, 0, At, B0); PG8_MMA(1, 1, At, B1); PG8_BAR; PG8_SCHED;
.LBB0_2262:
	s_ashr_i32 s13, s12, 31
	s_lshl_b64 s[4:5], s[12:13], 20
	s_add_u32 s16, s41, s4
	s_addc_u32 s17, s42, s5
	s_and_b64 s[4:5], s[18:19], exec
	s_cselect_b32 s4, s17, s27
	s_cselect_b32 s5, s16, s26
	s_ashr_i32 s15, s14, 31
	s_lshl_b64 s[20:21], s[14:15], 20
	s_add_u32 s20, s38, s20
	s_addc_u32 s21, s39, s21
	s_and_b64 s[30:31], s[18:19], exec
	s_cselect_b32 s13, s21, s29
	s_cselect_b32 s15, s20, s28
	s_add_u32 s23, s5, 0x80
	s_addc_u32 s54, s4, 0
	s_add_u32 s55, s28, 0x10000
	v_mov_b32_e32 v2, 0
	s_addc_u32 s56, s29, 0
	v_lshl_add_u64 v[164:165], s[26:27], 0, v[160:161]
	v_lshl_add_u64 v[166:167], s[26:27], 0, v[162:163]
	s_mov_b32 s57, -2
	s_mov_b64 s[28:29], 0
	ds_read_b128 v[172:175], v168
	ds_read_b128 v[176:179], v168 offset:1024
	ds_read_b128 v[180:183], v168 offset:2048
	ds_read_b128 v[184:187], v168 offset:3072
	ds_read_b128 v[188:191], v169
	ds_read_b128 v[192:195], v169 offset:1024
	ds_read_b128 v[196:199], v169 offset:2048
	ds_read_b128 v[200:203], v169 offset:3072
	s_add_u32 s30, s26, s28
	s_addc_u32 s31, s27, s29
	s_add_u32 s36, s30, 0x100
	s_addc_u32 s37, s31, 0
	s_add_u32 s30, s30, 0x180
	s_addc_u32 s31, s31, 0
	s_mov_b32 s35, s56
	s_mov_b32 s34, s55
	s_mov_b32 m0, s50
	v_lshl_add_u64 v[236:237], v[164:165], 0, s[28:29]
	ds_read_b128 v[204:207], v170
	ds_read_b128 v[208:211], v170 offset:1024
	ds_read_b128 v[212:215], v170 offset:2048
	ds_read_b128 v[216:219], v170 offset:3072
	ds_read_b128 v[220:223], v170 offset:4096
	ds_read_b128 v[224:227], v170 offset:5120
	ds_read_b128 v[228:231], v170 offset:6144
	ds_read_b128 v[232:235], v170 offset:7168
	global_load_lds_dwordx4 v[236:237], off
	v_lshl_add_u64 v[236:237], v[166:167], 0, s[28:29]
	s_mov_b32 m0, s51
	s_nop 0
	global_load_lds_dwordx4 v[236:237], off
	s_waitcnt vmcnt(8) lgkmcnt(0)
	s_barrier
	v_mfma_f32_16x16x32_bf16 v[126:129], v[172:175], v[204:207], 0
	v_mfma_f32_16x16x32_bf16 v[122:125], v[180:183], v[204:207], 0
	v_mfma_f32_16x16x32_bf16 v[110:113], v[172:175], v[212:215], 0
	v_mfma_f32_16x16x32_bf16 v[106:109], v[180:183], v[212:215], 0
	v_mfma_f32_16x16x32_bf16 v[94:97], v[172:175], v[220:223], 0
	v_mfma_f32_16x16x32_bf16 v[90:93], v[180:183], v[220:223], 0
	v_mfma_f32_16x16x32_bf16 v[78:81], v[172:175], v[228:231], 0
	v_mfma_f32_16x16x32_bf16 v[74:77], v[180:183], v[228:231], 0
	v_mfma_f32_16x16x32_bf16 v[126:129], v[176:179], v[208:211], v[126:129]
	v_mfma_f32_16x16x32_bf16 v[122:125], v[184:187], v[208:211], v[122:125]
	v_mfma_f32_16x16x32_bf16 v[110:113], v[176:179], v[216:219], v[110:113]
	v_mfma_f32_16x16x32_bf16 v[106:109], v[184:187], v[216:219], v[106:109]
	v_mfma_f32_16x16x32_bf16 v[94:97], v[176:179], v[224:227], v[94:97]
	v_mfma_f32_16x16x32_bf16 v[90:93], v[184:187], v[224:227], v[90:93]
	v_mfma_f32_16x16x32_bf16 v[78:81], v[176:179], v[232:235], v[78:81]
	v_mfma_f32_16x16x32_bf16 v[74:77], v[184:187], v[232:235], v[74:77]
	v_mfma_f32_16x16x32_bf16 v[118:121], v[188:191], v[204:207], 0
	v_mfma_f32_16x16x32_bf16 v[114:117], v[196:199], v[204:207], 0
	v_mfma_f32_16x16x32_bf16 v[102:105], v[188:191], v[212:215], 0
	v_mfma_f32_16x16x32_bf16 v[98:101], v[196:199], v[212:215], 0
	v_mfma_f32_16x16x32_bf16 v[86:89], v[188:191], v[220:223], 0
	v_mfma_f32_16x16x32_bf16 v[82:85], v[196:199], v[220:223], 0
	v_mfma_f32_16x16x32_bf16 v[70:73], v[188:191], v[228:231], 0
	v_mfma_f32_16x16x32_bf16 v[66:69], v[196:199], v[228:231], 0
	v_mfma_f32_16x16x32_bf16 v[118:121], v[192:195], v[208:211], v[118:121]
	v_mfma_f32_16x16x32_bf16 v[114:117], v[200:203], v[208:211], v[114:117]
	v_mfma_f32_16x16x32_bf16 v[102:105], v[192:195], v[216:219], v[102:105]
	v_mfma_f32_16x16x32_bf16 v[98:101], v[200:203], v[216:219], v[98:101]
	v_mfma_f32_16x16x32_bf16 v[86:89], v[192:195], v[224:227], v[86:89]
	v_mfma_f32_16x16x32_bf16 v[82:85], v[200:203], v[224:227], v[82:85]
	v_mfma_f32_16x16x32_bf16 v[70:73], v[192:195], v[232:235], v[70:73]
	v_mfma_f32_16x16x32_bf16 v[66:69], v[200:203], v[232:235], v[66:69]
	s_barrier
	s_mov_b32 m0, s52
	s_add_u32 s58, s34, 0x4000
	ds_read_b128 v[204:207], v170 offset:16384
	ds_read_b128 v[208:211], v170 offset:17408
	ds_read_b128 v[212:215], v170 offset:18432
	ds_read_b128 v[216:219], v170 offset:19456
	ds_read_b128 v[220:223], v170 offset:20480
	ds_read_b128 v[224:227], v170 offset:21504
	ds_read_b128 v[228:231], v170 offset:22528
	ds_read_b128 v[232:235], v170 offset:23552
	global_load_lds_dwordx4 v134, s[34:35]
	s_mov_b32 m0, s53
	s_addc_u32 s59, s35, 0
	s_add_i32 s62, s73, s40
	global_load_lds_dwordx4 v130, s[34:35]
	s_mov_b32 m0, s62
	s_nop 0
	global_load_lds_dwordx4 v134, s[58:59]
	s_add_i32 m0, s62, 0x2000
	s_nop 0
	global_load_lds_dwordx4 v130, s[58:59]
	s_mov_b32 m0, s25
	s_nop 0
	global_load_lds_dwordx4 v136, s[36:37]
	s_mov_b32 m0, s43
	s_nop 0
	global_load_lds_dwordx4 v132, s[36:37]
	s_waitcnt vmcnt(8) lgkmcnt(0)
	s_barrier
; #define PG8_STAGE(bufoff, gbase, voff) do { _Pragma("unroll") for (int _i = 0; _i < 2; ++_i) \
;         __builtin_amdgcn_global_load_lds((const unsigned*)((const char*)(gbase) + (voff)[_i]), (LAS unsigned*)(lds + (bufoff) + ldsw + _i * 8192), 16, 0, 0); } while (0)
; #define PG8_LDA(dst, b, h) do { _Pragma("unroll") for (int m = 0; m < 4; ++m) _Pragma("unroll") for (int k = 0; k < 2; ++k) dst[m][k] = *(const LAS bf16x8*)(lds + PG8_SA(b, h) + aoff + m * 2048 + k * 1024); } while (0)
; #define PG8_LDB(dst, b, h) do { _Pragma("unroll") for (int n = 0; n < 2; ++n) _Pragma("unroll") for (int k = 0; k < 2; ++k) dst[n][k] = *(const LAS bf16x8*)(lds + PG8_SB(b, h) + boff + n * 2048 + k * 1024); } while (0)
; #define PG8_MMA(ai, bj, At, Bt) do { __builtin_amdgcn_s_setprio(1); _Pragma("unroll") for (int m = 0; m < 4; ++m) _Pragma("unroll") for (int n = 0; n < 2; ++n) _Pragma("unroll") for (int k = 0; k < 2; ++k) \
;         acc[ai][bj][m][n] = __builtin_amdgcn_mfma_f32_16x16x32_bf16(Bt[n][k], At[m][k], acc[ai][bj][m][n], 0, 0, 0); __builtin_amdgcn_s_setprio(0); } while (0)
; #define PG8_BAR __builtin_amdgcn_s_barrier()
; template <class Epi, class Sched, bool ABLK = false, bool ALIGN_EPI = true, bool SP2 = true, bool BBLK = true>
; __device__ __forceinline__ void gemm_phase(LAS unsigned char* lds, const Gemm g, const Sched& S, const Epi& E) {
;     ...
;             PG8_LDB(B0, 0, 0); PG8_LDB(B1, 0, 1); PG8_SCHED; PG8_LDA(At, 0, 0); PG8_STAGE(PG8_SA(1, 1), a1 + hstepA, voffA);
;             PG8_WAIT_V(8); PG8_WAIT_L(0); PG8_BAR; PG8_MMA(0, 0, At, B0); PG8_MMA(0, 1, At, B1); PG8_BAR; PG8_SCHED;
;             PG8_LDA(At, 0, 1); PG8_STAGE(PG8_SB(0, 0), b2, voffB); PG8_STAGE(PG8_SB(0, 1), b2 + hstepB, voffB); PG8_STAGE(PG8_SA(0, 0), a2, voffA);
;             PG8_WAIT_V(8); PG8_WAIT_L(0); PG8_BAR; PG8_MMA(1, 0, At, B0); PG8_MMA(1, 1, At, B1); PG8_BAR; PG8_SCHED;
;             PG8_LDB(B0, 1, 0); PG8_LDB(B1, 1, 1); PG8_SCHED; PG8_LDA(At, 1, 0); PG8_STAGE(PG8_SA(0, 1), a2 + hstepA, voffA);
;             PG8_WAIT_V(8); PG8_WAIT_L(0); PG8_BAR; PG8_MMA(0, 0, At, B0); PG8_MMA(0, 1, At, B1); PG8_BAR; PG8_SCHED;
;             PG8_LDA(At, 1, 1); PG8_STAGE(PG8_SB(1, 0), b3, voffB); PG8_STAGE(PG8_SB(1, 1), b3 + hstepB, voffB); PG8_STAGE(PG8_SA(1, 0), a3, voffA);
;             PG8_WAIT_V(8); PG8_WAIT_L(0); PG8_BAR; PG8_MMA(1, 0, At, B0); PG8_MMA(1, 1, At, B1); PG8_BAR; PG8_SCHED;
	v_mfma_f32_16x16x32_bf16 v[62:65], v[172:175], v[204:207], 0
	v_mfma_f32_16x16x32_bf16 v[58:61], v[180:183], v[204:207], 0
	v_mfma_f32_16x16x32_bf16 v[46:49], v[172:175], v[212:215], 0
	v_mfma_f32_16x16x32_bf16 v[42:45], v[180:183], v[212:215], 0
	v_mfma_f32_16x16x32_bf16 v[30:33], v[172:175], v[220:223], 0
	v_mfma_f32_16x16x32_bf16 v[26:29], v[180:183], v[220:223], 0
	v_mfma_f32_16x16x32_bf16 v[14:17], v[172:175], v[228:231], 0
	v_mfma_f32_16x16x32_bf16 v[10:13], v[180:183], v[228:231], 0
	v_mfma_f32_16x16x32_bf16 v[62:65], v[176:179], v[208:211], v[62:65]
	v_mfma_f32_16x16x32_bf16 v[58:61], v[184:187], v[208:211], v[58:61]
	v_mfma_f32_16x16x32_bf16 v[46:49], v[176:179], v[216:219], v[46:49]
	v_mfma_f32_16x16x32_bf16 v[42:45], v[184:187], v[216:219], v[42:45]
	v_mfma_f32_16x16x32_bf16 v[30:33], v[176:179], v[224:227], v[30:33]
	v_mfma_f32_16x16x32_bf16 v[26:29], v[184:187], v[224:227], v[26:29]
	v_mfma_f32_16x16x32_bf16 v[14:17], v[176:179], v[232:235], v[14:17]
	v_mfma_f32_16x16x32_bf16 v[10:13], v[184:187], v[232:235], v[10:13]
	v_mfma_f32_16x16x32_bf16 v[54:57], v[188:191], v[204:207], 0
	v_mfma_f32_16x16x32_bf16 v[50:53], v[196:199], v[204:207], 0
	v_mfma_f32_16x16x32_bf16 v[38:41], v[188:191], v[212:215], 0
	v_mfma_f32_16x16x32_bf16 v[34:37], v[196:199], v[212:215], 0
	v_mfma_f32_16x16x32_bf16 v[22:25], v[188:191], v[220:223], 0
	v_mfma_f32_16x16x32_bf16 v[18:21], v[196:199], v[220:223], 0
	v_mfma_f32_16x16x32_bf16 v[6:9], v[188:191], v[228:231], 0
	v_mfma_f32_16x16x32_bf16 v[2:5], v[196:199], v[228:231], 0
	v_mfma_f32_16x16x32_bf16 v[54:57], v[192:195], v[208:211], v[54:57]
	v_mfma_f32_16x16x32_bf16 v[50:53], v[200:203], v[208:211], v[50:53]
	v_mfma_f32_16x16x32_bf16 v[38:41], v[192:195], v[216:219], v[38:41]
	v_mfma_f32_16x16x32_bf16 v[34:37], v[200:203], v[216:219], v[34:37]
	v_mfma_f32_16x16x32_bf16 v[22:25], v[192:195], v[224:227], v[22:25]
	v_mfma_f32_16x16x32_bf16 v[18:21], v[200:203], v[224:227], v[18:21]
	v_mfma_f32_16x16x32_bf16 v[6:9], v[192:195], v[232:235], v[6:9]
	v_mfma_f32_16x16x32_bf16 v[2:5], v[200:203], v[232:235], v[2:5]
	s_barrier
	v_add_u32_e32 v171, s60, v1
	ds_read_b128 v[172:175], v171
	ds_read_b128 v[176:179], v171 offset:1024
	ds_read_b128 v[180:183], v171 offset:2048
	ds_read_b128 v[184:187], v171 offset:3072
	v_add_u32_e32 v171, s61, v1
	ds_read_b128 v[188:191], v171
	ds_read_b128 v[192:195], v171 offset:1024
	ds_read_b128 v[196:199], v171 offset:2048
	ds_read_b128 v[200:203], v171 offset:3072
	s_add_u32 s36, s36, 0x80000
	s_addc_u32 s37, s37, 0
	s_mov_b32 m0, s44
	ds_read_b128 v[204:207], v170 offset:32768
	ds_read_b128 v[208:211], v170 offset:33792
	ds_read_b128 v[212:215], v170 offset:34816
	ds_read_b128 v[216:219], v170 offset:35840
	ds_read_b128 v[220:223], v170 offset:36864
	ds_read_b128 v[224:227], v170 offset:37888
	ds_read_b128 v[228:231], v170 offset:38912
	ds_read_b128 v[232:235], v170 offset:39936
	global_load_lds_dwordx4 v136, s[36:37]
	s_mov_b32 m0, s45
	s_nop 0
	global_load_lds_dwordx4 v132, s[36:37]
	s_waitcnt vmcnt(8) lgkmcnt(0)
	s_barrier
	v_mfma_f32_16x16x32_bf16 v[126:129], v[172:175], v[204:207], v[126:129]
	v_mfma_f32_16x16x32_bf16 v[122:125], v[180:183], v[204:207], v[122:125]
	v_mfma_f32_16x16x32_bf16 v[110:113], v[172:175], v[212:215], v[110:113]
	v_mfma_f32_16x16x32_bf16 v[106:109], v[180:183], v[212:215], v[106:109]
	v_mfma_f32_16x16x32_bf16 v[94:97], v[172:175], v[220:223], v[94:97]
	v_mfma_f32_16x16x32_bf16 v[90:93], v[180:183], v[220:223], v[90:93]
	v_mfma_f32_16x16x32_bf16 v[78:81], v[172:175], v[228:231], v[78:81]
	v_mfma_f32_16x16x32_bf16 v[74:77], v[180:183], v[228:231], v[74:77]
	v_mfma_f32_16x16x32_bf16 v[126:129], v[176:179], v[208:211], v[126:129]
	v_mfma_f32_16x16x32_bf16 v[122:125], v[184:187], v[208:211], v[122:125]
	v_mfma_f32_16x16x32_bf16 v[110:113], v[176:179], v[216:219], v[110:113]
	v_mfma_f32_16x16x32_bf16 v[106:109], v[184:187], v[216:219], v[106:109]
	v_mfma_f32_16x16x32_bf16 v[94:97], v[176:179], v[224:227], v[94:97]
	v_mfma_f32_16x16x32_bf16 v[90:93], v[184:187], v[224:227], v[90:93]
	v_mfma_f32_16x16x32_bf16 v[78:81], v[176:179], v[232:235], v[78:81]
	v_mfma_f32_16x16x32_bf16 v[74:77], v[184:187], v[232:235], v[74:77]
	v_mfma_f32_16x16x32_bf16 v[118:121], v[188:191], v[204:207], v[118:121]
	v_mfma_f32_16x16x32_bf16 v[114:117], v[196:199], v[204:207], v[114:117]
	v_mfma_f32_16x16x32_bf16 v[102:105], v[188:191], v[212:215], v[102:105]
	v_mfma_f32_16x16x32_bf16 v[98:101], v[196:199], v[212:215], v[98:101]
	v_mfma_f32_16x16x32_bf16 v[86:89], v[188:191], v[220:223], v[86:89]
	v_mfma_f32_16x16x32_bf16 v[82:85], v[196:199], v[220:223], v[82:85]
	v_mfma_f32_16x16x32_bf16 v[70:73], v[188:191], v[228:231], v[70:73]
	v_mfma_f32_16x16x32_bf16 v[66:69], v[196:199], v[228:231], v[66:69]
	v_mfma_f32_16x16x32_bf16 v[118:121], v[192:195], v[208:211], v[118:121]
	v_mfma_f32_16x16x32_bf16 v[114:117], v[200:203], v[208:211], v[114:117]
	v_mfma_f32_16x16x32_bf16 v[102:105], v[192:195], v[216:219], v[102:105]
	v_mfma_f32_16x16x32_bf16 v[98:101], v[200:203], v[216:219], v[98:101]
	v_mfma_f32_16x16x32_bf16 v[86:89], v[192:195], v[224:227], v[86:89]
	v_mfma_f32_16x16x32_bf16 v[82:85], v[200:203], v[224:227], v[82:85]
	v_mfma_f32_16x16x32_bf16 v[70:73], v[192:195], v[232:235], v[70:73]
	v_mfma_f32_16x16x32_bf16 v[66:69], v[200:203], v[232:235], v[66:69]
	s_barrier
; #define PG8_STAGE(bufoff, gbase, voff) do { _Pragma("unroll") for (int _i = 0; _i < 2; ++_i) \
;         __builtin_amdgcn_global_load_lds((const unsigned*)((const char*)(gbase) + (voff)[_i]), (LAS unsigned*)(lds + (bufoff) + ldsw + _i * 8192), 16, 0, 0); } while (0)
; #define PG8_LDA(dst, b, h) do { _Pragma("unroll") for (int m = 0; m < 4; ++m) _Pragma("unroll") for (int k = 0; k < 2; ++k) dst[m][k] = *(const LAS bf16x8*)(lds + PG8_SA(b, h) + aoff + m * 2048 + k * 1024); } while (0)
; #define PG8_WAIT_V(n) asm volatile("s_waitcnt vmcnt(" #n ")" ::: "memory")
; #define PG8_WAIT_L(n) asm volatile("s_waitcnt lgkmcnt(" #n ")" ::: "memory")
; template <class Epi, class Sched, bool ABLK = false, bool ALIGN_EPI = true, bool SP2 = true, bool BBLK = true>
; __device__ __forceinline__ void gemm_phase(LAS unsigned char* lds, const Gemm g, const Sched& S, const Epi& E) {
;     ...
;         for (int t = 0; t < nt; t += 2) {
;             const bool last = (t == nt - 2);
;             const char* a1 = a_tile(uA, tbA + t + 1);
;             const char* a2 = last ? a_tile(nuA, ntbA) : a_tile(uA, tbA + t + 2); const char* b2 = last ? nB : cB + (size_t)(t + 2) * kstepB;
;             const char* a3 = last ? a_tile(nuA, ntbA + 1) : a_tile(uA, tbA + t + 3); const char* b3 = b2 + kstepB;
;             if (last && has_next) S.a_ready(nxt);
;             if constexpr (SP2) {
;             PG8_LDB(B0, 0, 0); PG8_LDB(B1, 0, 1); PG8_SCHED; PG8_LDA(At, 0, 0); PG8_STAGE(PG8_SA(1, 1), a1 + hstepA, voffA);
;             PG8_WAIT_V(8); PG8_WAIT_L(0); PG8_BAR; PG8_MMA(0, 0, At, B0); PG8_MMA(0, 1, At, B1); PG8_BAR; PG8_SCHED;
;             PG8_LDA(At, 0, 1); PG8_STAGE(PG8_SB(0, 0), b2, voffB); PG8_STAGE(PG8_SB(0, 1), b2 + hstepB, voffB); PG8_STAGE(PG8_SA(0, 0), a2, voffA);
;             PG8_WAIT_V(8); PG8_WAIT_L(0); PG8_BAR; PG8_MMA(1, 0, At, B0); PG8_MMA(1, 1, At, B1); PG8_BAR; PG8_SCHED;
;             PG8_LDB(B0, 1, 0); PG8_LDB(B1, 1, 1); PG8_SCHED; PG8_LDA(At, 1, 0); PG8_STAGE(PG8_SA(0, 1), a2 + hstepA, voffA);
;             PG8_WAIT_V(8); PG8_WAIT_L(0); PG8_BAR; PG8_MMA(0, 0, At, B0); PG8_MMA(0, 1, At, B1); PG8_BAR; PG8_SCHED;
;             PG8_LDA(At, 1, 1); PG8_STAGE(PG8_SB(1, 0), b3, voffB); PG8_STAGE(PG8_SB(1, 1), b3 + hstepB, voffB); PG8_STAGE(PG8_SA(1, 0), a3, voffA);
;             PG8_WAIT_V(8); PG8_WAIT_L(0); PG8_BAR; PG8_MMA(1, 0, At, B0); PG8_MMA(1, 1, At, B1); PG8_BAR; PG8_SCHED;
	s_add_u32 s36, s34, 0x8000
	s_addc_u32 s37, s35, 0
	s_add_i32 s58, s60, s40
	s_mov_b32 m0, s58
	ds_read_b128 v[204:207], v170 offset:49152
	ds_read_b128 v[208:211], v170 offset:50176
	ds_read_b128 v[212:215], v170 offset:51200
	ds_read_b128 v[216:219], v170 offset:52224
	ds_read_b128 v[220:223], v170 offset:53248
	ds_read_b128 v[224:227], v170 offset:54272
	ds_read_b128 v[228:231], v170 offset:55296
	ds_read_b128 v[232:235], v170 offset:56320
	global_load_lds_dwordx4 v134, s[36:37]
	s_add_i32 m0, s58, 0x2000
	s_add_u32 s34, s34, 0xc000
	v_lshl_add_u64 v[236:237], s[36:37], 0, v[130:131]
	s_addc_u32 s35, s35, 0
	s_add_i32 s36, s61, s40
	global_load_lds_dwordx4 v[236:237], off
	s_mov_b32 m0, s36
	s_nop 0
	global_load_lds_dwordx4 v134, s[34:35]
	s_add_i32 m0, s36, 0x2000
	s_nop 0
	global_load_lds_dwordx4 v130, s[34:35]
	s_mov_b32 m0, s48
	s_nop 0
	global_load_lds_dwordx4 v136, s[30:31]
	s_mov_b32 m0, s49
	s_nop 0
	global_load_lds_dwordx4 v132, s[30:31]
	s_waitcnt vmcnt(8) lgkmcnt(0)
	s_barrier
	v_mfma_f32_16x16x32_bf16 v[62:65], v[172:175], v[204:207], v[62:65]
	v_mfma_f32_16x16x32_bf16 v[58:61], v[180:183], v[204:207], v[58:61]
	v_mfma_f32_16x16x32_bf16 v[46:49], v[172:175], v[212:215], v[46:49]
	v_mfma_f32_16x16x32_bf16 v[42:45], v[180:183], v[212:215], v[42:45]
	v_mfma_f32_16x16x32_bf16 v[30:33], v[172:175], v[220:223], v[30:33]
	v_mfma_f32_16x16x32_bf16 v[26:29], v[180:183], v[220:223], v[26:29]
	v_mfma_f32_16x16x32_bf16 v[14:17], v[172:175], v[228:231], v[14:17]
	v_mfma_f32_16x16x32_bf16 v[10:13], v[180:183], v[228:231], v[10:13]
	v_mfma_f32_16x16x32_bf16 v[62:65], v[176:179], v[208:211], v[62:65]
	v_mfma_f32_16x16x32_bf16 v[58:61], v[184:187], v[208:211], v[58:61]
	v_mfma_f32_16x16x32_bf16 v[46:49], v[176:179], v[216:219], v[46:49]
	v_mfma_f32_16x16x32_bf16 v[42:45], v[184:187], v[216:219], v[42:45]
	v_mfma_f32_16x16x32_bf16 v[30:33], v[176:179], v[224:227], v[30:33]
	v_mfma_f32_16x16x32_bf16 v[26:29], v[184:187], v[224:227], v[26:29]
	v_mfma_f32_16x16x32_bf16 v[14:17], v[176:179], v[232:235], v[14:17]
	v_mfma_f32_16x16x32_bf16 v[10:13], v[184:187], v[232:235], v[10:13]
	v_mfma_f32_16x16x32_bf16 v[54:57], v[188:191], v[204:207], v[54:57]
	v_mfma_f32_16x16x32_bf16 v[50:53], v[196:199], v[204:207], v[50:53]
	v_mfma_f32_16x16x32_bf16 v[38:41], v[188:191], v[212:215], v[38:41]
	v_mfma_f32_16x16x32_bf16 v[34:37], v[196:199], v[212:215], v[34:37]
	v_mfma_f32_16x16x32_bf16 v[22:25], v[188:191], v[220:223], v[22:25]
	v_mfma_f32_16x16x32_bf16 v[18:21], v[196:199], v[220:223], v[18:21]
	v_mfma_f32_16x16x32_bf16 v[6:9], v[188:191], v[228:231], v[6:9]
	v_mfma_f32_16x16x32_bf16 v[2:5], v[196:199], v[228:231], v[2:5]
	v_mfma_f32_16x16x32_bf16 v[54:57], v[192:195], v[208:211], v[54:57]
	v_mfma_f32_16x16x32_bf16 v[50:53], v[200:203], v[208:211], v[50:53]
	v_mfma_f32_16x16x32_bf16 v[38:41], v[192:195], v[216:219], v[38:41]
	v_mfma_f32_16x16x32_bf16 v[34:37], v[200:203], v[216:219], v[34:37]
	v_mfma_f32_16x16x32_bf16 v[22:25], v[192:195], v[224:227], v[22:25]
	v_mfma_f32_16x16x32_bf16 v[18:21], v[200:203], v[224:227], v[18:21]
	v_mfma_f32_16x16x32_bf16 v[6:9], v[192:195], v[232:235], v[6:9]
	v_mfma_f32_16x16x32_bf16 v[2:5], v[200:203], v[232:235], v[2:5]
	s_barrier
	s_add_i32 s57, s57, 2
	s_add_u32 s28, s28, 0x100
	s_addc_u32 s29, s29, 0
	s_add_u32 s55, s55, 0x10000
	s_addc_u32 s56, s56, 0
	s_cmp_gt_u32 s57, 29
.LBB0_2263:
	ds_read_b128 v[172:175], v168
	ds_read_b128 v[176:179], v168 offset:1024
	ds_read_b128 v[180:183], v168 offset:2048
	ds_read_b128 v[184:187], v168 offset:3072
	ds_read_b128 v[188:191], v169
	ds_read_b128 v[192:195], v169 offset:1024
	ds_read_b128 v[196:199], v169 offset:2048
	ds_read_b128 v[200:203], v169 offset:3072
	s_add_u32 s30, s26, s28
	s_addc_u32 s31, s27, s29
	s_add_u32 s36, s30, 0x100
	s_addc_u32 s37, s31, 0
	s_add_u32 s30, s30, 0x180
	s_addc_u32 s31, s31, 0
	s_cmpk_eq_i32 s28, 0xf00
	s_cbranch_scc1 .Lksel_25
	s_mov_b32 s35, s56
	s_mov_b32 s34, s55
.Lksel_25_back:
	s_mov_b32 m0, s50
	v_lshl_add_u64 v[236:237], v[164:165], 0, s[28:29]
	ds_read_b128 v[204:207], v170
	ds_read_b128 v[208:211], v170 offset:1024
	ds_read_b128 v[212:215], v170 offset:2048
	ds_read_b128 v[216:219], v170 offset:3072
	ds_read_b128 v[220:223], v170 offset:4096
	ds_read_b128 v[224:227], v170 offset:5120
	ds_read_b128 v[228:231], v170 offset:6144
	ds_read_b128 v[232:235], v170 offset:7168
	global_load_lds_dwordx4 v[236:237], off
	v_lshl_add_u64 v[236:237], v[166:167], 0, s[28:29]
	s_mov_b32 m0, s51
	s_nop 0
	global_load_lds_dwordx4 v[236:237], off
	s_waitcnt vmcnt(8) lgkmcnt(0)
	s_barrier
; #define PG8_STAGE(bufoff, gbase, voff) do { _Pragma("unroll") for (int _i = 0; _i < 2; ++_i) \
;         __builtin_amdgcn_global_load_lds((const unsigned*)((const char*)(gbase) + (voff)[_i]), (LAS unsigned*)(lds + (bufoff) + ldsw + _i * 8192), 16, 0, 0); } while (0)
; #define PG8_LDA(dst, b, h) do { _Pragma("unroll") for (int m = 0; m < 4; ++m) _Pragma("unroll") for (int k = 0; k < 2; ++k) dst[m][k] = *(const LAS bf16x8*)(lds + PG8_SA(b, h) + aoff + m * 2048 + k * 1024); } while (0)
; #define PG8_LDB(dst, b, h) do { _Pragma("unroll") for (int n = 0; n < 2; ++n) _Pragma("unroll") for (int k = 0; k < 2; ++k) dst[n][k] = *(const LAS bf16x8*)(lds + PG8_SB(b, h) + boff + n * 2048 + k * 1024); } while (0)
; #define PG8_MMA(ai, bj, At, Bt) do { __builtin_amdgcn_s_setprio(1); _Pragma("unroll") for (int m = 0; m < 4; ++m) _Pragma("unroll") for (int n = 0; n < 2; ++n) _Pragma("unroll") for (int k = 0; k < 2; ++k) \
;         acc[ai][bj][m][n] = __builtin_amdgcn_mfma_f32_16x16x32_bf16(Bt[n][k], At[m][k], acc[ai][bj][m][n], 0, 0, 0); __builtin_amdgcn_s_setprio(0); } while (0)
; #define PG8_WAIT_V(n) asm volatile("s_waitcnt vmcnt(" #n ")" ::: "memory")
; #define PG8_WAIT_L(n) asm volatile("s_waitcnt lgkmcnt(" #n ")" ::: "memory")
; #define PG8_BAR __builtin_amdgcn_s_barrier()
; #define PG8_SCHED __builtin_amdgcn_sched_barrier(0)
; template <class Epi, class Sched, bool ABLK = false, bool ALIGN_EPI = true, bool SP2 = true, bool BBLK = true>
; __device__ __forceinline__ void gemm_phase(LAS unsigned char* lds, const Gemm g, const Sched& S, const Epi& E) {
;     ...
;             PG8_LDB(B0, 0, 0); PG8_LDB(B1, 0, 1); PG8_SCHED; PG8_LDA(At, 0, 0); PG8_STAGE(PG8_SA(1, 1), a1 + hstepA, voffA);
;             PG8_WAIT_V(8); PG8_WAIT_L(0); PG8_BAR; PG8_MMA(0, 0, At, B0); PG8_MMA(0, 1, At, B1); PG8_BAR; PG8_SCHED;
;             PG8_LDA(At, 0, 1); PG8_STAGE(PG8_SB(0, 0), b2, voffB); PG8_STAGE(PG8_SB(0, 1), b2 + hstepB, voffB); PG8_STAGE(PG8_SA(0, 0), a2, voffA);
;             PG8_WAIT_V(8); PG8_WAIT_L(0); PG8_BAR; PG8_MMA(1, 0, At, B0); PG8_MMA(1, 1, At, B1); PG8_BAR; PG8_SCHED;
	v_mfma_f32_16x16x32_bf16 v[126:129], v[172:175], v[204:207], v[126:129]
	v_mfma_f32_16x16x32_bf16 v[122:125], v[180:183], v[204:207], v[122:125]
	v_mfma_f32_16x16x32_bf16 v[110:113], v[172:175], v[212:215], v[110:113]
	v_mfma_f32_16x16x32_bf16 v[106:109], v[180:183], v[212:215], v[106:109]
	v_mfma_f32_16x16x32_bf16 v[94:97], v[172:175], v[220:223], v[94:97]
	v_mfma_f32_16x16x32_bf16 v[90:93], v[180:183], v[220:223], v[90:93]
	v_mfma_f32_16x16x32_bf16 v[78:81], v[172:175], v[228:231], v[78:81]
	v_mfma_f32_16x16x32_bf16 v[74:77], v[180:183], v[228:231], v[74:77]
	v_mfma_f32_16x16x32_bf16 v[126:129], v[176:179], v[208:211], v[126:129]
	v_mfma_f32_16x16x32_bf16 v[122:125], v[184:187], v[208:211], v[122:125]
	v_mfma_f32_16x16x32_bf16 v[110:113], v[176:179], v[216:219], v[110:113]
	v_mfma_f32_16x16x32_bf16 v[106:109], v[184:187], v[216:219], v[106:109]
	v_mfma_f32_16x16x32_bf16 v[94:97], v[176:179], v[224:227], v[94:97]
	v_mfma_f32_16x16x32_bf16 v[90:93], v[184:187], v[224:227], v[90:93]
	v_mfma_f32_16x16x32_bf16 v[78:81], v[176:179], v[232:235], v[78:81]
	v_mfma_f32_16x16x32_bf16 v[74:77], v[184:187], v[232:235], v[74:77]
	v_mfma_f32_16x16x32_bf16 v[118:121], v[188:191], v[204:207], v[118:121]
	v_mfma_f32_16x16x32_bf16 v[114:117], v[196:199], v[204:207], v[114:117]
	v_mfma_f32_16x16x32_bf16 v[102:105], v[188:191], v[212:215], v[102:105]
	v_mfma_f32_16x16x32_bf16 v[98:101], v[196:199], v[212:215], v[98:101]
	v_mfma_f32_16x16x32_bf16 v[86:89], v[188:191], v[220:223], v[86:89]
	v_mfma_f32_16x16x32_bf16 v[82:85], v[196:199], v[220:223], v[82:85]
	v_mfma_f32_16x16x32_bf16 v[70:73], v[188:191], v[228:231], v[70:73]
	v_mfma_f32_16x16x32_bf16 v[66:69], v[196:199], v[228:231], v[66:69]
	v_mfma_f32_16x16x32_bf16 v[118:121], v[192:195], v[208:211], v[118:121]
	v_mfma_f32_16x16x32_bf16 v[114:117], v[200:203], v[208:211], v[114:117]
	v_mfma_f32_16x16x32_bf16 v[102:105], v[192:195], v[216:219], v[102:105]
	v_mfma_f32_16x16x32_bf16 v[98:101], v[200:203], v[216:219], v[98:101]
	v_mfma_f32_16x16x32_bf16 v[86:89], v[192:195], v[224:227], v[86:89]
	v_mfma_f32_16x16x32_bf16 v[82:85], v[200:203], v[224:227], v[82:85]
	v_mfma_f32_16x16x32_bf16 v[70:73], v[192:195], v[232:235], v[70:73]
	v_mfma_f32_16x16x32_bf16 v[66:69], v[200:203], v[232:235], v[66:69]
	s_barrier
	s_mov_b32 m0, s52
	s_add_u32 s58, s34, 0x4000
	ds_read_b128 v[204:207], v170 offset:16384
	ds_read_b128 v[208:211], v170 offset:17408
	ds_read_b128 v[212:215], v170 offset:18432
	ds_read_b128 v[216:219], v170 offset:19456
	ds_read_b128 v[220:223], v170 offset:20480
	ds_read_b128 v[224:227], v170 offset:21504
	ds_read_b128 v[228:231], v170 offset:22528
	ds_read_b128 v[232:235], v170 offset:23552
	global_load_lds_dwordx4 v134, s[34:35]
	s_mov_b32 m0, s53
	s_addc_u32 s59, s35, 0
	s_add_i32 s62, s73, s40
	global_load_lds_dwordx4 v130, s[34:35]
	s_mov_b32 m0, s62
	s_nop 0
	global_load_lds_dwordx4 v134, s[58:59]
	s_add_i32 m0, s62, 0x2000
	s_nop 0
	global_load_lds_dwordx4 v130, s[58:59]
	s_mov_b32 m0, s25
	s_nop 0
	global_load_lds_dwordx4 v136, s[36:37]
	s_mov_b32 m0, s43
	s_nop 0
	global_load_lds_dwordx4 v132, s[36:37]
	s_waitcnt vmcnt(8) lgkmcnt(0)
	s_barrier
	v_mfma_f32_16x16x32_bf16 v[62:65], v[172:175], v[204:207], v[62:65]
	v_mfma_f32_16x16x32_bf16 v[58:61], v[180:183], v[204:207], v[58:61]
	v_mfma_f32_16x16x32_bf16 v[46:49], v[172:175], v[212:215], v[46:49]
	v_mfma_f32_16x16x32_bf16 v[42:45], v[180:183], v[212:215], v[42:45]
	v_mfma_f32_16x16x32_bf16 v[30:33], v[172:175], v[220:223], v[30:33]
	v_mfma_f32_16x16x32_bf16 v[26:29], v[180:183], v[220:223], v[26:29]
	v_mfma_f32_16x16x32_bf16 v[14:17], v[172:175], v[228:231], v[14:17]
	v_mfma_f32_16x16x32_bf16 v[10:13], v[180:183], v[228:231], v[10:13]
	v_mfma_f32_16x16x32_bf16 v[62:65], v[176:179], v[208:211], v[62:65]
	v_mfma_f32_16x16x32_bf16 v[58:61], v[184:187], v[208:211], v[58:61]
	v_mfma_f32_16x16x32_bf16 v[46:49], v[176:179], v[216:219], v[46:49]
	v_mfma_f32_16x16x32_bf16 v[42:45], v[184:187], v[216:219], v[42:45]
	v_mfma_f32_16x16x32_bf16 v[30:33], v[176:179], v[224:227], v[30:33]
	v_mfma_f32_16x16x32_bf16 v[26:29], v[184:187], v[224:227], v[26:29]
	v_mfma_f32_16x16x32_bf16 v[14:17], v[176:179], v[232:235], v[14:17]
	v_mfma_f32_16x16x32_bf16 v[10:13], v[184:187], v[232:235], v[10:13]
	v_mfma_f32_16x16x32_bf16 v[54:57], v[188:191], v[204:207], v[54:57]
	v_mfma_f32_16x16x32_bf16 v[50:53], v[196:199], v[204:207], v[50:53]
	v_mfma_f32_16x16x32_bf16 v[38:41], v[188:191], v[212:215], v[38:41]
	v_mfma_f32_16x16x32_bf16 v[34:37], v[196:199], v[212:215], v[34:37]
	v_mfma_f32_16x16x32_bf16 v[22:25], v[188:191], v[220:223], v[22:25]
	v_mfma_f32_16x16x32_bf16 v[18:21], v[196:199], v[220:223], v[18:21]
	v_mfma_f32_16x16x32_bf16 v[6:9], v[188:191], v[228:231], v[6:9]
	v_mfma_f32_16x16x32_bf16 v[2:5], v[196:199], v[228:231], v[2:5]
	v_mfma_f32_16x16x32_bf16 v[54:57], v[192:195], v[208:211], v[54:57]
	v_mfma_f32_16x16x32_bf16 v[50:53], v[200:203], v[208:211], v[50:53]
	v_mfma_f32_16x16x32_bf16 v[38:41], v[192:195], v[216:219], v[38:41]
	v_mfma_f32_16x16x32_bf16 v[34:37], v[200:203], v[216:219], v[34:37]
	v_mfma_f32_16x16x32_bf16 v[22:25], v[192:195], v[224:227], v[22:25]
	v_mfma_f32_16x16x32_bf16 v[18:21], v[200:203], v[224:227], v[18:21]
	v_mfma_f32_16x16x32_bf16 v[6:9], v[192:195], v[232:235], v[6:9]
	v_mfma_f32_16x16x32_bf16 v[2:5], v[200:203], v[232:235], v[2:5]
	s_barrier
; #define PG8_STAGE(bufoff, gbase, voff) do { _Pragma("unroll") for (int _i = 0; _i < 2; ++_i) \
;         __builtin_amdgcn_global_load_lds((const unsigned*)((const char*)(gbase) + (voff)[_i]), (LAS unsigned*)(lds + (bufoff) + ldsw + _i * 8192), 16, 0, 0); } while (0)
; #define PG8_LDA(dst, b, h) do { _Pragma("unroll") for (int m = 0; m < 4; ++m) _Pragma("unroll") for (int k = 0; k < 2; ++k) dst[m][k] = *(const LAS bf16x8*)(lds + PG8_SA(b, h) + aoff + m * 2048 + k * 1024); } while (0)
; #define PG8_LDB(dst, b, h) do { _Pragma("unroll") for (int n = 0; n < 2; ++n) _Pragma("unroll") for (int k = 0; k < 2; ++k) dst[n][k] = *(const LAS bf16x8*)(lds + PG8_SB(b, h) + boff + n * 2048 + k * 1024); } while (0)
; #define PG8_MMA(ai, bj, At, Bt) do { __builtin_amdgcn_s_setprio(1); _Pragma("unroll") for (int m = 0; m < 4; ++m) _Pragma("unroll") for (int n = 0; n < 2; ++n) _Pragma("unroll") for (int k = 0; k < 2; ++k) \
;         acc[ai][bj][m][n] = __builtin_amdgcn_mfma_f32_16x16x32_bf16(Bt[n][k], At[m][k], acc[ai][bj][m][n], 0, 0, 0); __builtin_amdgcn_s_setprio(0); } while (0)
; #define PG8_WAIT_V(n) asm volatile("s_waitcnt vmcnt(" #n ")" ::: "memory")
; #define PG8_WAIT_L(n) asm volatile("s_waitcnt lgkmcnt(" #n ")" ::: "memory")
; #define PG8_BAR __builtin_amdgcn_s_barrier()
; #define PG8_SCHED __builtin_amdgcn_sched_barrier(0)
; template <class Epi, class Sched, bool ABLK = false, bool ALIGN_EPI = true, bool SP2 = true, bool BBLK = true>
; __device__ __forceinline__ void gemm_phase(LAS unsigned char* lds, const Gemm g, const Sched& S, const Epi& E) {
;     ...
;             PG8_LDB(B0, 1, 0); PG8_LDB(B1, 1, 1); PG8_SCHED; PG8_LDA(At, 1, 0); PG8_STAGE(PG8_SA(0, 1), a2 + hstepA, voffA);
;             PG8_WAIT_V(8); PG8_WAIT_L(0); PG8_BAR; PG8_MMA(0, 0, At, B0); PG8_MMA(0, 1, At, B1); PG8_BAR; PG8_SCHED;
;             PG8_LDA(At, 1, 1); PG8_STAGE(PG8_SB(1, 0), b3, voffB); PG8_STAGE(PG8_SB(1, 1), b3 + hstepB, voffB); PG8_STAGE(PG8_SA(1, 0), a3, voffA);
;             PG8_WAIT_V(8); PG8_WAIT_L(0); PG8_BAR; PG8_MMA(1, 0, At, B0); PG8_MMA(1, 1, At, B1); PG8_BAR; PG8_SCHED;
	v_add_u32_e32 v171, s60, v1
	ds_read_b128 v[172:175], v171
	ds_read_b128 v[176:179], v171 offset:1024
	ds_read_b128 v[180:183], v171 offset:2048
	ds_read_b128 v[184:187], v171 offset:3072
	v_add_u32_e32 v171, s61, v1
	ds_read_b128 v[188:191], v171
	ds_read_b128 v[192:195], v171 offset:1024
	ds_read_b128 v[196:199], v171 offset:2048
	ds_read_b128 v[200:203], v171 offset:3072
	s_add_u32 s36, s36, 0x80000
	s_addc_u32 s37, s37, 0
	s_mov_b32 m0, s44
	ds_read_b128 v[204:207], v170 offset:32768
	ds_read_b128 v[208:211], v170 offset:33792
	ds_read_b128 v[212:215], v170 offset:34816
	ds_read_b128 v[216:219], v170 offset:35840
	ds_read_b128 v[220:223], v170 offset:36864
	ds_read_b128 v[224:227], v170 offset:37888
	ds_read_b128 v[228:231], v170 offset:38912
	ds_read_b128 v[232:235], v170 offset:39936
	global_load_lds_dwordx4 v136, s[36:37]
	s_mov_b32 m0, s45
	s_nop 0
	global_load_lds_dwordx4 v132, s[36:37]
	s_waitcnt vmcnt(8) lgkmcnt(0)
	s_barrier
	v_mfma_f32_16x16x32_bf16 v[126:129], v[172:175], v[204:207], v[126:129]
	v_mfma_f32_16x16x32_bf16 v[122:125], v[180:183], v[204:207], v[122:125]
	v_mfma_f32_16x16x32_bf16 v[110:113], v[172:175], v[212:215], v[110:113]
	v_mfma_f32_16x16x32_bf16 v[106:109], v[180:183], v[212:215], v[106:109]
	v_mfma_f32_16x16x32_bf16 v[94:97], v[172:175], v[220:223], v[94:97]
	v_mfma_f32_16x16x32_bf16 v[90:93], v[180:183], v[220:223], v[90:93]
	v_mfma_f32_16x16x32_bf16 v[78:81], v[172:175], v[228:231], v[78:81]
	v_mfma_f32_16x16x32_bf16 v[74:77], v[180:183], v[228:231], v[74:77]
	v_mfma_f32_16x16x32_bf16 v[126:129], v[176:179], v[208:211], v[126:129]
	v_mfma_f32_16x16x32_bf16 v[122:125], v[184:187], v[208:211], v[122:125]
	v_mfma_f32_16x16x32_bf16 v[110:113], v[176:179], v[216:219], v[110:113]
	v_mfma_f32_16x16x32_bf16 v[106:109], v[184:187], v[216:219], v[106:109]
	v_mfma_f32_16x16x32_bf16 v[94:97], v[176:179], v[224:227], v[94:97]
	v_mfma_f32_16x16x32_bf16 v[90:93], v[184:187], v[224:227], v[90:93]
	v_mfma_f32_16x16x32_bf16 v[78:81], v[176:179], v[232:235], v[78:81]
	v_mfma_f32_16x16x32_bf16 v[74:77], v[184:187], v[232:235], v[74:77]
	v_mfma_f32_16x16x32_bf16 v[118:121], v[188:191], v[204:207], v[118:121]
	v_mfma_f32_16x16x32_bf16 v[114:117], v[196:199], v[204:207], v[114:117]
	v_mfma_f32_16x16x32_bf16 v[102:105], v[188:191], v[212:215], v[102:105]
	v_mfma_f32_16x16x32_bf16 v[98:101], v[196:199], v[212:215], v[98:101]
	v_mfma_f32_16x16x32_bf16 v[86:89], v[188:191], v[220:223], v[86:89]
	v_mfma_f32_16x16x32_bf16 v[82:85], v[196:199], v[220:223], v[82:85]
	v_mfma_f32_16x16x32_bf16 v[70:73], v[188:191], v[228:231], v[70:73]
	v_mfma_f32_16x16x32_bf16 v[66:69], v[196:199], v[228:231], v[66:69]
	v_mfma_f32_16x16x32_bf16 v[118:121], v[192:195], v[208:211], v[118:121]
	v_mfma_f32_16x16x32_bf16 v[114:117], v[200:203], v[208:211], v[114:117]
	v_mfma_f32_16x16x32_bf16 v[102:105], v[192:195], v[216:219], v[102:105]
	v_mfma_f32_16x16x32_bf16 v[98:101], v[200:203], v[216:219], v[98:101]
	v_mfma_f32_16x16x32_bf16 v[86:89], v[192:195], v[224:227], v[86:89]
	v_mfma_f32_16x16x32_bf16 v[82:85], v[200:203], v[224:227], v[82:85]
	v_mfma_f32_16x16x32_bf16 v[70:73], v[192:195], v[232:235], v[70:73]
	v_mfma_f32_16x16x32_bf16 v[66:69], v[200:203], v[232:235], v[66:69]
	s_barrier
	s_add_u32 s36, s34, 0x8000
	s_addc_u32 s37, s35, 0
	s_add_i32 s58, s60, s40
	s_mov_b32 m0, s58
	ds_read_b128 v[204:207], v170 offset:49152
	ds_read_b128 v[208:211], v170 offset:50176
	ds_read_b128 v[212:215], v170 offset:51200
	ds_read_b128 v[216:219], v170 offset:52224
	ds_read_b128 v[220:223], v170 offset:53248
	ds_read_b128 v[224:227], v170 offset:54272
	ds_read_b128 v[228:231], v170 offset:55296
	ds_read_b128 v[232:235], v170 offset:56320
	global_load_lds_dwordx4 v134, s[36:37]
	s_add_i32 m0, s58, 0x2000
	s_add_u32 s34, s34, 0xc000
	v_lshl_add_u64 v[236:237], s[36:37], 0, v[130:131]
	s_addc_u32 s35, s35, 0
	s_add_i32 s36, s61, s40
	global_load_lds_dwordx4 v[236:237], off
	s_mov_b32 m0, s36
	s_nop 0
	global_load_lds_dwordx4 v134, s[34:35]
	s_add_i32 m0, s36, 0x2000
	s_nop 0
	global_load_lds_dwordx4 v130, s[34:35]
	s_mov_b32 m0, s48
	s_nop 0
	global_load_lds_dwordx4 v136, s[30:31]
	s_mov_b32 m0, s49
	s_nop 0
	global_load_lds_dwordx4 v132, s[30:31]
	s_waitcnt vmcnt(8) lgkmcnt(0)
	s_barrier
	v_mfma_f32_16x16x32_bf16 v[62:65], v[172:175], v[204:207], v[62:65]
	v_mfma_f32_16x16x32_bf16 v[58:61], v[180:183], v[204:207], v[58:61]
	v_mfma_f32_16x16x32_bf16 v[46:49], v[172:175], v[212:215], v[46:49]
	v_mfma_f32_16x16x32_bf16 v[42:45], v[180:183], v[212:215], v[42:45]
	v_mfma_f32_16x16x32_bf16 v[30:33], v[172:175], v[220:223], v[30:33]
	v_mfma_f32_16x16x32_bf16 v[26:29], v[180:183], v[220:223], v[26:29]
	v_mfma_f32_16x16x32_bf16 v[14:17], v[172:175], v[228:231], v[14:17]
	v_mfma_f32_16x16x32_bf16 v[10:13], v[180:183], v[228:231], v[10:13]
	v_mfma_f32_16x16x32_bf16 v[62:65], v[176:179], v[208:211], v[62:65]
	v_mfma_f32_16x16x32_bf16 v[58:61], v[184:187], v[208:211], v[58:61]
	v_mfma_f32_16x16x32_bf16 v[46:49], v[176:179], v[216:219], v[46:49]
	v_mfma_f32_16x16x32_bf16 v[42:45], v[184:187], v[216:219], v[42:45]
	v_mfma_f32_16x16x32_bf16 v[30:33], v[176:179], v[224:227], v[30:33]
	v_mfma_f32_16x16x32_bf16 v[26:29], v[184:187], v[224:227], v[26:29]
	v_mfma_f32_16x16x32_bf16 v[14:17], v[176:179], v[232:235], v[14:17]
	v_mfma_f32_16x16x32_bf16 v[10:13], v[184:187], v[232:235], v[10:13]
	v_mfma_f32_16x16x32_bf16 v[54:57], v[188:191], v[204:207], v[54:57]
	v_mfma_f32_16x16x32_bf16 v[50:53], v[196:199], v[204:207], v[50:53]
	v_mfma_f32_16x16x32_bf16 v[38:41], v[188:191], v[212:215], v[38:41]
	v_mfma_f32_16x16x32_bf16 v[34:37], v[196:199], v[212:215], v[34:37]
	v_mfma_f32_16x16x32_bf16 v[22:25], v[188:191], v[220:223], v[22:25]
	v_mfma_f32_16x16x32_bf16 v[18:21], v[196:199], v[220:223], v[18:21]
	v_mfma_f32_16x16x32_bf16 v[6:9], v[188:191], v[228:231], v[6:9]
	v_mfma_f32_16x16x32_bf16 v[2:5], v[196:199], v[228:231], v[2:5]
	v_mfma_f32_16x16x32_bf16 v[54:57], v[192:195], v[208:211], v[54:57]
	v_mfma_f32_16x16x32_bf16 v[50:53], v[200:203], v[208:211], v[50:53]
	v_mfma_f32_16x16x32_bf16 v[38:41], v[192:195], v[216:219], v[38:41]
	v_mfma_f32_16x16x32_bf16 v[34:37], v[200:203], v[216:219], v[34:37]
	v_mfma_f32_16x16x32_bf16 v[22:25], v[192:195], v[224:227], v[22:25]
	v_mfma_f32_16x16x32_bf16 v[18:21], v[200:203], v[224:227], v[18:21]
	v_mfma_f32_16x16x32_bf16 v[6:9], v[192:195], v[232:235], v[6:9]
	v_mfma_f32_16x16x32_bf16 v[2:5], v[200:203], v[232:235], v[2:5]
	s_barrier
	s_add_i32 s57, s57, 2
	s_add_u32 s28, s28, 0x100
	s_addc_u32 s29, s29, 0
	s_add_u32 s55, s55, 0x10000
	s_addc_u32 s56, s56, 0
	s_cmp_gt_u32 s57, 29
	s_cbranch_scc0 .LBB0_2263
	s_and_b64 vcc, exec, s[10:11]
	s_cbranch_vccz .LBB0_2266
	s_barrier

; template <class Epi, class Sched, bool ABLK = false, bool ALIGN_EPI = true, bool SP2 = true, bool BBLK = true>
; __device__ __forceinline__ void gemm_phase(LAS unsigned char* lds, const Gemm g, const Sched& S, const Epi& E) {
;     ...
;             const char* a1 = a_tile(uA, tbA + t + 1);
;             const char* a2 = last ? a_tile(nuA, ntbA) : a_tile(uA, tbA + t + 2); const char* b2 = last ? nB : cB + (size_t)(t + 2) * kstepB;
;             const char* a3 = last ? a_tile(nuA, ntbA + 1) : a_tile(uA, tbA + t + 3); const char* b3 = b2 + kstepB;
.Lksel_25:
	s_mov_b32 s31, s54
	s_mov_b32 s30, s23
	s_mov_b32 s35, s13
	s_mov_b32 s34, s15
	s_mov_b32 s37, s4
	s_mov_b32 s36, s5
	s_branch .Lksel_25_back

; template <class Epi, class Sched, bool ABLK = false, bool ALIGN_EPI = true, bool SP2 = true, bool BBLK = true>
; __device__ __forceinline__ void gemm_phase(LAS unsigned char* lds, const Gemm g, const Sched& S, const Epi& E) {
;     ...
;     auto a_unit = [&](const Unit& u) -> const char* { return ABLK ? (const char*)g.A + (size_t)u.pm * ((size_t)g.lda / 64) * 32768 : (const char*)g.A + (size_t)u.pm * 2 * hstepA; };
;     auto a_tile = [&](const char* ub, int tau) -> const char* { return ub + (size_t)tau * (ABLK ? (size_t)32768 : kstep); };
;     const char* uA = a_unit(cur); int tbA = cur.k0 / BK;
;     const char* cA = a_tile(uA, tbA); const char* cB = (const char*)g.Bt + (size_t)cur.pn * tstepB + b_k0(cur.k0);
;     S.a_ready(cur);
;     if constexpr (SP2) {
;         PG8_STAGE(PG8_SB(0, 0), cB, voffB); PG8_STAGE(PG8_SB(0, 1), cB + hstepB, voffB); PG8_STAGE(PG8_SA(0, 0), cA, voffA); PG8_STAGE(PG8_SA(0, 1), cA + hstepA, voffA);
;         if (wr == 1) PG8_BAR;
;         PG8_WAIT_V(2); PG8_BAR;
;         PG8_STAGE(PG8_SB(1, 0), cB + kstepB, voffB); PG8_STAGE(PG8_SA(1, 0), a_tile(uA, tbA + 1), voffA); PG8_STAGE(PG8_SB(1, 1), cB + hstepB + kstepB, voffB);
;         PG8_WAIT_V(6); PG8_BAR;
;     } else {
;         PG8_STAGE(PG8_SB(0, 0), cB, voffB); PG8_STAGE(PG8_SA(0, 0), cA, voffA); PG8_STAGE(PG8_SB(0, 1), cB + hstepB, voffB); PG8_STAGE(PG8_SA(0, 1), cA + hstepA, voffA);
;         if (wr == 1) PG8_BAR;
;         PG8_WAIT_V(4); PG8_BAR;
;         PG8_STAGE(PG8_SB(1, 0), cB + kstepB, voffB); PG8_STAGE(PG8_SA(1, 0), a_tile(uA, tbA + 1), voffA); PG8_STAGE(PG8_SB(1, 1), cB + hstepB + kstepB, voffB);
;         PG8_WAIT_V(6); PG8_BAR;
;     }
;     for (;;) {
;         const bool has_next = S.next(ui + 1, nxt);
;         const int nt = cur.nt;
;         const char* nuA = has_next ? a_unit(nxt) : uA; const int ntbA = has_next ? nxt.k0 / BK : tbA; const char* nB = has_next ? (const char*)g.Bt + (size_t)nxt.pn * tstepB + b_k0(nxt.k0) : cB;
;         for (int t = 0; t < nt; t += 2) {
;             const bool last = (t == nt - 2);
;             const char* a1 = a_tile(uA, tbA + t + 1);
;             const char* a2 = last ? a_tile(nuA, ntbA) : a_tile(uA, tbA + t + 2); const char* b2 = last ? nB : cB + (size_t)(t + 2) * kstepB;
;             const char* a3 = last ? a_tile(nuA, ntbA + 1) : a_tile(uA, tbA + t + 3); const char* b3 = b2 + kstepB;
.LBB0_2327:
	s_ashr_i32 s81, s80, 31
	s_andn2_b64 vcc, exec, s[4:5]
	s_lshl_b64 s[30:31], s[80:81], 22
	s_add_u32 s30, s1, s30
	s_addc_u32 s31, s33, s31
	s_and_b64 s[34:35], s[4:5], exec
	s_cselect_b32 s43, s31, s41
	s_cselect_b32 s57, s30, s40
	s_ashr_i32 s34, s0, 31
	s_lshr_b32 s34, s34, 26
	s_add_i32 s34, s0, s34
	s_ashr_i32 s34, s34, 6
	s_and_b64 s[36:37], s[4:5], exec
	s_cselect_b32 s44, s34, s42
	s_ashr_i32 s79, s78, 31
	s_lshl_b64 s[36:37], s[78:79], 22
	s_add_u32 s45, s46, s36
	s_addc_u32 s58, s47, s37
	s_ashr_i32 s35, s34, 31
	s_lshl_b64 s[36:37], s[34:35], 15
	s_add_u32 s36, s45, s36
	s_addc_u32 s37, s58, s37
	v_cndmask_b32_e64 v2, 0, 1, s[4:5]
	s_and_b64 s[4:5], s[4:5], exec
	s_cselect_b32 s4, s37, s39
	s_cselect_b32 s5, s36, s38
	s_ashr_i32 s45, s44, 31
	s_lshl_b64 s[44:45], s[44:45], 15
	s_add_u32 s35, s57, s44
	s_addc_u32 s57, s43, s45
	s_add_u32 s58, s35, 0x8000
	s_addc_u32 s59, s57, 0
	s_add_u32 s62, s38, 0x10000
	s_addc_u32 s63, s39, 0
	s_ashr_i32 s43, s42, 31
	v_cmp_ne_u32_e64 s[6:7], 1, v2
	s_lshl_b64 s[38:39], s[42:43], 15
	v_lshl_add_u64 v[2:3], s[40:41], 0, v[138:139]
	s_add_u32 s64, s40, s38
	v_lshl_add_u64 v[142:143], v[2:3], 0, s[38:39]
	v_lshl_add_u64 v[2:3], s[40:41], 0, v[140:141]
	s_addc_u32 s65, s41, s39
	v_lshl_add_u64 v[144:145], v[2:3], 0, s[38:39]
	s_lshl_b32 s38, s56, 15
	s_add_i32 s38, s38, 0xfff00000
	v_mov_b32_e32 v2, 0
	s_add_u32 s66, s38, 0xf0000
	s_mov_b32 s67, 0
	s_mov_b64 s[38:39], 0
	ds_read_b128 v[152:155], v148
	ds_read_b128 v[156:159], v148 offset:1024
	ds_read_b128 v[160:163], v148 offset:2048
	ds_read_b128 v[164:167], v148 offset:3072
	ds_read_b128 v[168:171], v149
	ds_read_b128 v[172:175], v149 offset:1024
	ds_read_b128 v[176:179], v149 offset:2048
	ds_read_b128 v[180:183], v149 offset:3072
	s_add_u32 s40, s64, s38
	s_addc_u32 s41, s65, s39
	s_add_u32 s44, s40, 0x10000
	s_addc_u32 s45, s41, 0
	s_add_i32 s67, s67, 2
	s_add_u32 s42, s62, s38
	s_addc_u32 s43, s63, s39
	s_add_u32 s40, s40, 0x18000
	s_addc_u32 s41, s41, 0
	v_lshl_add_u64 v[216:217], v[142:143], 0, s[38:39]
	s_add_i32 m0, s49, 0xc000
	ds_read_b128 v[184:187], v150
	ds_read_b128 v[188:191], v150 offset:1024
	ds_read_b128 v[192:195], v150 offset:2048
	ds_read_b128 v[196:199], v150 offset:3072
	ds_read_b128 v[200:203], v150 offset:4096
	ds_read_b128 v[204:207], v150 offset:5120
	ds_read_b128 v[208:211], v150 offset:6144
	ds_read_b128 v[212:215], v150 offset:7168
	global_load_lds_dwordx4 v[216:217], off
	v_lshl_add_u64 v[216:217], v[144:145], 0, s[38:39]
	s_add_i32 m0, s49, 0xe000
	s_nop 0
	global_load_lds_dwordx4 v[216:217], off
	s_waitcnt vmcnt(8) lgkmcnt(0)
	s_barrier
	v_mfma_f32_16x16x32_bf16 v[126:129], v[152:155], v[184:187], 0
	v_mfma_f32_16x16x32_bf16 v[122:125], v[160:163], v[184:187], 0
	v_mfma_f32_16x16x32_bf16 v[110:113], v[152:155], v[192:195], 0
	v_mfma_f32_16x16x32_bf16 v[106:109], v[160:163], v[192:195], 0
	v_mfma_f32_16x16x32_bf16 v[94:97], v[152:155], v[200:203], 0
	v_mfma_f32_16x16x32_bf16 v[90:93], v[160:163], v[200:203], 0
	v_mfma_f32_16x16x32_bf16 v[78:81], v[152:155], v[208:211], 0
	v_mfma_f32_16x16x32_bf16 v[74:77], v[160:163], v[208:211], 0
	v_mfma_f32_16x16x32_bf16 v[126:129], v[156:159], v[188:191], v[126:129]
	v_mfma_f32_16x16x32_bf16 v[122:125], v[164:167], v[188:191], v[122:125]
	v_mfma_f32_16x16x32_bf16 v[110:113], v[156:159], v[196:199], v[110:113]
	v_mfma_f32_16x16x32_bf16 v[106:109], v[164:167], v[196:199], v[106:109]
	v_mfma_f32_16x16x32_bf16 v[94:97], v[156:159], v[204:207], v[94:97]
	v_mfma_f32_16x16x32_bf16 v[90:93], v[164:167], v[204:207], v[90:93]
	v_mfma_f32_16x16x32_bf16 v[78:81], v[156:159], v[212:215], v[78:81]
	v_mfma_f32_16x16x32_bf16 v[74:77], v[164:167], v[212:215], v[74:77]
	v_mfma_f32_16x16x32_bf16 v[118:121], v[168:171], v[184:187], 0
	v_mfma_f32_16x16x32_bf16 v[114:117], v[176:179], v[184:187], 0
	v_mfma_f32_16x16x32_bf16 v[102:105], v[168:171], v[192:195], 0
	v_mfma_f32_16x16x32_bf16 v[98:101], v[176:179], v[192:195], 0
	v_mfma_f32_16x16x32_bf16 v[86:89], v[168:171], v[200:203], 0
	v_mfma_f32_16x16x32_bf16 v[82:85], v[176:179], v[200:203], 0
	v_mfma_f32_16x16x32_bf16 v[70:73], v[168:171], v[208:211], 0
	v_mfma_f32_16x16x32_bf16 v[66:69], v[176:179], v[208:211], 0
	v_mfma_f32_16x16x32_bf16 v[118:121], v[172:175], v[188:191], v[118:121]
	v_mfma_f32_16x16x32_bf16 v[114:117], v[180:183], v[188:191], v[114:117]
	v_mfma_f32_16x16x32_bf16 v[102:105], v[172:175], v[196:199], v[102:105]
	v_mfma_f32_16x16x32_bf16 v[98:101], v[180:183], v[196:199], v[98:101]
	v_mfma_f32_16x16x32_bf16 v[86:89], v[172:175], v[204:207], v[86:89]
	v_mfma_f32_16x16x32_bf16 v[82:85], v[180:183], v[204:207], v[82:85]
	v_mfma_f32_16x16x32_bf16 v[70:73], v[172:175], v[212:215], v[70:73]
	v_mfma_f32_16x16x32_bf16 v[66:69], v[180:183], v[212:215], v[66:69]
	s_barrier
	s_add_i32 s70, s72, s48
	s_mov_b32 m0, s70
	ds_read_b128 v[184:187], v150 offset:16384
	ds_read_b128 v[188:191], v150 offset:17408
	ds_read_b128 v[192:195], v150 offset:18432
	ds_read_b128 v[196:199], v150 offset:19456
	ds_read_b128 v[200:203], v150 offset:20480
	ds_read_b128 v[204:207], v150 offset:21504
	ds_read_b128 v[208:211], v150 offset:22528
	ds_read_b128 v[212:215], v150 offset:23552
	global_load_lds_dwordx4 v130, s[42:43]
	s_add_i32 m0, s70, 0x2000
	s_add_u32 s76, s42, 0x4000
	s_addc_u32 s77, s43, 0
	s_add_i32 s70, s73, s48
	global_load_lds_dwordx4 v132, s[42:43]
	s_mov_b32 m0, s70
	s_nop 0
	global_load_lds_dwordx4 v130, s[76:77]
	s_add_i32 m0, s70, 0x2000
	s_nop 0
	global_load_lds_dwordx4 v132, s[76:77]
	s_mov_b32 m0, s49
	s_nop 0
	global_load_lds_dwordx4 v130, s[44:45]
	s_mov_b32 m0, s50
	s_nop 0
	global_load_lds_dwordx4 v132, s[44:45]
	s_waitcnt vmcnt(8) lgkmcnt(0)
	s_barrier
; #define PG8_STAGE(bufoff, gbase, voff) do { _Pragma("unroll") for (int _i = 0; _i < 2; ++_i) \
;         __builtin_amdgcn_global_load_lds((const unsigned*)((const char*)(gbase) + (voff)[_i]), (LAS unsigned*)(lds + (bufoff) + ldsw + _i * 8192), 16, 0, 0); } while (0)
; #define PG8_LDA(dst, b, h) do { _Pragma("unroll") for (int m = 0; m < 4; ++m) _Pragma("unroll") for (int k = 0; k < 2; ++k) dst[m][k] = *(const LAS bf16x8*)(lds + PG8_SA(b, h) + aoff + m * 2048 + k * 1024); } while (0)
; #define PG8_LDB(dst, b, h) do { _Pragma("unroll") for (int n = 0; n < 2; ++n) _Pragma("unroll") for (int k = 0; k < 2; ++k) dst[n][k] = *(const LAS bf16x8*)(lds + PG8_SB(b, h) + boff + n * 2048 + k * 1024); } while (0)
; #define PG8_MMA(ai, bj, At, Bt) do { __builtin_amdgcn_s_setprio(1); _Pragma("unroll") for (int m = 0; m < 4; ++m) _Pragma("unroll") for (int n = 0; n < 2; ++n) _Pragma("unroll") for (int k = 0; k < 2; ++k) \
;         acc[ai][bj][m][n] = __builtin_amdgcn_mfma_f32_16x16x32_bf16(Bt[n][k], At[m][k], acc[ai][bj][m][n], 0, 0, 0); __builtin_amdgcn_s_setprio(0); } while (0)
; #define PG8_BAR __builtin_amdgcn_s_barrier()
; template <class Epi, class Sched, bool ABLK = false, bool ALIGN_EPI = true, bool SP2 = true, bool BBLK = true>
; __device__ __forceinline__ void gemm_phase(LAS unsigned char* lds, const Gemm g, const Sched& S, const Epi& E) {
;     ...
;             PG8_LDB(B0, 0, 0); PG8_LDB(B1, 0, 1); PG8_SCHED; PG8_LDA(At, 0, 0); PG8_STAGE(PG8_SA(1, 1), a1 + hstepA, voffA);
;             PG8_WAIT_V(8); PG8_WAIT_L(0); PG8_BAR; PG8_MMA(0, 0, At, B0); PG8_MMA(0, 1, At, B1); PG8_BAR; PG8_SCHED;
;             PG8_LDA(At, 0, 1); PG8_STAGE(PG8_SB(0, 0), b2, voffB); PG8_STAGE(PG8_SB(0, 1), b2 + hstepB, voffB); PG8_STAGE(PG8_SA(0, 0), a2, voffA);
;             PG8_WAIT_V(8); PG8_WAIT_L(0); PG8_BAR; PG8_MMA(1, 0, At, B0); PG8_MMA(1, 1, At, B1); PG8_BAR; PG8_SCHED;
;             PG8_LDB(B0, 1, 0); PG8_LDB(B1, 1, 1); PG8_SCHED; PG8_LDA(At, 1, 0); PG8_STAGE(PG8_SA(0, 1), a2 + hstepA, voffA);
;             PG8_WAIT_V(8); PG8_WAIT_L(0); PG8_BAR; PG8_MMA(0, 0, At, B0); PG8_MMA(0, 1, At, B1); PG8_BAR; PG8_SCHED;
;             PG8_LDA(At, 1, 1); PG8_STAGE(PG8_SB(1, 0), b3, voffB); PG8_STAGE(PG8_SB(1, 1), b3 + hstepB, voffB); PG8_STAGE(PG8_SA(1, 0), a3, voffA);
;             PG8_WAIT_V(8); PG8_WAIT_L(0); PG8_BAR; PG8_MMA(1, 0, At, B0); PG8_MMA(1, 1, At, B1); PG8_BAR; PG8_SCHED;
	v_mfma_f32_16x16x32_bf16 v[62:65], v[152:155], v[184:187], 0
	v_mfma_f32_16x16x32_bf16 v[58:61], v[160:163], v[184:187], 0
	v_mfma_f32_16x16x32_bf16 v[46:49], v[152:155], v[192:195], 0
	v_mfma_f32_16x16x32_bf16 v[42:45], v[160:163], v[192:195], 0
	v_mfma_f32_16x16x32_bf16 v[30:33], v[152:155], v[200:203], 0
	v_mfma_f32_16x16x32_bf16 v[26:29], v[160:163], v[200:203], 0
	v_mfma_f32_16x16x32_bf16 v[14:17], v[152:155], v[208:211], 0
	v_mfma_f32_16x16x32_bf16 v[10:13], v[160:163], v[208:211], 0
	v_mfma_f32_16x16x32_bf16 v[62:65], v[156:159], v[188:191], v[62:65]
	v_mfma_f32_16x16x32_bf16 v[58:61], v[164:167], v[188:191], v[58:61]
	v_mfma_f32_16x16x32_bf16 v[46:49], v[156:159], v[196:199], v[46:49]
	v_mfma_f32_16x16x32_bf16 v[42:45], v[164:167], v[196:199], v[42:45]
	v_mfma_f32_16x16x32_bf16 v[30:33], v[156:159], v[204:207], v[30:33]
	v_mfma_f32_16x16x32_bf16 v[26:29], v[164:167], v[204:207], v[26:29]
	v_mfma_f32_16x16x32_bf16 v[14:17], v[156:159], v[212:215], v[14:17]
	v_mfma_f32_16x16x32_bf16 v[10:13], v[164:167], v[212:215], v[10:13]
	v_mfma_f32_16x16x32_bf16 v[54:57], v[168:171], v[184:187], 0
	v_mfma_f32_16x16x32_bf16 v[50:53], v[176:179], v[184:187], 0
	v_mfma_f32_16x16x32_bf16 v[38:41], v[168:171], v[192:195], 0
	v_mfma_f32_16x16x32_bf16 v[34:37], v[176:179], v[192:195], 0
	v_mfma_f32_16x16x32_bf16 v[22:25], v[168:171], v[200:203], 0
	v_mfma_f32_16x16x32_bf16 v[18:21], v[176:179], v[200:203], 0
	v_mfma_f32_16x16x32_bf16 v[6:9], v[168:171], v[208:211], 0
	v_mfma_f32_16x16x32_bf16 v[2:5], v[176:179], v[208:211], 0
	v_mfma_f32_16x16x32_bf16 v[54:57], v[172:175], v[188:191], v[54:57]
	v_mfma_f32_16x16x32_bf16 v[50:53], v[180:183], v[188:191], v[50:53]
	v_mfma_f32_16x16x32_bf16 v[38:41], v[172:175], v[196:199], v[38:41]
	v_mfma_f32_16x16x32_bf16 v[34:37], v[180:183], v[196:199], v[34:37]
	v_mfma_f32_16x16x32_bf16 v[22:25], v[172:175], v[204:207], v[22:25]
	v_mfma_f32_16x16x32_bf16 v[18:21], v[180:183], v[204:207], v[18:21]
	v_mfma_f32_16x16x32_bf16 v[6:9], v[172:175], v[212:215], v[6:9]
	v_mfma_f32_16x16x32_bf16 v[2:5], v[180:183], v[212:215], v[2:5]
	s_barrier
	v_add_u32_e32 v151, s60, v146
	ds_read_b128 v[152:155], v151
	ds_read_b128 v[156:159], v151 offset:1024
	ds_read_b128 v[160:163], v151 offset:2048
	ds_read_b128 v[164:167], v151 offset:3072
	v_add_u32_e32 v151, s61, v146
	ds_read_b128 v[168:171], v151
	ds_read_b128 v[172:175], v151 offset:1024
	ds_read_b128 v[176:179], v151 offset:2048
	ds_read_b128 v[180:183], v151 offset:3072
	s_add_u32 s44, s44, 0x4000
	s_addc_u32 s45, s45, 0
	s_mov_b32 m0, s51
	ds_read_b128 v[184:187], v150 offset:32768
	ds_read_b128 v[188:191], v150 offset:33792
	ds_read_b128 v[192:195], v150 offset:34816
	ds_read_b128 v[196:199], v150 offset:35840
	ds_read_b128 v[200:203], v150 offset:36864
	ds_read_b128 v[204:207], v150 offset:37888
	ds_read_b128 v[208:211], v150 offset:38912
	ds_read_b128 v[212:215], v150 offset:39936
	global_load_lds_dwordx4 v130, s[44:45]
	s_mov_b32 m0, s52
	s_nop 0
	global_load_lds_dwordx4 v132, s[44:45]
	s_waitcnt vmcnt(8) lgkmcnt(0)
	s_barrier
	v_mfma_f32_16x16x32_bf16 v[126:129], v[152:155], v[184:187], v[126:129]
	v_mfma_f32_16x16x32_bf16 v[122:125], v[160:163], v[184:187], v[122:125]
	v_mfma_f32_16x16x32_bf16 v[110:113], v[152:155], v[192:195], v[110:113]
	v_mfma_f32_16x16x32_bf16 v[106:109], v[160:163], v[192:195], v[106:109]
	v_mfma_f32_16x16x32_bf16 v[94:97], v[152:155], v[200:203], v[94:97]
	v_mfma_f32_16x16x32_bf16 v[90:93], v[160:163], v[200:203], v[90:93]
	v_mfma_f32_16x16x32_bf16 v[78:81], v[152:155], v[208:211], v[78:81]
	v_mfma_f32_16x16x32_bf16 v[74:77], v[160:163], v[208:211], v[74:77]
	v_mfma_f32_16x16x32_bf16 v[126:129], v[156:159], v[188:191], v[126:129]
	v_mfma_f32_16x16x32_bf16 v[122:125], v[164:167], v[188:191], v[122:125]
	v_mfma_f32_16x16x32_bf16 v[110:113], v[156:159], v[196:199], v[110:113]
	v_mfma_f32_16x16x32_bf16 v[106:109], v[164:167], v[196:199], v[106:109]
	v_mfma_f32_16x16x32_bf16 v[94:97], v[156:159], v[204:207], v[94:97]
	v_mfma_f32_16x16x32_bf16 v[90:93], v[164:167], v[204:207], v[90:93]
	v_mfma_f32_16x16x32_bf16 v[78:81], v[156:159], v[212:215], v[78:81]
	v_mfma_f32_16x16x32_bf16 v[74:77], v[164:167], v[212:215], v[74:77]
	v_mfma_f32_16x16x32_bf16 v[118:121], v[168:171], v[184:187], v[118:121]
	v_mfma_f32_16x16x32_bf16 v[114:117], v[176:179], v[184:187], v[114:117]
	v_mfma_f32_16x16x32_bf16 v[102:105], v[168:171], v[192:195], v[102:105]
	v_mfma_f32_16x16x32_bf16 v[98:101], v[176:179], v[192:195], v[98:101]
	v_mfma_f32_16x16x32_bf16 v[86:89], v[168:171], v[200:203], v[86:89]
	v_mfma_f32_16x16x32_bf16 v[82:85], v[176:179], v[200:203], v[82:85]
	v_mfma_f32_16x16x32_bf16 v[70:73], v[168:171], v[208:211], v[70:73]
	v_mfma_f32_16x16x32_bf16 v[66:69], v[176:179], v[208:211], v[66:69]
	v_mfma_f32_16x16x32_bf16 v[118:121], v[172:175], v[188:191], v[118:121]
	v_mfma_f32_16x16x32_bf16 v[114:117], v[180:183], v[188:191], v[114:117]
	v_mfma_f32_16x16x32_bf16 v[102:105], v[172:175], v[196:199], v[102:105]
	v_mfma_f32_16x16x32_bf16 v[98:101], v[180:183], v[196:199], v[98:101]
	v_mfma_f32_16x16x32_bf16 v[86:89], v[172:175], v[204:207], v[86:89]
	v_mfma_f32_16x16x32_bf16 v[82:85], v[180:183], v[204:207], v[82:85]
	v_mfma_f32_16x16x32_bf16 v[70:73], v[172:175], v[212:215], v[70:73]
	v_mfma_f32_16x16x32_bf16 v[66:69], v[180:183], v[212:215], v[66:69]
	s_barrier
; #define PG8_STAGE(bufoff, gbase, voff) do { _Pragma("unroll") for (int _i = 0; _i < 2; ++_i) \
;         __builtin_amdgcn_global_load_lds((const unsigned*)((const char*)(gbase) + (voff)[_i]), (LAS unsigned*)(lds + (bufoff) + ldsw + _i * 8192), 16, 0, 0); } while (0)
; #define PG8_LDA(dst, b, h) do { _Pragma("unroll") for (int m = 0; m < 4; ++m) _Pragma("unroll") for (int k = 0; k < 2; ++k) dst[m][k] = *(const LAS bf16x8*)(lds + PG8_SA(b, h) + aoff + m * 2048 + k * 1024); } while (0)
; #define PG8_WAIT_V(n) asm volatile("s_waitcnt vmcnt(" #n ")" ::: "memory")
; #define PG8_WAIT_L(n) asm volatile("s_waitcnt lgkmcnt(" #n ")" ::: "memory")
; template <class Epi, class Sched, bool ABLK = false, bool ALIGN_EPI = true, bool SP2 = true, bool BBLK = true>
; __device__ __forceinline__ void gemm_phase(LAS unsigned char* lds, const Gemm g, const Sched& S, const Epi& E) {
;     ...
;         for (int t = 0; t < nt; t += 2) {
;             const bool last = (t == nt - 2);
;             const char* a1 = a_tile(uA, tbA + t + 1);
;             const char* a2 = last ? a_tile(nuA, ntbA) : a_tile(uA, tbA + t + 2); const char* b2 = last ? nB : cB + (size_t)(t + 2) * kstepB;
;             const char* a3 = last ? a_tile(nuA, ntbA + 1) : a_tile(uA, tbA + t + 3); const char* b3 = b2 + kstepB;
;             if (last && has_next) S.a_ready(nxt);
;             if constexpr (SP2) {
;             PG8_LDB(B0, 0, 0); PG8_LDB(B1, 0, 1); PG8_SCHED; PG8_LDA(At, 0, 0); PG8_STAGE(PG8_SA(1, 1), a1 + hstepA, voffA);
;             PG8_WAIT_V(8); PG8_WAIT_L(0); PG8_BAR; PG8_MMA(0, 0, At, B0); PG8_MMA(0, 1, At, B1); PG8_BAR; PG8_SCHED;
;             PG8_LDA(At, 0, 1); PG8_STAGE(PG8_SB(0, 0), b2, voffB); PG8_STAGE(PG8_SB(0, 1), b2 + hstepB, voffB); PG8_STAGE(PG8_SA(0, 0), a2, voffA);
;             PG8_WAIT_V(8); PG8_WAIT_L(0); PG8_BAR; PG8_MMA(1, 0, At, B0); PG8_MMA(1, 1, At, B1); PG8_BAR; PG8_SCHED;
;             PG8_LDB(B0, 1, 0); PG8_LDB(B1, 1, 1); PG8_SCHED; PG8_LDA(At, 1, 0); PG8_STAGE(PG8_SA(0, 1), a2 + hstepA, voffA);
;             PG8_WAIT_V(8); PG8_WAIT_L(0); PG8_BAR; PG8_MMA(0, 0, At, B0); PG8_MMA(0, 1, At, B1); PG8_BAR; PG8_SCHED;
;             PG8_LDA(At, 1, 1); PG8_STAGE(PG8_SB(1, 0), b3, voffB); PG8_STAGE(PG8_SB(1, 1), b3 + hstepB, voffB); PG8_STAGE(PG8_SA(1, 0), a3, voffA);
;             PG8_WAIT_V(8); PG8_WAIT_L(0); PG8_BAR; PG8_MMA(1, 0, At, B0); PG8_MMA(1, 1, At, B1); PG8_BAR; PG8_SCHED;
	s_add_u32 s44, s42, 0x8000
	s_addc_u32 s45, s43, 0
	s_add_i32 s70, s60, s48
	s_mov_b32 m0, s70
	ds_read_b128 v[184:187], v150 offset:49152
	ds_read_b128 v[188:191], v150 offset:50176
	ds_read_b128 v[192:195], v150 offset:51200
	ds_read_b128 v[196:199], v150 offset:52224
	ds_read_b128 v[200:203], v150 offset:53248
	ds_read_b128 v[204:207], v150 offset:54272
	ds_read_b128 v[208:211], v150 offset:55296
	ds_read_b128 v[212:215], v150 offset:56320
	global_load_lds_dwordx4 v130, s[44:45]
	s_add_i32 m0, s70, 0x2000
	s_add_u32 s42, s42, 0xc000
	v_lshl_add_u64 v[216:217], s[44:45], 0, v[132:133]
	s_addc_u32 s43, s43, 0
	s_add_i32 s44, s61, s48
	global_load_lds_dwordx4 v[216:217], off
	s_mov_b32 m0, s44
	s_nop 0
	global_load_lds_dwordx4 v130, s[42:43]
	s_add_i32 m0, s44, 0x2000
	s_nop 0
	global_load_lds_dwordx4 v132, s[42:43]
	s_mov_b32 m0, s53
	s_nop 0
	global_load_lds_dwordx4 v130, s[40:41]
	s_mov_b32 m0, s54
	s_nop 0
	global_load_lds_dwordx4 v132, s[40:41]
	s_waitcnt vmcnt(8) lgkmcnt(0)
	s_barrier
	v_mfma_f32_16x16x32_bf16 v[62:65], v[152:155], v[184:187], v[62:65]
	v_mfma_f32_16x16x32_bf16 v[58:61], v[160:163], v[184:187], v[58:61]
	v_mfma_f32_16x16x32_bf16 v[46:49], v[152:155], v[192:195], v[46:49]
	v_mfma_f32_16x16x32_bf16 v[42:45], v[160:163], v[192:195], v[42:45]
	v_mfma_f32_16x16x32_bf16 v[30:33], v[152:155], v[200:203], v[30:33]
	v_mfma_f32_16x16x32_bf16 v[26:29], v[160:163], v[200:203], v[26:29]
	v_mfma_f32_16x16x32_bf16 v[14:17], v[152:155], v[208:211], v[14:17]
	v_mfma_f32_16x16x32_bf16 v[10:13], v[160:163], v[208:211], v[10:13]
	v_mfma_f32_16x16x32_bf16 v[62:65], v[156:159], v[188:191], v[62:65]
	v_mfma_f32_16x16x32_bf16 v[58:61], v[164:167], v[188:191], v[58:61]
	v_mfma_f32_16x16x32_bf16 v[46:49], v[156:159], v[196:199], v[46:49]
	v_mfma_f32_16x16x32_bf16 v[42:45], v[164:167], v[196:199], v[42:45]
	v_mfma_f32_16x16x32_bf16 v[30:33], v[156:159], v[204:207], v[30:33]
	v_mfma_f32_16x16x32_bf16 v[26:29], v[164:167], v[204:207], v[26:29]
	v_mfma_f32_16x16x32_bf16 v[14:17], v[156:159], v[212:215], v[14:17]
	v_mfma_f32_16x16x32_bf16 v[10:13], v[164:167], v[212:215], v[10:13]
	v_mfma_f32_16x16x32_bf16 v[54:57], v[168:171], v[184:187], v[54:57]
	v_mfma_f32_16x16x32_bf16 v[50:53], v[176:179], v[184:187], v[50:53]
	v_mfma_f32_16x16x32_bf16 v[38:41], v[168:171], v[192:195], v[38:41]
	v_mfma_f32_16x16x32_bf16 v[34:37], v[176:179], v[192:195], v[34:37]
	v_mfma_f32_16x16x32_bf16 v[22:25], v[168:171], v[200:203], v[22:25]
	v_mfma_f32_16x16x32_bf16 v[18:21], v[176:179], v[200:203], v[18:21]
	v_mfma_f32_16x16x32_bf16 v[6:9], v[168:171], v[208:211], v[6:9]
	v_mfma_f32_16x16x32_bf16 v[2:5], v[176:179], v[208:211], v[2:5]
	v_mfma_f32_16x16x32_bf16 v[54:57], v[172:175], v[188:191], v[54:57]
	v_mfma_f32_16x16x32_bf16 v[50:53], v[180:183], v[188:191], v[50:53]
	v_mfma_f32_16x16x32_bf16 v[38:41], v[172:175], v[196:199], v[38:41]
	v_mfma_f32_16x16x32_bf16 v[34:37], v[180:183], v[196:199], v[34:37]
	v_mfma_f32_16x16x32_bf16 v[22:25], v[172:175], v[204:207], v[22:25]
	v_mfma_f32_16x16x32_bf16 v[18:21], v[180:183], v[204:207], v[18:21]
	v_mfma_f32_16x16x32_bf16 v[6:9], v[172:175], v[212:215], v[6:9]
	v_mfma_f32_16x16x32_bf16 v[2:5], v[180:183], v[212:215], v[2:5]
	s_barrier
	s_add_u32 s38, s38, 0x10000
	s_addc_u32 s39, s39, 0
	s_cmp_ge_u32 s67, s56
.LBB0_2328:
	ds_read_b128 v[152:155], v148
	ds_read_b128 v[156:159], v148 offset:1024
	ds_read_b128 v[160:163], v148 offset:2048
	ds_read_b128 v[164:167], v148 offset:3072
	ds_read_b128 v[168:171], v149
	ds_read_b128 v[172:175], v149 offset:1024
	ds_read_b128 v[176:179], v149 offset:2048
	ds_read_b128 v[180:183], v149 offset:3072
	s_add_u32 s40, s64, s38
	s_addc_u32 s41, s65, s39
	s_add_u32 s44, s40, 0x10000
	s_addc_u32 s45, s41, 0
	s_add_i32 s67, s67, 2
	s_add_u32 s42, s62, s38
	s_addc_u32 s43, s63, s39
	s_add_u32 s40, s40, 0x18000
	s_addc_u32 s41, s41, 0
	s_cmp_eq_u32 s66, s38
	s_cbranch_scc1 .Lksel_27
.Lksel_27_back:
	v_lshl_add_u64 v[216:217], v[142:143], 0, s[38:39]
	s_add_i32 m0, s49, 0xc000
	ds_read_b128 v[184:187], v150
	ds_read_b128 v[188:191], v150 offset:1024
	ds_read_b128 v[192:195], v150 offset:2048
	ds_read_b128 v[196:199], v150 offset:3072
	ds_read_b128 v[200:203], v150 offset:4096
	ds_read_b128 v[204:207], v150 offset:5120
	ds_read_b128 v[208:211], v150 offset:6144
	ds_read_b128 v[212:215], v150 offset:7168
	global_load_lds_dwordx4 v[216:217], off
	v_lshl_add_u64 v[216:217], v[144:145], 0, s[38:39]
	s_add_i32 m0, s49, 0xe000
	s_nop 0
	global_load_lds_dwordx4 v[216:217], off
	s_waitcnt vmcnt(8) lgkmcnt(0)
	s_barrier
; #define PG8_STAGE(bufoff, gbase, voff) do { _Pragma("unroll") for (int _i = 0; _i < 2; ++_i) \
;         __builtin_amdgcn_global_load_lds((const unsigned*)((const char*)(gbase) + (voff)[_i]), (LAS unsigned*)(lds + (bufoff) + ldsw + _i * 8192), 16, 0, 0); } while (0)
; #define PG8_LDA(dst, b, h) do { _Pragma("unroll") for (int m = 0; m < 4; ++m) _Pragma("unroll") for (int k = 0; k < 2; ++k) dst[m][k] = *(const LAS bf16x8*)(lds + PG8_SA(b, h) + aoff + m * 2048 + k * 1024); } while (0)
; #define PG8_LDB(dst, b, h) do { _Pragma("unroll") for (int n = 0; n < 2; ++n) _Pragma("unroll") for (int k = 0; k < 2; ++k) dst[n][k] = *(const LAS bf16x8*)(lds + PG8_SB(b, h) + boff + n * 2048 + k * 1024); } while (0)
; #define PG8_MMA(ai, bj, At, Bt) do { __builtin_amdgcn_s_setprio(1); _Pragma("unroll") for (int m = 0; m < 4; ++m) _Pragma("unroll") for (int n = 0; n < 2; ++n) _Pragma("unroll") for (int k = 0; k < 2; ++k) \
;         acc[ai][bj][m][n] = __builtin_amdgcn_mfma_f32_16x16x32_bf16(Bt[n][k], At[m][k], acc[ai][bj][m][n], 0, 0, 0); __builtin_amdgcn_s_setprio(0); } while (0)
; #define PG8_WAIT_V(n) asm volatile("s_waitcnt vmcnt(" #n ")" ::: "memory")
; #define PG8_WAIT_L(n) asm volatile("s_waitcnt lgkmcnt(" #n ")" ::: "memory")
; #define PG8_BAR __builtin_amdgcn_s_barrier()
; #define PG8_SCHED __builtin_amdgcn_sched_barrier(0)
; template <class Epi, class Sched, bool ABLK = false, bool ALIGN_EPI = true, bool SP2 = true, bool BBLK = true>
; __device__ __forceinline__ void gemm_phase(LAS unsigned char* lds, const Gemm g, const Sched& S, const Epi& E) {
;     ...
;             PG8_LDB(B0, 0, 0); PG8_LDB(B1, 0, 1); PG8_SCHED; PG8_LDA(At, 0, 0); PG8_STAGE(PG8_SA(1, 1), a1 + hstepA, voffA);
;             PG8_WAIT_V(8); PG8_WAIT_L(0); PG8_BAR; PG8_MMA(0, 0, At, B0); PG8_MMA(0, 1, At, B1); PG8_BAR; PG8_SCHED;
;             PG8_LDA(At, 0, 1); PG8_STAGE(PG8_SB(0, 0), b2, voffB); PG8_STAGE(PG8_SB(0, 1), b2 + hstepB, voffB); PG8_STAGE(PG8_SA(0, 0), a2, voffA);
;             PG8_WAIT_V(8); PG8_WAIT_L(0); PG8_BAR; PG8_MMA(1, 0, At, B0); PG8_MMA(1, 1, At, B1); PG8_BAR; PG8_SCHED;
	v_mfma_f32_16x16x32_bf16 v[126:129], v[152:155], v[184:187], v[126:129]
	v_mfma_f32_16x16x32_bf16 v[122:125], v[160:163], v[184:187], v[122:125]
	v_mfma_f32_16x16x32_bf16 v[110:113], v[152:155], v[192:195], v[110:113]
	v_mfma_f32_16x16x32_bf16 v[106:109], v[160:163], v[192:195], v[106:109]
	v_mfma_f32_16x16x32_bf16 v[94:97], v[152:155], v[200:203], v[94:97]
	v_mfma_f32_16x16x32_bf16 v[90:93], v[160:163], v[200:203], v[90:93]
	v_mfma_f32_16x16x32_bf16 v[78:81], v[152:155], v[208:211], v[78:81]
	v_mfma_f32_16x16x32_bf16 v[74:77], v[160:163], v[208:211], v[74:77]
	v_mfma_f32_16x16x32_bf16 v[126:129], v[156:159], v[188:191], v[126:129]
	v_mfma_f32_16x16x32_bf16 v[122:125], v[164:167], v[188:191], v[122:125]
	v_mfma_f32_16x16x32_bf16 v[110:113], v[156:159], v[196:199], v[110:113]
	v_mfma_f32_16x16x32_bf16 v[106:109], v[164:167], v[196:199], v[106:109]
	v_mfma_f32_16x16x32_bf16 v[94:97], v[156:159], v[204:207], v[94:97]
	v_mfma_f32_16x16x32_bf16 v[90:93], v[164:167], v[204:207], v[90:93]
	v_mfma_f32_16x16x32_bf16 v[78:81], v[156:159], v[212:215], v[78:81]
	v_mfma_f32_16x16x32_bf16 v[74:77], v[164:167], v[212:215], v[74:77]
	v_mfma_f32_16x16x32_bf16 v[118:121], v[168:171], v[184:187], v[118:121]
	v_mfma_f32_16x16x32_bf16 v[114:117], v[176:179], v[184:187], v[114:117]
	v_mfma_f32_16x16x32_bf16 v[102:105], v[168:171], v[192:195], v[102:105]
	v_mfma_f32_16x16x32_bf16 v[98:101], v[176:179], v[192:195], v[98:101]
	v_mfma_f32_16x16x32_bf16 v[86:89], v[168:171], v[200:203], v[86:89]
	v_mfma_f32_16x16x32_bf16 v[82:85], v[176:179], v[200:203], v[82:85]
	v_mfma_f32_16x16x32_bf16 v[70:73], v[168:171], v[208:211], v[70:73]
	v_mfma_f32_16x16x32_bf16 v[66:69], v[176:179], v[208:211], v[66:69]
	v_mfma_f32_16x16x32_bf16 v[118:121], v[172:175], v[188:191], v[118:121]
	v_mfma_f32_16x16x32_bf16 v[114:117], v[180:183], v[188:191], v[114:117]
	v_mfma_f32_16x16x32_bf16 v[102:105], v[172:175], v[196:199], v[102:105]
	v_mfma_f32_16x16x32_bf16 v[98:101], v[180:183], v[196:199], v[98:101]
	v_mfma_f32_16x16x32_bf16 v[86:89], v[172:175], v[204:207], v[86:89]
	v_mfma_f32_16x16x32_bf16 v[82:85], v[180:183], v[204:207], v[82:85]
	v_mfma_f32_16x16x32_bf16 v[70:73], v[172:175], v[212:215], v[70:73]
	v_mfma_f32_16x16x32_bf16 v[66:69], v[180:183], v[212:215], v[66:69]
	s_barrier
	s_add_i32 s70, s72, s48
	s_mov_b32 m0, s70
	ds_read_b128 v[184:187], v150 offset:16384
	ds_read_b128 v[188:191], v150 offset:17408
	ds_read_b128 v[192:195], v150 offset:18432
	ds_read_b128 v[196:199], v150 offset:19456
	ds_read_b128 v[200:203], v150 offset:20480
	ds_read_b128 v[204:207], v150 offset:21504
	ds_read_b128 v[208:211], v150 offset:22528
	ds_read_b128 v[212:215], v150 offset:23552
	global_load_lds_dwordx4 v130, s[42:43]
	s_add_i32 m0, s70, 0x2000
	s_add_u32 s76, s42, 0x4000
	s_addc_u32 s77, s43, 0
	s_add_i32 s70, s73, s48
	global_load_lds_dwordx4 v132, s[42:43]
	s_mov_b32 m0, s70
	s_nop 0
	global_load_lds_dwordx4 v130, s[76:77]
	s_add_i32 m0, s70, 0x2000
	s_nop 0
	global_load_lds_dwordx4 v132, s[76:77]
	s_mov_b32 m0, s49
	s_nop 0
	global_load_lds_dwordx4 v130, s[44:45]
	s_mov_b32 m0, s50
	s_nop 0
	global_load_lds_dwordx4 v132, s[44:45]
	s_waitcnt vmcnt(8) lgkmcnt(0)
	s_barrier
	v_mfma_f32_16x16x32_bf16 v[62:65], v[152:155], v[184:187], v[62:65]
	v_mfma_f32_16x16x32_bf16 v[58:61], v[160:163], v[184:187], v[58:61]
	v_mfma_f32_16x16x32_bf16 v[46:49], v[152:155], v[192:195], v[46:49]
	v_mfma_f32_16x16x32_bf16 v[42:45], v[160:163], v[192:195], v[42:45]
	v_mfma_f32_16x16x32_bf16 v[30:33], v[152:155], v[200:203], v[30:33]
	v_mfma_f32_16x16x32_bf16 v[26:29], v[160:163], v[200:203], v[26:29]
	v_mfma_f32_16x16x32_bf16 v[14:17], v[152:155], v[208:211], v[14:17]
	v_mfma_f32_16x16x32_bf16 v[10:13], v[160:163], v[208:211], v[10:13]
	v_mfma_f32_16x16x32_bf16 v[62:65], v[156:159], v[188:191], v[62:65]
	v_mfma_f32_16x16x32_bf16 v[58:61], v[164:167], v[188:191], v[58:61]
	v_mfma_f32_16x16x32_bf16 v[46:49], v[156:159], v[196:199], v[46:49]
	v_mfma_f32_16x16x32_bf16 v[42:45], v[164:167], v[196:199], v[42:45]
	v_mfma_f32_16x16x32_bf16 v[30:33], v[156:159], v[204:207], v[30:33]
	v_mfma_f32_16x16x32_bf16 v[26:29], v[164:167], v[204:207], v[26:29]
	v_mfma_f32_16x16x32_bf16 v[14:17], v[156:159], v[212:215], v[14:17]
	v_mfma_f32_16x16x32_bf16 v[10:13], v[164:167], v[212:215], v[10:13]
	v_mfma_f32_16x16x32_bf16 v[54:57], v[168:171], v[184:187], v[54:57]
	v_mfma_f32_16x16x32_bf16 v[50:53], v[176:179], v[184:187], v[50:53]
	v_mfma_f32_16x16x32_bf16 v[38:41], v[168:171], v[192:195], v[38:41]
	v_mfma_f32_16x16x32_bf16 v[34:37], v[176:179], v[192:195], v[34:37]
	v_mfma_f32_16x16x32_bf16 v[22:25], v[168:171], v[200:203], v[22:25]
	v_mfma_f32_16x16x32_bf16 v[18:21], v[176:179], v[200:203], v[18:21]
	v_mfma_f32_16x16x32_bf16 v[6:9], v[168:171], v[208:211], v[6:9]
	v_mfma_f32_16x16x32_bf16 v[2:5], v[176:179], v[208:211], v[2:5]
	v_mfma_f32_16x16x32_bf16 v[54:57], v[172:175], v[188:191], v[54:57]
	v_mfma_f32_16x16x32_bf16 v[50:53], v[180:183], v[188:191], v[50:53]
	v_mfma_f32_16x16x32_bf16 v[38:41], v[172:175], v[196:199], v[38:41]
	v_mfma_f32_16x16x32_bf16 v[34:37], v[180:183], v[196:199], v[34:37]
	v_mfma_f32_16x16x32_bf16 v[22:25], v[172:175], v[204:207], v[22:25]
	v_mfma_f32_16x16x32_bf16 v[18:21], v[180:183], v[204:207], v[18:21]
	v_mfma_f32_16x16x32_bf16 v[6:9], v[172:175], v[212:215], v[6:9]
	v_mfma_f32_16x16x32_bf16 v[2:5], v[180:183], v[212:215], v[2:5]
	s_barrier
; #define PG8_STAGE(bufoff, gbase, voff) do { _Pragma("unroll") for (int _i = 0; _i < 2; ++_i) \
;         __builtin_amdgcn_global_load_lds((const unsigned*)((const char*)(gbase) + (voff)[_i]), (LAS unsigned*)(lds + (bufoff) + ldsw + _i * 8192), 16, 0, 0); } while (0)
; #define PG8_LDA(dst, b, h) do { _Pragma("unroll") for (int m = 0; m < 4; ++m) _Pragma("unroll") for (int k = 0; k < 2; ++k) dst[m][k] = *(const LAS bf16x8*)(lds + PG8_SA(b, h) + aoff + m * 2048 + k * 1024); } while (0)
; #define PG8_LDB(dst, b, h) do { _Pragma("unroll") for (int n = 0; n < 2; ++n) _Pragma("unroll") for (int k = 0; k < 2; ++k) dst[n][k] = *(const LAS bf16x8*)(lds + PG8_SB(b, h) + boff + n * 2048 + k * 1024); } while (0)
; #define PG8_MMA(ai, bj, At, Bt) do { __builtin_amdgcn_s_setprio(1); _Pragma("unroll") for (int m = 0; m < 4; ++m) _Pragma("unroll") for (int n = 0; n < 2; ++n) _Pragma("unroll") for (int k = 0; k < 2; ++k) \
;         acc[ai][bj][m][n] = __builtin_amdgcn_mfma_f32_16x16x32_bf16(Bt[n][k], At[m][k], acc[ai][bj][m][n], 0, 0, 0); __builtin_amdgcn_s_setprio(0); } while (0)
; #define PG8_WAIT_V(n) asm volatile("s_waitcnt vmcnt(" #n ")" ::: "memory")
; #define PG8_WAIT_L(n) asm volatile("s_waitcnt lgkmcnt(" #n ")" ::: "memory")
; #define PG8_BAR __builtin_amdgcn_s_barrier()
; #define PG8_SCHED __builtin_amdgcn_sched_barrier(0)
; template <class Epi, class Sched, bool ABLK = false, bool ALIGN_EPI = true, bool SP2 = true, bool BBLK = true>
; __device__ __forceinline__ void gemm_phase(LAS unsigned char* lds, const Gemm g, const Sched& S, const Epi& E) {
;     ...
;             PG8_LDB(B0, 1, 0); PG8_LDB(B1, 1, 1); PG8_SCHED; PG8_LDA(At, 1, 0); PG8_STAGE(PG8_SA(0, 1), a2 + hstepA, voffA);
;             PG8_WAIT_V(8); PG8_WAIT_L(0); PG8_BAR; PG8_MMA(0, 0, At, B0); PG8_MMA(0, 1, At, B1); PG8_BAR; PG8_SCHED;
;             PG8_LDA(At, 1, 1); PG8_STAGE(PG8_SB(1, 0), b3, voffB); PG8_STAGE(PG8_SB(1, 1), b3 + hstepB, voffB); PG8_STAGE(PG8_SA(1, 0), a3, voffA);
;             PG8_WAIT_V(8); PG8_WAIT_L(0); PG8_BAR; PG8_MMA(1, 0, At, B0); PG8_MMA(1, 1, At, B1); PG8_BAR; PG8_SCHED;
	v_add_u32_e32 v151, s60, v146
	ds_read_b128 v[152:155], v151
	ds_read_b128 v[156:159], v151 offset:1024
	ds_read_b128 v[160:163], v151 offset:2048
	ds_read_b128 v[164:167], v151 offset:3072
	v_add_u32_e32 v151, s61, v146
	ds_read_b128 v[168:171], v151
	ds_read_b128 v[172:175], v151 offset:1024
	ds_read_b128 v[176:179], v151 offset:2048
	ds_read_b128 v[180:183], v151 offset:3072
	s_add_u32 s44, s44, 0x4000
	s_addc_u32 s45, s45, 0
	s_mov_b32 m0, s51
	ds_read_b128 v[184:187], v150 offset:32768
	ds_read_b128 v[188:191], v150 offset:33792
	ds_read_b128 v[192:195], v150 offset:34816
	ds_read_b128 v[196:199], v150 offset:35840
	ds_read_b128 v[200:203], v150 offset:36864
	ds_read_b128 v[204:207], v150 offset:37888
	ds_read_b128 v[208:211], v150 offset:38912
	ds_read_b128 v[212:215], v150 offset:39936
	global_load_lds_dwordx4 v130, s[44:45]
	s_mov_b32 m0, s52
	s_nop 0
	global_load_lds_dwordx4 v132, s[44:45]
	s_waitcnt vmcnt(8) lgkmcnt(0)
	s_barrier
	v_mfma_f32_16x16x32_bf16 v[126:129], v[152:155], v[184:187], v[126:129]
	v_mfma_f32_16x16x32_bf16 v[122:125], v[160:163], v[184:187], v[122:125]
	v_mfma_f32_16x16x32_bf16 v[110:113], v[152:155], v[192:195], v[110:113]
	v_mfma_f32_16x16x32_bf16 v[106:109], v[160:163], v[192:195], v[106:109]
	v_mfma_f32_16x16x32_bf16 v[94:97], v[152:155], v[200:203], v[94:97]
	v_mfma_f32_16x16x32_bf16 v[90:93], v[160:163], v[200:203], v[90:93]
	v_mfma_f32_16x16x32_bf16 v[78:81], v[152:155], v[208:211], v[78:81]
	v_mfma_f32_16x16x32_bf16 v[74:77], v[160:163], v[208:211], v[74:77]
	v_mfma_f32_16x16x32_bf16 v[126:129], v[156:159], v[188:191], v[126:129]
	v_mfma_f32_16x16x32_bf16 v[122:125], v[164:167], v[188:191], v[122:125]
	v_mfma_f32_16x16x32_bf16 v[110:113], v[156:159], v[196:199], v[110:113]
	v_mfma_f32_16x16x32_bf16 v[106:109], v[164:167], v[196:199], v[106:109]
	v_mfma_f32_16x16x32_bf16 v[94:97], v[156:159], v[204:207], v[94:97]
	v_mfma_f32_16x16x32_bf16 v[90:93], v[164:167], v[204:207], v[90:93]
	v_mfma_f32_16x16x32_bf16 v[78:81], v[156:159], v[212:215], v[78:81]
	v_mfma_f32_16x16x32_bf16 v[74:77], v[164:167], v[212:215], v[74:77]
	v_mfma_f32_16x16x32_bf16 v[118:121], v[168:171], v[184:187], v[118:121]
	v_mfma_f32_16x16x32_bf16 v[114:117], v[176:179], v[184:187], v[114:117]
	v_mfma_f32_16x16x32_bf16 v[102:105], v[168:171], v[192:195], v[102:105]
	v_mfma_f32_16x16x32_bf16 v[98:101], v[176:179], v[192:195], v[98:101]
	v_mfma_f32_16x16x32_bf16 v[86:89], v[168:171], v[200:203], v[86:89]
	v_mfma_f32_16x16x32_bf16 v[82:85], v[176:179], v[200:203], v[82:85]
	v_mfma_f32_16x16x32_bf16 v[70:73], v[168:171], v[208:211], v[70:73]
	v_mfma_f32_16x16x32_bf16 v[66:69], v[176:179], v[208:211], v[66:69]
	v_mfma_f32_16x16x32_bf16 v[118:121], v[172:175], v[188:191], v[118:121]
	v_mfma_f32_16x16x32_bf16 v[114:117], v[180:183], v[188:191], v[114:117]
	v_mfma_f32_16x16x32_bf16 v[102:105], v[172:175], v[196:199], v[102:105]
	v_mfma_f32_16x16x32_bf16 v[98:101], v[180:183], v[196:199], v[98:101]
	v_mfma_f32_16x16x32_bf16 v[86:89], v[172:175], v[204:207], v[86:89]
	v_mfma_f32_16x16x32_bf16 v[82:85], v[180:183], v[204:207], v[82:85]
	v_mfma_f32_16x16x32_bf16 v[70:73], v[172:175], v[212:215], v[70:73]
	v_mfma_f32_16x16x32_bf16 v[66:69], v[180:183], v[212:215], v[66:69]
	s_barrier
	s_add_u32 s44, s42, 0x8000
	s_addc_u32 s45, s43, 0
	s_add_i32 s70, s60, s48
	s_mov_b32 m0, s70
	ds_read_b128 v[184:187], v150 offset:49152
	ds_read_b128 v[188:191], v150 offset:50176
	ds_read_b128 v[192:195], v150 offset:51200
	ds_read_b128 v[196:199], v150 offset:52224
	ds_read_b128 v[200:203], v150 offset:53248
	ds_read_b128 v[204:207], v150 offset:54272
	ds_read_b128 v[208:211], v150 offset:55296
	ds_read_b128 v[212:215], v150 offset:56320
	global_load_lds_dwordx4 v130, s[44:45]
	s_add_i32 m0, s70, 0x2000
	s_add_u32 s42, s42, 0xc000
	v_lshl_add_u64 v[216:217], s[44:45], 0, v[132:133]
	s_addc_u32 s43, s43, 0
	s_add_i32 s44, s61, s48
	global_load_lds_dwordx4 v[216:217], off
	s_mov_b32 m0, s44
	s_nop 0
	global_load_lds_dwordx4 v130, s[42:43]
	s_add_i32 m0, s44, 0x2000
	s_nop 0
	global_load_lds_dwordx4 v132, s[42:43]
	s_mov_b32 m0, s53
	s_nop 0
	global_load_lds_dwordx4 v130, s[40:41]
	s_mov_b32 m0, s54
	s_nop 0
	global_load_lds_dwordx4 v132, s[40:41]
	s_waitcnt vmcnt(8) lgkmcnt(0)
	s_barrier
	v_mfma_f32_16x16x32_bf16 v[62:65], v[152:155], v[184:187], v[62:65]
	v_mfma_f32_16x16x32_bf16 v[58:61], v[160:163], v[184:187], v[58:61]
	v_mfma_f32_16x16x32_bf16 v[46:49], v[152:155], v[192:195], v[46:49]
	v_mfma_f32_16x16x32_bf16 v[42:45], v[160:163], v[192:195], v[42:45]
	v_mfma_f32_16x16x32_bf16 v[30:33], v[152:155], v[200:203], v[30:33]
	v_mfma_f32_16x16x32_bf16 v[26:29], v[160:163], v[200:203], v[26:29]
	v_mfma_f32_16x16x32_bf16 v[14:17], v[152:155], v[208:211], v[14:17]
	v_mfma_f32_16x16x32_bf16 v[10:13], v[160:163], v[208:211], v[10:13]
	v_mfma_f32_16x16x32_bf16 v[62:65], v[156:159], v[188:191], v[62:65]
	v_mfma_f32_16x16x32_bf16 v[58:61], v[164:167], v[188:191], v[58:61]
	v_mfma_f32_16x16x32_bf16 v[46:49], v[156:159], v[196:199], v[46:49]
	v_mfma_f32_16x16x32_bf16 v[42:45], v[164:167], v[196:199], v[42:45]
	v_mfma_f32_16x16x32_bf16 v[30:33], v[156:159], v[204:207], v[30:33]
	v_mfma_f32_16x16x32_bf16 v[26:29], v[164:167], v[204:207], v[26:29]
	v_mfma_f32_16x16x32_bf16 v[14:17], v[156:159], v[212:215], v[14:17]
	v_mfma_f32_16x16x32_bf16 v[10:13], v[164:167], v[212:215], v[10:13]
	v_mfma_f32_16x16x32_bf16 v[54:57], v[168:171], v[184:187], v[54:57]
	v_mfma_f32_16x16x32_bf16 v[50:53], v[176:179], v[184:187], v[50:53]
	v_mfma_f32_16x16x32_bf16 v[38:41], v[168:171], v[192:195], v[38:41]
	v_mfma_f32_16x16x32_bf16 v[34:37], v[176:179], v[192:195], v[34:37]
	v_mfma_f32_16x16x32_bf16 v[22:25], v[168:171], v[200:203], v[22:25]
	v_mfma_f32_16x16x32_bf16 v[18:21], v[176:179], v[200:203], v[18:21]
	v_mfma_f32_16x16x32_bf16 v[6:9], v[168:171], v[208:211], v[6:9]
	v_mfma_f32_16x16x32_bf16 v[2:5], v[176:179], v[208:211], v[2:5]
	v_mfma_f32_16x16x32_bf16 v[54:57], v[172:175], v[188:191], v[54:57]
	v_mfma_f32_16x16x32_bf16 v[50:53], v[180:183], v[188:191], v[50:53]
	v_mfma_f32_16x16x32_bf16 v[38:41], v[172:175], v[196:199], v[38:41]
	v_mfma_f32_16x16x32_bf16 v[34:37], v[180:183], v[196:199], v[34:37]
	v_mfma_f32_16x16x32_bf16 v[22:25], v[172:175], v[204:207], v[22:25]
	v_mfma_f32_16x16x32_bf16 v[18:21], v[180:183], v[204:207], v[18:21]
	v_mfma_f32_16x16x32_bf16 v[6:9], v[172:175], v[212:215], v[6:9]
	v_mfma_f32_16x16x32_bf16 v[2:5], v[180:183], v[212:215], v[2:5]
	s_barrier
	s_add_u32 s38, s38, 0x10000
	s_addc_u32 s39, s39, 0
	s_cmp_ge_u32 s67, s56
	s_cbranch_scc0 .LBB0_2328
	s_and_b64 vcc, exec, s[14:15]
	s_cbranch_vccz .LBB0_2331
	s_barrier

; template <class Epi, class Sched, bool ABLK = false, bool ALIGN_EPI = true, bool SP2 = true, bool BBLK = true>
; __device__ __forceinline__ void gemm_phase(LAS unsigned char* lds, const Gemm g, const Sched& S, const Epi& E) {
;     ...
;             const char* a1 = a_tile(uA, tbA + t + 1);
;             const char* a2 = last ? a_tile(nuA, ntbA) : a_tile(uA, tbA + t + 2); const char* b2 = last ? nB : cB + (size_t)(t + 2) * kstepB;
;             const char* a3 = last ? a_tile(nuA, ntbA + 1) : a_tile(uA, tbA + t + 3); const char* b3 = b2 + kstepB;
.Lksel_27:
	s_mov_b32 s41, s59
	s_mov_b32 s40, s58
	s_mov_b32 s43, s4
	s_mov_b32 s42, s5
	s_mov_b32 s45, s57
	s_mov_b32 s44, s35
	s_branch .Lksel_27_back
